# one static s_setprio 1 for waves 0-3 at kernel entry (the half that does not defer in the GEMM stagger), every other s_setprio removed
# baseline (speedup 1.0000x reference)
; DI int HALF() { return __builtin_amdgcn_readfirstlane((int)(threadIdx.x >> 8)); }
; DI unsigned xb_add(unsigned* p, unsigned v) { return __hip_atomic_fetch_add(p, v, __ATOMIC_RELAXED, __HIP_MEMORY_SCOPE_AGENT); }
; DI unsigned xb_xcc_id() { return (unsigned)__builtin_amdgcn_s_getreg((3 << 11) | 20) & 0xFu; }
; __global__ void __launch_bounds__(512, 2) mega(Params p) {
;   extern __shared__ __attribute__((aligned(16))) bf16_t lds_all[];
;   bf16_t* lds = lds_all + HALF() * 32768;
;   cg::grid_group grid = cg::this_grid();
;   const int nb = NVB;
;   bf16_t* wt = (bf16_t*)(p.ws + O_WT);
;   bf16_t* z = (bf16_t*)(p.ws + O_Z);
;   bf16_t* hbuf = (bf16_t*)(p.ws + O_VST);
;   bf16_t* ubuf = z;
;   bf16_t* p16 = (bf16_t*)(p.ws + O_KVD);
;   float* rowpart = (float*)(p.ws + O_RP);
;   bf16_t* hid = (bf16_t*)(p.ws + O_HID);
;   const float* bias = (const float*)(p.ws + O_BIAS);
;   unsigned* bar = (unsigned*)(p.ws + O_BAR);
;   const unsigned xb_x = xb_xcc_id();
;   if (threadIdx.x == 0) (void)xb_add(&bar[XB_XCNT(xb_x)], 1u);
_Z4mega6Params:
	s_load_dwordx16 s[4:19], s[0:1], 0x0
	v_and_b32_e32 v196, 0x3ff, v0
	v_writelane_b32 v251, s2, 0
	s_add_u32 s2, s0, 0xb8
	s_addc_u32 s3, s1, 0
	s_waitcnt lgkmcnt(0)
	v_writelane_b32 v251, s4, 1
	s_mov_b32 s29, 0
	s_nop 0
	v_writelane_b32 v251, s5, 2
	v_writelane_b32 v251, s6, 3
	v_writelane_b32 v251, s7, 4
	v_writelane_b32 v251, s8, 5
	v_writelane_b32 v251, s9, 6
	v_writelane_b32 v251, s10, 7
	v_writelane_b32 v251, s11, 8
	v_writelane_b32 v251, s12, 9
	v_writelane_b32 v251, s13, 10
	v_writelane_b32 v251, s14, 11
	v_writelane_b32 v251, s15, 12
	v_writelane_b32 v251, s16, 13
	v_writelane_b32 v251, s17, 14
	v_writelane_b32 v251, s18, 15
	v_writelane_b32 v251, s19, 16
	s_load_dwordx16 s[4:19], s[0:1], 0x40
	s_waitcnt lgkmcnt(0)
	v_writelane_b32 v251, s4, 17
	s_nop 1
	v_writelane_b32 v251, s5, 18
	v_writelane_b32 v251, s6, 19
	v_writelane_b32 v251, s7, 20
	v_writelane_b32 v251, s8, 21
	v_writelane_b32 v251, s9, 22
	v_writelane_b32 v251, s10, 23
	v_writelane_b32 v251, s11, 24
	v_writelane_b32 v251, s12, 25
	v_writelane_b32 v251, s13, 26
	v_writelane_b32 v251, s14, 27
	v_writelane_b32 v251, s15, 28
	v_writelane_b32 v251, s16, 29
	v_writelane_b32 v251, s17, 30
	v_writelane_b32 v251, s18, 31
	v_writelane_b32 v251, s19, 32
	s_load_dwordx2 s[94:95], s[0:1], 0xb0
	s_load_dwordx4 s[4:7], s[0:1], 0xa0
	s_waitcnt lgkmcnt(0)
	v_writelane_b32 v251, s4, 33
	s_nop 1
	v_writelane_b32 v251, s5, 34
	v_writelane_b32 v251, s6, 35
	v_writelane_b32 v251, s7, 36
	s_load_dwordx8 s[4:11], s[0:1], 0x80
	s_waitcnt lgkmcnt(0)
	v_writelane_b32 v251, s4, 37
	s_nop 1
	v_writelane_b32 v251, s5, 38
	v_writelane_b32 v251, s6, 39
	v_writelane_b32 v251, s7, 40
	v_writelane_b32 v251, s8, 41
	v_writelane_b32 v251, s9, 42
	s_load_dword s0, s[0:1], 0xb8
	v_writelane_b32 v251, s10, 43
	v_writelane_b32 v251, s11, 44
	v_writelane_b32 v251, s2, 45
	v_readfirstlane_b32 s8, v196
	s_lshr_b32 s101, s8, 8
	s_mov_b32 s100, 0
	s_lshr_b32 s101, s8, 8
	s_cmp_lg_u32 s101, 0
	s_cbranch_scc1 .Lprio_static_done
	s_setprio 1
.Lprio_static_done:
	v_cmp_eq_u32_e64 s[4:5], 0, v196
	v_writelane_b32 v251, s3, 46
	s_waitcnt lgkmcnt(0)
	v_writelane_b32 v251, s0, 47
	s_add_u32 s0, s94, 0x1ee61000
	s_getreg_b32 s2, hwreg(HW_REG_XCC_ID, 0, 4)
	s_addc_u32 s1, s95, 0
	s_and_b32 s6, s2, 15
	s_lshl_b32 s7, s6, 6
	s_mov_b64 s[2:3], exec
	v_writelane_b32 v251, s4, 48
	s_nop 1
	v_writelane_b32 v251, s5, 49
	s_and_b64 s[4:5], s[2:3], s[4:5]
	s_mov_b64 exec, s[4:5]
	s_cbranch_execz .LBB0_3
	s_mov_b64 s[4:5], exec
	v_mbcnt_lo_u32_b32 v1, s4, 0
	v_mbcnt_hi_u32_b32 v1, s5, v1
	v_cmp_eq_u32_e32 vcc, 0, v1
	s_and_b64 s[10:11], exec, vcc
	s_mov_b64 exec, s[10:11]
	s_cbranch_execz .LBB0_3
	s_lshl_b32 s9, s7, 2
	s_bcnt1_i32_b64 s4, s[4:5]
	v_mov_b32_e32 v1, s9
	v_mov_b32_e32 v2, s4
	global_atomic_add v1, v2, s[0:1] offset:1024

; DI f32x4 mfma16(bf16x8 a, bf16x8 b, f32x4 c) { return __builtin_amdgcn_mfma_f32_16x16x32_bf16(a, b, c, 0, 0, 0); }
; #pragma unroll
;   for (int ks = KS0; ks < KS1; ++ks) {
;     bf16x8 af[8], bfr[4];
; #pragma unroll
;     for (int i = 0; i < 8; ++i) {
;       const int r = wm * 128 + i * 16 + (lane & 15);
;       af[i] = *(const bf16x8*)(S + r * 64 + (((ks * 4 + (lane >> 4)) ^ ((r >> 1) & 7)) << 3));
;     }
; #pragma unroll
;     for (int j = 0; j < 4; ++j) {
;       const int r = wn * 64 + j * 16 + (lane & 15);
;       bfr[j] = *(const bf16x8*)(S + 16384 + r * 64 + (((ks * 4 + (lane >> 4)) ^ ((r >> 1) & 7)) << 3));
;     }
;     __builtin_amdgcn_s_setprio(1);
; #pragma unroll
;     for (int i = 0; i < 8; ++i)
; #pragma unroll
;       for (int j = 0; j < 4; ++j) acc[i][j] = mfma16(bfr[j], af[i], acc[i][j]);
;     __builtin_amdgcn_s_setprio(0);
;   }
; }
; DI void gemm8_accum(f32x4 (&acc)[8][4], const bf16_t* a, size_t lda, const bf16_t* b, size_t ldb, int nkb, bf16_t* L,
;                     const bool pre, const bf16_t* an, size_t ldan, const bf16_t* bn, size_t ldbn) {
;     ...
;   for (int kb = 0; kb + 2 < nkb; ++kb) {
;     __syncthreads();
;     g8_store1(L + ((kb + 1) & 1) * 32768, ra, lrow, lch);
;     g8_load1o(ra, a + (kb + 2) * 64, offa);
;     __builtin_amdgcn_sched_barrier(0);
;     g8_compute<0, 1>(acc, L + (kb & 1) * 32768, wm, wn, lane);
;     __builtin_amdgcn_sched_barrier(0);
;     g8_store1(L + ((kb + 1) & 1) * 32768 + 16384, rb, lrow, lch);
;     g8_load1o(rb, b + (kb + 2) * 64, offb);
;     __builtin_amdgcn_sched_barrier(0);
;     g8_compute<1, 2>(acc, L + (kb & 1) * 32768, wm, wn, lane);
;   }
.LBB0_134:
	s_add_i32 s3, s2, 0x8000
	s_and_b32 s6, s3, 0x8000
	v_lshl_add_u32 v167, s6, 1, v163
	s_waitcnt lgkmcnt(0)
	s_barrier
	s_cmp_eq_u32 s100, 0
	s_cbranch_scc1 .Lstg_134_a
	v_mfma_f32_16x16x32_bf16 v[34:37], v[234:237], v[192:195], v[34:37]
	v_mfma_f32_16x16x32_bf16 v[38:41], v[238:241], v[192:195], v[38:41]
	v_mfma_f32_16x16x32_bf16 v[42:45], v[242:245], v[192:195], v[42:45]
	v_mfma_f32_16x16x32_bf16 v[46:49], v[246:249], v[192:195], v[46:49]
	v_mfma_f32_16x16x32_bf16 v[50:53], v[234:237], v[206:209], v[50:53]
	v_mfma_f32_16x16x32_bf16 v[54:57], v[238:241], v[206:209], v[54:57]
	v_mfma_f32_16x16x32_bf16 v[58:61], v[242:245], v[206:209], v[58:61]
	v_mfma_f32_16x16x32_bf16 v[62:65], v[246:249], v[206:209], v[62:65]
	v_mfma_f32_16x16x32_bf16 v[66:69], v[234:237], v[210:213], v[66:69]
	v_mfma_f32_16x16x32_bf16 v[70:73], v[238:241], v[210:213], v[70:73]
	v_mfma_f32_16x16x32_bf16 v[74:77], v[242:245], v[210:213], v[74:77]
	v_mfma_f32_16x16x32_bf16 v[78:81], v[246:249], v[210:213], v[78:81]
	v_mfma_f32_16x16x32_bf16 v[82:85], v[234:237], v[214:217], v[82:85]
	v_mfma_f32_16x16x32_bf16 v[86:89], v[238:241], v[214:217], v[86:89]
	v_mfma_f32_16x16x32_bf16 v[90:93], v[242:245], v[214:217], v[90:93]
	v_mfma_f32_16x16x32_bf16 v[94:97], v[246:249], v[214:217], v[94:97]
	v_mfma_f32_16x16x32_bf16 v[98:101], v[234:237], v[218:221], v[98:101]
	v_mfma_f32_16x16x32_bf16 v[102:105], v[238:241], v[218:221], v[102:105]
	v_mfma_f32_16x16x32_bf16 v[106:109], v[242:245], v[218:221], v[106:109]
	v_mfma_f32_16x16x32_bf16 v[110:113], v[246:249], v[218:221], v[110:113]
	v_mfma_f32_16x16x32_bf16 v[114:117], v[234:237], v[222:225], v[114:117]
	v_mfma_f32_16x16x32_bf16 v[118:121], v[238:241], v[222:225], v[118:121]
	v_mfma_f32_16x16x32_bf16 v[122:125], v[242:245], v[222:225], v[122:125]
	v_mfma_f32_16x16x32_bf16 v[126:129], v[246:249], v[222:225], v[126:129]
	v_mfma_f32_16x16x32_bf16 v[130:133], v[234:237], v[226:229], v[130:133]
	v_mfma_f32_16x16x32_bf16 v[134:137], v[238:241], v[226:229], v[134:137]
	v_mfma_f32_16x16x32_bf16 v[138:141], v[242:245], v[226:229], v[138:141]
	v_mfma_f32_16x16x32_bf16 v[142:145], v[246:249], v[226:229], v[142:145]
	v_mfma_f32_16x16x32_bf16 v[146:149], v[234:237], v[230:233], v[146:149]
	v_mfma_f32_16x16x32_bf16 v[150:153], v[238:241], v[230:233], v[150:153]
	v_mfma_f32_16x16x32_bf16 v[154:157], v[242:245], v[230:233], v[154:157]
	v_mfma_f32_16x16x32_bf16 v[158:161], v[246:249], v[230:233], v[158:161]
.Lstg_134_a:
	s_waitcnt vmcnt(5)
	ds_write_b128 v167, v[22:25]
	ds_write_b128 v167, v[18:21] offset:8192
	ds_write_b128 v167, v[26:29] offset:16384
	s_waitcnt vmcnt(4)
	ds_write_b128 v167, v[30:33] offset:24576
	v_lshl_add_u64 v[18:19], v[184:185], 0, s[0:1]
	v_lshl_add_u64 v[26:27], v[180:181], 0, s[0:1]
	global_load_dwordx4 v[22:25], v[18:19], off
	v_lshl_add_u64 v[30:31], v[178:179], 0, s[0:1]
	global_load_dwordx4 v[26:29], v[26:27], off
	v_lshl_add_u64 v[18:19], v[182:183], 0, s[0:1]
	global_load_dwordx4 v[18:21], v[18:19], off
	s_nop 0
	global_load_dwordx4 v[30:33], v[30:31], off
	s_and_b32 s2, s2, 0x8000
	s_lshl_b32 s2, s2, 1
	s_add_i32 s2, s2, 0
	v_lshl_add_u32 v169, v191, 1, s2
	v_add_u32_e32 v198, v169, v187
	ds_read_b128 v[192:195], v198
	ds_read_b128 v[206:209], v198 offset:2048
	ds_read_b128 v[210:213], v198 offset:4096
	ds_read_b128 v[214:217], v198 offset:6144
	ds_read_b128 v[218:221], v198 offset:8192
	ds_read_b128 v[222:225], v198 offset:10240
	ds_read_b128 v[226:229], v198 offset:12288
	ds_read_b128 v[230:233], v198 offset:14336
	v_add_u32_e32 v169, v169, v186
	ds_read_b128 v[234:237], v169 offset:32768
	ds_read_b128 v[238:241], v169 offset:34816
	ds_read_b128 v[242:245], v169 offset:36864
	ds_read_b128 v[246:249], v169 offset:38912
	s_waitcnt lgkmcnt(3)
	v_mfma_f32_16x16x32_bf16 v[34:37], v[234:237], v[192:195], v[34:37]
	s_waitcnt lgkmcnt(2)
	v_mfma_f32_16x16x32_bf16 v[38:41], v[238:241], v[192:195], v[38:41]
	s_waitcnt lgkmcnt(1)
	v_mfma_f32_16x16x32_bf16 v[42:45], v[242:245], v[192:195], v[42:45]
	s_waitcnt lgkmcnt(0)
	v_mfma_f32_16x16x32_bf16 v[46:49], v[246:249], v[192:195], v[46:49]
	v_mfma_f32_16x16x32_bf16 v[50:53], v[234:237], v[206:209], v[50:53]
	v_mfma_f32_16x16x32_bf16 v[54:57], v[238:241], v[206:209], v[54:57]
	v_mfma_f32_16x16x32_bf16 v[58:61], v[242:245], v[206:209], v[58:61]
	v_mfma_f32_16x16x32_bf16 v[62:65], v[246:249], v[206:209], v[62:65]
	v_mfma_f32_16x16x32_bf16 v[66:69], v[234:237], v[210:213], v[66:69]
	v_mfma_f32_16x16x32_bf16 v[70:73], v[238:241], v[210:213], v[70:73]
	v_mfma_f32_16x16x32_bf16 v[74:77], v[242:245], v[210:213], v[74:77]
	v_mfma_f32_16x16x32_bf16 v[78:81], v[246:249], v[210:213], v[78:81]
	v_mfma_f32_16x16x32_bf16 v[82:85], v[234:237], v[214:217], v[82:85]
	v_mfma_f32_16x16x32_bf16 v[86:89], v[238:241], v[214:217], v[86:89]
	v_mfma_f32_16x16x32_bf16 v[90:93], v[242:245], v[214:217], v[90:93]
	v_mfma_f32_16x16x32_bf16 v[94:97], v[246:249], v[214:217], v[94:97]
	v_mfma_f32_16x16x32_bf16 v[98:101], v[234:237], v[218:221], v[98:101]
	v_mfma_f32_16x16x32_bf16 v[102:105], v[238:241], v[218:221], v[102:105]
	v_mfma_f32_16x16x32_bf16 v[106:109], v[242:245], v[218:221], v[106:109]
	v_mfma_f32_16x16x32_bf16 v[110:113], v[246:249], v[218:221], v[110:113]
	v_mfma_f32_16x16x32_bf16 v[114:117], v[234:237], v[222:225], v[114:117]
	v_mfma_f32_16x16x32_bf16 v[118:121], v[238:241], v[222:225], v[118:121]
	v_mfma_f32_16x16x32_bf16 v[122:125], v[242:245], v[222:225], v[122:125]
	v_mfma_f32_16x16x32_bf16 v[126:129], v[246:249], v[222:225], v[126:129]
	v_mfma_f32_16x16x32_bf16 v[130:133], v[234:237], v[226:229], v[130:133]
	v_mfma_f32_16x16x32_bf16 v[134:137], v[238:241], v[226:229], v[134:137]
	v_mfma_f32_16x16x32_bf16 v[138:141], v[242:245], v[226:229], v[138:141]
	v_mfma_f32_16x16x32_bf16 v[142:145], v[246:249], v[226:229], v[142:145]
	v_mfma_f32_16x16x32_bf16 v[146:149], v[234:237], v[230:233], v[146:149]
	v_mfma_f32_16x16x32_bf16 v[150:153], v[238:241], v[230:233], v[150:153]
	v_mfma_f32_16x16x32_bf16 v[154:157], v[242:245], v[230:233], v[154:157]
	v_mfma_f32_16x16x32_bf16 v[158:161], v[246:249], v[230:233], v[158:161]
	s_waitcnt vmcnt(7)
; DI void gemm8_accum(f32x4 (&acc)[8][4], const bf16_t* a, size_t lda, const bf16_t* b, size_t ldb, int nkb, bf16_t* L,
;                     const bool pre, const bf16_t* an, size_t ldan, const bf16_t* bn, size_t ldbn) {
;     ...
;   for (int kb = 0; kb + 2 < nkb; ++kb) {
;     __syncthreads();
;     g8_store1(L + ((kb + 1) & 1) * 32768, ra, lrow, lch);
;     g8_load1o(ra, a + (kb + 2) * 64, offa);
;     __builtin_amdgcn_sched_barrier(0);
;     g8_compute<0, 1>(acc, L + (kb & 1) * 32768, wm, wn, lane);
;     __builtin_amdgcn_sched_barrier(0);
;     g8_store1(L + ((kb + 1) & 1) * 32768 + 16384, rb, lrow, lch);
;     g8_load1o(rb, b + (kb + 2) * 64, offb);
;     __builtin_amdgcn_sched_barrier(0);
;     g8_compute<1, 2>(acc, L + (kb & 1) * 32768, wm, wn, lane);
;   }
;   __syncthreads();
;   g8_store1(L + 32768, ra, lrow, lch);
;   g8_load1(ra, an, ldan, 0, lrow, lch);
;   __builtin_amdgcn_sched_barrier(0);
;   g8_compute<0, 1>(acc, L, wm, wn, lane);
;   __builtin_amdgcn_sched_barrier(0);
;   g8_store1(L + 32768 + 16384, rb, lrow, lch);
;   g8_load1(rb, bn, ldbn, 0, lrow, lch);
;   __builtin_amdgcn_sched_barrier(0);
;   g8_compute<1, 2>(acc, L, wm, wn, lane);
	ds_write_b128 v167, v[6:9] offset:32768
	s_waitcnt vmcnt(6)
	ds_write_b128 v167, v[2:5] offset:40960
	s_waitcnt vmcnt(5)
	ds_write_b128 v167, v[10:13] offset:49152
	s_waitcnt vmcnt(4)
	ds_write_b128 v167, v[14:17] offset:57344
	v_lshl_add_u64 v[2:3], v[176:177], 0, s[0:1]
	v_lshl_add_u64 v[4:5], v[174:175], 0, s[0:1]
	v_lshl_add_u64 v[10:11], v[172:173], 0, s[0:1]
	v_lshl_add_u64 v[14:15], v[170:171], 0, s[0:1]
	global_load_dwordx4 v[6:9], v[2:3], off
	s_nop 0
	global_load_dwordx4 v[2:5], v[4:5], off
	s_nop 0
	global_load_dwordx4 v[10:13], v[10:11], off
	s_nop 0
	global_load_dwordx4 v[14:17], v[14:15], off
	v_lshl_add_u32 v167, v188, 1, s2
	v_add_u32_e32 v169, v167, v187
	ds_read_b128 v[192:195], v169
	ds_read_b128 v[206:209], v169 offset:2048
	ds_read_b128 v[210:213], v169 offset:4096
	ds_read_b128 v[214:217], v169 offset:6144
	ds_read_b128 v[218:221], v169 offset:8192
	ds_read_b128 v[222:225], v169 offset:10240
	ds_read_b128 v[226:229], v169 offset:12288
	ds_read_b128 v[230:233], v169 offset:14336
	v_add_u32_e32 v167, v167, v186
	ds_read_b128 v[234:237], v167 offset:32768
	ds_read_b128 v[238:241], v167 offset:34816
	ds_read_b128 v[242:245], v167 offset:36864
	ds_read_b128 v[246:249], v167 offset:38912
	s_cmp_lg_u32 s101, 0
	s_cbranch_scc1 .Lstg_134_b
	s_waitcnt lgkmcnt(3)
	v_mfma_f32_16x16x32_bf16 v[34:37], v[234:237], v[192:195], v[34:37]
	s_waitcnt lgkmcnt(2)
	v_mfma_f32_16x16x32_bf16 v[38:41], v[238:241], v[192:195], v[38:41]
	s_waitcnt lgkmcnt(1)
	v_mfma_f32_16x16x32_bf16 v[42:45], v[242:245], v[192:195], v[42:45]
	s_waitcnt lgkmcnt(0)
	v_mfma_f32_16x16x32_bf16 v[46:49], v[246:249], v[192:195], v[46:49]
	v_mfma_f32_16x16x32_bf16 v[50:53], v[234:237], v[206:209], v[50:53]
	v_mfma_f32_16x16x32_bf16 v[54:57], v[238:241], v[206:209], v[54:57]
	v_mfma_f32_16x16x32_bf16 v[58:61], v[242:245], v[206:209], v[58:61]
	v_mfma_f32_16x16x32_bf16 v[62:65], v[246:249], v[206:209], v[62:65]
	v_mfma_f32_16x16x32_bf16 v[66:69], v[234:237], v[210:213], v[66:69]
	v_mfma_f32_16x16x32_bf16 v[70:73], v[238:241], v[210:213], v[70:73]
	v_mfma_f32_16x16x32_bf16 v[74:77], v[242:245], v[210:213], v[74:77]
	v_mfma_f32_16x16x32_bf16 v[78:81], v[246:249], v[210:213], v[78:81]
	v_mfma_f32_16x16x32_bf16 v[82:85], v[234:237], v[214:217], v[82:85]
	v_mfma_f32_16x16x32_bf16 v[86:89], v[238:241], v[214:217], v[86:89]
	v_mfma_f32_16x16x32_bf16 v[90:93], v[242:245], v[214:217], v[90:93]
	v_mfma_f32_16x16x32_bf16 v[94:97], v[246:249], v[214:217], v[94:97]
	v_mfma_f32_16x16x32_bf16 v[98:101], v[234:237], v[218:221], v[98:101]
	v_mfma_f32_16x16x32_bf16 v[102:105], v[238:241], v[218:221], v[102:105]
	v_mfma_f32_16x16x32_bf16 v[106:109], v[242:245], v[218:221], v[106:109]
	v_mfma_f32_16x16x32_bf16 v[110:113], v[246:249], v[218:221], v[110:113]
	v_mfma_f32_16x16x32_bf16 v[114:117], v[234:237], v[222:225], v[114:117]
	v_mfma_f32_16x16x32_bf16 v[118:121], v[238:241], v[222:225], v[118:121]
	v_mfma_f32_16x16x32_bf16 v[122:125], v[242:245], v[222:225], v[122:125]
	v_mfma_f32_16x16x32_bf16 v[126:129], v[246:249], v[222:225], v[126:129]
	v_mfma_f32_16x16x32_bf16 v[130:133], v[234:237], v[226:229], v[130:133]
	v_mfma_f32_16x16x32_bf16 v[134:137], v[238:241], v[226:229], v[134:137]
	v_mfma_f32_16x16x32_bf16 v[138:141], v[242:245], v[226:229], v[138:141]
	v_mfma_f32_16x16x32_bf16 v[142:145], v[246:249], v[226:229], v[142:145]
	v_mfma_f32_16x16x32_bf16 v[146:149], v[234:237], v[230:233], v[146:149]
	v_mfma_f32_16x16x32_bf16 v[150:153], v[238:241], v[230:233], v[150:153]
	v_mfma_f32_16x16x32_bf16 v[154:157], v[242:245], v[230:233], v[154:157]
	v_mfma_f32_16x16x32_bf16 v[158:161], v[246:249], v[230:233], v[158:161]
.Lstg_134_b:
	s_mov_b32 s100, s101
	s_add_u32 s0, s0, 0x80
	s_addc_u32 s1, s1, 0
	s_cmpk_lg_i32 s0, 0x700
	s_mov_b32 s2, s3
	s_cbranch_scc1 .LBB0_134
	s_cmp_eq_u32 s100, 0
	s_cbranch_scc1 .Lstg_134_c
	s_waitcnt lgkmcnt(0)
	v_mfma_f32_16x16x32_bf16 v[34:37], v[234:237], v[192:195], v[34:37]
	v_mfma_f32_16x16x32_bf16 v[38:41], v[238:241], v[192:195], v[38:41]
	v_mfma_f32_16x16x32_bf16 v[42:45], v[242:245], v[192:195], v[42:45]
	v_mfma_f32_16x16x32_bf16 v[46:49], v[246:249], v[192:195], v[46:49]
	v_mfma_f32_16x16x32_bf16 v[50:53], v[234:237], v[206:209], v[50:53]
	v_mfma_f32_16x16x32_bf16 v[54:57], v[238:241], v[206:209], v[54:57]
	v_mfma_f32_16x16x32_bf16 v[58:61], v[242:245], v[206:209], v[58:61]
	v_mfma_f32_16x16x32_bf16 v[62:65], v[246:249], v[206:209], v[62:65]
	v_mfma_f32_16x16x32_bf16 v[66:69], v[234:237], v[210:213], v[66:69]
	v_mfma_f32_16x16x32_bf16 v[70:73], v[238:241], v[210:213], v[70:73]
	v_mfma_f32_16x16x32_bf16 v[74:77], v[242:245], v[210:213], v[74:77]
	v_mfma_f32_16x16x32_bf16 v[78:81], v[246:249], v[210:213], v[78:81]
	v_mfma_f32_16x16x32_bf16 v[82:85], v[234:237], v[214:217], v[82:85]
	v_mfma_f32_16x16x32_bf16 v[86:89], v[238:241], v[214:217], v[86:89]
	v_mfma_f32_16x16x32_bf16 v[90:93], v[242:245], v[214:217], v[90:93]
	v_mfma_f32_16x16x32_bf16 v[94:97], v[246:249], v[214:217], v[94:97]
	v_mfma_f32_16x16x32_bf16 v[98:101], v[234:237], v[218:221], v[98:101]
	v_mfma_f32_16x16x32_bf16 v[102:105], v[238:241], v[218:221], v[102:105]
	v_mfma_f32_16x16x32_bf16 v[106:109], v[242:245], v[218:221], v[106:109]
	v_mfma_f32_16x16x32_bf16 v[110:113], v[246:249], v[218:221], v[110:113]
	v_mfma_f32_16x16x32_bf16 v[114:117], v[234:237], v[222:225], v[114:117]
	v_mfma_f32_16x16x32_bf16 v[118:121], v[238:241], v[222:225], v[118:121]
	v_mfma_f32_16x16x32_bf16 v[122:125], v[242:245], v[222:225], v[122:125]
	v_mfma_f32_16x16x32_bf16 v[126:129], v[246:249], v[222:225], v[126:129]
	v_mfma_f32_16x16x32_bf16 v[130:133], v[234:237], v[226:229], v[130:133]
	v_mfma_f32_16x16x32_bf16 v[134:137], v[238:241], v[226:229], v[134:137]
	v_mfma_f32_16x16x32_bf16 v[138:141], v[242:245], v[226:229], v[138:141]
	v_mfma_f32_16x16x32_bf16 v[142:145], v[246:249], v[226:229], v[142:145]
	v_mfma_f32_16x16x32_bf16 v[146:149], v[234:237], v[230:233], v[146:149]
	v_mfma_f32_16x16x32_bf16 v[150:153], v[238:241], v[230:233], v[150:153]
	v_mfma_f32_16x16x32_bf16 v[154:157], v[242:245], v[230:233], v[154:157]
	v_mfma_f32_16x16x32_bf16 v[158:161], v[246:249], v[230:233], v[158:161]
	s_mov_b32 s100, 0
; DI void gemm8_accum(f32x4 (&acc)[8][4], const bf16_t* a, size_t lda, const bf16_t* b, size_t ldb, int nkb, bf16_t* L,
;                     const bool pre, const bf16_t* an, size_t ldan, const bf16_t* bn, size_t ldbn) {
;     ...
;   __syncthreads();
;   g8_store1(L + 32768, ra, lrow, lch);
;   g8_load1(ra, an, ldan, 0, lrow, lch);
;   __builtin_amdgcn_sched_barrier(0);
;   g8_compute<0, 1>(acc, L, wm, wn, lane);
;   __builtin_amdgcn_sched_barrier(0);
;   g8_store1(L + 32768 + 16384, rb, lrow, lch);
;   g8_load1(rb, bn, ldbn, 0, lrow, lch);
;   __builtin_amdgcn_sched_barrier(0);
;   g8_compute<1, 2>(acc, L, wm, wn, lane);
;   __syncthreads();
;   g8_store1(L, ra, lrow, lch);
;   __builtin_amdgcn_sched_barrier(0);
;   g8_compute<0, 1>(acc, L + 32768, wm, wn, lane);
.Lstg_134_c:
	v_readlane_b32 s0, v254, 18
	s_add_i32 s11, s10, s0
	s_cmpk_gt_u32 s11, 0x15f
	s_cselect_b64 s[0:1], -1, 0
	s_cmpk_lt_u32 s11, 0x160
	s_cselect_b32 s2, s11, s10
	s_mul_hi_u32 s3, s2, 0xba2e8ba3
	s_lshr_b32 s3, s3, 6
	s_lshl_b32 s6, s3, 5
	s_mulk_i32 s3, 0x58
	s_sub_i32 s7, s2, s3
	s_and_b32 s2, s7, 3
	s_or_b32 s2, s6, s2
	s_or_b32 s28, s2, s38
	s_lshl_b64 s[2:3], s[28:29], 19
	s_add_u32 s2, s18, s2
	v_mov_b32_e32 v169, v1
	v_mov_b32_e32 v167, v1
	s_addc_u32 s3, s19, s3
	v_lshlrev_b64 v[184:185], 1, v[168:169]
	v_lshlrev_b64 v[166:167], 1, v[166:167]
	v_lshlrev_b64 v[198:199], 1, v[0:1]
	v_lshl_add_u64 v[170:171], s[2:3], 0, v[164:165]
	v_lshl_add_u64 v[172:173], s[2:3], 0, v[184:185]
	v_lshl_add_u64 v[176:177], s[2:3], 0, v[166:167]
	v_lshl_add_u64 v[180:181], s[2:3], 0, v[198:199]
	s_barrier
	global_load_dwordx4 v[168:171], v[170:171], off
	s_nop 0
	global_load_dwordx4 v[172:175], v[172:173], off
	s_nop 0
	global_load_dwordx4 v[176:179], v[176:177], off
	s_nop 0
	global_load_dwordx4 v[180:183], v[180:181], off
	s_lshl_b32 s2, s7, 17
	s_and_b32 s2, s2, 0xf80000
	s_add_u32 s2, s94, s2
	s_addc_u32 s3, s95, 0
	s_add_i32 s6, 0, 0x10000
	v_add3_u32 v0, s6, v189, v190
	s_waitcnt vmcnt(11)
	ds_write_b128 v0, v[22:25]
	s_waitcnt vmcnt(9)
	ds_write_b128 v0, v[18:21] offset:8192
	ds_write_b128 v0, v[26:29] offset:16384
	s_waitcnt vmcnt(8)
	ds_write_b128 v0, v[30:33] offset:24576
	v_lshlrev_b32_e32 v0, 1, v191
	v_add_u32_e32 v191, 0, v0
	v_add_u32_e32 v200, v191, v187
	ds_read_b128 v[18:21], v200
	ds_read_b128 v[22:25], v200 offset:2048
	ds_read_b128 v[26:29], v200 offset:4096
	ds_read_b128 v[30:33], v200 offset:6144
	ds_read_b128 v[192:195], v200 offset:8192
	ds_read_b128 v[206:209], v200 offset:10240
	ds_read_b128 v[210:213], v200 offset:12288
	ds_read_b128 v[214:217], v200 offset:14336
	v_add_u32_e32 v191, v191, v186
	ds_read_b128 v[218:221], v191 offset:32768
	ds_read_b128 v[222:225], v191 offset:34816
	ds_read_b128 v[226:229], v191 offset:36864
	ds_read_b128 v[230:233], v191 offset:38912
	s_waitcnt lgkmcnt(3)
	v_mfma_f32_16x16x32_bf16 v[34:37], v[218:221], v[18:21], v[34:37]
	s_waitcnt lgkmcnt(2)
	v_mfma_f32_16x16x32_bf16 v[38:41], v[222:225], v[18:21], v[38:41]
	s_waitcnt lgkmcnt(1)
	v_mfma_f32_16x16x32_bf16 v[42:45], v[226:229], v[18:21], v[42:45]
	s_waitcnt lgkmcnt(0)
	v_mfma_f32_16x16x32_bf16 v[18:21], v[230:233], v[18:21], v[46:49]
	v_mfma_f32_16x16x32_bf16 v[46:49], v[218:221], v[22:25], v[50:53]
	v_mfma_f32_16x16x32_bf16 v[50:53], v[222:225], v[22:25], v[54:57]
	v_mfma_f32_16x16x32_bf16 v[54:57], v[226:229], v[22:25], v[58:61]
	v_mfma_f32_16x16x32_bf16 v[22:25], v[230:233], v[22:25], v[62:65]
	v_mfma_f32_16x16x32_bf16 v[58:61], v[218:221], v[26:29], v[66:69]
	v_mfma_f32_16x16x32_bf16 v[62:65], v[222:225], v[26:29], v[70:73]
	v_mfma_f32_16x16x32_bf16 v[66:69], v[226:229], v[26:29], v[74:77]
	v_mfma_f32_16x16x32_bf16 v[26:29], v[230:233], v[26:29], v[78:81]
	v_mfma_f32_16x16x32_bf16 v[70:73], v[218:221], v[30:33], v[82:85]
	v_mfma_f32_16x16x32_bf16 v[74:77], v[222:225], v[30:33], v[86:89]
	v_mfma_f32_16x16x32_bf16 v[78:81], v[226:229], v[30:33], v[90:93]
	v_mfma_f32_16x16x32_bf16 v[30:33], v[230:233], v[30:33], v[94:97]
	v_mfma_f32_16x16x32_bf16 v[82:85], v[218:221], v[192:195], v[98:101]
	v_mfma_f32_16x16x32_bf16 v[86:89], v[222:225], v[192:195], v[102:105]
	v_mfma_f32_16x16x32_bf16 v[90:93], v[226:229], v[192:195], v[106:109]
	v_mfma_f32_16x16x32_bf16 v[94:97], v[230:233], v[192:195], v[110:113]
	v_mfma_f32_16x16x32_bf16 v[98:101], v[218:221], v[206:209], v[114:117]
	v_mfma_f32_16x16x32_bf16 v[102:105], v[222:225], v[206:209], v[118:121]
	v_mfma_f32_16x16x32_bf16 v[106:109], v[226:229], v[206:209], v[122:125]
	v_mfma_f32_16x16x32_bf16 v[110:113], v[230:233], v[206:209], v[126:129]
	v_mfma_f32_16x16x32_bf16 v[114:117], v[218:221], v[210:213], v[130:133]
	v_mfma_f32_16x16x32_bf16 v[118:121], v[222:225], v[210:213], v[134:137]
	v_mfma_f32_16x16x32_bf16 v[122:125], v[226:229], v[210:213], v[138:141]
	v_mfma_f32_16x16x32_bf16 v[126:129], v[230:233], v[210:213], v[142:145]
	v_mfma_f32_16x16x32_bf16 v[130:133], v[218:221], v[214:217], v[146:149]
	v_mfma_f32_16x16x32_bf16 v[134:137], v[222:225], v[214:217], v[150:153]
	v_mfma_f32_16x16x32_bf16 v[138:141], v[226:229], v[214:217], v[154:157]
	v_mfma_f32_16x16x32_bf16 v[142:145], v[230:233], v[214:217], v[158:161]
	v_readlane_b32 s7, v254, 36
	s_nop 1
	v_add3_u32 v146, s7, v189, v190
	s_waitcnt vmcnt(7)
	ds_write_b128 v146, v[6:9]
	s_waitcnt vmcnt(6)
	ds_write_b128 v146, v[2:5] offset:8192
	s_waitcnt vmcnt(5)
	ds_write_b128 v146, v[10:13] offset:16384
	s_waitcnt vmcnt(4)
	ds_write_b128 v146, v[14:17] offset:24576
	v_lshl_add_u64 v[2:3], s[2:3], 0, v[164:165]
	v_lshl_add_u64 v[6:7], s[2:3], 0, v[184:185]
	v_lshl_add_u64 v[10:11], s[2:3], 0, v[166:167]
	v_lshl_add_u64 v[14:15], s[2:3], 0, v[198:199]
	global_load_dwordx4 v[2:5], v[2:3], off
	s_nop 0
	global_load_dwordx4 v[6:9], v[6:7], off
	s_nop 0
	global_load_dwordx4 v[10:13], v[10:11], off
	s_nop 0
	global_load_dwordx4 v[14:17], v[14:15], off
	v_lshlrev_b32_e32 v184, 1, v188
	v_add_u32_e32 v185, 0, v184
	v_add_u32_e32 v198, v185, v187
	ds_read_b128 v[146:149], v198
	ds_read_b128 v[150:153], v198 offset:2048
	ds_read_b128 v[154:157], v198 offset:4096
	ds_read_b128 v[158:161], v198 offset:6144
	ds_read_b128 v[164:167], v198 offset:8192
	ds_read_b128 v[188:191], v198 offset:10240
	ds_read_b128 v[192:195], v198 offset:12288
	ds_read_b128 v[206:209], v198 offset:14336
	v_add_u32_e32 v185, v185, v186
	ds_read_b128 v[210:213], v185 offset:32768
	ds_read_b128 v[214:217], v185 offset:34816
	ds_read_b128 v[218:221], v185 offset:36864
	ds_read_b128 v[222:225], v185 offset:38912
	s_waitcnt lgkmcnt(3)
; DI void gemm8_accum(f32x4 (&acc)[8][4], const bf16_t* a, size_t lda, const bf16_t* b, size_t ldb, int nkb, bf16_t* L,
;                     const bool pre, const bf16_t* an, size_t ldan, const bf16_t* bn, size_t ldbn) {
;     ...
;   g8_compute<0, 1>(acc, L, wm, wn, lane);
;   __builtin_amdgcn_sched_barrier(0);
;   g8_store1(L + 32768 + 16384, rb, lrow, lch);
;   g8_load1(rb, bn, ldbn, 0, lrow, lch);
;   __builtin_amdgcn_sched_barrier(0);
;   g8_compute<1, 2>(acc, L, wm, wn, lane);
;   __syncthreads();
;   g8_store1(L, ra, lrow, lch);
;   __builtin_amdgcn_sched_barrier(0);
;   g8_compute<0, 1>(acc, L + 32768, wm, wn, lane);
;   __builtin_amdgcn_sched_barrier(0);
;   g8_store1(L + 16384, rb, lrow, lch);
;   __builtin_amdgcn_sched_barrier(0);
;   g8_compute<1, 2>(acc, L + 32768, wm, wn, lane);
	v_mfma_f32_16x16x32_bf16 v[34:37], v[210:213], v[146:149], v[34:37]
	s_waitcnt lgkmcnt(2)
	v_mfma_f32_16x16x32_bf16 v[38:41], v[214:217], v[146:149], v[38:41]
	s_waitcnt lgkmcnt(1)
	v_mfma_f32_16x16x32_bf16 v[42:45], v[218:221], v[146:149], v[42:45]
	s_waitcnt lgkmcnt(0)
	v_mfma_f32_16x16x32_bf16 v[18:21], v[222:225], v[146:149], v[18:21]
	v_mfma_f32_16x16x32_bf16 v[46:49], v[210:213], v[150:153], v[46:49]
	v_mfma_f32_16x16x32_bf16 v[50:53], v[214:217], v[150:153], v[50:53]
	v_mfma_f32_16x16x32_bf16 v[54:57], v[218:221], v[150:153], v[54:57]
	v_mfma_f32_16x16x32_bf16 v[22:25], v[222:225], v[150:153], v[22:25]
	v_mfma_f32_16x16x32_bf16 v[58:61], v[210:213], v[154:157], v[58:61]
	v_mfma_f32_16x16x32_bf16 v[62:65], v[214:217], v[154:157], v[62:65]
	v_mfma_f32_16x16x32_bf16 v[66:69], v[218:221], v[154:157], v[66:69]
	v_mfma_f32_16x16x32_bf16 v[26:29], v[222:225], v[154:157], v[26:29]
	v_mfma_f32_16x16x32_bf16 v[70:73], v[210:213], v[158:161], v[70:73]
	v_mfma_f32_16x16x32_bf16 v[74:77], v[214:217], v[158:161], v[74:77]
	v_mfma_f32_16x16x32_bf16 v[30:33], v[222:225], v[158:161], v[30:33]
	v_mfma_f32_16x16x32_bf16 v[78:81], v[218:221], v[158:161], v[78:81]
	v_mfma_f32_16x16x32_bf16 v[82:85], v[210:213], v[164:167], v[82:85]
	v_mfma_f32_16x16x32_bf16 v[86:89], v[214:217], v[164:167], v[86:89]
	v_mfma_f32_16x16x32_bf16 v[90:93], v[218:221], v[164:167], v[90:93]
	v_mfma_f32_16x16x32_bf16 v[94:97], v[222:225], v[164:167], v[94:97]
	v_mfma_f32_16x16x32_bf16 v[98:101], v[210:213], v[188:191], v[98:101]
	v_mfma_f32_16x16x32_bf16 v[102:105], v[214:217], v[188:191], v[102:105]
	v_mfma_f32_16x16x32_bf16 v[106:109], v[218:221], v[188:191], v[106:109]
	v_mfma_f32_16x16x32_bf16 v[110:113], v[222:225], v[188:191], v[110:113]
	v_mfma_f32_16x16x32_bf16 v[114:117], v[210:213], v[192:195], v[114:117]
	v_mfma_f32_16x16x32_bf16 v[118:121], v[214:217], v[192:195], v[118:121]
	v_mfma_f32_16x16x32_bf16 v[122:125], v[218:221], v[192:195], v[122:125]
	v_mfma_f32_16x16x32_bf16 v[126:129], v[222:225], v[192:195], v[126:129]
	v_mfma_f32_16x16x32_bf16 v[130:133], v[210:213], v[206:209], v[130:133]
	v_mfma_f32_16x16x32_bf16 v[134:137], v[214:217], v[206:209], v[134:137]
	v_mfma_f32_16x16x32_bf16 v[138:141], v[218:221], v[206:209], v[138:141]
	v_mfma_f32_16x16x32_bf16 v[142:145], v[222:225], v[206:209], v[142:145]
	s_barrier
	s_waitcnt vmcnt(7)
	ds_write_b128 v163, v[168:171]
	s_waitcnt vmcnt(6)
	ds_write_b128 v163, v[172:175] offset:8192
	s_waitcnt vmcnt(5)
	ds_write_b128 v163, v[176:179] offset:16384
	s_waitcnt vmcnt(4)
	ds_write_b128 v163, v[180:183] offset:24576
	v_add3_u32 v176, s6, v0, v187
	ds_read_b128 v[146:149], v176
	ds_read_b128 v[150:153], v176 offset:2048
	ds_read_b128 v[154:157], v176 offset:4096
	ds_read_b128 v[158:161], v176 offset:6144
	ds_read_b128 v[164:167], v176 offset:8192
	ds_read_b128 v[168:171], v176 offset:10240
	ds_read_b128 v[172:175], v176 offset:12288
	ds_read_b128 v[176:179], v176 offset:14336
	v_add3_u32 v0, s7, v0, v186
	ds_read_b128 v[180:183], v0
	ds_read_b128 v[188:191], v0 offset:2048
	ds_read_b128 v[192:195], v0 offset:4096
	ds_read_b128 v[206:209], v0 offset:6144
	s_waitcnt lgkmcnt(3)
	v_mfma_f32_16x16x32_bf16 v[34:37], v[180:183], v[146:149], v[34:37]
	s_waitcnt lgkmcnt(2)
	v_mfma_f32_16x16x32_bf16 v[38:41], v[188:191], v[146:149], v[38:41]
	s_waitcnt lgkmcnt(1)
	v_mfma_f32_16x16x32_bf16 v[42:45], v[192:195], v[146:149], v[42:45]
	s_waitcnt lgkmcnt(0)
	v_mfma_f32_16x16x32_bf16 v[18:21], v[206:209], v[146:149], v[18:21]
	v_mfma_f32_16x16x32_bf16 v[46:49], v[180:183], v[150:153], v[46:49]
	v_mfma_f32_16x16x32_bf16 v[50:53], v[188:191], v[150:153], v[50:53]
	v_mfma_f32_16x16x32_bf16 v[54:57], v[192:195], v[150:153], v[54:57]
	v_mfma_f32_16x16x32_bf16 v[22:25], v[206:209], v[150:153], v[22:25]
	v_mfma_f32_16x16x32_bf16 v[58:61], v[180:183], v[154:157], v[58:61]
	v_mfma_f32_16x16x32_bf16 v[62:65], v[188:191], v[154:157], v[62:65]
	v_mfma_f32_16x16x32_bf16 v[66:69], v[192:195], v[154:157], v[66:69]
	v_mfma_f32_16x16x32_bf16 v[26:29], v[206:209], v[154:157], v[26:29]
	v_mfma_f32_16x16x32_bf16 v[70:73], v[180:183], v[158:161], v[70:73]
	v_mfma_f32_16x16x32_bf16 v[74:77], v[188:191], v[158:161], v[74:77]
	v_mfma_f32_16x16x32_bf16 v[30:33], v[206:209], v[158:161], v[30:33]
	v_mfma_f32_16x16x32_bf16 v[78:81], v[192:195], v[158:161], v[78:81]
	v_mfma_f32_16x16x32_bf16 v[82:85], v[180:183], v[164:167], v[82:85]
	v_mfma_f32_16x16x32_bf16 v[86:89], v[188:191], v[164:167], v[86:89]
	v_mfma_f32_16x16x32_bf16 v[90:93], v[192:195], v[164:167], v[90:93]
	v_mfma_f32_16x16x32_bf16 v[94:97], v[206:209], v[164:167], v[94:97]
	v_mfma_f32_16x16x32_bf16 v[98:101], v[180:183], v[168:171], v[98:101]
	v_mfma_f32_16x16x32_bf16 v[102:105], v[188:191], v[168:171], v[102:105]
	v_mfma_f32_16x16x32_bf16 v[106:109], v[192:195], v[168:171], v[106:109]
	v_mfma_f32_16x16x32_bf16 v[110:113], v[206:209], v[168:171], v[110:113]
	v_mfma_f32_16x16x32_bf16 v[114:117], v[180:183], v[172:175], v[114:117]
	v_mfma_f32_16x16x32_bf16 v[118:121], v[188:191], v[172:175], v[118:121]
	v_mfma_f32_16x16x32_bf16 v[122:125], v[192:195], v[172:175], v[122:125]
	v_mfma_f32_16x16x32_bf16 v[126:129], v[206:209], v[172:175], v[126:129]
	v_mfma_f32_16x16x32_bf16 v[130:133], v[180:183], v[176:179], v[130:133]
	v_mfma_f32_16x16x32_bf16 v[134:137], v[188:191], v[176:179], v[134:137]
	v_mfma_f32_16x16x32_bf16 v[138:141], v[192:195], v[176:179], v[138:141]
	v_mfma_f32_16x16x32_bf16 v[142:145], v[206:209], v[176:179], v[142:145]
	s_waitcnt vmcnt(3)
	ds_write_b128 v163, v[2:5] offset:32768
	s_waitcnt vmcnt(2)
	ds_write_b128 v163, v[6:9] offset:40960
	s_waitcnt vmcnt(1)
	ds_write_b128 v163, v[10:13] offset:49152
	s_waitcnt vmcnt(0)
; DI int TID8() { int t = threadIdx.x; asm volatile("" : "+v"(t)); return t; }
; DI void gemm8_accum(f32x4 (&acc)[8][4], const bf16_t* a, size_t lda, const bf16_t* b, size_t ldb, int nkb, bf16_t* L,
;                     const bool pre, const bf16_t* an, size_t ldan, const bf16_t* bn, size_t ldbn) {
;     ...
;   g8_store1(L + 16384, rb, lrow, lch);
;   __builtin_amdgcn_sched_barrier(0);
;   g8_compute<1, 2>(acc, L + 32768, wm, wn, lane);
;   __syncthreads();
; }
; template <class F>
; DI void gemm8_epi_staged(f32x4 (&acc)[8][4], int m0, int n0, bf16_t* L0, F f, bf16_t* dst, size_t ld, int nmax) {
;   bf16_t* L = L0 + 32768;
;   const int tid = TID8(), lane = tid & 63, w = tid >> 6;
;   const int wm = w >> 2, wn = w & 3;
; #pragma unroll
;   for (int half = 0; half < 2; ++half) {
;     if (wm == half) {
; #pragma unroll
;       for (int i = 0; i < 8; ++i)
; #pragma unroll
;         for (int j = 0; j < 4; ++j) {
;           const int ml = i * 16 + (lane & 15);
;           const int nl = wn * 64 + j * 16 + (lane >> 4) * 4;
;           f32x4 a = acc[i][j];
;           f(m0 + half * 128 + ml, n0 + nl, a);
;           uint2 u;
;           u.x = pack2(a[0], a[1]);
;           u.y = pack2(a[2], a[3]);
;           *(uint2*)(L + ml * 264 + nl) = u;
;         }
;     }
	ds_write_b128 v163, v[14:17] offset:57344
	v_add3_u32 v0, s6, v184, v187
	ds_read_b128 v[2:5], v0
	ds_read_b128 v[6:9], v0 offset:2048
	ds_read_b128 v[10:13], v0 offset:4096
	ds_read_b128 v[14:17], v0 offset:6144
	ds_read_b128 v[146:149], v0 offset:8192
	ds_read_b128 v[150:153], v0 offset:10240
	ds_read_b128 v[154:157], v0 offset:12288
	ds_read_b128 v[158:161], v0 offset:14336
	v_add3_u32 v0, s7, v184, v186
	ds_read_b128 v[164:167], v0
	ds_read_b128 v[168:171], v0 offset:2048
	ds_read_b128 v[172:175], v0 offset:4096
	ds_read_b128 v[176:179], v0 offset:6144
	s_waitcnt lgkmcnt(3)
	v_mfma_f32_16x16x32_bf16 v[34:37], v[164:167], v[2:5], v[34:37]
	s_waitcnt lgkmcnt(2)
	v_mfma_f32_16x16x32_bf16 v[38:41], v[168:171], v[2:5], v[38:41]
	s_waitcnt lgkmcnt(1)
	v_mfma_f32_16x16x32_bf16 v[42:45], v[172:175], v[2:5], v[42:45]
	s_waitcnt lgkmcnt(0)
	v_mfma_f32_16x16x32_bf16 v[2:5], v[176:179], v[2:5], v[18:21]
	v_mfma_f32_16x16x32_bf16 v[18:21], v[164:167], v[6:9], v[46:49]
	v_mfma_f32_16x16x32_bf16 v[50:53], v[168:171], v[6:9], v[50:53]
	v_mfma_f32_16x16x32_bf16 v[180:183], v[172:175], v[6:9], v[54:57]
	v_mfma_f32_16x16x32_bf16 v[6:9], v[176:179], v[6:9], v[22:25]
	v_mfma_f32_16x16x32_bf16 v[22:25], v[164:167], v[10:13], v[58:61]
	v_mfma_f32_16x16x32_bf16 v[184:187], v[168:171], v[10:13], v[62:65]
	v_mfma_f32_16x16x32_bf16 v[66:69], v[172:175], v[10:13], v[66:69]
	v_mfma_f32_16x16x32_bf16 v[10:13], v[176:179], v[10:13], v[26:29]
	v_mfma_f32_16x16x32_bf16 v[26:29], v[164:167], v[14:17], v[70:73]
	v_mfma_f32_16x16x32_bf16 v[188:191], v[168:171], v[14:17], v[74:77]
	v_mfma_f32_16x16x32_bf16 v[78:81], v[172:175], v[14:17], v[78:81]
	v_mfma_f32_16x16x32_bf16 v[14:17], v[176:179], v[14:17], v[30:33]
	v_mfma_f32_16x16x32_bf16 v[82:85], v[164:167], v[146:149], v[82:85]
	v_mfma_f32_16x16x32_bf16 v[86:89], v[168:171], v[146:149], v[86:89]
	v_mfma_f32_16x16x32_bf16 v[90:93], v[172:175], v[146:149], v[90:93]
	v_mfma_f32_16x16x32_bf16 v[94:97], v[176:179], v[146:149], v[94:97]
	v_mfma_f32_16x16x32_bf16 v[98:101], v[164:167], v[150:153], v[98:101]
	v_mfma_f32_16x16x32_bf16 v[102:105], v[168:171], v[150:153], v[102:105]
	v_mfma_f32_16x16x32_bf16 v[106:109], v[172:175], v[150:153], v[106:109]
	v_mfma_f32_16x16x32_bf16 v[110:113], v[176:179], v[150:153], v[110:113]
	v_mfma_f32_16x16x32_bf16 v[114:117], v[164:167], v[154:157], v[114:117]
	v_mfma_f32_16x16x32_bf16 v[118:121], v[168:171], v[154:157], v[118:121]
	v_mfma_f32_16x16x32_bf16 v[122:125], v[172:175], v[154:157], v[122:125]
	v_mfma_f32_16x16x32_bf16 v[126:129], v[176:179], v[154:157], v[126:129]
	v_mfma_f32_16x16x32_bf16 v[130:133], v[164:167], v[158:161], v[130:133]
	v_mfma_f32_16x16x32_bf16 v[134:137], v[168:171], v[158:161], v[134:137]
	v_mfma_f32_16x16x32_bf16 v[138:141], v[172:175], v[158:161], v[138:141]
	v_mfma_f32_16x16x32_bf16 v[142:145], v[176:179], v[158:161], v[142:145]
	v_mov_b32_e32 v77, v196
	s_barrier
	s_movk_i32 s2, 0x100
	v_and_b32_e32 v0, 0xc0, v77
	v_lshrrev_b32_e32 v31, 1, v77
	v_lshlrev_b32_e32 v0, 1, v0
	v_and_b32_e32 v31, 24, v31
	v_and_b32_e32 v30, 15, v77
	v_add3_u32 v0, s6, v0, v31
	v_cmp_gt_u32_e32 vcc, s2, v77
	s_movk_i32 s2, 0x210
	v_mad_u32_u24 v72, v30, s2, v0
	v_cvt_pk_bf16_f32 v60, v34, v35
	v_cvt_pk_bf16_f32 v61, v36, v37
	v_cvt_pk_bf16_f32 v64, v38, v39
	v_cvt_pk_bf16_f32 v65, v40, v41
	v_cvt_pk_bf16_f32 v54, v42, v43
	v_cvt_pk_bf16_f32 v55, v44, v45
	v_cvt_pk_bf16_f32 v62, v2, v3
	v_cvt_pk_bf16_f32 v63, v4, v5
	v_cvt_pk_bf16_f32 v48, v18, v19
	v_cvt_pk_bf16_f32 v49, v20, v21
	v_cvt_pk_bf16_f32 v58, v50, v51
	v_cvt_pk_bf16_f32 v59, v52, v53
	v_add_u32_e32 v76, 0x2000, v72
	v_cvt_pk_bf16_f32 v46, v180, v181
	v_cvt_pk_bf16_f32 v47, v182, v183
	v_cvt_pk_bf16_f32 v56, v6, v7
	v_cvt_pk_bf16_f32 v57, v8, v9
	v_cvt_pk_bf16_f32 v40, v22, v23
	v_cvt_pk_bf16_f32 v41, v24, v25
	v_cvt_pk_bf16_f32 v52, v184, v185
	v_cvt_pk_bf16_f32 v53, v186, v187
	v_add_u32_e32 v75, 0x4000, v72
	v_cvt_pk_bf16_f32 v38, v66, v67
	v_cvt_pk_bf16_f32 v39, v68, v69
	v_cvt_pk_bf16_f32 v50, v10, v11
	v_cvt_pk_bf16_f32 v51, v12, v13
	v_cvt_pk_bf16_f32 v32, v26, v27
	v_cvt_pk_bf16_f32 v33, v28, v29
	v_cvt_pk_bf16_f32 v44, v188, v189
	v_cvt_pk_bf16_f32 v45, v190, v191
	v_add_u32_e32 v74, 0x6000, v72
	v_cvt_pk_bf16_f32 v30, v78, v79
	v_cvt_pk_bf16_f32 v31, v80, v81
	v_cvt_pk_bf16_f32 v42, v14, v15
	v_cvt_pk_bf16_f32 v43, v16, v17
	v_cvt_pk_bf16_f32 v24, v82, v83
	v_cvt_pk_bf16_f32 v25, v84, v85
	v_cvt_pk_bf16_f32 v36, v86, v87
	v_cvt_pk_bf16_f32 v37, v88, v89
	v_add_u32_e32 v73, 0x8000, v72
	v_cvt_pk_bf16_f32 v22, v90, v91
	v_cvt_pk_bf16_f32 v23, v92, v93
	v_cvt_pk_bf16_f32 v34, v94, v95
	v_cvt_pk_bf16_f32 v35, v96, v97
	v_cvt_pk_bf16_f32 v16, v98, v99
	v_cvt_pk_bf16_f32 v17, v100, v101
	v_cvt_pk_bf16_f32 v28, v102, v103
	v_cvt_pk_bf16_f32 v29, v104, v105
	v_add_u32_e32 v71, 0xa000, v72
	v_cvt_pk_bf16_f32 v14, v106, v107
	v_cvt_pk_bf16_f32 v15, v108, v109
	v_cvt_pk_bf16_f32 v26, v110, v111
	v_cvt_pk_bf16_f32 v27, v112, v113
	v_cvt_pk_bf16_f32 v8, v114, v115
	v_cvt_pk_bf16_f32 v9, v116, v117
	v_cvt_pk_bf16_f32 v20, v118, v119
	v_cvt_pk_bf16_f32 v21, v120, v121
	v_add_u32_e32 v70, 0xc000, v72
	v_cvt_pk_bf16_f32 v6, v122, v123
	v_cvt_pk_bf16_f32 v7, v124, v125
	v_cvt_pk_bf16_f32 v18, v126, v127
	v_cvt_pk_bf16_f32 v19, v128, v129
	v_cvt_pk_bf16_f32 v4, v130, v131
	v_cvt_pk_bf16_f32 v5, v132, v133
	v_cvt_pk_bf16_f32 v12, v134, v135
	v_cvt_pk_bf16_f32 v13, v136, v137
	v_add_u32_e32 v69, 0xe000, v72
	v_cvt_pk_bf16_f32 v2, v138, v139
	v_cvt_pk_bf16_f32 v3, v140, v141
	v_cvt_pk_bf16_f32 v10, v142, v143
	v_cvt_pk_bf16_f32 v11, v144, v145
	s_and_saveexec_b64 s[2:3], vcc
	s_cbranch_execz .LBB0_137
	ds_write2_b64 v72, v[60:61], v[64:65] offset1:4
	ds_write2_b64 v72, v[54:55], v[62:63] offset0:8 offset1:12
	ds_write2_b64 v76, v[48:49], v[58:59] offset0:32 offset1:36
	ds_write2_b64 v76, v[46:47], v[56:57] offset0:40 offset1:44
	ds_write2_b64 v75, v[40:41], v[52:53] offset0:64 offset1:68
	ds_write2_b64 v75, v[38:39], v[50:51] offset0:72 offset1:76
	ds_write2_b64 v74, v[32:33], v[44:45] offset0:96 offset1:100
	ds_write2_b64 v74, v[30:31], v[42:43] offset0:104 offset1:108
	ds_write2_b64 v73, v[24:25], v[36:37] offset0:128 offset1:132
	ds_write2_b64 v73, v[22:23], v[34:35] offset0:136 offset1:140
	ds_write2_b64 v71, v[16:17], v[28:29] offset0:160 offset1:164
	ds_write2_b64 v71, v[14:15], v[26:27] offset0:168 offset1:172
	ds_write2_b64 v70, v[8:9], v[20:21] offset0:192 offset1:196
	ds_write2_b64 v70, v[6:7], v[18:19] offset0:200 offset1:204
	ds_write2_b64 v69, v[4:5], v[12:13] offset0:224 offset1:228
	ds_write2_b64 v69, v[2:3], v[10:11] offset0:232 offset1:236

; DI int TID() { int t = threadIdx.x & 255; asm volatile("" : "+v"(t)); return t; }
; template <class AP, class BP>
; DI void gemm_accum(f32x4 (&acc)[4][4], AP ap, BP bp, int nkb, bf16_t* lds) {
;   const int tid = TID(), lane = tid & 63, w = tid >> 6;
;   const int wm = w >> 1, wn = w & 1;
;   const int lrow = tid >> 3, lch = tid & 7;
;   bf16_t* As = lds;
;   bf16_t* Bs = lds + 16384;
;   u32x4 ra0[4], rb0[4], ra1[4], rb1[4];
;   __syncthreads();
;   g_load(ra0, rb0, ap, bp, 0, lrow, lch);
;   g_load(ra1, rb1, ap, bp, 1, lrow, lch);
;   g_store(As, Bs, ra0, rb0, 0, lrow, lch);
;   __syncthreads();
;   for (int kb = 0; kb < nkb; kb += 2) {
;     const int k2 = (kb + 2 < nkb) ? kb + 2 : nkb - 2;
;     g_load(ra0, rb0, ap, bp, k2, lrow, lch);
;     __builtin_amdgcn_sched_barrier(0);
;     g_compute(acc, As, Bs, wm, wn, lane);
; __global__ void __launch_bounds__(512, 2) mega(Params p) {
;     ...
;         const int idx = t - 128;
;         const int c = idx & 63, bh = idx >> 6;
;         const bf16_t* rvT = (const bf16_t*)(p.ws + O_RVT) + ((size_t)bh * 128) * TS + c * 128;
;         const bf16_t* kzT = (const bf16_t*)(p.ws + O_KZT) + ((size_t)bh * 128) * TS + c * 128;
;         gemm_accum(acc, RowPtr{rvT, TS}, RowPtr{kzT, TS}, 2, lds);
.LBB0_265:
	s_lshl_b32 s2, s5, 1
	s_lshr_b32 s7, s7, 8
	s_add_i32 s20, s7, s2
	s_cmpk_gt_i32 s20, 0x7f
	s_mov_b64 s[2:3], -1
	s_cbranch_scc0 .LBB0_267
	s_add_i32 s2, s20, 0xffffff80
	s_lshr_b32 s3, s2, 6
	s_mul_hi_u32 s9, s3, 0x204000
	s_mul_i32 s21, s3, 0x204000
	v_readlane_b32 s3, v252, 30
	s_add_u32 s12, s3, s21
	v_readlane_b32 s3, v252, 31
	s_addc_u32 s13, s3, s9
	s_lshl_b32 s3, s20, 7
	s_and_b32 s3, s3, 0x1f80
	s_lshl_b32 s24, s3, 1
	s_add_u32 s12, s12, s24
	s_addc_u32 s13, s13, 0
	v_readlane_b32 s26, v252, 26
	v_readlane_b32 s27, v252, 27
	s_add_u32 s21, s26, s21
	v_and_b32_e32 v171, 0xff, v196
	s_addc_u32 s9, s27, s9
	v_mov_b32_e32 v82, v171
	s_add_u32 s24, s21, s24
	s_addc_u32 s25, s9, 0
	v_lshlrev_b32_e32 v0, 4, v82
	v_ashrrev_i32_e32 v34, 3, v82
	v_and_b32_e32 v0, 0x70, v0
	v_lshl_add_u64 v[22:23], s[12:13], 0, v[0:1]
	v_lshl_add_u64 v[30:31], s[24:25], 0, v[0:1]
	s_movk_i32 s9, 0x4080
	v_add_u32_e32 v0, 32, v34
	v_mad_i64_i32 v[70:71], s[12:13], v0, s9, v[22:23]
	v_mad_i64_i32 v[72:73], s[12:13], v0, s9, v[30:31]
	v_add_u32_e32 v0, 64, v34
	v_mad_i64_i32 v[74:75], s[12:13], v0, s9, v[22:23]
	v_mad_i64_i32 v[76:77], s[12:13], v0, s9, v[30:31]
	v_add_u32_e32 v0, 0x60, v34
	v_mad_i64_i32 v[66:67], s[12:13], v34, s9, v[22:23]
	v_mad_i64_i32 v[68:69], s[12:13], v34, s9, v[30:31]
	v_mad_i64_i32 v[78:79], s[12:13], v0, s9, v[22:23]
	s_barrier
	global_load_dwordx4 v[2:5], v[66:67], off
	global_load_dwordx4 v[6:9], v[68:69], off
	global_load_dwordx4 v[10:13], v[70:71], off
	global_load_dwordx4 v[14:17], v[72:73], off
	global_load_dwordx4 v[18:21], v[74:75], off
	global_load_dwordx4 v[22:25], v[78:79], off
	global_load_dwordx4 v[26:29], v[76:77], off
	v_mad_i64_i32 v[80:81], s[12:13], v0, s9, v[30:31]
	global_load_dwordx4 v[30:33], v[80:81], off
	v_lshrrev_b32_e32 v0, 1, v34
	v_xor_b32_e32 v0, v0, v82
	v_lshlrev_b32_e32 v0, 4, v0
	v_and_b32_e32 v0, 0x70, v0
	v_lshl_or_b32 v0, v34, 7, v0
	v_add_u32_e32 v0, s97, v0
	global_load_dwordx4 v[34:37], v[66:67], off offset:128
	global_load_dwordx4 v[38:41], v[70:71], off offset:128
	global_load_dwordx4 v[42:45], v[74:75], off offset:128
	global_load_dwordx4 v[46:49], v[78:79], off offset:128
	global_load_dwordx4 v[50:53], v[68:69], off offset:128
	global_load_dwordx4 v[54:57], v[72:73], off offset:128
	global_load_dwordx4 v[58:61], v[76:77], off offset:128
	global_load_dwordx4 v[62:65], v[80:81], off offset:128
	s_mov_b32 s9, 0x1ffffc0
	s_waitcnt vmcnt(15)
	ds_write_b128 v0, v[2:5]
	s_waitcnt vmcnt(13)
	ds_write_b128 v0, v[10:13] offset:4096
	s_waitcnt vmcnt(11)
	ds_write_b128 v0, v[18:21] offset:8192
	s_waitcnt vmcnt(10)
	ds_write_b128 v0, v[22:25] offset:12288
	ds_write_b128 v0, v[6:9] offset:32768
	ds_write_b128 v0, v[14:17] offset:36864
	s_waitcnt vmcnt(9)
	ds_write_b128 v0, v[26:29] offset:40960
	s_waitcnt vmcnt(8)
	ds_write_b128 v0, v[30:33] offset:45056
	s_waitcnt lgkmcnt(0)
	s_barrier
	global_load_dwordx4 v[2:5], v[66:67], off
	global_load_dwordx4 v[6:9], v[68:69], off
	global_load_dwordx4 v[10:13], v[70:71], off
	global_load_dwordx4 v[14:17], v[72:73], off
	global_load_dwordx4 v[18:21], v[74:75], off
	global_load_dwordx4 v[22:25], v[76:77], off
	global_load_dwordx4 v[26:29], v[78:79], off
	global_load_dwordx4 v[30:33], v[80:81], off
	v_and_b32_e32 v66, 15, v82
	v_lshrrev_b32_e32 v67, 1, v82
	v_and_or_b32 v66, v67, s9, v66
	v_lshrrev_b32_e32 v67, 4, v82
	v_bfe_u32 v69, v82, 1, 3
	v_bitop3_b32 v67, v67, v69, 3 bitop3:0x6c
	v_lshlrev_b32_e32 v70, 7, v82
	v_bfe_u32 v68, v82, 4, 2
	v_lshl_add_u32 v67, v67, 4, s97
	v_lshlrev_b32_e32 v66, 7, v66
	v_and_b32_e32 v70, 0x2780, v70
	v_add_u32_e32 v163, v67, v66
	v_add_u32_e32 v168, v67, v70
	v_bitop3_b32 v67, v68, v69, 4 bitop3:0x36
	v_lshl_add_u32 v67, v67, 4, s97
	v_add_u32_e32 v169, v67, v66
	v_add_u32_e32 v170, v67, v70
	ds_read_b128 v[66:69], v163
	ds_read_b128 v[70:73], v163 offset:2048
	ds_read_b128 v[74:77], v168 offset:32768
	ds_read_b128 v[78:81], v168 offset:34816
	ds_read_b128 v[82:85], v163 offset:4096
	ds_read_b128 v[86:89], v163 offset:6144
	ds_read_b128 v[90:93], v168 offset:36864
	ds_read_b128 v[94:97], v168 offset:38912
	ds_read_b128 v[98:101], v169
	ds_read_b128 v[102:105], v169 offset:2048
	ds_read_b128 v[106:109], v170 offset:32768
	ds_read_b128 v[110:113], v170 offset:34816
	ds_read_b128 v[114:117], v169 offset:4096
	ds_read_b128 v[118:121], v169 offset:6144
	ds_read_b128 v[122:125], v170 offset:36864
	ds_read_b128 v[126:129], v170 offset:38912
	s_waitcnt lgkmcnt(13)
	v_mfma_f32_16x16x32_bf16 v[130:133], v[74:77], v[66:69], 0
	s_waitcnt lgkmcnt(12)
	v_mfma_f32_16x16x32_bf16 v[134:137], v[78:81], v[66:69], 0
	s_waitcnt lgkmcnt(9)
	v_mfma_f32_16x16x32_bf16 v[138:141], v[90:93], v[66:69], 0
	s_waitcnt lgkmcnt(8)
	v_mfma_f32_16x16x32_bf16 v[66:69], v[94:97], v[66:69], 0
	v_mfma_f32_16x16x32_bf16 v[142:145], v[74:77], v[70:73], 0
	v_mfma_f32_16x16x32_bf16 v[146:149], v[78:81], v[70:73], 0
	v_mfma_f32_16x16x32_bf16 v[150:153], v[90:93], v[70:73], 0
	v_mfma_f32_16x16x32_bf16 v[70:73], v[94:97], v[70:73], 0
	v_mfma_f32_16x16x32_bf16 v[154:157], v[74:77], v[82:85], 0
	v_mfma_f32_16x16x32_bf16 v[158:161], v[78:81], v[82:85], 0
	v_mfma_f32_16x16x32_bf16 v[164:167], v[90:93], v[82:85], 0
	v_mfma_f32_16x16x32_bf16 v[82:85], v[94:97], v[82:85], 0
	v_mfma_f32_16x16x32_bf16 v[74:77], v[74:77], v[86:89], 0
	v_mfma_f32_16x16x32_bf16 v[78:81], v[78:81], v[86:89], 0
	v_mfma_f32_16x16x32_bf16 v[90:93], v[90:93], v[86:89], 0
	v_mfma_f32_16x16x32_bf16 v[86:89], v[94:97], v[86:89], 0
	s_waitcnt lgkmcnt(5)
	v_mfma_f32_16x16x32_bf16 v[94:97], v[106:109], v[98:101], v[130:133]
	s_waitcnt lgkmcnt(4)
	v_mfma_f32_16x16x32_bf16 v[130:133], v[110:113], v[98:101], v[134:137]
	s_waitcnt lgkmcnt(1)
; template <class AP, class BP>
; DI void gemm_accum(f32x4 (&acc)[4][4], AP ap, BP bp, int nkb, bf16_t* lds) {
;     ...
;   for (int kb = 0; kb < nkb; kb += 2) {
;     const int k2 = (kb + 2 < nkb) ? kb + 2 : nkb - 2;
;     g_load(ra0, rb0, ap, bp, k2, lrow, lch);
;     __builtin_amdgcn_sched_barrier(0);
;     g_compute(acc, As, Bs, wm, wn, lane);
;     g_store(As, Bs, ra1, rb1, 1, lrow, lch);
;     __syncthreads();
;     g_load(ra1, rb1, ap, bp, k2 + 1, lrow, lch);
;     __builtin_amdgcn_sched_barrier(0);
;     g_compute(acc, As + 8192, Bs + 8192, wm, wn, lane);
;     g_store(As, Bs, ra0, rb0, 0, lrow, lch);
;     __syncthreads();
	v_mfma_f32_16x16x32_bf16 v[134:137], v[122:125], v[98:101], v[138:141]
	s_waitcnt lgkmcnt(0)
	v_mfma_f32_16x16x32_bf16 v[66:69], v[126:129], v[98:101], v[66:69]
	v_mfma_f32_16x16x32_bf16 v[98:101], v[106:109], v[102:105], v[142:145]
	v_mfma_f32_16x16x32_bf16 v[138:141], v[110:113], v[102:105], v[146:149]
	v_mfma_f32_16x16x32_bf16 v[142:145], v[122:125], v[102:105], v[150:153]
	v_mfma_f32_16x16x32_bf16 v[70:73], v[126:129], v[102:105], v[70:73]
	v_mfma_f32_16x16x32_bf16 v[102:105], v[106:109], v[114:117], v[154:157]
	v_mfma_f32_16x16x32_bf16 v[146:149], v[110:113], v[114:117], v[158:161]
	v_mfma_f32_16x16x32_bf16 v[150:153], v[122:125], v[114:117], v[164:167]
	v_mfma_f32_16x16x32_bf16 v[82:85], v[126:129], v[114:117], v[82:85]
	v_mfma_f32_16x16x32_bf16 v[74:77], v[106:109], v[118:121], v[74:77]
	v_mfma_f32_16x16x32_bf16 v[78:81], v[110:113], v[118:121], v[78:81]
	v_mfma_f32_16x16x32_bf16 v[90:93], v[122:125], v[118:121], v[90:93]
	v_mfma_f32_16x16x32_bf16 v[86:89], v[126:129], v[118:121], v[86:89]
	s_waitcnt vmcnt(15)
	ds_write_b128 v0, v[34:37] offset:16384
	s_waitcnt vmcnt(11)
	ds_write_b128 v0, v[50:53] offset:49152
	ds_write_b128 v0, v[38:41] offset:20480
	s_waitcnt vmcnt(10)
	ds_write_b128 v0, v[54:57] offset:53248
	ds_write_b128 v0, v[42:45] offset:24576
	s_waitcnt vmcnt(9)
	ds_write_b128 v0, v[58:61] offset:57344
	ds_write_b128 v0, v[46:49] offset:28672
	s_waitcnt vmcnt(8)
	ds_write_b128 v0, v[62:65] offset:61440
	s_waitcnt lgkmcnt(0)
	s_barrier
	ds_read_b128 v[34:37], v163 offset:16384
	ds_read_b128 v[38:41], v163 offset:18432
	ds_read_b128 v[42:45], v168 offset:49152
	ds_read_b128 v[46:49], v168 offset:51200
	ds_read_b128 v[50:53], v163 offset:20480
	ds_read_b128 v[54:57], v163 offset:22528
	ds_read_b128 v[58:61], v168 offset:53248
	ds_read_b128 v[62:65], v168 offset:55296
	ds_read_b128 v[106:109], v169 offset:16384
	ds_read_b128 v[110:113], v169 offset:18432
	ds_read_b128 v[114:117], v170 offset:49152
	ds_read_b128 v[118:121], v170 offset:51200
	ds_read_b128 v[122:125], v169 offset:20480
	ds_read_b128 v[126:129], v169 offset:22528
	ds_read_b128 v[154:157], v170 offset:53248
	ds_read_b128 v[158:161], v170 offset:55296
	s_waitcnt lgkmcnt(13)
	v_mfma_f32_16x16x32_bf16 v[94:97], v[42:45], v[34:37], v[94:97]
	s_waitcnt lgkmcnt(12)
	v_mfma_f32_16x16x32_bf16 v[130:133], v[46:49], v[34:37], v[130:133]
	s_waitcnt lgkmcnt(9)
	v_mfma_f32_16x16x32_bf16 v[134:137], v[58:61], v[34:37], v[134:137]
	s_waitcnt lgkmcnt(8)
	v_mfma_f32_16x16x32_bf16 v[34:37], v[62:65], v[34:37], v[66:69]
	v_mfma_f32_16x16x32_bf16 v[66:69], v[42:45], v[38:41], v[98:101]
	v_mfma_f32_16x16x32_bf16 v[98:101], v[46:49], v[38:41], v[138:141]
	v_mfma_f32_16x16x32_bf16 v[138:141], v[58:61], v[38:41], v[142:145]
	v_mfma_f32_16x16x32_bf16 v[38:41], v[62:65], v[38:41], v[70:73]
	v_mfma_f32_16x16x32_bf16 v[70:73], v[42:45], v[50:53], v[102:105]
	v_mfma_f32_16x16x32_bf16 v[102:105], v[46:49], v[50:53], v[146:149]
	v_mfma_f32_16x16x32_bf16 v[142:145], v[58:61], v[50:53], v[150:153]
	v_mfma_f32_16x16x32_bf16 v[50:53], v[62:65], v[50:53], v[82:85]
	v_mfma_f32_16x16x32_bf16 v[42:45], v[42:45], v[54:57], v[74:77]
	v_mfma_f32_16x16x32_bf16 v[46:49], v[46:49], v[54:57], v[78:81]
	v_mfma_f32_16x16x32_bf16 v[58:61], v[58:61], v[54:57], v[90:93]
	v_mfma_f32_16x16x32_bf16 v[54:57], v[62:65], v[54:57], v[86:89]
	s_waitcnt lgkmcnt(5)
	v_mfma_f32_16x16x32_bf16 v[62:65], v[114:117], v[106:109], v[94:97]
	s_waitcnt lgkmcnt(4)
	v_mfma_f32_16x16x32_bf16 v[74:77], v[118:121], v[106:109], v[130:133]
	s_waitcnt lgkmcnt(1)
	v_mfma_f32_16x16x32_bf16 v[78:81], v[154:157], v[106:109], v[134:137]
	s_waitcnt lgkmcnt(0)
	v_mfma_f32_16x16x32_bf16 v[34:37], v[158:161], v[106:109], v[34:37]
	v_mfma_f32_16x16x32_bf16 v[66:69], v[114:117], v[110:113], v[66:69]
	v_mfma_f32_16x16x32_bf16 v[82:85], v[118:121], v[110:113], v[98:101]
	v_mfma_f32_16x16x32_bf16 v[86:89], v[154:157], v[110:113], v[138:141]
	v_mfma_f32_16x16x32_bf16 v[38:41], v[158:161], v[110:113], v[38:41]
	v_mfma_f32_16x16x32_bf16 v[70:73], v[114:117], v[122:125], v[70:73]
	v_mfma_f32_16x16x32_bf16 v[90:93], v[118:121], v[122:125], v[102:105]
	v_mfma_f32_16x16x32_bf16 v[94:97], v[154:157], v[122:125], v[142:145]
	v_mfma_f32_16x16x32_bf16 v[50:53], v[158:161], v[122:125], v[50:53]
	v_mfma_f32_16x16x32_bf16 v[42:45], v[114:117], v[126:129], v[42:45]
	v_mfma_f32_16x16x32_bf16 v[46:49], v[118:121], v[126:129], v[46:49]
	v_mfma_f32_16x16x32_bf16 v[58:61], v[154:157], v[126:129], v[58:61]
	v_mfma_f32_16x16x32_bf16 v[54:57], v[158:161], v[126:129], v[54:57]
	s_lshl_b32 s9, s2, 5
	s_and_b32 s9, s9, 0x7fffe000
	s_or_b32 s3, s9, s3
	s_mul_hi_u32 s9, s3, 0x2a30
	s_mulk_i32 s3, 0x2a30
	s_add_u32 s3, s16, s3
	s_addc_u32 s9, s17, s9
	s_lshl_b32 s2, s2, 2
	s_and_b32 s2, s2, 0x300
	s_waitcnt vmcnt(7)
	ds_write_b128 v0, v[2:5]
	s_waitcnt vmcnt(6)
	ds_write_b128 v0, v[6:9] offset:32768
	s_waitcnt vmcnt(5)
	ds_write_b128 v0, v[10:13] offset:4096
	s_waitcnt vmcnt(4)
	ds_write_b128 v0, v[14:17] offset:36864
	s_waitcnt vmcnt(3)
	ds_write_b128 v0, v[18:21] offset:8192
	s_waitcnt vmcnt(2)
	ds_write_b128 v0, v[22:25] offset:40960
	s_waitcnt vmcnt(1)
	ds_write_b128 v0, v[26:29] offset:12288
	s_waitcnt vmcnt(0)
	ds_write_b128 v0, v[30:33] offset:45056
	s_add_u32 s2, s3, s2
	v_mov_b32_e32 v11, v171
	s_waitcnt lgkmcnt(0)
	s_barrier
; DI int TID() { int t = threadIdx.x & 255; asm volatile("" : "+v"(t)); return t; }
; template <class F>
; DI void gemm_epi_staged(f32x4 (&acc)[4][4], int m0, int n0, bf16_t* lds, F f, bf16_t* dst, size_t ld, int nmax) {
;   const int tid_ = TID();
;   const int lane = tid_ & 63, w = tid_ >> 6;
;   const int wm = w >> 1, wn = w & 1;
; #pragma unroll
;   for (int i = 0; i < 4; ++i)
; #pragma unroll
;     for (int j = 0; j < 4; ++j) {
;       const int ml = wm * 64 + i * 16 + (lane & 15);
;       const int nl = wn * 64 + j * 16 + (lane >> 4) * 4;
;       f32x4 a = acc[i][j];
;       f(m0 + ml, n0 + nl, a);
;       uint2 u;
;       u.x = pack2(a[0], a[1]);
;       u.y = pack2(a[2], a[3]);
;       *(uint2*)(lds + ml * 136 + nl) = u;
;     }
;   __syncthreads();
; #pragma unroll
;   for (int it = 0; it < 8; ++it) {
;     const int idx = tid_ + 256 * it;
;     const int row = idx >> 4, ch = idx & 15;
;     const u32x4 v = *(const u32x4*)(lds + row * 136 + ch * 8);
;     const int n = n0 + ch * 8;
;     if (n < nmax) *(u32x4*)(dst + (size_t)(m0 + row) * ld + n) = v;
;   }
	s_addc_u32 s3, s9, 0
	s_mov_b32 s9, 0xfffffc0
	v_lshrrev_b32_e32 v2, 1, v11
	v_and_b32_e32 v3, 15, v11
	v_and_b32_e32 v0, 64, v11
	v_and_or_b32 v2, v2, s9, v3
	v_lshrrev_b32_e32 v3, 2, v11
	v_and_or_b32 v0, v3, 12, v0
	s_movk_i32 s12, 0x110
	v_mul_lo_u32 v4, v2, s12
	v_lshlrev_b32_e32 v0, 1, v0
	v_cvt_pk_bf16_f32 v2, v62, v63
	v_cvt_pk_bf16_f32 v3, v64, v65
	v_add3_u32 v0, s97, v4, v0
	v_cvt_pk_bf16_f32 v4, v74, v75
	v_cvt_pk_bf16_f32 v5, v76, v77
	ds_write2_b64 v0, v[2:3], v[4:5] offset1:4
	v_cvt_pk_bf16_f32 v2, v78, v79
	v_cvt_pk_bf16_f32 v3, v80, v81
	v_cvt_pk_bf16_f32 v4, v34, v35
	v_cvt_pk_bf16_f32 v5, v36, v37
	ds_write2_b64 v0, v[2:3], v[4:5] offset0:8 offset1:12
	v_cvt_pk_bf16_f32 v2, v66, v67
	v_cvt_pk_bf16_f32 v3, v68, v69
	v_cvt_pk_bf16_f32 v4, v82, v83
	v_cvt_pk_bf16_f32 v5, v84, v85
	v_add_u32_e32 v6, 0x1000, v0
	ds_write2_b64 v6, v[2:3], v[4:5] offset0:32 offset1:36
	v_cvt_pk_bf16_f32 v2, v86, v87
	v_cvt_pk_bf16_f32 v3, v88, v89
	v_cvt_pk_bf16_f32 v4, v38, v39
	v_cvt_pk_bf16_f32 v5, v40, v41
	ds_write2_b64 v6, v[2:3], v[4:5] offset0:40 offset1:44
	v_cvt_pk_bf16_f32 v2, v70, v71
	v_cvt_pk_bf16_f32 v3, v72, v73
	v_cvt_pk_bf16_f32 v4, v90, v91
	v_cvt_pk_bf16_f32 v5, v92, v93
	v_add_u32_e32 v6, 0x2000, v0
	ds_write2_b64 v6, v[2:3], v[4:5] offset0:64 offset1:68
	v_cvt_pk_bf16_f32 v2, v94, v95
	v_cvt_pk_bf16_f32 v3, v96, v97
	v_cvt_pk_bf16_f32 v4, v50, v51
	v_cvt_pk_bf16_f32 v5, v52, v53
	ds_write2_b64 v6, v[2:3], v[4:5] offset0:72 offset1:76
	v_cvt_pk_bf16_f32 v2, v42, v43
	v_cvt_pk_bf16_f32 v3, v44, v45
	v_cvt_pk_bf16_f32 v4, v46, v47
	v_cvt_pk_bf16_f32 v5, v48, v49
	v_add_u32_e32 v0, 0x3000, v0
	ds_write2_b64 v0, v[2:3], v[4:5] offset0:96 offset1:100
	v_cvt_pk_bf16_f32 v2, v58, v59
	v_cvt_pk_bf16_f32 v3, v60, v61
	v_cvt_pk_bf16_f32 v4, v54, v55
	v_cvt_pk_bf16_f32 v5, v56, v57
	ds_write2_b64 v0, v[2:3], v[4:5] offset0:104 offset1:108
	v_lshlrev_b32_e32 v0, 4, v11
	v_and_b32_e32 v0, 0xf0, v0
	v_add_u32_e32 v10, s97, v0
	v_lshl_add_u64 v[2:3], s[2:3], 0, v[0:1]
	s_mov_b64 s[2:3], 0x1230
	v_ashrrev_i32_e32 v0, 4, v11
	v_add_u32_e32 v6, 0x100, v11
	v_lshl_add_u64 v[12:13], v[2:3], 0, s[2:3]
	v_mad_u64_u32 v[2:3], s[2:3], v0, s12, v[10:11]
	v_ashrrev_i32_e32 v16, 4, v6
	s_waitcnt lgkmcnt(0)
	s_barrier
	ds_read_b128 v[2:5], v2
	v_mad_u64_u32 v[6:7], s[2:3], v16, s12, v[10:11]
	ds_read_b128 v[6:9], v6
	v_mad_i64_i32 v[14:15], s[2:3], v0, s35, v[12:13]
	s_waitcnt lgkmcnt(1)
	global_store_dwordx4 v[14:15], v[2:5], off
	v_add_u32_e32 v0, 0x200, v11
	v_ashrrev_i32_e32 v0, 4, v0
	v_mad_i64_i32 v[2:3], s[2:3], v16, s35, v[12:13]
	s_waitcnt lgkmcnt(0)
	global_store_dwordx4 v[2:3], v[6:9], off
	v_mad_u64_u32 v[2:3], s[2:3], v0, s12, v[10:11]
	s_nop 0
	v_add_u32_e32 v6, 0x300, v11
	v_ashrrev_i32_e32 v16, 4, v6
	ds_read_b128 v[2:5], v2
	v_mad_u64_u32 v[6:7], s[2:3], v16, s12, v[10:11]
	ds_read_b128 v[6:9], v6
	v_mad_i64_i32 v[14:15], s[2:3], v0, s35, v[12:13]
	s_waitcnt lgkmcnt(1)
	global_store_dwordx4 v[14:15], v[2:5], off
	v_add_u32_e32 v0, 0x400, v11
	v_ashrrev_i32_e32 v0, 4, v0
	v_mad_i64_i32 v[2:3], s[2:3], v16, s35, v[12:13]
	s_waitcnt lgkmcnt(0)
	global_store_dwordx4 v[2:3], v[6:9], off
	v_mad_u64_u32 v[2:3], s[2:3], v0, s12, v[10:11]
	s_nop 0
	v_add_u32_e32 v6, 0x500, v11
	v_ashrrev_i32_e32 v16, 4, v6
	ds_read_b128 v[2:5], v2
	v_mad_u64_u32 v[6:7], s[2:3], v16, s12, v[10:11]
	ds_read_b128 v[6:9], v6
	v_mad_i64_i32 v[14:15], s[2:3], v0, s35, v[12:13]
	s_waitcnt lgkmcnt(1)
	global_store_dwordx4 v[14:15], v[2:5], off
	v_add_u32_e32 v0, 0x600, v11
	v_ashrrev_i32_e32 v0, 4, v0
	v_mad_i64_i32 v[2:3], s[2:3], v16, s35, v[12:13]
	s_waitcnt lgkmcnt(0)
	global_store_dwordx4 v[2:3], v[6:9], off
	v_mad_u64_u32 v[2:3], s[2:3], v0, s12, v[10:11]
	s_nop 0
	v_add_u32_e32 v6, 0x700, v11
	v_ashrrev_i32_e32 v14, 4, v6
	ds_read_b128 v[2:5], v2
	v_mad_u64_u32 v[6:7], s[2:3], v14, s12, v[10:11]
	ds_read_b128 v[6:9], v6
	v_mad_i64_i32 v[10:11], s[2:3], v0, s35, v[12:13]
	s_waitcnt lgkmcnt(1)
	global_store_dwordx4 v[10:11], v[2:5], off
	s_mov_b32 s9, 0x800000
	s_nop 0
	v_mad_i64_i32 v[2:3], s[2:3], v14, s35, v[12:13]
	s_waitcnt lgkmcnt(0)
	global_store_dwordx4 v[2:3], v[6:9], off
	s_mov_b64 s[2:3], 0

; template <class AP, class BP>
; DI void gemm_accum(f32x4 (&acc)[4][4], AP ap, BP bp, int nkb, bf16_t* lds) {
;     ...
;   for (int kb = 0; kb < nkb; kb += 2) {
;     const int k2 = (kb + 2 < nkb) ? kb + 2 : nkb - 2;
;     g_load(ra0, rb0, ap, bp, k2, lrow, lch);
;     __builtin_amdgcn_sched_barrier(0);
;     g_compute(acc, As, Bs, wm, wn, lane);
;     g_store(As, Bs, ra1, rb1, 1, lrow, lch);
;     __syncthreads();
;     g_load(ra1, rb1, ap, bp, k2 + 1, lrow, lch);
;     __builtin_amdgcn_sched_barrier(0);
; __global__ void __launch_bounds__(512, 2) mega(Params p) {
;     ...
;         auto ap = [&](int r, int kb) -> const bf16_t* {
;           int row = m0 + r;
;           int bg = row >> 9, c = row & 511;
;           int tk = 16 * c + kb;
;           tk = tk > (SEQ - 1) ? (SEQ - 1) : tk;
;           return kvd + ((size_t)(bg * SEQ + tk)) * 64;
;         };
.LBB0_269:
	s_add_i32 s12, s20, 2
	s_cmp_lt_u32 s20, 30
	s_cselect_b64 s[20:21], -1, 0
	s_and_b64 vcc, s[20:21], exec
	s_cselect_b32 s13, s12, 30
	v_add_u32_e32 v98, s13, v131
	v_add_u32_e32 v106, s13, v0
	v_add_u32_e32 v138, s13, v134
	v_add_u32_e32 v148, s13, v136
	v_min_u32_e32 v98, 0x1fff, v98
	v_min_u32_e32 v106, 0x1fff, v106
	v_min_u32_e32 v138, 0x1fff, v138
	v_min_u32_e32 v148, 0x1fff, v148
	v_or_b32_e32 v98, v98, v132
	v_or_b32_e32 v106, v106, v133
	v_or_b32_e32 v138, v138, v135
	v_or_b32_e32 v148, v148, v137
	s_lshl_b32 s28, s13, 7
	v_ashrrev_i32_e32 v99, 31, v98
	v_ashrrev_i32_e32 v107, 31, v106
	v_ashrrev_i32_e32 v139, 31, v138
	v_ashrrev_i32_e32 v149, 31, v148
	v_lshl_add_u64 v[146:147], v[114:115], 0, s[28:29]
	v_lshlrev_b64 v[98:99], 7, v[98:99]
	v_lshlrev_b64 v[106:107], 7, v[106:107]
	v_lshlrev_b64 v[138:139], 7, v[138:139]
	v_lshlrev_b64 v[148:149], 7, v[148:149]
	v_lshl_add_u64 v[98:99], v[116:117], 0, v[98:99]
	v_lshl_add_u64 v[102:103], v[146:147], 0, v[118:119]
	v_lshl_add_u64 v[106:107], v[116:117], 0, v[106:107]
	v_lshl_add_u64 v[110:111], v[146:147], 0, v[120:121]
	v_lshl_add_u64 v[138:139], v[116:117], 0, v[138:139]
	v_lshl_add_u64 v[142:143], v[146:147], 0, v[122:123]
	v_lshl_add_u64 v[148:149], v[116:117], 0, v[148:149]
	v_lshl_add_u64 v[150:151], v[146:147], 0, v[124:125]
	global_load_dwordx4 v[98:101], v[98:99], off
	s_nop 0
	global_load_dwordx4 v[102:105], v[102:103], off
	s_nop 0
	global_load_dwordx4 v[106:109], v[106:107], off
	s_nop 0
	global_load_dwordx4 v[110:113], v[110:111], off
	s_nop 0
	global_load_dwordx4 v[138:141], v[138:139], off
	s_nop 0
	global_load_dwordx4 v[142:145], v[142:143], off
	s_nop 0
	global_load_dwordx4 v[146:149], v[148:149], off
	s_nop 0
	global_load_dwordx4 v[150:153], v[150:151], off
	ds_read_b128 v[154:157], v127
	ds_read_b128 v[158:161], v127 offset:2048
	ds_read_b128 v[164:167], v128 offset:32768
	ds_read_b128 v[168:171], v128 offset:34816
	ds_read_b128 v[172:175], v127 offset:4096
	ds_read_b128 v[176:179], v127 offset:6144
	ds_read_b128 v[180:183], v128 offset:36864
	ds_read_b128 v[184:187], v128 offset:38912
	ds_read_b128 v[188:191], v129
	ds_read_b128 v[192:195], v129 offset:2048
	ds_read_b128 v[206:209], v130 offset:32768
	ds_read_b128 v[210:213], v130 offset:34816
	ds_read_b128 v[214:217], v129 offset:4096
	ds_read_b128 v[218:221], v129 offset:6144
	ds_read_b128 v[222:225], v130 offset:36864
	ds_read_b128 v[226:229], v130 offset:38912
	s_waitcnt lgkmcnt(13)
	v_mfma_f32_16x16x32_bf16 v[94:97], v[164:167], v[154:157], v[94:97]
	s_waitcnt lgkmcnt(12)
	v_mfma_f32_16x16x32_bf16 v[50:53], v[168:171], v[154:157], v[50:53]
	s_waitcnt lgkmcnt(9)
	v_mfma_f32_16x16x32_bf16 v[46:49], v[180:183], v[154:157], v[46:49]
	s_waitcnt lgkmcnt(8)
	v_mfma_f32_16x16x32_bf16 v[66:69], v[184:187], v[154:157], v[66:69]
	v_mfma_f32_16x16x32_bf16 v[62:65], v[164:167], v[158:161], v[62:65]
	v_mfma_f32_16x16x32_bf16 v[58:61], v[168:171], v[158:161], v[58:61]
	v_mfma_f32_16x16x32_bf16 v[54:57], v[180:183], v[158:161], v[54:57]
	v_mfma_f32_16x16x32_bf16 v[42:45], v[184:187], v[158:161], v[42:45]
	v_mfma_f32_16x16x32_bf16 v[34:37], v[164:167], v[172:175], v[34:37]
	v_mfma_f32_16x16x32_bf16 v[26:29], v[168:171], v[172:175], v[26:29]
	v_mfma_f32_16x16x32_bf16 v[22:25], v[180:183], v[172:175], v[22:25]
	v_mfma_f32_16x16x32_bf16 v[18:21], v[184:187], v[172:175], v[18:21]
	v_mfma_f32_16x16x32_bf16 v[14:17], v[164:167], v[176:179], v[14:17]
	v_mfma_f32_16x16x32_bf16 v[10:13], v[168:171], v[176:179], v[10:13]
	v_mfma_f32_16x16x32_bf16 v[6:9], v[180:183], v[176:179], v[6:9]
	v_mfma_f32_16x16x32_bf16 v[2:5], v[184:187], v[176:179], v[2:5]
	s_waitcnt lgkmcnt(5)
	v_mfma_f32_16x16x32_bf16 v[94:97], v[206:209], v[188:191], v[94:97]
	s_waitcnt lgkmcnt(4)
	v_mfma_f32_16x16x32_bf16 v[50:53], v[210:213], v[188:191], v[50:53]
	s_waitcnt lgkmcnt(1)
	v_mfma_f32_16x16x32_bf16 v[46:49], v[222:225], v[188:191], v[46:49]
	s_waitcnt lgkmcnt(0)
	v_mfma_f32_16x16x32_bf16 v[66:69], v[226:229], v[188:191], v[66:69]
	v_mfma_f32_16x16x32_bf16 v[62:65], v[206:209], v[192:195], v[62:65]
	v_mfma_f32_16x16x32_bf16 v[58:61], v[210:213], v[192:195], v[58:61]
	v_mfma_f32_16x16x32_bf16 v[54:57], v[222:225], v[192:195], v[54:57]
	v_mfma_f32_16x16x32_bf16 v[42:45], v[226:229], v[192:195], v[42:45]
	v_mfma_f32_16x16x32_bf16 v[34:37], v[206:209], v[214:217], v[34:37]
	v_mfma_f32_16x16x32_bf16 v[26:29], v[210:213], v[214:217], v[26:29]
	v_mfma_f32_16x16x32_bf16 v[22:25], v[222:225], v[214:217], v[22:25]
	v_mfma_f32_16x16x32_bf16 v[18:21], v[226:229], v[214:217], v[18:21]
	v_mfma_f32_16x16x32_bf16 v[14:17], v[206:209], v[218:221], v[14:17]
	v_mfma_f32_16x16x32_bf16 v[10:13], v[210:213], v[218:221], v[10:13]
	v_mfma_f32_16x16x32_bf16 v[6:9], v[222:225], v[218:221], v[6:9]
	v_mfma_f32_16x16x32_bf16 v[2:5], v[226:229], v[218:221], v[2:5]
	s_or_b32 s13, s13, 1
	s_waitcnt vmcnt(14)
	ds_write_b128 v126, v[30:33] offset:16384
	ds_write_b128 v126, v[38:41] offset:49152
	s_waitcnt vmcnt(13)
	ds_write_b128 v126, v[70:73] offset:20480
	s_waitcnt vmcnt(12)
	ds_write_b128 v126, v[74:77] offset:53248
	s_waitcnt vmcnt(10)
	ds_write_b128 v126, v[82:85] offset:24576
	ds_write_b128 v126, v[78:81] offset:57344
	s_waitcnt vmcnt(9)
	ds_write_b128 v126, v[86:89] offset:28672
	s_waitcnt vmcnt(8)
	ds_write_b128 v126, v[90:93] offset:61440
	v_add_u32_e32 v32, s13, v131
	v_add_u32_e32 v33, s13, v0
	v_add_u32_e32 v38, s13, v134
	v_add_u32_e32 v39, s13, v136
	v_min_u32_e32 v32, 0x1fff, v32
	v_min_u32_e32 v33, 0x1fff, v33
	v_min_u32_e32 v41, 0x1fff, v38
	v_min_u32_e32 v71, 0x1fff, v39
	s_lshl_b32 s28, s13, 7
	v_or_b32_e32 v32, v32, v132
	v_or_b32_e32 v40, v33, v133
	v_or_b32_e32 v70, v41, v135
	v_or_b32_e32 v72, v71, v137
	v_lshl_add_u64 v[30:31], v[114:115], 0, s[28:29]
	v_ashrrev_i32_e32 v33, 31, v32
	v_ashrrev_i32_e32 v41, 31, v40
	v_ashrrev_i32_e32 v71, 31, v70
	v_ashrrev_i32_e32 v73, 31, v72
	v_lshl_add_u64 v[38:39], v[30:31], 0, v[118:119]
	v_lshl_add_u64 v[74:75], v[30:31], 0, v[120:121]
	v_lshl_add_u64 v[78:79], v[30:31], 0, v[122:123]
	v_lshl_add_u64 v[90:91], v[30:31], 0, v[124:125]
	v_lshlrev_b64 v[30:31], 7, v[32:33]
	v_lshlrev_b64 v[32:33], 7, v[40:41]
	v_lshlrev_b64 v[40:41], 7, v[70:71]
	v_lshlrev_b64 v[70:71], 7, v[72:73]
	v_lshl_add_u64 v[30:31], v[116:117], 0, v[30:31]
	v_lshl_add_u64 v[72:73], v[116:117], 0, v[32:33]
	v_lshl_add_u64 v[80:81], v[116:117], 0, v[40:41]
	v_lshl_add_u64 v[86:87], v[116:117], 0, v[70:71]
	s_waitcnt lgkmcnt(0)
	s_barrier
; template <class AP, class BP>
; DI void gemm_accum(f32x4 (&acc)[4][4], AP ap, BP bp, int nkb, bf16_t* lds) {
;     ...
;     g_compute(acc, As, Bs, wm, wn, lane);
;     g_store(As, Bs, ra1, rb1, 1, lrow, lch);
;     __syncthreads();
;     g_load(ra1, rb1, ap, bp, k2 + 1, lrow, lch);
;     __builtin_amdgcn_sched_barrier(0);
;     g_compute(acc, As + 8192, Bs + 8192, wm, wn, lane);
;     g_store(As, Bs, ra0, rb0, 0, lrow, lch);
;     __syncthreads();
;   }
; __global__ void __launch_bounds__(512, 2) mega(Params p) {
;     ...
;         const float* bs = bias + kv * 256;
;         bf16_t* hd = hid + (size_t)kv * 4096 * 256;
;         gemm_epi(acc, m0, n0, [&](int m, int n, f32x4& a) {
;           float o[4];
; #pragma unroll
;           for (int j = 0; j < 4; ++j) {
;             float xv = a[j] + bs[n + j];
;             float y = 0.7978845608028654f * (xv + 0.044715f * xv * xv * xv);
;             float th = 1.f - 2.f * __builtin_amdgcn_rcpf(__expf(2.f * y) + 1.f);
;             o[j] = 0.5f * xv * (1.f + th);
;           }
;           uint2 u;
;           u.x = pack2(o[0], o[1]);
;           u.y = pack2(o[2], o[3]);
;           *(uint2*)(hd + (size_t)m * 256 + n) = u;
;         });
	global_load_dwordx4 v[30:33], v[30:31], off
	s_nop 0
	global_load_dwordx4 v[38:41], v[38:39], off
	s_nop 0
	global_load_dwordx4 v[70:73], v[72:73], off
	s_nop 0
	global_load_dwordx4 v[74:77], v[74:75], off
	s_nop 0
	global_load_dwordx4 v[82:85], v[80:81], off
	s_nop 0
	global_load_dwordx4 v[78:81], v[78:79], off
	s_nop 0
	global_load_dwordx4 v[86:89], v[86:87], off
	s_nop 0
	global_load_dwordx4 v[90:93], v[90:91], off
	ds_read_b128 v[154:157], v127 offset:16384
	ds_read_b128 v[158:161], v127 offset:18432
	ds_read_b128 v[164:167], v128 offset:49152
	ds_read_b128 v[168:171], v128 offset:51200
	ds_read_b128 v[172:175], v127 offset:20480
	ds_read_b128 v[176:179], v127 offset:22528
	ds_read_b128 v[180:183], v128 offset:53248
	ds_read_b128 v[184:187], v128 offset:55296
	ds_read_b128 v[188:191], v129 offset:16384
	ds_read_b128 v[192:195], v129 offset:18432
	ds_read_b128 v[206:209], v130 offset:49152
	ds_read_b128 v[210:213], v130 offset:51200
	ds_read_b128 v[214:217], v129 offset:20480
	ds_read_b128 v[218:221], v129 offset:22528
	ds_read_b128 v[222:225], v130 offset:53248
	ds_read_b128 v[226:229], v130 offset:55296
	s_waitcnt lgkmcnt(13)
	v_mfma_f32_16x16x32_bf16 v[94:97], v[164:167], v[154:157], v[94:97]
	s_waitcnt lgkmcnt(12)
	v_mfma_f32_16x16x32_bf16 v[50:53], v[168:171], v[154:157], v[50:53]
	s_waitcnt lgkmcnt(9)
	v_mfma_f32_16x16x32_bf16 v[46:49], v[180:183], v[154:157], v[46:49]
	s_waitcnt lgkmcnt(8)
	v_mfma_f32_16x16x32_bf16 v[66:69], v[184:187], v[154:157], v[66:69]
	v_mfma_f32_16x16x32_bf16 v[62:65], v[164:167], v[158:161], v[62:65]
	v_mfma_f32_16x16x32_bf16 v[58:61], v[168:171], v[158:161], v[58:61]
	v_mfma_f32_16x16x32_bf16 v[54:57], v[180:183], v[158:161], v[54:57]
	v_mfma_f32_16x16x32_bf16 v[42:45], v[184:187], v[158:161], v[42:45]
	v_mfma_f32_16x16x32_bf16 v[34:37], v[164:167], v[172:175], v[34:37]
	v_mfma_f32_16x16x32_bf16 v[26:29], v[168:171], v[172:175], v[26:29]
	v_mfma_f32_16x16x32_bf16 v[22:25], v[180:183], v[172:175], v[22:25]
	v_mfma_f32_16x16x32_bf16 v[18:21], v[184:187], v[172:175], v[18:21]
	v_mfma_f32_16x16x32_bf16 v[14:17], v[164:167], v[176:179], v[14:17]
	v_mfma_f32_16x16x32_bf16 v[10:13], v[168:171], v[176:179], v[10:13]
	v_mfma_f32_16x16x32_bf16 v[6:9], v[180:183], v[176:179], v[6:9]
	v_mfma_f32_16x16x32_bf16 v[2:5], v[184:187], v[176:179], v[2:5]
	s_waitcnt lgkmcnt(5)
	v_mfma_f32_16x16x32_bf16 v[94:97], v[206:209], v[188:191], v[94:97]
	s_waitcnt lgkmcnt(4)
	v_mfma_f32_16x16x32_bf16 v[50:53], v[210:213], v[188:191], v[50:53]
	s_waitcnt lgkmcnt(1)
	v_mfma_f32_16x16x32_bf16 v[46:49], v[222:225], v[188:191], v[46:49]
	s_waitcnt lgkmcnt(0)
	v_mfma_f32_16x16x32_bf16 v[66:69], v[226:229], v[188:191], v[66:69]
	v_mfma_f32_16x16x32_bf16 v[62:65], v[206:209], v[192:195], v[62:65]
	v_mfma_f32_16x16x32_bf16 v[58:61], v[210:213], v[192:195], v[58:61]
	v_mfma_f32_16x16x32_bf16 v[54:57], v[222:225], v[192:195], v[54:57]
	v_mfma_f32_16x16x32_bf16 v[42:45], v[226:229], v[192:195], v[42:45]
	v_mfma_f32_16x16x32_bf16 v[34:37], v[206:209], v[214:217], v[34:37]
	v_mfma_f32_16x16x32_bf16 v[26:29], v[210:213], v[214:217], v[26:29]
	v_mfma_f32_16x16x32_bf16 v[22:25], v[222:225], v[214:217], v[22:25]
	v_mfma_f32_16x16x32_bf16 v[18:21], v[226:229], v[214:217], v[18:21]
	v_mfma_f32_16x16x32_bf16 v[14:17], v[206:209], v[218:221], v[14:17]
	v_mfma_f32_16x16x32_bf16 v[10:13], v[210:213], v[218:221], v[10:13]
	v_mfma_f32_16x16x32_bf16 v[6:9], v[222:225], v[218:221], v[6:9]
	v_mfma_f32_16x16x32_bf16 v[2:5], v[226:229], v[218:221], v[2:5]
	s_mov_b32 s20, s12
	s_waitcnt vmcnt(15)
	ds_write_b128 v126, v[98:101]
	s_waitcnt vmcnt(14)
	ds_write_b128 v126, v[102:105] offset:32768
	s_waitcnt vmcnt(13)
	ds_write_b128 v126, v[106:109] offset:4096
	s_waitcnt vmcnt(12)
	ds_write_b128 v126, v[110:113] offset:36864
	s_waitcnt vmcnt(11)
	ds_write_b128 v126, v[138:141] offset:8192
	s_waitcnt vmcnt(10)
	ds_write_b128 v126, v[142:145] offset:40960
	s_waitcnt vmcnt(9)
	ds_write_b128 v126, v[146:149] offset:12288
	s_waitcnt vmcnt(8)
	ds_write_b128 v126, v[150:153] offset:45056
	s_waitcnt lgkmcnt(0)
	s_barrier
	s_cbranch_vccnz .LBB0_269
	v_and_b32_e32 v0, 0xff, v196
	s_lshl_b32 s12, s2, 8
	s_ashr_i32 s13, s12, 31
	s_waitcnt vmcnt(7)
	v_ashrrev_i32_e32 v31, 1, v0
	v_and_b32_e32 v30, 64, v0
	v_and_b32_e32 v31, 0xffffffc0, v31
	v_and_or_b32 v32, v0, 15, s9
	v_lshrrev_b32_e32 v0, 2, v0
	s_lshl_b64 s[12:13], s[12:13], 2
	v_readlane_b32 s20, v251, 53
	s_waitcnt vmcnt(5)
	v_add_u32_e32 v70, v32, v31
	v_and_b32_e32 v0, 12, v0
	v_readlane_b32 s21, v251, 54
	s_add_u32 s12, s20, s12
	v_or3_b32 v0, v30, v0, s7
	v_ashrrev_i32_e32 v71, 31, v70
	s_addc_u32 s13, s21, s13
	v_lshlrev_b64 v[40:41], 9, v[70:71]
	v_lshlrev_b32_e32 v71, 2, v0
	global_load_dwordx4 v[30:33], v71, s[12:13]
	s_lshl_b64 s[2:3], s[2:3], 21
	s_add_u32 s2, s44, s2
	s_addc_u32 s3, s45, s3
	v_lshl_add_u64 v[40:41], s[2:3], 0, v[40:41]
	v_lshlrev_b32_e32 v0, 1, v0
	s_mov_b32 s9, 0x800000
	s_waitcnt vmcnt(0)
; __global__ void __launch_bounds__(512, 2) mega(Params p) {
;     ...
;         gemm_epi(acc, m0, n0, [&](int m, int n, f32x4& a) {
;           float o[4];
; #pragma unroll
;           for (int j = 0; j < 4; ++j) {
;             float xv = a[j] + bs[n + j];
;             float y = 0.7978845608028654f * (xv + 0.044715f * xv * xv * xv);
;             float th = 1.f - 2.f * __builtin_amdgcn_rcpf(__expf(2.f * y) + 1.f);
;             o[j] = 0.5f * xv * (1.f + th);
;           }
;           uint2 u;
;           u.x = pack2(o[0], o[1]);
;           u.y = pack2(o[2], o[3]);
;           *(uint2*)(hd + (size_t)m * 256 + n) = u;
;         });
	v_pk_add_f32 v[38:39], v[94:95], v[30:31]
	s_nop 0
	v_mul_f32_e32 v72, 0x3d372713, v38
	v_mul_f32_e32 v73, 0x3d372713, v39
	v_mul_f32_e32 v72, v38, v72
	v_mul_f32_e32 v73, v39, v73
	v_fma_f32 v72, v38, v72, v38
	v_fma_f32 v73, v39, v73, v39
	v_mul_f32_e32 v72, 0x3f4c422a, v72
	v_mul_f32_e32 v73, 0x3f4c422a, v73
	v_add_f32_e32 v72, v72, v72
	v_add_f32_e32 v73, v73, v73
	v_mul_f32_e32 v72, 0x3fb8aa3b, v72
	v_mul_f32_e32 v73, 0x3fb8aa3b, v73
	v_exp_f32_e32 v72, v72
	v_exp_f32_e32 v73, v73
	v_pk_mul_f32 v[38:39], v[38:39], 0.5 op_sel_hi:[1,0]
	v_pk_add_f32 v[62:63], v[62:63], v[30:31]
	v_add_f32_e32 v72, 1.0, v72
	v_add_f32_e32 v73, 1.0, v73
	v_rcp_f32_e32 v72, v72
	v_rcp_f32_e32 v73, v73
	v_pk_add_f32 v[64:65], v[64:65], v[32:33]
	v_pk_add_f32 v[34:35], v[34:35], v[30:31]
	v_pk_add_f32 v[36:37], v[36:37], v[32:33]
	v_pk_fma_f32 v[72:73], v[72:73], 2.0, 1.0 op_sel_hi:[1,0,0] neg_lo:[1,0,0] neg_hi:[1,0,0]
	v_pk_add_f32 v[14:15], v[14:15], v[30:31]
	v_pk_add_f32 v[72:73], v[72:73], 1.0 op_sel_hi:[1,0]
	v_pk_add_f32 v[16:17], v[16:17], v[32:33]
	v_pk_mul_f32 v[38:39], v[38:39], v[72:73]
	v_pk_add_f32 v[72:73], v[96:97], v[32:33]
	v_cvt_pk_bf16_f32 v38, v38, v39
	v_mul_f32_e32 v74, 0x3d372713, v72
	v_mul_f32_e32 v75, 0x3d372713, v73
	v_mul_f32_e32 v74, v72, v74
	v_mul_f32_e32 v75, v73, v75
	v_fma_f32 v74, v72, v74, v72
	v_fma_f32 v75, v73, v75, v73
	v_mul_f32_e32 v74, 0x3f4c422a, v74
	v_mul_f32_e32 v75, 0x3f4c422a, v75
	v_add_f32_e32 v74, v74, v74
	v_add_f32_e32 v75, v75, v75
	v_mul_f32_e32 v74, 0x3fb8aa3b, v74
	v_mul_f32_e32 v75, 0x3fb8aa3b, v75
	v_exp_f32_e32 v74, v74
	v_exp_f32_e32 v75, v75
	v_pk_mul_f32 v[72:73], v[72:73], 0.5 op_sel_hi:[1,0]
	v_add_f32_e32 v74, 1.0, v74
	v_add_f32_e32 v75, 1.0, v75
	v_rcp_f32_e32 v74, v74
	v_rcp_f32_e32 v75, v75
	s_nop 0
	v_pk_fma_f32 v[74:75], v[74:75], 2.0, 1.0 op_sel_hi:[1,0,0] neg_lo:[1,0,0] neg_hi:[1,0,0]
	s_nop 0
	v_pk_add_f32 v[74:75], v[74:75], 1.0 op_sel_hi:[1,0]
	s_nop 0
	v_pk_mul_f32 v[72:73], v[72:73], v[74:75]
	s_nop 0
	v_cvt_pk_bf16_f32 v39, v72, v73
	v_lshl_add_u64 v[72:73], v[40:41], 0, v[0:1]
	global_store_dwordx2 v[72:73], v[38:39], off
	global_load_dwordx4 v[38:41], v71, s[12:13] offset:64
	s_waitcnt vmcnt(0)
	v_pk_add_f32 v[50:51], v[50:51], v[38:39]
	s_nop 0
	v_mul_f32_e32 v74, 0x3d372713, v50
	v_mul_f32_e32 v75, 0x3d372713, v51
	v_mul_f32_e32 v74, v50, v74
	v_mul_f32_e32 v75, v51, v75
	v_fma_f32 v74, v50, v74, v50
	v_fma_f32 v75, v51, v75, v51
	v_mul_f32_e32 v74, 0x3f4c422a, v74
	v_mul_f32_e32 v75, 0x3f4c422a, v75
	v_add_f32_e32 v74, v74, v74
	v_add_f32_e32 v75, v75, v75
	v_mul_f32_e32 v74, 0x3fb8aa3b, v74
	v_mul_f32_e32 v75, 0x3fb8aa3b, v75
	v_exp_f32_e32 v74, v74
	v_exp_f32_e32 v75, v75
	v_pk_mul_f32 v[50:51], v[50:51], 0.5 op_sel_hi:[1,0]
	v_pk_add_f32 v[52:53], v[52:53], v[40:41]
	v_add_f32_e32 v74, 1.0, v74
	v_add_f32_e32 v75, 1.0, v75
	v_rcp_f32_e32 v74, v74
	v_rcp_f32_e32 v75, v75
	v_pk_add_f32 v[58:59], v[58:59], v[38:39]
	v_pk_add_f32 v[60:61], v[60:61], v[40:41]
	v_pk_add_f32 v[26:27], v[26:27], v[38:39]
	v_pk_fma_f32 v[74:75], v[74:75], 2.0, 1.0 op_sel_hi:[1,0,0] neg_lo:[1,0,0] neg_hi:[1,0,0]
	v_pk_add_f32 v[28:29], v[28:29], v[40:41]
	v_pk_add_f32 v[74:75], v[74:75], 1.0 op_sel_hi:[1,0]
	v_pk_add_f32 v[10:11], v[10:11], v[38:39]
	v_pk_mul_f32 v[50:51], v[50:51], v[74:75]
	v_mul_f32_e32 v74, 0x3d372713, v52
	v_mul_f32_e32 v75, 0x3d372713, v53
	v_mul_f32_e32 v74, v52, v74
	v_mul_f32_e32 v75, v53, v75
	v_fma_f32 v74, v52, v74, v52
	v_fma_f32 v75, v53, v75, v53
	v_mul_f32_e32 v74, 0x3f4c422a, v74
	v_mul_f32_e32 v75, 0x3f4c422a, v75
	v_add_f32_e32 v74, v74, v74
	v_add_f32_e32 v75, v75, v75
	v_mul_f32_e32 v74, 0x3fb8aa3b, v74
	v_mul_f32_e32 v75, 0x3fb8aa3b, v75
	v_exp_f32_e32 v74, v74
	v_exp_f32_e32 v75, v75
	v_pk_mul_f32 v[52:53], v[52:53], 0.5 op_sel_hi:[1,0]
	v_cvt_pk_bf16_f32 v50, v50, v51
	v_add_f32_e32 v74, 1.0, v74
	v_add_f32_e32 v75, 1.0, v75
	v_rcp_f32_e32 v74, v74
	v_rcp_f32_e32 v75, v75
	v_pk_add_f32 v[12:13], v[12:13], v[40:41]
	v_pk_fma_f32 v[74:75], v[74:75], 2.0, 1.0 op_sel_hi:[1,0,0] neg_lo:[1,0,0] neg_hi:[1,0,0]
	s_nop 0
	v_pk_add_f32 v[74:75], v[74:75], 1.0 op_sel_hi:[1,0]
	s_nop 0
	v_pk_mul_f32 v[52:53], v[52:53], v[74:75]
	s_nop 0
	v_cvt_pk_bf16_f32 v51, v52, v53
	global_store_dwordx2 v[72:73], v[50:51], off offset:32
	global_load_dwordx4 v[50:53], v71, s[12:13] offset:128
	s_waitcnt vmcnt(0)
	v_pk_add_f32 v[46:47], v[46:47], v[50:51]
	s_nop 0
	v_mul_f32_e32 v74, 0x3d372713, v46
	v_mul_f32_e32 v75, 0x3d372713, v47
	v_mul_f32_e32 v74, v46, v74
	v_mul_f32_e32 v75, v47, v75
	v_fma_f32 v74, v46, v74, v46
	v_fma_f32 v75, v47, v75, v47
	v_mul_f32_e32 v74, 0x3f4c422a, v74
	v_mul_f32_e32 v75, 0x3f4c422a, v75
	v_add_f32_e32 v74, v74, v74
	v_add_f32_e32 v75, v75, v75
	v_mul_f32_e32 v74, 0x3fb8aa3b, v74
	v_mul_f32_e32 v75, 0x3fb8aa3b, v75
	v_exp_f32_e32 v74, v74
	v_exp_f32_e32 v75, v75
	v_pk_mul_f32 v[46:47], v[46:47], 0.5 op_sel_hi:[1,0]
	v_pk_add_f32 v[48:49], v[48:49], v[52:53]
	v_add_f32_e32 v74, 1.0, v74
	v_add_f32_e32 v75, 1.0, v75
	v_rcp_f32_e32 v74, v74
	v_rcp_f32_e32 v75, v75
	v_pk_add_f32 v[54:55], v[54:55], v[50:51]
	v_pk_add_f32 v[56:57], v[56:57], v[52:53]
	v_pk_add_f32 v[22:23], v[22:23], v[50:51]
	v_pk_fma_f32 v[74:75], v[74:75], 2.0, 1.0 op_sel_hi:[1,0,0] neg_lo:[1,0,0] neg_hi:[1,0,0]
	v_pk_add_f32 v[24:25], v[24:25], v[52:53]
	v_pk_add_f32 v[74:75], v[74:75], 1.0 op_sel_hi:[1,0]
	v_pk_add_f32 v[6:7], v[6:7], v[50:51]
	v_pk_mul_f32 v[46:47], v[46:47], v[74:75]
	v_mul_f32_e32 v74, 0x3d372713, v48
	v_mul_f32_e32 v75, 0x3d372713, v49
	v_mul_f32_e32 v74, v48, v74
	v_mul_f32_e32 v75, v49, v75
	v_fma_f32 v74, v48, v74, v48
	v_fma_f32 v75, v49, v75, v49
	v_mul_f32_e32 v74, 0x3f4c422a, v74
	v_mul_f32_e32 v75, 0x3f4c422a, v75
	v_add_f32_e32 v74, v74, v74
	v_add_f32_e32 v75, v75, v75
	v_mul_f32_e32 v74, 0x3fb8aa3b, v74
	v_mul_f32_e32 v75, 0x3fb8aa3b, v75
	v_exp_f32_e32 v74, v74
	v_exp_f32_e32 v75, v75
	v_pk_mul_f32 v[48:49], v[48:49], 0.5 op_sel_hi:[1,0]
	v_cvt_pk_bf16_f32 v46, v46, v47
	v_add_f32_e32 v74, 1.0, v74
	v_add_f32_e32 v75, 1.0, v75
	v_rcp_f32_e32 v74, v74
	v_rcp_f32_e32 v75, v75
	v_pk_add_f32 v[8:9], v[8:9], v[52:53]
	v_pk_fma_f32 v[74:75], v[74:75], 2.0, 1.0 op_sel_hi:[1,0,0] neg_lo:[1,0,0] neg_hi:[1,0,0]
	s_nop 0
	v_pk_add_f32 v[74:75], v[74:75], 1.0 op_sel_hi:[1,0]
	s_nop 0
	v_pk_mul_f32 v[48:49], v[48:49], v[74:75]
	s_nop 0
	v_cvt_pk_bf16_f32 v47, v48, v49
	global_store_dwordx2 v[72:73], v[46:47], off offset:64
	global_load_dwordx4 v[46:49], v71, s[12:13] offset:192
	s_waitcnt vmcnt(0)
; __global__ void __launch_bounds__(512, 2) mega(Params p) {
;     ...
;         gemm_epi(acc, m0, n0, [&](int m, int n, f32x4& a) {
;           float o[4];
; #pragma unroll
;           for (int j = 0; j < 4; ++j) {
;             float xv = a[j] + bs[n + j];
;             float y = 0.7978845608028654f * (xv + 0.044715f * xv * xv * xv);
;             float th = 1.f - 2.f * __builtin_amdgcn_rcpf(__expf(2.f * y) + 1.f);
;             o[j] = 0.5f * xv * (1.f + th);
;           }
;           uint2 u;
;           u.x = pack2(o[0], o[1]);
;           u.y = pack2(o[2], o[3]);
;           *(uint2*)(hd + (size_t)m * 256 + n) = u;
;         });
	v_pk_add_f32 v[66:67], v[66:67], v[46:47]
	s_nop 0
	v_mul_f32_e32 v71, 0x3d372713, v66
	v_mul_f32_e32 v71, v66, v71
	v_fma_f32 v71, v66, v71, v66
	v_mul_f32_e32 v71, 0x3f4c422a, v71
	v_add_f32_e32 v71, v71, v71
	v_mul_f32_e32 v71, 0x3fb8aa3b, v71
	v_exp_f32_e32 v71, v71
	v_pk_add_f32 v[68:69], v[68:69], v[48:49]
	v_pk_add_f32 v[42:43], v[42:43], v[46:47]
	v_pk_add_f32 v[44:45], v[44:45], v[48:49]
	v_add_f32_e32 v71, 1.0, v71
	v_rcp_f32_e32 v74, v71
	v_mul_f32_e32 v71, 0x3d372713, v67
	v_mul_f32_e32 v71, v67, v71
	v_fma_f32 v71, v67, v71, v67
	v_mul_f32_e32 v71, 0x3f4c422a, v71
	v_add_f32_e32 v71, v71, v71
	v_mul_f32_e32 v71, 0x3fb8aa3b, v71
	v_exp_f32_e32 v71, v71
	v_pk_mul_f32 v[66:67], v[66:67], 0.5 op_sel_hi:[1,0]
	v_pk_add_f32 v[18:19], v[18:19], v[46:47]
	v_pk_add_f32 v[20:21], v[20:21], v[48:49]
	v_add_f32_e32 v71, 1.0, v71
	v_rcp_f32_e32 v75, v71
	v_mul_f32_e32 v71, 0x3d372713, v68
	v_mul_f32_e32 v71, v68, v71
	v_fma_f32 v71, v68, v71, v68
	v_mul_f32_e32 v71, 0x3f4c422a, v71
	v_add_f32_e32 v71, v71, v71
	v_mul_f32_e32 v71, 0x3fb8aa3b, v71
	v_exp_f32_e32 v71, v71
	v_pk_fma_f32 v[74:75], v[74:75], 2.0, 1.0 op_sel_hi:[1,0,0] neg_lo:[1,0,0] neg_hi:[1,0,0]
	v_pk_add_f32 v[2:3], v[2:3], v[46:47]
	v_pk_add_f32 v[74:75], v[74:75], 1.0 op_sel_hi:[1,0]
	v_add_f32_e32 v71, 1.0, v71
	v_pk_mul_f32 v[66:67], v[66:67], v[74:75]
	v_rcp_f32_e32 v74, v71
	v_mul_f32_e32 v71, 0x3d372713, v69
	v_mul_f32_e32 v71, v69, v71
	v_fma_f32 v71, v69, v71, v69
	v_mul_f32_e32 v71, 0x3f4c422a, v71
	v_add_f32_e32 v71, v71, v71
	v_mul_f32_e32 v71, 0x3fb8aa3b, v71
	v_exp_f32_e32 v71, v71
	v_pk_mul_f32 v[68:69], v[68:69], 0.5 op_sel_hi:[1,0]
	v_cvt_pk_bf16_f32 v66, v66, v67
	v_pk_add_f32 v[4:5], v[4:5], v[48:49]
	v_add_f32_e32 v71, 1.0, v71
	v_rcp_f32_e32 v75, v71
	s_nop 0
	v_pk_fma_f32 v[74:75], v[74:75], 2.0, 1.0 op_sel_hi:[1,0,0] neg_lo:[1,0,0] neg_hi:[1,0,0]
	s_nop 0
	v_pk_add_f32 v[74:75], v[74:75], 1.0 op_sel_hi:[1,0]
	s_nop 0
	v_pk_mul_f32 v[68:69], v[68:69], v[74:75]
	s_nop 0
	v_cvt_pk_bf16_f32 v67, v68, v69
	v_mul_f32_e32 v68, 0x3d372713, v62
	v_mul_f32_e32 v69, 0x3d372713, v63
	v_mul_f32_e32 v68, v62, v68
	v_mul_f32_e32 v69, v63, v69
	v_fma_f32 v68, v62, v68, v62
	v_fma_f32 v69, v63, v69, v63
	v_mul_f32_e32 v68, 0x3f4c422a, v68
	v_mul_f32_e32 v69, 0x3f4c422a, v69
	v_add_f32_e32 v68, v68, v68
	v_add_f32_e32 v69, v69, v69
	v_mul_f32_e32 v68, 0x3fb8aa3b, v68
	v_mul_f32_e32 v69, 0x3fb8aa3b, v69
	v_exp_f32_e32 v68, v68
	v_exp_f32_e32 v69, v69
	v_pk_mul_f32 v[62:63], v[62:63], 0.5 op_sel_hi:[1,0]
	global_store_dwordx2 v[72:73], v[66:67], off offset:96
	v_add_f32_e32 v68, 1.0, v68
	v_add_f32_e32 v69, 1.0, v69
	v_rcp_f32_e32 v68, v68
	v_rcp_f32_e32 v69, v69
	v_or_b32_e32 v66, 16, v70
	v_ashrrev_i32_e32 v67, 31, v66
	v_lshlrev_b64 v[66:67], 9, v[66:67]
	v_pk_fma_f32 v[68:69], v[68:69], 2.0, 1.0 op_sel_hi:[1,0,0] neg_lo:[1,0,0] neg_hi:[1,0,0]
	s_nop 0
	v_pk_add_f32 v[68:69], v[68:69], 1.0 op_sel_hi:[1,0]
	s_nop 0
	v_pk_mul_f32 v[62:63], v[62:63], v[68:69]
	v_mul_f32_e32 v68, 0x3d372713, v64
	v_mul_f32_e32 v69, 0x3d372713, v65
	v_mul_f32_e32 v68, v64, v68
	v_mul_f32_e32 v69, v65, v69
	v_fma_f32 v68, v64, v68, v64
	v_fma_f32 v69, v65, v69, v65
	v_mul_f32_e32 v68, 0x3f4c422a, v68
	v_mul_f32_e32 v69, 0x3f4c422a, v69
	v_add_f32_e32 v68, v68, v68
	v_add_f32_e32 v69, v69, v69
	v_mul_f32_e32 v68, 0x3fb8aa3b, v68
	v_mul_f32_e32 v69, 0x3fb8aa3b, v69
	v_exp_f32_e32 v68, v68
	v_exp_f32_e32 v69, v69
	v_pk_mul_f32 v[64:65], v[64:65], 0.5 op_sel_hi:[1,0]
	v_add_f32_e32 v68, 1.0, v68
	v_add_f32_e32 v69, 1.0, v69
	v_rcp_f32_e32 v68, v68
	v_rcp_f32_e32 v69, v69
	s_nop 0
	v_pk_fma_f32 v[68:69], v[68:69], 2.0, 1.0 op_sel_hi:[1,0,0] neg_lo:[1,0,0] neg_hi:[1,0,0]
	s_nop 0
	v_pk_add_f32 v[68:69], v[68:69], 1.0 op_sel_hi:[1,0]
	s_nop 0
	v_pk_mul_f32 v[64:65], v[64:65], v[68:69]
	v_cvt_pk_bf16_f32 v68, v62, v63
	v_cvt_pk_bf16_f32 v69, v64, v65
	v_mul_f32_e32 v64, 0x3d372713, v58
	v_mul_f32_e32 v65, 0x3d372713, v59
	v_mul_f32_e32 v64, v58, v64
	v_mul_f32_e32 v65, v59, v65
	v_fma_f32 v64, v58, v64, v58
	v_fma_f32 v65, v59, v65, v59
	v_mul_f32_e32 v64, 0x3f4c422a, v64
	v_mul_f32_e32 v65, 0x3f4c422a, v65
	v_add_f32_e32 v64, v64, v64
	v_add_f32_e32 v65, v65, v65
	v_mul_f32_e32 v64, 0x3fb8aa3b, v64
	v_mul_f32_e32 v65, 0x3fb8aa3b, v65
	v_exp_f32_e32 v64, v64
	v_exp_f32_e32 v65, v65
	v_pk_mul_f32 v[58:59], v[58:59], 0.5 op_sel_hi:[1,0]
	v_lshl_add_u64 v[62:63], s[2:3], 0, v[66:67]
	v_add_f32_e32 v64, 1.0, v64
	v_add_f32_e32 v65, 1.0, v65
	v_rcp_f32_e32 v64, v64
	v_rcp_f32_e32 v65, v65
	v_lshl_add_u64 v[62:63], v[62:63], 0, v[0:1]
	global_store_dwordx2 v[62:63], v[68:69], off
	v_pk_fma_f32 v[64:65], v[64:65], 2.0, 1.0 op_sel_hi:[1,0,0] neg_lo:[1,0,0] neg_hi:[1,0,0]
	s_nop 0
	v_pk_add_f32 v[64:65], v[64:65], 1.0 op_sel_hi:[1,0]
	s_nop 0
	v_pk_mul_f32 v[58:59], v[58:59], v[64:65]
	v_mul_f32_e32 v64, 0x3d372713, v60
	v_mul_f32_e32 v65, 0x3d372713, v61
	v_mul_f32_e32 v64, v60, v64
	v_mul_f32_e32 v65, v61, v65
	v_fma_f32 v64, v60, v64, v60
	v_fma_f32 v65, v61, v65, v61
	v_mul_f32_e32 v64, 0x3f4c422a, v64
	v_mul_f32_e32 v65, 0x3f4c422a, v65
	v_add_f32_e32 v64, v64, v64
	v_add_f32_e32 v65, v65, v65
	v_mul_f32_e32 v64, 0x3fb8aa3b, v64
	v_mul_f32_e32 v65, 0x3fb8aa3b, v65
	v_exp_f32_e32 v64, v64
	v_exp_f32_e32 v65, v65
	v_pk_mul_f32 v[60:61], v[60:61], 0.5 op_sel_hi:[1,0]
	v_cvt_pk_bf16_f32 v58, v58, v59
	v_add_f32_e32 v64, 1.0, v64
	v_add_f32_e32 v65, 1.0, v65
	v_rcp_f32_e32 v64, v64
	v_rcp_f32_e32 v65, v65
	s_nop 0
	v_pk_fma_f32 v[64:65], v[64:65], 2.0, 1.0 op_sel_hi:[1,0,0] neg_lo:[1,0,0] neg_hi:[1,0,0]
	s_nop 0
	v_pk_add_f32 v[64:65], v[64:65], 1.0 op_sel_hi:[1,0]
	s_nop 0
	v_pk_mul_f32 v[60:61], v[60:61], v[64:65]
; __global__ void __launch_bounds__(512, 2) mega(Params p) {
;     ...
;         gemm_epi(acc, m0, n0, [&](int m, int n, f32x4& a) {
;           float o[4];
; #pragma unroll
;           for (int j = 0; j < 4; ++j) {
;             float xv = a[j] + bs[n + j];
;             float y = 0.7978845608028654f * (xv + 0.044715f * xv * xv * xv);
;             float th = 1.f - 2.f * __builtin_amdgcn_rcpf(__expf(2.f * y) + 1.f);
;             o[j] = 0.5f * xv * (1.f + th);
;           }
;           uint2 u;
;           u.x = pack2(o[0], o[1]);
;           u.y = pack2(o[2], o[3]);
;           *(uint2*)(hd + (size_t)m * 256 + n) = u;
;         });
	s_nop 0
	v_cvt_pk_bf16_f32 v59, v60, v61
	global_store_dwordx2 v[62:63], v[58:59], off offset:32
	v_mul_f32_e32 v58, 0x3d372713, v54
	v_mul_f32_e32 v59, 0x3d372713, v55
	v_mul_f32_e32 v58, v54, v58
	v_mul_f32_e32 v59, v55, v59
	v_fma_f32 v58, v54, v58, v54
	v_fma_f32 v59, v55, v59, v55
	v_mul_f32_e32 v58, 0x3f4c422a, v58
	v_mul_f32_e32 v59, 0x3f4c422a, v59
	v_add_f32_e32 v58, v58, v58
	v_add_f32_e32 v59, v59, v59
	v_mul_f32_e32 v58, 0x3fb8aa3b, v58
	v_mul_f32_e32 v59, 0x3fb8aa3b, v59
	v_exp_f32_e32 v58, v58
	v_exp_f32_e32 v59, v59
	v_pk_mul_f32 v[54:55], v[54:55], 0.5 op_sel_hi:[1,0]
	v_add_f32_e32 v58, 1.0, v58
	v_add_f32_e32 v59, 1.0, v59
	v_rcp_f32_e32 v58, v58
	v_rcp_f32_e32 v59, v59
	s_nop 0
	v_pk_fma_f32 v[58:59], v[58:59], 2.0, 1.0 op_sel_hi:[1,0,0] neg_lo:[1,0,0] neg_hi:[1,0,0]
	s_nop 0
	v_pk_add_f32 v[58:59], v[58:59], 1.0 op_sel_hi:[1,0]
	s_nop 0
	v_pk_mul_f32 v[54:55], v[54:55], v[58:59]
	v_mul_f32_e32 v58, 0x3d372713, v56
	v_mul_f32_e32 v59, 0x3d372713, v57
	v_mul_f32_e32 v58, v56, v58
	v_mul_f32_e32 v59, v57, v59
	v_fma_f32 v58, v56, v58, v56
	v_fma_f32 v59, v57, v59, v57
	v_mul_f32_e32 v58, 0x3f4c422a, v58
	v_mul_f32_e32 v59, 0x3f4c422a, v59
	v_add_f32_e32 v58, v58, v58
	v_add_f32_e32 v59, v59, v59
	v_mul_f32_e32 v58, 0x3fb8aa3b, v58
	v_mul_f32_e32 v59, 0x3fb8aa3b, v59
	v_exp_f32_e32 v58, v58
	v_exp_f32_e32 v59, v59
	v_pk_mul_f32 v[56:57], v[56:57], 0.5 op_sel_hi:[1,0]
	v_cvt_pk_bf16_f32 v54, v54, v55
	v_add_f32_e32 v58, 1.0, v58
	v_add_f32_e32 v59, 1.0, v59
	v_rcp_f32_e32 v58, v58
	v_rcp_f32_e32 v59, v59
	s_nop 0
	v_pk_fma_f32 v[58:59], v[58:59], 2.0, 1.0 op_sel_hi:[1,0,0] neg_lo:[1,0,0] neg_hi:[1,0,0]
	s_nop 0
	v_pk_add_f32 v[58:59], v[58:59], 1.0 op_sel_hi:[1,0]
	s_nop 0
	v_pk_mul_f32 v[56:57], v[56:57], v[58:59]
	s_nop 0
	v_cvt_pk_bf16_f32 v55, v56, v57
	global_store_dwordx2 v[62:63], v[54:55], off offset:64
	v_mul_f32_e32 v54, 0x3d372713, v42
	v_mul_f32_e32 v55, 0x3d372713, v43
	v_mul_f32_e32 v54, v42, v54
	v_mul_f32_e32 v55, v43, v55
	v_fma_f32 v54, v42, v54, v42
	v_fma_f32 v55, v43, v55, v43
	v_mul_f32_e32 v54, 0x3f4c422a, v54
	v_mul_f32_e32 v55, 0x3f4c422a, v55
	v_add_f32_e32 v54, v54, v54
	v_add_f32_e32 v55, v55, v55
	v_mul_f32_e32 v54, 0x3fb8aa3b, v54
	v_mul_f32_e32 v55, 0x3fb8aa3b, v55
	v_exp_f32_e32 v54, v54
	v_exp_f32_e32 v55, v55
	v_pk_mul_f32 v[42:43], v[42:43], 0.5 op_sel_hi:[1,0]
	v_add_f32_e32 v54, 1.0, v54
	v_add_f32_e32 v55, 1.0, v55
	v_rcp_f32_e32 v54, v54
	v_rcp_f32_e32 v55, v55
	s_nop 0
	v_pk_fma_f32 v[54:55], v[54:55], 2.0, 1.0 op_sel_hi:[1,0,0] neg_lo:[1,0,0] neg_hi:[1,0,0]
	s_nop 0
	v_pk_add_f32 v[54:55], v[54:55], 1.0 op_sel_hi:[1,0]
	s_nop 0
	v_pk_mul_f32 v[42:43], v[42:43], v[54:55]
	v_mul_f32_e32 v54, 0x3d372713, v44
	v_mul_f32_e32 v55, 0x3d372713, v45
	v_mul_f32_e32 v54, v44, v54
	v_mul_f32_e32 v55, v45, v55
	v_fma_f32 v54, v44, v54, v44
	v_fma_f32 v55, v45, v55, v45
	v_mul_f32_e32 v54, 0x3f4c422a, v54
	v_mul_f32_e32 v55, 0x3f4c422a, v55
	v_add_f32_e32 v54, v54, v54
	v_add_f32_e32 v55, v55, v55
	v_mul_f32_e32 v54, 0x3fb8aa3b, v54
	v_mul_f32_e32 v55, 0x3fb8aa3b, v55
	v_exp_f32_e32 v54, v54
	v_exp_f32_e32 v55, v55
	v_pk_mul_f32 v[44:45], v[44:45], 0.5 op_sel_hi:[1,0]
	v_cvt_pk_bf16_f32 v42, v42, v43
	v_add_f32_e32 v54, 1.0, v54
	v_add_f32_e32 v55, 1.0, v55
	v_rcp_f32_e32 v54, v54
	v_rcp_f32_e32 v55, v55
	s_nop 0
	v_pk_fma_f32 v[54:55], v[54:55], 2.0, 1.0 op_sel_hi:[1,0,0] neg_lo:[1,0,0] neg_hi:[1,0,0]
	s_nop 0
	v_pk_add_f32 v[54:55], v[54:55], 1.0 op_sel_hi:[1,0]
	s_nop 0
	v_pk_mul_f32 v[44:45], v[44:45], v[54:55]
	s_nop 0
	v_cvt_pk_bf16_f32 v43, v44, v45
	v_mul_f32_e32 v44, 0x3d372713, v34
	v_mul_f32_e32 v45, 0x3d372713, v35
	v_mul_f32_e32 v44, v34, v44
	v_mul_f32_e32 v45, v35, v45
	v_fma_f32 v44, v34, v44, v34
	v_fma_f32 v45, v35, v45, v35
	v_mul_f32_e32 v44, 0x3f4c422a, v44
	v_mul_f32_e32 v45, 0x3f4c422a, v45
	v_add_f32_e32 v44, v44, v44
	v_add_f32_e32 v45, v45, v45
	v_mul_f32_e32 v44, 0x3fb8aa3b, v44
	v_mul_f32_e32 v45, 0x3fb8aa3b, v45
	v_exp_f32_e32 v44, v44
	v_exp_f32_e32 v45, v45
	v_pk_mul_f32 v[34:35], v[34:35], 0.5 op_sel_hi:[1,0]
	global_store_dwordx2 v[62:63], v[42:43], off offset:96
	v_add_f32_e32 v44, 1.0, v44
	v_add_f32_e32 v45, 1.0, v45
	v_rcp_f32_e32 v44, v44
	v_rcp_f32_e32 v45, v45
	v_or_b32_e32 v42, 32, v70
	v_ashrrev_i32_e32 v43, 31, v42
	v_lshlrev_b64 v[42:43], 9, v[42:43]
	v_pk_fma_f32 v[44:45], v[44:45], 2.0, 1.0 op_sel_hi:[1,0,0] neg_lo:[1,0,0] neg_hi:[1,0,0]
	s_nop 0
	v_pk_add_f32 v[44:45], v[44:45], 1.0 op_sel_hi:[1,0]
	s_nop 0
	v_pk_mul_f32 v[34:35], v[34:35], v[44:45]
	v_mul_f32_e32 v44, 0x3d372713, v36
	v_mul_f32_e32 v45, 0x3d372713, v37
	v_mul_f32_e32 v44, v36, v44
	v_mul_f32_e32 v45, v37, v45
	v_fma_f32 v44, v36, v44, v36
	v_fma_f32 v45, v37, v45, v37
	v_mul_f32_e32 v44, 0x3f4c422a, v44
	v_mul_f32_e32 v45, 0x3f4c422a, v45
	v_add_f32_e32 v44, v44, v44
	v_add_f32_e32 v45, v45, v45
	v_mul_f32_e32 v44, 0x3fb8aa3b, v44
	v_mul_f32_e32 v45, 0x3fb8aa3b, v45
	v_exp_f32_e32 v44, v44
	v_exp_f32_e32 v45, v45
	v_pk_mul_f32 v[36:37], v[36:37], 0.5 op_sel_hi:[1,0]
	v_add_f32_e32 v44, 1.0, v44
	v_add_f32_e32 v45, 1.0, v45
	v_rcp_f32_e32 v44, v44
	v_rcp_f32_e32 v45, v45
	s_nop 0
	v_pk_fma_f32 v[44:45], v[44:45], 2.0, 1.0 op_sel_hi:[1,0,0] neg_lo:[1,0,0] neg_hi:[1,0,0]
	s_nop 0
	v_pk_add_f32 v[44:45], v[44:45], 1.0 op_sel_hi:[1,0]
	s_nop 0
	v_pk_mul_f32 v[36:37], v[36:37], v[44:45]
	v_cvt_pk_bf16_f32 v44, v34, v35
	v_cvt_pk_bf16_f32 v45, v36, v37
	v_mul_f32_e32 v36, 0x3d372713, v26
	v_mul_f32_e32 v37, 0x3d372713, v27
	v_mul_f32_e32 v36, v26, v36
	v_mul_f32_e32 v37, v27, v37
	v_fma_f32 v36, v26, v36, v26
	v_fma_f32 v37, v27, v37, v27
	v_mul_f32_e32 v36, 0x3f4c422a, v36
; __global__ void __launch_bounds__(512, 2) mega(Params p) {
;     ...
;         gemm_epi(acc, m0, n0, [&](int m, int n, f32x4& a) {
;           float o[4];
; #pragma unroll
;           for (int j = 0; j < 4; ++j) {
;             float xv = a[j] + bs[n + j];
;             float y = 0.7978845608028654f * (xv + 0.044715f * xv * xv * xv);
;             float th = 1.f - 2.f * __builtin_amdgcn_rcpf(__expf(2.f * y) + 1.f);
;             o[j] = 0.5f * xv * (1.f + th);
;           }
;           uint2 u;
;           u.x = pack2(o[0], o[1]);
;           u.y = pack2(o[2], o[3]);
;           *(uint2*)(hd + (size_t)m * 256 + n) = u;
;         });
	v_mul_f32_e32 v37, 0x3f4c422a, v37
	v_add_f32_e32 v36, v36, v36
	v_add_f32_e32 v37, v37, v37
	v_mul_f32_e32 v36, 0x3fb8aa3b, v36
	v_mul_f32_e32 v37, 0x3fb8aa3b, v37
	v_exp_f32_e32 v36, v36
	v_exp_f32_e32 v37, v37
	v_pk_mul_f32 v[26:27], v[26:27], 0.5 op_sel_hi:[1,0]
	v_lshl_add_u64 v[34:35], s[2:3], 0, v[42:43]
	v_add_f32_e32 v36, 1.0, v36
	v_add_f32_e32 v37, 1.0, v37
	v_rcp_f32_e32 v36, v36
	v_rcp_f32_e32 v37, v37
	v_lshl_add_u64 v[34:35], v[34:35], 0, v[0:1]
	global_store_dwordx2 v[34:35], v[44:45], off
	v_pk_fma_f32 v[36:37], v[36:37], 2.0, 1.0 op_sel_hi:[1,0,0] neg_lo:[1,0,0] neg_hi:[1,0,0]
	s_nop 0
	v_pk_add_f32 v[36:37], v[36:37], 1.0 op_sel_hi:[1,0]
	s_nop 0
	v_pk_mul_f32 v[26:27], v[26:27], v[36:37]
	v_mul_f32_e32 v36, 0x3d372713, v28
	v_mul_f32_e32 v37, 0x3d372713, v29
	v_mul_f32_e32 v36, v28, v36
	v_mul_f32_e32 v37, v29, v37
	v_fma_f32 v36, v28, v36, v28
	v_fma_f32 v37, v29, v37, v29
	v_mul_f32_e32 v36, 0x3f4c422a, v36
	v_mul_f32_e32 v37, 0x3f4c422a, v37
	v_add_f32_e32 v36, v36, v36
	v_add_f32_e32 v37, v37, v37
	v_mul_f32_e32 v36, 0x3fb8aa3b, v36
	v_mul_f32_e32 v37, 0x3fb8aa3b, v37
	v_exp_f32_e32 v36, v36
	v_exp_f32_e32 v37, v37
	v_pk_mul_f32 v[28:29], v[28:29], 0.5 op_sel_hi:[1,0]
	v_cvt_pk_bf16_f32 v26, v26, v27
	v_add_f32_e32 v36, 1.0, v36
	v_add_f32_e32 v37, 1.0, v37
	v_rcp_f32_e32 v36, v36
	v_rcp_f32_e32 v37, v37
	s_nop 0
	v_pk_fma_f32 v[36:37], v[36:37], 2.0, 1.0 op_sel_hi:[1,0,0] neg_lo:[1,0,0] neg_hi:[1,0,0]
	s_nop 0
	v_pk_add_f32 v[36:37], v[36:37], 1.0 op_sel_hi:[1,0]
	s_nop 0
	v_pk_mul_f32 v[28:29], v[28:29], v[36:37]
	s_nop 0
	v_cvt_pk_bf16_f32 v27, v28, v29
	global_store_dwordx2 v[34:35], v[26:27], off offset:32
	v_mul_f32_e32 v26, 0x3d372713, v22
	v_mul_f32_e32 v27, 0x3d372713, v23
	v_mul_f32_e32 v26, v22, v26
	v_mul_f32_e32 v27, v23, v27
	v_fma_f32 v26, v22, v26, v22
	v_fma_f32 v27, v23, v27, v23
	v_mul_f32_e32 v26, 0x3f4c422a, v26
	v_mul_f32_e32 v27, 0x3f4c422a, v27
	v_add_f32_e32 v26, v26, v26
	v_add_f32_e32 v27, v27, v27
	v_mul_f32_e32 v26, 0x3fb8aa3b, v26
	v_mul_f32_e32 v27, 0x3fb8aa3b, v27
	v_exp_f32_e32 v26, v26
	v_exp_f32_e32 v27, v27
	v_pk_mul_f32 v[22:23], v[22:23], 0.5 op_sel_hi:[1,0]
	v_add_f32_e32 v26, 1.0, v26
	v_add_f32_e32 v27, 1.0, v27
	v_rcp_f32_e32 v26, v26
	v_rcp_f32_e32 v27, v27
	s_nop 0
	v_pk_fma_f32 v[26:27], v[26:27], 2.0, 1.0 op_sel_hi:[1,0,0] neg_lo:[1,0,0] neg_hi:[1,0,0]
	s_nop 0
	v_pk_add_f32 v[26:27], v[26:27], 1.0 op_sel_hi:[1,0]
	s_nop 0
	v_pk_mul_f32 v[22:23], v[22:23], v[26:27]
	v_mul_f32_e32 v26, 0x3d372713, v24
	v_mul_f32_e32 v27, 0x3d372713, v25
	v_mul_f32_e32 v26, v24, v26
	v_mul_f32_e32 v27, v25, v27
	v_fma_f32 v26, v24, v26, v24
	v_fma_f32 v27, v25, v27, v25
	v_mul_f32_e32 v26, 0x3f4c422a, v26
	v_mul_f32_e32 v27, 0x3f4c422a, v27
	v_add_f32_e32 v26, v26, v26
	v_add_f32_e32 v27, v27, v27
	v_mul_f32_e32 v26, 0x3fb8aa3b, v26
	v_mul_f32_e32 v27, 0x3fb8aa3b, v27
	v_exp_f32_e32 v26, v26
	v_exp_f32_e32 v27, v27
	v_pk_mul_f32 v[24:25], v[24:25], 0.5 op_sel_hi:[1,0]
	v_cvt_pk_bf16_f32 v22, v22, v23
	v_add_f32_e32 v26, 1.0, v26
	v_add_f32_e32 v27, 1.0, v27
	v_rcp_f32_e32 v26, v26
	v_rcp_f32_e32 v27, v27
	s_nop 0
	v_pk_fma_f32 v[26:27], v[26:27], 2.0, 1.0 op_sel_hi:[1,0,0] neg_lo:[1,0,0] neg_hi:[1,0,0]
	s_nop 0
	v_pk_add_f32 v[26:27], v[26:27], 1.0 op_sel_hi:[1,0]
	s_nop 0
	v_pk_mul_f32 v[24:25], v[24:25], v[26:27]
	s_nop 0
	v_cvt_pk_bf16_f32 v23, v24, v25
	global_store_dwordx2 v[34:35], v[22:23], off offset:64
	v_mul_f32_e32 v22, 0x3d372713, v18
	v_mul_f32_e32 v23, 0x3d372713, v19
	v_mul_f32_e32 v22, v18, v22
	v_mul_f32_e32 v23, v19, v23
	v_fma_f32 v22, v18, v22, v18
	v_fma_f32 v23, v19, v23, v19
	v_mul_f32_e32 v22, 0x3f4c422a, v22
	v_mul_f32_e32 v23, 0x3f4c422a, v23
	v_add_f32_e32 v22, v22, v22
	v_add_f32_e32 v23, v23, v23
	v_mul_f32_e32 v22, 0x3fb8aa3b, v22
	v_mul_f32_e32 v23, 0x3fb8aa3b, v23
	v_exp_f32_e32 v22, v22
	v_exp_f32_e32 v23, v23
	v_pk_mul_f32 v[18:19], v[18:19], 0.5 op_sel_hi:[1,0]
	v_add_f32_e32 v22, 1.0, v22
	v_add_f32_e32 v23, 1.0, v23
	v_rcp_f32_e32 v22, v22
	v_rcp_f32_e32 v23, v23
	s_nop 0
	v_pk_fma_f32 v[22:23], v[22:23], 2.0, 1.0 op_sel_hi:[1,0,0] neg_lo:[1,0,0] neg_hi:[1,0,0]
	s_nop 0
	v_pk_add_f32 v[22:23], v[22:23], 1.0 op_sel_hi:[1,0]
	s_nop 0
	v_pk_mul_f32 v[18:19], v[18:19], v[22:23]
	v_mul_f32_e32 v22, 0x3d372713, v20
	v_mul_f32_e32 v23, 0x3d372713, v21
	v_mul_f32_e32 v22, v20, v22
	v_mul_f32_e32 v23, v21, v23
	v_fma_f32 v22, v20, v22, v20
	v_fma_f32 v23, v21, v23, v21
	v_mul_f32_e32 v22, 0x3f4c422a, v22
	v_mul_f32_e32 v23, 0x3f4c422a, v23
	v_add_f32_e32 v22, v22, v22
	v_add_f32_e32 v23, v23, v23
	v_mul_f32_e32 v22, 0x3fb8aa3b, v22
	v_mul_f32_e32 v23, 0x3fb8aa3b, v23
	v_exp_f32_e32 v22, v22
	v_exp_f32_e32 v23, v23
	v_pk_mul_f32 v[20:21], v[20:21], 0.5 op_sel_hi:[1,0]
	v_cvt_pk_bf16_f32 v18, v18, v19
	v_add_f32_e32 v22, 1.0, v22
	v_add_f32_e32 v23, 1.0, v23
	v_rcp_f32_e32 v22, v22
	v_rcp_f32_e32 v23, v23
	s_nop 0
	v_pk_fma_f32 v[22:23], v[22:23], 2.0, 1.0 op_sel_hi:[1,0,0] neg_lo:[1,0,0] neg_hi:[1,0,0]
	s_nop 0
	v_pk_add_f32 v[22:23], v[22:23], 1.0 op_sel_hi:[1,0]
	s_nop 0
	v_pk_mul_f32 v[20:21], v[20:21], v[22:23]
	s_nop 0
	v_cvt_pk_bf16_f32 v19, v20, v21
	v_mul_f32_e32 v20, 0x3d372713, v14
	v_mul_f32_e32 v21, 0x3d372713, v15
	v_mul_f32_e32 v20, v14, v20
	v_mul_f32_e32 v21, v15, v21
	v_fma_f32 v20, v14, v20, v14
	v_fma_f32 v21, v15, v21, v15
	v_mul_f32_e32 v20, 0x3f4c422a, v20
	v_mul_f32_e32 v21, 0x3f4c422a, v21
	v_add_f32_e32 v20, v20, v20
	v_add_f32_e32 v21, v21, v21
	v_mul_f32_e32 v20, 0x3fb8aa3b, v20
	v_mul_f32_e32 v21, 0x3fb8aa3b, v21
	v_exp_f32_e32 v20, v20
	v_exp_f32_e32 v21, v21
	v_pk_mul_f32 v[14:15], v[14:15], 0.5 op_sel_hi:[1,0]
; __global__ void __launch_bounds__(512, 2) mega(Params p) {
;     ...
;         gemm_epi(acc, m0, n0, [&](int m, int n, f32x4& a) {
;           float o[4];
; #pragma unroll
;           for (int j = 0; j < 4; ++j) {
;             float xv = a[j] + bs[n + j];
;             float y = 0.7978845608028654f * (xv + 0.044715f * xv * xv * xv);
;             float th = 1.f - 2.f * __builtin_amdgcn_rcpf(__expf(2.f * y) + 1.f);
;             o[j] = 0.5f * xv * (1.f + th);
;           }
;           uint2 u;
;           u.x = pack2(o[0], o[1]);
;           u.y = pack2(o[2], o[3]);
;           *(uint2*)(hd + (size_t)m * 256 + n) = u;
;         });
	global_store_dwordx2 v[34:35], v[18:19], off offset:96
	v_add_f32_e32 v20, 1.0, v20
	v_add_f32_e32 v21, 1.0, v21
	v_rcp_f32_e32 v20, v20
	v_rcp_f32_e32 v21, v21
	v_or_b32_e32 v18, 48, v70
	v_ashrrev_i32_e32 v19, 31, v18
	v_lshlrev_b64 v[18:19], 9, v[18:19]
	v_pk_fma_f32 v[20:21], v[20:21], 2.0, 1.0 op_sel_hi:[1,0,0] neg_lo:[1,0,0] neg_hi:[1,0,0]
	s_nop 0
	v_pk_add_f32 v[20:21], v[20:21], 1.0 op_sel_hi:[1,0]
	s_nop 0
	v_pk_mul_f32 v[14:15], v[14:15], v[20:21]
	v_mul_f32_e32 v20, 0x3d372713, v16
	v_mul_f32_e32 v21, 0x3d372713, v17
	v_mul_f32_e32 v20, v16, v20
	v_mul_f32_e32 v21, v17, v21
	v_fma_f32 v20, v16, v20, v16
	v_fma_f32 v21, v17, v21, v17
	v_mul_f32_e32 v20, 0x3f4c422a, v20
	v_mul_f32_e32 v21, 0x3f4c422a, v21
	v_add_f32_e32 v20, v20, v20
	v_add_f32_e32 v21, v21, v21
	v_mul_f32_e32 v20, 0x3fb8aa3b, v20
	v_mul_f32_e32 v21, 0x3fb8aa3b, v21
	v_exp_f32_e32 v20, v20
	v_exp_f32_e32 v21, v21
	v_pk_mul_f32 v[16:17], v[16:17], 0.5 op_sel_hi:[1,0]
	v_add_f32_e32 v20, 1.0, v20
	v_add_f32_e32 v21, 1.0, v21
	v_rcp_f32_e32 v20, v20
	v_rcp_f32_e32 v21, v21
	s_nop 0
	v_pk_fma_f32 v[20:21], v[20:21], 2.0, 1.0 op_sel_hi:[1,0,0] neg_lo:[1,0,0] neg_hi:[1,0,0]
	s_nop 0
	v_pk_add_f32 v[20:21], v[20:21], 1.0 op_sel_hi:[1,0]
	s_nop 0
	v_pk_mul_f32 v[16:17], v[16:17], v[20:21]
	v_cvt_pk_bf16_f32 v20, v14, v15
	v_lshl_add_u64 v[14:15], s[2:3], 0, v[18:19]
	v_lshl_add_u64 v[14:15], v[14:15], 0, v[0:1]
	v_mul_f32_e32 v0, 0x3d372713, v10
	v_mul_f32_e32 v0, v10, v0
	v_fma_f32 v0, v10, v0, v10
	v_mul_f32_e32 v0, 0x3f4c422a, v0
	v_add_f32_e32 v0, v0, v0
	v_mul_f32_e32 v0, 0x3fb8aa3b, v0
	v_exp_f32_e32 v0, v0
	v_cvt_pk_bf16_f32 v21, v16, v17
	global_store_dwordx2 v[14:15], v[20:21], off
	v_add_f32_e32 v0, 1.0, v0
	v_rcp_f32_e32 v16, v0
	v_mul_f32_e32 v0, 0x3d372713, v11
	v_mul_f32_e32 v0, v11, v0
	v_fma_f32 v0, v11, v0, v11
	v_mul_f32_e32 v0, 0x3f4c422a, v0
	v_add_f32_e32 v0, v0, v0
	v_mul_f32_e32 v0, 0x3fb8aa3b, v0
	v_exp_f32_e32 v0, v0
	v_pk_mul_f32 v[10:11], v[10:11], 0.5 op_sel_hi:[1,0]
	v_add_f32_e32 v0, 1.0, v0
	v_rcp_f32_e32 v17, v0
	v_mul_f32_e32 v0, 0x3d372713, v12
	v_mul_f32_e32 v0, v12, v0
	v_fma_f32 v0, v12, v0, v12
	v_mul_f32_e32 v0, 0x3f4c422a, v0
	v_add_f32_e32 v0, v0, v0
	v_mul_f32_e32 v0, 0x3fb8aa3b, v0
	v_exp_f32_e32 v0, v0
	v_pk_fma_f32 v[16:17], v[16:17], 2.0, 1.0 op_sel_hi:[1,0,0] neg_lo:[1,0,0] neg_hi:[1,0,0]
	v_add_f32_e32 v0, 1.0, v0
	v_pk_add_f32 v[16:17], v[16:17], 1.0 op_sel_hi:[1,0]
	s_nop 0
	v_pk_mul_f32 v[10:11], v[10:11], v[16:17]
	v_rcp_f32_e32 v16, v0
	v_mul_f32_e32 v0, 0x3d372713, v13
	v_mul_f32_e32 v0, v13, v0
	v_fma_f32 v0, v13, v0, v13
	v_mul_f32_e32 v0, 0x3f4c422a, v0
	v_add_f32_e32 v0, v0, v0
	v_mul_f32_e32 v0, 0x3fb8aa3b, v0
	v_exp_f32_e32 v0, v0
	v_pk_mul_f32 v[12:13], v[12:13], 0.5 op_sel_hi:[1,0]
	v_cvt_pk_bf16_f32 v10, v10, v11
	v_add_f32_e32 v0, 1.0, v0
	v_rcp_f32_e32 v17, v0
	v_mul_f32_e32 v0, 0x3d372713, v6
	v_mul_f32_e32 v0, v6, v0
	v_fma_f32 v0, v6, v0, v6
	v_mul_f32_e32 v0, 0x3f4c422a, v0
	v_add_f32_e32 v0, v0, v0
	v_mul_f32_e32 v0, 0x3fb8aa3b, v0
	v_exp_f32_e32 v0, v0
	v_pk_fma_f32 v[16:17], v[16:17], 2.0, 1.0 op_sel_hi:[1,0,0] neg_lo:[1,0,0] neg_hi:[1,0,0]
	v_add_f32_e32 v0, 1.0, v0
	v_pk_add_f32 v[16:17], v[16:17], 1.0 op_sel_hi:[1,0]
	s_nop 0
	v_pk_mul_f32 v[12:13], v[12:13], v[16:17]
	s_nop 0
	v_cvt_pk_bf16_f32 v11, v12, v13
	global_store_dwordx2 v[14:15], v[10:11], off offset:32
	v_rcp_f32_e32 v10, v0
	v_mul_f32_e32 v0, 0x3d372713, v7
	v_mul_f32_e32 v0, v7, v0
	v_fma_f32 v0, v7, v0, v7
	v_mul_f32_e32 v0, 0x3f4c422a, v0
	v_add_f32_e32 v0, v0, v0
	v_mul_f32_e32 v0, 0x3fb8aa3b, v0
	v_exp_f32_e32 v0, v0
	v_pk_mul_f32 v[6:7], v[6:7], 0.5 op_sel_hi:[1,0]
	v_add_f32_e32 v0, 1.0, v0
	v_rcp_f32_e32 v11, v0
	v_mul_f32_e32 v0, 0x3d372713, v8
	v_mul_f32_e32 v0, v8, v0
	v_fma_f32 v0, v8, v0, v8
	v_mul_f32_e32 v0, 0x3f4c422a, v0
	v_add_f32_e32 v0, v0, v0
	v_mul_f32_e32 v0, 0x3fb8aa3b, v0
	v_exp_f32_e32 v0, v0
	v_pk_fma_f32 v[10:11], v[10:11], 2.0, 1.0 op_sel_hi:[1,0,0] neg_lo:[1,0,0] neg_hi:[1,0,0]
	v_add_f32_e32 v0, 1.0, v0
	v_pk_add_f32 v[10:11], v[10:11], 1.0 op_sel_hi:[1,0]
	s_nop 0
	v_pk_mul_f32 v[6:7], v[6:7], v[10:11]
	v_rcp_f32_e32 v10, v0
	v_mul_f32_e32 v0, 0x3d372713, v9
	v_mul_f32_e32 v0, v9, v0
	v_fma_f32 v0, v9, v0, v9
	v_mul_f32_e32 v0, 0x3f4c422a, v0
	v_add_f32_e32 v0, v0, v0
	v_mul_f32_e32 v0, 0x3fb8aa3b, v0
	v_exp_f32_e32 v0, v0
	v_pk_mul_f32 v[8:9], v[8:9], 0.5 op_sel_hi:[1,0]
	v_cvt_pk_bf16_f32 v6, v6, v7
	v_add_f32_e32 v0, 1.0, v0
	v_rcp_f32_e32 v11, v0
	v_mul_f32_e32 v0, 0x3d372713, v2
	v_mul_f32_e32 v0, v2, v0
	v_fma_f32 v0, v2, v0, v2
	v_mul_f32_e32 v0, 0x3f4c422a, v0
	v_add_f32_e32 v0, v0, v0
	v_mul_f32_e32 v0, 0x3fb8aa3b, v0
	v_exp_f32_e32 v0, v0
	v_pk_fma_f32 v[10:11], v[10:11], 2.0, 1.0 op_sel_hi:[1,0,0] neg_lo:[1,0,0] neg_hi:[1,0,0]
	v_add_f32_e32 v0, 1.0, v0
	v_pk_add_f32 v[10:11], v[10:11], 1.0 op_sel_hi:[1,0]
	s_nop 0
	v_pk_mul_f32 v[8:9], v[8:9], v[10:11]
	s_nop 0
	v_cvt_pk_bf16_f32 v7, v8, v9
	global_store_dwordx2 v[14:15], v[6:7], off offset:64
	v_rcp_f32_e32 v6, v0
	v_mul_f32_e32 v0, 0x3d372713, v3
	v_mul_f32_e32 v0, v3, v0
	v_fma_f32 v0, v3, v0, v3
	v_mul_f32_e32 v0, 0x3f4c422a, v0
	v_add_f32_e32 v0, v0, v0
	v_mul_f32_e32 v0, 0x3fb8aa3b, v0
	v_exp_f32_e32 v0, v0
	v_pk_mul_f32 v[2:3], v[2:3], 0.5 op_sel_hi:[1,0]
	v_add_f32_e32 v0, 1.0, v0
	v_rcp_f32_e32 v7, v0
	v_mul_f32_e32 v0, 0x3d372713, v4
	v_mul_f32_e32 v0, v4, v0
	v_fma_f32 v0, v4, v0, v4
	v_mul_f32_e32 v0, 0x3f4c422a, v0
	v_add_f32_e32 v0, v0, v0
	v_mul_f32_e32 v0, 0x3fb8aa3b, v0
	v_exp_f32_e32 v0, v0
	v_pk_fma_f32 v[6:7], v[6:7], 2.0, 1.0 op_sel_hi:[1,0,0] neg_lo:[1,0,0] neg_hi:[1,0,0]
	v_add_f32_e32 v0, 1.0, v0
	v_pk_add_f32 v[6:7], v[6:7], 1.0 op_sel_hi:[1,0]
	s_nop 0
	v_pk_mul_f32 v[2:3], v[2:3], v[6:7]
	v_rcp_f32_e32 v6, v0
	v_mul_f32_e32 v0, 0x3d372713, v5
	v_mul_f32_e32 v0, v5, v0
	v_fma_f32 v0, v5, v0, v5
	v_mul_f32_e32 v0, 0x3f4c422a, v0
	v_add_f32_e32 v0, v0, v0
	v_mul_f32_e32 v0, 0x3fb8aa3b, v0
	v_exp_f32_e32 v0, v0
	v_pk_mul_f32 v[4:5], v[4:5], 0.5 op_sel_hi:[1,0]
	v_cvt_pk_bf16_f32 v2, v2, v3
	v_add_f32_e32 v0, 1.0, v0
	v_rcp_f32_e32 v7, v0
	s_nop 0
	v_pk_fma_f32 v[6:7], v[6:7], 2.0, 1.0 op_sel_hi:[1,0,0] neg_lo:[1,0,0] neg_hi:[1,0,0]
	s_nop 0
	v_pk_add_f32 v[6:7], v[6:7], 1.0 op_sel_hi:[1,0]
	s_nop 0
	v_pk_mul_f32 v[4:5], v[4:5], v[6:7]
	s_nop 0
	v_cvt_pk_bf16_f32 v3, v4, v5
	global_store_dwordx2 v[14:15], v[2:3], off offset:96
	s_branch .LBB0_260

; DI int TID() { int t = threadIdx.x & 255; asm volatile("" : "+v"(t)); return t; }
; #define VBID ((int)(blockIdx.x * 2) + HALF())
; __global__ void __launch_bounds__(512, 2) mega(Params p) {
;     ...
;     float nsa_c;
;     {
;       const int ln = TID() & 63;
;       float gq = fabsf(p.nsa_q_norm[layer * 64 + ln]), gk = fabsf(p.nsa_k_norm[layer * 64 + ln]);
; #pragma unroll
;       for (int o = 32; o > 0; o >>= 1) {
;         gq = fmaxf(gq, shx(gq, o, ln));
;         gk = fmaxf(gk, shx(gk, o, ln));
;       }
;       nsa_c = 8.f * gq * gk;
;     }
;     const bool nsa_fx = nsa_c < 30.f;
;     const float nsa_cl = nsa_c * 1.4426950408889634f;
;     for (int t = VBID; t < 2048; t += nb) {
.LBB0_356:
	s_or_b64 exec, exec, s[0:1]
	v_and_b32_e32 v0, 0xff, v196
	s_barrier
	s_cmp_lg_u32 s101, 0
	s_cbranch_scc0 .Lnsa_prio_skip
.Lnsa_prio_skip:
	v_readlane_b32 s36, v251, 1
	v_and_b32_e32 v6, 63, v0
	v_or_b32_e32 v0, s6, v6
	v_lshlrev_b64 v[2:3], 2, v[0:1]
	v_readlane_b32 s44, v251, 9
	v_readlane_b32 s45, v251, 10
	v_readlane_b32 s46, v251, 11
	v_readlane_b32 s47, v251, 12
	v_lshl_add_u64 v[4:5], s[44:45], 0, v[2:3]
	global_load_dword v0, v[4:5], off
	v_lshl_add_u64 v[2:3], s[46:47], 0, v[2:3]
	global_load_dword v2, v[2:3], off
	v_lshlrev_b32_e32 v3, 2, v6
	v_xor_b32_e32 v4, 0x80, v3
	v_readfirstlane_b32 s1, v196
	s_lshr_b32 s0, s1, 8
	v_readlane_b32 s2, v252, 12
	s_add_i32 s20, s0, s2
	s_cmpk_lt_i32 s20, 0x800
	v_readlane_b32 s37, v251, 2
	v_readlane_b32 s38, v251, 3
	v_readlane_b32 s39, v251, 4
	v_readlane_b32 s40, v251, 5
	v_readlane_b32 s41, v251, 6
	v_readlane_b32 s42, v251, 7
	v_readlane_b32 s43, v251, 8
	v_readlane_b32 s48, v251, 13
	v_readlane_b32 s49, v251, 14
	v_readlane_b32 s50, v251, 15
	v_readlane_b32 s51, v251, 16
	s_waitcnt vmcnt(1)
	v_and_b32_e32 v5, 0x7fffffff, v0
	ds_bpermute_b32 v5, v4, v5
	s_waitcnt vmcnt(0)
	v_and_b32_e32 v6, 0x7fffffff, v2
	ds_bpermute_b32 v4, v4, v6
	v_max_f32_e64 v0, |v0|, |v0|
	v_max_f32_e64 v2, |v2|, |v2|
	s_waitcnt lgkmcnt(1)
	v_max_f32_e32 v5, v5, v5
	v_xor_b32_e32 v6, 64, v3
	s_waitcnt lgkmcnt(0)
	v_max_f32_e32 v4, v4, v4
	v_max_f32_e32 v0, v0, v5
	v_max_f32_e32 v2, v2, v4
	ds_bpermute_b32 v4, v6, v0
	ds_bpermute_b32 v5, v6, v2
	v_xor_b32_e32 v6, 32, v3
	s_waitcnt lgkmcnt(1)
	v_max_f32_e32 v4, v4, v4
	s_waitcnt lgkmcnt(0)
	v_max_f32_e32 v5, v5, v5
	v_max_f32_e32 v0, v0, v4
	v_max_f32_e32 v2, v2, v5
	ds_bpermute_b32 v4, v6, v0
	ds_bpermute_b32 v5, v6, v2
	v_xor_b32_e32 v6, 16, v3
	s_waitcnt lgkmcnt(1)
	v_max_f32_e32 v4, v4, v4
	s_waitcnt lgkmcnt(0)
	v_max_f32_e32 v5, v5, v5
	v_max_f32_e32 v0, v0, v4
	v_max_f32_e32 v2, v2, v5
	ds_bpermute_b32 v4, v6, v0
	ds_bpermute_b32 v5, v6, v2
	v_xor_b32_e32 v6, 8, v3
	v_xor_b32_e32 v3, 4, v3
	s_waitcnt lgkmcnt(1)
	v_max_f32_e32 v4, v4, v4
	s_waitcnt lgkmcnt(0)
	v_max_f32_e32 v5, v5, v5
	v_max_f32_e32 v0, v0, v4
	v_max_f32_e32 v4, v2, v5
	ds_bpermute_b32 v2, v6, v0
	ds_bpermute_b32 v5, v6, v4
	s_waitcnt lgkmcnt(1)
	v_max_f32_e32 v2, v2, v2
	s_waitcnt lgkmcnt(0)
	v_max_f32_e32 v5, v5, v5
	v_max_f32_e32 v2, v0, v2
	v_max_f32_e32 v0, v4, v5
	ds_bpermute_b32 v4, v3, v2
	ds_bpermute_b32 v3, v3, v0
	s_cbranch_scc0 .LBB0_733
	s_waitcnt lgkmcnt(1)
	v_max_f32_e32 v4, v4, v4
	v_max_f32_e32 v2, v2, v2
	v_max_f32_e32 v2, v2, v4
	s_waitcnt lgkmcnt(0)
	v_max_f32_e32 v3, v3, v3
	v_max_f32_e32 v0, v0, v0
	v_max_f32_e32 v0, v0, v3
	v_mul_f32_e32 v2, 0x41000000, v2
	v_mul_f32_e32 v0, v0, v2
	s_mov_b32 s2, 0x41f00000
	v_cmp_ngt_f32_e64 s[2:3], s2, v0
	s_bfe_u32 s1, s1, 0x10008
	v_mul_f32_e32 v205, 0xbfb8aa3b, v0
	v_writelane_b32 v254, s2, 55
	s_nop 1
	v_writelane_b32 v254, s3, 56
	s_lshl_b32 s2, s1, 8
	v_writelane_b32 v254, s2, 57
	s_lshl_b32 s2, s1, 9
	v_readlane_b32 s3, v252, 39
	s_add_u32 s4, s3, s2
	v_readlane_b32 s2, v252, 40
	s_addc_u32 s5, s2, 0
	v_writelane_b32 v254, s4, 58
	s_lshl_b32 s21, s1, 2
	s_lshl_b32 s1, s1, 7
	v_writelane_b32 v254, s5, 59
	s_add_u32 s2, s16, s1
	v_writelane_b32 v254, s2, 60
	s_addc_u32 s2, s17, 0
	v_writelane_b32 v254, s2, 61
	v_readlane_b32 s2, v252, 12
	s_add_i32 s24, s0, s2
	v_readlane_b32 s0, v254, 8
	s_add_u32 s2, s0, s1
	v_readlane_b32 s0, v254, 9
	s_addc_u32 s3, s0, 0
	v_writelane_b32 v254, s2, 62
	s_nop 1
	v_writelane_b32 v254, s3, 63
	s_branch .LBB0_360

; DI unsigned xb_add(unsigned* p, unsigned v) { return __hip_atomic_fetch_add(p, v, __ATOMIC_RELAXED, __HIP_MEMORY_SCOPE_AGENT); }
; DI void xcd_barrier(unsigned* bar, const unsigned x, const unsigned nloc, const unsigned nx) {
;   asm volatile("s_waitcnt vmcnt(0)" ::: "memory");
;   __syncthreads();
;   if (threadIdx.x == 0) {
;     __builtin_amdgcn_s_waitcnt(0);
;     const unsigned old = xb_add(&bar[XB_XSUB(x)], 1u);
;     const unsigned gen = old / nloc;
;     if (old + 1u == (gen + 1u) * nloc) {
;       __builtin_amdgcn_fence(__ATOMIC_RELEASE, "agent");
;       asm volatile("s_waitcnt vmcnt(0)" ::: "memory");
;       const unsigned og = xb_add(&bar[XB_TOP], 1u);
;       const unsigned tg = og / nx;
;       if (og + 1u == (tg + 1u) * nx) xb_add(&bar[XB_TOPGEN], 1u);
.LBB0_733:
	s_waitcnt vmcnt(0)
	s_waitcnt lgkmcnt(0)
	s_barrier
	s_mov_b64 s[0:1], exec
	v_readlane_b32 s2, v251, 48
	v_readlane_b32 s3, v251, 49
	v_readlane_b32 s38, v254, 43
	s_and_b64 s[2:3], s[0:1], s[2:3]
	v_readlane_b32 s39, v254, 44
	v_readlane_b32 s40, v254, 45
	v_readlane_b32 s36, v254, 49
	v_readlane_b32 s41, v254, 46
	v_readlane_b32 s37, v254, 50
	s_mov_b64 exec, s[2:3]
	s_cbranch_execz .LBB0_770
	s_mov_b64 s[2:3], exec
	v_mbcnt_lo_u32_b32 v0, s2, 0
	v_mbcnt_hi_u32_b32 v0, s3, v0
	v_cmp_eq_u32_e32 vcc, 0, v0
	s_waitcnt vmcnt(0) expcnt(0) lgkmcnt(0)
	s_and_saveexec_b64 s[4:5], vcc
	s_cbranch_execz .LBB0_736
	s_bcnt1_i32_b64 s2, s[2:3]
	v_mov_b32_e32 v2, s2
	v_readlane_b32 s2, v252, 13
	v_readlane_b32 s3, v252, 14
	s_nop 4
	global_atomic_add v2, v1, v2, s[2:3] sc0

; DI void gemm8_accum(f32x4 (&acc)[8][4], const bf16_t* a, size_t lda, const bf16_t* b, size_t ldb, int nkb, bf16_t* L,
;                     const bool pre, const bf16_t* an, size_t ldan, const bf16_t* bn, size_t ldbn) {
;     ...
;   for (int kb = 0; kb + 2 < nkb; ++kb) {
;     __syncthreads();
;     g8_store1(L + ((kb + 1) & 1) * 32768, ra, lrow, lch);
;     g8_load1o(ra, a + (kb + 2) * 64, offa);
;     __builtin_amdgcn_sched_barrier(0);
;     g8_compute<0, 1>(acc, L + (kb & 1) * 32768, wm, wn, lane);
;     __builtin_amdgcn_sched_barrier(0);
;     g8_store1(L + ((kb + 1) & 1) * 32768 + 16384, rb, lrow, lch);
;     g8_load1o(rb, b + (kb + 2) * 64, offb);
;     __builtin_amdgcn_sched_barrier(0);
;     g8_compute<1, 2>(acc, L + (kb & 1) * 32768, wm, wn, lane);
;   }
.LBB0_778:
	s_add_i32 s3, s2, 0x8000
	s_and_b32 s20, s3, 0x8000
	v_lshl_add_u32 v191, s20, 1, v163
	s_waitcnt lgkmcnt(0)
	s_barrier
	s_cmp_eq_u32 s100, 0
	s_cbranch_scc1 .Lstg_778_a
	v_mfma_f32_16x16x32_bf16 v[158:161], v[230:233], v[192:195], v[158:161]
	v_mfma_f32_16x16x32_bf16 v[154:157], v[234:237], v[192:195], v[154:157]
	v_mfma_f32_16x16x32_bf16 v[150:153], v[238:241], v[192:195], v[150:153]
	v_mfma_f32_16x16x32_bf16 v[146:149], v[242:245], v[192:195], v[146:149]
	v_mfma_f32_16x16x32_bf16 v[142:145], v[230:233], v[198:201], v[142:145]
	v_mfma_f32_16x16x32_bf16 v[138:141], v[234:237], v[198:201], v[138:141]
	v_mfma_f32_16x16x32_bf16 v[134:137], v[238:241], v[198:201], v[134:137]
	v_mfma_f32_16x16x32_bf16 v[130:133], v[242:245], v[198:201], v[130:133]
	v_mfma_f32_16x16x32_bf16 v[126:129], v[230:233], v[206:209], v[126:129]
	v_mfma_f32_16x16x32_bf16 v[122:125], v[234:237], v[206:209], v[122:125]
	v_mfma_f32_16x16x32_bf16 v[118:121], v[238:241], v[206:209], v[118:121]
	v_mfma_f32_16x16x32_bf16 v[114:117], v[242:245], v[206:209], v[114:117]
	v_mfma_f32_16x16x32_bf16 v[110:113], v[230:233], v[210:213], v[110:113]
	v_mfma_f32_16x16x32_bf16 v[106:109], v[234:237], v[210:213], v[106:109]
	v_mfma_f32_16x16x32_bf16 v[102:105], v[238:241], v[210:213], v[102:105]
	v_mfma_f32_16x16x32_bf16 v[98:101], v[242:245], v[210:213], v[98:101]
	v_mfma_f32_16x16x32_bf16 v[94:97], v[230:233], v[214:217], v[94:97]
	v_mfma_f32_16x16x32_bf16 v[90:93], v[234:237], v[214:217], v[90:93]
	v_mfma_f32_16x16x32_bf16 v[86:89], v[238:241], v[214:217], v[86:89]
	v_mfma_f32_16x16x32_bf16 v[82:85], v[242:245], v[214:217], v[82:85]
	v_mfma_f32_16x16x32_bf16 v[78:81], v[230:233], v[218:221], v[78:81]
	v_mfma_f32_16x16x32_bf16 v[74:77], v[234:237], v[218:221], v[74:77]
	v_mfma_f32_16x16x32_bf16 v[70:73], v[238:241], v[218:221], v[70:73]
	v_mfma_f32_16x16x32_bf16 v[66:69], v[242:245], v[218:221], v[66:69]
	v_mfma_f32_16x16x32_bf16 v[62:65], v[230:233], v[222:225], v[62:65]
	v_mfma_f32_16x16x32_bf16 v[58:61], v[234:237], v[222:225], v[58:61]
	v_mfma_f32_16x16x32_bf16 v[54:57], v[238:241], v[222:225], v[54:57]
	v_mfma_f32_16x16x32_bf16 v[50:53], v[242:245], v[222:225], v[50:53]
	v_mfma_f32_16x16x32_bf16 v[46:49], v[230:233], v[226:229], v[46:49]
	v_mfma_f32_16x16x32_bf16 v[42:45], v[234:237], v[226:229], v[42:45]
	v_mfma_f32_16x16x32_bf16 v[38:41], v[238:241], v[226:229], v[38:41]
	v_mfma_f32_16x16x32_bf16 v[34:37], v[242:245], v[226:229], v[34:37]
.Lstg_778_a:
	s_waitcnt vmcnt(5)
	ds_write_b128 v191, v[22:25]
	ds_write_b128 v191, v[18:21] offset:8192
	ds_write_b128 v191, v[26:29] offset:16384
	s_waitcnt vmcnt(4)
	ds_write_b128 v191, v[30:33] offset:24576
	v_lshl_add_u64 v[18:19], v[186:187], 0, s[0:1]
	v_lshl_add_u64 v[26:27], v[182:183], 0, s[0:1]
	global_load_dwordx4 v[22:25], v[18:19], off
	v_lshl_add_u64 v[30:31], v[180:181], 0, s[0:1]
	global_load_dwordx4 v[26:29], v[26:27], off
	v_lshl_add_u64 v[18:19], v[184:185], 0, s[0:1]
	global_load_dwordx4 v[18:21], v[18:19], off
	s_nop 0
	global_load_dwordx4 v[30:33], v[30:31], off
	s_and_b32 s2, s2, 0x8000
	s_lshl_b32 s2, s2, 1
	s_add_i32 s2, s2, 0
	v_lshl_add_u32 v202, v169, 1, s2
	v_add_u32_e32 v203, v202, v188
	ds_read_b128 v[192:195], v203
	ds_read_b128 v[198:201], v203 offset:2048
	ds_read_b128 v[206:209], v203 offset:4096
	ds_read_b128 v[210:213], v203 offset:6144
	ds_read_b128 v[214:217], v203 offset:8192
	ds_read_b128 v[218:221], v203 offset:10240
	ds_read_b128 v[222:225], v203 offset:12288
	ds_read_b128 v[226:229], v203 offset:14336
	v_add_u32_e32 v202, v202, v171
	ds_read_b128 v[230:233], v202 offset:32768
	ds_read_b128 v[234:237], v202 offset:34816
	ds_read_b128 v[238:241], v202 offset:36864
	ds_read_b128 v[242:245], v202 offset:38912
	s_waitcnt lgkmcnt(3)
	v_mfma_f32_16x16x32_bf16 v[158:161], v[230:233], v[192:195], v[158:161]
	s_waitcnt lgkmcnt(2)
	v_mfma_f32_16x16x32_bf16 v[154:157], v[234:237], v[192:195], v[154:157]
	s_waitcnt lgkmcnt(1)
	v_mfma_f32_16x16x32_bf16 v[150:153], v[238:241], v[192:195], v[150:153]
	s_waitcnt lgkmcnt(0)
	v_mfma_f32_16x16x32_bf16 v[146:149], v[242:245], v[192:195], v[146:149]
	v_mfma_f32_16x16x32_bf16 v[142:145], v[230:233], v[198:201], v[142:145]
	v_mfma_f32_16x16x32_bf16 v[138:141], v[234:237], v[198:201], v[138:141]
	v_mfma_f32_16x16x32_bf16 v[134:137], v[238:241], v[198:201], v[134:137]
	v_mfma_f32_16x16x32_bf16 v[130:133], v[242:245], v[198:201], v[130:133]
	v_mfma_f32_16x16x32_bf16 v[126:129], v[230:233], v[206:209], v[126:129]
	v_mfma_f32_16x16x32_bf16 v[122:125], v[234:237], v[206:209], v[122:125]
	v_mfma_f32_16x16x32_bf16 v[118:121], v[238:241], v[206:209], v[118:121]
	v_mfma_f32_16x16x32_bf16 v[114:117], v[242:245], v[206:209], v[114:117]
	v_mfma_f32_16x16x32_bf16 v[110:113], v[230:233], v[210:213], v[110:113]
	v_mfma_f32_16x16x32_bf16 v[106:109], v[234:237], v[210:213], v[106:109]
	v_mfma_f32_16x16x32_bf16 v[102:105], v[238:241], v[210:213], v[102:105]
	v_mfma_f32_16x16x32_bf16 v[98:101], v[242:245], v[210:213], v[98:101]
	v_mfma_f32_16x16x32_bf16 v[94:97], v[230:233], v[214:217], v[94:97]
	v_mfma_f32_16x16x32_bf16 v[90:93], v[234:237], v[214:217], v[90:93]
	v_mfma_f32_16x16x32_bf16 v[86:89], v[238:241], v[214:217], v[86:89]
	v_mfma_f32_16x16x32_bf16 v[82:85], v[242:245], v[214:217], v[82:85]
	v_mfma_f32_16x16x32_bf16 v[78:81], v[230:233], v[218:221], v[78:81]
	v_mfma_f32_16x16x32_bf16 v[74:77], v[234:237], v[218:221], v[74:77]
	v_mfma_f32_16x16x32_bf16 v[70:73], v[238:241], v[218:221], v[70:73]
	v_mfma_f32_16x16x32_bf16 v[66:69], v[242:245], v[218:221], v[66:69]
	v_mfma_f32_16x16x32_bf16 v[62:65], v[230:233], v[222:225], v[62:65]
	v_mfma_f32_16x16x32_bf16 v[58:61], v[234:237], v[222:225], v[58:61]
	v_mfma_f32_16x16x32_bf16 v[54:57], v[238:241], v[222:225], v[54:57]
	v_mfma_f32_16x16x32_bf16 v[50:53], v[242:245], v[222:225], v[50:53]
	v_mfma_f32_16x16x32_bf16 v[46:49], v[230:233], v[226:229], v[46:49]
	v_mfma_f32_16x16x32_bf16 v[42:45], v[234:237], v[226:229], v[42:45]
	v_mfma_f32_16x16x32_bf16 v[38:41], v[238:241], v[226:229], v[38:41]
	v_mfma_f32_16x16x32_bf16 v[34:37], v[242:245], v[226:229], v[34:37]
	s_waitcnt vmcnt(7)
; DI void gemm8_accum(f32x4 (&acc)[8][4], const bf16_t* a, size_t lda, const bf16_t* b, size_t ldb, int nkb, bf16_t* L,
;                     const bool pre, const bf16_t* an, size_t ldan, const bf16_t* bn, size_t ldbn) {
;     ...
;   for (int kb = 0; kb + 2 < nkb; ++kb) {
;     __syncthreads();
;     g8_store1(L + ((kb + 1) & 1) * 32768, ra, lrow, lch);
;     g8_load1o(ra, a + (kb + 2) * 64, offa);
;     __builtin_amdgcn_sched_barrier(0);
;     g8_compute<0, 1>(acc, L + (kb & 1) * 32768, wm, wn, lane);
;     __builtin_amdgcn_sched_barrier(0);
;     g8_store1(L + ((kb + 1) & 1) * 32768 + 16384, rb, lrow, lch);
;     g8_load1o(rb, b + (kb + 2) * 64, offb);
;     __builtin_amdgcn_sched_barrier(0);
;     g8_compute<1, 2>(acc, L + (kb & 1) * 32768, wm, wn, lane);
;   }
	ds_write_b128 v191, v[14:17] offset:32768
	s_waitcnt vmcnt(6)
	ds_write_b128 v191, v[2:5] offset:40960
	s_waitcnt vmcnt(5)
	ds_write_b128 v191, v[6:9] offset:49152
	s_waitcnt vmcnt(4)
	ds_write_b128 v191, v[10:13] offset:57344
	v_lshl_add_u64 v[2:3], v[178:179], 0, s[0:1]
	v_lshl_add_u64 v[4:5], v[176:177], 0, s[0:1]
	v_lshl_add_u64 v[6:7], v[174:175], 0, s[0:1]
	v_lshl_add_u64 v[10:11], v[172:173], 0, s[0:1]
	global_load_dwordx4 v[14:17], v[2:3], off
	s_nop 0
	global_load_dwordx4 v[2:5], v[4:5], off
	s_nop 0
	global_load_dwordx4 v[6:9], v[6:7], off
	s_nop 0
	global_load_dwordx4 v[10:13], v[10:11], off
	v_lshl_add_u32 v191, v189, 1, s2
	v_add_u32_e32 v202, v191, v188
	ds_read_b128 v[192:195], v202
	ds_read_b128 v[198:201], v202 offset:2048
	ds_read_b128 v[206:209], v202 offset:4096
	ds_read_b128 v[210:213], v202 offset:6144
	ds_read_b128 v[214:217], v202 offset:8192
	ds_read_b128 v[218:221], v202 offset:10240
	ds_read_b128 v[222:225], v202 offset:12288
	ds_read_b128 v[226:229], v202 offset:14336
	v_add_u32_e32 v191, v191, v171
	ds_read_b128 v[230:233], v191 offset:32768
	ds_read_b128 v[234:237], v191 offset:34816
	ds_read_b128 v[238:241], v191 offset:36864
	ds_read_b128 v[242:245], v191 offset:38912
	s_cmp_lg_u32 s101, 0
	s_cbranch_scc1 .Lstg_778_b
	s_waitcnt lgkmcnt(3)
	v_mfma_f32_16x16x32_bf16 v[158:161], v[230:233], v[192:195], v[158:161]
	s_waitcnt lgkmcnt(2)
	v_mfma_f32_16x16x32_bf16 v[154:157], v[234:237], v[192:195], v[154:157]
	s_waitcnt lgkmcnt(1)
	v_mfma_f32_16x16x32_bf16 v[150:153], v[238:241], v[192:195], v[150:153]
	s_waitcnt lgkmcnt(0)
	v_mfma_f32_16x16x32_bf16 v[146:149], v[242:245], v[192:195], v[146:149]
	v_mfma_f32_16x16x32_bf16 v[142:145], v[230:233], v[198:201], v[142:145]
	v_mfma_f32_16x16x32_bf16 v[138:141], v[234:237], v[198:201], v[138:141]
	v_mfma_f32_16x16x32_bf16 v[134:137], v[238:241], v[198:201], v[134:137]
	v_mfma_f32_16x16x32_bf16 v[130:133], v[242:245], v[198:201], v[130:133]
	v_mfma_f32_16x16x32_bf16 v[126:129], v[230:233], v[206:209], v[126:129]
	v_mfma_f32_16x16x32_bf16 v[122:125], v[234:237], v[206:209], v[122:125]
	v_mfma_f32_16x16x32_bf16 v[118:121], v[238:241], v[206:209], v[118:121]
	v_mfma_f32_16x16x32_bf16 v[114:117], v[242:245], v[206:209], v[114:117]
	v_mfma_f32_16x16x32_bf16 v[110:113], v[230:233], v[210:213], v[110:113]
	v_mfma_f32_16x16x32_bf16 v[106:109], v[234:237], v[210:213], v[106:109]
	v_mfma_f32_16x16x32_bf16 v[102:105], v[238:241], v[210:213], v[102:105]
	v_mfma_f32_16x16x32_bf16 v[98:101], v[242:245], v[210:213], v[98:101]
	v_mfma_f32_16x16x32_bf16 v[94:97], v[230:233], v[214:217], v[94:97]
	v_mfma_f32_16x16x32_bf16 v[90:93], v[234:237], v[214:217], v[90:93]
	v_mfma_f32_16x16x32_bf16 v[86:89], v[238:241], v[214:217], v[86:89]
	v_mfma_f32_16x16x32_bf16 v[82:85], v[242:245], v[214:217], v[82:85]
	v_mfma_f32_16x16x32_bf16 v[78:81], v[230:233], v[218:221], v[78:81]
	v_mfma_f32_16x16x32_bf16 v[74:77], v[234:237], v[218:221], v[74:77]
	v_mfma_f32_16x16x32_bf16 v[70:73], v[238:241], v[218:221], v[70:73]
	v_mfma_f32_16x16x32_bf16 v[66:69], v[242:245], v[218:221], v[66:69]
	v_mfma_f32_16x16x32_bf16 v[62:65], v[230:233], v[222:225], v[62:65]
	v_mfma_f32_16x16x32_bf16 v[58:61], v[234:237], v[222:225], v[58:61]
	v_mfma_f32_16x16x32_bf16 v[54:57], v[238:241], v[222:225], v[54:57]
	v_mfma_f32_16x16x32_bf16 v[50:53], v[242:245], v[222:225], v[50:53]
	v_mfma_f32_16x16x32_bf16 v[46:49], v[230:233], v[226:229], v[46:49]
	v_mfma_f32_16x16x32_bf16 v[42:45], v[234:237], v[226:229], v[42:45]
	v_mfma_f32_16x16x32_bf16 v[38:41], v[238:241], v[226:229], v[38:41]
	v_mfma_f32_16x16x32_bf16 v[34:37], v[242:245], v[226:229], v[34:37]
.Lstg_778_b:
	s_mov_b32 s100, s101
	s_add_u32 s0, s0, 0x80
	s_addc_u32 s1, s1, 0
	s_cmpk_lg_i32 s0, 0x300
	s_mov_b32 s2, s3
	s_cbranch_scc1 .LBB0_778
	s_cmp_eq_u32 s100, 0
	s_cbranch_scc1 .Lstg_778_c
	s_waitcnt lgkmcnt(0)
	v_mfma_f32_16x16x32_bf16 v[158:161], v[230:233], v[192:195], v[158:161]
	v_mfma_f32_16x16x32_bf16 v[154:157], v[234:237], v[192:195], v[154:157]
	v_mfma_f32_16x16x32_bf16 v[150:153], v[238:241], v[192:195], v[150:153]
	v_mfma_f32_16x16x32_bf16 v[146:149], v[242:245], v[192:195], v[146:149]
	v_mfma_f32_16x16x32_bf16 v[142:145], v[230:233], v[198:201], v[142:145]
	v_mfma_f32_16x16x32_bf16 v[138:141], v[234:237], v[198:201], v[138:141]
	v_mfma_f32_16x16x32_bf16 v[134:137], v[238:241], v[198:201], v[134:137]
	v_mfma_f32_16x16x32_bf16 v[130:133], v[242:245], v[198:201], v[130:133]
	v_mfma_f32_16x16x32_bf16 v[126:129], v[230:233], v[206:209], v[126:129]
	v_mfma_f32_16x16x32_bf16 v[122:125], v[234:237], v[206:209], v[122:125]
	v_mfma_f32_16x16x32_bf16 v[118:121], v[238:241], v[206:209], v[118:121]
	v_mfma_f32_16x16x32_bf16 v[114:117], v[242:245], v[206:209], v[114:117]
	v_mfma_f32_16x16x32_bf16 v[110:113], v[230:233], v[210:213], v[110:113]
	v_mfma_f32_16x16x32_bf16 v[106:109], v[234:237], v[210:213], v[106:109]
	v_mfma_f32_16x16x32_bf16 v[102:105], v[238:241], v[210:213], v[102:105]
	v_mfma_f32_16x16x32_bf16 v[98:101], v[242:245], v[210:213], v[98:101]
	v_mfma_f32_16x16x32_bf16 v[94:97], v[230:233], v[214:217], v[94:97]
	v_mfma_f32_16x16x32_bf16 v[90:93], v[234:237], v[214:217], v[90:93]
	v_mfma_f32_16x16x32_bf16 v[86:89], v[238:241], v[214:217], v[86:89]
	v_mfma_f32_16x16x32_bf16 v[82:85], v[242:245], v[214:217], v[82:85]
	v_mfma_f32_16x16x32_bf16 v[78:81], v[230:233], v[218:221], v[78:81]
	v_mfma_f32_16x16x32_bf16 v[74:77], v[234:237], v[218:221], v[74:77]
	v_mfma_f32_16x16x32_bf16 v[70:73], v[238:241], v[218:221], v[70:73]
	v_mfma_f32_16x16x32_bf16 v[66:69], v[242:245], v[218:221], v[66:69]
	v_mfma_f32_16x16x32_bf16 v[62:65], v[230:233], v[222:225], v[62:65]
	v_mfma_f32_16x16x32_bf16 v[58:61], v[234:237], v[222:225], v[58:61]
	v_mfma_f32_16x16x32_bf16 v[54:57], v[238:241], v[222:225], v[54:57]
	v_mfma_f32_16x16x32_bf16 v[50:53], v[242:245], v[222:225], v[50:53]
	v_mfma_f32_16x16x32_bf16 v[46:49], v[230:233], v[226:229], v[46:49]
	v_mfma_f32_16x16x32_bf16 v[42:45], v[234:237], v[226:229], v[42:45]
	v_mfma_f32_16x16x32_bf16 v[38:41], v[238:241], v[226:229], v[38:41]
	v_mfma_f32_16x16x32_bf16 v[34:37], v[242:245], v[226:229], v[34:37]
	s_mov_b32 s100, 0
; DI void gemm8_accum(f32x4 (&acc)[8][4], const bf16_t* a, size_t lda, const bf16_t* b, size_t ldb, int nkb, bf16_t* L,
;                     const bool pre, const bf16_t* an, size_t ldan, const bf16_t* bn, size_t ldbn) {
;     ...
;   __syncthreads();
;   g8_store1(L + 32768, ra, lrow, lch);
;   g8_load1(ra, an, ldan, 0, lrow, lch);
;   __builtin_amdgcn_sched_barrier(0);
;   g8_compute<0, 1>(acc, L, wm, wn, lane);
;   __builtin_amdgcn_sched_barrier(0);
;   g8_store1(L + 32768 + 16384, rb, lrow, lch);
;   g8_load1(rb, bn, ldbn, 0, lrow, lch);
;   __builtin_amdgcn_sched_barrier(0);
;   g8_compute<1, 2>(acc, L, wm, wn, lane);
;   __syncthreads();
;   g8_store1(L, ra, lrow, lch);
;   __builtin_amdgcn_sched_barrier(0);
;   g8_compute<0, 1>(acc, L + 32768, wm, wn, lane);
.Lstg_778_c:
	s_mul_i32 s0, s13, 0x2a30
	s_movk_i32 s25, 0x1518
	s_add_u32 s2, s16, s0
	v_mad_u64_u32 v[180:181], s[0:1], v190, s25, v[170:171]
	s_addc_u32 s3, s17, 0
	v_mov_b32_e32 v181, v1
	v_lshl_add_u64 v[172:173], v[180:181], 1, s[2:3]
	v_add_u32_e32 v174, 0x54600, v180
	v_mov_b32_e32 v175, v1
	v_add_u32_e32 v182, 0xa8c00, v180
	v_mov_b32_e32 v183, v1
	v_add_u32_e32 v180, 0xfd200, v180
	v_lshl_add_u64 v[176:177], v[174:175], 1, s[2:3]
	v_lshl_add_u64 v[182:183], v[182:183], 1, s[2:3]
	v_lshl_add_u64 v[184:185], v[180:181], 1, s[2:3]
	s_barrier
	global_load_dwordx4 v[172:175], v[172:173], off offset:2608
	s_nop 0
	global_load_dwordx4 v[176:179], v[176:177], off offset:2608
	s_nop 0
	global_load_dwordx4 v[180:183], v[182:183], off offset:2608
	s_nop 0
	global_load_dwordx4 v[184:187], v[184:185], off offset:2608
	s_mul_i32 s0, s7, 0x2a3000
	s_lshl_b32 s1, s6, 1
	v_readlane_b32 s6, v252, 1
	v_readlane_b32 s7, v252, 2
	s_add_u32 s6, s6, s1
	s_addc_u32 s7, s7, 0
	s_add_i32 s20, 0, 0x10000
	v_add3_u32 v170, s20, v165, v167
	s_waitcnt vmcnt(11)
	ds_write_b128 v170, v[22:25]
	s_waitcnt vmcnt(9)
	ds_write_b128 v170, v[18:21] offset:8192
	ds_write_b128 v170, v[26:29] offset:16384
	s_waitcnt vmcnt(8)
	ds_write_b128 v170, v[30:33] offset:24576
	v_lshlrev_b32_e32 v170, 1, v169
	v_add_u32_e32 v169, 0, v170
	v_add_u32_e32 v194, v169, v188
	ds_read_b128 v[18:21], v194
	ds_read_b128 v[22:25], v194 offset:2048
	ds_read_b128 v[26:29], v194 offset:4096
	ds_read_b128 v[30:33], v194 offset:6144
	ds_read_b128 v[190:193], v194 offset:8192
	ds_read_b128 v[198:201], v194 offset:10240
	ds_read_b128 v[206:209], v194 offset:12288
	ds_read_b128 v[210:213], v194 offset:14336
	v_add_u32_e32 v169, v169, v171
	ds_read_b128 v[214:217], v169 offset:32768
	ds_read_b128 v[218:221], v169 offset:34816
	ds_read_b128 v[222:225], v169 offset:36864
	ds_read_b128 v[226:229], v169 offset:38912
	s_waitcnt lgkmcnt(3)
	v_mfma_f32_16x16x32_bf16 v[158:161], v[214:217], v[18:21], v[158:161]
	s_waitcnt lgkmcnt(2)
	v_mfma_f32_16x16x32_bf16 v[154:157], v[218:221], v[18:21], v[154:157]
	s_waitcnt lgkmcnt(1)
	v_mfma_f32_16x16x32_bf16 v[150:153], v[222:225], v[18:21], v[150:153]
	s_waitcnt lgkmcnt(0)
	v_mfma_f32_16x16x32_bf16 v[18:21], v[226:229], v[18:21], v[146:149]
	v_mfma_f32_16x16x32_bf16 v[142:145], v[214:217], v[22:25], v[142:145]
	v_mfma_f32_16x16x32_bf16 v[138:141], v[218:221], v[22:25], v[138:141]
	v_mfma_f32_16x16x32_bf16 v[134:137], v[222:225], v[22:25], v[134:137]
	v_mfma_f32_16x16x32_bf16 v[22:25], v[226:229], v[22:25], v[130:133]
	v_mfma_f32_16x16x32_bf16 v[126:129], v[214:217], v[26:29], v[126:129]
	v_mfma_f32_16x16x32_bf16 v[122:125], v[218:221], v[26:29], v[122:125]
	v_mfma_f32_16x16x32_bf16 v[118:121], v[222:225], v[26:29], v[118:121]
	v_mfma_f32_16x16x32_bf16 v[26:29], v[226:229], v[26:29], v[114:117]
	v_mfma_f32_16x16x32_bf16 v[110:113], v[214:217], v[30:33], v[110:113]
	v_mfma_f32_16x16x32_bf16 v[106:109], v[218:221], v[30:33], v[106:109]
	v_mfma_f32_16x16x32_bf16 v[102:105], v[222:225], v[30:33], v[102:105]
	v_mfma_f32_16x16x32_bf16 v[30:33], v[226:229], v[30:33], v[98:101]
	v_mfma_f32_16x16x32_bf16 v[94:97], v[214:217], v[190:193], v[94:97]
	v_mfma_f32_16x16x32_bf16 v[90:93], v[218:221], v[190:193], v[90:93]
	v_mfma_f32_16x16x32_bf16 v[86:89], v[222:225], v[190:193], v[86:89]
	v_mfma_f32_16x16x32_bf16 v[82:85], v[226:229], v[190:193], v[82:85]
	v_mfma_f32_16x16x32_bf16 v[78:81], v[214:217], v[198:201], v[78:81]
	v_mfma_f32_16x16x32_bf16 v[74:77], v[218:221], v[198:201], v[74:77]
	v_mfma_f32_16x16x32_bf16 v[70:73], v[222:225], v[198:201], v[70:73]
	v_mfma_f32_16x16x32_bf16 v[66:69], v[226:229], v[198:201], v[66:69]
	v_mfma_f32_16x16x32_bf16 v[62:65], v[214:217], v[206:209], v[62:65]
	v_mfma_f32_16x16x32_bf16 v[58:61], v[218:221], v[206:209], v[58:61]
	v_mfma_f32_16x16x32_bf16 v[54:57], v[222:225], v[206:209], v[54:57]
	v_mfma_f32_16x16x32_bf16 v[50:53], v[226:229], v[206:209], v[50:53]
	v_mfma_f32_16x16x32_bf16 v[46:49], v[214:217], v[210:213], v[46:49]
	v_mfma_f32_16x16x32_bf16 v[42:45], v[218:221], v[210:213], v[42:45]
	v_mfma_f32_16x16x32_bf16 v[38:41], v[222:225], v[210:213], v[38:41]
	v_mfma_f32_16x16x32_bf16 v[34:37], v[226:229], v[210:213], v[34:37]
	v_readlane_b32 s1, v254, 36
	v_mov_b32_e32 v169, v1
	s_nop 0
	v_add3_u32 v98, s1, v165, v167
	v_mov_b32_e32 v167, v1
	v_mov_b32_e32 v165, v1
	s_waitcnt vmcnt(7)
	ds_write_b128 v98, v[14:17]
	s_waitcnt vmcnt(6)
	ds_write_b128 v98, v[2:5] offset:8192
	s_waitcnt vmcnt(5)
	ds_write_b128 v98, v[6:9] offset:16384
	s_waitcnt vmcnt(4)
	ds_write_b128 v98, v[10:13] offset:24576
	v_lshl_add_u64 v[2:3], v[0:1], 1, s[6:7]
	v_lshl_add_u64 v[6:7], v[168:169], 1, s[6:7]
	v_lshl_add_u64 v[10:11], v[166:167], 1, s[6:7]
	v_lshl_add_u64 v[14:15], v[164:165], 1, s[6:7]
	global_load_dwordx4 v[2:5], v[2:3], off
	s_nop 0
	global_load_dwordx4 v[6:9], v[6:7], off
	s_nop 0
	global_load_dwordx4 v[10:13], v[10:11], off
	s_nop 0
	global_load_dwordx4 v[14:17], v[14:15], off
	v_lshlrev_b32_e32 v0, 1, v189
	v_add_u32_e32 v168, 0, v0
	v_add_u32_e32 v169, v168, v188
	ds_read_b128 v[98:101], v169
	ds_read_b128 v[114:117], v169 offset:2048
	ds_read_b128 v[130:133], v169 offset:4096
	ds_read_b128 v[146:149], v169 offset:6144
	ds_read_b128 v[164:167], v169 offset:8192
	ds_read_b128 v[190:193], v169 offset:10240
	ds_read_b128 v[198:201], v169 offset:12288
	ds_read_b128 v[206:209], v169 offset:14336
	v_add_u32_e32 v168, v168, v171
	ds_read_b128 v[210:213], v168 offset:32768
	ds_read_b128 v[214:217], v168 offset:34816
	ds_read_b128 v[218:221], v168 offset:36864
	ds_read_b128 v[222:225], v168 offset:38912
	s_waitcnt lgkmcnt(3)
; DI void gemm8_accum(f32x4 (&acc)[8][4], const bf16_t* a, size_t lda, const bf16_t* b, size_t ldb, int nkb, bf16_t* L,
;                     const bool pre, const bf16_t* an, size_t ldan, const bf16_t* bn, size_t ldbn) {
;     ...
;   g8_compute<0, 1>(acc, L, wm, wn, lane);
;   __builtin_amdgcn_sched_barrier(0);
;   g8_store1(L + 32768 + 16384, rb, lrow, lch);
;   g8_load1(rb, bn, ldbn, 0, lrow, lch);
;   __builtin_amdgcn_sched_barrier(0);
;   g8_compute<1, 2>(acc, L, wm, wn, lane);
;   __syncthreads();
;   g8_store1(L, ra, lrow, lch);
;   __builtin_amdgcn_sched_barrier(0);
;   g8_compute<0, 1>(acc, L + 32768, wm, wn, lane);
;   __builtin_amdgcn_sched_barrier(0);
;   g8_store1(L + 16384, rb, lrow, lch);
;   __builtin_amdgcn_sched_barrier(0);
;   g8_compute<1, 2>(acc, L + 32768, wm, wn, lane);
	v_mfma_f32_16x16x32_bf16 v[158:161], v[210:213], v[98:101], v[158:161]
	s_waitcnt lgkmcnt(2)
	v_mfma_f32_16x16x32_bf16 v[154:157], v[214:217], v[98:101], v[154:157]
	s_waitcnt lgkmcnt(1)
	v_mfma_f32_16x16x32_bf16 v[150:153], v[218:221], v[98:101], v[150:153]
	s_waitcnt lgkmcnt(0)
	v_mfma_f32_16x16x32_bf16 v[18:21], v[222:225], v[98:101], v[18:21]
	v_mfma_f32_16x16x32_bf16 v[98:101], v[210:213], v[114:117], v[142:145]
	v_mfma_f32_16x16x32_bf16 v[138:141], v[214:217], v[114:117], v[138:141]
	v_mfma_f32_16x16x32_bf16 v[134:137], v[218:221], v[114:117], v[134:137]
	v_mfma_f32_16x16x32_bf16 v[22:25], v[222:225], v[114:117], v[22:25]
	v_mfma_f32_16x16x32_bf16 v[114:117], v[210:213], v[130:133], v[126:129]
	v_mfma_f32_16x16x32_bf16 v[122:125], v[214:217], v[130:133], v[122:125]
	v_mfma_f32_16x16x32_bf16 v[118:121], v[218:221], v[130:133], v[118:121]
	v_mfma_f32_16x16x32_bf16 v[26:29], v[222:225], v[130:133], v[26:29]
	v_mfma_f32_16x16x32_bf16 v[110:113], v[210:213], v[146:149], v[110:113]
	v_mfma_f32_16x16x32_bf16 v[106:109], v[214:217], v[146:149], v[106:109]
	v_mfma_f32_16x16x32_bf16 v[102:105], v[218:221], v[146:149], v[102:105]
	v_mfma_f32_16x16x32_bf16 v[30:33], v[222:225], v[146:149], v[30:33]
	v_mfma_f32_16x16x32_bf16 v[94:97], v[210:213], v[164:167], v[94:97]
	v_mfma_f32_16x16x32_bf16 v[90:93], v[214:217], v[164:167], v[90:93]
	v_mfma_f32_16x16x32_bf16 v[86:89], v[218:221], v[164:167], v[86:89]
	v_mfma_f32_16x16x32_bf16 v[82:85], v[222:225], v[164:167], v[82:85]
	v_mfma_f32_16x16x32_bf16 v[78:81], v[210:213], v[190:193], v[78:81]
	v_mfma_f32_16x16x32_bf16 v[74:77], v[214:217], v[190:193], v[74:77]
	v_mfma_f32_16x16x32_bf16 v[70:73], v[218:221], v[190:193], v[70:73]
	v_mfma_f32_16x16x32_bf16 v[66:69], v[222:225], v[190:193], v[66:69]
	v_mfma_f32_16x16x32_bf16 v[62:65], v[210:213], v[198:201], v[62:65]
	v_mfma_f32_16x16x32_bf16 v[58:61], v[214:217], v[198:201], v[58:61]
	v_mfma_f32_16x16x32_bf16 v[54:57], v[218:221], v[198:201], v[54:57]
	v_mfma_f32_16x16x32_bf16 v[50:53], v[222:225], v[198:201], v[50:53]
	v_mfma_f32_16x16x32_bf16 v[46:49], v[210:213], v[206:209], v[46:49]
	v_mfma_f32_16x16x32_bf16 v[42:45], v[214:217], v[206:209], v[42:45]
	v_mfma_f32_16x16x32_bf16 v[38:41], v[218:221], v[206:209], v[38:41]
	v_mfma_f32_16x16x32_bf16 v[34:37], v[222:225], v[206:209], v[34:37]
	s_barrier
	s_waitcnt vmcnt(7)
	ds_write_b128 v163, v[172:175]
	s_waitcnt vmcnt(6)
	ds_write_b128 v163, v[176:179] offset:8192
	s_waitcnt vmcnt(5)
	ds_write_b128 v163, v[180:183] offset:16384
	s_waitcnt vmcnt(4)
	ds_write_b128 v163, v[184:187] offset:24576
	v_add3_u32 v168, s20, v170, v188
	ds_read_b128 v[126:129], v168
	ds_read_b128 v[130:133], v168 offset:2048
	ds_read_b128 v[142:145], v168 offset:4096
	ds_read_b128 v[146:149], v168 offset:6144
	ds_read_b128 v[164:167], v168 offset:8192
	ds_read_b128 v[172:175], v168 offset:10240
	ds_read_b128 v[176:179], v168 offset:12288
	ds_read_b128 v[180:183], v168 offset:14336
	v_add3_u32 v168, s1, v170, v171
	ds_read_b128 v[184:187], v168
	ds_read_b128 v[190:193], v168 offset:2048
	ds_read_b128 v[198:201], v168 offset:4096
	ds_read_b128 v[206:209], v168 offset:6144
	s_waitcnt lgkmcnt(3)
	v_mfma_f32_16x16x32_bf16 v[158:161], v[184:187], v[126:129], v[158:161]
	s_waitcnt lgkmcnt(2)
	v_mfma_f32_16x16x32_bf16 v[154:157], v[190:193], v[126:129], v[154:157]
	s_waitcnt lgkmcnt(1)
	v_mfma_f32_16x16x32_bf16 v[150:153], v[198:201], v[126:129], v[150:153]
	s_waitcnt lgkmcnt(0)
	v_mfma_f32_16x16x32_bf16 v[18:21], v[206:209], v[126:129], v[18:21]
	v_mfma_f32_16x16x32_bf16 v[98:101], v[184:187], v[130:133], v[98:101]
	v_mfma_f32_16x16x32_bf16 v[126:129], v[190:193], v[130:133], v[138:141]
	v_mfma_f32_16x16x32_bf16 v[134:137], v[198:201], v[130:133], v[134:137]
	v_mfma_f32_16x16x32_bf16 v[130:133], v[206:209], v[130:133], v[22:25]
	v_mfma_f32_16x16x32_bf16 v[114:117], v[184:187], v[142:145], v[114:117]
	v_mfma_f32_16x16x32_bf16 v[122:125], v[190:193], v[142:145], v[122:125]
	v_mfma_f32_16x16x32_bf16 v[118:121], v[198:201], v[142:145], v[118:121]
	v_mfma_f32_16x16x32_bf16 v[26:29], v[206:209], v[142:145], v[26:29]
	v_mfma_f32_16x16x32_bf16 v[110:113], v[184:187], v[146:149], v[110:113]
	v_mfma_f32_16x16x32_bf16 v[106:109], v[190:193], v[146:149], v[106:109]
	v_mfma_f32_16x16x32_bf16 v[102:105], v[198:201], v[146:149], v[102:105]
	v_mfma_f32_16x16x32_bf16 v[138:141], v[206:209], v[146:149], v[30:33]
	v_mfma_f32_16x16x32_bf16 v[142:145], v[184:187], v[164:167], v[94:97]
	v_mfma_f32_16x16x32_bf16 v[90:93], v[190:193], v[164:167], v[90:93]
	v_mfma_f32_16x16x32_bf16 v[146:149], v[198:201], v[164:167], v[86:89]
	v_mfma_f32_16x16x32_bf16 v[82:85], v[206:209], v[164:167], v[82:85]
	v_mfma_f32_16x16x32_bf16 v[164:167], v[184:187], v[172:175], v[78:81]
	v_mfma_f32_16x16x32_bf16 v[74:77], v[190:193], v[172:175], v[74:77]
	v_mfma_f32_16x16x32_bf16 v[210:213], v[198:201], v[172:175], v[70:73]
	v_mfma_f32_16x16x32_bf16 v[66:69], v[206:209], v[172:175], v[66:69]
	v_mfma_f32_16x16x32_bf16 v[172:175], v[184:187], v[176:179], v[62:65]
	v_mfma_f32_16x16x32_bf16 v[58:61], v[190:193], v[176:179], v[58:61]
	v_mfma_f32_16x16x32_bf16 v[214:217], v[198:201], v[176:179], v[54:57]
	v_mfma_f32_16x16x32_bf16 v[50:53], v[206:209], v[176:179], v[50:53]
	v_mfma_f32_16x16x32_bf16 v[176:179], v[184:187], v[180:183], v[46:49]
	v_mfma_f32_16x16x32_bf16 v[184:187], v[190:193], v[180:183], v[42:45]
	v_mfma_f32_16x16x32_bf16 v[190:193], v[198:201], v[180:183], v[38:41]
	v_mfma_f32_16x16x32_bf16 v[180:183], v[206:209], v[180:183], v[34:37]
	s_waitcnt vmcnt(3)
	ds_write_b128 v163, v[2:5] offset:32768
	s_waitcnt vmcnt(2)
	ds_write_b128 v163, v[6:9] offset:40960
	s_waitcnt vmcnt(1)
; DI float bflo(unsigned u) { return __uint_as_float(u << 16); }
; DI float bfhi(unsigned u) { return __uint_as_float(u & 0xffff0000u); }
; DI float sigmoidf(float x) { return __builtin_amdgcn_rcpf(1.f + __expf(-x)); }
; DI float inv_sigmoidf(float x) { return 1.f + __expf(-x); }
; DI void gemm8_accum(f32x4 (&acc)[8][4], const bf16_t* a, size_t lda, const bf16_t* b, size_t ldb, int nkb, bf16_t* L,
;                     const bool pre, const bf16_t* an, size_t ldan, const bf16_t* bn, size_t ldbn) {
;     ...
;   g8_compute<0, 1>(acc, L + 32768, wm, wn, lane);
;   __builtin_amdgcn_sched_barrier(0);
;   g8_store1(L + 16384, rb, lrow, lch);
;   __builtin_amdgcn_sched_barrier(0);
;   g8_compute<1, 2>(acc, L + 32768, wm, wn, lane);
;   __syncthreads();
; __global__ void __launch_bounds__(512, 2) mega(Params p) {
;     ...
;       gemm8_epi(acc8, m0, n0, [&](int m, int n, f32x4& a) {
;         uint2 ua = *(const uint2*)(z + (size_t)m * ZS + C_MA + n);
;         uint2 ub = *(const uint2*)(z + (size_t)m * ZS + C_MB + n);
;         a[0] *= sigmoidf(bflo(ua.x)) * inv_sigmoidf(bflo(ub.x));
;         a[1] *= sigmoidf(bfhi(ua.x)) * inv_sigmoidf(bfhi(ub.x));
;         a[2] *= sigmoidf(bflo(ua.y)) * inv_sigmoidf(bflo(ub.y));
;         a[3] *= sigmoidf(bfhi(ua.y)) * inv_sigmoidf(bfhi(ub.y));
;       });
	ds_write_b128 v163, v[10:13] offset:49152
	s_waitcnt vmcnt(0)
	ds_write_b128 v163, v[14:17] offset:57344
	v_add3_u32 v6, s20, v0, v188
	ds_read_b128 v[2:5], v6
	ds_read_b128 v[34:37], v6 offset:2048
	ds_read_b128 v[42:45], v6 offset:4096
	ds_read_b128 v[198:201], v6 offset:6144
	ds_read_b128 v[206:209], v6 offset:8192
	ds_read_b128 v[218:221], v6 offset:10240
	ds_read_b128 v[222:225], v6 offset:12288
	ds_read_b128 v[226:229], v6 offset:14336
	v_add3_u32 v0, s1, v0, v171
	ds_read_b128 v[168:171], v0
	ds_read_b128 v[230:233], v0 offset:2048
	ds_read_b128 v[234:237], v0 offset:4096
	ds_read_b128 v[238:241], v0 offset:6144
	s_waitcnt lgkmcnt(3)
	v_mfma_f32_16x16x32_bf16 v[158:161], v[168:171], v[2:5], v[158:161]
	s_waitcnt lgkmcnt(2)
	v_mfma_f32_16x16x32_bf16 v[6:9], v[230:233], v[2:5], v[154:157]
	s_waitcnt lgkmcnt(1)
	v_mfma_f32_16x16x32_bf16 v[10:13], v[234:237], v[2:5], v[150:153]
	s_waitcnt lgkmcnt(0)
	v_mfma_f32_16x16x32_bf16 v[14:17], v[238:241], v[2:5], v[18:21]
	v_mfma_f32_16x16x32_bf16 v[22:25], v[168:171], v[34:37], v[98:101]
	v_mfma_f32_16x16x32_bf16 v[30:33], v[230:233], v[34:37], v[126:129]
	v_mfma_f32_16x16x32_bf16 v[38:41], v[234:237], v[34:37], v[134:137]
	v_mfma_f32_16x16x32_bf16 v[46:49], v[238:241], v[34:37], v[130:133]
	v_mfma_f32_16x16x32_bf16 v[54:57], v[168:171], v[42:45], v[114:117]
	v_mfma_f32_16x16x32_bf16 v[62:65], v[230:233], v[42:45], v[122:125]
	v_mfma_f32_16x16x32_bf16 v[70:73], v[234:237], v[42:45], v[118:121]
	v_mfma_f32_16x16x32_bf16 v[78:81], v[238:241], v[42:45], v[26:29]
	v_mfma_f32_16x16x32_bf16 v[86:89], v[168:171], v[198:201], v[110:113]
	v_mfma_f32_16x16x32_bf16 v[94:97], v[230:233], v[198:201], v[106:109]
	v_mfma_f32_16x16x32_bf16 v[102:105], v[234:237], v[198:201], v[102:105]
	v_mfma_f32_16x16x32_bf16 v[110:113], v[238:241], v[198:201], v[138:141]
	v_mfma_f32_16x16x32_bf16 v[118:121], v[168:171], v[206:209], v[142:145]
	v_mfma_f32_16x16x32_bf16 v[126:129], v[230:233], v[206:209], v[90:93]
	v_mfma_f32_16x16x32_bf16 v[122:125], v[234:237], v[206:209], v[146:149]
	v_mfma_f32_16x16x32_bf16 v[114:117], v[238:241], v[206:209], v[82:85]
	v_mfma_f32_16x16x32_bf16 v[106:109], v[168:171], v[218:221], v[164:167]
	v_mfma_f32_16x16x32_bf16 v[98:101], v[230:233], v[218:221], v[74:77]
	v_mfma_f32_16x16x32_bf16 v[90:93], v[234:237], v[218:221], v[210:213]
	v_mfma_f32_16x16x32_bf16 v[82:85], v[238:241], v[218:221], v[66:69]
	v_mfma_f32_16x16x32_bf16 v[74:77], v[168:171], v[222:225], v[172:175]
	v_mfma_f32_16x16x32_bf16 v[66:69], v[230:233], v[222:225], v[58:61]
	v_mfma_f32_16x16x32_bf16 v[58:61], v[234:237], v[222:225], v[214:217]
	v_mfma_f32_16x16x32_bf16 v[50:53], v[238:241], v[222:225], v[50:53]
	v_mfma_f32_16x16x32_bf16 v[42:45], v[168:171], v[226:229], v[176:179]
	v_mfma_f32_16x16x32_bf16 v[34:37], v[230:233], v[226:229], v[184:187]
	v_mfma_f32_16x16x32_bf16 v[26:29], v[234:237], v[226:229], v[190:193]
	v_mfma_f32_16x16x32_bf16 v[18:21], v[238:241], v[226:229], v[180:183]
	v_mov_b32_e32 v0, v196
	s_barrier
	v_mov_b64_e32 v[136:137], s[16:17]
	v_ashrrev_i32_e32 v3, 1, v0
	v_and_b32_e32 v2, 0xc0, v0
	v_and_b32_e32 v3, 0xffffff80, v3
	v_and_or_b32 v4, v0, 15, s13
	v_lshrrev_b32_e32 v0, 2, v0
	v_add_u32_e32 v142, v4, v3
	v_and_b32_e32 v0, 12, v0
	v_or3_b32 v0, v2, v0, s12
	v_mad_i64_i32 v[2:3], s[26:27], v142, s35, v[136:137]
	s_mov_b64 s[30:31], 0x1a30
	s_mov_b64 s[42:43], 0x2230
	v_lshl_add_u64 v[138:139], v[2:3], 0, s[30:31]
	v_lshlrev_b32_e32 v0, 1, v0
	v_lshl_add_u64 v[140:141], v[2:3], 0, s[42:43]
	v_lshl_add_u64 v[4:5], v[138:139], 0, v[0:1]
	v_lshl_add_u64 v[2:3], v[140:141], 0, v[0:1]
	global_load_dwordx2 v[4:5], v[4:5], off
	v_or_b32_e32 v134, 32, v0
	global_load_dwordx2 v[2:3], v[2:3], off
	v_mov_b32_e32 v135, v1
	v_mov_b32_e32 v172, v196
	s_movk_i32 s1, 0x3c0
	s_movk_i32 s96, 0x1518
	s_waitcnt vmcnt(1)
	v_lshlrev_b32_e32 v130, 16, v4
	v_and_b32_e32 v4, 0xffff0000, v4
	s_waitcnt vmcnt(0)
	v_lshlrev_b32_e32 v131, 16, v2
	v_and_b32_e32 v2, 0xffff0000, v2
	v_mul_f32_e32 v2, 0xbfb8aa3b, v2
	v_exp_f32_e32 v133, v2
	v_lshlrev_b32_e32 v2, 16, v5
	v_mul_f32_e32 v4, 0xbfb8aa3b, v4
	v_mul_f32_e32 v2, 0xbfb8aa3b, v2
	v_exp_f32_e32 v4, v4
	v_exp_f32_e32 v2, v2
	v_and_b32_e32 v5, 0xffff0000, v5
	v_mul_f32_e32 v130, 0xbfb8aa3b, v130
	v_mul_f32_e32 v5, 0xbfb8aa3b, v5
	v_exp_f32_e32 v130, v130
	v_exp_f32_e32 v5, v5
	v_mul_f32_e32 v131, 0xbfb8aa3b, v131
	v_add_f32_e32 v4, 1.0, v4
	v_add_f32_e32 v2, 1.0, v2
	v_exp_f32_e32 v132, v131
	v_rcp_f32_e32 v131, v4
	v_rcp_f32_e32 v4, v2
	v_lshlrev_b32_e32 v2, 16, v3
	v_and_b32_e32 v3, 0xffff0000, v3
	v_mul_f32_e32 v2, 0xbfb8aa3b, v2
	v_mul_f32_e32 v3, 0xbfb8aa3b, v3
	v_add_f32_e32 v130, 1.0, v130
	v_exp_f32_e32 v2, v2
	v_add_f32_e32 v5, 1.0, v5
	v_exp_f32_e32 v3, v3
	v_rcp_f32_e32 v130, v130
	v_rcp_f32_e32 v5, v5
	v_pk_add_f32 v[132:133], v[132:133], 1.0 op_sel_hi:[1,0]
	v_pk_add_f32 v[2:3], v[2:3], 1.0 op_sel_hi:[1,0]
	v_pk_mul_f32 v[130:131], v[130:131], v[132:133]
	v_pk_mul_f32 v[2:3], v[4:5], v[2:3]
	v_lshl_add_u64 v[132:133], v[140:141], 0, v[134:135]
	v_pk_mul_f32 v[4:5], v[160:161], v[2:3]
	v_pk_mul_f32 v[2:3], v[158:159], v[130:131]
	v_lshl_add_u64 v[130:131], v[138:139], 0, v[134:135]
	global_load_dwordx2 v[130:131], v[130:131], off
	s_nop 0
	global_load_dwordx2 v[132:133], v[132:133], off
	s_waitcnt vmcnt(1)
	v_lshlrev_b32_e32 v143, 16, v130
	v_and_b32_e32 v130, 0xffff0000, v130
	v_mul_f32_e32 v130, 0xbfb8aa3b, v130
	v_exp_f32_e32 v130, v130
	v_mul_f32_e32 v143, 0xbfb8aa3b, v143
	v_exp_f32_e32 v143, v143
	v_add_f32_e32 v130, 1.0, v130
	v_rcp_f32_e32 v145, v130
	s_waitcnt vmcnt(0)
; DI float bflo(unsigned u) { return __uint_as_float(u << 16); }
; DI float bfhi(unsigned u) { return __uint_as_float(u & 0xffff0000u); }
; DI float sigmoidf(float x) { return __builtin_amdgcn_rcpf(1.f + __expf(-x)); }
; DI float inv_sigmoidf(float x) { return 1.f + __expf(-x); }
; __global__ void __launch_bounds__(512, 2) mega(Params p) {
;     ...
;       gemm8_epi(acc8, m0, n0, [&](int m, int n, f32x4& a) {
;         uint2 ua = *(const uint2*)(z + (size_t)m * ZS + C_MA + n);
;         uint2 ub = *(const uint2*)(z + (size_t)m * ZS + C_MB + n);
;         a[0] *= sigmoidf(bflo(ua.x)) * inv_sigmoidf(bflo(ub.x));
;         a[1] *= sigmoidf(bfhi(ua.x)) * inv_sigmoidf(bfhi(ub.x));
;         a[2] *= sigmoidf(bflo(ua.y)) * inv_sigmoidf(bflo(ub.y));
;         a[3] *= sigmoidf(bfhi(ua.y)) * inv_sigmoidf(bfhi(ub.y));
;       });
	v_and_b32_e32 v130, 0xffff0000, v132
	v_mul_f32_e32 v130, 0xbfb8aa3b, v130
	v_exp_f32_e32 v147, v130
	v_lshlrev_b32_e32 v130, 16, v131
	v_and_b32_e32 v131, 0xffff0000, v131
	v_mul_f32_e32 v130, 0xbfb8aa3b, v130
	v_mul_f32_e32 v131, 0xbfb8aa3b, v131
	v_exp_f32_e32 v130, v130
	v_exp_f32_e32 v131, v131
	v_add_f32_e32 v143, 1.0, v143
	v_rcp_f32_e32 v144, v143
	v_lshlrev_b32_e32 v143, 16, v132
	v_lshlrev_b32_e32 v132, 16, v133
	v_and_b32_e32 v133, 0xffff0000, v133
	v_mul_f32_e32 v132, 0xbfb8aa3b, v132
	v_mul_f32_e32 v133, 0xbfb8aa3b, v133
	v_add_f32_e32 v130, 1.0, v130
	v_exp_f32_e32 v132, v132
	v_add_f32_e32 v131, 1.0, v131
	v_exp_f32_e32 v133, v133
	v_rcp_f32_e32 v130, v130
	v_rcp_f32_e32 v131, v131
	v_mul_f32_e32 v143, 0xbfb8aa3b, v143
	v_pk_add_f32 v[132:133], v[132:133], 1.0 op_sel_hi:[1,0]
	v_exp_f32_e32 v146, v143
	v_pk_mul_f32 v[130:131], v[130:131], v[132:133]
	v_or_b32_e32 v132, 64, v0
	v_mov_b32_e32 v133, v1
	v_pk_mul_f32 v[8:9], v[8:9], v[130:131]
	v_lshl_add_u64 v[130:131], v[138:139], 0, v[132:133]
	global_load_dwordx2 v[130:131], v[130:131], off
	v_pk_add_f32 v[146:147], v[146:147], 1.0 op_sel_hi:[1,0]
	s_nop 0
	v_pk_mul_f32 v[144:145], v[144:145], v[146:147]
	s_nop 0
	v_pk_mul_f32 v[6:7], v[6:7], v[144:145]
	v_lshl_add_u64 v[144:145], v[140:141], 0, v[132:133]
	global_load_dwordx2 v[144:145], v[144:145], off
	s_waitcnt vmcnt(1)
	v_lshlrev_b32_e32 v143, 16, v130
	v_and_b32_e32 v130, 0xffff0000, v130
	v_mul_f32_e32 v130, 0xbfb8aa3b, v130
	v_exp_f32_e32 v130, v130
	v_mul_f32_e32 v143, 0xbfb8aa3b, v143
	v_exp_f32_e32 v143, v143
	v_add_f32_e32 v130, 1.0, v130
	v_rcp_f32_e32 v147, v130
	s_waitcnt vmcnt(0)
	v_and_b32_e32 v130, 0xffff0000, v144
	v_add_f32_e32 v143, 1.0, v143
	v_mul_f32_e32 v130, 0xbfb8aa3b, v130
	v_rcp_f32_e32 v146, v143
	v_lshlrev_b32_e32 v143, 16, v144
	v_exp_f32_e32 v149, v130
	v_lshlrev_b32_e32 v130, 16, v131
	v_and_b32_e32 v131, 0xffff0000, v131
	v_mul_f32_e32 v143, 0xbfb8aa3b, v143
	v_mul_f32_e32 v130, 0xbfb8aa3b, v130
	v_mul_f32_e32 v131, 0xbfb8aa3b, v131
	v_exp_f32_e32 v148, v143
	v_exp_f32_e32 v130, v130
	v_lshlrev_b32_e32 v143, 16, v145
	v_exp_f32_e32 v131, v131
	v_mul_f32_e32 v143, 0xbfb8aa3b, v143
	v_exp_f32_e32 v144, v143
	v_and_b32_e32 v143, 0xffff0000, v145
	v_mul_f32_e32 v143, 0xbfb8aa3b, v143
	v_add_f32_e32 v130, 1.0, v130
	v_add_f32_e32 v131, 1.0, v131
	v_exp_f32_e32 v145, v143
	v_rcp_f32_e32 v130, v130
	v_rcp_f32_e32 v131, v131
	v_pk_add_f32 v[148:149], v[148:149], 1.0 op_sel_hi:[1,0]
	v_pk_add_f32 v[144:145], v[144:145], 1.0 op_sel_hi:[1,0]
	v_pk_mul_f32 v[146:147], v[146:147], v[148:149]
	v_pk_mul_f32 v[130:131], v[130:131], v[144:145]
	v_pk_mul_f32 v[10:11], v[10:11], v[146:147]
	v_pk_mul_f32 v[12:13], v[12:13], v[130:131]
	v_or_b32_e32 v130, 0x60, v0
	v_mov_b32_e32 v131, v1
	v_lshl_add_u64 v[138:139], v[138:139], 0, v[130:131]
	global_load_dwordx2 v[138:139], v[138:139], off
	v_lshl_add_u64 v[140:141], v[140:141], 0, v[130:131]
	global_load_dwordx2 v[140:141], v[140:141], off
	s_waitcnt vmcnt(1)
	v_lshlrev_b32_e32 v143, 16, v138
	v_and_b32_e32 v138, 0xffff0000, v138
	v_mul_f32_e32 v138, 0xbfb8aa3b, v138
	v_exp_f32_e32 v138, v138
	v_mul_f32_e32 v143, 0xbfb8aa3b, v143
	v_exp_f32_e32 v143, v143
	v_add_f32_e32 v138, 1.0, v138
	v_rcp_f32_e32 v145, v138
	s_waitcnt vmcnt(0)
	v_and_b32_e32 v138, 0xffff0000, v140
	v_mul_f32_e32 v138, 0xbfb8aa3b, v138
	v_exp_f32_e32 v147, v138
	v_lshlrev_b32_e32 v138, 16, v139
	v_and_b32_e32 v139, 0xffff0000, v139
	v_mul_f32_e32 v138, 0xbfb8aa3b, v138
	v_mul_f32_e32 v139, 0xbfb8aa3b, v139
	v_exp_f32_e32 v138, v138
	v_exp_f32_e32 v139, v139
	v_add_f32_e32 v143, 1.0, v143
	v_rcp_f32_e32 v144, v143
	v_lshlrev_b32_e32 v143, 16, v140
	v_lshlrev_b32_e32 v140, 16, v141
	v_and_b32_e32 v141, 0xffff0000, v141
	v_mul_f32_e32 v140, 0xbfb8aa3b, v140
	v_mul_f32_e32 v141, 0xbfb8aa3b, v141
	v_add_f32_e32 v138, 1.0, v138
	v_exp_f32_e32 v140, v140
	v_add_f32_e32 v139, 1.0, v139
	v_exp_f32_e32 v141, v141
	v_rcp_f32_e32 v138, v138
	v_rcp_f32_e32 v139, v139
	v_mul_f32_e32 v143, 0xbfb8aa3b, v143
	v_exp_f32_e32 v146, v143
	v_pk_add_f32 v[140:141], v[140:141], 1.0 op_sel_hi:[1,0]
	v_pk_add_f32 v[146:147], v[146:147], 1.0 op_sel_hi:[1,0]
	v_pk_mul_f32 v[138:139], v[138:139], v[140:141]
	v_pk_mul_f32 v[144:145], v[144:145], v[146:147]
	v_pk_mul_f32 v[16:17], v[16:17], v[138:139]
	v_or_b32_e32 v138, 16, v142
	v_mad_i64_i32 v[140:141], s[26:27], v138, s35, v[136:137]
	v_lshl_add_u64 v[138:139], v[140:141], 0, s[30:31]
	v_pk_mul_f32 v[14:15], v[14:15], v[144:145]
	v_lshl_add_u64 v[144:145], v[138:139], 0, v[0:1]
	global_load_dwordx2 v[144:145], v[144:145], off
	v_lshl_add_u64 v[140:141], v[140:141], 0, s[42:43]
	v_lshl_add_u64 v[146:147], v[140:141], 0, v[0:1]
	global_load_dwordx2 v[146:147], v[146:147], off
	s_waitcnt vmcnt(1)
	v_lshlrev_b32_e32 v143, 16, v144
	v_mul_f32_e32 v143, 0xbfb8aa3b, v143
	v_exp_f32_e32 v143, v143
	s_nop 0
	v_add_f32_e32 v143, 1.0, v143
	v_rcp_f32_e32 v148, v143
	s_waitcnt vmcnt(0)
; DI float bflo(unsigned u) { return __uint_as_float(u << 16); }
; DI float bfhi(unsigned u) { return __uint_as_float(u & 0xffff0000u); }
; DI float sigmoidf(float x) { return __builtin_amdgcn_rcpf(1.f + __expf(-x)); }
; DI float inv_sigmoidf(float x) { return 1.f + __expf(-x); }
; __global__ void __launch_bounds__(512, 2) mega(Params p) {
;     ...
;       gemm8_epi(acc8, m0, n0, [&](int m, int n, f32x4& a) {
;         uint2 ua = *(const uint2*)(z + (size_t)m * ZS + C_MA + n);
;         uint2 ub = *(const uint2*)(z + (size_t)m * ZS + C_MB + n);
;         a[0] *= sigmoidf(bflo(ua.x)) * inv_sigmoidf(bflo(ub.x));
;         a[1] *= sigmoidf(bfhi(ua.x)) * inv_sigmoidf(bfhi(ub.x));
;         a[2] *= sigmoidf(bflo(ua.y)) * inv_sigmoidf(bflo(ub.y));
;         a[3] *= sigmoidf(bfhi(ua.y)) * inv_sigmoidf(bfhi(ub.y));
;       });
	v_lshlrev_b32_e32 v143, 16, v146
	v_mul_f32_e32 v143, 0xbfb8aa3b, v143
	v_exp_f32_e32 v150, v143
	v_and_b32_e32 v143, 0xffff0000, v144
	v_mul_f32_e32 v143, 0xbfb8aa3b, v143
	v_exp_f32_e32 v143, v143
	s_nop 0
	v_add_f32_e32 v143, 1.0, v143
	v_rcp_f32_e32 v149, v143
	v_and_b32_e32 v143, 0xffff0000, v146
	v_mul_f32_e32 v143, 0xbfb8aa3b, v143
	v_exp_f32_e32 v151, v143
	v_lshlrev_b32_e32 v143, 16, v145
	v_mul_f32_e32 v143, 0xbfb8aa3b, v143
	v_exp_f32_e32 v143, v143
	v_pk_add_f32 v[150:151], v[150:151], 1.0 op_sel_hi:[1,0]
	v_add_f32_e32 v143, 1.0, v143
	v_rcp_f32_e32 v144, v143
	v_lshlrev_b32_e32 v143, 16, v147
	v_mul_f32_e32 v143, 0xbfb8aa3b, v143
	v_exp_f32_e32 v146, v143
	v_and_b32_e32 v143, 0xffff0000, v145
	v_mul_f32_e32 v143, 0xbfb8aa3b, v143
	v_exp_f32_e32 v143, v143
	v_pk_mul_f32 v[148:149], v[148:149], v[150:151]
	v_add_f32_e32 v143, 1.0, v143
	v_rcp_f32_e32 v145, v143
	v_and_b32_e32 v143, 0xffff0000, v147
	v_mul_f32_e32 v143, 0xbfb8aa3b, v143
	v_exp_f32_e32 v147, v143
	v_pk_mul_f32 v[22:23], v[22:23], v[148:149]
	v_pk_add_f32 v[146:147], v[146:147], 1.0 op_sel_hi:[1,0]
	s_nop 0
	v_pk_mul_f32 v[144:145], v[144:145], v[146:147]
	v_lshl_add_u64 v[146:147], v[140:141], 0, v[134:135]
	v_pk_mul_f32 v[24:25], v[24:25], v[144:145]
	v_lshl_add_u64 v[144:145], v[138:139], 0, v[134:135]
	global_load_dwordx2 v[144:145], v[144:145], off
	s_nop 0
	global_load_dwordx2 v[146:147], v[146:147], off
	s_waitcnt vmcnt(1)
	v_lshlrev_b32_e32 v143, 16, v144
	v_mul_f32_e32 v143, 0xbfb8aa3b, v143
	v_exp_f32_e32 v143, v143
	s_nop 0
	v_add_f32_e32 v143, 1.0, v143
	v_rcp_f32_e32 v148, v143
	s_waitcnt vmcnt(0)
	v_lshlrev_b32_e32 v143, 16, v146
	v_mul_f32_e32 v143, 0xbfb8aa3b, v143
	v_exp_f32_e32 v150, v143
	v_and_b32_e32 v143, 0xffff0000, v144
	v_mul_f32_e32 v143, 0xbfb8aa3b, v143
	v_exp_f32_e32 v143, v143
	s_nop 0
	v_add_f32_e32 v143, 1.0, v143
	v_rcp_f32_e32 v149, v143
	v_and_b32_e32 v143, 0xffff0000, v146
	v_mul_f32_e32 v143, 0xbfb8aa3b, v143
	v_exp_f32_e32 v151, v143
	v_lshlrev_b32_e32 v143, 16, v145
	v_mul_f32_e32 v143, 0xbfb8aa3b, v143
	v_exp_f32_e32 v143, v143
	v_pk_add_f32 v[150:151], v[150:151], 1.0 op_sel_hi:[1,0]
	v_add_f32_e32 v143, 1.0, v143
	v_rcp_f32_e32 v144, v143
	v_lshlrev_b32_e32 v143, 16, v147
	v_mul_f32_e32 v143, 0xbfb8aa3b, v143
	v_exp_f32_e32 v146, v143
	v_and_b32_e32 v143, 0xffff0000, v145
	v_mul_f32_e32 v143, 0xbfb8aa3b, v143
	v_exp_f32_e32 v143, v143
	v_pk_mul_f32 v[148:149], v[148:149], v[150:151]
	v_add_f32_e32 v143, 1.0, v143
	v_rcp_f32_e32 v145, v143
	v_and_b32_e32 v143, 0xffff0000, v147
	v_mul_f32_e32 v143, 0xbfb8aa3b, v143
	v_exp_f32_e32 v147, v143
	v_pk_mul_f32 v[30:31], v[30:31], v[148:149]
	v_pk_add_f32 v[146:147], v[146:147], 1.0 op_sel_hi:[1,0]
	s_nop 0
	v_pk_mul_f32 v[144:145], v[144:145], v[146:147]
	v_lshl_add_u64 v[146:147], v[140:141], 0, v[132:133]
	v_pk_mul_f32 v[32:33], v[32:33], v[144:145]
	v_lshl_add_u64 v[144:145], v[138:139], 0, v[132:133]
	global_load_dwordx2 v[144:145], v[144:145], off
	v_lshl_add_u64 v[138:139], v[138:139], 0, v[130:131]
	global_load_dwordx2 v[146:147], v[146:147], off
	v_lshl_add_u64 v[140:141], v[140:141], 0, v[130:131]
	global_load_dwordx2 v[138:139], v[138:139], off
	s_nop 0
	global_load_dwordx2 v[140:141], v[140:141], off
	s_waitcnt vmcnt(3)
	v_lshlrev_b32_e32 v143, 16, v144
	v_mul_f32_e32 v143, 0xbfb8aa3b, v143
	v_exp_f32_e32 v143, v143
	s_nop 0
	v_add_f32_e32 v143, 1.0, v143
	v_rcp_f32_e32 v148, v143
	s_waitcnt vmcnt(2)
	v_lshlrev_b32_e32 v143, 16, v146
	v_mul_f32_e32 v143, 0xbfb8aa3b, v143
	v_exp_f32_e32 v150, v143
	v_and_b32_e32 v143, 0xffff0000, v144
	v_mul_f32_e32 v143, 0xbfb8aa3b, v143
	v_exp_f32_e32 v143, v143
	s_nop 0
	v_add_f32_e32 v143, 1.0, v143
	v_rcp_f32_e32 v149, v143
	v_and_b32_e32 v143, 0xffff0000, v146
	v_mul_f32_e32 v143, 0xbfb8aa3b, v143
	v_exp_f32_e32 v151, v143
	v_lshlrev_b32_e32 v143, 16, v145
	v_mul_f32_e32 v143, 0xbfb8aa3b, v143
	v_exp_f32_e32 v143, v143
	v_pk_add_f32 v[150:151], v[150:151], 1.0 op_sel_hi:[1,0]
	v_add_f32_e32 v143, 1.0, v143
	v_rcp_f32_e32 v144, v143
	v_lshlrev_b32_e32 v143, 16, v147
	v_mul_f32_e32 v143, 0xbfb8aa3b, v143
	v_exp_f32_e32 v146, v143
	v_and_b32_e32 v143, 0xffff0000, v145
	v_mul_f32_e32 v143, 0xbfb8aa3b, v143
	v_exp_f32_e32 v143, v143
	v_pk_mul_f32 v[148:149], v[148:149], v[150:151]
	v_add_f32_e32 v143, 1.0, v143
	v_rcp_f32_e32 v145, v143
	v_and_b32_e32 v143, 0xffff0000, v147
	v_mul_f32_e32 v143, 0xbfb8aa3b, v143
	v_exp_f32_e32 v147, v143
	s_waitcnt vmcnt(1)
	v_lshlrev_b32_e32 v143, 16, v138
	v_and_b32_e32 v138, 0xffff0000, v138
	v_mul_f32_e32 v138, 0xbfb8aa3b, v138
	v_exp_f32_e32 v138, v138
	v_pk_add_f32 v[146:147], v[146:147], 1.0 op_sel_hi:[1,0]
	v_mul_f32_e32 v143, 0xbfb8aa3b, v143
	v_pk_mul_f32 v[144:145], v[144:145], v[146:147]
	v_add_f32_e32 v138, 1.0, v138
	v_pk_mul_f32 v[40:41], v[40:41], v[144:145]
	v_rcp_f32_e32 v145, v138
	s_waitcnt vmcnt(0)
	v_and_b32_e32 v138, 0xffff0000, v140
	v_exp_f32_e32 v143, v143
	v_mul_f32_e32 v138, 0xbfb8aa3b, v138
	v_exp_f32_e32 v147, v138
	v_lshlrev_b32_e32 v138, 16, v139
	v_and_b32_e32 v139, 0xffff0000, v139
	v_mul_f32_e32 v138, 0xbfb8aa3b, v138
	v_mul_f32_e32 v139, 0xbfb8aa3b, v139
	v_exp_f32_e32 v138, v138
	v_exp_f32_e32 v139, v139
	v_add_f32_e32 v143, 1.0, v143
	v_rcp_f32_e32 v144, v143
	v_lshlrev_b32_e32 v143, 16, v140
	v_lshlrev_b32_e32 v140, 16, v141
	v_and_b32_e32 v141, 0xffff0000, v141
	v_mul_f32_e32 v140, 0xbfb8aa3b, v140
	v_mul_f32_e32 v141, 0xbfb8aa3b, v141
	v_add_f32_e32 v138, 1.0, v138
	v_exp_f32_e32 v140, v140
	v_add_f32_e32 v139, 1.0, v139
	v_exp_f32_e32 v141, v141
	v_rcp_f32_e32 v138, v138
	v_rcp_f32_e32 v139, v139
	v_mul_f32_e32 v143, 0xbfb8aa3b, v143
	v_exp_f32_e32 v146, v143
	v_pk_add_f32 v[140:141], v[140:141], 1.0 op_sel_hi:[1,0]
	v_pk_mul_f32 v[38:39], v[38:39], v[148:149]
	v_pk_mul_f32 v[138:139], v[138:139], v[140:141]
	v_pk_add_f32 v[146:147], v[146:147], 1.0 op_sel_hi:[1,0]
	v_pk_mul_f32 v[48:49], v[48:49], v[138:139]
	v_or_b32_e32 v138, 32, v142
	v_mad_i64_i32 v[140:141], s[26:27], v138, s35, v[136:137]
	v_pk_mul_f32 v[144:145], v[144:145], v[146:147]
	v_lshl_add_u64 v[138:139], v[140:141], 0, s[30:31]
	v_pk_mul_f32 v[46:47], v[46:47], v[144:145]
	v_lshl_add_u64 v[144:145], v[138:139], 0, v[0:1]
	global_load_dwordx2 v[144:145], v[144:145], off
	v_lshl_add_u64 v[140:141], v[140:141], 0, s[42:43]
	v_lshl_add_u64 v[146:147], v[140:141], 0, v[0:1]
	global_load_dwordx2 v[146:147], v[146:147], off
	s_waitcnt vmcnt(1)
; DI float bflo(unsigned u) { return __uint_as_float(u << 16); }
; DI float bfhi(unsigned u) { return __uint_as_float(u & 0xffff0000u); }
; DI float sigmoidf(float x) { return __builtin_amdgcn_rcpf(1.f + __expf(-x)); }
; DI float inv_sigmoidf(float x) { return 1.f + __expf(-x); }
; __global__ void __launch_bounds__(512, 2) mega(Params p) {
;     ...
;       gemm8_epi(acc8, m0, n0, [&](int m, int n, f32x4& a) {
;         uint2 ua = *(const uint2*)(z + (size_t)m * ZS + C_MA + n);
;         uint2 ub = *(const uint2*)(z + (size_t)m * ZS + C_MB + n);
;         a[0] *= sigmoidf(bflo(ua.x)) * inv_sigmoidf(bflo(ub.x));
;         a[1] *= sigmoidf(bfhi(ua.x)) * inv_sigmoidf(bfhi(ub.x));
;         a[2] *= sigmoidf(bflo(ua.y)) * inv_sigmoidf(bflo(ub.y));
;         a[3] *= sigmoidf(bfhi(ua.y)) * inv_sigmoidf(bfhi(ub.y));
;       });
	v_lshlrev_b32_e32 v143, 16, v144
	v_mul_f32_e32 v143, 0xbfb8aa3b, v143
	v_exp_f32_e32 v143, v143
	s_nop 0
	v_add_f32_e32 v143, 1.0, v143
	v_rcp_f32_e32 v148, v143
	s_waitcnt vmcnt(0)
	v_lshlrev_b32_e32 v143, 16, v146
	v_mul_f32_e32 v143, 0xbfb8aa3b, v143
	v_exp_f32_e32 v150, v143
	v_and_b32_e32 v143, 0xffff0000, v144
	v_mul_f32_e32 v143, 0xbfb8aa3b, v143
	v_exp_f32_e32 v143, v143
	s_nop 0
	v_add_f32_e32 v143, 1.0, v143
	v_rcp_f32_e32 v149, v143
	v_and_b32_e32 v143, 0xffff0000, v146
	v_mul_f32_e32 v143, 0xbfb8aa3b, v143
	v_exp_f32_e32 v151, v143
	v_lshlrev_b32_e32 v143, 16, v145
	v_mul_f32_e32 v143, 0xbfb8aa3b, v143
	v_exp_f32_e32 v143, v143
	v_pk_add_f32 v[150:151], v[150:151], 1.0 op_sel_hi:[1,0]
	v_add_f32_e32 v143, 1.0, v143
	v_rcp_f32_e32 v144, v143
	v_lshlrev_b32_e32 v143, 16, v147
	v_mul_f32_e32 v143, 0xbfb8aa3b, v143
	v_exp_f32_e32 v146, v143
	v_and_b32_e32 v143, 0xffff0000, v145
	v_mul_f32_e32 v143, 0xbfb8aa3b, v143
	v_exp_f32_e32 v143, v143
	v_pk_mul_f32 v[148:149], v[148:149], v[150:151]
	v_add_f32_e32 v143, 1.0, v143
	v_rcp_f32_e32 v145, v143
	v_and_b32_e32 v143, 0xffff0000, v147
	v_mul_f32_e32 v143, 0xbfb8aa3b, v143
	v_exp_f32_e32 v147, v143
	v_pk_mul_f32 v[54:55], v[54:55], v[148:149]
	v_pk_add_f32 v[146:147], v[146:147], 1.0 op_sel_hi:[1,0]
	s_nop 0
	v_pk_mul_f32 v[144:145], v[144:145], v[146:147]
	v_lshl_add_u64 v[146:147], v[140:141], 0, v[134:135]
	v_pk_mul_f32 v[56:57], v[56:57], v[144:145]
	v_lshl_add_u64 v[144:145], v[138:139], 0, v[134:135]
	global_load_dwordx2 v[144:145], v[144:145], off
	s_nop 0
	global_load_dwordx2 v[146:147], v[146:147], off
	s_waitcnt vmcnt(1)
	v_lshlrev_b32_e32 v143, 16, v144
	v_mul_f32_e32 v143, 0xbfb8aa3b, v143
	v_exp_f32_e32 v143, v143
	s_nop 0
	v_add_f32_e32 v143, 1.0, v143
	v_rcp_f32_e32 v148, v143
	s_waitcnt vmcnt(0)
	v_lshlrev_b32_e32 v143, 16, v146
	v_mul_f32_e32 v143, 0xbfb8aa3b, v143
	v_exp_f32_e32 v150, v143
	v_and_b32_e32 v143, 0xffff0000, v144
	v_mul_f32_e32 v143, 0xbfb8aa3b, v143
	v_exp_f32_e32 v143, v143
	s_nop 0
	v_add_f32_e32 v143, 1.0, v143
	v_rcp_f32_e32 v149, v143
	v_and_b32_e32 v143, 0xffff0000, v146
	v_mul_f32_e32 v143, 0xbfb8aa3b, v143
	v_exp_f32_e32 v151, v143
	v_lshlrev_b32_e32 v143, 16, v145
	v_mul_f32_e32 v143, 0xbfb8aa3b, v143
	v_exp_f32_e32 v143, v143
	v_pk_add_f32 v[150:151], v[150:151], 1.0 op_sel_hi:[1,0]
	v_add_f32_e32 v143, 1.0, v143
	v_rcp_f32_e32 v144, v143
	v_lshlrev_b32_e32 v143, 16, v147
	v_mul_f32_e32 v143, 0xbfb8aa3b, v143
	v_exp_f32_e32 v146, v143
	v_and_b32_e32 v143, 0xffff0000, v145
	v_mul_f32_e32 v143, 0xbfb8aa3b, v143
	v_exp_f32_e32 v143, v143
	v_pk_mul_f32 v[148:149], v[148:149], v[150:151]
	v_add_f32_e32 v143, 1.0, v143
	v_rcp_f32_e32 v145, v143
	v_and_b32_e32 v143, 0xffff0000, v147
	v_mul_f32_e32 v143, 0xbfb8aa3b, v143
	v_exp_f32_e32 v147, v143
	v_pk_mul_f32 v[62:63], v[62:63], v[148:149]
	v_pk_add_f32 v[146:147], v[146:147], 1.0 op_sel_hi:[1,0]
	s_nop 0
	v_pk_mul_f32 v[144:145], v[144:145], v[146:147]
	v_lshl_add_u64 v[146:147], v[140:141], 0, v[132:133]
	v_pk_mul_f32 v[64:65], v[64:65], v[144:145]
	v_lshl_add_u64 v[144:145], v[138:139], 0, v[132:133]
	global_load_dwordx2 v[144:145], v[144:145], off
	v_lshl_add_u64 v[138:139], v[138:139], 0, v[130:131]
	global_load_dwordx2 v[146:147], v[146:147], off
	v_lshl_add_u64 v[140:141], v[140:141], 0, v[130:131]
	global_load_dwordx2 v[138:139], v[138:139], off
	s_nop 0
	global_load_dwordx2 v[140:141], v[140:141], off
	s_waitcnt vmcnt(3)
	v_lshlrev_b32_e32 v143, 16, v144
	v_mul_f32_e32 v143, 0xbfb8aa3b, v143
	v_exp_f32_e32 v143, v143
	s_nop 0
	v_add_f32_e32 v143, 1.0, v143
	v_rcp_f32_e32 v148, v143
	s_waitcnt vmcnt(2)
	v_lshlrev_b32_e32 v143, 16, v146
	v_mul_f32_e32 v143, 0xbfb8aa3b, v143
	v_exp_f32_e32 v150, v143
	v_and_b32_e32 v143, 0xffff0000, v144
	v_mul_f32_e32 v143, 0xbfb8aa3b, v143
	v_exp_f32_e32 v143, v143
	s_nop 0
	v_add_f32_e32 v143, 1.0, v143
	v_rcp_f32_e32 v149, v143
	v_and_b32_e32 v143, 0xffff0000, v146
	v_mul_f32_e32 v143, 0xbfb8aa3b, v143
	v_exp_f32_e32 v151, v143
	v_lshlrev_b32_e32 v143, 16, v145
	v_mul_f32_e32 v143, 0xbfb8aa3b, v143
	v_exp_f32_e32 v143, v143
	v_pk_add_f32 v[150:151], v[150:151], 1.0 op_sel_hi:[1,0]
	v_add_f32_e32 v143, 1.0, v143
	v_rcp_f32_e32 v144, v143
	v_lshlrev_b32_e32 v143, 16, v147
	v_mul_f32_e32 v143, 0xbfb8aa3b, v143
	v_exp_f32_e32 v146, v143
	v_and_b32_e32 v143, 0xffff0000, v145
	v_mul_f32_e32 v143, 0xbfb8aa3b, v143
	v_exp_f32_e32 v143, v143
	v_pk_mul_f32 v[148:149], v[148:149], v[150:151]
	v_add_f32_e32 v143, 1.0, v143
	v_rcp_f32_e32 v145, v143
	v_and_b32_e32 v143, 0xffff0000, v147
	v_mul_f32_e32 v143, 0xbfb8aa3b, v143
	v_exp_f32_e32 v147, v143
	s_waitcnt vmcnt(1)
	v_lshlrev_b32_e32 v143, 16, v138
	v_and_b32_e32 v138, 0xffff0000, v138
	v_mul_f32_e32 v138, 0xbfb8aa3b, v138
	v_exp_f32_e32 v138, v138
	v_pk_add_f32 v[146:147], v[146:147], 1.0 op_sel_hi:[1,0]
	v_mul_f32_e32 v143, 0xbfb8aa3b, v143
	v_pk_mul_f32 v[144:145], v[144:145], v[146:147]
	v_add_f32_e32 v138, 1.0, v138
	v_pk_mul_f32 v[72:73], v[72:73], v[144:145]
	v_rcp_f32_e32 v145, v138
	s_waitcnt vmcnt(0)
; DI float bflo(unsigned u) { return __uint_as_float(u << 16); }
; DI float bfhi(unsigned u) { return __uint_as_float(u & 0xffff0000u); }
; DI float sigmoidf(float x) { return __builtin_amdgcn_rcpf(1.f + __expf(-x)); }
; DI float inv_sigmoidf(float x) { return 1.f + __expf(-x); }
; __global__ void __launch_bounds__(512, 2) mega(Params p) {
;     ...
;       gemm8_epi(acc8, m0, n0, [&](int m, int n, f32x4& a) {
;         uint2 ua = *(const uint2*)(z + (size_t)m * ZS + C_MA + n);
;         uint2 ub = *(const uint2*)(z + (size_t)m * ZS + C_MB + n);
;         a[0] *= sigmoidf(bflo(ua.x)) * inv_sigmoidf(bflo(ub.x));
;         a[1] *= sigmoidf(bfhi(ua.x)) * inv_sigmoidf(bfhi(ub.x));
;         a[2] *= sigmoidf(bflo(ua.y)) * inv_sigmoidf(bflo(ub.y));
;         a[3] *= sigmoidf(bfhi(ua.y)) * inv_sigmoidf(bfhi(ub.y));
;       });
	v_and_b32_e32 v138, 0xffff0000, v140
	v_exp_f32_e32 v143, v143
	v_mul_f32_e32 v138, 0xbfb8aa3b, v138
	v_exp_f32_e32 v147, v138
	v_lshlrev_b32_e32 v138, 16, v139
	v_and_b32_e32 v139, 0xffff0000, v139
	v_mul_f32_e32 v138, 0xbfb8aa3b, v138
	v_mul_f32_e32 v139, 0xbfb8aa3b, v139
	v_exp_f32_e32 v138, v138
	v_exp_f32_e32 v139, v139
	v_add_f32_e32 v143, 1.0, v143
	v_rcp_f32_e32 v144, v143
	v_lshlrev_b32_e32 v143, 16, v140
	v_lshlrev_b32_e32 v140, 16, v141
	v_and_b32_e32 v141, 0xffff0000, v141
	v_mul_f32_e32 v140, 0xbfb8aa3b, v140
	v_mul_f32_e32 v141, 0xbfb8aa3b, v141
	v_add_f32_e32 v138, 1.0, v138
	v_exp_f32_e32 v140, v140
	v_add_f32_e32 v139, 1.0, v139
	v_exp_f32_e32 v141, v141
	v_rcp_f32_e32 v138, v138
	v_rcp_f32_e32 v139, v139
	v_mul_f32_e32 v143, 0xbfb8aa3b, v143
	v_exp_f32_e32 v146, v143
	v_pk_add_f32 v[140:141], v[140:141], 1.0 op_sel_hi:[1,0]
	v_pk_mul_f32 v[70:71], v[70:71], v[148:149]
	v_pk_mul_f32 v[138:139], v[138:139], v[140:141]
	v_pk_add_f32 v[146:147], v[146:147], 1.0 op_sel_hi:[1,0]
	v_pk_mul_f32 v[80:81], v[80:81], v[138:139]
	v_or_b32_e32 v138, 48, v142
	v_mad_i64_i32 v[140:141], s[26:27], v138, s35, v[136:137]
	v_pk_mul_f32 v[144:145], v[144:145], v[146:147]
	v_lshl_add_u64 v[138:139], v[140:141], 0, s[30:31]
	v_pk_mul_f32 v[78:79], v[78:79], v[144:145]
	v_lshl_add_u64 v[144:145], v[138:139], 0, v[0:1]
	global_load_dwordx2 v[144:145], v[144:145], off
	v_lshl_add_u64 v[140:141], v[140:141], 0, s[42:43]
	v_lshl_add_u64 v[146:147], v[140:141], 0, v[0:1]
	global_load_dwordx2 v[146:147], v[146:147], off
	s_waitcnt vmcnt(1)
	v_lshlrev_b32_e32 v143, 16, v144
	v_mul_f32_e32 v143, 0xbfb8aa3b, v143
	v_exp_f32_e32 v143, v143
	s_nop 0
	v_add_f32_e32 v143, 1.0, v143
	v_rcp_f32_e32 v148, v143
	s_waitcnt vmcnt(0)
	v_lshlrev_b32_e32 v143, 16, v146
	v_mul_f32_e32 v143, 0xbfb8aa3b, v143
	v_exp_f32_e32 v150, v143
	v_and_b32_e32 v143, 0xffff0000, v144
	v_mul_f32_e32 v143, 0xbfb8aa3b, v143
	v_exp_f32_e32 v143, v143
	s_nop 0
	v_add_f32_e32 v143, 1.0, v143
	v_rcp_f32_e32 v149, v143
	v_and_b32_e32 v143, 0xffff0000, v146
	v_mul_f32_e32 v143, 0xbfb8aa3b, v143
	v_exp_f32_e32 v151, v143
	v_lshlrev_b32_e32 v143, 16, v145
	v_mul_f32_e32 v143, 0xbfb8aa3b, v143
	v_exp_f32_e32 v143, v143
	v_pk_add_f32 v[150:151], v[150:151], 1.0 op_sel_hi:[1,0]
	v_add_f32_e32 v143, 1.0, v143
	v_rcp_f32_e32 v144, v143
	v_lshlrev_b32_e32 v143, 16, v147
	v_mul_f32_e32 v143, 0xbfb8aa3b, v143
	v_exp_f32_e32 v146, v143
	v_and_b32_e32 v143, 0xffff0000, v145
	v_mul_f32_e32 v143, 0xbfb8aa3b, v143
	v_exp_f32_e32 v143, v143
	v_pk_mul_f32 v[148:149], v[148:149], v[150:151]
	v_add_f32_e32 v143, 1.0, v143
	v_rcp_f32_e32 v145, v143
	v_and_b32_e32 v143, 0xffff0000, v147
	v_mul_f32_e32 v143, 0xbfb8aa3b, v143
	v_exp_f32_e32 v147, v143
	v_pk_mul_f32 v[86:87], v[86:87], v[148:149]
	v_pk_add_f32 v[146:147], v[146:147], 1.0 op_sel_hi:[1,0]
	s_nop 0
	v_pk_mul_f32 v[144:145], v[144:145], v[146:147]
	v_lshl_add_u64 v[146:147], v[140:141], 0, v[134:135]
	v_pk_mul_f32 v[88:89], v[88:89], v[144:145]
	v_lshl_add_u64 v[144:145], v[138:139], 0, v[134:135]
	global_load_dwordx2 v[144:145], v[144:145], off
	s_nop 0
	global_load_dwordx2 v[146:147], v[146:147], off
	s_waitcnt vmcnt(1)
	v_lshlrev_b32_e32 v143, 16, v144
	v_mul_f32_e32 v143, 0xbfb8aa3b, v143
	v_exp_f32_e32 v143, v143
	s_nop 0
	v_add_f32_e32 v143, 1.0, v143
	v_rcp_f32_e32 v148, v143
	s_waitcnt vmcnt(0)
	v_lshlrev_b32_e32 v143, 16, v146
	v_mul_f32_e32 v143, 0xbfb8aa3b, v143
	v_exp_f32_e32 v150, v143
	v_and_b32_e32 v143, 0xffff0000, v144
	v_mul_f32_e32 v143, 0xbfb8aa3b, v143
	v_exp_f32_e32 v143, v143
	s_nop 0
	v_add_f32_e32 v143, 1.0, v143
	v_rcp_f32_e32 v149, v143
	v_and_b32_e32 v143, 0xffff0000, v146
	v_mul_f32_e32 v143, 0xbfb8aa3b, v143
	v_exp_f32_e32 v151, v143
	v_lshlrev_b32_e32 v143, 16, v145
	v_mul_f32_e32 v143, 0xbfb8aa3b, v143
	v_exp_f32_e32 v143, v143
	v_pk_add_f32 v[150:151], v[150:151], 1.0 op_sel_hi:[1,0]
	v_add_f32_e32 v143, 1.0, v143
	v_rcp_f32_e32 v144, v143
	v_lshlrev_b32_e32 v143, 16, v147
	v_mul_f32_e32 v143, 0xbfb8aa3b, v143
	v_exp_f32_e32 v146, v143
	v_and_b32_e32 v143, 0xffff0000, v145
	v_mul_f32_e32 v143, 0xbfb8aa3b, v143
	v_exp_f32_e32 v143, v143
	v_pk_mul_f32 v[148:149], v[148:149], v[150:151]
	v_add_f32_e32 v143, 1.0, v143
	v_rcp_f32_e32 v145, v143
	v_and_b32_e32 v143, 0xffff0000, v147
	v_mul_f32_e32 v143, 0xbfb8aa3b, v143
	v_exp_f32_e32 v147, v143
	v_pk_mul_f32 v[94:95], v[94:95], v[148:149]
	v_pk_add_f32 v[146:147], v[146:147], 1.0 op_sel_hi:[1,0]
	s_nop 0
	v_pk_mul_f32 v[144:145], v[144:145], v[146:147]
	v_lshl_add_u64 v[146:147], v[140:141], 0, v[132:133]
	v_pk_mul_f32 v[96:97], v[96:97], v[144:145]
	v_lshl_add_u64 v[144:145], v[138:139], 0, v[132:133]
	global_load_dwordx2 v[144:145], v[144:145], off
	v_lshl_add_u64 v[138:139], v[138:139], 0, v[130:131]
	global_load_dwordx2 v[146:147], v[146:147], off
	v_lshl_add_u64 v[140:141], v[140:141], 0, v[130:131]
	global_load_dwordx2 v[138:139], v[138:139], off
	s_nop 0
	global_load_dwordx2 v[140:141], v[140:141], off
	s_waitcnt vmcnt(3)
	v_lshlrev_b32_e32 v143, 16, v144
	v_mul_f32_e32 v143, 0xbfb8aa3b, v143
	v_exp_f32_e32 v143, v143
	s_nop 0
	v_add_f32_e32 v143, 1.0, v143
	v_rcp_f32_e32 v148, v143
	s_waitcnt vmcnt(2)
; DI float bflo(unsigned u) { return __uint_as_float(u << 16); }
; DI float bfhi(unsigned u) { return __uint_as_float(u & 0xffff0000u); }
; DI float sigmoidf(float x) { return __builtin_amdgcn_rcpf(1.f + __expf(-x)); }
; DI float inv_sigmoidf(float x) { return 1.f + __expf(-x); }
; __global__ void __launch_bounds__(512, 2) mega(Params p) {
;     ...
;       gemm8_epi(acc8, m0, n0, [&](int m, int n, f32x4& a) {
;         uint2 ua = *(const uint2*)(z + (size_t)m * ZS + C_MA + n);
;         uint2 ub = *(const uint2*)(z + (size_t)m * ZS + C_MB + n);
;         a[0] *= sigmoidf(bflo(ua.x)) * inv_sigmoidf(bflo(ub.x));
;         a[1] *= sigmoidf(bfhi(ua.x)) * inv_sigmoidf(bfhi(ub.x));
;         a[2] *= sigmoidf(bflo(ua.y)) * inv_sigmoidf(bflo(ub.y));
;         a[3] *= sigmoidf(bfhi(ua.y)) * inv_sigmoidf(bfhi(ub.y));
;       });
	v_lshlrev_b32_e32 v143, 16, v146
	v_mul_f32_e32 v143, 0xbfb8aa3b, v143
	v_exp_f32_e32 v150, v143
	v_and_b32_e32 v143, 0xffff0000, v144
	v_mul_f32_e32 v143, 0xbfb8aa3b, v143
	v_exp_f32_e32 v143, v143
	s_nop 0
	v_add_f32_e32 v143, 1.0, v143
	v_rcp_f32_e32 v149, v143
	v_and_b32_e32 v143, 0xffff0000, v146
	v_mul_f32_e32 v143, 0xbfb8aa3b, v143
	v_exp_f32_e32 v151, v143
	v_lshlrev_b32_e32 v143, 16, v145
	v_mul_f32_e32 v143, 0xbfb8aa3b, v143
	v_exp_f32_e32 v143, v143
	v_pk_add_f32 v[150:151], v[150:151], 1.0 op_sel_hi:[1,0]
	v_add_f32_e32 v143, 1.0, v143
	v_rcp_f32_e32 v144, v143
	v_lshlrev_b32_e32 v143, 16, v147
	v_mul_f32_e32 v143, 0xbfb8aa3b, v143
	v_exp_f32_e32 v146, v143
	v_and_b32_e32 v143, 0xffff0000, v145
	v_mul_f32_e32 v143, 0xbfb8aa3b, v143
	v_exp_f32_e32 v143, v143
	v_pk_mul_f32 v[148:149], v[148:149], v[150:151]
	v_add_f32_e32 v143, 1.0, v143
	v_rcp_f32_e32 v145, v143
	v_and_b32_e32 v143, 0xffff0000, v147
	v_mul_f32_e32 v143, 0xbfb8aa3b, v143
	v_exp_f32_e32 v147, v143
	s_waitcnt vmcnt(1)
	v_lshlrev_b32_e32 v143, 16, v138
	v_and_b32_e32 v138, 0xffff0000, v138
	v_mul_f32_e32 v138, 0xbfb8aa3b, v138
	v_exp_f32_e32 v138, v138
	v_pk_add_f32 v[146:147], v[146:147], 1.0 op_sel_hi:[1,0]
	v_mul_f32_e32 v143, 0xbfb8aa3b, v143
	v_pk_mul_f32 v[144:145], v[144:145], v[146:147]
	v_add_f32_e32 v138, 1.0, v138
	v_pk_mul_f32 v[104:105], v[104:105], v[144:145]
	v_rcp_f32_e32 v145, v138
	s_waitcnt vmcnt(0)
	v_and_b32_e32 v138, 0xffff0000, v140
	v_exp_f32_e32 v143, v143
	v_mul_f32_e32 v138, 0xbfb8aa3b, v138
	v_exp_f32_e32 v147, v138
	v_lshlrev_b32_e32 v138, 16, v139
	v_and_b32_e32 v139, 0xffff0000, v139
	v_mul_f32_e32 v138, 0xbfb8aa3b, v138
	v_mul_f32_e32 v139, 0xbfb8aa3b, v139
	v_exp_f32_e32 v138, v138
	v_exp_f32_e32 v139, v139
	v_add_f32_e32 v143, 1.0, v143
	v_rcp_f32_e32 v144, v143
	v_lshlrev_b32_e32 v143, 16, v140
	v_lshlrev_b32_e32 v140, 16, v141
	v_and_b32_e32 v141, 0xffff0000, v141
	v_mul_f32_e32 v140, 0xbfb8aa3b, v140
	v_mul_f32_e32 v141, 0xbfb8aa3b, v141
	v_add_f32_e32 v138, 1.0, v138
	v_exp_f32_e32 v140, v140
	v_add_f32_e32 v139, 1.0, v139
	v_exp_f32_e32 v141, v141
	v_rcp_f32_e32 v138, v138
	v_rcp_f32_e32 v139, v139
	v_mul_f32_e32 v143, 0xbfb8aa3b, v143
	v_exp_f32_e32 v146, v143
	v_pk_add_f32 v[140:141], v[140:141], 1.0 op_sel_hi:[1,0]
	v_pk_mul_f32 v[102:103], v[102:103], v[148:149]
	v_pk_mul_f32 v[138:139], v[138:139], v[140:141]
	v_pk_add_f32 v[146:147], v[146:147], 1.0 op_sel_hi:[1,0]
	v_pk_mul_f32 v[112:113], v[112:113], v[138:139]
	v_or_b32_e32 v138, 64, v142
	v_mad_i64_i32 v[140:141], s[26:27], v138, s35, v[136:137]
	v_pk_mul_f32 v[144:145], v[144:145], v[146:147]
	v_lshl_add_u64 v[138:139], v[140:141], 0, s[30:31]
	v_pk_mul_f32 v[110:111], v[110:111], v[144:145]
	v_lshl_add_u64 v[144:145], v[138:139], 0, v[0:1]
	global_load_dwordx2 v[144:145], v[144:145], off
	v_lshl_add_u64 v[140:141], v[140:141], 0, s[42:43]
	v_lshl_add_u64 v[146:147], v[140:141], 0, v[0:1]
	global_load_dwordx2 v[146:147], v[146:147], off
	s_waitcnt vmcnt(1)
	v_lshlrev_b32_e32 v143, 16, v144
	v_mul_f32_e32 v143, 0xbfb8aa3b, v143
	v_exp_f32_e32 v143, v143
	s_nop 0
	v_add_f32_e32 v143, 1.0, v143
	v_rcp_f32_e32 v148, v143
	s_waitcnt vmcnt(0)
	v_lshlrev_b32_e32 v143, 16, v146
	v_mul_f32_e32 v143, 0xbfb8aa3b, v143
	v_exp_f32_e32 v150, v143
	v_and_b32_e32 v143, 0xffff0000, v144
	v_mul_f32_e32 v143, 0xbfb8aa3b, v143
	v_exp_f32_e32 v143, v143
	s_nop 0
	v_add_f32_e32 v143, 1.0, v143
	v_rcp_f32_e32 v149, v143
	v_and_b32_e32 v143, 0xffff0000, v146
	v_mul_f32_e32 v143, 0xbfb8aa3b, v143
	v_exp_f32_e32 v151, v143
	v_lshlrev_b32_e32 v143, 16, v145
	v_mul_f32_e32 v143, 0xbfb8aa3b, v143
	v_exp_f32_e32 v143, v143
	v_pk_add_f32 v[150:151], v[150:151], 1.0 op_sel_hi:[1,0]
	v_add_f32_e32 v143, 1.0, v143
	v_rcp_f32_e32 v144, v143
	v_lshlrev_b32_e32 v143, 16, v147
	v_mul_f32_e32 v143, 0xbfb8aa3b, v143
	v_exp_f32_e32 v146, v143
	v_and_b32_e32 v143, 0xffff0000, v145
	v_mul_f32_e32 v143, 0xbfb8aa3b, v143
	v_exp_f32_e32 v143, v143
	v_pk_mul_f32 v[148:149], v[148:149], v[150:151]
	v_add_f32_e32 v143, 1.0, v143
	v_rcp_f32_e32 v145, v143
	v_and_b32_e32 v143, 0xffff0000, v147
	v_mul_f32_e32 v143, 0xbfb8aa3b, v143
	v_exp_f32_e32 v147, v143
	v_pk_mul_f32 v[118:119], v[118:119], v[148:149]
	v_pk_add_f32 v[146:147], v[146:147], 1.0 op_sel_hi:[1,0]
	s_nop 0
	v_pk_mul_f32 v[144:145], v[144:145], v[146:147]
	v_lshl_add_u64 v[146:147], v[140:141], 0, v[134:135]
	v_pk_mul_f32 v[120:121], v[120:121], v[144:145]
	v_lshl_add_u64 v[144:145], v[138:139], 0, v[134:135]
	global_load_dwordx2 v[144:145], v[144:145], off
	s_nop 0
	global_load_dwordx2 v[146:147], v[146:147], off
	s_waitcnt vmcnt(1)
	v_lshlrev_b32_e32 v143, 16, v144
	v_mul_f32_e32 v143, 0xbfb8aa3b, v143
	v_exp_f32_e32 v143, v143
	s_nop 0
	v_add_f32_e32 v143, 1.0, v143
	v_rcp_f32_e32 v148, v143
	s_waitcnt vmcnt(0)
	v_lshlrev_b32_e32 v143, 16, v146
	v_mul_f32_e32 v143, 0xbfb8aa3b, v143
	v_exp_f32_e32 v150, v143
	v_and_b32_e32 v143, 0xffff0000, v144
	v_mul_f32_e32 v143, 0xbfb8aa3b, v143
	v_exp_f32_e32 v143, v143
	s_nop 0
	v_add_f32_e32 v143, 1.0, v143
	v_rcp_f32_e32 v149, v143
	v_and_b32_e32 v143, 0xffff0000, v146
	v_mul_f32_e32 v143, 0xbfb8aa3b, v143
	v_exp_f32_e32 v151, v143
	v_lshlrev_b32_e32 v143, 16, v145
	v_mul_f32_e32 v143, 0xbfb8aa3b, v143
	v_exp_f32_e32 v143, v143
	v_pk_add_f32 v[150:151], v[150:151], 1.0 op_sel_hi:[1,0]
	v_add_f32_e32 v143, 1.0, v143
	v_rcp_f32_e32 v144, v143
	v_lshlrev_b32_e32 v143, 16, v147
	v_mul_f32_e32 v143, 0xbfb8aa3b, v143
	v_exp_f32_e32 v146, v143
	v_and_b32_e32 v143, 0xffff0000, v145
	v_mul_f32_e32 v143, 0xbfb8aa3b, v143
	v_exp_f32_e32 v143, v143
	v_pk_mul_f32 v[148:149], v[148:149], v[150:151]
	v_add_f32_e32 v143, 1.0, v143
	v_rcp_f32_e32 v145, v143
	v_and_b32_e32 v143, 0xffff0000, v147
	v_mul_f32_e32 v143, 0xbfb8aa3b, v143
	v_exp_f32_e32 v147, v143
	v_pk_mul_f32 v[126:127], v[126:127], v[148:149]
	v_pk_add_f32 v[146:147], v[146:147], 1.0 op_sel_hi:[1,0]
	s_nop 0
	v_pk_mul_f32 v[144:145], v[144:145], v[146:147]
	v_lshl_add_u64 v[146:147], v[140:141], 0, v[132:133]
	v_pk_mul_f32 v[128:129], v[128:129], v[144:145]
	v_lshl_add_u64 v[144:145], v[138:139], 0, v[132:133]
	global_load_dwordx2 v[144:145], v[144:145], off
	v_lshl_add_u64 v[138:139], v[138:139], 0, v[130:131]
	global_load_dwordx2 v[146:147], v[146:147], off
	v_lshl_add_u64 v[140:141], v[140:141], 0, v[130:131]
	global_load_dwordx2 v[138:139], v[138:139], off
	s_nop 0
	global_load_dwordx2 v[140:141], v[140:141], off
	s_waitcnt vmcnt(3)
; DI float bflo(unsigned u) { return __uint_as_float(u << 16); }
; DI float bfhi(unsigned u) { return __uint_as_float(u & 0xffff0000u); }
; DI float sigmoidf(float x) { return __builtin_amdgcn_rcpf(1.f + __expf(-x)); }
; DI float inv_sigmoidf(float x) { return 1.f + __expf(-x); }
; __global__ void __launch_bounds__(512, 2) mega(Params p) {
;     ...
;       gemm8_epi(acc8, m0, n0, [&](int m, int n, f32x4& a) {
;         uint2 ua = *(const uint2*)(z + (size_t)m * ZS + C_MA + n);
;         uint2 ub = *(const uint2*)(z + (size_t)m * ZS + C_MB + n);
;         a[0] *= sigmoidf(bflo(ua.x)) * inv_sigmoidf(bflo(ub.x));
;         a[1] *= sigmoidf(bfhi(ua.x)) * inv_sigmoidf(bfhi(ub.x));
;         a[2] *= sigmoidf(bflo(ua.y)) * inv_sigmoidf(bflo(ub.y));
;         a[3] *= sigmoidf(bfhi(ua.y)) * inv_sigmoidf(bfhi(ub.y));
;       });
	v_lshlrev_b32_e32 v143, 16, v144
	v_mul_f32_e32 v143, 0xbfb8aa3b, v143
	v_exp_f32_e32 v143, v143
	s_nop 0
	v_add_f32_e32 v143, 1.0, v143
	v_rcp_f32_e32 v148, v143
	s_waitcnt vmcnt(2)
	v_lshlrev_b32_e32 v143, 16, v146
	v_mul_f32_e32 v143, 0xbfb8aa3b, v143
	v_exp_f32_e32 v150, v143
	v_and_b32_e32 v143, 0xffff0000, v144
	v_mul_f32_e32 v143, 0xbfb8aa3b, v143
	v_exp_f32_e32 v143, v143
	s_nop 0
	v_add_f32_e32 v143, 1.0, v143
	v_rcp_f32_e32 v149, v143
	v_and_b32_e32 v143, 0xffff0000, v146
	v_mul_f32_e32 v143, 0xbfb8aa3b, v143
	v_exp_f32_e32 v151, v143
	v_lshlrev_b32_e32 v143, 16, v145
	v_mul_f32_e32 v143, 0xbfb8aa3b, v143
	v_exp_f32_e32 v143, v143
	v_pk_add_f32 v[150:151], v[150:151], 1.0 op_sel_hi:[1,0]
	v_add_f32_e32 v143, 1.0, v143
	v_rcp_f32_e32 v144, v143
	v_lshlrev_b32_e32 v143, 16, v147
	v_mul_f32_e32 v143, 0xbfb8aa3b, v143
	v_exp_f32_e32 v146, v143
	v_and_b32_e32 v143, 0xffff0000, v145
	v_mul_f32_e32 v143, 0xbfb8aa3b, v143
	v_exp_f32_e32 v143, v143
	v_pk_mul_f32 v[148:149], v[148:149], v[150:151]
	v_add_f32_e32 v143, 1.0, v143
	v_rcp_f32_e32 v145, v143
	v_and_b32_e32 v143, 0xffff0000, v147
	v_mul_f32_e32 v143, 0xbfb8aa3b, v143
	v_exp_f32_e32 v147, v143
	s_waitcnt vmcnt(1)
	v_lshlrev_b32_e32 v143, 16, v138
	v_and_b32_e32 v138, 0xffff0000, v138
	v_mul_f32_e32 v138, 0xbfb8aa3b, v138
	v_exp_f32_e32 v138, v138
	v_pk_add_f32 v[146:147], v[146:147], 1.0 op_sel_hi:[1,0]
	v_mul_f32_e32 v143, 0xbfb8aa3b, v143
	v_pk_mul_f32 v[144:145], v[144:145], v[146:147]
	v_add_f32_e32 v138, 1.0, v138
	v_pk_mul_f32 v[124:125], v[124:125], v[144:145]
	v_rcp_f32_e32 v145, v138
	s_waitcnt vmcnt(0)
	v_and_b32_e32 v138, 0xffff0000, v140
	v_exp_f32_e32 v143, v143
	v_mul_f32_e32 v138, 0xbfb8aa3b, v138
	v_exp_f32_e32 v147, v138
	v_lshlrev_b32_e32 v138, 16, v139
	v_and_b32_e32 v139, 0xffff0000, v139
	v_mul_f32_e32 v138, 0xbfb8aa3b, v138
	v_mul_f32_e32 v139, 0xbfb8aa3b, v139
	v_exp_f32_e32 v138, v138
	v_exp_f32_e32 v139, v139
	v_add_f32_e32 v143, 1.0, v143
	v_rcp_f32_e32 v144, v143
	v_lshlrev_b32_e32 v143, 16, v140
	v_lshlrev_b32_e32 v140, 16, v141
	v_and_b32_e32 v141, 0xffff0000, v141
	v_mul_f32_e32 v140, 0xbfb8aa3b, v140
	v_mul_f32_e32 v141, 0xbfb8aa3b, v141
	v_add_f32_e32 v138, 1.0, v138
	v_exp_f32_e32 v140, v140
	v_add_f32_e32 v139, 1.0, v139
	v_exp_f32_e32 v141, v141
	v_rcp_f32_e32 v138, v138
	v_rcp_f32_e32 v139, v139
	v_mul_f32_e32 v143, 0xbfb8aa3b, v143
	v_exp_f32_e32 v146, v143
	v_pk_add_f32 v[140:141], v[140:141], 1.0 op_sel_hi:[1,0]
	v_pk_mul_f32 v[122:123], v[122:123], v[148:149]
	v_pk_mul_f32 v[138:139], v[138:139], v[140:141]
	v_pk_add_f32 v[146:147], v[146:147], 1.0 op_sel_hi:[1,0]
	v_pk_mul_f32 v[116:117], v[116:117], v[138:139]
	v_or_b32_e32 v138, 0x50, v142
	v_mad_i64_i32 v[140:141], s[26:27], v138, s35, v[136:137]
	v_pk_mul_f32 v[144:145], v[144:145], v[146:147]
	v_lshl_add_u64 v[138:139], v[140:141], 0, s[30:31]
	v_pk_mul_f32 v[114:115], v[114:115], v[144:145]
	v_lshl_add_u64 v[144:145], v[138:139], 0, v[0:1]
	global_load_dwordx2 v[144:145], v[144:145], off
	v_lshl_add_u64 v[140:141], v[140:141], 0, s[42:43]
	v_lshl_add_u64 v[146:147], v[140:141], 0, v[0:1]
	global_load_dwordx2 v[146:147], v[146:147], off
	s_waitcnt vmcnt(1)
	v_lshlrev_b32_e32 v143, 16, v144
	v_mul_f32_e32 v143, 0xbfb8aa3b, v143
	v_exp_f32_e32 v143, v143
	s_nop 0
	v_add_f32_e32 v143, 1.0, v143
	v_rcp_f32_e32 v148, v143
	s_waitcnt vmcnt(0)
	v_lshlrev_b32_e32 v143, 16, v146
	v_mul_f32_e32 v143, 0xbfb8aa3b, v143
	v_exp_f32_e32 v150, v143
	v_and_b32_e32 v143, 0xffff0000, v144
	v_mul_f32_e32 v143, 0xbfb8aa3b, v143
	v_exp_f32_e32 v143, v143
	s_nop 0
	v_add_f32_e32 v143, 1.0, v143
	v_rcp_f32_e32 v149, v143
	v_and_b32_e32 v143, 0xffff0000, v146
	v_mul_f32_e32 v143, 0xbfb8aa3b, v143
	v_exp_f32_e32 v151, v143
	v_lshlrev_b32_e32 v143, 16, v145
	v_mul_f32_e32 v143, 0xbfb8aa3b, v143
	v_exp_f32_e32 v143, v143
	v_pk_add_f32 v[150:151], v[150:151], 1.0 op_sel_hi:[1,0]
	v_add_f32_e32 v143, 1.0, v143
	v_rcp_f32_e32 v144, v143
	v_lshlrev_b32_e32 v143, 16, v147
	v_mul_f32_e32 v143, 0xbfb8aa3b, v143
	v_exp_f32_e32 v146, v143
	v_and_b32_e32 v143, 0xffff0000, v145
	v_mul_f32_e32 v143, 0xbfb8aa3b, v143
	v_exp_f32_e32 v143, v143
	v_pk_mul_f32 v[148:149], v[148:149], v[150:151]
	v_add_f32_e32 v143, 1.0, v143
	v_rcp_f32_e32 v145, v143
	v_and_b32_e32 v143, 0xffff0000, v147
	v_mul_f32_e32 v143, 0xbfb8aa3b, v143
	v_exp_f32_e32 v147, v143
	v_pk_mul_f32 v[106:107], v[106:107], v[148:149]
	v_pk_add_f32 v[146:147], v[146:147], 1.0 op_sel_hi:[1,0]
	s_nop 0
	v_pk_mul_f32 v[144:145], v[144:145], v[146:147]
	v_lshl_add_u64 v[146:147], v[140:141], 0, v[134:135]
	v_pk_mul_f32 v[108:109], v[108:109], v[144:145]
	v_lshl_add_u64 v[144:145], v[138:139], 0, v[134:135]
	global_load_dwordx2 v[144:145], v[144:145], off
	s_nop 0
	global_load_dwordx2 v[146:147], v[146:147], off
	s_waitcnt vmcnt(1)
	v_lshlrev_b32_e32 v143, 16, v144
	v_mul_f32_e32 v143, 0xbfb8aa3b, v143
	v_exp_f32_e32 v143, v143
	s_nop 0
	v_add_f32_e32 v143, 1.0, v143
	v_rcp_f32_e32 v148, v143
	s_waitcnt vmcnt(0)
; DI float bflo(unsigned u) { return __uint_as_float(u << 16); }
; DI float bfhi(unsigned u) { return __uint_as_float(u & 0xffff0000u); }
; DI float sigmoidf(float x) { return __builtin_amdgcn_rcpf(1.f + __expf(-x)); }
; DI float inv_sigmoidf(float x) { return 1.f + __expf(-x); }
; __global__ void __launch_bounds__(512, 2) mega(Params p) {
;     ...
;       gemm8_epi(acc8, m0, n0, [&](int m, int n, f32x4& a) {
;         uint2 ua = *(const uint2*)(z + (size_t)m * ZS + C_MA + n);
;         uint2 ub = *(const uint2*)(z + (size_t)m * ZS + C_MB + n);
;         a[0] *= sigmoidf(bflo(ua.x)) * inv_sigmoidf(bflo(ub.x));
;         a[1] *= sigmoidf(bfhi(ua.x)) * inv_sigmoidf(bfhi(ub.x));
;         a[2] *= sigmoidf(bflo(ua.y)) * inv_sigmoidf(bflo(ub.y));
;         a[3] *= sigmoidf(bfhi(ua.y)) * inv_sigmoidf(bfhi(ub.y));
;       });
	v_lshlrev_b32_e32 v143, 16, v146
	v_mul_f32_e32 v143, 0xbfb8aa3b, v143
	v_exp_f32_e32 v150, v143
	v_and_b32_e32 v143, 0xffff0000, v144
	v_mul_f32_e32 v143, 0xbfb8aa3b, v143
	v_exp_f32_e32 v143, v143
	s_nop 0
	v_add_f32_e32 v143, 1.0, v143
	v_rcp_f32_e32 v149, v143
	v_and_b32_e32 v143, 0xffff0000, v146
	v_mul_f32_e32 v143, 0xbfb8aa3b, v143
	v_exp_f32_e32 v151, v143
	v_lshlrev_b32_e32 v143, 16, v145
	v_mul_f32_e32 v143, 0xbfb8aa3b, v143
	v_exp_f32_e32 v143, v143
	v_pk_add_f32 v[150:151], v[150:151], 1.0 op_sel_hi:[1,0]
	v_add_f32_e32 v143, 1.0, v143
	v_rcp_f32_e32 v144, v143
	v_lshlrev_b32_e32 v143, 16, v147
	v_mul_f32_e32 v143, 0xbfb8aa3b, v143
	v_exp_f32_e32 v146, v143
	v_and_b32_e32 v143, 0xffff0000, v145
	v_mul_f32_e32 v143, 0xbfb8aa3b, v143
	v_exp_f32_e32 v143, v143
	v_pk_mul_f32 v[148:149], v[148:149], v[150:151]
	v_add_f32_e32 v143, 1.0, v143
	v_rcp_f32_e32 v145, v143
	v_and_b32_e32 v143, 0xffff0000, v147
	v_mul_f32_e32 v143, 0xbfb8aa3b, v143
	v_exp_f32_e32 v147, v143
	v_pk_mul_f32 v[98:99], v[98:99], v[148:149]
	v_pk_add_f32 v[146:147], v[146:147], 1.0 op_sel_hi:[1,0]
	s_nop 0
	v_pk_mul_f32 v[144:145], v[144:145], v[146:147]
	v_lshl_add_u64 v[146:147], v[140:141], 0, v[132:133]
	v_pk_mul_f32 v[100:101], v[100:101], v[144:145]
	v_lshl_add_u64 v[144:145], v[138:139], 0, v[132:133]
	global_load_dwordx2 v[144:145], v[144:145], off
	v_lshl_add_u64 v[138:139], v[138:139], 0, v[130:131]
	global_load_dwordx2 v[146:147], v[146:147], off
	v_lshl_add_u64 v[140:141], v[140:141], 0, v[130:131]
	global_load_dwordx2 v[138:139], v[138:139], off
	s_nop 0
	global_load_dwordx2 v[140:141], v[140:141], off
	s_waitcnt vmcnt(3)
	v_lshlrev_b32_e32 v143, 16, v144
	v_mul_f32_e32 v143, 0xbfb8aa3b, v143
	v_exp_f32_e32 v143, v143
	s_nop 0
	v_add_f32_e32 v143, 1.0, v143
	v_rcp_f32_e32 v148, v143
	s_waitcnt vmcnt(2)
	v_lshlrev_b32_e32 v143, 16, v146
	v_mul_f32_e32 v143, 0xbfb8aa3b, v143
	v_exp_f32_e32 v150, v143
	v_and_b32_e32 v143, 0xffff0000, v144
	v_mul_f32_e32 v143, 0xbfb8aa3b, v143
	v_exp_f32_e32 v143, v143
	s_nop 0
	v_add_f32_e32 v143, 1.0, v143
	v_rcp_f32_e32 v149, v143
	v_and_b32_e32 v143, 0xffff0000, v146
	v_mul_f32_e32 v143, 0xbfb8aa3b, v143
	v_exp_f32_e32 v151, v143
	v_lshlrev_b32_e32 v143, 16, v145
	v_mul_f32_e32 v143, 0xbfb8aa3b, v143
	v_exp_f32_e32 v143, v143
	v_pk_add_f32 v[150:151], v[150:151], 1.0 op_sel_hi:[1,0]
	v_add_f32_e32 v143, 1.0, v143
	v_rcp_f32_e32 v144, v143
	v_lshlrev_b32_e32 v143, 16, v147
	v_mul_f32_e32 v143, 0xbfb8aa3b, v143
	v_exp_f32_e32 v146, v143
	v_and_b32_e32 v143, 0xffff0000, v145
	v_mul_f32_e32 v143, 0xbfb8aa3b, v143
	v_exp_f32_e32 v143, v143
	v_pk_mul_f32 v[148:149], v[148:149], v[150:151]
	v_add_f32_e32 v143, 1.0, v143
	v_rcp_f32_e32 v145, v143
	v_and_b32_e32 v143, 0xffff0000, v147
	v_mul_f32_e32 v143, 0xbfb8aa3b, v143
	v_exp_f32_e32 v147, v143
	s_waitcnt vmcnt(1)
	v_lshlrev_b32_e32 v143, 16, v138
	v_and_b32_e32 v138, 0xffff0000, v138
	v_mul_f32_e32 v138, 0xbfb8aa3b, v138
	v_exp_f32_e32 v138, v138
	v_pk_add_f32 v[146:147], v[146:147], 1.0 op_sel_hi:[1,0]
	v_mul_f32_e32 v143, 0xbfb8aa3b, v143
	v_pk_mul_f32 v[144:145], v[144:145], v[146:147]
	v_add_f32_e32 v138, 1.0, v138
	v_pk_mul_f32 v[92:93], v[92:93], v[144:145]
	v_rcp_f32_e32 v145, v138
	s_waitcnt vmcnt(0)
	v_and_b32_e32 v138, 0xffff0000, v140
	v_exp_f32_e32 v143, v143
	v_mul_f32_e32 v138, 0xbfb8aa3b, v138
	v_exp_f32_e32 v147, v138
	v_lshlrev_b32_e32 v138, 16, v139
	v_and_b32_e32 v139, 0xffff0000, v139
	v_mul_f32_e32 v138, 0xbfb8aa3b, v138
	v_mul_f32_e32 v139, 0xbfb8aa3b, v139
	v_exp_f32_e32 v138, v138
	v_exp_f32_e32 v139, v139
	v_add_f32_e32 v143, 1.0, v143
	v_rcp_f32_e32 v144, v143
	v_lshlrev_b32_e32 v143, 16, v140
	v_lshlrev_b32_e32 v140, 16, v141
	v_and_b32_e32 v141, 0xffff0000, v141
	v_mul_f32_e32 v140, 0xbfb8aa3b, v140
	v_mul_f32_e32 v141, 0xbfb8aa3b, v141
	v_add_f32_e32 v138, 1.0, v138
	v_exp_f32_e32 v140, v140
	v_add_f32_e32 v139, 1.0, v139
	v_exp_f32_e32 v141, v141
	v_rcp_f32_e32 v138, v138
	v_rcp_f32_e32 v139, v139
	v_mul_f32_e32 v143, 0xbfb8aa3b, v143
	v_exp_f32_e32 v146, v143
	v_pk_add_f32 v[140:141], v[140:141], 1.0 op_sel_hi:[1,0]
	v_pk_mul_f32 v[90:91], v[90:91], v[148:149]
	v_pk_mul_f32 v[138:139], v[138:139], v[140:141]
	v_pk_add_f32 v[146:147], v[146:147], 1.0 op_sel_hi:[1,0]
	v_pk_mul_f32 v[84:85], v[84:85], v[138:139]
	v_or_b32_e32 v138, 0x60, v142
	v_mad_i64_i32 v[140:141], s[26:27], v138, s35, v[136:137]
	v_pk_mul_f32 v[144:145], v[144:145], v[146:147]
	v_lshl_add_u64 v[138:139], v[140:141], 0, s[30:31]
	v_pk_mul_f32 v[82:83], v[82:83], v[144:145]
	v_lshl_add_u64 v[144:145], v[138:139], 0, v[0:1]
	global_load_dwordx2 v[144:145], v[144:145], off
	v_lshl_add_u64 v[140:141], v[140:141], 0, s[42:43]
	v_lshl_add_u64 v[146:147], v[140:141], 0, v[0:1]
	global_load_dwordx2 v[146:147], v[146:147], off
	s_waitcnt vmcnt(1)
	v_lshlrev_b32_e32 v143, 16, v144
	v_mul_f32_e32 v143, 0xbfb8aa3b, v143
	v_exp_f32_e32 v143, v143
	s_nop 0
	v_add_f32_e32 v143, 1.0, v143
	v_rcp_f32_e32 v148, v143
	s_waitcnt vmcnt(0)
; DI float bflo(unsigned u) { return __uint_as_float(u << 16); }
; DI float bfhi(unsigned u) { return __uint_as_float(u & 0xffff0000u); }
; DI float sigmoidf(float x) { return __builtin_amdgcn_rcpf(1.f + __expf(-x)); }
; DI float inv_sigmoidf(float x) { return 1.f + __expf(-x); }
; __global__ void __launch_bounds__(512, 2) mega(Params p) {
;     ...
;       gemm8_epi(acc8, m0, n0, [&](int m, int n, f32x4& a) {
;         uint2 ua = *(const uint2*)(z + (size_t)m * ZS + C_MA + n);
;         uint2 ub = *(const uint2*)(z + (size_t)m * ZS + C_MB + n);
;         a[0] *= sigmoidf(bflo(ua.x)) * inv_sigmoidf(bflo(ub.x));
;         a[1] *= sigmoidf(bfhi(ua.x)) * inv_sigmoidf(bfhi(ub.x));
;         a[2] *= sigmoidf(bflo(ua.y)) * inv_sigmoidf(bflo(ub.y));
;         a[3] *= sigmoidf(bfhi(ua.y)) * inv_sigmoidf(bfhi(ub.y));
;       });
	v_lshlrev_b32_e32 v143, 16, v146
	v_mul_f32_e32 v143, 0xbfb8aa3b, v143
	v_exp_f32_e32 v150, v143
	v_and_b32_e32 v143, 0xffff0000, v144
	v_mul_f32_e32 v143, 0xbfb8aa3b, v143
	v_exp_f32_e32 v143, v143
	s_nop 0
	v_add_f32_e32 v143, 1.0, v143
	v_rcp_f32_e32 v149, v143
	v_and_b32_e32 v143, 0xffff0000, v146
	v_mul_f32_e32 v143, 0xbfb8aa3b, v143
	v_exp_f32_e32 v151, v143
	v_lshlrev_b32_e32 v143, 16, v145
	v_mul_f32_e32 v143, 0xbfb8aa3b, v143
	v_exp_f32_e32 v143, v143
	v_pk_add_f32 v[150:151], v[150:151], 1.0 op_sel_hi:[1,0]
	v_add_f32_e32 v143, 1.0, v143
	v_rcp_f32_e32 v144, v143
	v_lshlrev_b32_e32 v143, 16, v147
	v_mul_f32_e32 v143, 0xbfb8aa3b, v143
	v_exp_f32_e32 v146, v143
	v_and_b32_e32 v143, 0xffff0000, v145
	v_mul_f32_e32 v143, 0xbfb8aa3b, v143
	v_exp_f32_e32 v143, v143
	v_pk_mul_f32 v[148:149], v[148:149], v[150:151]
	v_add_f32_e32 v143, 1.0, v143
	v_rcp_f32_e32 v145, v143
	v_and_b32_e32 v143, 0xffff0000, v147
	v_mul_f32_e32 v143, 0xbfb8aa3b, v143
	v_exp_f32_e32 v147, v143
	v_pk_mul_f32 v[74:75], v[74:75], v[148:149]
	v_pk_add_f32 v[146:147], v[146:147], 1.0 op_sel_hi:[1,0]
	s_nop 0
	v_pk_mul_f32 v[144:145], v[144:145], v[146:147]
	v_lshl_add_u64 v[146:147], v[140:141], 0, v[134:135]
	v_pk_mul_f32 v[76:77], v[76:77], v[144:145]
	v_lshl_add_u64 v[144:145], v[138:139], 0, v[134:135]
	global_load_dwordx2 v[144:145], v[144:145], off
	s_nop 0
	global_load_dwordx2 v[146:147], v[146:147], off
	s_waitcnt vmcnt(1)
	v_lshlrev_b32_e32 v143, 16, v144
	v_mul_f32_e32 v143, 0xbfb8aa3b, v143
	v_exp_f32_e32 v143, v143
	s_nop 0
	v_add_f32_e32 v143, 1.0, v143
	v_rcp_f32_e32 v148, v143
	s_waitcnt vmcnt(0)
	v_lshlrev_b32_e32 v143, 16, v146
	v_mul_f32_e32 v143, 0xbfb8aa3b, v143
	v_exp_f32_e32 v150, v143
	v_and_b32_e32 v143, 0xffff0000, v144
	v_mul_f32_e32 v143, 0xbfb8aa3b, v143
	v_exp_f32_e32 v143, v143
	s_nop 0
	v_add_f32_e32 v143, 1.0, v143
	v_rcp_f32_e32 v149, v143
	v_and_b32_e32 v143, 0xffff0000, v146
	v_mul_f32_e32 v143, 0xbfb8aa3b, v143
	v_exp_f32_e32 v151, v143
	v_lshlrev_b32_e32 v143, 16, v145
	v_mul_f32_e32 v143, 0xbfb8aa3b, v143
	v_exp_f32_e32 v143, v143
	v_pk_add_f32 v[150:151], v[150:151], 1.0 op_sel_hi:[1,0]
	v_add_f32_e32 v143, 1.0, v143
	v_rcp_f32_e32 v144, v143
	v_lshlrev_b32_e32 v143, 16, v147
	v_mul_f32_e32 v143, 0xbfb8aa3b, v143
	v_exp_f32_e32 v146, v143
	v_and_b32_e32 v143, 0xffff0000, v145
	v_mul_f32_e32 v143, 0xbfb8aa3b, v143
	v_exp_f32_e32 v143, v143
	v_pk_mul_f32 v[148:149], v[148:149], v[150:151]
	v_add_f32_e32 v143, 1.0, v143
	v_rcp_f32_e32 v145, v143
	v_and_b32_e32 v143, 0xffff0000, v147
	v_mul_f32_e32 v143, 0xbfb8aa3b, v143
	v_exp_f32_e32 v147, v143
	v_pk_mul_f32 v[66:67], v[66:67], v[148:149]
	v_pk_add_f32 v[146:147], v[146:147], 1.0 op_sel_hi:[1,0]
	s_nop 0
	v_pk_mul_f32 v[144:145], v[144:145], v[146:147]
	v_lshl_add_u64 v[146:147], v[140:141], 0, v[132:133]
	v_pk_mul_f32 v[68:69], v[68:69], v[144:145]
	v_lshl_add_u64 v[144:145], v[138:139], 0, v[132:133]
	global_load_dwordx2 v[144:145], v[144:145], off
	v_lshl_add_u64 v[138:139], v[138:139], 0, v[130:131]
	global_load_dwordx2 v[146:147], v[146:147], off
	v_lshl_add_u64 v[140:141], v[140:141], 0, v[130:131]
	global_load_dwordx2 v[138:139], v[138:139], off
	s_nop 0
	global_load_dwordx2 v[140:141], v[140:141], off
	s_waitcnt vmcnt(3)
	v_lshlrev_b32_e32 v143, 16, v144
	v_mul_f32_e32 v143, 0xbfb8aa3b, v143
	v_exp_f32_e32 v143, v143
	s_nop 0
	v_add_f32_e32 v143, 1.0, v143
	v_rcp_f32_e32 v148, v143
	s_waitcnt vmcnt(2)
	v_lshlrev_b32_e32 v143, 16, v146
	v_mul_f32_e32 v143, 0xbfb8aa3b, v143
	v_exp_f32_e32 v150, v143
	v_and_b32_e32 v143, 0xffff0000, v144
	v_mul_f32_e32 v143, 0xbfb8aa3b, v143
	v_exp_f32_e32 v143, v143
	s_nop 0
	v_add_f32_e32 v143, 1.0, v143
	v_rcp_f32_e32 v149, v143
	v_and_b32_e32 v143, 0xffff0000, v146
	v_mul_f32_e32 v143, 0xbfb8aa3b, v143
	v_exp_f32_e32 v151, v143
	v_lshlrev_b32_e32 v143, 16, v145
	v_mul_f32_e32 v143, 0xbfb8aa3b, v143
	v_exp_f32_e32 v143, v143
	v_pk_add_f32 v[150:151], v[150:151], 1.0 op_sel_hi:[1,0]
	v_add_f32_e32 v143, 1.0, v143
	v_rcp_f32_e32 v144, v143
	v_lshlrev_b32_e32 v143, 16, v147
	v_mul_f32_e32 v143, 0xbfb8aa3b, v143
	v_exp_f32_e32 v146, v143
	v_and_b32_e32 v143, 0xffff0000, v145
	v_mul_f32_e32 v143, 0xbfb8aa3b, v143
	v_exp_f32_e32 v143, v143
	v_pk_mul_f32 v[148:149], v[148:149], v[150:151]
	v_add_f32_e32 v143, 1.0, v143
	v_rcp_f32_e32 v145, v143
	v_and_b32_e32 v143, 0xffff0000, v147
	v_mul_f32_e32 v143, 0xbfb8aa3b, v143
	v_exp_f32_e32 v147, v143
	s_waitcnt vmcnt(1)
	v_lshlrev_b32_e32 v143, 16, v138
	v_and_b32_e32 v138, 0xffff0000, v138
	v_mul_f32_e32 v138, 0xbfb8aa3b, v138
	v_exp_f32_e32 v138, v138
	v_pk_add_f32 v[146:147], v[146:147], 1.0 op_sel_hi:[1,0]
	v_mul_f32_e32 v143, 0xbfb8aa3b, v143
	v_pk_mul_f32 v[144:145], v[144:145], v[146:147]
	v_add_f32_e32 v138, 1.0, v138
	v_pk_mul_f32 v[60:61], v[60:61], v[144:145]
	v_rcp_f32_e32 v145, v138
	s_waitcnt vmcnt(0)
	v_and_b32_e32 v138, 0xffff0000, v140
	v_exp_f32_e32 v143, v143
	v_mul_f32_e32 v138, 0xbfb8aa3b, v138
	v_exp_f32_e32 v147, v138
	v_lshlrev_b32_e32 v138, 16, v139
	v_and_b32_e32 v139, 0xffff0000, v139
	v_mul_f32_e32 v138, 0xbfb8aa3b, v138
	v_mul_f32_e32 v139, 0xbfb8aa3b, v139
	v_exp_f32_e32 v138, v138
	v_exp_f32_e32 v139, v139
	v_add_f32_e32 v143, 1.0, v143
	v_rcp_f32_e32 v144, v143
	v_lshlrev_b32_e32 v143, 16, v140
	v_lshlrev_b32_e32 v140, 16, v141
	v_and_b32_e32 v141, 0xffff0000, v141
	v_mul_f32_e32 v140, 0xbfb8aa3b, v140
	v_mul_f32_e32 v141, 0xbfb8aa3b, v141
	v_add_f32_e32 v138, 1.0, v138
	v_exp_f32_e32 v140, v140
	v_add_f32_e32 v139, 1.0, v139
	v_exp_f32_e32 v141, v141
	v_rcp_f32_e32 v138, v138
	v_rcp_f32_e32 v139, v139
	v_mul_f32_e32 v143, 0xbfb8aa3b, v143
	v_pk_add_f32 v[140:141], v[140:141], 1.0 op_sel_hi:[1,0]
	v_exp_f32_e32 v146, v143
	v_pk_mul_f32 v[138:139], v[138:139], v[140:141]
	v_pk_mul_f32 v[58:59], v[58:59], v[148:149]
	v_pk_mul_f32 v[52:53], v[52:53], v[138:139]
	v_or_b32_e32 v138, 0x70, v142
	v_mad_i64_i32 v[138:139], s[26:27], v138, s35, v[136:137]
	v_lshl_add_u64 v[136:137], v[138:139], 0, s[30:31]
	v_lshl_add_u64 v[140:141], v[136:137], 0, v[0:1]
	global_load_dwordx2 v[140:141], v[140:141], off
	v_lshl_add_u64 v[138:139], v[138:139], 0, s[42:43]
	v_lshl_add_u64 v[142:143], v[138:139], 0, v[0:1]
	global_load_dwordx2 v[142:143], v[142:143], off
	v_pk_add_f32 v[146:147], v[146:147], 1.0 op_sel_hi:[1,0]
	s_waitcnt vmcnt(1)
; DI float bflo(unsigned u) { return __uint_as_float(u << 16); }
; DI float bfhi(unsigned u) { return __uint_as_float(u & 0xffff0000u); }
; DI float sigmoidf(float x) { return __builtin_amdgcn_rcpf(1.f + __expf(-x)); }
; DI float inv_sigmoidf(float x) { return 1.f + __expf(-x); }
; DI int TID8() { int t = threadIdx.x; asm volatile("" : "+v"(t)); return t; }
; DI void gemm8_accum(f32x4 (&acc)[8][4], const bf16_t* a, size_t lda, const bf16_t* b, size_t ldb, int nkb, bf16_t* L,
;                     const bool pre, const bf16_t* an, size_t ldan, const bf16_t* bn, size_t ldbn) {
;   const int tid = TID8(), lane = tid & 63, w = tid >> 6;
;   const int wm = w >> 2, wn = w & 3;
;   const int lrow = tid >> 3, lch = tid & 7;
;   u32x4 ra[4], rb[4];
;   unsigned offa[4], offb[4];
; #pragma unroll
;   for (int i = 0; i < 4; ++i) {
;     offa[i] = (unsigned)(lrow + 64 * i) * (unsigned)lda + (unsigned)(lch * 8);
;     offb[i] = (unsigned)(lrow + 64 * i) * (unsigned)ldb + (unsigned)(lch * 8);
;   }
; __global__ void __launch_bounds__(512, 2) mega(Params p) {
;     ...
;       gemm8_epi(acc8, m0, n0, [&](int m, int n, f32x4& a) {
;         uint2 ua = *(const uint2*)(z + (size_t)m * ZS + C_MA + n);
;         uint2 ub = *(const uint2*)(z + (size_t)m * ZS + C_MB + n);
;         a[0] *= sigmoidf(bflo(ua.x)) * inv_sigmoidf(bflo(ub.x));
;         a[1] *= sigmoidf(bfhi(ua.x)) * inv_sigmoidf(bfhi(ub.x));
;         a[2] *= sigmoidf(bflo(ua.y)) * inv_sigmoidf(bflo(ub.y));
;         a[3] *= sigmoidf(bfhi(ua.y)) * inv_sigmoidf(bfhi(ub.y));
;       });
	v_lshlrev_b32_e32 v0, 16, v140
	v_mul_f32_e32 v0, 0xbfb8aa3b, v0
	v_exp_f32_e32 v0, v0
	v_pk_mul_f32 v[144:145], v[144:145], v[146:147]
	v_add_f32_e32 v0, 1.0, v0
	v_pk_mul_f32 v[50:51], v[50:51], v[144:145]
	v_rcp_f32_e32 v144, v0
	s_waitcnt vmcnt(0)
	v_lshlrev_b32_e32 v0, 16, v142
	v_mul_f32_e32 v0, 0xbfb8aa3b, v0
	v_exp_f32_e32 v146, v0
	v_and_b32_e32 v0, 0xffff0000, v140
	v_mul_f32_e32 v0, 0xbfb8aa3b, v0
	v_exp_f32_e32 v0, v0
	s_nop 0
	v_add_f32_e32 v0, 1.0, v0
	v_rcp_f32_e32 v145, v0
	v_and_b32_e32 v0, 0xffff0000, v142
	v_mul_f32_e32 v0, 0xbfb8aa3b, v0
	v_exp_f32_e32 v147, v0
	v_lshlrev_b32_e32 v0, 16, v141
	v_mul_f32_e32 v0, 0xbfb8aa3b, v0
	v_exp_f32_e32 v0, v0
	v_pk_add_f32 v[146:147], v[146:147], 1.0 op_sel_hi:[1,0]
	v_add_f32_e32 v0, 1.0, v0
	v_rcp_f32_e32 v140, v0
	v_lshlrev_b32_e32 v0, 16, v143
	v_mul_f32_e32 v0, 0xbfb8aa3b, v0
	v_exp_f32_e32 v142, v0
	v_and_b32_e32 v0, 0xffff0000, v141
	v_mul_f32_e32 v0, 0xbfb8aa3b, v0
	v_exp_f32_e32 v0, v0
	v_pk_mul_f32 v[144:145], v[144:145], v[146:147]
	v_add_f32_e32 v0, 1.0, v0
	v_rcp_f32_e32 v141, v0
	v_and_b32_e32 v0, 0xffff0000, v143
	v_mul_f32_e32 v0, 0xbfb8aa3b, v0
	v_exp_f32_e32 v143, v0
	v_pk_mul_f32 v[42:43], v[42:43], v[144:145]
	v_pk_add_f32 v[142:143], v[142:143], 1.0 op_sel_hi:[1,0]
	s_nop 0
	v_pk_mul_f32 v[140:141], v[140:141], v[142:143]
	s_nop 0
	v_pk_mul_f32 v[44:45], v[44:45], v[140:141]
	v_lshl_add_u64 v[140:141], v[136:137], 0, v[134:135]
	global_load_dwordx2 v[140:141], v[140:141], off
	v_lshl_add_u64 v[134:135], v[138:139], 0, v[134:135]
	global_load_dwordx2 v[134:135], v[134:135], off
	s_waitcnt vmcnt(1)
	v_lshlrev_b32_e32 v0, 16, v140
	v_mul_f32_e32 v0, 0xbfb8aa3b, v0
	v_exp_f32_e32 v0, v0
	s_nop 0
	v_add_f32_e32 v0, 1.0, v0
	v_rcp_f32_e32 v142, v0
	s_waitcnt vmcnt(0)
	v_lshlrev_b32_e32 v0, 16, v134
	v_mul_f32_e32 v0, 0xbfb8aa3b, v0
	v_exp_f32_e32 v144, v0
	v_and_b32_e32 v0, 0xffff0000, v140
	v_mul_f32_e32 v0, 0xbfb8aa3b, v0
	v_exp_f32_e32 v0, v0
	s_nop 0
	v_add_f32_e32 v0, 1.0, v0
	v_rcp_f32_e32 v143, v0
	v_and_b32_e32 v0, 0xffff0000, v134
	v_mul_f32_e32 v0, 0xbfb8aa3b, v0
	v_exp_f32_e32 v145, v0
	v_lshlrev_b32_e32 v0, 16, v141
	v_mul_f32_e32 v0, 0xbfb8aa3b, v0
	v_exp_f32_e32 v0, v0
	v_pk_add_f32 v[144:145], v[144:145], 1.0 op_sel_hi:[1,0]
	v_add_f32_e32 v0, 1.0, v0
	v_rcp_f32_e32 v140, v0
	v_lshlrev_b32_e32 v0, 16, v135
	v_mul_f32_e32 v0, 0xbfb8aa3b, v0
	v_exp_f32_e32 v134, v0
	v_and_b32_e32 v0, 0xffff0000, v141
	v_mul_f32_e32 v0, 0xbfb8aa3b, v0
	v_exp_f32_e32 v0, v0
	v_pk_mul_f32 v[142:143], v[142:143], v[144:145]
	v_mov_b32_e32 v145, v1
	v_pk_mul_f32 v[34:35], v[34:35], v[142:143]
	v_add_f32_e32 v0, 1.0, v0
	v_rcp_f32_e32 v141, v0
	v_and_b32_e32 v0, 0xffff0000, v135
	v_mul_f32_e32 v0, 0xbfb8aa3b, v0
	v_exp_f32_e32 v135, v0
	s_nop 0
	v_pk_add_f32 v[134:135], v[134:135], 1.0 op_sel_hi:[1,0]
	s_nop 0
	v_pk_mul_f32 v[134:135], v[140:141], v[134:135]
	s_nop 0
	v_pk_mul_f32 v[36:37], v[36:37], v[134:135]
	v_lshl_add_u64 v[134:135], v[136:137], 0, v[132:133]
	global_load_dwordx2 v[134:135], v[134:135], off
	v_lshl_add_u64 v[132:133], v[138:139], 0, v[132:133]
	global_load_dwordx2 v[132:133], v[132:133], off
	s_waitcnt vmcnt(1)
	v_lshlrev_b32_e32 v0, 16, v134
	v_mul_f32_e32 v0, 0xbfb8aa3b, v0
	v_exp_f32_e32 v0, v0
	s_nop 0
	v_add_f32_e32 v0, 1.0, v0
	v_rcp_f32_e32 v140, v0
	s_waitcnt vmcnt(0)
	v_lshlrev_b32_e32 v0, 16, v132
	v_mul_f32_e32 v0, 0xbfb8aa3b, v0
	v_exp_f32_e32 v142, v0
	v_and_b32_e32 v0, 0xffff0000, v134
	v_mul_f32_e32 v0, 0xbfb8aa3b, v0
	v_exp_f32_e32 v0, v0
	s_nop 0
	v_add_f32_e32 v0, 1.0, v0
	v_rcp_f32_e32 v141, v0
	v_and_b32_e32 v0, 0xffff0000, v132
	v_mul_f32_e32 v0, 0xbfb8aa3b, v0
	v_exp_f32_e32 v143, v0
	v_lshlrev_b32_e32 v0, 16, v135
	v_mul_f32_e32 v0, 0xbfb8aa3b, v0
	v_exp_f32_e32 v0, v0
	v_pk_add_f32 v[142:143], v[142:143], 1.0 op_sel_hi:[1,0]
	v_add_f32_e32 v0, 1.0, v0
	v_rcp_f32_e32 v134, v0
	v_lshlrev_b32_e32 v0, 16, v133
	v_mul_f32_e32 v0, 0xbfb8aa3b, v0
	v_exp_f32_e32 v132, v0
	v_and_b32_e32 v0, 0xffff0000, v135
	v_mul_f32_e32 v0, 0xbfb8aa3b, v0
	v_exp_f32_e32 v0, v0
	v_pk_mul_f32 v[140:141], v[140:141], v[142:143]
	v_mov_b32_e32 v143, v1
	v_pk_mul_f32 v[26:27], v[26:27], v[140:141]
	v_add_f32_e32 v0, 1.0, v0
	v_rcp_f32_e32 v135, v0
	v_and_b32_e32 v0, 0xffff0000, v133
	v_mul_f32_e32 v0, 0xbfb8aa3b, v0
	v_exp_f32_e32 v133, v0
	s_nop 0
	v_pk_add_f32 v[132:133], v[132:133], 1.0 op_sel_hi:[1,0]
	s_nop 0
	v_pk_mul_f32 v[132:133], v[134:135], v[132:133]
	s_nop 0
	v_pk_mul_f32 v[28:29], v[28:29], v[132:133]
	v_lshl_add_u64 v[132:133], v[136:137], 0, v[130:131]
	global_load_dwordx2 v[132:133], v[132:133], off
	v_lshl_add_u64 v[130:131], v[138:139], 0, v[130:131]
	global_load_dwordx2 v[130:131], v[130:131], off
	v_mov_b32_e32 v139, v1
	v_ashrrev_i32_e32 v173, 3, v172
	v_lshrrev_b32_e32 v140, 1, v173
	v_xor_b32_e32 v140, v140, v172
	v_lshlrev_b32_e32 v140, 3, v140
	v_and_b32_e32 v174, 56, v140
	v_lshrrev_b32_e32 v175, 1, v172
	v_bfe_u32 v176, v172, 1, 3
	v_lshlrev_b32_e32 v191, 1, v174
	v_lshlrev_b32_e32 v163, 6, v173
	s_waitcnt vmcnt(1)
	v_lshlrev_b32_e32 v0, 16, v132
	v_mul_f32_e32 v0, 0xbfb8aa3b, v0
	v_exp_f32_e32 v0, v0
	s_nop 0
	v_add_f32_e32 v0, 1.0, v0
	v_rcp_f32_e32 v134, v0
	s_waitcnt vmcnt(0)
; DI float bflo(unsigned u) { return __uint_as_float(u << 16); }
; DI float bfhi(unsigned u) { return __uint_as_float(u & 0xffff0000u); }
; DI float sigmoidf(float x) { return __builtin_amdgcn_rcpf(1.f + __expf(-x)); }
; DI float inv_sigmoidf(float x) { return 1.f + __expf(-x); }
; DI int TID8() { int t = threadIdx.x; asm volatile("" : "+v"(t)); return t; }
; DI void gemm8_accum(f32x4 (&acc)[8][4], const bf16_t* a, size_t lda, const bf16_t* b, size_t ldb, int nkb, bf16_t* L,
;                     const bool pre, const bf16_t* an, size_t ldan, const bf16_t* bn, size_t ldbn) {
;   const int tid = TID8(), lane = tid & 63, w = tid >> 6;
;   const int wm = w >> 2, wn = w & 3;
;   const int lrow = tid >> 3, lch = tid & 7;
;   u32x4 ra[4], rb[4];
;   unsigned offa[4], offb[4];
; #pragma unroll
;   for (int i = 0; i < 4; ++i) {
;     offa[i] = (unsigned)(lrow + 64 * i) * (unsigned)lda + (unsigned)(lch * 8);
;     offb[i] = (unsigned)(lrow + 64 * i) * (unsigned)ldb + (unsigned)(lch * 8);
;   }
;   if (!pre) {
;     g8_load1o(ra, a, offa);
;     g8_load1o(rb, b, offb);
;     __syncthreads();
;     g8_store(L, ra, rb, lrow, lch);
;   }
;   g8_load1o(ra, a + 64, offa);
;   g8_load1o(rb, b + 64, offb);
;   for (int kb = 0; kb + 2 < nkb; ++kb) {
;     __syncthreads();
;     g8_store1(L + ((kb + 1) & 1) * 32768, ra, lrow, lch);
;     g8_load1o(ra, a + (kb + 2) * 64, offa);
;     __builtin_amdgcn_sched_barrier(0);
;     g8_compute<0, 1>(acc, L + (kb & 1) * 32768, wm, wn, lane);
;     __builtin_amdgcn_sched_barrier(0);
;     g8_store1(L + ((kb + 1) & 1) * 32768 + 16384, rb, lrow, lch);
;     g8_load1o(rb, b + (kb + 2) * 64, offb);
;     __builtin_amdgcn_sched_barrier(0);
;     g8_compute<1, 2>(acc, L + (kb & 1) * 32768, wm, wn, lane);
; __global__ void __launch_bounds__(512, 2) mega(Params p) {
;     ...
;       gemm8_epi(acc8, m0, n0, [&](int m, int n, f32x4& a) {
;         uint2 ua = *(const uint2*)(z + (size_t)m * ZS + C_MA + n);
;         uint2 ub = *(const uint2*)(z + (size_t)m * ZS + C_MB + n);
;         a[0] *= sigmoidf(bflo(ua.x)) * inv_sigmoidf(bflo(ub.x));
;         a[1] *= sigmoidf(bfhi(ua.x)) * inv_sigmoidf(bfhi(ub.x));
;         a[2] *= sigmoidf(bflo(ua.y)) * inv_sigmoidf(bflo(ub.y));
;         a[3] *= sigmoidf(bfhi(ua.y)) * inv_sigmoidf(bfhi(ub.y));
;       });
	v_lshlrev_b32_e32 v0, 16, v130
	v_mul_f32_e32 v0, 0xbfb8aa3b, v0
	v_exp_f32_e32 v136, v0
	v_and_b32_e32 v0, 0xffff0000, v132
	v_mul_f32_e32 v0, 0xbfb8aa3b, v0
	v_exp_f32_e32 v0, v0
	s_nop 0
	v_add_f32_e32 v0, 1.0, v0
	v_rcp_f32_e32 v135, v0
	v_and_b32_e32 v0, 0xffff0000, v130
	v_mul_f32_e32 v0, 0xbfb8aa3b, v0
	v_exp_f32_e32 v137, v0
	v_lshlrev_b32_e32 v0, 16, v133
	v_mul_f32_e32 v0, 0xbfb8aa3b, v0
	v_exp_f32_e32 v0, v0
	v_pk_add_f32 v[136:137], v[136:137], 1.0 op_sel_hi:[1,0]
	v_add_f32_e32 v0, 1.0, v0
	v_rcp_f32_e32 v132, v0
	v_lshlrev_b32_e32 v0, 16, v131
	v_mul_f32_e32 v0, 0xbfb8aa3b, v0
	v_exp_f32_e32 v130, v0
	v_and_b32_e32 v0, 0xffff0000, v133
	v_mul_f32_e32 v0, 0xbfb8aa3b, v0
	v_exp_f32_e32 v0, v0
	v_pk_mul_f32 v[134:135], v[134:135], v[136:137]
	v_mov_b32_e32 v137, v1
	v_pk_mul_f32 v[18:19], v[18:19], v[134:135]
	v_add_f32_e32 v0, 1.0, v0
	v_rcp_f32_e32 v133, v0
	v_and_b32_e32 v0, 0xffff0000, v131
	v_mul_f32_e32 v0, 0xbfb8aa3b, v0
	v_exp_f32_e32 v131, v0
	v_lshlrev_b32_e32 v0, 3, v172
	v_and_b32_e32 v0, 56, v0
	v_mov_b32_e32 v135, v1
	v_pk_add_f32 v[130:131], v[130:131], 1.0 op_sel_hi:[1,0]
	s_nop 0
	v_pk_mul_f32 v[130:131], v[132:133], v[130:131]
	v_lshl_or_b32 v132, v173, 9, v0
	v_pk_mul_f32 v[20:21], v[20:21], v[130:131]
	v_mad_u64_u32 v[130:131], s[26:27], v173, s25, v[0:1]
	v_mov_b32_e32 v131, v1
	v_add_u32_e32 v144, 0x18000, v132
	v_add_u32_e32 v0, 0x54600, v130
	v_add_u32_e32 v142, 0x10000, v132
	v_lshlrev_b64 v[186:187], 1, v[130:131]
	v_lshlrev_b64 v[170:171], 1, v[144:145]
	v_add_u32_e32 v136, 0xa8c00, v130
	v_add_u32_e32 v138, 0xfd200, v130
	v_lshl_add_u64 v[130:131], s[2:3], 0, v[186:187]
	v_lshlrev_b64 v[184:185], 1, v[0:1]
	v_lshlrev_b64 v[168:169], 1, v[142:143]
	v_lshl_add_u64 v[142:143], s[6:7], 0, v[170:171]
	global_load_dwordx4 v[146:149], v[130:131], off offset:2736
	v_lshlrev_b64 v[182:183], 1, v[136:137]
	global_load_dwordx4 v[142:145], v[142:143], off offset:128
	v_lshl_add_u64 v[130:131], s[2:3], 0, v[184:185]
	v_add_u32_e32 v134, 0x8000, v132
	v_mov_b32_e32 v133, v1
	global_load_dwordx4 v[150:153], v[130:131], off offset:2736
	v_lshl_add_u64 v[130:131], s[2:3], 0, v[182:183]
	v_lshlrev_b64 v[180:181], 1, v[138:139]
	global_load_dwordx4 v[154:157], v[130:131], off offset:2736
	v_lshl_add_u64 v[130:131], s[2:3], 0, v[180:181]
	v_lshlrev_b64 v[164:165], 1, v[132:133]
	v_lshlrev_b64 v[166:167], 1, v[134:135]
	global_load_dwordx4 v[158:161], v[130:131], off offset:2736
	v_lshl_add_u64 v[130:131], s[6:7], 0, v[164:165]
	v_lshl_add_u64 v[134:135], s[6:7], 0, v[166:167]
	global_load_dwordx4 v[130:133], v[130:131], off offset:128
	v_bfe_u32 v0, v172, 4, 2
	global_load_dwordx4 v[138:141], v[134:135], off offset:128
	v_lshl_add_u64 v[134:135], s[6:7], 0, v[168:169]
	global_load_dwordx4 v[134:137], v[134:135], off offset:128
	v_bitop3_b32 v175, v175, v0, 7 bitop3:0x6c
	v_lshlrev_b32_e32 v192, 3, v175
	v_lshlrev_b32_e32 v175, 5, v172
	v_and_b32_e32 v175, 0xffffe000, v175
	v_lshlrev_b32_e32 v172, 6, v172
	v_and_or_b32 v188, v172, s1, v175
	v_readlane_b32 s1, v254, 20
	s_add_u32 s2, s1, s21
	v_readlane_b32 s1, v254, 21
	s_addc_u32 s3, s1, 0
	v_readlane_b32 s1, v254, 22
	v_bitop3_b32 v0, v0, v176, 4 bitop3:0x36
	s_add_u32 s0, s1, s0
	v_readlane_b32 s1, v254, 23
	v_and_b32_e32 v193, 0x33c0, v172
	v_lshlrev_b32_e32 v190, 3, v0
	v_lshlrev_b32_e32 v0, 7, v173
	s_addc_u32 s1, s1, 0
	v_add3_u32 v0, 0, v191, v0
	v_lshl_add_u64 v[172:173], s[2:3], 0, v[170:171]
	v_lshl_add_u64 v[174:175], s[2:3], 0, v[168:169]
	v_lshl_add_u64 v[176:177], s[2:3], 0, v[166:167]
	v_lshl_add_u64 v[178:179], s[2:3], 0, v[164:165]
	v_lshl_add_u64 v[180:181], s[0:1], 0, v[180:181]
	v_lshl_add_u64 v[182:183], s[0:1], 0, v[182:183]
	v_lshl_add_u64 v[184:185], s[0:1], 0, v[184:185]
	v_lshl_add_u64 v[186:187], s[0:1], 0, v[186:187]
	s_mov_b64 s[0:1], 0
	s_mov_b32 s2, 0
	v_lshlrev_b32_e32 v189, 1, v188
	v_lshlrev_b32_e32 v188, 1, v193
.LBB0_780:
	s_add_i32 s3, s2, 0x8000
	s_and_b32 s6, s3, 0x8000
	v_lshl_add_u32 v193, s6, 1, v0
	s_waitcnt lgkmcnt(0)
	s_barrier
	s_cmp_eq_u32 s100, 0
	s_cbranch_scc1 .Lstg_780_a
	v_mfma_f32_16x16x32_bf16 v[2:5], v[234:237], v[198:201], v[2:5]
	v_mfma_f32_16x16x32_bf16 v[6:9], v[238:241], v[198:201], v[6:9]
	v_mfma_f32_16x16x32_bf16 v[10:13], v[242:245], v[198:201], v[10:13]
	v_mfma_f32_16x16x32_bf16 v[14:17], v[246:249], v[198:201], v[14:17]
	v_mfma_f32_16x16x32_bf16 v[22:25], v[234:237], v[206:209], v[22:25]
	v_mfma_f32_16x16x32_bf16 v[30:33], v[238:241], v[206:209], v[30:33]
	v_mfma_f32_16x16x32_bf16 v[38:41], v[242:245], v[206:209], v[38:41]
	v_mfma_f32_16x16x32_bf16 v[46:49], v[246:249], v[206:209], v[46:49]
	v_mfma_f32_16x16x32_bf16 v[54:57], v[234:237], v[210:213], v[54:57]
	v_mfma_f32_16x16x32_bf16 v[62:65], v[238:241], v[210:213], v[62:65]
	v_mfma_f32_16x16x32_bf16 v[70:73], v[242:245], v[210:213], v[70:73]
	v_mfma_f32_16x16x32_bf16 v[78:81], v[246:249], v[210:213], v[78:81]
	v_mfma_f32_16x16x32_bf16 v[86:89], v[234:237], v[214:217], v[86:89]
	v_mfma_f32_16x16x32_bf16 v[94:97], v[238:241], v[214:217], v[94:97]
	v_mfma_f32_16x16x32_bf16 v[102:105], v[242:245], v[214:217], v[102:105]
	v_mfma_f32_16x16x32_bf16 v[110:113], v[246:249], v[214:217], v[110:113]
	v_mfma_f32_16x16x32_bf16 v[118:121], v[234:237], v[218:221], v[118:121]
	v_mfma_f32_16x16x32_bf16 v[126:129], v[238:241], v[218:221], v[126:129]
	v_mfma_f32_16x16x32_bf16 v[122:125], v[242:245], v[218:221], v[122:125]
	v_mfma_f32_16x16x32_bf16 v[114:117], v[246:249], v[218:221], v[114:117]
	v_mfma_f32_16x16x32_bf16 v[106:109], v[234:237], v[222:225], v[106:109]
	v_mfma_f32_16x16x32_bf16 v[98:101], v[238:241], v[222:225], v[98:101]
	v_mfma_f32_16x16x32_bf16 v[90:93], v[242:245], v[222:225], v[90:93]
	v_mfma_f32_16x16x32_bf16 v[82:85], v[246:249], v[222:225], v[82:85]
	v_mfma_f32_16x16x32_bf16 v[74:77], v[234:237], v[226:229], v[74:77]
	v_mfma_f32_16x16x32_bf16 v[66:69], v[238:241], v[226:229], v[66:69]
	v_mfma_f32_16x16x32_bf16 v[58:61], v[242:245], v[226:229], v[58:61]
	v_mfma_f32_16x16x32_bf16 v[50:53], v[246:249], v[226:229], v[50:53]
	v_mfma_f32_16x16x32_bf16 v[42:45], v[234:237], v[230:233], v[42:45]
	v_mfma_f32_16x16x32_bf16 v[34:37], v[238:241], v[230:233], v[34:37]
	v_mfma_f32_16x16x32_bf16 v[26:29], v[242:245], v[230:233], v[26:29]
	v_mfma_f32_16x16x32_bf16 v[18:21], v[246:249], v[230:233], v[18:21]
; DI void gemm8_accum(f32x4 (&acc)[8][4], const bf16_t* a, size_t lda, const bf16_t* b, size_t ldb, int nkb, bf16_t* L,
;                     const bool pre, const bf16_t* an, size_t ldan, const bf16_t* bn, size_t ldbn) {
;     ...
;   for (int kb = 0; kb + 2 < nkb; ++kb) {
;     __syncthreads();
;     g8_store1(L + ((kb + 1) & 1) * 32768, ra, lrow, lch);
;     g8_load1o(ra, a + (kb + 2) * 64, offa);
;     __builtin_amdgcn_sched_barrier(0);
;     g8_compute<0, 1>(acc, L + (kb & 1) * 32768, wm, wn, lane);
;     __builtin_amdgcn_sched_barrier(0);
;     g8_store1(L + ((kb + 1) & 1) * 32768 + 16384, rb, lrow, lch);
;     g8_load1o(rb, b + (kb + 2) * 64, offb);
;     __builtin_amdgcn_sched_barrier(0);
;     g8_compute<1, 2>(acc, L + (kb & 1) * 32768, wm, wn, lane);
;   }
.Lstg_780_a:
	s_waitcnt vmcnt(7)
	ds_write_b128 v193, v[146:149]
	s_waitcnt vmcnt(5)
	ds_write_b128 v193, v[150:153] offset:8192
	s_waitcnt vmcnt(4)
	ds_write_b128 v193, v[154:157] offset:16384
	s_waitcnt vmcnt(3)
	ds_write_b128 v193, v[158:161] offset:24576
	v_lshl_add_u64 v[146:147], v[186:187], 0, s[0:1]
	v_lshl_add_u64 v[150:151], v[184:185], 0, s[0:1]
	v_lshl_add_u64 v[154:155], v[182:183], 0, s[0:1]
	v_lshl_add_u64 v[158:159], v[180:181], 0, s[0:1]
	global_load_dwordx4 v[146:149], v[146:147], off
	s_nop 0
	global_load_dwordx4 v[150:153], v[150:151], off
	s_nop 0
	global_load_dwordx4 v[154:157], v[154:155], off
	s_nop 0
	global_load_dwordx4 v[158:161], v[158:159], off
	s_and_b32 s2, s2, 0x8000
	s_lshl_b32 s2, s2, 1
	s_add_i32 s2, s2, 0
	v_lshl_add_u32 v194, v192, 1, s2
	v_add_u32_e32 v195, v194, v189
	ds_read_b128 v[198:201], v195
	ds_read_b128 v[206:209], v195 offset:2048
	ds_read_b128 v[210:213], v195 offset:4096
	ds_read_b128 v[214:217], v195 offset:6144
	ds_read_b128 v[218:221], v195 offset:8192
	ds_read_b128 v[222:225], v195 offset:10240
	ds_read_b128 v[226:229], v195 offset:12288
	ds_read_b128 v[230:233], v195 offset:14336
	v_add_u32_e32 v194, v194, v188
	ds_read_b128 v[234:237], v194 offset:32768
	ds_read_b128 v[238:241], v194 offset:34816
	ds_read_b128 v[242:245], v194 offset:36864
	ds_read_b128 v[246:249], v194 offset:38912
	s_waitcnt lgkmcnt(3)
	v_mfma_f32_16x16x32_bf16 v[2:5], v[234:237], v[198:201], v[2:5]
	s_waitcnt lgkmcnt(2)
	v_mfma_f32_16x16x32_bf16 v[6:9], v[238:241], v[198:201], v[6:9]
	s_waitcnt lgkmcnt(1)
	v_mfma_f32_16x16x32_bf16 v[10:13], v[242:245], v[198:201], v[10:13]
	s_waitcnt lgkmcnt(0)
	v_mfma_f32_16x16x32_bf16 v[14:17], v[246:249], v[198:201], v[14:17]
	v_mfma_f32_16x16x32_bf16 v[22:25], v[234:237], v[206:209], v[22:25]
	v_mfma_f32_16x16x32_bf16 v[30:33], v[238:241], v[206:209], v[30:33]
	v_mfma_f32_16x16x32_bf16 v[38:41], v[242:245], v[206:209], v[38:41]
	v_mfma_f32_16x16x32_bf16 v[46:49], v[246:249], v[206:209], v[46:49]
	v_mfma_f32_16x16x32_bf16 v[54:57], v[234:237], v[210:213], v[54:57]
	v_mfma_f32_16x16x32_bf16 v[62:65], v[238:241], v[210:213], v[62:65]
	v_mfma_f32_16x16x32_bf16 v[70:73], v[242:245], v[210:213], v[70:73]
	v_mfma_f32_16x16x32_bf16 v[78:81], v[246:249], v[210:213], v[78:81]
	v_mfma_f32_16x16x32_bf16 v[86:89], v[234:237], v[214:217], v[86:89]
	v_mfma_f32_16x16x32_bf16 v[94:97], v[238:241], v[214:217], v[94:97]
	v_mfma_f32_16x16x32_bf16 v[102:105], v[242:245], v[214:217], v[102:105]
	v_mfma_f32_16x16x32_bf16 v[110:113], v[246:249], v[214:217], v[110:113]
	v_mfma_f32_16x16x32_bf16 v[118:121], v[234:237], v[218:221], v[118:121]
	v_mfma_f32_16x16x32_bf16 v[126:129], v[238:241], v[218:221], v[126:129]
	v_mfma_f32_16x16x32_bf16 v[122:125], v[242:245], v[218:221], v[122:125]
	v_mfma_f32_16x16x32_bf16 v[114:117], v[246:249], v[218:221], v[114:117]
	v_mfma_f32_16x16x32_bf16 v[106:109], v[234:237], v[222:225], v[106:109]
	v_mfma_f32_16x16x32_bf16 v[98:101], v[238:241], v[222:225], v[98:101]
	v_mfma_f32_16x16x32_bf16 v[90:93], v[242:245], v[222:225], v[90:93]
	v_mfma_f32_16x16x32_bf16 v[82:85], v[246:249], v[222:225], v[82:85]
	v_mfma_f32_16x16x32_bf16 v[74:77], v[234:237], v[226:229], v[74:77]
	v_mfma_f32_16x16x32_bf16 v[66:69], v[238:241], v[226:229], v[66:69]
	v_mfma_f32_16x16x32_bf16 v[58:61], v[242:245], v[226:229], v[58:61]
	v_mfma_f32_16x16x32_bf16 v[50:53], v[246:249], v[226:229], v[50:53]
	v_mfma_f32_16x16x32_bf16 v[42:45], v[234:237], v[230:233], v[42:45]
	v_mfma_f32_16x16x32_bf16 v[34:37], v[238:241], v[230:233], v[34:37]
	v_mfma_f32_16x16x32_bf16 v[26:29], v[242:245], v[230:233], v[26:29]
	v_mfma_f32_16x16x32_bf16 v[18:21], v[246:249], v[230:233], v[18:21]
	s_waitcnt vmcnt(6)
	ds_write_b128 v193, v[130:133] offset:32768
	s_waitcnt vmcnt(5)
	ds_write_b128 v193, v[138:141] offset:40960
	s_waitcnt vmcnt(4)
	ds_write_b128 v193, v[134:137] offset:49152
	ds_write_b128 v193, v[142:145] offset:57344
	v_lshl_add_u64 v[130:131], v[178:179], 0, s[0:1]
	v_lshl_add_u64 v[134:135], v[176:177], 0, s[0:1]
	global_load_dwordx4 v[130:133], v[130:131], off
	s_nop 0
	global_load_dwordx4 v[138:141], v[134:135], off
	v_lshl_add_u64 v[134:135], v[174:175], 0, s[0:1]
	v_lshl_add_u64 v[142:143], v[172:173], 0, s[0:1]
	global_load_dwordx4 v[134:137], v[134:135], off
	s_nop 0
	global_load_dwordx4 v[142:145], v[142:143], off
	v_lshl_add_u32 v193, v190, 1, s2
	v_add_u32_e32 v194, v193, v189
	ds_read_b128 v[198:201], v194
	ds_read_b128 v[206:209], v194 offset:2048
	ds_read_b128 v[210:213], v194 offset:4096
	ds_read_b128 v[214:217], v194 offset:6144
	ds_read_b128 v[218:221], v194 offset:8192
	ds_read_b128 v[222:225], v194 offset:10240
	ds_read_b128 v[226:229], v194 offset:12288
	ds_read_b128 v[230:233], v194 offset:14336
	v_add_u32_e32 v193, v193, v188
	ds_read_b128 v[234:237], v193 offset:32768
	ds_read_b128 v[238:241], v193 offset:34816
	ds_read_b128 v[242:245], v193 offset:36864
	ds_read_b128 v[246:249], v193 offset:38912
	s_cmp_lg_u32 s101, 0
	s_cbranch_scc1 .Lstg_780_b
; DI void gemm8_accum(f32x4 (&acc)[8][4], const bf16_t* a, size_t lda, const bf16_t* b, size_t ldb, int nkb, bf16_t* L,
;                     const bool pre, const bf16_t* an, size_t ldan, const bf16_t* bn, size_t ldbn) {
;     ...
;     g8_compute<0, 1>(acc, L + (kb & 1) * 32768, wm, wn, lane);
;     __builtin_amdgcn_sched_barrier(0);
;     g8_store1(L + ((kb + 1) & 1) * 32768 + 16384, rb, lrow, lch);
;     g8_load1o(rb, b + (kb + 2) * 64, offb);
;     __builtin_amdgcn_sched_barrier(0);
;     g8_compute<1, 2>(acc, L + (kb & 1) * 32768, wm, wn, lane);
;   }
;   __syncthreads();
	s_waitcnt lgkmcnt(3)
	v_mfma_f32_16x16x32_bf16 v[2:5], v[234:237], v[198:201], v[2:5]
	s_waitcnt lgkmcnt(2)
	v_mfma_f32_16x16x32_bf16 v[6:9], v[238:241], v[198:201], v[6:9]
	s_waitcnt lgkmcnt(1)
	v_mfma_f32_16x16x32_bf16 v[10:13], v[242:245], v[198:201], v[10:13]
	s_waitcnt lgkmcnt(0)
	v_mfma_f32_16x16x32_bf16 v[14:17], v[246:249], v[198:201], v[14:17]
	v_mfma_f32_16x16x32_bf16 v[22:25], v[234:237], v[206:209], v[22:25]
	v_mfma_f32_16x16x32_bf16 v[30:33], v[238:241], v[206:209], v[30:33]
	v_mfma_f32_16x16x32_bf16 v[38:41], v[242:245], v[206:209], v[38:41]
	v_mfma_f32_16x16x32_bf16 v[46:49], v[246:249], v[206:209], v[46:49]
	v_mfma_f32_16x16x32_bf16 v[54:57], v[234:237], v[210:213], v[54:57]
	v_mfma_f32_16x16x32_bf16 v[62:65], v[238:241], v[210:213], v[62:65]
	v_mfma_f32_16x16x32_bf16 v[70:73], v[242:245], v[210:213], v[70:73]
	v_mfma_f32_16x16x32_bf16 v[78:81], v[246:249], v[210:213], v[78:81]
	v_mfma_f32_16x16x32_bf16 v[86:89], v[234:237], v[214:217], v[86:89]
	v_mfma_f32_16x16x32_bf16 v[94:97], v[238:241], v[214:217], v[94:97]
	v_mfma_f32_16x16x32_bf16 v[102:105], v[242:245], v[214:217], v[102:105]
	v_mfma_f32_16x16x32_bf16 v[110:113], v[246:249], v[214:217], v[110:113]
	v_mfma_f32_16x16x32_bf16 v[118:121], v[234:237], v[218:221], v[118:121]
	v_mfma_f32_16x16x32_bf16 v[126:129], v[238:241], v[218:221], v[126:129]
	v_mfma_f32_16x16x32_bf16 v[122:125], v[242:245], v[218:221], v[122:125]
	v_mfma_f32_16x16x32_bf16 v[114:117], v[246:249], v[218:221], v[114:117]
	v_mfma_f32_16x16x32_bf16 v[106:109], v[234:237], v[222:225], v[106:109]
	v_mfma_f32_16x16x32_bf16 v[98:101], v[238:241], v[222:225], v[98:101]
	v_mfma_f32_16x16x32_bf16 v[90:93], v[242:245], v[222:225], v[90:93]
	v_mfma_f32_16x16x32_bf16 v[82:85], v[246:249], v[222:225], v[82:85]
	v_mfma_f32_16x16x32_bf16 v[74:77], v[234:237], v[226:229], v[74:77]
	v_mfma_f32_16x16x32_bf16 v[66:69], v[238:241], v[226:229], v[66:69]
	v_mfma_f32_16x16x32_bf16 v[58:61], v[242:245], v[226:229], v[58:61]
	v_mfma_f32_16x16x32_bf16 v[50:53], v[246:249], v[226:229], v[50:53]
	v_mfma_f32_16x16x32_bf16 v[42:45], v[234:237], v[230:233], v[42:45]
	v_mfma_f32_16x16x32_bf16 v[34:37], v[238:241], v[230:233], v[34:37]
	v_mfma_f32_16x16x32_bf16 v[26:29], v[242:245], v[230:233], v[26:29]
	v_mfma_f32_16x16x32_bf16 v[18:21], v[246:249], v[230:233], v[18:21]
.Lstg_780_b:
	s_mov_b32 s100, s101
	s_add_u32 s0, s0, 0x80
	s_addc_u32 s1, s1, 0
	s_cmpk_lg_i32 s0, 0x300
	s_mov_b32 s2, s3
	s_cbranch_scc1 .LBB0_780
	s_cmp_eq_u32 s100, 0
	s_cbranch_scc1 .Lstg_780_c
	s_waitcnt lgkmcnt(0)
	v_mfma_f32_16x16x32_bf16 v[2:5], v[234:237], v[198:201], v[2:5]
	v_mfma_f32_16x16x32_bf16 v[6:9], v[238:241], v[198:201], v[6:9]
	v_mfma_f32_16x16x32_bf16 v[10:13], v[242:245], v[198:201], v[10:13]
	v_mfma_f32_16x16x32_bf16 v[14:17], v[246:249], v[198:201], v[14:17]
	v_mfma_f32_16x16x32_bf16 v[22:25], v[234:237], v[206:209], v[22:25]
	v_mfma_f32_16x16x32_bf16 v[30:33], v[238:241], v[206:209], v[30:33]
	v_mfma_f32_16x16x32_bf16 v[38:41], v[242:245], v[206:209], v[38:41]
	v_mfma_f32_16x16x32_bf16 v[46:49], v[246:249], v[206:209], v[46:49]
	v_mfma_f32_16x16x32_bf16 v[54:57], v[234:237], v[210:213], v[54:57]
	v_mfma_f32_16x16x32_bf16 v[62:65], v[238:241], v[210:213], v[62:65]
	v_mfma_f32_16x16x32_bf16 v[70:73], v[242:245], v[210:213], v[70:73]
	v_mfma_f32_16x16x32_bf16 v[78:81], v[246:249], v[210:213], v[78:81]
	v_mfma_f32_16x16x32_bf16 v[86:89], v[234:237], v[214:217], v[86:89]
	v_mfma_f32_16x16x32_bf16 v[94:97], v[238:241], v[214:217], v[94:97]
	v_mfma_f32_16x16x32_bf16 v[102:105], v[242:245], v[214:217], v[102:105]
	v_mfma_f32_16x16x32_bf16 v[110:113], v[246:249], v[214:217], v[110:113]
	v_mfma_f32_16x16x32_bf16 v[118:121], v[234:237], v[218:221], v[118:121]
	v_mfma_f32_16x16x32_bf16 v[126:129], v[238:241], v[218:221], v[126:129]
	v_mfma_f32_16x16x32_bf16 v[122:125], v[242:245], v[218:221], v[122:125]
	v_mfma_f32_16x16x32_bf16 v[114:117], v[246:249], v[218:221], v[114:117]
	v_mfma_f32_16x16x32_bf16 v[106:109], v[234:237], v[222:225], v[106:109]
	v_mfma_f32_16x16x32_bf16 v[98:101], v[238:241], v[222:225], v[98:101]
	v_mfma_f32_16x16x32_bf16 v[90:93], v[242:245], v[222:225], v[90:93]
	v_mfma_f32_16x16x32_bf16 v[82:85], v[246:249], v[222:225], v[82:85]
	v_mfma_f32_16x16x32_bf16 v[74:77], v[234:237], v[226:229], v[74:77]
	v_mfma_f32_16x16x32_bf16 v[66:69], v[238:241], v[226:229], v[66:69]
	v_mfma_f32_16x16x32_bf16 v[58:61], v[242:245], v[226:229], v[58:61]
	v_mfma_f32_16x16x32_bf16 v[50:53], v[246:249], v[226:229], v[50:53]
	v_mfma_f32_16x16x32_bf16 v[42:45], v[234:237], v[230:233], v[42:45]
	v_mfma_f32_16x16x32_bf16 v[34:37], v[238:241], v[230:233], v[34:37]
	v_mfma_f32_16x16x32_bf16 v[26:29], v[242:245], v[230:233], v[26:29]
	v_mfma_f32_16x16x32_bf16 v[18:21], v[246:249], v[230:233], v[18:21]
	s_mov_b32 s100, 0
; DI void gemm8_accum(f32x4 (&acc)[8][4], const bf16_t* a, size_t lda, const bf16_t* b, size_t ldb, int nkb, bf16_t* L,
;                     const bool pre, const bf16_t* an, size_t ldan, const bf16_t* bn, size_t ldbn) {
;     ...
;   __syncthreads();
;   g8_store1(L + 32768, ra, lrow, lch);
;   g8_load1(ra, an, ldan, 0, lrow, lch);
;   __builtin_amdgcn_sched_barrier(0);
;   g8_compute<0, 1>(acc, L, wm, wn, lane);
;   __builtin_amdgcn_sched_barrier(0);
;   g8_store1(L + 32768 + 16384, rb, lrow, lch);
;   g8_load1(rb, bn, ldbn, 0, lrow, lch);
;   __builtin_amdgcn_sched_barrier(0);
;   g8_compute<1, 2>(acc, L, wm, wn, lane);
.Lstg_780_c:
	v_readlane_b32 s0, v254, 18
	s_add_i32 s21, s24, s0
	s_cmp_gt_u32 s21, 63
	s_cselect_b64 s[2:3], -1, 0
	s_cmp_lt_u32 s21, 64
	s_cselect_b32 s6, s21, s24
	s_lshl_b32 s0, s6, 1
	s_and_b32 s0, s0, 0x7fffffe0
	s_and_b32 s1, s6, 3
	s_or_b32 s0, s1, s0
	v_readlane_b32 s1, v252, 25
	s_or_b32 s28, s0, s1
	s_lshl_b32 s6, s6, 16
	s_lshl_b64 s[0:1], s[28:29], 18
	s_and_b32 s24, s6, 0xc0000
	v_readlane_b32 s6, v252, 39
	s_add_u32 s6, s6, s0
	v_readlane_b32 s0, v252, 40
	v_lshlrev_b32_e32 v163, 1, v163
	s_addc_u32 s7, s0, s1
	v_add3_u32 v172, s20, v191, v163
	s_barrier
	s_waitcnt vmcnt(7)
	ds_write_b128 v172, v[146:149]
	s_waitcnt vmcnt(6)
	ds_write_b128 v172, v[150:153] offset:8192
	s_waitcnt vmcnt(5)
	ds_write_b128 v172, v[154:157] offset:16384
	s_waitcnt vmcnt(4)
	ds_write_b128 v172, v[158:161] offset:24576
	v_lshl_add_u64 v[146:147], s[6:7], 0, v[164:165]
	v_lshl_add_u64 v[150:151], s[6:7], 0, v[166:167]
	v_lshl_add_u64 v[154:155], s[6:7], 0, v[168:169]
	v_lshl_add_u64 v[158:159], s[6:7], 0, v[170:171]
	global_load_dwordx4 v[146:149], v[146:147], off
	v_readlane_b32 s0, v252, 3
	global_load_dwordx4 v[150:153], v[150:151], off
	v_readlane_b32 s1, v252, 4
	global_load_dwordx4 v[154:157], v[154:155], off
	s_add_u32 s0, s0, s24
	global_load_dwordx4 v[158:161], v[158:159], off
	s_addc_u32 s1, s1, 0
	v_lshlrev_b32_e32 v202, 1, v192
	v_add_u32_e32 v203, 0, v202
	v_add_u32_e32 v204, v203, v189
	ds_read_b128 v[172:175], v204
	ds_read_b128 v[176:179], v204 offset:2048
	ds_read_b128 v[180:183], v204 offset:4096
	ds_read_b128 v[184:187], v204 offset:6144
	ds_read_b128 v[192:195], v204 offset:8192
	ds_read_b128 v[198:201], v204 offset:10240
	ds_read_b128 v[206:209], v204 offset:12288
	ds_read_b128 v[210:213], v204 offset:14336
	v_add_u32_e32 v203, v203, v188
	ds_read_b128 v[214:217], v203 offset:32768
	ds_read_b128 v[218:221], v203 offset:34816
	ds_read_b128 v[222:225], v203 offset:36864
	ds_read_b128 v[226:229], v203 offset:38912
	s_waitcnt lgkmcnt(3)
	v_mfma_f32_16x16x32_bf16 v[2:5], v[214:217], v[172:175], v[2:5]
	s_waitcnt lgkmcnt(2)
	v_mfma_f32_16x16x32_bf16 v[6:9], v[218:221], v[172:175], v[6:9]
	s_waitcnt lgkmcnt(1)
	v_mfma_f32_16x16x32_bf16 v[10:13], v[222:225], v[172:175], v[10:13]
	s_waitcnt lgkmcnt(0)
	v_mfma_f32_16x16x32_bf16 v[14:17], v[226:229], v[172:175], v[14:17]
	v_mfma_f32_16x16x32_bf16 v[22:25], v[214:217], v[176:179], v[22:25]
	v_mfma_f32_16x16x32_bf16 v[30:33], v[218:221], v[176:179], v[30:33]
	v_mfma_f32_16x16x32_bf16 v[38:41], v[222:225], v[176:179], v[38:41]
	v_mfma_f32_16x16x32_bf16 v[46:49], v[226:229], v[176:179], v[46:49]
	v_mfma_f32_16x16x32_bf16 v[54:57], v[214:217], v[180:183], v[54:57]
	v_mfma_f32_16x16x32_bf16 v[62:65], v[218:221], v[180:183], v[62:65]
	v_mfma_f32_16x16x32_bf16 v[70:73], v[222:225], v[180:183], v[70:73]
	v_mfma_f32_16x16x32_bf16 v[78:81], v[226:229], v[180:183], v[78:81]
	v_mfma_f32_16x16x32_bf16 v[86:89], v[214:217], v[184:187], v[86:89]
	v_mfma_f32_16x16x32_bf16 v[94:97], v[218:221], v[184:187], v[94:97]
	v_mfma_f32_16x16x32_bf16 v[102:105], v[222:225], v[184:187], v[102:105]
	v_mfma_f32_16x16x32_bf16 v[110:113], v[226:229], v[184:187], v[110:113]
	v_mfma_f32_16x16x32_bf16 v[118:121], v[214:217], v[192:195], v[118:121]
	v_mfma_f32_16x16x32_bf16 v[126:129], v[218:221], v[192:195], v[126:129]
	v_mfma_f32_16x16x32_bf16 v[122:125], v[222:225], v[192:195], v[122:125]
	v_mfma_f32_16x16x32_bf16 v[114:117], v[226:229], v[192:195], v[114:117]
	v_mfma_f32_16x16x32_bf16 v[106:109], v[214:217], v[198:201], v[106:109]
	v_mfma_f32_16x16x32_bf16 v[98:101], v[218:221], v[198:201], v[98:101]
	v_mfma_f32_16x16x32_bf16 v[90:93], v[222:225], v[198:201], v[90:93]
	v_mfma_f32_16x16x32_bf16 v[82:85], v[226:229], v[198:201], v[82:85]
	v_mfma_f32_16x16x32_bf16 v[74:77], v[214:217], v[206:209], v[74:77]
	v_mfma_f32_16x16x32_bf16 v[66:69], v[218:221], v[206:209], v[66:69]
	v_mfma_f32_16x16x32_bf16 v[58:61], v[222:225], v[206:209], v[58:61]
	v_mfma_f32_16x16x32_bf16 v[50:53], v[226:229], v[206:209], v[50:53]
	v_mfma_f32_16x16x32_bf16 v[42:45], v[214:217], v[210:213], v[42:45]
	v_mfma_f32_16x16x32_bf16 v[34:37], v[218:221], v[210:213], v[34:37]
	v_mfma_f32_16x16x32_bf16 v[26:29], v[222:225], v[210:213], v[26:29]
	v_mfma_f32_16x16x32_bf16 v[18:21], v[226:229], v[210:213], v[18:21]
	v_readlane_b32 s6, v254, 36
	s_nop 1
	v_add3_u32 v163, s6, v191, v163
	s_waitcnt vmcnt(7)
	ds_write_b128 v163, v[130:133]
	s_waitcnt vmcnt(6)
	ds_write_b128 v163, v[138:141] offset:8192
	s_waitcnt vmcnt(5)
	ds_write_b128 v163, v[134:137] offset:16384
	s_waitcnt vmcnt(4)
	ds_write_b128 v163, v[142:145] offset:24576
	v_lshl_add_u64 v[130:131], s[0:1], 0, v[164:165]
	v_lshl_add_u64 v[138:139], s[0:1], 0, v[168:169]
	global_load_dwordx4 v[130:133], v[130:131], off
	v_lshl_add_u64 v[134:135], s[0:1], 0, v[166:167]
	global_load_dwordx4 v[138:141], v[138:139], off
	v_lshl_add_u64 v[142:143], s[0:1], 0, v[170:171]
	global_load_dwordx4 v[134:137], v[134:135], off
	s_nop 0
	global_load_dwordx4 v[142:145], v[142:143], off
	v_lshlrev_b32_e32 v163, 1, v190
	v_add_u32_e32 v194, 0, v163
	v_add_u32_e32 v195, v194, v189
	ds_read_b128 v[164:167], v195
	ds_read_b128 v[168:171], v195 offset:2048
	ds_read_b128 v[172:175], v195 offset:4096
	ds_read_b128 v[176:179], v195 offset:6144
	ds_read_b128 v[180:183], v195 offset:8192
	ds_read_b128 v[184:187], v195 offset:10240
	ds_read_b128 v[190:193], v195 offset:12288
	ds_read_b128 v[198:201], v195 offset:14336
	v_add_u32_e32 v194, v194, v188
	ds_read_b128 v[206:209], v194 offset:32768
	ds_read_b128 v[210:213], v194 offset:34816
	ds_read_b128 v[214:217], v194 offset:36864
	ds_read_b128 v[218:221], v194 offset:38912
	s_waitcnt lgkmcnt(3)
; DI void gemm8_accum(f32x4 (&acc)[8][4], const bf16_t* a, size_t lda, const bf16_t* b, size_t ldb, int nkb, bf16_t* L,
;                     const bool pre, const bf16_t* an, size_t ldan, const bf16_t* bn, size_t ldbn) {
;     ...
;   g8_compute<1, 2>(acc, L, wm, wn, lane);
;   __syncthreads();
;   g8_store1(L, ra, lrow, lch);
;   __builtin_amdgcn_sched_barrier(0);
;   g8_compute<0, 1>(acc, L + 32768, wm, wn, lane);
;   __builtin_amdgcn_sched_barrier(0);
;   g8_store1(L + 16384, rb, lrow, lch);
;   __builtin_amdgcn_sched_barrier(0);
;   g8_compute<1, 2>(acc, L + 32768, wm, wn, lane);
;   __syncthreads();
; }
	v_mfma_f32_16x16x32_bf16 v[2:5], v[206:209], v[164:167], v[2:5]
	s_waitcnt lgkmcnt(2)
	v_mfma_f32_16x16x32_bf16 v[6:9], v[210:213], v[164:167], v[6:9]
	s_waitcnt lgkmcnt(1)
	v_mfma_f32_16x16x32_bf16 v[10:13], v[214:217], v[164:167], v[10:13]
	s_waitcnt lgkmcnt(0)
	v_mfma_f32_16x16x32_bf16 v[14:17], v[218:221], v[164:167], v[14:17]
	v_mfma_f32_16x16x32_bf16 v[22:25], v[206:209], v[168:171], v[22:25]
	v_mfma_f32_16x16x32_bf16 v[30:33], v[210:213], v[168:171], v[30:33]
	v_mfma_f32_16x16x32_bf16 v[38:41], v[214:217], v[168:171], v[38:41]
	v_mfma_f32_16x16x32_bf16 v[46:49], v[218:221], v[168:171], v[46:49]
	v_mfma_f32_16x16x32_bf16 v[54:57], v[206:209], v[172:175], v[54:57]
	v_mfma_f32_16x16x32_bf16 v[62:65], v[210:213], v[172:175], v[62:65]
	v_mfma_f32_16x16x32_bf16 v[70:73], v[214:217], v[172:175], v[70:73]
	v_mfma_f32_16x16x32_bf16 v[78:81], v[218:221], v[172:175], v[78:81]
	v_mfma_f32_16x16x32_bf16 v[86:89], v[206:209], v[176:179], v[86:89]
	v_mfma_f32_16x16x32_bf16 v[94:97], v[210:213], v[176:179], v[94:97]
	v_mfma_f32_16x16x32_bf16 v[102:105], v[214:217], v[176:179], v[102:105]
	v_mfma_f32_16x16x32_bf16 v[110:113], v[218:221], v[176:179], v[110:113]
	v_mfma_f32_16x16x32_bf16 v[118:121], v[206:209], v[180:183], v[118:121]
	v_mfma_f32_16x16x32_bf16 v[126:129], v[210:213], v[180:183], v[126:129]
	v_mfma_f32_16x16x32_bf16 v[122:125], v[214:217], v[180:183], v[122:125]
	v_mfma_f32_16x16x32_bf16 v[114:117], v[218:221], v[180:183], v[114:117]
	v_mfma_f32_16x16x32_bf16 v[106:109], v[206:209], v[184:187], v[106:109]
	v_mfma_f32_16x16x32_bf16 v[98:101], v[210:213], v[184:187], v[98:101]
	v_mfma_f32_16x16x32_bf16 v[90:93], v[214:217], v[184:187], v[90:93]
	v_mfma_f32_16x16x32_bf16 v[82:85], v[218:221], v[184:187], v[82:85]
	v_mfma_f32_16x16x32_bf16 v[74:77], v[206:209], v[190:193], v[74:77]
	v_mfma_f32_16x16x32_bf16 v[66:69], v[210:213], v[190:193], v[66:69]
	v_mfma_f32_16x16x32_bf16 v[58:61], v[214:217], v[190:193], v[58:61]
	v_mfma_f32_16x16x32_bf16 v[50:53], v[218:221], v[190:193], v[50:53]
	v_mfma_f32_16x16x32_bf16 v[42:45], v[206:209], v[198:201], v[42:45]
	v_mfma_f32_16x16x32_bf16 v[34:37], v[210:213], v[198:201], v[34:37]
	v_mfma_f32_16x16x32_bf16 v[26:29], v[214:217], v[198:201], v[26:29]
	v_mfma_f32_16x16x32_bf16 v[18:21], v[218:221], v[198:201], v[18:21]
	s_barrier
	s_waitcnt vmcnt(7)
	ds_write_b128 v0, v[146:149]
	s_waitcnt vmcnt(6)
	ds_write_b128 v0, v[150:153] offset:8192
	s_waitcnt vmcnt(5)
	ds_write_b128 v0, v[154:157] offset:16384
	s_waitcnt vmcnt(4)
	ds_write_b128 v0, v[158:161] offset:24576
	v_add3_u32 v176, s20, v202, v189
	ds_read_b128 v[146:149], v176
	ds_read_b128 v[150:153], v176 offset:2048
	ds_read_b128 v[154:157], v176 offset:4096
	ds_read_b128 v[158:161], v176 offset:6144
	ds_read_b128 v[164:167], v176 offset:8192
	ds_read_b128 v[168:171], v176 offset:10240
	ds_read_b128 v[172:175], v176 offset:12288
	ds_read_b128 v[176:179], v176 offset:14336
	v_add3_u32 v194, s6, v202, v188
	ds_read_b128 v[180:183], v194
	ds_read_b128 v[184:187], v194 offset:2048
	ds_read_b128 v[190:193], v194 offset:4096
	ds_read_b128 v[198:201], v194 offset:6144
	s_waitcnt lgkmcnt(3)
	v_mfma_f32_16x16x32_bf16 v[2:5], v[180:183], v[146:149], v[2:5]
	s_waitcnt lgkmcnt(2)
	v_mfma_f32_16x16x32_bf16 v[6:9], v[184:187], v[146:149], v[6:9]
	s_waitcnt lgkmcnt(1)
	v_mfma_f32_16x16x32_bf16 v[10:13], v[190:193], v[146:149], v[10:13]
	s_waitcnt lgkmcnt(0)
	v_mfma_f32_16x16x32_bf16 v[14:17], v[198:201], v[146:149], v[14:17]
	v_mfma_f32_16x16x32_bf16 v[22:25], v[180:183], v[150:153], v[22:25]
	v_mfma_f32_16x16x32_bf16 v[30:33], v[184:187], v[150:153], v[30:33]
	v_mfma_f32_16x16x32_bf16 v[38:41], v[190:193], v[150:153], v[38:41]
	v_mfma_f32_16x16x32_bf16 v[46:49], v[198:201], v[150:153], v[46:49]
	v_mfma_f32_16x16x32_bf16 v[54:57], v[180:183], v[154:157], v[54:57]
	v_mfma_f32_16x16x32_bf16 v[62:65], v[184:187], v[154:157], v[62:65]
	v_mfma_f32_16x16x32_bf16 v[70:73], v[190:193], v[154:157], v[70:73]
	v_mfma_f32_16x16x32_bf16 v[78:81], v[198:201], v[154:157], v[78:81]
	v_mfma_f32_16x16x32_bf16 v[146:149], v[180:183], v[158:161], v[86:89]
	v_mfma_f32_16x16x32_bf16 v[150:153], v[184:187], v[158:161], v[94:97]
	v_mfma_f32_16x16x32_bf16 v[154:157], v[190:193], v[158:161], v[102:105]
	v_mfma_f32_16x16x32_bf16 v[158:161], v[198:201], v[158:161], v[110:113]
	v_mfma_f32_16x16x32_bf16 v[206:209], v[180:183], v[164:167], v[118:121]
	v_mfma_f32_16x16x32_bf16 v[210:213], v[184:187], v[164:167], v[126:129]
	v_mfma_f32_16x16x32_bf16 v[214:217], v[190:193], v[164:167], v[122:125]
	v_mfma_f32_16x16x32_bf16 v[164:167], v[198:201], v[164:167], v[114:117]
	v_mfma_f32_16x16x32_bf16 v[218:221], v[180:183], v[168:171], v[106:109]
	v_mfma_f32_16x16x32_bf16 v[222:225], v[184:187], v[168:171], v[98:101]
	v_mfma_f32_16x16x32_bf16 v[226:229], v[190:193], v[168:171], v[90:93]
	v_mfma_f32_16x16x32_bf16 v[168:171], v[198:201], v[168:171], v[82:85]
	v_mfma_f32_16x16x32_bf16 v[230:233], v[180:183], v[172:175], v[74:77]
	v_mfma_f32_16x16x32_bf16 v[234:237], v[184:187], v[172:175], v[66:69]
	v_mfma_f32_16x16x32_bf16 v[238:241], v[190:193], v[172:175], v[58:61]
	v_mfma_f32_16x16x32_bf16 v[172:175], v[198:201], v[172:175], v[50:53]
	v_mfma_f32_16x16x32_bf16 v[180:183], v[180:183], v[176:179], v[42:45]
	v_mfma_f32_16x16x32_bf16 v[184:187], v[184:187], v[176:179], v[34:37]
	v_mfma_f32_16x16x32_bf16 v[190:193], v[190:193], v[176:179], v[26:29]
	v_mfma_f32_16x16x32_bf16 v[176:179], v[198:201], v[176:179], v[18:21]
	s_waitcnt vmcnt(3)
	ds_write_b128 v0, v[130:133] offset:32768
	s_waitcnt vmcnt(1)
	ds_write_b128 v0, v[134:137] offset:40960
	ds_write_b128 v0, v[138:141] offset:49152
	s_waitcnt vmcnt(0)
; DI void gemm8_accum(f32x4 (&acc)[8][4], const bf16_t* a, size_t lda, const bf16_t* b, size_t ldb, int nkb, bf16_t* L,
;                     const bool pre, const bf16_t* an, size_t ldan, const bf16_t* bn, size_t ldbn) {
;     ...
;   g8_compute<1, 2>(acc, L, wm, wn, lane);
;   __syncthreads();
;   g8_store1(L, ra, lrow, lch);
;   __builtin_amdgcn_sched_barrier(0);
;   g8_compute<0, 1>(acc, L + 32768, wm, wn, lane);
;   __builtin_amdgcn_sched_barrier(0);
;   g8_store1(L + 16384, rb, lrow, lch);
;   __builtin_amdgcn_sched_barrier(0);
;   g8_compute<1, 2>(acc, L + 32768, wm, wn, lane);
;   __syncthreads();
; }
; template <class F>
; DI void gemm8_epi_staged(f32x4 (&acc)[8][4], int m0, int n0, bf16_t* L0, F f, bf16_t* dst, size_t ld, int nmax) {
;     ...
;     if (wm == half) {
; #pragma unroll
;       for (int i = 0; i < 8; ++i)
; #pragma unroll
;         for (int j = 0; j < 4; ++j) {
;           const int ml = i * 16 + (lane & 15);
;           const int nl = wn * 64 + j * 16 + (lane >> 4) * 4;
;           f32x4 a = acc[i][j];
;           f(m0 + half * 128 + ml, n0 + nl, a);
;           uint2 u;
;           u.x = pack2(a[0], a[1]);
;           u.y = pack2(a[2], a[3]);
;           *(uint2*)(L + ml * 264 + nl) = u;
;         }
	ds_write_b128 v0, v[142:145] offset:57344
	v_add3_u32 v0, s20, v163, v189
	ds_read_b128 v[18:21], v0
	ds_read_b128 v[26:29], v0 offset:2048
	ds_read_b128 v[34:37], v0 offset:4096
	ds_read_b128 v[42:45], v0 offset:6144
	ds_read_b128 v[50:53], v0 offset:8192
	ds_read_b128 v[130:133], v0 offset:10240
	ds_read_b128 v[134:137], v0 offset:12288
	ds_read_b128 v[138:141], v0 offset:14336
	v_add3_u32 v0, s6, v163, v188
	ds_read_b128 v[142:145], v0
	ds_read_b128 v[198:201], v0 offset:2048
	ds_read_b128 v[242:245], v0 offset:4096
	ds_read_b128 v[246:249], v0 offset:6144
	s_waitcnt lgkmcnt(3)
	v_mfma_f32_16x16x32_bf16 v[126:129], v[142:145], v[18:21], v[2:5]
	s_waitcnt lgkmcnt(2)
	v_mfma_f32_16x16x32_bf16 v[122:125], v[198:201], v[18:21], v[6:9]
	s_waitcnt lgkmcnt(1)
	v_mfma_f32_16x16x32_bf16 v[118:121], v[242:245], v[18:21], v[10:13]
	s_waitcnt lgkmcnt(0)
	v_mfma_f32_16x16x32_bf16 v[114:117], v[246:249], v[18:21], v[14:17]
	v_mfma_f32_16x16x32_bf16 v[110:113], v[142:145], v[26:29], v[22:25]
	v_mfma_f32_16x16x32_bf16 v[106:109], v[198:201], v[26:29], v[30:33]
	v_mfma_f32_16x16x32_bf16 v[102:105], v[242:245], v[26:29], v[38:41]
	v_mfma_f32_16x16x32_bf16 v[98:101], v[246:249], v[26:29], v[46:49]
	v_mfma_f32_16x16x32_bf16 v[94:97], v[142:145], v[34:37], v[54:57]
	v_mfma_f32_16x16x32_bf16 v[90:93], v[198:201], v[34:37], v[62:65]
	v_mfma_f32_16x16x32_bf16 v[86:89], v[242:245], v[34:37], v[70:73]
	v_mfma_f32_16x16x32_bf16 v[82:85], v[246:249], v[34:37], v[78:81]
	v_mfma_f32_16x16x32_bf16 v[78:81], v[142:145], v[42:45], v[146:149]
	v_mfma_f32_16x16x32_bf16 v[74:77], v[198:201], v[42:45], v[150:153]
	v_mfma_f32_16x16x32_bf16 v[70:73], v[242:245], v[42:45], v[154:157]
	v_mfma_f32_16x16x32_bf16 v[66:69], v[246:249], v[42:45], v[158:161]
	v_mfma_f32_16x16x32_bf16 v[62:65], v[142:145], v[50:53], v[206:209]
	v_mfma_f32_16x16x32_bf16 v[58:61], v[198:201], v[50:53], v[210:213]
	v_mfma_f32_16x16x32_bf16 v[54:57], v[242:245], v[50:53], v[214:217]
	v_mfma_f32_16x16x32_bf16 v[50:53], v[246:249], v[50:53], v[164:167]
	v_mfma_f32_16x16x32_bf16 v[46:49], v[142:145], v[130:133], v[218:221]
	v_mfma_f32_16x16x32_bf16 v[42:45], v[198:201], v[130:133], v[222:225]
	v_mfma_f32_16x16x32_bf16 v[38:41], v[242:245], v[130:133], v[226:229]
	v_mfma_f32_16x16x32_bf16 v[34:37], v[246:249], v[130:133], v[168:171]
	v_mfma_f32_16x16x32_bf16 v[30:33], v[142:145], v[134:137], v[230:233]
	v_mfma_f32_16x16x32_bf16 v[26:29], v[198:201], v[134:137], v[234:237]
	v_mfma_f32_16x16x32_bf16 v[22:25], v[242:245], v[134:137], v[238:241]
	v_mfma_f32_16x16x32_bf16 v[18:21], v[246:249], v[134:137], v[172:175]
	v_mfma_f32_16x16x32_bf16 v[14:17], v[142:145], v[138:141], v[180:183]
	v_mfma_f32_16x16x32_bf16 v[10:13], v[198:201], v[138:141], v[184:187]
	v_mfma_f32_16x16x32_bf16 v[6:9], v[242:245], v[138:141], v[190:193]
	v_mfma_f32_16x16x32_bf16 v[2:5], v[246:249], v[138:141], v[176:179]
	v_mov_b32_e32 v140, v196
	s_barrier
	s_movk_i32 s0, 0x100
	v_and_b32_e32 v0, 0xc0, v140
	v_lshrrev_b32_e32 v130, 2, v140
	v_and_b32_e32 v139, 15, v140
	v_and_or_b32 v0, v130, 12, v0
	v_mul_u32_u24_e32 v131, 0x210, v139
	v_or_b32_e32 v130, s12, v0
	v_lshlrev_b32_e32 v0, 1, v0
	v_cmp_gt_u32_e32 vcc, s0, v140
	v_lshlrev_b32_e32 v130, 1, v130
	v_add3_u32 v138, s20, v131, v0
	s_and_saveexec_b64 s[0:1], vcc
	s_cbranch_execz .LBB0_783
	v_or_b32_e32 v141, s13, v139
	v_mul_u32_u24_e32 v0, 0x2a30, v141
	v_lshl_add_u64 v[132:133], s[16:17], 0, v[0:1]
	s_mov_b64 s[6:7], 0x2230
	v_lshl_add_u64 v[136:137], v[132:133], 0, s[6:7]
	v_mov_b32_e32 v131, v1
	v_lshl_add_u64 v[132:133], v[136:137], 0, v[130:131]
	global_load_dwordx2 v[132:133], v[132:133], off
	v_add_u32_e32 v148, 0x4000, v138
	s_waitcnt vmcnt(0)
	v_lshlrev_b32_e32 v0, 16, v132
	v_mul_f32_e32 v0, 0xbfb8aa3b, v0
	v_exp_f32_e32 v0, v0
	s_nop 0
	v_add_f32_e32 v0, 1.0, v0
	v_rcp_f32_e32 v134, v0
	v_and_b32_e32 v0, 0xffff0000, v132
	v_mul_f32_e32 v0, 0xbfb8aa3b, v0
	v_exp_f32_e32 v0, v0
	s_nop 0
	v_add_f32_e32 v0, 1.0, v0
	v_rcp_f32_e32 v135, v0
	v_lshlrev_b32_e32 v0, 16, v133
	v_mul_f32_e32 v0, 0xbfb8aa3b, v0
	v_exp_f32_e32 v0, v0
	v_pk_mul_f32 v[134:135], v[126:127], v[134:135]
	v_add_f32_e32 v0, 1.0, v0
	v_rcp_f32_e32 v132, v0
	v_and_b32_e32 v0, 0xffff0000, v133
	v_mul_f32_e32 v0, 0xbfb8aa3b, v0
	v_exp_f32_e32 v0, v0
	v_cvt_pk_bf16_f32 v134, v134, v135
	v_add_f32_e32 v0, 1.0, v0
	v_rcp_f32_e32 v133, v0
	v_or_b32_e32 v0, 32, v130
	v_pk_mul_f32 v[132:133], v[128:129], v[132:133]
	s_nop 0
	v_cvt_pk_bf16_f32 v135, v132, v133
	v_lshl_add_u64 v[132:133], v[136:137], 0, v[0:1]
	global_load_dwordx2 v[132:133], v[132:133], off
	s_waitcnt vmcnt(0)
	v_lshlrev_b32_e32 v142, 16, v132
	v_and_b32_e32 v132, 0xffff0000, v132
	v_mul_f32_e32 v132, 0xbfb8aa3b, v132
	v_exp_f32_e32 v132, v132
	v_mul_f32_e32 v142, 0xbfb8aa3b, v142
	v_exp_f32_e32 v142, v142
	v_add_f32_e32 v132, 1.0, v132
	v_rcp_f32_e32 v143, v132
	v_lshlrev_b32_e32 v132, 16, v133
	v_and_b32_e32 v133, 0xffff0000, v133
	v_mul_f32_e32 v132, 0xbfb8aa3b, v132
	v_mul_f32_e32 v133, 0xbfb8aa3b, v133
	v_exp_f32_e32 v132, v132
	v_exp_f32_e32 v133, v133
	v_add_f32_e32 v142, 1.0, v142
	v_rcp_f32_e32 v142, v142
	v_add_f32_e32 v132, 1.0, v132
	v_add_f32_e32 v133, 1.0, v133
	v_rcp_f32_e32 v132, v132
	v_rcp_f32_e32 v133, v133
	v_pk_mul_f32 v[142:143], v[122:123], v[142:143]
	v_pk_mul_f32 v[132:133], v[124:125], v[132:133]
	v_cvt_pk_bf16_f32 v142, v142, v143
	v_cvt_pk_bf16_f32 v143, v132, v133
	ds_write2_b64 v138, v[134:135], v[142:143] offset1:4
	v_or_b32_e32 v134, 64, v130
	v_mov_b32_e32 v135, v1
	v_lshl_add_u64 v[132:133], v[136:137], 0, v[134:135]
	global_load_dwordx2 v[132:133], v[132:133], off
	s_waitcnt vmcnt(0)
; DI float bflo(unsigned u) { return __uint_as_float(u << 16); }
; DI float bfhi(unsigned u) { return __uint_as_float(u & 0xffff0000u); }
; DI float sigmoidf(float x) { return __builtin_amdgcn_rcpf(1.f + __expf(-x)); }
; template <class F>
; DI void gemm8_epi_staged(f32x4 (&acc)[8][4], int m0, int n0, bf16_t* L0, F f, bf16_t* dst, size_t ld, int nmax) {
;     ...
;     if (wm == half) {
; #pragma unroll
;       for (int i = 0; i < 8; ++i)
; #pragma unroll
;         for (int j = 0; j < 4; ++j) {
;           const int ml = i * 16 + (lane & 15);
;           const int nl = wn * 64 + j * 16 + (lane >> 4) * 4;
;           f32x4 a = acc[i][j];
;           f(m0 + half * 128 + ml, n0 + nl, a);
;           uint2 u;
;           u.x = pack2(a[0], a[1]);
;           u.y = pack2(a[2], a[3]);
;           *(uint2*)(L + ml * 264 + nl) = u;
;         }
; __global__ void __launch_bounds__(512, 2) mega(Params p) {
;     ...
;       gemm8_epi_staged(acc8, m0, n0, lds_all, [&](int m, int n, f32x4& a) {
;         uint2 ub = *(const uint2*)(z + (size_t)m * ZS + C_MB + n);
;         a[0] *= sigmoidf(bflo(ub.x)); a[1] *= sigmoidf(bfhi(ub.x));
;         a[2] *= sigmoidf(bflo(ub.y)); a[3] *= sigmoidf(bfhi(ub.y));
;       }, z + C_RK, ZS, 1024);
	v_lshlrev_b32_e32 v142, 16, v132
	v_and_b32_e32 v132, 0xffff0000, v132
	v_mul_f32_e32 v132, 0xbfb8aa3b, v132
	v_exp_f32_e32 v132, v132
	v_mul_f32_e32 v142, 0xbfb8aa3b, v142
	v_exp_f32_e32 v142, v142
	v_add_f32_e32 v132, 1.0, v132
	v_rcp_f32_e32 v143, v132
	v_lshlrev_b32_e32 v132, 16, v133
	v_and_b32_e32 v133, 0xffff0000, v133
	v_mul_f32_e32 v132, 0xbfb8aa3b, v132
	v_mul_f32_e32 v133, 0xbfb8aa3b, v133
	v_exp_f32_e32 v132, v132
	v_exp_f32_e32 v133, v133
	v_add_f32_e32 v142, 1.0, v142
	v_rcp_f32_e32 v142, v142
	v_add_f32_e32 v132, 1.0, v132
	v_add_f32_e32 v133, 1.0, v133
	v_rcp_f32_e32 v132, v132
	v_rcp_f32_e32 v133, v133
	v_pk_mul_f32 v[142:143], v[118:119], v[142:143]
	v_pk_mul_f32 v[132:133], v[120:121], v[132:133]
	v_cvt_pk_bf16_f32 v142, v142, v143
	v_cvt_pk_bf16_f32 v143, v132, v133
	v_or_b32_e32 v132, 0x60, v130
	v_mov_b32_e32 v133, v1
	v_lshl_add_u64 v[136:137], v[136:137], 0, v[132:133]
	global_load_dwordx2 v[136:137], v[136:137], off
	s_waitcnt vmcnt(0)
	v_lshlrev_b32_e32 v144, 16, v136
	v_and_b32_e32 v136, 0xffff0000, v136
	v_mul_f32_e32 v136, 0xbfb8aa3b, v136
	v_exp_f32_e32 v136, v136
	v_mul_f32_e32 v144, 0xbfb8aa3b, v144
	v_exp_f32_e32 v144, v144
	v_add_f32_e32 v136, 1.0, v136
	v_rcp_f32_e32 v145, v136
	v_lshlrev_b32_e32 v136, 16, v137
	v_and_b32_e32 v137, 0xffff0000, v137
	v_mul_f32_e32 v136, 0xbfb8aa3b, v136
	v_mul_f32_e32 v137, 0xbfb8aa3b, v137
	v_exp_f32_e32 v136, v136
	v_exp_f32_e32 v137, v137
	v_add_f32_e32 v144, 1.0, v144
	v_rcp_f32_e32 v144, v144
	v_add_f32_e32 v136, 1.0, v136
	v_add_f32_e32 v137, 1.0, v137
	v_rcp_f32_e32 v136, v136
	v_rcp_f32_e32 v137, v137
	v_pk_mul_f32 v[144:145], v[114:115], v[144:145]
	v_pk_mul_f32 v[136:137], v[116:117], v[136:137]
	v_cvt_pk_bf16_f32 v144, v144, v145
	v_cvt_pk_bf16_f32 v145, v136, v137
	v_or_b32_e32 v136, 16, v141
	v_mul_u32_u24_e32 v136, 0x2a30, v136
	v_mov_b32_e32 v137, v1
	v_lshl_add_u64 v[136:137], s[16:17], 0, v[136:137]
	v_lshl_add_u64 v[136:137], v[136:137], 0, s[6:7]
	ds_write2_b64 v138, v[142:143], v[144:145] offset0:8 offset1:12
	v_lshl_add_u64 v[142:143], v[136:137], 0, v[130:131]
	global_load_dwordx2 v[142:143], v[142:143], off
	s_waitcnt vmcnt(0)
	v_lshlrev_b32_e32 v144, 16, v142
	v_and_b32_e32 v142, 0xffff0000, v142
	v_mul_f32_e32 v142, 0xbfb8aa3b, v142
	v_exp_f32_e32 v142, v142
	v_mul_f32_e32 v144, 0xbfb8aa3b, v144
	v_exp_f32_e32 v144, v144
	v_add_f32_e32 v142, 1.0, v142
	v_rcp_f32_e32 v145, v142
	v_lshlrev_b32_e32 v142, 16, v143
	v_and_b32_e32 v143, 0xffff0000, v143
	v_mul_f32_e32 v142, 0xbfb8aa3b, v142
	v_mul_f32_e32 v143, 0xbfb8aa3b, v143
	v_exp_f32_e32 v142, v142
	v_exp_f32_e32 v143, v143
	v_add_f32_e32 v144, 1.0, v144
	v_rcp_f32_e32 v144, v144
	v_add_f32_e32 v142, 1.0, v142
	v_add_f32_e32 v143, 1.0, v143
	v_rcp_f32_e32 v142, v142
	v_rcp_f32_e32 v143, v143
	v_pk_mul_f32 v[144:145], v[110:111], v[144:145]
	v_pk_mul_f32 v[142:143], v[112:113], v[142:143]
	v_cvt_pk_bf16_f32 v144, v144, v145
	v_cvt_pk_bf16_f32 v145, v142, v143
	v_lshl_add_u64 v[142:143], v[136:137], 0, v[0:1]
	global_load_dwordx2 v[142:143], v[142:143], off
	s_waitcnt vmcnt(0)
	v_lshlrev_b32_e32 v146, 16, v142
	v_and_b32_e32 v142, 0xffff0000, v142
	v_mul_f32_e32 v142, 0xbfb8aa3b, v142
	v_exp_f32_e32 v142, v142
	v_mul_f32_e32 v146, 0xbfb8aa3b, v146
	v_exp_f32_e32 v146, v146
	v_add_f32_e32 v142, 1.0, v142
	v_rcp_f32_e32 v147, v142
	v_lshlrev_b32_e32 v142, 16, v143
	v_and_b32_e32 v143, 0xffff0000, v143
	v_mul_f32_e32 v142, 0xbfb8aa3b, v142
	v_mul_f32_e32 v143, 0xbfb8aa3b, v143
	v_exp_f32_e32 v142, v142
	v_exp_f32_e32 v143, v143
	v_add_f32_e32 v146, 1.0, v146
	v_rcp_f32_e32 v146, v146
	v_add_f32_e32 v142, 1.0, v142
	v_add_f32_e32 v143, 1.0, v143
	v_rcp_f32_e32 v142, v142
	v_rcp_f32_e32 v143, v143
	v_pk_mul_f32 v[146:147], v[106:107], v[146:147]
	v_pk_mul_f32 v[142:143], v[108:109], v[142:143]
	v_cvt_pk_bf16_f32 v146, v146, v147
	v_cvt_pk_bf16_f32 v147, v142, v143
	v_add_u32_e32 v142, 0x2000, v138
	ds_write2_b64 v142, v[144:145], v[146:147] offset0:32 offset1:36
	v_lshl_add_u64 v[144:145], v[136:137], 0, v[134:135]
	global_load_dwordx2 v[144:145], v[144:145], off
	v_lshl_add_u64 v[136:137], v[136:137], 0, v[132:133]
	global_load_dwordx2 v[136:137], v[136:137], off
	s_waitcnt vmcnt(1)
	v_lshlrev_b32_e32 v143, 16, v144
	v_mul_f32_e32 v143, 0xbfb8aa3b, v143
	v_exp_f32_e32 v143, v143
	s_nop 0
	v_add_f32_e32 v143, 1.0, v143
	v_rcp_f32_e32 v146, v143
	v_and_b32_e32 v143, 0xffff0000, v144
	v_mul_f32_e32 v143, 0xbfb8aa3b, v143
	v_exp_f32_e32 v143, v143
	s_nop 0
	v_add_f32_e32 v143, 1.0, v143
	v_rcp_f32_e32 v147, v143
	v_lshlrev_b32_e32 v143, 16, v145
	v_mul_f32_e32 v143, 0xbfb8aa3b, v143
	v_exp_f32_e32 v143, v143
	v_pk_mul_f32 v[146:147], v[102:103], v[146:147]
	v_add_f32_e32 v143, 1.0, v143
	v_rcp_f32_e32 v144, v143
	v_and_b32_e32 v143, 0xffff0000, v145
	v_mul_f32_e32 v143, 0xbfb8aa3b, v143
	v_exp_f32_e32 v143, v143
	v_cvt_pk_bf16_f32 v146, v146, v147
	v_add_f32_e32 v143, 1.0, v143
	v_rcp_f32_e32 v145, v143
	s_waitcnt vmcnt(0)
	v_lshlrev_b32_e32 v143, 16, v136
	v_and_b32_e32 v136, 0xffff0000, v136
	v_mul_f32_e32 v136, 0xbfb8aa3b, v136
	v_exp_f32_e32 v136, v136
	v_pk_mul_f32 v[144:145], v[104:105], v[144:145]
	v_mul_f32_e32 v143, 0xbfb8aa3b, v143
	v_cvt_pk_bf16_f32 v147, v144, v145
	v_add_f32_e32 v136, 1.0, v136
	v_rcp_f32_e32 v145, v136
	v_lshlrev_b32_e32 v136, 16, v137
	v_and_b32_e32 v137, 0xffff0000, v137
	v_mul_f32_e32 v136, 0xbfb8aa3b, v136
	v_mul_f32_e32 v137, 0xbfb8aa3b, v137
	v_exp_f32_e32 v143, v143
	v_exp_f32_e32 v136, v136
	v_exp_f32_e32 v137, v137
	v_add_f32_e32 v143, 1.0, v143
	v_add_f32_e32 v136, 1.0, v136
	v_add_f32_e32 v137, 1.0, v137
	v_rcp_f32_e32 v144, v143
	v_rcp_f32_e32 v136, v136
	v_rcp_f32_e32 v137, v137
	v_pk_mul_f32 v[144:145], v[98:99], v[144:145]
	s_nop 0
	v_cvt_pk_bf16_f32 v144, v144, v145
	v_pk_mul_f32 v[136:137], v[100:101], v[136:137]
	s_nop 0
	v_cvt_pk_bf16_f32 v145, v136, v137
	v_or_b32_e32 v136, 32, v141
	v_mul_u32_u24_e32 v136, 0x2a30, v136
	v_mov_b32_e32 v137, v1
	v_lshl_add_u64 v[136:137], s[16:17], 0, v[136:137]
	v_lshl_add_u64 v[136:137], v[136:137], 0, s[6:7]
	ds_write2_b64 v142, v[146:147], v[144:145] offset0:40 offset1:44
	v_lshl_add_u64 v[142:143], v[136:137], 0, v[130:131]
	global_load_dwordx2 v[142:143], v[142:143], off
	s_waitcnt vmcnt(0)
; DI float bflo(unsigned u) { return __uint_as_float(u << 16); }
; DI float bfhi(unsigned u) { return __uint_as_float(u & 0xffff0000u); }
; DI float sigmoidf(float x) { return __builtin_amdgcn_rcpf(1.f + __expf(-x)); }
; template <class F>
; DI void gemm8_epi_staged(f32x4 (&acc)[8][4], int m0, int n0, bf16_t* L0, F f, bf16_t* dst, size_t ld, int nmax) {
;     ...
;     if (wm == half) {
; #pragma unroll
;       for (int i = 0; i < 8; ++i)
; #pragma unroll
;         for (int j = 0; j < 4; ++j) {
;           const int ml = i * 16 + (lane & 15);
;           const int nl = wn * 64 + j * 16 + (lane >> 4) * 4;
;           f32x4 a = acc[i][j];
;           f(m0 + half * 128 + ml, n0 + nl, a);
;           uint2 u;
;           u.x = pack2(a[0], a[1]);
;           u.y = pack2(a[2], a[3]);
;           *(uint2*)(L + ml * 264 + nl) = u;
;         }
; __global__ void __launch_bounds__(512, 2) mega(Params p) {
;     ...
;       gemm8_epi_staged(acc8, m0, n0, lds_all, [&](int m, int n, f32x4& a) {
;         uint2 ub = *(const uint2*)(z + (size_t)m * ZS + C_MB + n);
;         a[0] *= sigmoidf(bflo(ub.x)); a[1] *= sigmoidf(bfhi(ub.x));
;         a[2] *= sigmoidf(bflo(ub.y)); a[3] *= sigmoidf(bfhi(ub.y));
;       }, z + C_RK, ZS, 1024);
	v_lshlrev_b32_e32 v144, 16, v142
	v_and_b32_e32 v142, 0xffff0000, v142
	v_mul_f32_e32 v142, 0xbfb8aa3b, v142
	v_exp_f32_e32 v142, v142
	v_mul_f32_e32 v144, 0xbfb8aa3b, v144
	v_exp_f32_e32 v144, v144
	v_add_f32_e32 v142, 1.0, v142
	v_rcp_f32_e32 v145, v142
	v_lshlrev_b32_e32 v142, 16, v143
	v_and_b32_e32 v143, 0xffff0000, v143
	v_mul_f32_e32 v142, 0xbfb8aa3b, v142
	v_mul_f32_e32 v143, 0xbfb8aa3b, v143
	v_exp_f32_e32 v142, v142
	v_exp_f32_e32 v143, v143
	v_add_f32_e32 v144, 1.0, v144
	v_rcp_f32_e32 v144, v144
	v_add_f32_e32 v142, 1.0, v142
	v_add_f32_e32 v143, 1.0, v143
	v_rcp_f32_e32 v142, v142
	v_rcp_f32_e32 v143, v143
	v_pk_mul_f32 v[144:145], v[94:95], v[144:145]
	v_pk_mul_f32 v[142:143], v[96:97], v[142:143]
	v_cvt_pk_bf16_f32 v144, v144, v145
	v_cvt_pk_bf16_f32 v145, v142, v143
	v_lshl_add_u64 v[142:143], v[136:137], 0, v[0:1]
	global_load_dwordx2 v[142:143], v[142:143], off
	s_waitcnt vmcnt(0)
	v_lshlrev_b32_e32 v146, 16, v142
	v_and_b32_e32 v142, 0xffff0000, v142
	v_mul_f32_e32 v142, 0xbfb8aa3b, v142
	v_exp_f32_e32 v142, v142
	v_mul_f32_e32 v146, 0xbfb8aa3b, v146
	v_exp_f32_e32 v146, v146
	v_add_f32_e32 v142, 1.0, v142
	v_rcp_f32_e32 v147, v142
	v_lshlrev_b32_e32 v142, 16, v143
	v_and_b32_e32 v143, 0xffff0000, v143
	v_mul_f32_e32 v142, 0xbfb8aa3b, v142
	v_mul_f32_e32 v143, 0xbfb8aa3b, v143
	v_exp_f32_e32 v142, v142
	v_exp_f32_e32 v143, v143
	v_add_f32_e32 v146, 1.0, v146
	v_rcp_f32_e32 v146, v146
	v_add_f32_e32 v142, 1.0, v142
	v_add_f32_e32 v143, 1.0, v143
	v_rcp_f32_e32 v142, v142
	v_rcp_f32_e32 v143, v143
	v_pk_mul_f32 v[146:147], v[90:91], v[146:147]
	v_pk_mul_f32 v[142:143], v[92:93], v[142:143]
	v_cvt_pk_bf16_f32 v146, v146, v147
	v_cvt_pk_bf16_f32 v147, v142, v143
	v_lshl_add_u64 v[142:143], v[136:137], 0, v[134:135]
	global_load_dwordx2 v[142:143], v[142:143], off
	v_lshl_add_u64 v[136:137], v[136:137], 0, v[132:133]
	global_load_dwordx2 v[136:137], v[136:137], off
	ds_write2_b64 v148, v[144:145], v[146:147] offset0:64 offset1:68
	s_waitcnt vmcnt(1)
	v_lshlrev_b32_e32 v144, 16, v142
	v_and_b32_e32 v142, 0xffff0000, v142
	v_mul_f32_e32 v142, 0xbfb8aa3b, v142
	v_exp_f32_e32 v142, v142
	v_mul_f32_e32 v144, 0xbfb8aa3b, v144
	v_exp_f32_e32 v144, v144
	v_add_f32_e32 v142, 1.0, v142
	v_rcp_f32_e32 v145, v142
	v_lshlrev_b32_e32 v142, 16, v143
	v_and_b32_e32 v143, 0xffff0000, v143
	v_mul_f32_e32 v142, 0xbfb8aa3b, v142
	v_mul_f32_e32 v143, 0xbfb8aa3b, v143
	v_exp_f32_e32 v142, v142
	v_exp_f32_e32 v143, v143
	v_add_f32_e32 v144, 1.0, v144
	v_rcp_f32_e32 v144, v144
	v_add_f32_e32 v142, 1.0, v142
	v_add_f32_e32 v143, 1.0, v143
	v_rcp_f32_e32 v142, v142
	v_rcp_f32_e32 v143, v143
	v_pk_mul_f32 v[144:145], v[86:87], v[144:145]
	v_pk_mul_f32 v[142:143], v[88:89], v[142:143]
	v_cvt_pk_bf16_f32 v144, v144, v145
	v_cvt_pk_bf16_f32 v145, v142, v143
	s_waitcnt vmcnt(0)
	v_lshlrev_b32_e32 v142, 16, v136
	v_and_b32_e32 v136, 0xffff0000, v136
	v_mul_f32_e32 v136, 0xbfb8aa3b, v136
	v_exp_f32_e32 v136, v136
	v_mul_f32_e32 v142, 0xbfb8aa3b, v142
	v_exp_f32_e32 v142, v142
	v_add_f32_e32 v136, 1.0, v136
	v_rcp_f32_e32 v143, v136
	v_lshlrev_b32_e32 v136, 16, v137
	v_and_b32_e32 v137, 0xffff0000, v137
	v_mul_f32_e32 v136, 0xbfb8aa3b, v136
	v_mul_f32_e32 v137, 0xbfb8aa3b, v137
	v_exp_f32_e32 v136, v136
	v_exp_f32_e32 v137, v137
	v_add_f32_e32 v142, 1.0, v142
	v_rcp_f32_e32 v142, v142
	v_add_f32_e32 v136, 1.0, v136
	v_add_f32_e32 v137, 1.0, v137
	v_rcp_f32_e32 v136, v136
	v_rcp_f32_e32 v137, v137
	v_pk_mul_f32 v[142:143], v[82:83], v[142:143]
	v_pk_mul_f32 v[136:137], v[84:85], v[136:137]
	v_cvt_pk_bf16_f32 v142, v142, v143
	v_cvt_pk_bf16_f32 v143, v136, v137
	v_or_b32_e32 v136, 48, v141
	v_mul_u32_u24_e32 v136, 0x2a30, v136
	v_mov_b32_e32 v137, v1
	v_lshl_add_u64 v[136:137], s[16:17], 0, v[136:137]
	v_lshl_add_u64 v[136:137], v[136:137], 0, s[6:7]
	ds_write2_b64 v148, v[144:145], v[142:143] offset0:72 offset1:76
	v_lshl_add_u64 v[142:143], v[136:137], 0, v[130:131]
	global_load_dwordx2 v[142:143], v[142:143], off
	v_add_u32_e32 v148, 0x6000, v138
	s_waitcnt vmcnt(0)
	v_lshlrev_b32_e32 v144, 16, v142
	v_and_b32_e32 v142, 0xffff0000, v142
	v_mul_f32_e32 v142, 0xbfb8aa3b, v142
	v_exp_f32_e32 v142, v142
	v_mul_f32_e32 v144, 0xbfb8aa3b, v144
	v_exp_f32_e32 v144, v144
	v_add_f32_e32 v142, 1.0, v142
	v_rcp_f32_e32 v145, v142
	v_lshlrev_b32_e32 v142, 16, v143
	v_and_b32_e32 v143, 0xffff0000, v143
	v_mul_f32_e32 v142, 0xbfb8aa3b, v142
	v_mul_f32_e32 v143, 0xbfb8aa3b, v143
	v_exp_f32_e32 v142, v142
	v_exp_f32_e32 v143, v143
	v_add_f32_e32 v144, 1.0, v144
	v_rcp_f32_e32 v144, v144
	v_add_f32_e32 v142, 1.0, v142
	v_add_f32_e32 v143, 1.0, v143
	v_rcp_f32_e32 v142, v142
	v_rcp_f32_e32 v143, v143
	v_pk_mul_f32 v[144:145], v[78:79], v[144:145]
	v_pk_mul_f32 v[142:143], v[80:81], v[142:143]
	v_cvt_pk_bf16_f32 v144, v144, v145
	v_cvt_pk_bf16_f32 v145, v142, v143
	v_lshl_add_u64 v[142:143], v[136:137], 0, v[0:1]
	global_load_dwordx2 v[142:143], v[142:143], off
	s_waitcnt vmcnt(0)
	v_lshlrev_b32_e32 v146, 16, v142
	v_and_b32_e32 v142, 0xffff0000, v142
	v_mul_f32_e32 v142, 0xbfb8aa3b, v142
	v_exp_f32_e32 v142, v142
	v_mul_f32_e32 v146, 0xbfb8aa3b, v146
	v_exp_f32_e32 v146, v146
	v_add_f32_e32 v142, 1.0, v142
	v_rcp_f32_e32 v147, v142
	v_lshlrev_b32_e32 v142, 16, v143
	v_and_b32_e32 v143, 0xffff0000, v143
	v_mul_f32_e32 v142, 0xbfb8aa3b, v142
	v_mul_f32_e32 v143, 0xbfb8aa3b, v143
	v_exp_f32_e32 v142, v142
	v_exp_f32_e32 v143, v143
	v_add_f32_e32 v146, 1.0, v146
	v_rcp_f32_e32 v146, v146
	v_add_f32_e32 v142, 1.0, v142
	v_add_f32_e32 v143, 1.0, v143
	v_rcp_f32_e32 v142, v142
	v_rcp_f32_e32 v143, v143
	v_pk_mul_f32 v[146:147], v[74:75], v[146:147]
	v_pk_mul_f32 v[142:143], v[76:77], v[142:143]
	v_cvt_pk_bf16_f32 v146, v146, v147
	v_cvt_pk_bf16_f32 v147, v142, v143
	v_lshl_add_u64 v[142:143], v[136:137], 0, v[134:135]
	global_load_dwordx2 v[142:143], v[142:143], off
	v_lshl_add_u64 v[136:137], v[136:137], 0, v[132:133]
	global_load_dwordx2 v[136:137], v[136:137], off
	ds_write2_b64 v148, v[144:145], v[146:147] offset0:96 offset1:100
	s_waitcnt vmcnt(1)
; DI float bflo(unsigned u) { return __uint_as_float(u << 16); }
; DI float bfhi(unsigned u) { return __uint_as_float(u & 0xffff0000u); }
; DI float sigmoidf(float x) { return __builtin_amdgcn_rcpf(1.f + __expf(-x)); }
; template <class F>
; DI void gemm8_epi_staged(f32x4 (&acc)[8][4], int m0, int n0, bf16_t* L0, F f, bf16_t* dst, size_t ld, int nmax) {
;     ...
;     if (wm == half) {
; #pragma unroll
;       for (int i = 0; i < 8; ++i)
; #pragma unroll
;         for (int j = 0; j < 4; ++j) {
;           const int ml = i * 16 + (lane & 15);
;           const int nl = wn * 64 + j * 16 + (lane >> 4) * 4;
;           f32x4 a = acc[i][j];
;           f(m0 + half * 128 + ml, n0 + nl, a);
;           uint2 u;
;           u.x = pack2(a[0], a[1]);
;           u.y = pack2(a[2], a[3]);
;           *(uint2*)(L + ml * 264 + nl) = u;
;         }
; __global__ void __launch_bounds__(512, 2) mega(Params p) {
;     ...
;       gemm8_epi_staged(acc8, m0, n0, lds_all, [&](int m, int n, f32x4& a) {
;         uint2 ub = *(const uint2*)(z + (size_t)m * ZS + C_MB + n);
;         a[0] *= sigmoidf(bflo(ub.x)); a[1] *= sigmoidf(bfhi(ub.x));
;         a[2] *= sigmoidf(bflo(ub.y)); a[3] *= sigmoidf(bfhi(ub.y));
;       }, z + C_RK, ZS, 1024);
	v_lshlrev_b32_e32 v144, 16, v142
	v_and_b32_e32 v142, 0xffff0000, v142
	v_mul_f32_e32 v142, 0xbfb8aa3b, v142
	v_exp_f32_e32 v142, v142
	v_mul_f32_e32 v144, 0xbfb8aa3b, v144
	v_exp_f32_e32 v144, v144
	v_add_f32_e32 v142, 1.0, v142
	v_rcp_f32_e32 v145, v142
	v_lshlrev_b32_e32 v142, 16, v143
	v_and_b32_e32 v143, 0xffff0000, v143
	v_mul_f32_e32 v142, 0xbfb8aa3b, v142
	v_mul_f32_e32 v143, 0xbfb8aa3b, v143
	v_exp_f32_e32 v142, v142
	v_exp_f32_e32 v143, v143
	v_add_f32_e32 v144, 1.0, v144
	v_rcp_f32_e32 v144, v144
	v_add_f32_e32 v142, 1.0, v142
	v_add_f32_e32 v143, 1.0, v143
	v_rcp_f32_e32 v142, v142
	v_rcp_f32_e32 v143, v143
	v_pk_mul_f32 v[144:145], v[70:71], v[144:145]
	v_pk_mul_f32 v[142:143], v[72:73], v[142:143]
	v_cvt_pk_bf16_f32 v144, v144, v145
	v_cvt_pk_bf16_f32 v145, v142, v143
	s_waitcnt vmcnt(0)
	v_lshlrev_b32_e32 v142, 16, v136
	v_and_b32_e32 v136, 0xffff0000, v136
	v_mul_f32_e32 v136, 0xbfb8aa3b, v136
	v_exp_f32_e32 v136, v136
	v_mul_f32_e32 v142, 0xbfb8aa3b, v142
	v_exp_f32_e32 v142, v142
	v_add_f32_e32 v136, 1.0, v136
	v_rcp_f32_e32 v143, v136
	v_lshlrev_b32_e32 v136, 16, v137
	v_and_b32_e32 v137, 0xffff0000, v137
	v_mul_f32_e32 v136, 0xbfb8aa3b, v136
	v_mul_f32_e32 v137, 0xbfb8aa3b, v137
	v_exp_f32_e32 v136, v136
	v_exp_f32_e32 v137, v137
	v_add_f32_e32 v142, 1.0, v142
	v_rcp_f32_e32 v142, v142
	v_add_f32_e32 v136, 1.0, v136
	v_add_f32_e32 v137, 1.0, v137
	v_rcp_f32_e32 v136, v136
	v_rcp_f32_e32 v137, v137
	v_pk_mul_f32 v[142:143], v[66:67], v[142:143]
	v_pk_mul_f32 v[136:137], v[68:69], v[136:137]
	v_cvt_pk_bf16_f32 v142, v142, v143
	v_cvt_pk_bf16_f32 v143, v136, v137
	v_or_b32_e32 v136, 64, v141
	v_mul_u32_u24_e32 v136, 0x2a30, v136
	v_mov_b32_e32 v137, v1
	v_lshl_add_u64 v[136:137], s[16:17], 0, v[136:137]
	v_lshl_add_u64 v[136:137], v[136:137], 0, s[6:7]
	ds_write2_b64 v148, v[144:145], v[142:143] offset0:104 offset1:108
	v_lshl_add_u64 v[142:143], v[136:137], 0, v[130:131]
	global_load_dwordx2 v[142:143], v[142:143], off
	v_add_u32_e32 v148, 0x8000, v138
	s_waitcnt vmcnt(0)
	v_lshlrev_b32_e32 v144, 16, v142
	v_and_b32_e32 v142, 0xffff0000, v142
	v_mul_f32_e32 v142, 0xbfb8aa3b, v142
	v_exp_f32_e32 v142, v142
	v_mul_f32_e32 v144, 0xbfb8aa3b, v144
	v_exp_f32_e32 v144, v144
	v_add_f32_e32 v142, 1.0, v142
	v_rcp_f32_e32 v145, v142
	v_lshlrev_b32_e32 v142, 16, v143
	v_and_b32_e32 v143, 0xffff0000, v143
	v_mul_f32_e32 v142, 0xbfb8aa3b, v142
	v_mul_f32_e32 v143, 0xbfb8aa3b, v143
	v_exp_f32_e32 v142, v142
	v_exp_f32_e32 v143, v143
	v_add_f32_e32 v144, 1.0, v144
	v_rcp_f32_e32 v144, v144
	v_add_f32_e32 v142, 1.0, v142
	v_add_f32_e32 v143, 1.0, v143
	v_rcp_f32_e32 v142, v142
	v_rcp_f32_e32 v143, v143
	v_pk_mul_f32 v[144:145], v[62:63], v[144:145]
	v_pk_mul_f32 v[142:143], v[64:65], v[142:143]
	v_cvt_pk_bf16_f32 v144, v144, v145
	v_cvt_pk_bf16_f32 v145, v142, v143
	v_lshl_add_u64 v[142:143], v[136:137], 0, v[0:1]
	global_load_dwordx2 v[142:143], v[142:143], off
	s_waitcnt vmcnt(0)
	v_lshlrev_b32_e32 v146, 16, v142
	v_and_b32_e32 v142, 0xffff0000, v142
	v_mul_f32_e32 v142, 0xbfb8aa3b, v142
	v_exp_f32_e32 v142, v142
	v_mul_f32_e32 v146, 0xbfb8aa3b, v146
	v_exp_f32_e32 v146, v146
	v_add_f32_e32 v142, 1.0, v142
	v_rcp_f32_e32 v147, v142
	v_lshlrev_b32_e32 v142, 16, v143
	v_and_b32_e32 v143, 0xffff0000, v143
	v_mul_f32_e32 v142, 0xbfb8aa3b, v142
	v_mul_f32_e32 v143, 0xbfb8aa3b, v143
	v_exp_f32_e32 v142, v142
	v_exp_f32_e32 v143, v143
	v_add_f32_e32 v146, 1.0, v146
	v_rcp_f32_e32 v146, v146
	v_add_f32_e32 v142, 1.0, v142
	v_add_f32_e32 v143, 1.0, v143
	v_rcp_f32_e32 v142, v142
	v_rcp_f32_e32 v143, v143
	v_pk_mul_f32 v[146:147], v[58:59], v[146:147]
	v_pk_mul_f32 v[142:143], v[60:61], v[142:143]
	v_cvt_pk_bf16_f32 v146, v146, v147
	v_cvt_pk_bf16_f32 v147, v142, v143
	v_lshl_add_u64 v[142:143], v[136:137], 0, v[134:135]
	global_load_dwordx2 v[142:143], v[142:143], off
	v_lshl_add_u64 v[136:137], v[136:137], 0, v[132:133]
	global_load_dwordx2 v[136:137], v[136:137], off
	ds_write2_b64 v148, v[144:145], v[146:147] offset0:128 offset1:132
	s_waitcnt vmcnt(1)
	v_lshlrev_b32_e32 v144, 16, v142
	v_and_b32_e32 v142, 0xffff0000, v142
	v_mul_f32_e32 v142, 0xbfb8aa3b, v142
	v_exp_f32_e32 v142, v142
	v_mul_f32_e32 v144, 0xbfb8aa3b, v144
	v_exp_f32_e32 v144, v144
	v_add_f32_e32 v142, 1.0, v142
	v_rcp_f32_e32 v145, v142
	v_lshlrev_b32_e32 v142, 16, v143
	v_and_b32_e32 v143, 0xffff0000, v143
	v_mul_f32_e32 v142, 0xbfb8aa3b, v142
	v_mul_f32_e32 v143, 0xbfb8aa3b, v143
	v_exp_f32_e32 v142, v142
	v_exp_f32_e32 v143, v143
	v_add_f32_e32 v144, 1.0, v144
	v_rcp_f32_e32 v144, v144
	v_add_f32_e32 v142, 1.0, v142
	v_add_f32_e32 v143, 1.0, v143
	v_rcp_f32_e32 v142, v142
	v_rcp_f32_e32 v143, v143
	v_pk_mul_f32 v[144:145], v[54:55], v[144:145]
	v_pk_mul_f32 v[142:143], v[56:57], v[142:143]
	v_cvt_pk_bf16_f32 v144, v144, v145
	v_cvt_pk_bf16_f32 v145, v142, v143
	s_waitcnt vmcnt(0)
	v_lshlrev_b32_e32 v142, 16, v136
	v_and_b32_e32 v136, 0xffff0000, v136
	v_mul_f32_e32 v136, 0xbfb8aa3b, v136
	v_exp_f32_e32 v136, v136
	v_mul_f32_e32 v142, 0xbfb8aa3b, v142
	v_exp_f32_e32 v142, v142
	v_add_f32_e32 v136, 1.0, v136
	v_rcp_f32_e32 v143, v136
	v_lshlrev_b32_e32 v136, 16, v137
	v_and_b32_e32 v137, 0xffff0000, v137
	v_mul_f32_e32 v136, 0xbfb8aa3b, v136
	v_mul_f32_e32 v137, 0xbfb8aa3b, v137
	v_exp_f32_e32 v136, v136
	v_exp_f32_e32 v137, v137
	v_add_f32_e32 v142, 1.0, v142
	v_rcp_f32_e32 v142, v142
	v_add_f32_e32 v136, 1.0, v136
	v_add_f32_e32 v137, 1.0, v137
	v_rcp_f32_e32 v136, v136
	v_rcp_f32_e32 v137, v137
	v_pk_mul_f32 v[142:143], v[50:51], v[142:143]
	v_pk_mul_f32 v[136:137], v[52:53], v[136:137]
	v_cvt_pk_bf16_f32 v142, v142, v143
	v_cvt_pk_bf16_f32 v143, v136, v137
	v_or_b32_e32 v136, 0x50, v141
	v_mul_u32_u24_e32 v136, 0x2a30, v136
	v_mov_b32_e32 v137, v1
	v_lshl_add_u64 v[136:137], s[16:17], 0, v[136:137]
	v_lshl_add_u64 v[136:137], v[136:137], 0, s[6:7]
	ds_write2_b64 v148, v[144:145], v[142:143] offset0:136 offset1:140
	v_lshl_add_u64 v[142:143], v[136:137], 0, v[130:131]
	global_load_dwordx2 v[142:143], v[142:143], off
	v_add_u32_e32 v148, 0xa000, v138
	s_waitcnt vmcnt(0)
; DI float bflo(unsigned u) { return __uint_as_float(u << 16); }
; DI float bfhi(unsigned u) { return __uint_as_float(u & 0xffff0000u); }
; DI float sigmoidf(float x) { return __builtin_amdgcn_rcpf(1.f + __expf(-x)); }
; template <class F>
; DI void gemm8_epi_staged(f32x4 (&acc)[8][4], int m0, int n0, bf16_t* L0, F f, bf16_t* dst, size_t ld, int nmax) {
;     ...
;     if (wm == half) {
; #pragma unroll
;       for (int i = 0; i < 8; ++i)
; #pragma unroll
;         for (int j = 0; j < 4; ++j) {
;           const int ml = i * 16 + (lane & 15);
;           const int nl = wn * 64 + j * 16 + (lane >> 4) * 4;
;           f32x4 a = acc[i][j];
;           f(m0 + half * 128 + ml, n0 + nl, a);
;           uint2 u;
;           u.x = pack2(a[0], a[1]);
;           u.y = pack2(a[2], a[3]);
;           *(uint2*)(L + ml * 264 + nl) = u;
;         }
; __global__ void __launch_bounds__(512, 2) mega(Params p) {
;     ...
;       gemm8_epi_staged(acc8, m0, n0, lds_all, [&](int m, int n, f32x4& a) {
;         uint2 ub = *(const uint2*)(z + (size_t)m * ZS + C_MB + n);
;         a[0] *= sigmoidf(bflo(ub.x)); a[1] *= sigmoidf(bfhi(ub.x));
;         a[2] *= sigmoidf(bflo(ub.y)); a[3] *= sigmoidf(bfhi(ub.y));
;       }, z + C_RK, ZS, 1024);
	v_lshlrev_b32_e32 v144, 16, v142
	v_and_b32_e32 v142, 0xffff0000, v142
	v_mul_f32_e32 v142, 0xbfb8aa3b, v142
	v_exp_f32_e32 v142, v142
	v_mul_f32_e32 v144, 0xbfb8aa3b, v144
	v_exp_f32_e32 v144, v144
	v_add_f32_e32 v142, 1.0, v142
	v_rcp_f32_e32 v145, v142
	v_lshlrev_b32_e32 v142, 16, v143
	v_and_b32_e32 v143, 0xffff0000, v143
	v_mul_f32_e32 v142, 0xbfb8aa3b, v142
	v_mul_f32_e32 v143, 0xbfb8aa3b, v143
	v_exp_f32_e32 v142, v142
	v_exp_f32_e32 v143, v143
	v_add_f32_e32 v144, 1.0, v144
	v_rcp_f32_e32 v144, v144
	v_add_f32_e32 v142, 1.0, v142
	v_add_f32_e32 v143, 1.0, v143
	v_rcp_f32_e32 v142, v142
	v_rcp_f32_e32 v143, v143
	v_pk_mul_f32 v[144:145], v[46:47], v[144:145]
	v_pk_mul_f32 v[142:143], v[48:49], v[142:143]
	v_cvt_pk_bf16_f32 v144, v144, v145
	v_cvt_pk_bf16_f32 v145, v142, v143
	v_lshl_add_u64 v[142:143], v[136:137], 0, v[0:1]
	global_load_dwordx2 v[142:143], v[142:143], off
	s_waitcnt vmcnt(0)
	v_lshlrev_b32_e32 v146, 16, v142
	v_and_b32_e32 v142, 0xffff0000, v142
	v_mul_f32_e32 v142, 0xbfb8aa3b, v142
	v_exp_f32_e32 v142, v142
	v_mul_f32_e32 v146, 0xbfb8aa3b, v146
	v_exp_f32_e32 v146, v146
	v_add_f32_e32 v142, 1.0, v142
	v_rcp_f32_e32 v147, v142
	v_lshlrev_b32_e32 v142, 16, v143
	v_and_b32_e32 v143, 0xffff0000, v143
	v_mul_f32_e32 v142, 0xbfb8aa3b, v142
	v_mul_f32_e32 v143, 0xbfb8aa3b, v143
	v_exp_f32_e32 v142, v142
	v_exp_f32_e32 v143, v143
	v_add_f32_e32 v146, 1.0, v146
	v_rcp_f32_e32 v146, v146
	v_add_f32_e32 v142, 1.0, v142
	v_add_f32_e32 v143, 1.0, v143
	v_rcp_f32_e32 v142, v142
	v_rcp_f32_e32 v143, v143
	v_pk_mul_f32 v[146:147], v[42:43], v[146:147]
	v_pk_mul_f32 v[142:143], v[44:45], v[142:143]
	v_cvt_pk_bf16_f32 v146, v146, v147
	v_cvt_pk_bf16_f32 v147, v142, v143
	v_lshl_add_u64 v[142:143], v[136:137], 0, v[134:135]
	global_load_dwordx2 v[142:143], v[142:143], off
	v_lshl_add_u64 v[136:137], v[136:137], 0, v[132:133]
	global_load_dwordx2 v[136:137], v[136:137], off
	ds_write2_b64 v148, v[144:145], v[146:147] offset0:160 offset1:164
	s_waitcnt vmcnt(1)
	v_lshlrev_b32_e32 v144, 16, v142
	v_and_b32_e32 v142, 0xffff0000, v142
	v_mul_f32_e32 v142, 0xbfb8aa3b, v142
	v_exp_f32_e32 v142, v142
	v_mul_f32_e32 v144, 0xbfb8aa3b, v144
	v_exp_f32_e32 v144, v144
	v_add_f32_e32 v142, 1.0, v142
	v_rcp_f32_e32 v145, v142
	v_lshlrev_b32_e32 v142, 16, v143
	v_and_b32_e32 v143, 0xffff0000, v143
	v_mul_f32_e32 v142, 0xbfb8aa3b, v142
	v_mul_f32_e32 v143, 0xbfb8aa3b, v143
	v_exp_f32_e32 v142, v142
	v_exp_f32_e32 v143, v143
	v_add_f32_e32 v144, 1.0, v144
	v_rcp_f32_e32 v144, v144
	v_add_f32_e32 v142, 1.0, v142
	v_add_f32_e32 v143, 1.0, v143
	v_rcp_f32_e32 v142, v142
	v_rcp_f32_e32 v143, v143
	v_pk_mul_f32 v[144:145], v[38:39], v[144:145]
	v_pk_mul_f32 v[142:143], v[40:41], v[142:143]
	v_cvt_pk_bf16_f32 v144, v144, v145
	v_cvt_pk_bf16_f32 v145, v142, v143
	s_waitcnt vmcnt(0)
	v_lshlrev_b32_e32 v142, 16, v136
	v_and_b32_e32 v136, 0xffff0000, v136
	v_mul_f32_e32 v136, 0xbfb8aa3b, v136
	v_exp_f32_e32 v136, v136
	v_mul_f32_e32 v142, 0xbfb8aa3b, v142
	v_exp_f32_e32 v142, v142
	v_add_f32_e32 v136, 1.0, v136
	v_rcp_f32_e32 v143, v136
	v_lshlrev_b32_e32 v136, 16, v137
	v_and_b32_e32 v137, 0xffff0000, v137
	v_mul_f32_e32 v136, 0xbfb8aa3b, v136
	v_mul_f32_e32 v137, 0xbfb8aa3b, v137
	v_exp_f32_e32 v136, v136
	v_exp_f32_e32 v137, v137
	v_add_f32_e32 v142, 1.0, v142
	v_rcp_f32_e32 v142, v142
	v_add_f32_e32 v136, 1.0, v136
	v_add_f32_e32 v137, 1.0, v137
	v_rcp_f32_e32 v136, v136
	v_rcp_f32_e32 v137, v137
	v_pk_mul_f32 v[142:143], v[34:35], v[142:143]
	v_pk_mul_f32 v[136:137], v[36:37], v[136:137]
	v_cvt_pk_bf16_f32 v142, v142, v143
	v_cvt_pk_bf16_f32 v143, v136, v137
	v_or_b32_e32 v136, 0x60, v141
	v_mul_u32_u24_e32 v136, 0x2a30, v136
	v_mov_b32_e32 v137, v1
	v_lshl_add_u64 v[136:137], s[16:17], 0, v[136:137]
	v_lshl_add_u64 v[136:137], v[136:137], 0, s[6:7]
	ds_write2_b64 v148, v[144:145], v[142:143] offset0:168 offset1:172
	v_lshl_add_u64 v[142:143], v[136:137], 0, v[130:131]
	global_load_dwordx2 v[142:143], v[142:143], off
	v_add_u32_e32 v148, 0xc000, v138
	s_waitcnt vmcnt(0)
	v_lshlrev_b32_e32 v144, 16, v142
	v_and_b32_e32 v142, 0xffff0000, v142
	v_mul_f32_e32 v142, 0xbfb8aa3b, v142
	v_exp_f32_e32 v142, v142
	v_mul_f32_e32 v144, 0xbfb8aa3b, v144
	v_exp_f32_e32 v144, v144
	v_add_f32_e32 v142, 1.0, v142
	v_rcp_f32_e32 v145, v142
	v_lshlrev_b32_e32 v142, 16, v143
	v_and_b32_e32 v143, 0xffff0000, v143
	v_mul_f32_e32 v142, 0xbfb8aa3b, v142
	v_mul_f32_e32 v143, 0xbfb8aa3b, v143
	v_exp_f32_e32 v142, v142
	v_exp_f32_e32 v143, v143
	v_add_f32_e32 v144, 1.0, v144
	v_rcp_f32_e32 v144, v144
	v_add_f32_e32 v142, 1.0, v142
	v_add_f32_e32 v143, 1.0, v143
	v_rcp_f32_e32 v142, v142
	v_rcp_f32_e32 v143, v143
	v_pk_mul_f32 v[144:145], v[30:31], v[144:145]
	v_pk_mul_f32 v[142:143], v[32:33], v[142:143]
	v_cvt_pk_bf16_f32 v144, v144, v145
	v_cvt_pk_bf16_f32 v145, v142, v143
	v_lshl_add_u64 v[142:143], v[136:137], 0, v[0:1]
	global_load_dwordx2 v[142:143], v[142:143], off
	s_waitcnt vmcnt(0)
	v_lshlrev_b32_e32 v146, 16, v142
	v_and_b32_e32 v142, 0xffff0000, v142
	v_mul_f32_e32 v142, 0xbfb8aa3b, v142
	v_exp_f32_e32 v142, v142
	v_mul_f32_e32 v146, 0xbfb8aa3b, v146
	v_exp_f32_e32 v146, v146
	v_add_f32_e32 v142, 1.0, v142
	v_rcp_f32_e32 v147, v142
	v_lshlrev_b32_e32 v142, 16, v143
	v_and_b32_e32 v143, 0xffff0000, v143
	v_mul_f32_e32 v142, 0xbfb8aa3b, v142
	v_mul_f32_e32 v143, 0xbfb8aa3b, v143
	v_exp_f32_e32 v142, v142
	v_exp_f32_e32 v143, v143
	v_add_f32_e32 v146, 1.0, v146
	v_rcp_f32_e32 v146, v146
	v_add_f32_e32 v142, 1.0, v142
	v_add_f32_e32 v143, 1.0, v143
	v_rcp_f32_e32 v142, v142
	v_rcp_f32_e32 v143, v143
	v_pk_mul_f32 v[146:147], v[26:27], v[146:147]
	v_pk_mul_f32 v[142:143], v[28:29], v[142:143]
	v_cvt_pk_bf16_f32 v146, v146, v147
	v_cvt_pk_bf16_f32 v147, v142, v143
	v_lshl_add_u64 v[142:143], v[136:137], 0, v[134:135]
	global_load_dwordx2 v[142:143], v[142:143], off
	v_lshl_add_u64 v[136:137], v[136:137], 0, v[132:133]
	global_load_dwordx2 v[136:137], v[136:137], off
	ds_write2_b64 v148, v[144:145], v[146:147] offset0:192 offset1:196
	s_waitcnt vmcnt(1)
; DI float bflo(unsigned u) { return __uint_as_float(u << 16); }
; DI float bfhi(unsigned u) { return __uint_as_float(u & 0xffff0000u); }
; DI float sigmoidf(float x) { return __builtin_amdgcn_rcpf(1.f + __expf(-x)); }
; template <class F>
; DI void gemm8_epi_staged(f32x4 (&acc)[8][4], int m0, int n0, bf16_t* L0, F f, bf16_t* dst, size_t ld, int nmax) {
;     ...
;     if (wm == half) {
; #pragma unroll
;       for (int i = 0; i < 8; ++i)
; #pragma unroll
;         for (int j = 0; j < 4; ++j) {
;           const int ml = i * 16 + (lane & 15);
;           const int nl = wn * 64 + j * 16 + (lane >> 4) * 4;
;           f32x4 a = acc[i][j];
;           f(m0 + half * 128 + ml, n0 + nl, a);
;           uint2 u;
;           u.x = pack2(a[0], a[1]);
;           u.y = pack2(a[2], a[3]);
;           *(uint2*)(L + ml * 264 + nl) = u;
;         }
; __global__ void __launch_bounds__(512, 2) mega(Params p) {
;     ...
;       gemm8_epi_staged(acc8, m0, n0, lds_all, [&](int m, int n, f32x4& a) {
;         uint2 ub = *(const uint2*)(z + (size_t)m * ZS + C_MB + n);
;         a[0] *= sigmoidf(bflo(ub.x)); a[1] *= sigmoidf(bfhi(ub.x));
;         a[2] *= sigmoidf(bflo(ub.y)); a[3] *= sigmoidf(bfhi(ub.y));
;       }, z + C_RK, ZS, 1024);
	v_lshlrev_b32_e32 v144, 16, v142
	v_and_b32_e32 v142, 0xffff0000, v142
	v_mul_f32_e32 v142, 0xbfb8aa3b, v142
	v_exp_f32_e32 v142, v142
	v_mul_f32_e32 v144, 0xbfb8aa3b, v144
	v_exp_f32_e32 v144, v144
	v_add_f32_e32 v142, 1.0, v142
	v_rcp_f32_e32 v145, v142
	v_lshlrev_b32_e32 v142, 16, v143
	v_and_b32_e32 v143, 0xffff0000, v143
	v_mul_f32_e32 v142, 0xbfb8aa3b, v142
	v_mul_f32_e32 v143, 0xbfb8aa3b, v143
	v_exp_f32_e32 v142, v142
	v_exp_f32_e32 v143, v143
	v_add_f32_e32 v144, 1.0, v144
	v_rcp_f32_e32 v144, v144
	v_add_f32_e32 v142, 1.0, v142
	v_add_f32_e32 v143, 1.0, v143
	v_rcp_f32_e32 v142, v142
	v_rcp_f32_e32 v143, v143
	v_pk_mul_f32 v[144:145], v[22:23], v[144:145]
	v_pk_mul_f32 v[142:143], v[24:25], v[142:143]
	v_cvt_pk_bf16_f32 v144, v144, v145
	v_cvt_pk_bf16_f32 v145, v142, v143
	s_waitcnt vmcnt(0)
	v_lshlrev_b32_e32 v142, 16, v136
	v_and_b32_e32 v136, 0xffff0000, v136
	v_mul_f32_e32 v136, 0xbfb8aa3b, v136
	v_exp_f32_e32 v136, v136
	v_mul_f32_e32 v142, 0xbfb8aa3b, v142
	v_exp_f32_e32 v142, v142
	v_add_f32_e32 v136, 1.0, v136
	v_rcp_f32_e32 v143, v136
	v_lshlrev_b32_e32 v136, 16, v137
	v_and_b32_e32 v137, 0xffff0000, v137
	v_mul_f32_e32 v136, 0xbfb8aa3b, v136
	v_mul_f32_e32 v137, 0xbfb8aa3b, v137
	v_exp_f32_e32 v136, v136
	v_exp_f32_e32 v137, v137
	v_add_f32_e32 v142, 1.0, v142
	v_rcp_f32_e32 v142, v142
	v_add_f32_e32 v136, 1.0, v136
	v_add_f32_e32 v137, 1.0, v137
	v_rcp_f32_e32 v136, v136
	v_rcp_f32_e32 v137, v137
	v_pk_mul_f32 v[142:143], v[18:19], v[142:143]
	v_pk_mul_f32 v[136:137], v[20:21], v[136:137]
	v_cvt_pk_bf16_f32 v142, v142, v143
	v_cvt_pk_bf16_f32 v143, v136, v137
	v_or_b32_e32 v136, 0x70, v141
	v_mul_u32_u24_e32 v136, 0x2a30, v136
	v_mov_b32_e32 v137, v1
	v_lshl_add_u64 v[136:137], s[16:17], 0, v[136:137]
	v_lshl_add_u64 v[136:137], v[136:137], 0, s[6:7]
	ds_write2_b64 v148, v[144:145], v[142:143] offset0:200 offset1:204
	v_lshl_add_u64 v[142:143], v[136:137], 0, v[130:131]
	global_load_dwordx2 v[142:143], v[142:143], off
	v_lshl_add_u64 v[134:135], v[136:137], 0, v[134:135]
	global_load_dwordx2 v[134:135], v[134:135], off
	v_lshl_add_u64 v[132:133], v[136:137], 0, v[132:133]
	global_load_dwordx2 v[132:133], v[132:133], off
	s_waitcnt vmcnt(2)
	v_lshlrev_b32_e32 v131, 16, v142
	v_mul_f32_e32 v131, 0xbfb8aa3b, v131
	v_exp_f32_e32 v131, v131
	s_nop 0
	v_add_f32_e32 v131, 1.0, v131
	v_rcp_f32_e32 v144, v131
	v_and_b32_e32 v131, 0xffff0000, v142
	v_mul_f32_e32 v131, 0xbfb8aa3b, v131
	v_exp_f32_e32 v131, v131
	s_nop 0
	v_add_f32_e32 v131, 1.0, v131
	v_rcp_f32_e32 v145, v131
	v_lshlrev_b32_e32 v131, 16, v143
	v_mul_f32_e32 v131, 0xbfb8aa3b, v131
	v_exp_f32_e32 v131, v131
	v_pk_mul_f32 v[144:145], v[14:15], v[144:145]
	v_add_f32_e32 v131, 1.0, v131
	v_rcp_f32_e32 v142, v131
	v_and_b32_e32 v131, 0xffff0000, v143
	v_mul_f32_e32 v131, 0xbfb8aa3b, v131
	v_exp_f32_e32 v131, v131
	v_cvt_pk_bf16_f32 v144, v144, v145
	v_add_f32_e32 v131, 1.0, v131
	v_rcp_f32_e32 v143, v131
	s_waitcnt vmcnt(1)
	v_lshlrev_b32_e32 v131, 16, v134
	v_mul_f32_e32 v131, 0xbfb8aa3b, v131
	v_exp_f32_e32 v131, v131
	v_pk_mul_f32 v[142:143], v[16:17], v[142:143]
	v_add_f32_e32 v131, 1.0, v131
	v_cvt_pk_bf16_f32 v145, v142, v143
	v_lshl_add_u64 v[142:143], v[136:137], 0, v[0:1]
	global_load_dwordx2 v[142:143], v[142:143], off
	s_waitcnt vmcnt(0)
	v_lshlrev_b32_e32 v0, 16, v142
	v_mul_f32_e32 v0, 0xbfb8aa3b, v0
	v_exp_f32_e32 v0, v0
	s_nop 0
	v_add_f32_e32 v0, 1.0, v0
	v_rcp_f32_e32 v146, v0
	v_and_b32_e32 v0, 0xffff0000, v142
	v_mul_f32_e32 v0, 0xbfb8aa3b, v0
	v_exp_f32_e32 v0, v0
	s_nop 0
	v_add_f32_e32 v0, 1.0, v0
	v_rcp_f32_e32 v147, v0
	v_lshlrev_b32_e32 v0, 16, v143
	v_mul_f32_e32 v0, 0xbfb8aa3b, v0
	v_exp_f32_e32 v0, v0
	v_pk_mul_f32 v[146:147], v[10:11], v[146:147]
	v_add_f32_e32 v0, 1.0, v0
	v_rcp_f32_e32 v142, v0
	v_and_b32_e32 v0, 0xffff0000, v143
	v_mul_f32_e32 v0, 0xbfb8aa3b, v0
	v_exp_f32_e32 v0, v0
	v_cvt_pk_bf16_f32 v146, v146, v147
	v_add_f32_e32 v0, 1.0, v0
	v_rcp_f32_e32 v143, v0
	v_add_u32_e32 v0, 0xe000, v138
	v_pk_mul_f32 v[142:143], v[12:13], v[142:143]
	s_nop 0
	v_cvt_pk_bf16_f32 v147, v142, v143
	v_rcp_f32_e32 v142, v131
	v_and_b32_e32 v131, 0xffff0000, v134
	v_mul_f32_e32 v131, 0xbfb8aa3b, v131
	v_exp_f32_e32 v131, v131
	ds_write2_b64 v0, v[144:145], v[146:147] offset0:224 offset1:228
	v_add_f32_e32 v131, 1.0, v131
	v_rcp_f32_e32 v143, v131
	v_lshlrev_b32_e32 v131, 16, v135
	v_mul_f32_e32 v131, 0xbfb8aa3b, v131
	v_exp_f32_e32 v131, v131
	v_pk_mul_f32 v[142:143], v[6:7], v[142:143]
	v_add_f32_e32 v131, 1.0, v131
	v_rcp_f32_e32 v134, v131
	v_and_b32_e32 v131, 0xffff0000, v135
	v_mul_f32_e32 v131, 0xbfb8aa3b, v131
	v_exp_f32_e32 v131, v131
	s_nop 0
	v_add_f32_e32 v131, 1.0, v131
	v_rcp_f32_e32 v135, v131
	v_lshlrev_b32_e32 v131, 16, v132
	v_mul_f32_e32 v131, 0xbfb8aa3b, v131
	v_exp_f32_e32 v131, v131
	v_pk_mul_f32 v[144:145], v[8:9], v[134:135]
	v_cvt_pk_bf16_f32 v134, v142, v143
	v_cvt_pk_bf16_f32 v135, v144, v145
	v_add_f32_e32 v131, 1.0, v131
	v_rcp_f32_e32 v136, v131
	v_and_b32_e32 v131, 0xffff0000, v132
	v_mul_f32_e32 v131, 0xbfb8aa3b, v131
	v_exp_f32_e32 v131, v131
	s_nop 0
	v_add_f32_e32 v131, 1.0, v131
	v_rcp_f32_e32 v137, v131
	v_lshlrev_b32_e32 v131, 16, v133
	v_mul_f32_e32 v131, 0xbfb8aa3b, v131
	v_exp_f32_e32 v131, v131
	v_pk_mul_f32 v[136:137], v[2:3], v[136:137]
	v_add_f32_e32 v131, 1.0, v131
	v_rcp_f32_e32 v132, v131
	v_and_b32_e32 v131, 0xffff0000, v133
	v_mul_f32_e32 v131, 0xbfb8aa3b, v131
	v_exp_f32_e32 v131, v131
	v_cvt_pk_bf16_f32 v136, v136, v137
	v_add_f32_e32 v131, 1.0, v131
	v_rcp_f32_e32 v133, v131
	s_nop 0
	v_pk_mul_f32 v[132:133], v[4:5], v[132:133]
	s_nop 0
	v_cvt_pk_bf16_f32 v137, v132, v133
	ds_write2_b64 v0, v[134:135], v[136:137] offset0:232 offset1:236

; DI void gemm8_accum(f32x4 (&acc)[8][4], const bf16_t* a, size_t lda, const bf16_t* b, size_t ldb, int nkb, bf16_t* L,
;                     const bool pre, const bf16_t* an, size_t ldan, const bf16_t* bn, size_t ldbn) {
;     ...
;   for (int kb = 0; kb + 2 < nkb; ++kb) {
;     __syncthreads();
;     g8_store1(L + ((kb + 1) & 1) * 32768, ra, lrow, lch);
;     g8_load1o(ra, a + (kb + 2) * 64, offa);
;     __builtin_amdgcn_sched_barrier(0);
;     g8_compute<0, 1>(acc, L + (kb & 1) * 32768, wm, wn, lane);
;     __builtin_amdgcn_sched_barrier(0);
;     g8_store1(L + ((kb + 1) & 1) * 32768 + 16384, rb, lrow, lch);
;     g8_load1o(rb, b + (kb + 2) * 64, offb);
;     __builtin_amdgcn_sched_barrier(0);
;     g8_compute<1, 2>(acc, L + (kb & 1) * 32768, wm, wn, lane);
;   }
.LBB0_830:
	s_add_i32 s3, s2, 0x8000
	s_and_b32 s7, s3, 0x8000
	v_lshl_add_u32 v171, s7, 1, v163
	s_waitcnt lgkmcnt(0)
	s_barrier
	s_cmp_eq_u32 s100, 0
	s_cbranch_scc1 .Lstg_830_a
	v_mfma_f32_16x16x32_bf16 v[158:161], v[234:237], v[198:201], v[158:161]
	v_mfma_f32_16x16x32_bf16 v[154:157], v[238:241], v[198:201], v[154:157]
	v_mfma_f32_16x16x32_bf16 v[150:153], v[242:245], v[198:201], v[150:153]
	v_mfma_f32_16x16x32_bf16 v[146:149], v[246:249], v[198:201], v[146:149]
	v_mfma_f32_16x16x32_bf16 v[142:145], v[234:237], v[206:209], v[142:145]
	v_mfma_f32_16x16x32_bf16 v[138:141], v[238:241], v[206:209], v[138:141]
	v_mfma_f32_16x16x32_bf16 v[134:137], v[242:245], v[206:209], v[134:137]
	v_mfma_f32_16x16x32_bf16 v[130:133], v[246:249], v[206:209], v[130:133]
	v_mfma_f32_16x16x32_bf16 v[126:129], v[234:237], v[210:213], v[126:129]
	v_mfma_f32_16x16x32_bf16 v[122:125], v[238:241], v[210:213], v[122:125]
	v_mfma_f32_16x16x32_bf16 v[118:121], v[242:245], v[210:213], v[118:121]
	v_mfma_f32_16x16x32_bf16 v[114:117], v[246:249], v[210:213], v[114:117]
	v_mfma_f32_16x16x32_bf16 v[110:113], v[234:237], v[214:217], v[110:113]
	v_mfma_f32_16x16x32_bf16 v[106:109], v[238:241], v[214:217], v[106:109]
	v_mfma_f32_16x16x32_bf16 v[102:105], v[242:245], v[214:217], v[102:105]
	v_mfma_f32_16x16x32_bf16 v[98:101], v[246:249], v[214:217], v[98:101]
	v_mfma_f32_16x16x32_bf16 v[94:97], v[234:237], v[218:221], v[94:97]
	v_mfma_f32_16x16x32_bf16 v[90:93], v[238:241], v[218:221], v[90:93]
	v_mfma_f32_16x16x32_bf16 v[86:89], v[242:245], v[218:221], v[86:89]
	v_mfma_f32_16x16x32_bf16 v[82:85], v[246:249], v[218:221], v[82:85]
	v_mfma_f32_16x16x32_bf16 v[78:81], v[234:237], v[222:225], v[78:81]
	v_mfma_f32_16x16x32_bf16 v[74:77], v[238:241], v[222:225], v[74:77]
	v_mfma_f32_16x16x32_bf16 v[70:73], v[242:245], v[222:225], v[70:73]
	v_mfma_f32_16x16x32_bf16 v[66:69], v[246:249], v[222:225], v[66:69]
	v_mfma_f32_16x16x32_bf16 v[62:65], v[234:237], v[226:229], v[62:65]
	v_mfma_f32_16x16x32_bf16 v[58:61], v[238:241], v[226:229], v[58:61]
	v_mfma_f32_16x16x32_bf16 v[54:57], v[242:245], v[226:229], v[54:57]
	v_mfma_f32_16x16x32_bf16 v[50:53], v[246:249], v[226:229], v[50:53]
	v_mfma_f32_16x16x32_bf16 v[46:49], v[234:237], v[230:233], v[46:49]
	v_mfma_f32_16x16x32_bf16 v[42:45], v[238:241], v[230:233], v[42:45]
	v_mfma_f32_16x16x32_bf16 v[38:41], v[242:245], v[230:233], v[38:41]
	v_mfma_f32_16x16x32_bf16 v[34:37], v[246:249], v[230:233], v[34:37]
.Lstg_830_a:
	s_waitcnt vmcnt(7)
	ds_write_b128 v171, v[18:21]
	s_waitcnt vmcnt(6)
	ds_write_b128 v171, v[22:25] offset:8192
	s_waitcnt vmcnt(5)
	ds_write_b128 v171, v[26:29] offset:16384
	s_waitcnt vmcnt(4)
	ds_write_b128 v171, v[30:33] offset:24576
	v_lshl_add_u64 v[18:19], v[192:193], 0, s[0:1]
	v_lshl_add_u64 v[22:23], v[190:191], 0, s[0:1]
	v_lshl_add_u64 v[26:27], v[188:189], 0, s[0:1]
	v_lshl_add_u64 v[30:31], v[186:187], 0, s[0:1]
	global_load_dwordx4 v[18:21], v[18:19], off
	s_nop 0
	global_load_dwordx4 v[22:25], v[22:23], off
	s_nop 0
	global_load_dwordx4 v[26:29], v[26:27], off
	s_nop 0
	global_load_dwordx4 v[30:33], v[30:31], off
	s_and_b32 s2, s2, 0x8000
	s_lshl_b32 s2, s2, 1
	s_add_i32 s2, s2, 0
	v_lshl_add_u32 v173, v169, 1, s2
	v_add_u32_e32 v175, v173, v195
	ds_read_b128 v[198:201], v175
	ds_read_b128 v[206:209], v175 offset:2048
	ds_read_b128 v[210:213], v175 offset:4096
	ds_read_b128 v[214:217], v175 offset:6144
	ds_read_b128 v[218:221], v175 offset:8192
	ds_read_b128 v[222:225], v175 offset:10240
	ds_read_b128 v[226:229], v175 offset:12288
	ds_read_b128 v[230:233], v175 offset:14336
	v_add_u32_e32 v173, v173, v194
	ds_read_b128 v[234:237], v173 offset:32768
	ds_read_b128 v[238:241], v173 offset:34816
	ds_read_b128 v[242:245], v173 offset:36864
	ds_read_b128 v[246:249], v173 offset:38912
	s_waitcnt lgkmcnt(3)
	v_mfma_f32_16x16x32_bf16 v[158:161], v[234:237], v[198:201], v[158:161]
	s_waitcnt lgkmcnt(2)
	v_mfma_f32_16x16x32_bf16 v[154:157], v[238:241], v[198:201], v[154:157]
	s_waitcnt lgkmcnt(1)
	v_mfma_f32_16x16x32_bf16 v[150:153], v[242:245], v[198:201], v[150:153]
	s_waitcnt lgkmcnt(0)
	v_mfma_f32_16x16x32_bf16 v[146:149], v[246:249], v[198:201], v[146:149]
	v_mfma_f32_16x16x32_bf16 v[142:145], v[234:237], v[206:209], v[142:145]
	v_mfma_f32_16x16x32_bf16 v[138:141], v[238:241], v[206:209], v[138:141]
	v_mfma_f32_16x16x32_bf16 v[134:137], v[242:245], v[206:209], v[134:137]
	v_mfma_f32_16x16x32_bf16 v[130:133], v[246:249], v[206:209], v[130:133]
	v_mfma_f32_16x16x32_bf16 v[126:129], v[234:237], v[210:213], v[126:129]
	v_mfma_f32_16x16x32_bf16 v[122:125], v[238:241], v[210:213], v[122:125]
	v_mfma_f32_16x16x32_bf16 v[118:121], v[242:245], v[210:213], v[118:121]
	v_mfma_f32_16x16x32_bf16 v[114:117], v[246:249], v[210:213], v[114:117]
	v_mfma_f32_16x16x32_bf16 v[110:113], v[234:237], v[214:217], v[110:113]
	v_mfma_f32_16x16x32_bf16 v[106:109], v[238:241], v[214:217], v[106:109]
	v_mfma_f32_16x16x32_bf16 v[102:105], v[242:245], v[214:217], v[102:105]
	v_mfma_f32_16x16x32_bf16 v[98:101], v[246:249], v[214:217], v[98:101]
	v_mfma_f32_16x16x32_bf16 v[94:97], v[234:237], v[218:221], v[94:97]
	v_mfma_f32_16x16x32_bf16 v[90:93], v[238:241], v[218:221], v[90:93]
	v_mfma_f32_16x16x32_bf16 v[86:89], v[242:245], v[218:221], v[86:89]
	v_mfma_f32_16x16x32_bf16 v[82:85], v[246:249], v[218:221], v[82:85]
	v_mfma_f32_16x16x32_bf16 v[78:81], v[234:237], v[222:225], v[78:81]
	v_mfma_f32_16x16x32_bf16 v[74:77], v[238:241], v[222:225], v[74:77]
	v_mfma_f32_16x16x32_bf16 v[70:73], v[242:245], v[222:225], v[70:73]
	v_mfma_f32_16x16x32_bf16 v[66:69], v[246:249], v[222:225], v[66:69]
	v_mfma_f32_16x16x32_bf16 v[62:65], v[234:237], v[226:229], v[62:65]
	v_mfma_f32_16x16x32_bf16 v[58:61], v[238:241], v[226:229], v[58:61]
	v_mfma_f32_16x16x32_bf16 v[54:57], v[242:245], v[226:229], v[54:57]
	v_mfma_f32_16x16x32_bf16 v[50:53], v[246:249], v[226:229], v[50:53]
	v_mfma_f32_16x16x32_bf16 v[46:49], v[234:237], v[230:233], v[46:49]
	v_mfma_f32_16x16x32_bf16 v[42:45], v[238:241], v[230:233], v[42:45]
	v_mfma_f32_16x16x32_bf16 v[38:41], v[242:245], v[230:233], v[38:41]
	v_mfma_f32_16x16x32_bf16 v[34:37], v[246:249], v[230:233], v[34:37]
	s_waitcnt vmcnt(7)
; DI void gemm8_accum(f32x4 (&acc)[8][4], const bf16_t* a, size_t lda, const bf16_t* b, size_t ldb, int nkb, bf16_t* L,
;                     const bool pre, const bf16_t* an, size_t ldan, const bf16_t* bn, size_t ldbn) {
;     ...
;     g8_compute<0, 1>(acc, L + (kb & 1) * 32768, wm, wn, lane);
;     __builtin_amdgcn_sched_barrier(0);
;     g8_store1(L + ((kb + 1) & 1) * 32768 + 16384, rb, lrow, lch);
;     g8_load1o(rb, b + (kb + 2) * 64, offb);
;     __builtin_amdgcn_sched_barrier(0);
;     g8_compute<1, 2>(acc, L + (kb & 1) * 32768, wm, wn, lane);
;   }
;   __syncthreads();
	ds_write_b128 v171, v[14:17] offset:32768
	s_waitcnt vmcnt(6)
	ds_write_b128 v171, v[2:5] offset:40960
	s_waitcnt vmcnt(5)
	ds_write_b128 v171, v[6:9] offset:49152
	s_waitcnt vmcnt(4)
	ds_write_b128 v171, v[10:13] offset:57344
	v_lshl_add_u64 v[2:3], v[184:185], 0, s[0:1]
	v_lshl_add_u64 v[4:5], v[182:183], 0, s[0:1]
	v_lshl_add_u64 v[6:7], v[180:181], 0, s[0:1]
	v_lshl_add_u64 v[10:11], v[178:179], 0, s[0:1]
	global_load_dwordx4 v[14:17], v[2:3], off
	s_nop 0
	global_load_dwordx4 v[2:5], v[4:5], off
	s_nop 0
	global_load_dwordx4 v[6:9], v[6:7], off
	s_nop 0
	global_load_dwordx4 v[10:13], v[10:11], off
	v_lshl_add_u32 v171, v205, 1, s2
	v_add_u32_e32 v173, v171, v195
	ds_read_b128 v[198:201], v173
	ds_read_b128 v[206:209], v173 offset:2048
	ds_read_b128 v[210:213], v173 offset:4096
	ds_read_b128 v[214:217], v173 offset:6144
	ds_read_b128 v[218:221], v173 offset:8192
	ds_read_b128 v[222:225], v173 offset:10240
	ds_read_b128 v[226:229], v173 offset:12288
	ds_read_b128 v[230:233], v173 offset:14336
	v_add_u32_e32 v171, v171, v194
	ds_read_b128 v[234:237], v171 offset:32768
	ds_read_b128 v[238:241], v171 offset:34816
	ds_read_b128 v[242:245], v171 offset:36864
	ds_read_b128 v[246:249], v171 offset:38912
	s_cmp_lg_u32 s101, 0
	s_cbranch_scc1 .Lstg_830_b
	s_waitcnt lgkmcnt(3)
	v_mfma_f32_16x16x32_bf16 v[158:161], v[234:237], v[198:201], v[158:161]
	s_waitcnt lgkmcnt(2)
	v_mfma_f32_16x16x32_bf16 v[154:157], v[238:241], v[198:201], v[154:157]
	s_waitcnt lgkmcnt(1)
	v_mfma_f32_16x16x32_bf16 v[150:153], v[242:245], v[198:201], v[150:153]
	s_waitcnt lgkmcnt(0)
	v_mfma_f32_16x16x32_bf16 v[146:149], v[246:249], v[198:201], v[146:149]
	v_mfma_f32_16x16x32_bf16 v[142:145], v[234:237], v[206:209], v[142:145]
	v_mfma_f32_16x16x32_bf16 v[138:141], v[238:241], v[206:209], v[138:141]
	v_mfma_f32_16x16x32_bf16 v[134:137], v[242:245], v[206:209], v[134:137]
	v_mfma_f32_16x16x32_bf16 v[130:133], v[246:249], v[206:209], v[130:133]
	v_mfma_f32_16x16x32_bf16 v[126:129], v[234:237], v[210:213], v[126:129]
	v_mfma_f32_16x16x32_bf16 v[122:125], v[238:241], v[210:213], v[122:125]
	v_mfma_f32_16x16x32_bf16 v[118:121], v[242:245], v[210:213], v[118:121]
	v_mfma_f32_16x16x32_bf16 v[114:117], v[246:249], v[210:213], v[114:117]
	v_mfma_f32_16x16x32_bf16 v[110:113], v[234:237], v[214:217], v[110:113]
	v_mfma_f32_16x16x32_bf16 v[106:109], v[238:241], v[214:217], v[106:109]
	v_mfma_f32_16x16x32_bf16 v[102:105], v[242:245], v[214:217], v[102:105]
	v_mfma_f32_16x16x32_bf16 v[98:101], v[246:249], v[214:217], v[98:101]
	v_mfma_f32_16x16x32_bf16 v[94:97], v[234:237], v[218:221], v[94:97]
	v_mfma_f32_16x16x32_bf16 v[90:93], v[238:241], v[218:221], v[90:93]
	v_mfma_f32_16x16x32_bf16 v[86:89], v[242:245], v[218:221], v[86:89]
	v_mfma_f32_16x16x32_bf16 v[82:85], v[246:249], v[218:221], v[82:85]
	v_mfma_f32_16x16x32_bf16 v[78:81], v[234:237], v[222:225], v[78:81]
	v_mfma_f32_16x16x32_bf16 v[74:77], v[238:241], v[222:225], v[74:77]
	v_mfma_f32_16x16x32_bf16 v[70:73], v[242:245], v[222:225], v[70:73]
	v_mfma_f32_16x16x32_bf16 v[66:69], v[246:249], v[222:225], v[66:69]
	v_mfma_f32_16x16x32_bf16 v[62:65], v[234:237], v[226:229], v[62:65]
	v_mfma_f32_16x16x32_bf16 v[58:61], v[238:241], v[226:229], v[58:61]
	v_mfma_f32_16x16x32_bf16 v[54:57], v[242:245], v[226:229], v[54:57]
	v_mfma_f32_16x16x32_bf16 v[50:53], v[246:249], v[226:229], v[50:53]
	v_mfma_f32_16x16x32_bf16 v[46:49], v[234:237], v[230:233], v[46:49]
	v_mfma_f32_16x16x32_bf16 v[42:45], v[238:241], v[230:233], v[42:45]
	v_mfma_f32_16x16x32_bf16 v[38:41], v[242:245], v[230:233], v[38:41]
	v_mfma_f32_16x16x32_bf16 v[34:37], v[246:249], v[230:233], v[34:37]
.Lstg_830_b:
	s_mov_b32 s100, s101
	s_add_u32 s0, s0, 0x80
	s_addc_u32 s1, s1, 0
	s_cmpk_lg_i32 s0, 0x700
	s_mov_b32 s2, s3
	s_cbranch_scc1 .LBB0_830
	s_cmp_eq_u32 s100, 0
	s_cbranch_scc1 .Lstg_830_c
	s_waitcnt lgkmcnt(0)
	v_mfma_f32_16x16x32_bf16 v[158:161], v[234:237], v[198:201], v[158:161]
	v_mfma_f32_16x16x32_bf16 v[154:157], v[238:241], v[198:201], v[154:157]
	v_mfma_f32_16x16x32_bf16 v[150:153], v[242:245], v[198:201], v[150:153]
	v_mfma_f32_16x16x32_bf16 v[146:149], v[246:249], v[198:201], v[146:149]
	v_mfma_f32_16x16x32_bf16 v[142:145], v[234:237], v[206:209], v[142:145]
	v_mfma_f32_16x16x32_bf16 v[138:141], v[238:241], v[206:209], v[138:141]
	v_mfma_f32_16x16x32_bf16 v[134:137], v[242:245], v[206:209], v[134:137]
	v_mfma_f32_16x16x32_bf16 v[130:133], v[246:249], v[206:209], v[130:133]
	v_mfma_f32_16x16x32_bf16 v[126:129], v[234:237], v[210:213], v[126:129]
	v_mfma_f32_16x16x32_bf16 v[122:125], v[238:241], v[210:213], v[122:125]
	v_mfma_f32_16x16x32_bf16 v[118:121], v[242:245], v[210:213], v[118:121]
	v_mfma_f32_16x16x32_bf16 v[114:117], v[246:249], v[210:213], v[114:117]
	v_mfma_f32_16x16x32_bf16 v[110:113], v[234:237], v[214:217], v[110:113]
	v_mfma_f32_16x16x32_bf16 v[106:109], v[238:241], v[214:217], v[106:109]
	v_mfma_f32_16x16x32_bf16 v[102:105], v[242:245], v[214:217], v[102:105]
	v_mfma_f32_16x16x32_bf16 v[98:101], v[246:249], v[214:217], v[98:101]
	v_mfma_f32_16x16x32_bf16 v[94:97], v[234:237], v[218:221], v[94:97]
	v_mfma_f32_16x16x32_bf16 v[90:93], v[238:241], v[218:221], v[90:93]
	v_mfma_f32_16x16x32_bf16 v[86:89], v[242:245], v[218:221], v[86:89]
	v_mfma_f32_16x16x32_bf16 v[82:85], v[246:249], v[218:221], v[82:85]
	v_mfma_f32_16x16x32_bf16 v[78:81], v[234:237], v[222:225], v[78:81]
	v_mfma_f32_16x16x32_bf16 v[74:77], v[238:241], v[222:225], v[74:77]
	v_mfma_f32_16x16x32_bf16 v[70:73], v[242:245], v[222:225], v[70:73]
	v_mfma_f32_16x16x32_bf16 v[66:69], v[246:249], v[222:225], v[66:69]
	v_mfma_f32_16x16x32_bf16 v[62:65], v[234:237], v[226:229], v[62:65]
	v_mfma_f32_16x16x32_bf16 v[58:61], v[238:241], v[226:229], v[58:61]
	v_mfma_f32_16x16x32_bf16 v[54:57], v[242:245], v[226:229], v[54:57]
	v_mfma_f32_16x16x32_bf16 v[50:53], v[246:249], v[226:229], v[50:53]
	v_mfma_f32_16x16x32_bf16 v[46:49], v[234:237], v[230:233], v[46:49]
	v_mfma_f32_16x16x32_bf16 v[42:45], v[238:241], v[230:233], v[42:45]
	v_mfma_f32_16x16x32_bf16 v[38:41], v[242:245], v[230:233], v[38:41]
	v_mfma_f32_16x16x32_bf16 v[34:37], v[246:249], v[230:233], v[34:37]
	s_mov_b32 s100, 0
; DI void gemm8_accum(f32x4 (&acc)[8][4], const bf16_t* a, size_t lda, const bf16_t* b, size_t ldb, int nkb, bf16_t* L,
;                     const bool pre, const bf16_t* an, size_t ldan, const bf16_t* bn, size_t ldbn) {
;     ...
;   __syncthreads();
;   g8_store1(L + 32768, ra, lrow, lch);
;   g8_load1(ra, an, ldan, 0, lrow, lch);
;   __builtin_amdgcn_sched_barrier(0);
;   g8_compute<0, 1>(acc, L, wm, wn, lane);
;   __builtin_amdgcn_sched_barrier(0);
;   g8_store1(L + 32768 + 16384, rb, lrow, lch);
;   g8_load1(rb, bn, ldbn, 0, lrow, lch);
;   __builtin_amdgcn_sched_barrier(0);
;   g8_compute<1, 2>(acc, L, wm, wn, lane);
.Lstg_830_c:
	v_readlane_b32 s0, v254, 18
	s_add_i32 s12, s13, s0
	s_cmp_gt_u32 s12, 63
	s_cselect_b64 s[0:1], -1, 0
	s_cmp_lt_u32 s12, 64
	s_cselect_b32 s7, s12, s13
	s_lshl_b32 s2, s7, 1
	s_and_b32 s2, s2, 0x7fffffe0
	s_and_b32 s3, s7, 3
	s_or_b32 s2, s3, s2
	v_readlane_b32 s3, v252, 25
	s_or_b32 s2, s2, s3
	s_lshl_b32 s13, s11, 8
	s_mul_hi_u32 s3, s2, 0x2a3000
	s_mul_i32 s2, s2, 0x2a3000
	s_add_u32 s2, s16, s2
	s_addc_u32 s3, s17, s3
	v_mov_b32_e32 v177, v1
	v_mov_b32_e32 v175, v1
	v_mov_b32_e32 v173, v1
	v_lshl_add_u64 v[178:179], v[0:1], 1, s[2:3]
	v_lshl_add_u64 v[180:181], v[176:177], 1, s[2:3]
	v_lshl_add_u64 v[174:175], v[174:175], 1, s[2:3]
	v_lshl_add_u64 v[184:185], v[172:173], 1, s[2:3]
	s_barrier
	global_load_dwordx4 v[176:179], v[178:179], off offset:3632
	s_nop 0
	global_load_dwordx4 v[180:183], v[180:181], off offset:3632
	s_nop 0
	global_load_dwordx4 v[172:175], v[174:175], off offset:3632
	s_nop 0
	global_load_dwordx4 v[184:187], v[184:185], off offset:3632
	s_lshl_b32 s2, s7, 17
	s_and_b32 s2, s2, 0x180000
	v_readlane_b32 s20, v251, 63
	v_readlane_b32 s21, v252, 0
	s_add_u32 s2, s20, s2
	s_addc_u32 s3, s21, 0
	s_add_i32 s7, 0, 0x10000
	v_add3_u32 v0, s7, v165, v167
	s_waitcnt vmcnt(11)
	ds_write_b128 v0, v[18:21]
	s_waitcnt vmcnt(10)
	ds_write_b128 v0, v[22:25] offset:8192
	s_waitcnt vmcnt(9)
	ds_write_b128 v0, v[26:29] offset:16384
	s_waitcnt vmcnt(8)
	ds_write_b128 v0, v[30:33] offset:24576
	v_lshlrev_b32_e32 v0, 1, v169
	v_add_u32_e32 v169, 0, v0
	v_add_u32_e32 v171, v169, v195
	ds_read_b128 v[18:21], v171
	ds_read_b128 v[22:25], v171 offset:2048
	ds_read_b128 v[26:29], v171 offset:4096
	ds_read_b128 v[30:33], v171 offset:6144
	ds_read_b128 v[188:191], v171 offset:8192
	ds_read_b128 v[198:201], v171 offset:10240
	ds_read_b128 v[206:209], v171 offset:12288
	ds_read_b128 v[210:213], v171 offset:14336
	v_add_u32_e32 v169, v169, v194
	ds_read_b128 v[214:217], v169 offset:32768
	ds_read_b128 v[218:221], v169 offset:34816
	ds_read_b128 v[222:225], v169 offset:36864
	ds_read_b128 v[226:229], v169 offset:38912
	s_waitcnt lgkmcnt(3)
	v_mfma_f32_16x16x32_bf16 v[158:161], v[214:217], v[18:21], v[158:161]
	s_waitcnt lgkmcnt(2)
	v_mfma_f32_16x16x32_bf16 v[154:157], v[218:221], v[18:21], v[154:157]
	s_waitcnt lgkmcnt(1)
	v_mfma_f32_16x16x32_bf16 v[150:153], v[222:225], v[18:21], v[150:153]
	s_waitcnt lgkmcnt(0)
	v_mfma_f32_16x16x32_bf16 v[18:21], v[226:229], v[18:21], v[146:149]
	v_mfma_f32_16x16x32_bf16 v[142:145], v[214:217], v[22:25], v[142:145]
	v_mfma_f32_16x16x32_bf16 v[138:141], v[218:221], v[22:25], v[138:141]
	v_mfma_f32_16x16x32_bf16 v[134:137], v[222:225], v[22:25], v[134:137]
	v_mfma_f32_16x16x32_bf16 v[22:25], v[226:229], v[22:25], v[130:133]
	v_mfma_f32_16x16x32_bf16 v[126:129], v[214:217], v[26:29], v[126:129]
	v_mfma_f32_16x16x32_bf16 v[122:125], v[218:221], v[26:29], v[122:125]
	v_mfma_f32_16x16x32_bf16 v[118:121], v[222:225], v[26:29], v[118:121]
	v_mfma_f32_16x16x32_bf16 v[26:29], v[226:229], v[26:29], v[114:117]
	v_mfma_f32_16x16x32_bf16 v[110:113], v[214:217], v[30:33], v[110:113]
	v_mfma_f32_16x16x32_bf16 v[106:109], v[218:221], v[30:33], v[106:109]
	v_mfma_f32_16x16x32_bf16 v[102:105], v[222:225], v[30:33], v[102:105]
	v_mfma_f32_16x16x32_bf16 v[30:33], v[226:229], v[30:33], v[98:101]
	v_mfma_f32_16x16x32_bf16 v[94:97], v[214:217], v[188:191], v[94:97]
	v_mfma_f32_16x16x32_bf16 v[90:93], v[218:221], v[188:191], v[90:93]
	v_mfma_f32_16x16x32_bf16 v[86:89], v[222:225], v[188:191], v[86:89]
	v_mfma_f32_16x16x32_bf16 v[82:85], v[226:229], v[188:191], v[82:85]
	v_mfma_f32_16x16x32_bf16 v[78:81], v[214:217], v[198:201], v[78:81]
	v_mfma_f32_16x16x32_bf16 v[74:77], v[218:221], v[198:201], v[74:77]
	v_mfma_f32_16x16x32_bf16 v[70:73], v[222:225], v[198:201], v[70:73]
	v_mfma_f32_16x16x32_bf16 v[66:69], v[226:229], v[198:201], v[66:69]
	v_mfma_f32_16x16x32_bf16 v[62:65], v[214:217], v[206:209], v[62:65]
	v_mfma_f32_16x16x32_bf16 v[58:61], v[218:221], v[206:209], v[58:61]
	v_mfma_f32_16x16x32_bf16 v[54:57], v[222:225], v[206:209], v[54:57]
	v_mfma_f32_16x16x32_bf16 v[50:53], v[226:229], v[206:209], v[50:53]
	v_mfma_f32_16x16x32_bf16 v[46:49], v[214:217], v[210:213], v[46:49]
	v_mfma_f32_16x16x32_bf16 v[38:41], v[222:225], v[210:213], v[38:41]
	v_mfma_f32_16x16x32_bf16 v[34:37], v[226:229], v[210:213], v[34:37]
	v_mfma_f32_16x16x32_bf16 v[42:45], v[218:221], v[210:213], v[42:45]
	v_readlane_b32 s20, v254, 36
	v_mov_b32_e32 v171, v1
	v_mov_b32_e32 v169, v1
	v_add3_u32 v98, s20, v165, v167
	v_mov_b32_e32 v167, v1
	v_mov_b32_e32 v165, v1
	s_waitcnt vmcnt(7)
	ds_write_b128 v98, v[14:17]
	s_waitcnt vmcnt(6)
	ds_write_b128 v98, v[2:5] offset:8192
	s_waitcnt vmcnt(5)
	ds_write_b128 v98, v[6:9] offset:16384
	s_waitcnt vmcnt(4)
	ds_write_b128 v98, v[10:13] offset:24576
	v_lshl_add_u64 v[2:3], v[170:171], 1, s[2:3]
	v_lshl_add_u64 v[6:7], v[168:169], 1, s[2:3]
	v_lshl_add_u64 v[10:11], v[166:167], 1, s[2:3]
	v_lshl_add_u64 v[14:15], v[164:165], 1, s[2:3]
	global_load_dwordx4 v[2:5], v[2:3], off
	s_nop 0
	global_load_dwordx4 v[6:9], v[6:7], off
	s_nop 0
	global_load_dwordx4 v[10:13], v[10:11], off
	s_nop 0
	global_load_dwordx4 v[14:17], v[14:15], off
	v_lshlrev_b32_e32 v192, 1, v205
	v_add_u32_e32 v193, 0, v192
	v_add_u32_e32 v198, v193, v195
	ds_read_b128 v[98:101], v198
	ds_read_b128 v[114:117], v198 offset:2048
	ds_read_b128 v[130:133], v198 offset:4096
	ds_read_b128 v[146:149], v198 offset:6144
	ds_read_b128 v[164:167], v198 offset:8192
	ds_read_b128 v[168:171], v198 offset:10240
	ds_read_b128 v[188:191], v198 offset:12288
	ds_read_b128 v[198:201], v198 offset:14336
	v_add_u32_e32 v193, v193, v194
	ds_read_b128 v[206:209], v193 offset:32768
	ds_read_b128 v[210:213], v193 offset:34816
	ds_read_b128 v[214:217], v193 offset:36864
	ds_read_b128 v[218:221], v193 offset:38912
	s_waitcnt lgkmcnt(3)
; DI void gemm8_accum(f32x4 (&acc)[8][4], const bf16_t* a, size_t lda, const bf16_t* b, size_t ldb, int nkb, bf16_t* L,
;                     const bool pre, const bf16_t* an, size_t ldan, const bf16_t* bn, size_t ldbn) {
;     ...
;   __syncthreads();
;   g8_store1(L + 32768, ra, lrow, lch);
;   g8_load1(ra, an, ldan, 0, lrow, lch);
;   __builtin_amdgcn_sched_barrier(0);
;   g8_compute<0, 1>(acc, L, wm, wn, lane);
;   __builtin_amdgcn_sched_barrier(0);
;   g8_store1(L + 32768 + 16384, rb, lrow, lch);
;   g8_load1(rb, bn, ldbn, 0, lrow, lch);
;   __builtin_amdgcn_sched_barrier(0);
;   g8_compute<1, 2>(acc, L, wm, wn, lane);
;   __syncthreads();
;   g8_store1(L, ra, lrow, lch);
;   __builtin_amdgcn_sched_barrier(0);
;   g8_compute<0, 1>(acc, L + 32768, wm, wn, lane);
;   __builtin_amdgcn_sched_barrier(0);
;   g8_store1(L + 16384, rb, lrow, lch);
;   __builtin_amdgcn_sched_barrier(0);
;   g8_compute<1, 2>(acc, L + 32768, wm, wn, lane);
	v_mfma_f32_16x16x32_bf16 v[158:161], v[206:209], v[98:101], v[158:161]
	s_waitcnt lgkmcnt(2)
	v_mfma_f32_16x16x32_bf16 v[154:157], v[210:213], v[98:101], v[154:157]
	s_waitcnt lgkmcnt(1)
	v_mfma_f32_16x16x32_bf16 v[150:153], v[214:217], v[98:101], v[150:153]
	s_waitcnt lgkmcnt(0)
	v_mfma_f32_16x16x32_bf16 v[18:21], v[218:221], v[98:101], v[18:21]
	v_mfma_f32_16x16x32_bf16 v[98:101], v[206:209], v[114:117], v[142:145]
	v_mfma_f32_16x16x32_bf16 v[138:141], v[210:213], v[114:117], v[138:141]
	v_mfma_f32_16x16x32_bf16 v[134:137], v[214:217], v[114:117], v[134:137]
	v_mfma_f32_16x16x32_bf16 v[22:25], v[218:221], v[114:117], v[22:25]
	v_mfma_f32_16x16x32_bf16 v[114:117], v[206:209], v[130:133], v[126:129]
	v_mfma_f32_16x16x32_bf16 v[122:125], v[210:213], v[130:133], v[122:125]
	v_mfma_f32_16x16x32_bf16 v[118:121], v[214:217], v[130:133], v[118:121]
	v_mfma_f32_16x16x32_bf16 v[26:29], v[218:221], v[130:133], v[26:29]
	v_mfma_f32_16x16x32_bf16 v[110:113], v[206:209], v[146:149], v[110:113]
	v_mfma_f32_16x16x32_bf16 v[106:109], v[210:213], v[146:149], v[106:109]
	v_mfma_f32_16x16x32_bf16 v[102:105], v[214:217], v[146:149], v[102:105]
	v_mfma_f32_16x16x32_bf16 v[30:33], v[218:221], v[146:149], v[30:33]
	v_mfma_f32_16x16x32_bf16 v[94:97], v[206:209], v[164:167], v[94:97]
	v_mfma_f32_16x16x32_bf16 v[90:93], v[210:213], v[164:167], v[90:93]
	v_mfma_f32_16x16x32_bf16 v[86:89], v[214:217], v[164:167], v[86:89]
	v_mfma_f32_16x16x32_bf16 v[82:85], v[218:221], v[164:167], v[82:85]
	v_mfma_f32_16x16x32_bf16 v[78:81], v[206:209], v[168:171], v[78:81]
	v_mfma_f32_16x16x32_bf16 v[74:77], v[210:213], v[168:171], v[74:77]
	v_mfma_f32_16x16x32_bf16 v[70:73], v[214:217], v[168:171], v[70:73]
	v_mfma_f32_16x16x32_bf16 v[66:69], v[218:221], v[168:171], v[66:69]
	v_mfma_f32_16x16x32_bf16 v[62:65], v[206:209], v[188:191], v[62:65]
	v_mfma_f32_16x16x32_bf16 v[58:61], v[210:213], v[188:191], v[58:61]
	v_mfma_f32_16x16x32_bf16 v[54:57], v[214:217], v[188:191], v[54:57]
	v_mfma_f32_16x16x32_bf16 v[50:53], v[218:221], v[188:191], v[50:53]
	v_mfma_f32_16x16x32_bf16 v[46:49], v[206:209], v[198:201], v[46:49]
	v_mfma_f32_16x16x32_bf16 v[38:41], v[214:217], v[198:201], v[38:41]
	v_mfma_f32_16x16x32_bf16 v[34:37], v[218:221], v[198:201], v[34:37]
	v_mfma_f32_16x16x32_bf16 v[42:45], v[210:213], v[198:201], v[42:45]
	s_barrier
	s_waitcnt vmcnt(7)
	ds_write_b128 v163, v[176:179]
	s_waitcnt vmcnt(6)
	ds_write_b128 v163, v[180:183] offset:8192
	s_waitcnt vmcnt(5)
	ds_write_b128 v163, v[172:175] offset:16384
	s_waitcnt vmcnt(4)
	ds_write_b128 v163, v[184:187] offset:24576
	v_add3_u32 v176, s7, v0, v195
	ds_read_b128 v[126:129], v176
	ds_read_b128 v[130:133], v176 offset:2048
	ds_read_b128 v[142:145], v176 offset:4096
	ds_read_b128 v[146:149], v176 offset:6144
	ds_read_b128 v[164:167], v176 offset:8192
	ds_read_b128 v[168:171], v176 offset:10240
	ds_read_b128 v[172:175], v176 offset:12288
	ds_read_b128 v[176:179], v176 offset:14336
	v_add3_u32 v0, s20, v0, v194
	ds_read_b128 v[180:183], v0
	ds_read_b128 v[184:187], v0 offset:2048
	ds_read_b128 v[188:191], v0 offset:4096
	ds_read_b128 v[198:201], v0 offset:6144
	s_waitcnt lgkmcnt(3)
	v_mfma_f32_16x16x32_bf16 v[158:161], v[180:183], v[126:129], v[158:161]
	s_waitcnt lgkmcnt(2)
	v_mfma_f32_16x16x32_bf16 v[154:157], v[184:187], v[126:129], v[154:157]
	s_waitcnt lgkmcnt(1)
	v_mfma_f32_16x16x32_bf16 v[150:153], v[188:191], v[126:129], v[150:153]
	s_waitcnt lgkmcnt(0)
	v_mfma_f32_16x16x32_bf16 v[18:21], v[198:201], v[126:129], v[18:21]
	v_mfma_f32_16x16x32_bf16 v[98:101], v[180:183], v[130:133], v[98:101]
	v_mfma_f32_16x16x32_bf16 v[126:129], v[184:187], v[130:133], v[138:141]
	v_mfma_f32_16x16x32_bf16 v[134:137], v[188:191], v[130:133], v[134:137]
	v_mfma_f32_16x16x32_bf16 v[22:25], v[198:201], v[130:133], v[22:25]
	v_mfma_f32_16x16x32_bf16 v[114:117], v[180:183], v[142:145], v[114:117]
	v_mfma_f32_16x16x32_bf16 v[122:125], v[184:187], v[142:145], v[122:125]
	v_mfma_f32_16x16x32_bf16 v[118:121], v[188:191], v[142:145], v[118:121]
	v_mfma_f32_16x16x32_bf16 v[26:29], v[198:201], v[142:145], v[26:29]
	v_mfma_f32_16x16x32_bf16 v[130:133], v[180:183], v[146:149], v[110:113]
	v_mfma_f32_16x16x32_bf16 v[30:33], v[198:201], v[146:149], v[30:33]
	v_mfma_f32_16x16x32_bf16 v[138:141], v[184:187], v[146:149], v[106:109]
	v_mfma_f32_16x16x32_bf16 v[142:145], v[188:191], v[146:149], v[102:105]
	v_mfma_f32_16x16x32_bf16 v[146:149], v[180:183], v[164:167], v[94:97]
	v_mfma_f32_16x16x32_bf16 v[206:209], v[184:187], v[164:167], v[90:93]
	v_mfma_f32_16x16x32_bf16 v[210:213], v[188:191], v[164:167], v[86:89]
	v_mfma_f32_16x16x32_bf16 v[164:167], v[198:201], v[164:167], v[82:85]
	v_mfma_f32_16x16x32_bf16 v[214:217], v[180:183], v[168:171], v[78:81]
	v_mfma_f32_16x16x32_bf16 v[218:221], v[184:187], v[168:171], v[74:77]
	v_mfma_f32_16x16x32_bf16 v[222:225], v[188:191], v[168:171], v[70:73]
	v_mfma_f32_16x16x32_bf16 v[168:171], v[198:201], v[168:171], v[66:69]
	v_mfma_f32_16x16x32_bf16 v[226:229], v[180:183], v[172:175], v[62:65]
	v_mfma_f32_16x16x32_bf16 v[230:233], v[184:187], v[172:175], v[58:61]
	v_mfma_f32_16x16x32_bf16 v[234:237], v[188:191], v[172:175], v[54:57]
	v_mfma_f32_16x16x32_bf16 v[172:175], v[198:201], v[172:175], v[50:53]
	v_mfma_f32_16x16x32_bf16 v[180:183], v[180:183], v[176:179], v[46:49]
	v_mfma_f32_16x16x32_bf16 v[184:187], v[184:187], v[176:179], v[42:45]
	v_mfma_f32_16x16x32_bf16 v[188:191], v[188:191], v[176:179], v[38:41]
	v_mfma_f32_16x16x32_bf16 v[176:179], v[198:201], v[176:179], v[34:37]
	s_waitcnt vmcnt(3)
	ds_write_b128 v163, v[2:5] offset:32768
	s_waitcnt vmcnt(2)
	ds_write_b128 v163, v[6:9] offset:40960
	s_waitcnt vmcnt(1)
; DI int TID8() { int t = threadIdx.x; asm volatile("" : "+v"(t)); return t; }
; DI void gemm8_accum(f32x4 (&acc)[8][4], const bf16_t* a, size_t lda, const bf16_t* b, size_t ldb, int nkb, bf16_t* L,
;                     const bool pre, const bf16_t* an, size_t ldan, const bf16_t* bn, size_t ldbn) {
;     ...
;   g8_compute<1, 2>(acc, L, wm, wn, lane);
;   __syncthreads();
;   g8_store1(L, ra, lrow, lch);
;   __builtin_amdgcn_sched_barrier(0);
;   g8_compute<0, 1>(acc, L + 32768, wm, wn, lane);
;   __builtin_amdgcn_sched_barrier(0);
;   g8_store1(L + 16384, rb, lrow, lch);
;   __builtin_amdgcn_sched_barrier(0);
;   g8_compute<1, 2>(acc, L + 32768, wm, wn, lane);
;   __syncthreads();
; }
; DI void gemm8_epi_resid(f32x4 (&acc)[8][4], int m0, int n0, int ntile8, bf16_t* L, const float* xin, float* out, bf16_t* xb, float* rowpart) {
;   const int tid = TID8(), lane = tid & 63, w = tid >> 6;
;   const int wm = w >> 2, wn = w & 3;
;   float* red = (float*)(L + 32768);
; #pragma unroll
;   for (int i = 0; i < 8; ++i) {
;     const int ml = wm * 128 + i * 16 + (lane & 15);
;     const size_t rowoff = (size_t)(m0 + ml) * DM;
;     float ss = 0.f;
; #pragma unroll
;     for (int j = 0; j < 4; ++j) {
;       const int n = n0 + wn * 64 + j * 16 + (lane >> 4) * 4;
;       const float4 xv = *(const float4*)(xin + rowoff + n);
;       const float o0 = xv.x + acc[i][j][0], o1 = xv.y + acc[i][j][1], o2 = xv.z + acc[i][j][2], o3 = xv.w + acc[i][j][3];
	ds_write_b128 v163, v[10:13] offset:49152
	s_waitcnt vmcnt(0)
	ds_write_b128 v163, v[14:17] offset:57344
	v_add3_u32 v0, s7, v192, v195
	ds_read_b128 v[2:5], v0
	ds_read_b128 v[6:9], v0 offset:2048
	ds_read_b128 v[10:13], v0 offset:4096
	ds_read_b128 v[14:17], v0 offset:6144
	ds_read_b128 v[34:37], v0 offset:8192
	ds_read_b128 v[198:201], v0 offset:10240
	ds_read_b128 v[238:241], v0 offset:12288
	ds_read_b128 v[242:245], v0 offset:14336
	v_add3_u32 v0, s20, v192, v194
	ds_read_b128 v[192:195], v0
	ds_read_b128 v[246:249], v0 offset:2048
	ds_read_b128 v[38:41], v0 offset:4096
	ds_read_b128 v[42:45], v0 offset:6144
	s_waitcnt lgkmcnt(3)
	v_mfma_f32_16x16x32_bf16 v[158:161], v[192:195], v[2:5], v[158:161]
	s_waitcnt lgkmcnt(2)
	v_mfma_f32_16x16x32_bf16 v[154:157], v[246:249], v[2:5], v[154:157]
	s_waitcnt lgkmcnt(1)
	v_mfma_f32_16x16x32_bf16 v[150:153], v[38:41], v[2:5], v[150:153]
	s_waitcnt lgkmcnt(0)
	v_mfma_f32_16x16x32_bf16 v[2:5], v[42:45], v[2:5], v[18:21]
	v_mfma_f32_16x16x32_bf16 v[110:113], v[192:195], v[6:9], v[98:101]
	v_mfma_f32_16x16x32_bf16 v[106:109], v[246:249], v[6:9], v[126:129]
	v_mfma_f32_16x16x32_bf16 v[102:105], v[38:41], v[6:9], v[134:137]
	v_mfma_f32_16x16x32_bf16 v[98:101], v[42:45], v[6:9], v[22:25]
	v_mfma_f32_16x16x32_bf16 v[94:97], v[192:195], v[10:13], v[114:117]
	v_mfma_f32_16x16x32_bf16 v[90:93], v[246:249], v[10:13], v[122:125]
	v_mfma_f32_16x16x32_bf16 v[86:89], v[38:41], v[10:13], v[118:121]
	v_mfma_f32_16x16x32_bf16 v[82:85], v[42:45], v[10:13], v[26:29]
	v_mfma_f32_16x16x32_bf16 v[78:81], v[192:195], v[14:17], v[130:133]
	v_mfma_f32_16x16x32_bf16 v[74:77], v[246:249], v[14:17], v[138:141]
	v_mfma_f32_16x16x32_bf16 v[70:73], v[38:41], v[14:17], v[142:145]
	v_mfma_f32_16x16x32_bf16 v[66:69], v[42:45], v[14:17], v[30:33]
	v_mfma_f32_16x16x32_bf16 v[62:65], v[192:195], v[34:37], v[146:149]
	v_mfma_f32_16x16x32_bf16 v[58:61], v[246:249], v[34:37], v[206:209]
	v_mfma_f32_16x16x32_bf16 v[54:57], v[38:41], v[34:37], v[210:213]
	v_mfma_f32_16x16x32_bf16 v[50:53], v[42:45], v[34:37], v[164:167]
	v_mfma_f32_16x16x32_bf16 v[46:49], v[192:195], v[198:201], v[214:217]
	v_mfma_f32_16x16x32_bf16 v[128:131], v[246:249], v[198:201], v[218:221]
	v_mfma_f32_16x16x32_bf16 v[124:127], v[38:41], v[198:201], v[222:225]
	v_mfma_f32_16x16x32_bf16 v[34:37], v[42:45], v[198:201], v[168:171]
	v_mfma_f32_16x16x32_bf16 v[30:33], v[192:195], v[238:241], v[226:229]
	v_mfma_f32_16x16x32_bf16 v[26:29], v[246:249], v[238:241], v[230:233]
	v_mfma_f32_16x16x32_bf16 v[22:25], v[38:41], v[238:241], v[234:237]
	v_mfma_f32_16x16x32_bf16 v[18:21], v[42:45], v[238:241], v[172:175]
	v_mfma_f32_16x16x32_bf16 v[14:17], v[192:195], v[242:245], v[180:183]
	v_mfma_f32_16x16x32_bf16 v[10:13], v[246:249], v[242:245], v[184:187]
	v_mfma_f32_16x16x32_bf16 v[6:9], v[38:41], v[242:245], v[188:191]
	v_mfma_f32_16x16x32_bf16 v[38:41], v[42:45], v[242:245], v[176:179]
	v_mov_b32_e32 v118, v196
	s_barrier
	s_movk_i32 s2, 0xff80
	v_ashrrev_i32_e32 v0, 1, v118
	v_and_b32_e32 v42, 15, v118
	v_and_or_b32 v121, v0, s2, v42
	v_bfe_u32 v119, v118, 6, 2
	v_lshrrev_b32_e32 v42, 2, v118
	v_add_u32_e32 v116, s6, v121
	v_lshlrev_b32_e32 v0, 6, v119
	v_and_b32_e32 v42, 12, v42
	v_ashrrev_i32_e32 v117, 31, v116
	v_readlane_b32 s2, v254, 51
	v_or3_b32 v114, v42, s13, v0
	v_lshlrev_b64 v[122:123], 12, v[116:117]
	v_readlane_b32 s3, v254, 52
	v_lshlrev_b32_e32 v0, 2, v114
	v_readlane_b32 s24, v251, 33
	v_lshl_add_u64 v[42:43], s[2:3], 0, v[122:123]
	v_lshl_add_u64 v[140:141], v[42:43], 0, v[0:1]
	v_lshlrev_b64 v[132:133], 11, v[116:117]
	v_readlane_b32 s26, v251, 35
	v_readlane_b32 s27, v251, 36
	v_mov_b32_e32 v115, v1
	v_lshlrev_b32_e32 v114, 1, v114
	v_lshl_add_u64 v[122:123], s[26:27], 0, v[122:123]
	v_lshl_add_u64 v[132:133], s[18:19], 0, v[132:133]
	v_lshl_add_u64 v[122:123], v[122:123], 0, v[0:1]
	v_lshl_add_u64 v[144:145], v[132:133], 0, v[114:115]
	v_and_b32_e32 v146, 63, v118
	v_lshlrev_b32_e32 v120, 2, v146
	v_xor_b32_e32 v117, 64, v120
	v_xor_b32_e32 v120, 0x80, v120
	v_cmp_gt_u32_e32 vcc, 16, v146
	v_readlane_b32 s25, v251, 34
	v_lshl_add_u32 v188, v119, 10, s7
	v_lshl_add_u32 v188, v121, 2, v188
	v_mov_b32_e32 v189, v117
	v_mov_b32_e32 v190, v120
	v_and_b32_e32 v240, 63, v118
	v_cmp_gt_u32_e64 s[88:89], 16, v240
	v_and_b32_e32 v243, 15, v118
	v_bfe_u32 v242, v118, 4, 2
	v_and_b32_e32 v240, 8, v243
	v_cmp_eq_u32_e64 s[90:91], 0, v240
	v_lshlrev_b32_e32 v236, 12, v243
	v_lshl_or_b32 v236, v242, 4, v236
	v_lshlrev_b32_e32 v237, 11, v243
	v_lshl_or_b32 v237, v242, 3, v237
	v_sub_co_u32_e32 v238, vcc, v140, v236
	v_subbrev_co_u32_e32 v239, vcc, 0, v141, vcc
	s_nop 0
	v_readfirstlane_b32 s40, v238
	v_readfirstlane_b32 s41, v239
	v_sub_co_u32_e32 v238, vcc, v122, v236
	v_subbrev_co_u32_e32 v239, vcc, 0, v123, vcc
	s_nop 0
	v_readfirstlane_b32 s44, v238
	v_readfirstlane_b32 s45, v239
	v_sub_co_u32_e32 v238, vcc, v144, v237
	v_subbrev_co_u32_e32 v239, vcc, 0, v145, vcc
	s_nop 0
	v_readfirstlane_b32 s48, v238
	v_readfirstlane_b32 s49, v239
	s_add_u32 s42, s40, 0x8000
	s_addc_u32 s43, s41, 0
	s_add_u32 s46, s44, 0x8000
	s_addc_u32 s47, s45, 0
	s_add_u32 s50, s48, 0x4000
	s_addc_u32 s51, s49, 0
	v_and_b32_e32 v238, 7, v243
	v_lshrrev_b32_e32 v239, 3, v243
	v_lshlrev_b32_e32 v244, 12, v238
	v_lshl_or_b32 v244, v239, 6, v244
	v_lshl_or_b32 v244, v242, 4, v244
	v_lshlrev_b32_e32 v245, 11, v238
	v_lshl_or_b32 v245, v239, 5, v245
	v_lshl_or_b32 v245, v242, 3, v245
	global_load_dwordx4 v[192:195], v244, s[40:41]
	global_load_dwordx4 v[198:201], v244, s[40:41] offset:128
	global_load_dwordx4 v[202:205], v244, s[42:43]
	global_load_dwordx4 v[206:209], v244, s[42:43] offset:128
	s_add_u32 s40, s40, 0x10000
	s_addc_u32 s41, s41, 0
	s_add_u32 s42, s42, 0x10000
	s_addc_u32 s43, s43, 0
	global_load_dwordx4 v[216:219], v244, s[40:41]
	global_load_dwordx4 v[220:223], v244, s[40:41] offset:128
	global_load_dwordx4 v[224:227], v244, s[42:43]
	global_load_dwordx4 v[228:231], v244, s[42:43] offset:128
	s_add_u32 s40, s40, 0x10000
	s_addc_u32 s41, s41, 0
	s_add_u32 s42, s42, 0x10000
	s_addc_u32 s43, s43, 0
	s_waitcnt vmcnt(4)
; DI void gemm8_epi_resid(f32x4 (&acc)[8][4], int m0, int n0, int ntile8, bf16_t* L, const float* xin, float* out, bf16_t* xb, float* rowpart) {
;     ...
;   for (int i = 0; i < 8; ++i) {
;     const int ml = wm * 128 + i * 16 + (lane & 15);
;     const size_t rowoff = (size_t)(m0 + ml) * DM;
;     float ss = 0.f;
; #pragma unroll
;     for (int j = 0; j < 4; ++j) {
;       const int n = n0 + wn * 64 + j * 16 + (lane >> 4) * 4;
;       const float4 xv = *(const float4*)(xin + rowoff + n);
;       const float o0 = xv.x + acc[i][j][0], o1 = xv.y + acc[i][j][1], o2 = xv.z + acc[i][j][2], o3 = xv.w + acc[i][j][3];
;       *(float4*)(out + rowoff + n) = make_float4(o0, o1, o2, o3);
;       ss += o0 * o0 + o1 * o1 + o2 * o2 + o3 * o3;
;       uint2 u;
;       u.x = pack2(o0, o1);
;       u.y = pack2(o2, o3);
;       *(uint2*)(xb + rowoff + n) = u;
;     }
;     ss += shx(ss, 16, lane);
;     ss += shx(ss, 32, lane);
;     if ((lane >> 4) == 0) red[wn * 256 + ml] = ss;
;   }
	v_mov_b32_dpp v232, v154 row_ror:8 row_mask:0xf bank_mask:0xf
	v_mov_b32_dpp v233, v155 row_ror:8 row_mask:0xf bank_mask:0xf
	v_mov_b32_dpp v234, v156 row_ror:8 row_mask:0xf bank_mask:0xf
	v_mov_b32_dpp v235, v157 row_ror:8 row_mask:0xf bank_mask:0xf
	v_cndmask_b32_e64 v232, v232, v158, s[90:91]
	v_cndmask_b32_e64 v233, v233, v159, s[90:91]
	v_cndmask_b32_e64 v234, v234, v160, s[90:91]
	v_cndmask_b32_e64 v235, v235, v161, s[90:91]
	v_pk_add_f32 v[232:233], v[232:233], v[192:193]
	v_pk_add_f32 v[234:235], v[234:235], v[194:195]
	s_nop 0
	global_store_dwordx4 v244, v[232:235], s[44:45]
	v_cvt_pk_bf16_f32 v240, v232, v233
	v_cvt_pk_bf16_f32 v241, v234, v235
	v_pk_mul_f32 v[236:237], v[232:233], v[232:233]
	v_pk_mul_f32 v[238:239], v[234:235], v[234:235]
	global_store_dwordx2 v245, v[240:241], s[48:49]
	v_add_f32_e32 v242, v236, v237
	v_add_f32_e32 v242, v242, v238
	v_add_f32_e32 v242, v242, v239
	v_mov_b32_dpp v232, v158 row_ror:8 row_mask:0xf bank_mask:0xf
	v_mov_b32_dpp v233, v159 row_ror:8 row_mask:0xf bank_mask:0xf
	v_mov_b32_dpp v234, v160 row_ror:8 row_mask:0xf bank_mask:0xf
	v_mov_b32_dpp v235, v161 row_ror:8 row_mask:0xf bank_mask:0xf
	v_cndmask_b32_e64 v232, v154, v232, s[90:91]
	v_cndmask_b32_e64 v233, v155, v233, s[90:91]
	v_cndmask_b32_e64 v234, v156, v234, s[90:91]
	v_cndmask_b32_e64 v235, v157, v235, s[90:91]
	v_pk_add_f32 v[232:233], v[232:233], v[202:203]
	v_pk_add_f32 v[234:235], v[234:235], v[204:205]
	s_nop 0
	global_store_dwordx4 v244, v[232:235], s[46:47]
	v_cvt_pk_bf16_f32 v240, v232, v233
	v_cvt_pk_bf16_f32 v241, v234, v235
	v_pk_mul_f32 v[236:237], v[232:233], v[232:233]
	v_pk_mul_f32 v[238:239], v[234:235], v[234:235]
	global_store_dwordx2 v245, v[240:241], s[50:51]
	v_add_f32_e32 v191, v236, v237
	v_add_f32_e32 v191, v191, v238
	v_add_f32_e32 v191, v191, v239
	v_mov_b32_dpp v232, v2 row_ror:8 row_mask:0xf bank_mask:0xf
	v_mov_b32_dpp v233, v3 row_ror:8 row_mask:0xf bank_mask:0xf
	v_mov_b32_dpp v234, v4 row_ror:8 row_mask:0xf bank_mask:0xf
	v_mov_b32_dpp v235, v5 row_ror:8 row_mask:0xf bank_mask:0xf
	v_cndmask_b32_e64 v232, v232, v150, s[90:91]
	v_cndmask_b32_e64 v233, v233, v151, s[90:91]
	v_cndmask_b32_e64 v234, v234, v152, s[90:91]
	v_cndmask_b32_e64 v235, v235, v153, s[90:91]
	v_pk_add_f32 v[232:233], v[232:233], v[198:199]
	v_pk_add_f32 v[234:235], v[234:235], v[200:201]
	s_nop 0
	global_store_dwordx4 v244, v[232:235], s[44:45] offset:128
	v_cvt_pk_bf16_f32 v240, v232, v233
	v_cvt_pk_bf16_f32 v241, v234, v235
	v_pk_mul_f32 v[236:237], v[232:233], v[232:233]
	v_pk_mul_f32 v[238:239], v[234:235], v[234:235]
	global_store_dwordx2 v245, v[240:241], s[48:49] offset:64
	v_add_f32_e32 v242, v242, v236
	v_add_f32_e32 v242, v242, v237
	v_add_f32_e32 v242, v242, v238
	v_add_f32_e32 v242, v242, v239
	v_mov_b32_dpp v232, v150 row_ror:8 row_mask:0xf bank_mask:0xf
	v_mov_b32_dpp v233, v151 row_ror:8 row_mask:0xf bank_mask:0xf
	v_mov_b32_dpp v234, v152 row_ror:8 row_mask:0xf bank_mask:0xf
	v_mov_b32_dpp v235, v153 row_ror:8 row_mask:0xf bank_mask:0xf
	v_cndmask_b32_e64 v232, v2, v232, s[90:91]
	v_cndmask_b32_e64 v233, v3, v233, s[90:91]
	v_cndmask_b32_e64 v234, v4, v234, s[90:91]
	v_cndmask_b32_e64 v235, v5, v235, s[90:91]
	v_pk_add_f32 v[232:233], v[232:233], v[206:207]
	v_pk_add_f32 v[234:235], v[234:235], v[208:209]
	s_nop 0
	global_store_dwordx4 v244, v[232:235], s[46:47] offset:128
	v_cvt_pk_bf16_f32 v240, v232, v233
	v_cvt_pk_bf16_f32 v241, v234, v235
	v_pk_mul_f32 v[236:237], v[232:233], v[232:233]
	v_pk_mul_f32 v[238:239], v[234:235], v[234:235]
	global_store_dwordx2 v245, v[240:241], s[50:51] offset:64
	v_add_f32_e32 v191, v191, v236
	v_add_f32_e32 v191, v191, v237
	v_add_f32_e32 v191, v191, v238
	v_add_f32_e32 v191, v191, v239
	s_nop 1
	v_add_f32_dpp v242, v242, v242 row_ror:8 row_mask:0xf bank_mask:0xf
	v_add_f32_dpp v191, v191, v191 row_ror:8 row_mask:0xf bank_mask:0xf
	s_add_u32 s44, s44, 0x10000
	s_addc_u32 s45, s45, 0
	s_add_u32 s46, s46, 0x10000
	s_addc_u32 s47, s47, 0
	s_add_u32 s48, s48, 0x8000
	s_addc_u32 s49, s49, 0
	s_add_u32 s50, s50, 0x8000
	s_addc_u32 s51, s51, 0
	v_cndmask_b32_e64 v242, v191, v242, s[90:91]
	ds_bpermute_b32 v243, v189, v242
	global_load_dwordx4 v[192:195], v244, s[40:41]
	global_load_dwordx4 v[198:201], v244, s[40:41] offset:128
	global_load_dwordx4 v[202:205], v244, s[42:43]
	global_load_dwordx4 v[206:209], v244, s[42:43] offset:128
	s_add_u32 s40, s40, 0x10000
	s_addc_u32 s41, s41, 0
	s_add_u32 s42, s42, 0x10000
	s_addc_u32 s43, s43, 0
	s_waitcnt lgkmcnt(0)
	v_add_f32_e32 v242, v242, v243
	ds_bpermute_b32 v243, v190, v242
	s_waitcnt lgkmcnt(0)
	v_add_f32_e32 v242, v242, v243
	s_and_saveexec_b64 s[2:3], s[88:89]
	ds_write_b32 v188, v242
	s_or_b64 exec, exec, s[2:3]
	s_waitcnt vmcnt(12)
; DI void gemm8_epi_resid(f32x4 (&acc)[8][4], int m0, int n0, int ntile8, bf16_t* L, const float* xin, float* out, bf16_t* xb, float* rowpart) {
;     ...
;   for (int i = 0; i < 8; ++i) {
;     const int ml = wm * 128 + i * 16 + (lane & 15);
;     const size_t rowoff = (size_t)(m0 + ml) * DM;
;     float ss = 0.f;
; #pragma unroll
;     for (int j = 0; j < 4; ++j) {
;       const int n = n0 + wn * 64 + j * 16 + (lane >> 4) * 4;
;       const float4 xv = *(const float4*)(xin + rowoff + n);
;       const float o0 = xv.x + acc[i][j][0], o1 = xv.y + acc[i][j][1], o2 = xv.z + acc[i][j][2], o3 = xv.w + acc[i][j][3];
;       *(float4*)(out + rowoff + n) = make_float4(o0, o1, o2, o3);
;       ss += o0 * o0 + o1 * o1 + o2 * o2 + o3 * o3;
;       uint2 u;
;       u.x = pack2(o0, o1);
;       u.y = pack2(o2, o3);
;       *(uint2*)(xb + rowoff + n) = u;
;     }
;     ss += shx(ss, 16, lane);
;     ss += shx(ss, 32, lane);
;     if ((lane >> 4) == 0) red[wn * 256 + ml] = ss;
;   }
	v_mov_b32_dpp v232, v106 row_ror:8 row_mask:0xf bank_mask:0xf
	v_mov_b32_dpp v233, v107 row_ror:8 row_mask:0xf bank_mask:0xf
	v_mov_b32_dpp v234, v108 row_ror:8 row_mask:0xf bank_mask:0xf
	v_mov_b32_dpp v235, v109 row_ror:8 row_mask:0xf bank_mask:0xf
	v_cndmask_b32_e64 v232, v232, v110, s[90:91]
	v_cndmask_b32_e64 v233, v233, v111, s[90:91]
	v_cndmask_b32_e64 v234, v234, v112, s[90:91]
	v_cndmask_b32_e64 v235, v235, v113, s[90:91]
	v_pk_add_f32 v[232:233], v[232:233], v[216:217]
	v_pk_add_f32 v[234:235], v[234:235], v[218:219]
	s_nop 0
	global_store_dwordx4 v244, v[232:235], s[44:45]
	v_cvt_pk_bf16_f32 v240, v232, v233
	v_cvt_pk_bf16_f32 v241, v234, v235
	v_pk_mul_f32 v[236:237], v[232:233], v[232:233]
	v_pk_mul_f32 v[238:239], v[234:235], v[234:235]
	global_store_dwordx2 v245, v[240:241], s[48:49]
	v_add_f32_e32 v242, v236, v237
	v_add_f32_e32 v242, v242, v238
	v_add_f32_e32 v242, v242, v239
	v_mov_b32_dpp v232, v110 row_ror:8 row_mask:0xf bank_mask:0xf
	v_mov_b32_dpp v233, v111 row_ror:8 row_mask:0xf bank_mask:0xf
	v_mov_b32_dpp v234, v112 row_ror:8 row_mask:0xf bank_mask:0xf
	v_mov_b32_dpp v235, v113 row_ror:8 row_mask:0xf bank_mask:0xf
	v_cndmask_b32_e64 v232, v106, v232, s[90:91]
	v_cndmask_b32_e64 v233, v107, v233, s[90:91]
	v_cndmask_b32_e64 v234, v108, v234, s[90:91]
	v_cndmask_b32_e64 v235, v109, v235, s[90:91]
	v_pk_add_f32 v[232:233], v[232:233], v[224:225]
	v_pk_add_f32 v[234:235], v[234:235], v[226:227]
	s_nop 0
	global_store_dwordx4 v244, v[232:235], s[46:47]
	v_cvt_pk_bf16_f32 v240, v232, v233
	v_cvt_pk_bf16_f32 v241, v234, v235
	v_pk_mul_f32 v[236:237], v[232:233], v[232:233]
	v_pk_mul_f32 v[238:239], v[234:235], v[234:235]
	global_store_dwordx2 v245, v[240:241], s[50:51]
	v_add_f32_e32 v191, v236, v237
	v_add_f32_e32 v191, v191, v238
	v_add_f32_e32 v191, v191, v239
	v_mov_b32_dpp v232, v98 row_ror:8 row_mask:0xf bank_mask:0xf
	v_mov_b32_dpp v233, v99 row_ror:8 row_mask:0xf bank_mask:0xf
	v_mov_b32_dpp v234, v100 row_ror:8 row_mask:0xf bank_mask:0xf
	v_mov_b32_dpp v235, v101 row_ror:8 row_mask:0xf bank_mask:0xf
	v_cndmask_b32_e64 v232, v232, v102, s[90:91]
	v_cndmask_b32_e64 v233, v233, v103, s[90:91]
	v_cndmask_b32_e64 v234, v234, v104, s[90:91]
	v_cndmask_b32_e64 v235, v235, v105, s[90:91]
	v_pk_add_f32 v[232:233], v[232:233], v[220:221]
	v_pk_add_f32 v[234:235], v[234:235], v[222:223]
	s_nop 0
	global_store_dwordx4 v244, v[232:235], s[44:45] offset:128
	v_cvt_pk_bf16_f32 v240, v232, v233
	v_cvt_pk_bf16_f32 v241, v234, v235
	v_pk_mul_f32 v[236:237], v[232:233], v[232:233]
	v_pk_mul_f32 v[238:239], v[234:235], v[234:235]
	global_store_dwordx2 v245, v[240:241], s[48:49] offset:64
	v_add_f32_e32 v242, v242, v236
	v_add_f32_e32 v242, v242, v237
	v_add_f32_e32 v242, v242, v238
	v_add_f32_e32 v242, v242, v239
	v_mov_b32_dpp v232, v102 row_ror:8 row_mask:0xf bank_mask:0xf
	v_mov_b32_dpp v233, v103 row_ror:8 row_mask:0xf bank_mask:0xf
	v_mov_b32_dpp v234, v104 row_ror:8 row_mask:0xf bank_mask:0xf
	v_mov_b32_dpp v235, v105 row_ror:8 row_mask:0xf bank_mask:0xf
	v_cndmask_b32_e64 v232, v98, v232, s[90:91]
	v_cndmask_b32_e64 v233, v99, v233, s[90:91]
	v_cndmask_b32_e64 v234, v100, v234, s[90:91]
	v_cndmask_b32_e64 v235, v101, v235, s[90:91]
	v_pk_add_f32 v[232:233], v[232:233], v[228:229]
	v_pk_add_f32 v[234:235], v[234:235], v[230:231]
	s_nop 0
	global_store_dwordx4 v244, v[232:235], s[46:47] offset:128
	v_cvt_pk_bf16_f32 v240, v232, v233
	v_cvt_pk_bf16_f32 v241, v234, v235
	v_pk_mul_f32 v[236:237], v[232:233], v[232:233]
	v_pk_mul_f32 v[238:239], v[234:235], v[234:235]
	global_store_dwordx2 v245, v[240:241], s[50:51] offset:64
	v_add_f32_e32 v191, v191, v236
	v_add_f32_e32 v191, v191, v237
	v_add_f32_e32 v191, v191, v238
	v_add_f32_e32 v191, v191, v239
	s_nop 1
	v_add_f32_dpp v242, v242, v242 row_ror:8 row_mask:0xf bank_mask:0xf
	v_add_f32_dpp v191, v191, v191 row_ror:8 row_mask:0xf bank_mask:0xf
	s_add_u32 s44, s44, 0x10000
	s_addc_u32 s45, s45, 0
	s_add_u32 s46, s46, 0x10000
	s_addc_u32 s47, s47, 0
	s_add_u32 s48, s48, 0x8000
	s_addc_u32 s49, s49, 0
	s_add_u32 s50, s50, 0x8000
	s_addc_u32 s51, s51, 0
	v_cndmask_b32_e64 v242, v191, v242, s[90:91]
	ds_bpermute_b32 v243, v189, v242
	global_load_dwordx4 v[216:219], v244, s[40:41]
	global_load_dwordx4 v[220:223], v244, s[40:41] offset:128
	global_load_dwordx4 v[224:227], v244, s[42:43]
	global_load_dwordx4 v[228:231], v244, s[42:43] offset:128
	s_add_u32 s40, s40, 0x10000
	s_addc_u32 s41, s41, 0
	s_add_u32 s42, s42, 0x10000
	s_addc_u32 s43, s43, 0
	s_waitcnt lgkmcnt(0)
	v_add_f32_e32 v242, v242, v243
	ds_bpermute_b32 v243, v190, v242
	s_waitcnt lgkmcnt(0)
	v_add_f32_e32 v242, v242, v243
	s_and_saveexec_b64 s[2:3], s[88:89]
	ds_write_b32 v188, v242 offset:64
	s_or_b64 exec, exec, s[2:3]
	s_waitcnt vmcnt(12)
; DI void gemm8_epi_resid(f32x4 (&acc)[8][4], int m0, int n0, int ntile8, bf16_t* L, const float* xin, float* out, bf16_t* xb, float* rowpart) {
;     ...
;   for (int i = 0; i < 8; ++i) {
;     const int ml = wm * 128 + i * 16 + (lane & 15);
;     const size_t rowoff = (size_t)(m0 + ml) * DM;
;     float ss = 0.f;
; #pragma unroll
;     for (int j = 0; j < 4; ++j) {
;       const int n = n0 + wn * 64 + j * 16 + (lane >> 4) * 4;
;       const float4 xv = *(const float4*)(xin + rowoff + n);
;       const float o0 = xv.x + acc[i][j][0], o1 = xv.y + acc[i][j][1], o2 = xv.z + acc[i][j][2], o3 = xv.w + acc[i][j][3];
;       *(float4*)(out + rowoff + n) = make_float4(o0, o1, o2, o3);
;       ss += o0 * o0 + o1 * o1 + o2 * o2 + o3 * o3;
;       uint2 u;
;       u.x = pack2(o0, o1);
;       u.y = pack2(o2, o3);
;       *(uint2*)(xb + rowoff + n) = u;
;     }
;     ss += shx(ss, 16, lane);
;     ss += shx(ss, 32, lane);
;     if ((lane >> 4) == 0) red[wn * 256 + ml] = ss;
;   }
	v_mov_b32_dpp v232, v90 row_ror:8 row_mask:0xf bank_mask:0xf
	v_mov_b32_dpp v233, v91 row_ror:8 row_mask:0xf bank_mask:0xf
	v_mov_b32_dpp v234, v92 row_ror:8 row_mask:0xf bank_mask:0xf
	v_mov_b32_dpp v235, v93 row_ror:8 row_mask:0xf bank_mask:0xf
	v_cndmask_b32_e64 v232, v232, v94, s[90:91]
	v_cndmask_b32_e64 v233, v233, v95, s[90:91]
	v_cndmask_b32_e64 v234, v234, v96, s[90:91]
	v_cndmask_b32_e64 v235, v235, v97, s[90:91]
	v_pk_add_f32 v[232:233], v[232:233], v[192:193]
	v_pk_add_f32 v[234:235], v[234:235], v[194:195]
	s_nop 0
	global_store_dwordx4 v244, v[232:235], s[44:45]
	v_cvt_pk_bf16_f32 v240, v232, v233
	v_cvt_pk_bf16_f32 v241, v234, v235
	v_pk_mul_f32 v[236:237], v[232:233], v[232:233]
	v_pk_mul_f32 v[238:239], v[234:235], v[234:235]
	global_store_dwordx2 v245, v[240:241], s[48:49]
	v_add_f32_e32 v242, v236, v237
	v_add_f32_e32 v242, v242, v238
	v_add_f32_e32 v242, v242, v239
	v_mov_b32_dpp v232, v94 row_ror:8 row_mask:0xf bank_mask:0xf
	v_mov_b32_dpp v233, v95 row_ror:8 row_mask:0xf bank_mask:0xf
	v_mov_b32_dpp v234, v96 row_ror:8 row_mask:0xf bank_mask:0xf
	v_mov_b32_dpp v235, v97 row_ror:8 row_mask:0xf bank_mask:0xf
	v_cndmask_b32_e64 v232, v90, v232, s[90:91]
	v_cndmask_b32_e64 v233, v91, v233, s[90:91]
	v_cndmask_b32_e64 v234, v92, v234, s[90:91]
	v_cndmask_b32_e64 v235, v93, v235, s[90:91]
	v_pk_add_f32 v[232:233], v[232:233], v[202:203]
	v_pk_add_f32 v[234:235], v[234:235], v[204:205]
	s_nop 0
	global_store_dwordx4 v244, v[232:235], s[46:47]
	v_cvt_pk_bf16_f32 v240, v232, v233
	v_cvt_pk_bf16_f32 v241, v234, v235
	v_pk_mul_f32 v[236:237], v[232:233], v[232:233]
	v_pk_mul_f32 v[238:239], v[234:235], v[234:235]
	global_store_dwordx2 v245, v[240:241], s[50:51]
	v_add_f32_e32 v191, v236, v237
	v_add_f32_e32 v191, v191, v238
	v_add_f32_e32 v191, v191, v239
	v_mov_b32_dpp v232, v82 row_ror:8 row_mask:0xf bank_mask:0xf
	v_mov_b32_dpp v233, v83 row_ror:8 row_mask:0xf bank_mask:0xf
	v_mov_b32_dpp v234, v84 row_ror:8 row_mask:0xf bank_mask:0xf
	v_mov_b32_dpp v235, v85 row_ror:8 row_mask:0xf bank_mask:0xf
	v_cndmask_b32_e64 v232, v232, v86, s[90:91]
	v_cndmask_b32_e64 v233, v233, v87, s[90:91]
	v_cndmask_b32_e64 v234, v234, v88, s[90:91]
	v_cndmask_b32_e64 v235, v235, v89, s[90:91]
	v_pk_add_f32 v[232:233], v[232:233], v[198:199]
	v_pk_add_f32 v[234:235], v[234:235], v[200:201]
	s_nop 0
	global_store_dwordx4 v244, v[232:235], s[44:45] offset:128
	v_cvt_pk_bf16_f32 v240, v232, v233
	v_cvt_pk_bf16_f32 v241, v234, v235
	v_pk_mul_f32 v[236:237], v[232:233], v[232:233]
	v_pk_mul_f32 v[238:239], v[234:235], v[234:235]
	global_store_dwordx2 v245, v[240:241], s[48:49] offset:64
	v_add_f32_e32 v242, v242, v236
	v_add_f32_e32 v242, v242, v237
	v_add_f32_e32 v242, v242, v238
	v_add_f32_e32 v242, v242, v239
	v_mov_b32_dpp v232, v86 row_ror:8 row_mask:0xf bank_mask:0xf
	v_mov_b32_dpp v233, v87 row_ror:8 row_mask:0xf bank_mask:0xf
	v_mov_b32_dpp v234, v88 row_ror:8 row_mask:0xf bank_mask:0xf
	v_mov_b32_dpp v235, v89 row_ror:8 row_mask:0xf bank_mask:0xf
	v_cndmask_b32_e64 v232, v82, v232, s[90:91]
	v_cndmask_b32_e64 v233, v83, v233, s[90:91]
	v_cndmask_b32_e64 v234, v84, v234, s[90:91]
	v_cndmask_b32_e64 v235, v85, v235, s[90:91]
	v_pk_add_f32 v[232:233], v[232:233], v[206:207]
	v_pk_add_f32 v[234:235], v[234:235], v[208:209]
	s_nop 0
	global_store_dwordx4 v244, v[232:235], s[46:47] offset:128
	v_cvt_pk_bf16_f32 v240, v232, v233
	v_cvt_pk_bf16_f32 v241, v234, v235
	v_pk_mul_f32 v[236:237], v[232:233], v[232:233]
	v_pk_mul_f32 v[238:239], v[234:235], v[234:235]
	global_store_dwordx2 v245, v[240:241], s[50:51] offset:64
	v_add_f32_e32 v191, v191, v236
	v_add_f32_e32 v191, v191, v237
	v_add_f32_e32 v191, v191, v238
	v_add_f32_e32 v191, v191, v239
	s_nop 1
	v_add_f32_dpp v242, v242, v242 row_ror:8 row_mask:0xf bank_mask:0xf
	v_add_f32_dpp v191, v191, v191 row_ror:8 row_mask:0xf bank_mask:0xf
	s_add_u32 s44, s44, 0x10000
	s_addc_u32 s45, s45, 0
	s_add_u32 s46, s46, 0x10000
	s_addc_u32 s47, s47, 0
	s_add_u32 s48, s48, 0x8000
	s_addc_u32 s49, s49, 0
	s_add_u32 s50, s50, 0x8000
	s_addc_u32 s51, s51, 0
	v_cndmask_b32_e64 v242, v191, v242, s[90:91]
	ds_bpermute_b32 v243, v189, v242
	global_load_dwordx4 v[192:195], v244, s[40:41]
	global_load_dwordx4 v[198:201], v244, s[40:41] offset:128
	global_load_dwordx4 v[202:205], v244, s[42:43]
	global_load_dwordx4 v[206:209], v244, s[42:43] offset:128
	s_add_u32 s40, s40, 0x10000
	s_addc_u32 s41, s41, 0
	s_add_u32 s42, s42, 0x10000
	s_addc_u32 s43, s43, 0
	s_waitcnt lgkmcnt(0)
	v_add_f32_e32 v242, v242, v243
	ds_bpermute_b32 v243, v190, v242
	s_waitcnt lgkmcnt(0)
	v_add_f32_e32 v242, v242, v243
	s_and_saveexec_b64 s[2:3], s[88:89]
	ds_write_b32 v188, v242 offset:128
	s_or_b64 exec, exec, s[2:3]
	s_waitcnt vmcnt(12)
; DI void gemm8_epi_resid(f32x4 (&acc)[8][4], int m0, int n0, int ntile8, bf16_t* L, const float* xin, float* out, bf16_t* xb, float* rowpart) {
;     ...
;   for (int i = 0; i < 8; ++i) {
;     const int ml = wm * 128 + i * 16 + (lane & 15);
;     const size_t rowoff = (size_t)(m0 + ml) * DM;
;     float ss = 0.f;
; #pragma unroll
;     for (int j = 0; j < 4; ++j) {
;       const int n = n0 + wn * 64 + j * 16 + (lane >> 4) * 4;
;       const float4 xv = *(const float4*)(xin + rowoff + n);
;       const float o0 = xv.x + acc[i][j][0], o1 = xv.y + acc[i][j][1], o2 = xv.z + acc[i][j][2], o3 = xv.w + acc[i][j][3];
;       *(float4*)(out + rowoff + n) = make_float4(o0, o1, o2, o3);
;       ss += o0 * o0 + o1 * o1 + o2 * o2 + o3 * o3;
;       uint2 u;
;       u.x = pack2(o0, o1);
;       u.y = pack2(o2, o3);
;       *(uint2*)(xb + rowoff + n) = u;
;     }
;     ss += shx(ss, 16, lane);
;     ss += shx(ss, 32, lane);
;     if ((lane >> 4) == 0) red[wn * 256 + ml] = ss;
;   }
	v_mov_b32_dpp v232, v74 row_ror:8 row_mask:0xf bank_mask:0xf
	v_mov_b32_dpp v233, v75 row_ror:8 row_mask:0xf bank_mask:0xf
	v_mov_b32_dpp v234, v76 row_ror:8 row_mask:0xf bank_mask:0xf
	v_mov_b32_dpp v235, v77 row_ror:8 row_mask:0xf bank_mask:0xf
	v_cndmask_b32_e64 v232, v232, v78, s[90:91]
	v_cndmask_b32_e64 v233, v233, v79, s[90:91]
	v_cndmask_b32_e64 v234, v234, v80, s[90:91]
	v_cndmask_b32_e64 v235, v235, v81, s[90:91]
	v_pk_add_f32 v[232:233], v[232:233], v[216:217]
	v_pk_add_f32 v[234:235], v[234:235], v[218:219]
	s_nop 0
	global_store_dwordx4 v244, v[232:235], s[44:45]
	v_cvt_pk_bf16_f32 v240, v232, v233
	v_cvt_pk_bf16_f32 v241, v234, v235
	v_pk_mul_f32 v[236:237], v[232:233], v[232:233]
	v_pk_mul_f32 v[238:239], v[234:235], v[234:235]
	global_store_dwordx2 v245, v[240:241], s[48:49]
	v_add_f32_e32 v242, v236, v237
	v_add_f32_e32 v242, v242, v238
	v_add_f32_e32 v242, v242, v239
	v_mov_b32_dpp v232, v78 row_ror:8 row_mask:0xf bank_mask:0xf
	v_mov_b32_dpp v233, v79 row_ror:8 row_mask:0xf bank_mask:0xf
	v_mov_b32_dpp v234, v80 row_ror:8 row_mask:0xf bank_mask:0xf
	v_mov_b32_dpp v235, v81 row_ror:8 row_mask:0xf bank_mask:0xf
	v_cndmask_b32_e64 v232, v74, v232, s[90:91]
	v_cndmask_b32_e64 v233, v75, v233, s[90:91]
	v_cndmask_b32_e64 v234, v76, v234, s[90:91]
	v_cndmask_b32_e64 v235, v77, v235, s[90:91]
	v_pk_add_f32 v[232:233], v[232:233], v[224:225]
	v_pk_add_f32 v[234:235], v[234:235], v[226:227]
	s_nop 0
	global_store_dwordx4 v244, v[232:235], s[46:47]
	v_cvt_pk_bf16_f32 v240, v232, v233
	v_cvt_pk_bf16_f32 v241, v234, v235
	v_pk_mul_f32 v[236:237], v[232:233], v[232:233]
	v_pk_mul_f32 v[238:239], v[234:235], v[234:235]
	global_store_dwordx2 v245, v[240:241], s[50:51]
	v_add_f32_e32 v191, v236, v237
	v_add_f32_e32 v191, v191, v238
	v_add_f32_e32 v191, v191, v239
	v_mov_b32_dpp v232, v66 row_ror:8 row_mask:0xf bank_mask:0xf
	v_mov_b32_dpp v233, v67 row_ror:8 row_mask:0xf bank_mask:0xf
	v_mov_b32_dpp v234, v68 row_ror:8 row_mask:0xf bank_mask:0xf
	v_mov_b32_dpp v235, v69 row_ror:8 row_mask:0xf bank_mask:0xf
	v_cndmask_b32_e64 v232, v232, v70, s[90:91]
	v_cndmask_b32_e64 v233, v233, v71, s[90:91]
	v_cndmask_b32_e64 v234, v234, v72, s[90:91]
	v_cndmask_b32_e64 v235, v235, v73, s[90:91]
	v_pk_add_f32 v[232:233], v[232:233], v[220:221]
	v_pk_add_f32 v[234:235], v[234:235], v[222:223]
	s_nop 0
	global_store_dwordx4 v244, v[232:235], s[44:45] offset:128
	v_cvt_pk_bf16_f32 v240, v232, v233
	v_cvt_pk_bf16_f32 v241, v234, v235
	v_pk_mul_f32 v[236:237], v[232:233], v[232:233]
	v_pk_mul_f32 v[238:239], v[234:235], v[234:235]
	global_store_dwordx2 v245, v[240:241], s[48:49] offset:64
	v_add_f32_e32 v242, v242, v236
	v_add_f32_e32 v242, v242, v237
	v_add_f32_e32 v242, v242, v238
	v_add_f32_e32 v242, v242, v239
	v_mov_b32_dpp v232, v70 row_ror:8 row_mask:0xf bank_mask:0xf
	v_mov_b32_dpp v233, v71 row_ror:8 row_mask:0xf bank_mask:0xf
	v_mov_b32_dpp v234, v72 row_ror:8 row_mask:0xf bank_mask:0xf
	v_mov_b32_dpp v235, v73 row_ror:8 row_mask:0xf bank_mask:0xf
	v_cndmask_b32_e64 v232, v66, v232, s[90:91]
	v_cndmask_b32_e64 v233, v67, v233, s[90:91]
	v_cndmask_b32_e64 v234, v68, v234, s[90:91]
	v_cndmask_b32_e64 v235, v69, v235, s[90:91]
	v_pk_add_f32 v[232:233], v[232:233], v[228:229]
	v_pk_add_f32 v[234:235], v[234:235], v[230:231]
	s_nop 0
	global_store_dwordx4 v244, v[232:235], s[46:47] offset:128
	v_cvt_pk_bf16_f32 v240, v232, v233
	v_cvt_pk_bf16_f32 v241, v234, v235
	v_pk_mul_f32 v[236:237], v[232:233], v[232:233]
	v_pk_mul_f32 v[238:239], v[234:235], v[234:235]
	global_store_dwordx2 v245, v[240:241], s[50:51] offset:64
	v_add_f32_e32 v191, v191, v236
	v_add_f32_e32 v191, v191, v237
	v_add_f32_e32 v191, v191, v238
	v_add_f32_e32 v191, v191, v239
	s_nop 1
	v_add_f32_dpp v242, v242, v242 row_ror:8 row_mask:0xf bank_mask:0xf
	v_add_f32_dpp v191, v191, v191 row_ror:8 row_mask:0xf bank_mask:0xf
	s_add_u32 s44, s44, 0x10000
	s_addc_u32 s45, s45, 0
	s_add_u32 s46, s46, 0x10000
	s_addc_u32 s47, s47, 0
	s_add_u32 s48, s48, 0x8000
	s_addc_u32 s49, s49, 0
	s_add_u32 s50, s50, 0x8000
	s_addc_u32 s51, s51, 0
	v_cndmask_b32_e64 v242, v191, v242, s[90:91]
	ds_bpermute_b32 v243, v189, v242
	global_load_dwordx4 v[216:219], v244, s[40:41]
	global_load_dwordx4 v[220:223], v244, s[40:41] offset:128
	global_load_dwordx4 v[224:227], v244, s[42:43]
	global_load_dwordx4 v[228:231], v244, s[42:43] offset:128
	s_add_u32 s40, s40, 0x10000
	s_addc_u32 s41, s41, 0
	s_add_u32 s42, s42, 0x10000
	s_addc_u32 s43, s43, 0
	s_waitcnt lgkmcnt(0)
	v_add_f32_e32 v242, v242, v243
	ds_bpermute_b32 v243, v190, v242
	s_waitcnt lgkmcnt(0)
	v_add_f32_e32 v242, v242, v243
	s_and_saveexec_b64 s[2:3], s[88:89]
	ds_write_b32 v188, v242 offset:192
	s_or_b64 exec, exec, s[2:3]
	s_waitcnt vmcnt(12)
; DI void gemm8_epi_resid(f32x4 (&acc)[8][4], int m0, int n0, int ntile8, bf16_t* L, const float* xin, float* out, bf16_t* xb, float* rowpart) {
;     ...
;   for (int i = 0; i < 8; ++i) {
;     const int ml = wm * 128 + i * 16 + (lane & 15);
;     const size_t rowoff = (size_t)(m0 + ml) * DM;
;     float ss = 0.f;
; #pragma unroll
;     for (int j = 0; j < 4; ++j) {
;       const int n = n0 + wn * 64 + j * 16 + (lane >> 4) * 4;
;       const float4 xv = *(const float4*)(xin + rowoff + n);
;       const float o0 = xv.x + acc[i][j][0], o1 = xv.y + acc[i][j][1], o2 = xv.z + acc[i][j][2], o3 = xv.w + acc[i][j][3];
;       *(float4*)(out + rowoff + n) = make_float4(o0, o1, o2, o3);
;       ss += o0 * o0 + o1 * o1 + o2 * o2 + o3 * o3;
;       uint2 u;
;       u.x = pack2(o0, o1);
;       u.y = pack2(o2, o3);
;       *(uint2*)(xb + rowoff + n) = u;
;     }
;     ss += shx(ss, 16, lane);
;     ss += shx(ss, 32, lane);
;     if ((lane >> 4) == 0) red[wn * 256 + ml] = ss;
;   }
	v_mov_b32_dpp v232, v58 row_ror:8 row_mask:0xf bank_mask:0xf
	v_mov_b32_dpp v233, v59 row_ror:8 row_mask:0xf bank_mask:0xf
	v_mov_b32_dpp v234, v60 row_ror:8 row_mask:0xf bank_mask:0xf
	v_mov_b32_dpp v235, v61 row_ror:8 row_mask:0xf bank_mask:0xf
	v_cndmask_b32_e64 v232, v232, v62, s[90:91]
	v_cndmask_b32_e64 v233, v233, v63, s[90:91]
	v_cndmask_b32_e64 v234, v234, v64, s[90:91]
	v_cndmask_b32_e64 v235, v235, v65, s[90:91]
	v_pk_add_f32 v[232:233], v[232:233], v[192:193]
	v_pk_add_f32 v[234:235], v[234:235], v[194:195]
	s_nop 0
	global_store_dwordx4 v244, v[232:235], s[44:45]
	v_cvt_pk_bf16_f32 v240, v232, v233
	v_cvt_pk_bf16_f32 v241, v234, v235
	v_pk_mul_f32 v[236:237], v[232:233], v[232:233]
	v_pk_mul_f32 v[238:239], v[234:235], v[234:235]
	global_store_dwordx2 v245, v[240:241], s[48:49]
	v_add_f32_e32 v242, v236, v237
	v_add_f32_e32 v242, v242, v238
	v_add_f32_e32 v242, v242, v239
	v_mov_b32_dpp v232, v62 row_ror:8 row_mask:0xf bank_mask:0xf
	v_mov_b32_dpp v233, v63 row_ror:8 row_mask:0xf bank_mask:0xf
	v_mov_b32_dpp v234, v64 row_ror:8 row_mask:0xf bank_mask:0xf
	v_mov_b32_dpp v235, v65 row_ror:8 row_mask:0xf bank_mask:0xf
	v_cndmask_b32_e64 v232, v58, v232, s[90:91]
	v_cndmask_b32_e64 v233, v59, v233, s[90:91]
	v_cndmask_b32_e64 v234, v60, v234, s[90:91]
	v_cndmask_b32_e64 v235, v61, v235, s[90:91]
	v_pk_add_f32 v[232:233], v[232:233], v[202:203]
	v_pk_add_f32 v[234:235], v[234:235], v[204:205]
	s_nop 0
	global_store_dwordx4 v244, v[232:235], s[46:47]
	v_cvt_pk_bf16_f32 v240, v232, v233
	v_cvt_pk_bf16_f32 v241, v234, v235
	v_pk_mul_f32 v[236:237], v[232:233], v[232:233]
	v_pk_mul_f32 v[238:239], v[234:235], v[234:235]
	global_store_dwordx2 v245, v[240:241], s[50:51]
	v_add_f32_e32 v191, v236, v237
	v_add_f32_e32 v191, v191, v238
	v_add_f32_e32 v191, v191, v239
	v_mov_b32_dpp v232, v50 row_ror:8 row_mask:0xf bank_mask:0xf
	v_mov_b32_dpp v233, v51 row_ror:8 row_mask:0xf bank_mask:0xf
	v_mov_b32_dpp v234, v52 row_ror:8 row_mask:0xf bank_mask:0xf
	v_mov_b32_dpp v235, v53 row_ror:8 row_mask:0xf bank_mask:0xf
	v_cndmask_b32_e64 v232, v232, v54, s[90:91]
	v_cndmask_b32_e64 v233, v233, v55, s[90:91]
	v_cndmask_b32_e64 v234, v234, v56, s[90:91]
	v_cndmask_b32_e64 v235, v235, v57, s[90:91]
	v_pk_add_f32 v[232:233], v[232:233], v[198:199]
	v_pk_add_f32 v[234:235], v[234:235], v[200:201]
	s_nop 0
	global_store_dwordx4 v244, v[232:235], s[44:45] offset:128
	v_cvt_pk_bf16_f32 v240, v232, v233
	v_cvt_pk_bf16_f32 v241, v234, v235
	v_pk_mul_f32 v[236:237], v[232:233], v[232:233]
	v_pk_mul_f32 v[238:239], v[234:235], v[234:235]
	global_store_dwordx2 v245, v[240:241], s[48:49] offset:64
	v_add_f32_e32 v242, v242, v236
	v_add_f32_e32 v242, v242, v237
	v_add_f32_e32 v242, v242, v238
	v_add_f32_e32 v242, v242, v239
	v_mov_b32_dpp v232, v54 row_ror:8 row_mask:0xf bank_mask:0xf
	v_mov_b32_dpp v233, v55 row_ror:8 row_mask:0xf bank_mask:0xf
	v_mov_b32_dpp v234, v56 row_ror:8 row_mask:0xf bank_mask:0xf
	v_mov_b32_dpp v235, v57 row_ror:8 row_mask:0xf bank_mask:0xf
	v_cndmask_b32_e64 v232, v50, v232, s[90:91]
	v_cndmask_b32_e64 v233, v51, v233, s[90:91]
	v_cndmask_b32_e64 v234, v52, v234, s[90:91]
	v_cndmask_b32_e64 v235, v53, v235, s[90:91]
	v_pk_add_f32 v[232:233], v[232:233], v[206:207]
	v_pk_add_f32 v[234:235], v[234:235], v[208:209]
	s_nop 0
	global_store_dwordx4 v244, v[232:235], s[46:47] offset:128
	v_cvt_pk_bf16_f32 v240, v232, v233
	v_cvt_pk_bf16_f32 v241, v234, v235
	v_pk_mul_f32 v[236:237], v[232:233], v[232:233]
	v_pk_mul_f32 v[238:239], v[234:235], v[234:235]
	global_store_dwordx2 v245, v[240:241], s[50:51] offset:64
	v_add_f32_e32 v191, v191, v236
	v_add_f32_e32 v191, v191, v237
	v_add_f32_e32 v191, v191, v238
	v_add_f32_e32 v191, v191, v239
	s_nop 1
	v_add_f32_dpp v242, v242, v242 row_ror:8 row_mask:0xf bank_mask:0xf
	v_add_f32_dpp v191, v191, v191 row_ror:8 row_mask:0xf bank_mask:0xf
	s_add_u32 s44, s44, 0x10000
	s_addc_u32 s45, s45, 0
	s_add_u32 s46, s46, 0x10000
	s_addc_u32 s47, s47, 0
	s_add_u32 s48, s48, 0x8000
	s_addc_u32 s49, s49, 0
	s_add_u32 s50, s50, 0x8000
	s_addc_u32 s51, s51, 0
	v_cndmask_b32_e64 v242, v191, v242, s[90:91]
	ds_bpermute_b32 v243, v189, v242
	global_load_dwordx4 v[192:195], v244, s[40:41]
	global_load_dwordx4 v[198:201], v244, s[40:41] offset:128
	global_load_dwordx4 v[202:205], v244, s[42:43]
	global_load_dwordx4 v[206:209], v244, s[42:43] offset:128
	s_add_u32 s40, s40, 0x10000
	s_addc_u32 s41, s41, 0
	s_add_u32 s42, s42, 0x10000
	s_addc_u32 s43, s43, 0
	s_waitcnt lgkmcnt(0)
	v_add_f32_e32 v242, v242, v243
	ds_bpermute_b32 v243, v190, v242
	s_waitcnt lgkmcnt(0)
	v_add_f32_e32 v242, v242, v243
	s_and_saveexec_b64 s[2:3], s[88:89]
	ds_write_b32 v188, v242 offset:256
	s_or_b64 exec, exec, s[2:3]
	s_waitcnt vmcnt(12)
; DI void gemm8_epi_resid(f32x4 (&acc)[8][4], int m0, int n0, int ntile8, bf16_t* L, const float* xin, float* out, bf16_t* xb, float* rowpart) {
;     ...
;   for (int i = 0; i < 8; ++i) {
;     const int ml = wm * 128 + i * 16 + (lane & 15);
;     const size_t rowoff = (size_t)(m0 + ml) * DM;
;     float ss = 0.f;
; #pragma unroll
;     for (int j = 0; j < 4; ++j) {
;       const int n = n0 + wn * 64 + j * 16 + (lane >> 4) * 4;
;       const float4 xv = *(const float4*)(xin + rowoff + n);
;       const float o0 = xv.x + acc[i][j][0], o1 = xv.y + acc[i][j][1], o2 = xv.z + acc[i][j][2], o3 = xv.w + acc[i][j][3];
;       *(float4*)(out + rowoff + n) = make_float4(o0, o1, o2, o3);
;       ss += o0 * o0 + o1 * o1 + o2 * o2 + o3 * o3;
;       uint2 u;
;       u.x = pack2(o0, o1);
;       u.y = pack2(o2, o3);
;       *(uint2*)(xb + rowoff + n) = u;
;     }
;     ss += shx(ss, 16, lane);
;     ss += shx(ss, 32, lane);
;     if ((lane >> 4) == 0) red[wn * 256 + ml] = ss;
;   }
	v_mov_b32_dpp v232, v128 row_ror:8 row_mask:0xf bank_mask:0xf
	v_mov_b32_dpp v233, v129 row_ror:8 row_mask:0xf bank_mask:0xf
	v_mov_b32_dpp v234, v130 row_ror:8 row_mask:0xf bank_mask:0xf
	v_mov_b32_dpp v235, v131 row_ror:8 row_mask:0xf bank_mask:0xf
	v_cndmask_b32_e64 v232, v232, v46, s[90:91]
	v_cndmask_b32_e64 v233, v233, v47, s[90:91]
	v_cndmask_b32_e64 v234, v234, v48, s[90:91]
	v_cndmask_b32_e64 v235, v235, v49, s[90:91]
	v_pk_add_f32 v[232:233], v[232:233], v[216:217]
	v_pk_add_f32 v[234:235], v[234:235], v[218:219]
	s_nop 0
	global_store_dwordx4 v244, v[232:235], s[44:45]
	v_cvt_pk_bf16_f32 v240, v232, v233
	v_cvt_pk_bf16_f32 v241, v234, v235
	v_pk_mul_f32 v[236:237], v[232:233], v[232:233]
	v_pk_mul_f32 v[238:239], v[234:235], v[234:235]
	global_store_dwordx2 v245, v[240:241], s[48:49]
	v_add_f32_e32 v242, v236, v237
	v_add_f32_e32 v242, v242, v238
	v_add_f32_e32 v242, v242, v239
	v_mov_b32_dpp v232, v46 row_ror:8 row_mask:0xf bank_mask:0xf
	v_mov_b32_dpp v233, v47 row_ror:8 row_mask:0xf bank_mask:0xf
	v_mov_b32_dpp v234, v48 row_ror:8 row_mask:0xf bank_mask:0xf
	v_mov_b32_dpp v235, v49 row_ror:8 row_mask:0xf bank_mask:0xf
	v_cndmask_b32_e64 v232, v128, v232, s[90:91]
	v_cndmask_b32_e64 v233, v129, v233, s[90:91]
	v_cndmask_b32_e64 v234, v130, v234, s[90:91]
	v_cndmask_b32_e64 v235, v131, v235, s[90:91]
	v_pk_add_f32 v[232:233], v[232:233], v[224:225]
	v_pk_add_f32 v[234:235], v[234:235], v[226:227]
	s_nop 0
	global_store_dwordx4 v244, v[232:235], s[46:47]
	v_cvt_pk_bf16_f32 v240, v232, v233
	v_cvt_pk_bf16_f32 v241, v234, v235
	v_pk_mul_f32 v[236:237], v[232:233], v[232:233]
	v_pk_mul_f32 v[238:239], v[234:235], v[234:235]
	global_store_dwordx2 v245, v[240:241], s[50:51]
	v_add_f32_e32 v191, v236, v237
	v_add_f32_e32 v191, v191, v238
	v_add_f32_e32 v191, v191, v239
	v_mov_b32_dpp v232, v34 row_ror:8 row_mask:0xf bank_mask:0xf
	v_mov_b32_dpp v233, v35 row_ror:8 row_mask:0xf bank_mask:0xf
	v_mov_b32_dpp v234, v36 row_ror:8 row_mask:0xf bank_mask:0xf
	v_mov_b32_dpp v235, v37 row_ror:8 row_mask:0xf bank_mask:0xf
	v_cndmask_b32_e64 v232, v232, v124, s[90:91]
	v_cndmask_b32_e64 v233, v233, v125, s[90:91]
	v_cndmask_b32_e64 v234, v234, v126, s[90:91]
	v_cndmask_b32_e64 v235, v235, v127, s[90:91]
	v_pk_add_f32 v[232:233], v[232:233], v[220:221]
	v_pk_add_f32 v[234:235], v[234:235], v[222:223]
	s_nop 0
	global_store_dwordx4 v244, v[232:235], s[44:45] offset:128
	v_cvt_pk_bf16_f32 v240, v232, v233
	v_cvt_pk_bf16_f32 v241, v234, v235
	v_pk_mul_f32 v[236:237], v[232:233], v[232:233]
	v_pk_mul_f32 v[238:239], v[234:235], v[234:235]
	global_store_dwordx2 v245, v[240:241], s[48:49] offset:64
	v_add_f32_e32 v242, v242, v236
	v_add_f32_e32 v242, v242, v237
	v_add_f32_e32 v242, v242, v238
	v_add_f32_e32 v242, v242, v239
	v_mov_b32_dpp v232, v124 row_ror:8 row_mask:0xf bank_mask:0xf
	v_mov_b32_dpp v233, v125 row_ror:8 row_mask:0xf bank_mask:0xf
	v_mov_b32_dpp v234, v126 row_ror:8 row_mask:0xf bank_mask:0xf
	v_mov_b32_dpp v235, v127 row_ror:8 row_mask:0xf bank_mask:0xf
	v_cndmask_b32_e64 v232, v34, v232, s[90:91]
	v_cndmask_b32_e64 v233, v35, v233, s[90:91]
	v_cndmask_b32_e64 v234, v36, v234, s[90:91]
	v_cndmask_b32_e64 v235, v37, v235, s[90:91]
	v_pk_add_f32 v[232:233], v[232:233], v[228:229]
	v_pk_add_f32 v[234:235], v[234:235], v[230:231]
	s_nop 0
	global_store_dwordx4 v244, v[232:235], s[46:47] offset:128
	v_cvt_pk_bf16_f32 v240, v232, v233
	v_cvt_pk_bf16_f32 v241, v234, v235
	v_pk_mul_f32 v[236:237], v[232:233], v[232:233]
	v_pk_mul_f32 v[238:239], v[234:235], v[234:235]
	global_store_dwordx2 v245, v[240:241], s[50:51] offset:64
	v_add_f32_e32 v191, v191, v236
	v_add_f32_e32 v191, v191, v237
	v_add_f32_e32 v191, v191, v238
	v_add_f32_e32 v191, v191, v239
	s_nop 1
	v_add_f32_dpp v242, v242, v242 row_ror:8 row_mask:0xf bank_mask:0xf
	v_add_f32_dpp v191, v191, v191 row_ror:8 row_mask:0xf bank_mask:0xf
	s_add_u32 s44, s44, 0x10000
	s_addc_u32 s45, s45, 0
	s_add_u32 s46, s46, 0x10000
	s_addc_u32 s47, s47, 0
	s_add_u32 s48, s48, 0x8000
	s_addc_u32 s49, s49, 0
	s_add_u32 s50, s50, 0x8000
	s_addc_u32 s51, s51, 0
	v_cndmask_b32_e64 v242, v191, v242, s[90:91]
	ds_bpermute_b32 v243, v189, v242
	global_load_dwordx4 v[216:219], v244, s[40:41]
	global_load_dwordx4 v[220:223], v244, s[40:41] offset:128
	global_load_dwordx4 v[224:227], v244, s[42:43]
	global_load_dwordx4 v[228:231], v244, s[42:43] offset:128
	s_add_u32 s40, s40, 0x10000
	s_addc_u32 s41, s41, 0
	s_add_u32 s42, s42, 0x10000
	s_addc_u32 s43, s43, 0
	s_waitcnt lgkmcnt(0)
	v_add_f32_e32 v242, v242, v243
	ds_bpermute_b32 v243, v190, v242
	s_waitcnt lgkmcnt(0)
	v_add_f32_e32 v242, v242, v243
	s_and_saveexec_b64 s[2:3], s[88:89]
	ds_write_b32 v188, v242 offset:320
	s_or_b64 exec, exec, s[2:3]
	s_waitcnt vmcnt(12)
; DI void gemm8_epi_resid(f32x4 (&acc)[8][4], int m0, int n0, int ntile8, bf16_t* L, const float* xin, float* out, bf16_t* xb, float* rowpart) {
;     ...
;   for (int i = 0; i < 8; ++i) {
;     const int ml = wm * 128 + i * 16 + (lane & 15);
;     const size_t rowoff = (size_t)(m0 + ml) * DM;
;     float ss = 0.f;
; #pragma unroll
;     for (int j = 0; j < 4; ++j) {
;       const int n = n0 + wn * 64 + j * 16 + (lane >> 4) * 4;
;       const float4 xv = *(const float4*)(xin + rowoff + n);
;       const float o0 = xv.x + acc[i][j][0], o1 = xv.y + acc[i][j][1], o2 = xv.z + acc[i][j][2], o3 = xv.w + acc[i][j][3];
;       *(float4*)(out + rowoff + n) = make_float4(o0, o1, o2, o3);
;       ss += o0 * o0 + o1 * o1 + o2 * o2 + o3 * o3;
;       uint2 u;
;       u.x = pack2(o0, o1);
;       u.y = pack2(o2, o3);
;       *(uint2*)(xb + rowoff + n) = u;
;     }
;     ss += shx(ss, 16, lane);
;     ss += shx(ss, 32, lane);
;     if ((lane >> 4) == 0) red[wn * 256 + ml] = ss;
;   }
	v_mov_b32_dpp v232, v26 row_ror:8 row_mask:0xf bank_mask:0xf
	v_mov_b32_dpp v233, v27 row_ror:8 row_mask:0xf bank_mask:0xf
	v_mov_b32_dpp v234, v28 row_ror:8 row_mask:0xf bank_mask:0xf
	v_mov_b32_dpp v235, v29 row_ror:8 row_mask:0xf bank_mask:0xf
	v_cndmask_b32_e64 v232, v232, v30, s[90:91]
	v_cndmask_b32_e64 v233, v233, v31, s[90:91]
	v_cndmask_b32_e64 v234, v234, v32, s[90:91]
	v_cndmask_b32_e64 v235, v235, v33, s[90:91]
	v_pk_add_f32 v[232:233], v[232:233], v[192:193]
	v_pk_add_f32 v[234:235], v[234:235], v[194:195]
	s_nop 0
	global_store_dwordx4 v244, v[232:235], s[44:45]
	v_cvt_pk_bf16_f32 v240, v232, v233
	v_cvt_pk_bf16_f32 v241, v234, v235
	v_pk_mul_f32 v[236:237], v[232:233], v[232:233]
	v_pk_mul_f32 v[238:239], v[234:235], v[234:235]
	global_store_dwordx2 v245, v[240:241], s[48:49]
	v_add_f32_e32 v242, v236, v237
	v_add_f32_e32 v242, v242, v238
	v_add_f32_e32 v242, v242, v239
	v_mov_b32_dpp v232, v30 row_ror:8 row_mask:0xf bank_mask:0xf
	v_mov_b32_dpp v233, v31 row_ror:8 row_mask:0xf bank_mask:0xf
	v_mov_b32_dpp v234, v32 row_ror:8 row_mask:0xf bank_mask:0xf
	v_mov_b32_dpp v235, v33 row_ror:8 row_mask:0xf bank_mask:0xf
	v_cndmask_b32_e64 v232, v26, v232, s[90:91]
	v_cndmask_b32_e64 v233, v27, v233, s[90:91]
	v_cndmask_b32_e64 v234, v28, v234, s[90:91]
	v_cndmask_b32_e64 v235, v29, v235, s[90:91]
	v_pk_add_f32 v[232:233], v[232:233], v[202:203]
	v_pk_add_f32 v[234:235], v[234:235], v[204:205]
	s_nop 0
	global_store_dwordx4 v244, v[232:235], s[46:47]
	v_cvt_pk_bf16_f32 v240, v232, v233
	v_cvt_pk_bf16_f32 v241, v234, v235
	v_pk_mul_f32 v[236:237], v[232:233], v[232:233]
	v_pk_mul_f32 v[238:239], v[234:235], v[234:235]
	global_store_dwordx2 v245, v[240:241], s[50:51]
	v_add_f32_e32 v191, v236, v237
	v_add_f32_e32 v191, v191, v238
	v_add_f32_e32 v191, v191, v239
	v_mov_b32_dpp v232, v18 row_ror:8 row_mask:0xf bank_mask:0xf
	v_mov_b32_dpp v233, v19 row_ror:8 row_mask:0xf bank_mask:0xf
	v_mov_b32_dpp v234, v20 row_ror:8 row_mask:0xf bank_mask:0xf
	v_mov_b32_dpp v235, v21 row_ror:8 row_mask:0xf bank_mask:0xf
	v_cndmask_b32_e64 v232, v232, v22, s[90:91]
	v_cndmask_b32_e64 v233, v233, v23, s[90:91]
	v_cndmask_b32_e64 v234, v234, v24, s[90:91]
	v_cndmask_b32_e64 v235, v235, v25, s[90:91]
	v_pk_add_f32 v[232:233], v[232:233], v[198:199]
	v_pk_add_f32 v[234:235], v[234:235], v[200:201]
	s_nop 0
	global_store_dwordx4 v244, v[232:235], s[44:45] offset:128
	v_cvt_pk_bf16_f32 v240, v232, v233
	v_cvt_pk_bf16_f32 v241, v234, v235
	v_pk_mul_f32 v[236:237], v[232:233], v[232:233]
	v_pk_mul_f32 v[238:239], v[234:235], v[234:235]
	global_store_dwordx2 v245, v[240:241], s[48:49] offset:64
	v_add_f32_e32 v242, v242, v236
	v_add_f32_e32 v242, v242, v237
	v_add_f32_e32 v242, v242, v238
	v_add_f32_e32 v242, v242, v239
	v_mov_b32_dpp v232, v22 row_ror:8 row_mask:0xf bank_mask:0xf
	v_mov_b32_dpp v233, v23 row_ror:8 row_mask:0xf bank_mask:0xf
	v_mov_b32_dpp v234, v24 row_ror:8 row_mask:0xf bank_mask:0xf
	v_mov_b32_dpp v235, v25 row_ror:8 row_mask:0xf bank_mask:0xf
	v_cndmask_b32_e64 v232, v18, v232, s[90:91]
	v_cndmask_b32_e64 v233, v19, v233, s[90:91]
	v_cndmask_b32_e64 v234, v20, v234, s[90:91]
	v_cndmask_b32_e64 v235, v21, v235, s[90:91]
	v_pk_add_f32 v[232:233], v[232:233], v[206:207]
	v_pk_add_f32 v[234:235], v[234:235], v[208:209]
	s_nop 0
	global_store_dwordx4 v244, v[232:235], s[46:47] offset:128
	v_cvt_pk_bf16_f32 v240, v232, v233
	v_cvt_pk_bf16_f32 v241, v234, v235
	v_pk_mul_f32 v[236:237], v[232:233], v[232:233]
	v_pk_mul_f32 v[238:239], v[234:235], v[234:235]
	global_store_dwordx2 v245, v[240:241], s[50:51] offset:64
	v_add_f32_e32 v191, v191, v236
	v_add_f32_e32 v191, v191, v237
	v_add_f32_e32 v191, v191, v238
	v_add_f32_e32 v191, v191, v239
	s_nop 1
	v_add_f32_dpp v242, v242, v242 row_ror:8 row_mask:0xf bank_mask:0xf
	v_add_f32_dpp v191, v191, v191 row_ror:8 row_mask:0xf bank_mask:0xf
	s_add_u32 s44, s44, 0x10000
	s_addc_u32 s45, s45, 0
	s_add_u32 s46, s46, 0x10000
	s_addc_u32 s47, s47, 0
	s_add_u32 s48, s48, 0x8000
	s_addc_u32 s49, s49, 0
	s_add_u32 s50, s50, 0x8000
	s_addc_u32 s51, s51, 0
	v_cndmask_b32_e64 v242, v191, v242, s[90:91]
	ds_bpermute_b32 v243, v189, v242
	s_waitcnt lgkmcnt(0)
	v_add_f32_e32 v242, v242, v243
	ds_bpermute_b32 v243, v190, v242
	s_waitcnt lgkmcnt(0)
	v_add_f32_e32 v242, v242, v243
	s_and_saveexec_b64 s[2:3], s[88:89]
	ds_write_b32 v188, v242 offset:384
	s_or_b64 exec, exec, s[2:3]
	s_waitcnt vmcnt(8)
; DI void gemm8_epi_resid(f32x4 (&acc)[8][4], int m0, int n0, int ntile8, bf16_t* L, const float* xin, float* out, bf16_t* xb, float* rowpart) {
;     ...
;   for (int i = 0; i < 8; ++i) {
;     const int ml = wm * 128 + i * 16 + (lane & 15);
;     const size_t rowoff = (size_t)(m0 + ml) * DM;
;     float ss = 0.f;
; #pragma unroll
;     for (int j = 0; j < 4; ++j) {
;       const int n = n0 + wn * 64 + j * 16 + (lane >> 4) * 4;
;       const float4 xv = *(const float4*)(xin + rowoff + n);
;       const float o0 = xv.x + acc[i][j][0], o1 = xv.y + acc[i][j][1], o2 = xv.z + acc[i][j][2], o3 = xv.w + acc[i][j][3];
;       *(float4*)(out + rowoff + n) = make_float4(o0, o1, o2, o3);
;       ss += o0 * o0 + o1 * o1 + o2 * o2 + o3 * o3;
;       uint2 u;
;       u.x = pack2(o0, o1);
;       u.y = pack2(o2, o3);
;       *(uint2*)(xb + rowoff + n) = u;
;     }
;     ss += shx(ss, 16, lane);
;     ss += shx(ss, 32, lane);
;     if ((lane >> 4) == 0) red[wn * 256 + ml] = ss;
;   }
; __global__ void __launch_bounds__(512, 2) mega(Params p) {
;     ...
;     GEMM8_TILE_LOOP(22) {
;       const int m0 = mt * 256, n0 = ntile * 256;
;       f32x4 acc8[8][4];
;       zero_acc8(acc8);
;       gemm8_accum(acc8, hbuf + (size_t)m0 * DM, DM, wl + W_IN + (size_t)n0 * 1024, 1024, 16, lds_all, !first_,
;                   hbuf + (size_t)mtn * 256 * DM, DM, wl + W_IN + (size_t)ntilen * 256 * 1024, 1024);
;       gemm8_epi_staged(acc8, m0, n0, lds_all, [&](int, int, f32x4&) {}, z, ZS, ZS);
;     }
	v_mov_b32_dpp v232, v10 row_ror:8 row_mask:0xf bank_mask:0xf
	v_mov_b32_dpp v233, v11 row_ror:8 row_mask:0xf bank_mask:0xf
	v_mov_b32_dpp v234, v12 row_ror:8 row_mask:0xf bank_mask:0xf
	v_mov_b32_dpp v235, v13 row_ror:8 row_mask:0xf bank_mask:0xf
	v_cndmask_b32_e64 v232, v232, v14, s[90:91]
	v_cndmask_b32_e64 v233, v233, v15, s[90:91]
	v_cndmask_b32_e64 v234, v234, v16, s[90:91]
	v_cndmask_b32_e64 v235, v235, v17, s[90:91]
	v_pk_add_f32 v[232:233], v[232:233], v[216:217]
	v_pk_add_f32 v[234:235], v[234:235], v[218:219]
	s_nop 0
	global_store_dwordx4 v244, v[232:235], s[44:45]
	v_cvt_pk_bf16_f32 v240, v232, v233
	v_cvt_pk_bf16_f32 v241, v234, v235
	v_pk_mul_f32 v[236:237], v[232:233], v[232:233]
	v_pk_mul_f32 v[238:239], v[234:235], v[234:235]
	global_store_dwordx2 v245, v[240:241], s[48:49]
	v_add_f32_e32 v242, v236, v237
	v_add_f32_e32 v242, v242, v238
	v_add_f32_e32 v242, v242, v239
	v_mov_b32_dpp v232, v14 row_ror:8 row_mask:0xf bank_mask:0xf
	v_mov_b32_dpp v233, v15 row_ror:8 row_mask:0xf bank_mask:0xf
	v_mov_b32_dpp v234, v16 row_ror:8 row_mask:0xf bank_mask:0xf
	v_mov_b32_dpp v235, v17 row_ror:8 row_mask:0xf bank_mask:0xf
	v_cndmask_b32_e64 v232, v10, v232, s[90:91]
	v_cndmask_b32_e64 v233, v11, v233, s[90:91]
	v_cndmask_b32_e64 v234, v12, v234, s[90:91]
	v_cndmask_b32_e64 v235, v13, v235, s[90:91]
	v_pk_add_f32 v[232:233], v[232:233], v[224:225]
	v_pk_add_f32 v[234:235], v[234:235], v[226:227]
	s_nop 0
	global_store_dwordx4 v244, v[232:235], s[46:47]
	v_cvt_pk_bf16_f32 v240, v232, v233
	v_cvt_pk_bf16_f32 v241, v234, v235
	v_pk_mul_f32 v[236:237], v[232:233], v[232:233]
	v_pk_mul_f32 v[238:239], v[234:235], v[234:235]
	global_store_dwordx2 v245, v[240:241], s[50:51]
	v_add_f32_e32 v191, v236, v237
	v_add_f32_e32 v191, v191, v238
	v_add_f32_e32 v191, v191, v239
	v_mov_b32_dpp v232, v38 row_ror:8 row_mask:0xf bank_mask:0xf
	v_mov_b32_dpp v233, v39 row_ror:8 row_mask:0xf bank_mask:0xf
	v_mov_b32_dpp v234, v40 row_ror:8 row_mask:0xf bank_mask:0xf
	v_mov_b32_dpp v235, v41 row_ror:8 row_mask:0xf bank_mask:0xf
	v_cndmask_b32_e64 v232, v232, v6, s[90:91]
	v_cndmask_b32_e64 v233, v233, v7, s[90:91]
	v_cndmask_b32_e64 v234, v234, v8, s[90:91]
	v_cndmask_b32_e64 v235, v235, v9, s[90:91]
	v_pk_add_f32 v[232:233], v[232:233], v[220:221]
	v_pk_add_f32 v[234:235], v[234:235], v[222:223]
	s_nop 0
	global_store_dwordx4 v244, v[232:235], s[44:45] offset:128
	v_cvt_pk_bf16_f32 v240, v232, v233
	v_cvt_pk_bf16_f32 v241, v234, v235
	v_pk_mul_f32 v[236:237], v[232:233], v[232:233]
	v_pk_mul_f32 v[238:239], v[234:235], v[234:235]
	global_store_dwordx2 v245, v[240:241], s[48:49] offset:64
	v_add_f32_e32 v242, v242, v236
	v_add_f32_e32 v242, v242, v237
	v_add_f32_e32 v242, v242, v238
	v_add_f32_e32 v242, v242, v239
	v_mov_b32_dpp v232, v6 row_ror:8 row_mask:0xf bank_mask:0xf
	v_mov_b32_dpp v233, v7 row_ror:8 row_mask:0xf bank_mask:0xf
	v_mov_b32_dpp v234, v8 row_ror:8 row_mask:0xf bank_mask:0xf
	v_mov_b32_dpp v235, v9 row_ror:8 row_mask:0xf bank_mask:0xf
	v_cndmask_b32_e64 v232, v38, v232, s[90:91]
	v_cndmask_b32_e64 v233, v39, v233, s[90:91]
	v_cndmask_b32_e64 v234, v40, v234, s[90:91]
	v_cndmask_b32_e64 v235, v41, v235, s[90:91]
	v_pk_add_f32 v[232:233], v[232:233], v[228:229]
	v_pk_add_f32 v[234:235], v[234:235], v[230:231]
	s_nop 0
	global_store_dwordx4 v244, v[232:235], s[46:47] offset:128
	v_cvt_pk_bf16_f32 v240, v232, v233
	v_cvt_pk_bf16_f32 v241, v234, v235
	v_pk_mul_f32 v[236:237], v[232:233], v[232:233]
	v_pk_mul_f32 v[238:239], v[234:235], v[234:235]
	global_store_dwordx2 v245, v[240:241], s[50:51] offset:64
	v_add_f32_e32 v191, v191, v236
	v_add_f32_e32 v191, v191, v237
	v_add_f32_e32 v191, v191, v238
	v_add_f32_e32 v191, v191, v239
	s_nop 1
	v_add_f32_dpp v242, v242, v242 row_ror:8 row_mask:0xf bank_mask:0xf
	v_add_f32_dpp v191, v191, v191 row_ror:8 row_mask:0xf bank_mask:0xf
	s_add_u32 s44, s44, 0x10000
	s_addc_u32 s45, s45, 0
	s_add_u32 s46, s46, 0x10000
	s_addc_u32 s47, s47, 0
	s_add_u32 s48, s48, 0x8000
	s_addc_u32 s49, s49, 0
	s_add_u32 s50, s50, 0x8000
	s_addc_u32 s51, s51, 0
	v_cndmask_b32_e64 v242, v191, v242, s[90:91]
	ds_bpermute_b32 v243, v189, v242
	s_waitcnt lgkmcnt(0)
	v_add_f32_e32 v242, v242, v243
	ds_bpermute_b32 v243, v190, v242
	s_waitcnt lgkmcnt(0)
	v_add_f32_e32 v242, v242, v243
	s_and_saveexec_b64 s[2:3], s[88:89]
	ds_write_b32 v188, v242 offset:448
	s_or_b64 exec, exec, s[2:3]
	s_branch .LBB0_824

; DI f32x4 mfma16(bf16x8 a, bf16x8 b, f32x4 c) { return __builtin_amdgcn_mfma_f32_16x16x32_bf16(a, b, c, 0, 0, 0); }
; #pragma unroll
;   for (int ks = KS0; ks < KS1; ++ks) {
;     bf16x8 af[8], bfr[4];
; #pragma unroll
;     for (int i = 0; i < 8; ++i) {
;       const int r = wm * 128 + i * 16 + (lane & 15);
;       af[i] = *(const bf16x8*)(S + r * 64 + (((ks * 4 + (lane >> 4)) ^ ((r >> 1) & 7)) << 3));
;     }
; #pragma unroll
;     for (int j = 0; j < 4; ++j) {
;       const int r = wn * 64 + j * 16 + (lane & 15);
;       bfr[j] = *(const bf16x8*)(S + 16384 + r * 64 + (((ks * 4 + (lane >> 4)) ^ ((r >> 1) & 7)) << 3));
;     }
;     __builtin_amdgcn_s_setprio(1);
; #pragma unroll
;     for (int i = 0; i < 8; ++i)
; #pragma unroll
;       for (int j = 0; j < 4; ++j) acc[i][j] = mfma16(bfr[j], af[i], acc[i][j]);
;     __builtin_amdgcn_s_setprio(0);
;   }
; }
; DI void gemm8_accum(f32x4 (&acc)[8][4], const bf16_t* a, size_t lda, const bf16_t* b, size_t ldb, int nkb, bf16_t* L,
;                     const bool pre, const bf16_t* an, size_t ldan, const bf16_t* bn, size_t ldbn) {
;     ...
;   for (int kb = 0; kb + 2 < nkb; ++kb) {
;     __syncthreads();
;     g8_store1(L + ((kb + 1) & 1) * 32768, ra, lrow, lch);
;     g8_load1o(ra, a + (kb + 2) * 64, offa);
;     __builtin_amdgcn_sched_barrier(0);
;     g8_compute<0, 1>(acc, L + (kb & 1) * 32768, wm, wn, lane);
;     __builtin_amdgcn_sched_barrier(0);
;     g8_store1(L + ((kb + 1) & 1) * 32768 + 16384, rb, lrow, lch);
;     g8_load1o(rb, b + (kb + 2) * 64, offb);
;     __builtin_amdgcn_sched_barrier(0);
;     g8_compute<1, 2>(acc, L + (kb & 1) * 32768, wm, wn, lane);
;   }
.LBB0_892:
	s_add_i32 s3, s2, 0x8000
	s_and_b32 s6, s3, 0x8000
	v_lshl_add_u32 v167, s6, 1, v163
	s_waitcnt lgkmcnt(0)
	s_barrier
	s_cmp_eq_u32 s100, 0
	s_cbranch_scc1 .Lstg_892_a
	v_mfma_f32_16x16x32_bf16 v[158:161], v[230:233], v[192:195], v[158:161]
	v_mfma_f32_16x16x32_bf16 v[154:157], v[234:237], v[192:195], v[154:157]
	v_mfma_f32_16x16x32_bf16 v[150:153], v[238:241], v[192:195], v[150:153]
	v_mfma_f32_16x16x32_bf16 v[146:149], v[242:245], v[192:195], v[146:149]
	v_mfma_f32_16x16x32_bf16 v[142:145], v[230:233], v[198:201], v[142:145]
	v_mfma_f32_16x16x32_bf16 v[138:141], v[234:237], v[198:201], v[138:141]
	v_mfma_f32_16x16x32_bf16 v[134:137], v[238:241], v[198:201], v[134:137]
	v_mfma_f32_16x16x32_bf16 v[130:133], v[242:245], v[198:201], v[130:133]
	v_mfma_f32_16x16x32_bf16 v[126:129], v[230:233], v[206:209], v[126:129]
	v_mfma_f32_16x16x32_bf16 v[122:125], v[234:237], v[206:209], v[122:125]
	v_mfma_f32_16x16x32_bf16 v[118:121], v[238:241], v[206:209], v[118:121]
	v_mfma_f32_16x16x32_bf16 v[114:117], v[242:245], v[206:209], v[114:117]
	v_mfma_f32_16x16x32_bf16 v[110:113], v[230:233], v[210:213], v[110:113]
	v_mfma_f32_16x16x32_bf16 v[106:109], v[234:237], v[210:213], v[106:109]
	v_mfma_f32_16x16x32_bf16 v[102:105], v[238:241], v[210:213], v[102:105]
	v_mfma_f32_16x16x32_bf16 v[98:101], v[242:245], v[210:213], v[98:101]
	v_mfma_f32_16x16x32_bf16 v[94:97], v[230:233], v[214:217], v[94:97]
	v_mfma_f32_16x16x32_bf16 v[90:93], v[234:237], v[214:217], v[90:93]
	v_mfma_f32_16x16x32_bf16 v[86:89], v[238:241], v[214:217], v[86:89]
	v_mfma_f32_16x16x32_bf16 v[82:85], v[242:245], v[214:217], v[82:85]
	v_mfma_f32_16x16x32_bf16 v[78:81], v[230:233], v[218:221], v[78:81]
	v_mfma_f32_16x16x32_bf16 v[74:77], v[234:237], v[218:221], v[74:77]
	v_mfma_f32_16x16x32_bf16 v[70:73], v[238:241], v[218:221], v[70:73]
	v_mfma_f32_16x16x32_bf16 v[66:69], v[242:245], v[218:221], v[66:69]
	v_mfma_f32_16x16x32_bf16 v[62:65], v[230:233], v[222:225], v[62:65]
	v_mfma_f32_16x16x32_bf16 v[58:61], v[234:237], v[222:225], v[58:61]
	v_mfma_f32_16x16x32_bf16 v[54:57], v[238:241], v[222:225], v[54:57]
	v_mfma_f32_16x16x32_bf16 v[50:53], v[242:245], v[222:225], v[50:53]
	v_mfma_f32_16x16x32_bf16 v[46:49], v[230:233], v[226:229], v[46:49]
	v_mfma_f32_16x16x32_bf16 v[42:45], v[234:237], v[226:229], v[42:45]
	v_mfma_f32_16x16x32_bf16 v[38:41], v[238:241], v[226:229], v[38:41]
	v_mfma_f32_16x16x32_bf16 v[34:37], v[242:245], v[226:229], v[34:37]
.Lstg_892_a:
	s_waitcnt vmcnt(5)
	ds_write_b128 v167, v[22:25]
	ds_write_b128 v167, v[18:21] offset:8192
	ds_write_b128 v167, v[26:29] offset:16384
	s_waitcnt vmcnt(4)
	ds_write_b128 v167, v[30:33] offset:24576
	v_lshl_add_u64 v[18:19], v[184:185], 0, s[0:1]
	v_lshl_add_u64 v[26:27], v[180:181], 0, s[0:1]
	global_load_dwordx4 v[22:25], v[18:19], off
	v_lshl_add_u64 v[30:31], v[178:179], 0, s[0:1]
	global_load_dwordx4 v[26:29], v[26:27], off
	v_lshl_add_u64 v[18:19], v[182:183], 0, s[0:1]
	global_load_dwordx4 v[18:21], v[18:19], off
	s_nop 0
	global_load_dwordx4 v[30:33], v[30:31], off
	s_and_b32 s2, s2, 0x8000
	s_lshl_b32 s2, s2, 1
	s_add_i32 s2, s2, 0
	v_lshl_add_u32 v169, v191, 1, s2
	v_add_u32_e32 v202, v169, v187
	ds_read_b128 v[192:195], v202
	ds_read_b128 v[198:201], v202 offset:2048
	ds_read_b128 v[206:209], v202 offset:4096
	ds_read_b128 v[210:213], v202 offset:6144
	ds_read_b128 v[214:217], v202 offset:8192
	ds_read_b128 v[218:221], v202 offset:10240
	ds_read_b128 v[222:225], v202 offset:12288
	ds_read_b128 v[226:229], v202 offset:14336
	v_add_u32_e32 v169, v169, v186
	ds_read_b128 v[230:233], v169 offset:32768
	ds_read_b128 v[234:237], v169 offset:34816
	ds_read_b128 v[238:241], v169 offset:36864
	ds_read_b128 v[242:245], v169 offset:38912
	s_waitcnt lgkmcnt(3)
	v_mfma_f32_16x16x32_bf16 v[158:161], v[230:233], v[192:195], v[158:161]
	s_waitcnt lgkmcnt(2)
	v_mfma_f32_16x16x32_bf16 v[154:157], v[234:237], v[192:195], v[154:157]
	s_waitcnt lgkmcnt(1)
	v_mfma_f32_16x16x32_bf16 v[150:153], v[238:241], v[192:195], v[150:153]
	s_waitcnt lgkmcnt(0)
	v_mfma_f32_16x16x32_bf16 v[146:149], v[242:245], v[192:195], v[146:149]
	v_mfma_f32_16x16x32_bf16 v[142:145], v[230:233], v[198:201], v[142:145]
	v_mfma_f32_16x16x32_bf16 v[138:141], v[234:237], v[198:201], v[138:141]
	v_mfma_f32_16x16x32_bf16 v[134:137], v[238:241], v[198:201], v[134:137]
	v_mfma_f32_16x16x32_bf16 v[130:133], v[242:245], v[198:201], v[130:133]
	v_mfma_f32_16x16x32_bf16 v[126:129], v[230:233], v[206:209], v[126:129]
	v_mfma_f32_16x16x32_bf16 v[122:125], v[234:237], v[206:209], v[122:125]
	v_mfma_f32_16x16x32_bf16 v[118:121], v[238:241], v[206:209], v[118:121]
	v_mfma_f32_16x16x32_bf16 v[114:117], v[242:245], v[206:209], v[114:117]
	v_mfma_f32_16x16x32_bf16 v[110:113], v[230:233], v[210:213], v[110:113]
	v_mfma_f32_16x16x32_bf16 v[106:109], v[234:237], v[210:213], v[106:109]
	v_mfma_f32_16x16x32_bf16 v[102:105], v[238:241], v[210:213], v[102:105]
	v_mfma_f32_16x16x32_bf16 v[98:101], v[242:245], v[210:213], v[98:101]
	v_mfma_f32_16x16x32_bf16 v[94:97], v[230:233], v[214:217], v[94:97]
	v_mfma_f32_16x16x32_bf16 v[90:93], v[234:237], v[214:217], v[90:93]
	v_mfma_f32_16x16x32_bf16 v[86:89], v[238:241], v[214:217], v[86:89]
	v_mfma_f32_16x16x32_bf16 v[82:85], v[242:245], v[214:217], v[82:85]
	v_mfma_f32_16x16x32_bf16 v[78:81], v[230:233], v[218:221], v[78:81]
	v_mfma_f32_16x16x32_bf16 v[74:77], v[234:237], v[218:221], v[74:77]
	v_mfma_f32_16x16x32_bf16 v[70:73], v[238:241], v[218:221], v[70:73]
	v_mfma_f32_16x16x32_bf16 v[66:69], v[242:245], v[218:221], v[66:69]
	v_mfma_f32_16x16x32_bf16 v[62:65], v[230:233], v[222:225], v[62:65]
	v_mfma_f32_16x16x32_bf16 v[58:61], v[234:237], v[222:225], v[58:61]
	v_mfma_f32_16x16x32_bf16 v[54:57], v[238:241], v[222:225], v[54:57]
	v_mfma_f32_16x16x32_bf16 v[50:53], v[242:245], v[222:225], v[50:53]
	v_mfma_f32_16x16x32_bf16 v[46:49], v[230:233], v[226:229], v[46:49]
	v_mfma_f32_16x16x32_bf16 v[42:45], v[234:237], v[226:229], v[42:45]
	v_mfma_f32_16x16x32_bf16 v[38:41], v[238:241], v[226:229], v[38:41]
	v_mfma_f32_16x16x32_bf16 v[34:37], v[242:245], v[226:229], v[34:37]
	s_waitcnt vmcnt(7)
; DI f32x4 mfma16(bf16x8 a, bf16x8 b, f32x4 c) { return __builtin_amdgcn_mfma_f32_16x16x32_bf16(a, b, c, 0, 0, 0); }
; #pragma unroll
;   for (int ks = KS0; ks < KS1; ++ks) {
;     bf16x8 af[8], bfr[4];
; #pragma unroll
;     for (int i = 0; i < 8; ++i) {
;       const int r = wm * 128 + i * 16 + (lane & 15);
;       af[i] = *(const bf16x8*)(S + r * 64 + (((ks * 4 + (lane >> 4)) ^ ((r >> 1) & 7)) << 3));
;     }
; #pragma unroll
;     for (int j = 0; j < 4; ++j) {
;       const int r = wn * 64 + j * 16 + (lane & 15);
;       bfr[j] = *(const bf16x8*)(S + 16384 + r * 64 + (((ks * 4 + (lane >> 4)) ^ ((r >> 1) & 7)) << 3));
;     }
;     __builtin_amdgcn_s_setprio(1);
; #pragma unroll
;     for (int i = 0; i < 8; ++i)
; #pragma unroll
;       for (int j = 0; j < 4; ++j) acc[i][j] = mfma16(bfr[j], af[i], acc[i][j]);
;     __builtin_amdgcn_s_setprio(0);
;   }
; }
; DI void gemm8_accum(f32x4 (&acc)[8][4], const bf16_t* a, size_t lda, const bf16_t* b, size_t ldb, int nkb, bf16_t* L,
;                     const bool pre, const bf16_t* an, size_t ldan, const bf16_t* bn, size_t ldbn) {
;     ...
;   for (int kb = 0; kb + 2 < nkb; ++kb) {
;     __syncthreads();
;     g8_store1(L + ((kb + 1) & 1) * 32768, ra, lrow, lch);
;     g8_load1o(ra, a + (kb + 2) * 64, offa);
;     __builtin_amdgcn_sched_barrier(0);
;     g8_compute<0, 1>(acc, L + (kb & 1) * 32768, wm, wn, lane);
;     __builtin_amdgcn_sched_barrier(0);
;     g8_store1(L + ((kb + 1) & 1) * 32768 + 16384, rb, lrow, lch);
;     g8_load1o(rb, b + (kb + 2) * 64, offb);
;     __builtin_amdgcn_sched_barrier(0);
;     g8_compute<1, 2>(acc, L + (kb & 1) * 32768, wm, wn, lane);
;   }
	ds_write_b128 v167, v[14:17] offset:32768
	s_waitcnt vmcnt(6)
	ds_write_b128 v167, v[2:5] offset:40960
	s_waitcnt vmcnt(5)
	ds_write_b128 v167, v[6:9] offset:49152
	s_waitcnt vmcnt(4)
	ds_write_b128 v167, v[10:13] offset:57344
	v_lshl_add_u64 v[2:3], v[176:177], 0, s[0:1]
	v_lshl_add_u64 v[4:5], v[174:175], 0, s[0:1]
	v_lshl_add_u64 v[6:7], v[172:173], 0, s[0:1]
	v_lshl_add_u64 v[10:11], v[170:171], 0, s[0:1]
	global_load_dwordx4 v[14:17], v[2:3], off
	s_nop 0
	global_load_dwordx4 v[2:5], v[4:5], off
	s_nop 0
	global_load_dwordx4 v[6:9], v[6:7], off
	s_nop 0
	global_load_dwordx4 v[10:13], v[10:11], off
	v_lshl_add_u32 v167, v188, 1, s2
	v_add_u32_e32 v169, v167, v187
	ds_read_b128 v[192:195], v169
	ds_read_b128 v[198:201], v169 offset:2048
	ds_read_b128 v[206:209], v169 offset:4096
	ds_read_b128 v[210:213], v169 offset:6144
	ds_read_b128 v[214:217], v169 offset:8192
	ds_read_b128 v[218:221], v169 offset:10240
	ds_read_b128 v[222:225], v169 offset:12288
	ds_read_b128 v[226:229], v169 offset:14336
	v_add_u32_e32 v167, v167, v186
	ds_read_b128 v[230:233], v167 offset:32768
	ds_read_b128 v[234:237], v167 offset:34816
	ds_read_b128 v[238:241], v167 offset:36864
	ds_read_b128 v[242:245], v167 offset:38912
	s_cmp_lg_u32 s101, 0
	s_cbranch_scc1 .Lstg_892_b
	s_waitcnt lgkmcnt(3)
	v_mfma_f32_16x16x32_bf16 v[158:161], v[230:233], v[192:195], v[158:161]
	s_waitcnt lgkmcnt(2)
	v_mfma_f32_16x16x32_bf16 v[154:157], v[234:237], v[192:195], v[154:157]
	s_waitcnt lgkmcnt(1)
	v_mfma_f32_16x16x32_bf16 v[150:153], v[238:241], v[192:195], v[150:153]
	s_waitcnt lgkmcnt(0)
	v_mfma_f32_16x16x32_bf16 v[146:149], v[242:245], v[192:195], v[146:149]
	v_mfma_f32_16x16x32_bf16 v[142:145], v[230:233], v[198:201], v[142:145]
	v_mfma_f32_16x16x32_bf16 v[138:141], v[234:237], v[198:201], v[138:141]
	v_mfma_f32_16x16x32_bf16 v[134:137], v[238:241], v[198:201], v[134:137]
	v_mfma_f32_16x16x32_bf16 v[130:133], v[242:245], v[198:201], v[130:133]
	v_mfma_f32_16x16x32_bf16 v[126:129], v[230:233], v[206:209], v[126:129]
	v_mfma_f32_16x16x32_bf16 v[122:125], v[234:237], v[206:209], v[122:125]
	v_mfma_f32_16x16x32_bf16 v[118:121], v[238:241], v[206:209], v[118:121]
	v_mfma_f32_16x16x32_bf16 v[114:117], v[242:245], v[206:209], v[114:117]
	v_mfma_f32_16x16x32_bf16 v[110:113], v[230:233], v[210:213], v[110:113]
	v_mfma_f32_16x16x32_bf16 v[106:109], v[234:237], v[210:213], v[106:109]
	v_mfma_f32_16x16x32_bf16 v[102:105], v[238:241], v[210:213], v[102:105]
	v_mfma_f32_16x16x32_bf16 v[98:101], v[242:245], v[210:213], v[98:101]
	v_mfma_f32_16x16x32_bf16 v[94:97], v[230:233], v[214:217], v[94:97]
	v_mfma_f32_16x16x32_bf16 v[90:93], v[234:237], v[214:217], v[90:93]
	v_mfma_f32_16x16x32_bf16 v[86:89], v[238:241], v[214:217], v[86:89]
	v_mfma_f32_16x16x32_bf16 v[82:85], v[242:245], v[214:217], v[82:85]
	v_mfma_f32_16x16x32_bf16 v[78:81], v[230:233], v[218:221], v[78:81]
	v_mfma_f32_16x16x32_bf16 v[74:77], v[234:237], v[218:221], v[74:77]
	v_mfma_f32_16x16x32_bf16 v[70:73], v[238:241], v[218:221], v[70:73]
	v_mfma_f32_16x16x32_bf16 v[66:69], v[242:245], v[218:221], v[66:69]
	v_mfma_f32_16x16x32_bf16 v[62:65], v[230:233], v[222:225], v[62:65]
	v_mfma_f32_16x16x32_bf16 v[58:61], v[234:237], v[222:225], v[58:61]
	v_mfma_f32_16x16x32_bf16 v[54:57], v[238:241], v[222:225], v[54:57]
	v_mfma_f32_16x16x32_bf16 v[50:53], v[242:245], v[222:225], v[50:53]
	v_mfma_f32_16x16x32_bf16 v[46:49], v[230:233], v[226:229], v[46:49]
	v_mfma_f32_16x16x32_bf16 v[42:45], v[234:237], v[226:229], v[42:45]
	v_mfma_f32_16x16x32_bf16 v[38:41], v[238:241], v[226:229], v[38:41]
	v_mfma_f32_16x16x32_bf16 v[34:37], v[242:245], v[226:229], v[34:37]
.Lstg_892_b:
	s_mov_b32 s100, s101
	s_add_u32 s0, s0, 0x80
	s_addc_u32 s1, s1, 0
	s_cmpk_lg_i32 s0, 0x700
	s_mov_b32 s2, s3
	s_cbranch_scc1 .LBB0_892
	s_cmp_eq_u32 s100, 0
	s_cbranch_scc1 .Lstg_892_c
	s_waitcnt lgkmcnt(0)
	v_mfma_f32_16x16x32_bf16 v[158:161], v[230:233], v[192:195], v[158:161]
	v_mfma_f32_16x16x32_bf16 v[154:157], v[234:237], v[192:195], v[154:157]
	v_mfma_f32_16x16x32_bf16 v[150:153], v[238:241], v[192:195], v[150:153]
	v_mfma_f32_16x16x32_bf16 v[146:149], v[242:245], v[192:195], v[146:149]
	v_mfma_f32_16x16x32_bf16 v[142:145], v[230:233], v[198:201], v[142:145]
	v_mfma_f32_16x16x32_bf16 v[138:141], v[234:237], v[198:201], v[138:141]
	v_mfma_f32_16x16x32_bf16 v[134:137], v[238:241], v[198:201], v[134:137]
	v_mfma_f32_16x16x32_bf16 v[130:133], v[242:245], v[198:201], v[130:133]
	v_mfma_f32_16x16x32_bf16 v[126:129], v[230:233], v[206:209], v[126:129]
	v_mfma_f32_16x16x32_bf16 v[122:125], v[234:237], v[206:209], v[122:125]
	v_mfma_f32_16x16x32_bf16 v[118:121], v[238:241], v[206:209], v[118:121]
	v_mfma_f32_16x16x32_bf16 v[114:117], v[242:245], v[206:209], v[114:117]
	v_mfma_f32_16x16x32_bf16 v[110:113], v[230:233], v[210:213], v[110:113]
	v_mfma_f32_16x16x32_bf16 v[106:109], v[234:237], v[210:213], v[106:109]
	v_mfma_f32_16x16x32_bf16 v[102:105], v[238:241], v[210:213], v[102:105]
	v_mfma_f32_16x16x32_bf16 v[98:101], v[242:245], v[210:213], v[98:101]
	v_mfma_f32_16x16x32_bf16 v[94:97], v[230:233], v[214:217], v[94:97]
	v_mfma_f32_16x16x32_bf16 v[90:93], v[234:237], v[214:217], v[90:93]
	v_mfma_f32_16x16x32_bf16 v[86:89], v[238:241], v[214:217], v[86:89]
	v_mfma_f32_16x16x32_bf16 v[82:85], v[242:245], v[214:217], v[82:85]
	v_mfma_f32_16x16x32_bf16 v[78:81], v[230:233], v[218:221], v[78:81]
	v_mfma_f32_16x16x32_bf16 v[74:77], v[234:237], v[218:221], v[74:77]
	v_mfma_f32_16x16x32_bf16 v[70:73], v[238:241], v[218:221], v[70:73]
	v_mfma_f32_16x16x32_bf16 v[66:69], v[242:245], v[218:221], v[66:69]
	v_mfma_f32_16x16x32_bf16 v[62:65], v[230:233], v[222:225], v[62:65]
	v_mfma_f32_16x16x32_bf16 v[58:61], v[234:237], v[222:225], v[58:61]
	v_mfma_f32_16x16x32_bf16 v[54:57], v[238:241], v[222:225], v[54:57]
	v_mfma_f32_16x16x32_bf16 v[50:53], v[242:245], v[222:225], v[50:53]
	v_mfma_f32_16x16x32_bf16 v[46:49], v[230:233], v[226:229], v[46:49]
	v_mfma_f32_16x16x32_bf16 v[42:45], v[234:237], v[226:229], v[42:45]
	v_mfma_f32_16x16x32_bf16 v[38:41], v[238:241], v[226:229], v[38:41]
	v_mfma_f32_16x16x32_bf16 v[34:37], v[242:245], v[226:229], v[34:37]
	s_mov_b32 s100, 0
; DI void gemm8_accum(f32x4 (&acc)[8][4], const bf16_t* a, size_t lda, const bf16_t* b, size_t ldb, int nkb, bf16_t* L,
;                     const bool pre, const bf16_t* an, size_t ldan, const bf16_t* bn, size_t ldbn) {
;     ...
;   __syncthreads();
;   g8_store1(L + 32768, ra, lrow, lch);
;   g8_load1(ra, an, ldan, 0, lrow, lch);
;   __builtin_amdgcn_sched_barrier(0);
;   g8_compute<0, 1>(acc, L, wm, wn, lane);
;   __builtin_amdgcn_sched_barrier(0);
;   g8_store1(L + 32768 + 16384, rb, lrow, lch);
;   g8_load1(rb, bn, ldbn, 0, lrow, lch);
;   __builtin_amdgcn_sched_barrier(0);
;   g8_compute<1, 2>(acc, L, wm, wn, lane);
;   __syncthreads();
;   g8_store1(L, ra, lrow, lch);
;   __builtin_amdgcn_sched_barrier(0);
;   g8_compute<0, 1>(acc, L + 32768, wm, wn, lane);
;   __builtin_amdgcn_sched_barrier(0);
;   g8_store1(L + 16384, rb, lrow, lch);
;   __builtin_amdgcn_sched_barrier(0);
;   g8_compute<1, 2>(acc, L + 32768, wm, wn, lane);
.Lstg_892_c:
	v_readlane_b32 s0, v254, 18
	s_add_i32 s12, s13, s0
	s_cmpk_gt_u32 s12, 0xff
	s_cselect_b64 s[0:1], -1, 0
	s_cmpk_lt_u32 s12, 0x100
	s_cselect_b32 s7, s12, s13
	s_lshr_b32 s2, s7, 1
	s_and_b32 s2, s2, 0x1fffffe0
	s_and_b32 s3, s7, 3
	s_or_b32 s2, s3, s2
	v_readlane_b32 s3, v252, 25
	s_or_b32 s28, s2, s3
	s_lshl_b32 s6, s20, 8
	s_lshl_b64 s[2:3], s[28:29], 19
	s_add_u32 s2, s18, s2
	v_mov_b32_e32 v169, v1
	v_mov_b32_e32 v167, v1
	s_addc_u32 s3, s19, s3
	v_lshlrev_b64 v[184:185], 1, v[168:169]
	v_lshlrev_b64 v[166:167], 1, v[166:167]
	v_lshlrev_b64 v[202:203], 1, v[0:1]
	v_lshl_add_u64 v[170:171], s[2:3], 0, v[164:165]
	v_lshl_add_u64 v[172:173], s[2:3], 0, v[184:185]
	v_lshl_add_u64 v[176:177], s[2:3], 0, v[166:167]
	v_lshl_add_u64 v[180:181], s[2:3], 0, v[202:203]
	s_barrier
	global_load_dwordx4 v[168:171], v[170:171], off
	s_nop 0
	global_load_dwordx4 v[172:175], v[172:173], off
	s_nop 0
	global_load_dwordx4 v[176:179], v[176:177], off
	s_nop 0
	global_load_dwordx4 v[180:183], v[180:181], off
	s_lshl_b32 s2, s7, 17
	s_and_b32 s2, s2, 0x780000
	v_readlane_b32 s20, v251, 61
	v_readlane_b32 s21, v251, 62
	s_add_u32 s2, s20, s2
	s_addc_u32 s3, s21, 0
	s_add_i32 s7, 0, 0x10000
	v_add3_u32 v0, s7, v189, v190
	s_waitcnt vmcnt(11)
	ds_write_b128 v0, v[22:25]
	s_waitcnt vmcnt(9)
	ds_write_b128 v0, v[18:21] offset:8192
	ds_write_b128 v0, v[26:29] offset:16384
	s_waitcnt vmcnt(8)
	ds_write_b128 v0, v[30:33] offset:24576
	v_lshlrev_b32_e32 v0, 1, v191
	v_add_u32_e32 v191, 0, v0
	v_add_u32_e32 v204, v191, v187
	ds_read_b128 v[18:21], v204
	ds_read_b128 v[22:25], v204 offset:2048
	ds_read_b128 v[26:29], v204 offset:4096
	ds_read_b128 v[30:33], v204 offset:6144
	ds_read_b128 v[192:195], v204 offset:8192
	ds_read_b128 v[198:201], v204 offset:10240
	ds_read_b128 v[206:209], v204 offset:12288
	ds_read_b128 v[210:213], v204 offset:14336
	v_add_u32_e32 v191, v191, v186
	ds_read_b128 v[214:217], v191 offset:32768
	ds_read_b128 v[218:221], v191 offset:34816
	ds_read_b128 v[222:225], v191 offset:36864
	ds_read_b128 v[226:229], v191 offset:38912
	s_waitcnt lgkmcnt(3)
	v_mfma_f32_16x16x32_bf16 v[158:161], v[214:217], v[18:21], v[158:161]
	s_waitcnt lgkmcnt(2)
	v_mfma_f32_16x16x32_bf16 v[154:157], v[218:221], v[18:21], v[154:157]
	s_waitcnt lgkmcnt(1)
	v_mfma_f32_16x16x32_bf16 v[150:153], v[222:225], v[18:21], v[150:153]
	s_waitcnt lgkmcnt(0)
	v_mfma_f32_16x16x32_bf16 v[18:21], v[226:229], v[18:21], v[146:149]
	v_mfma_f32_16x16x32_bf16 v[142:145], v[214:217], v[22:25], v[142:145]
	v_mfma_f32_16x16x32_bf16 v[138:141], v[218:221], v[22:25], v[138:141]
	v_mfma_f32_16x16x32_bf16 v[134:137], v[222:225], v[22:25], v[134:137]
	v_mfma_f32_16x16x32_bf16 v[22:25], v[226:229], v[22:25], v[130:133]
	v_mfma_f32_16x16x32_bf16 v[126:129], v[214:217], v[26:29], v[126:129]
	v_mfma_f32_16x16x32_bf16 v[122:125], v[218:221], v[26:29], v[122:125]
	v_mfma_f32_16x16x32_bf16 v[118:121], v[222:225], v[26:29], v[118:121]
	v_mfma_f32_16x16x32_bf16 v[26:29], v[226:229], v[26:29], v[114:117]
	v_mfma_f32_16x16x32_bf16 v[110:113], v[214:217], v[30:33], v[110:113]
	v_mfma_f32_16x16x32_bf16 v[106:109], v[218:221], v[30:33], v[106:109]
	v_mfma_f32_16x16x32_bf16 v[102:105], v[222:225], v[30:33], v[102:105]
	v_mfma_f32_16x16x32_bf16 v[30:33], v[226:229], v[30:33], v[98:101]
	v_mfma_f32_16x16x32_bf16 v[94:97], v[214:217], v[192:195], v[94:97]
	v_mfma_f32_16x16x32_bf16 v[90:93], v[218:221], v[192:195], v[90:93]
	v_mfma_f32_16x16x32_bf16 v[86:89], v[222:225], v[192:195], v[86:89]
	v_mfma_f32_16x16x32_bf16 v[82:85], v[226:229], v[192:195], v[82:85]
	v_mfma_f32_16x16x32_bf16 v[78:81], v[214:217], v[198:201], v[78:81]
	v_mfma_f32_16x16x32_bf16 v[74:77], v[218:221], v[198:201], v[74:77]
	v_mfma_f32_16x16x32_bf16 v[70:73], v[222:225], v[198:201], v[70:73]
	v_mfma_f32_16x16x32_bf16 v[66:69], v[226:229], v[198:201], v[66:69]
	v_mfma_f32_16x16x32_bf16 v[62:65], v[214:217], v[206:209], v[62:65]
	v_mfma_f32_16x16x32_bf16 v[58:61], v[218:221], v[206:209], v[58:61]
	v_mfma_f32_16x16x32_bf16 v[54:57], v[222:225], v[206:209], v[54:57]
	v_mfma_f32_16x16x32_bf16 v[50:53], v[226:229], v[206:209], v[50:53]
	v_mfma_f32_16x16x32_bf16 v[46:49], v[214:217], v[210:213], v[46:49]
	v_mfma_f32_16x16x32_bf16 v[42:45], v[218:221], v[210:213], v[42:45]
	v_mfma_f32_16x16x32_bf16 v[38:41], v[222:225], v[210:213], v[38:41]
	v_mfma_f32_16x16x32_bf16 v[34:37], v[226:229], v[210:213], v[34:37]
	v_readlane_b32 s13, v254, 36
	s_nop 1
	v_add3_u32 v98, s13, v189, v190
	s_waitcnt vmcnt(7)
	ds_write_b128 v98, v[14:17]
	s_waitcnt vmcnt(6)
	ds_write_b128 v98, v[2:5] offset:8192
	s_waitcnt vmcnt(5)
	ds_write_b128 v98, v[6:9] offset:16384
	s_waitcnt vmcnt(4)
	ds_write_b128 v98, v[10:13] offset:24576
	v_lshl_add_u64 v[2:3], s[2:3], 0, v[164:165]
	v_lshl_add_u64 v[6:7], s[2:3], 0, v[184:185]
	v_lshl_add_u64 v[10:11], s[2:3], 0, v[166:167]
	v_lshl_add_u64 v[14:15], s[2:3], 0, v[202:203]
	global_load_dwordx4 v[2:5], v[2:3], off
	s_nop 0
	global_load_dwordx4 v[6:9], v[6:7], off
	s_nop 0
	global_load_dwordx4 v[10:13], v[10:11], off
	s_nop 0
	global_load_dwordx4 v[14:17], v[14:15], off
	v_lshlrev_b32_e32 v202, 1, v188
	v_add_u32_e32 v184, 0, v202
	v_add_u32_e32 v185, v184, v187
	ds_read_b128 v[98:101], v185
	ds_read_b128 v[114:117], v185 offset:2048
	ds_read_b128 v[130:133], v185 offset:4096
	ds_read_b128 v[146:149], v185 offset:6144
	ds_read_b128 v[164:167], v185 offset:8192
	ds_read_b128 v[188:191], v185 offset:10240
	ds_read_b128 v[192:195], v185 offset:12288
	ds_read_b128 v[198:201], v185 offset:14336
	v_add_u32_e32 v184, v184, v186
	ds_read_b128 v[206:209], v184 offset:32768
	ds_read_b128 v[210:213], v184 offset:34816
	ds_read_b128 v[214:217], v184 offset:36864
	ds_read_b128 v[218:221], v184 offset:38912
	s_waitcnt lgkmcnt(3)
; DI void gemm8_accum(f32x4 (&acc)[8][4], const bf16_t* a, size_t lda, const bf16_t* b, size_t ldb, int nkb, bf16_t* L,
;                     const bool pre, const bf16_t* an, size_t ldan, const bf16_t* bn, size_t ldbn) {
;     ...
;   __syncthreads();
;   g8_store1(L + 32768, ra, lrow, lch);
;   g8_load1(ra, an, ldan, 0, lrow, lch);
;   __builtin_amdgcn_sched_barrier(0);
;   g8_compute<0, 1>(acc, L, wm, wn, lane);
;   __builtin_amdgcn_sched_barrier(0);
;   g8_store1(L + 32768 + 16384, rb, lrow, lch);
;   g8_load1(rb, bn, ldbn, 0, lrow, lch);
;   __builtin_amdgcn_sched_barrier(0);
;   g8_compute<1, 2>(acc, L, wm, wn, lane);
;   __syncthreads();
;   g8_store1(L, ra, lrow, lch);
;   __builtin_amdgcn_sched_barrier(0);
;   g8_compute<0, 1>(acc, L + 32768, wm, wn, lane);
;   __builtin_amdgcn_sched_barrier(0);
;   g8_store1(L + 16384, rb, lrow, lch);
;   __builtin_amdgcn_sched_barrier(0);
;   g8_compute<1, 2>(acc, L + 32768, wm, wn, lane);
	v_mfma_f32_16x16x32_bf16 v[158:161], v[206:209], v[98:101], v[158:161]
	s_waitcnt lgkmcnt(2)
	v_mfma_f32_16x16x32_bf16 v[154:157], v[210:213], v[98:101], v[154:157]
	s_waitcnt lgkmcnt(1)
	v_mfma_f32_16x16x32_bf16 v[150:153], v[214:217], v[98:101], v[150:153]
	s_waitcnt lgkmcnt(0)
	v_mfma_f32_16x16x32_bf16 v[18:21], v[218:221], v[98:101], v[18:21]
	v_mfma_f32_16x16x32_bf16 v[98:101], v[206:209], v[114:117], v[142:145]
	v_mfma_f32_16x16x32_bf16 v[138:141], v[210:213], v[114:117], v[138:141]
	v_mfma_f32_16x16x32_bf16 v[134:137], v[214:217], v[114:117], v[134:137]
	v_mfma_f32_16x16x32_bf16 v[22:25], v[218:221], v[114:117], v[22:25]
	v_mfma_f32_16x16x32_bf16 v[114:117], v[206:209], v[130:133], v[126:129]
	v_mfma_f32_16x16x32_bf16 v[122:125], v[210:213], v[130:133], v[122:125]
	v_mfma_f32_16x16x32_bf16 v[118:121], v[214:217], v[130:133], v[118:121]
	v_mfma_f32_16x16x32_bf16 v[26:29], v[218:221], v[130:133], v[26:29]
	v_mfma_f32_16x16x32_bf16 v[110:113], v[206:209], v[146:149], v[110:113]
	v_mfma_f32_16x16x32_bf16 v[106:109], v[210:213], v[146:149], v[106:109]
	v_mfma_f32_16x16x32_bf16 v[102:105], v[214:217], v[146:149], v[102:105]
	v_mfma_f32_16x16x32_bf16 v[30:33], v[218:221], v[146:149], v[30:33]
	v_mfma_f32_16x16x32_bf16 v[94:97], v[206:209], v[164:167], v[94:97]
	v_mfma_f32_16x16x32_bf16 v[90:93], v[210:213], v[164:167], v[90:93]
	v_mfma_f32_16x16x32_bf16 v[86:89], v[214:217], v[164:167], v[86:89]
	v_mfma_f32_16x16x32_bf16 v[82:85], v[218:221], v[164:167], v[82:85]
	v_mfma_f32_16x16x32_bf16 v[78:81], v[206:209], v[188:191], v[78:81]
	v_mfma_f32_16x16x32_bf16 v[74:77], v[210:213], v[188:191], v[74:77]
	v_mfma_f32_16x16x32_bf16 v[70:73], v[214:217], v[188:191], v[70:73]
	v_mfma_f32_16x16x32_bf16 v[66:69], v[218:221], v[188:191], v[66:69]
	v_mfma_f32_16x16x32_bf16 v[62:65], v[206:209], v[192:195], v[62:65]
	v_mfma_f32_16x16x32_bf16 v[58:61], v[210:213], v[192:195], v[58:61]
	v_mfma_f32_16x16x32_bf16 v[54:57], v[214:217], v[192:195], v[54:57]
	v_mfma_f32_16x16x32_bf16 v[50:53], v[218:221], v[192:195], v[50:53]
	v_mfma_f32_16x16x32_bf16 v[46:49], v[206:209], v[198:201], v[46:49]
	v_mfma_f32_16x16x32_bf16 v[42:45], v[210:213], v[198:201], v[42:45]
	v_mfma_f32_16x16x32_bf16 v[38:41], v[214:217], v[198:201], v[38:41]
	v_mfma_f32_16x16x32_bf16 v[34:37], v[218:221], v[198:201], v[34:37]
	s_barrier
	s_waitcnt vmcnt(7)
	ds_write_b128 v163, v[168:171]
	s_waitcnt vmcnt(6)
	ds_write_b128 v163, v[172:175] offset:8192
	s_waitcnt vmcnt(5)
	ds_write_b128 v163, v[176:179] offset:16384
	s_waitcnt vmcnt(4)
	ds_write_b128 v163, v[180:183] offset:24576
	v_add3_u32 v176, s7, v0, v187
	ds_read_b128 v[126:129], v176
	ds_read_b128 v[130:133], v176 offset:2048
	ds_read_b128 v[142:145], v176 offset:4096
	ds_read_b128 v[146:149], v176 offset:6144
	ds_read_b128 v[164:167], v176 offset:8192
	ds_read_b128 v[168:171], v176 offset:10240
	ds_read_b128 v[172:175], v176 offset:12288
	ds_read_b128 v[176:179], v176 offset:14336
	v_add3_u32 v0, s13, v0, v186
	ds_read_b128 v[180:183], v0
	ds_read_b128 v[188:191], v0 offset:2048
	ds_read_b128 v[192:195], v0 offset:4096
	ds_read_b128 v[198:201], v0 offset:6144
	s_waitcnt lgkmcnt(0)
	v_mfma_f32_16x16x32_bf16 v[18:21], v[198:201], v[126:129], v[18:21]
	v_mfma_f32_16x16x32_bf16 v[98:101], v[180:183], v[130:133], v[98:101]
	v_mfma_f32_16x16x32_bf16 v[138:141], v[188:191], v[130:133], v[138:141]
	v_mfma_f32_16x16x32_bf16 v[134:137], v[192:195], v[130:133], v[134:137]
	v_mfma_f32_16x16x32_bf16 v[22:25], v[198:201], v[130:133], v[22:25]
	v_mfma_f32_16x16x32_bf16 v[130:133], v[180:183], v[142:145], v[114:117]
	v_mfma_f32_16x16x32_bf16 v[26:29], v[198:201], v[142:145], v[26:29]
	v_mfma_f32_16x16x32_bf16 v[30:33], v[198:201], v[146:149], v[30:33]
	v_mfma_f32_16x16x32_bf16 v[54:57], v[192:195], v[172:175], v[54:57]
	v_mfma_f32_16x16x32_bf16 v[50:53], v[198:201], v[172:175], v[50:53]
	v_mfma_f32_16x16x32_bf16 v[158:161], v[180:183], v[126:129], v[158:161]
	v_mfma_f32_16x16x32_bf16 v[154:157], v[188:191], v[126:129], v[154:157]
	v_mfma_f32_16x16x32_bf16 v[150:153], v[192:195], v[126:129], v[150:153]
	v_mfma_f32_16x16x32_bf16 v[206:209], v[188:191], v[142:145], v[122:125]
	v_mfma_f32_16x16x32_bf16 v[210:213], v[192:195], v[142:145], v[118:121]
	v_mfma_f32_16x16x32_bf16 v[142:145], v[180:183], v[146:149], v[110:113]
	v_mfma_f32_16x16x32_bf16 v[214:217], v[188:191], v[146:149], v[106:109]
	v_mfma_f32_16x16x32_bf16 v[218:221], v[192:195], v[146:149], v[102:105]
	v_mfma_f32_16x16x32_bf16 v[146:149], v[180:183], v[164:167], v[94:97]
	v_mfma_f32_16x16x32_bf16 v[222:225], v[188:191], v[164:167], v[90:93]
	v_mfma_f32_16x16x32_bf16 v[226:229], v[192:195], v[164:167], v[86:89]
	v_mfma_f32_16x16x32_bf16 v[164:167], v[198:201], v[164:167], v[82:85]
	v_mfma_f32_16x16x32_bf16 v[230:233], v[180:183], v[168:171], v[78:81]
	v_mfma_f32_16x16x32_bf16 v[234:237], v[188:191], v[168:171], v[74:77]
	v_mfma_f32_16x16x32_bf16 v[238:241], v[192:195], v[168:171], v[70:73]
	v_mfma_f32_16x16x32_bf16 v[168:171], v[198:201], v[168:171], v[66:69]
	v_mfma_f32_16x16x32_bf16 v[242:245], v[180:183], v[172:175], v[62:65]
	v_mfma_f32_16x16x32_bf16 v[246:249], v[188:191], v[172:175], v[58:61]
	v_mfma_f32_16x16x32_bf16 v[182:185], v[180:183], v[176:179], v[46:49]
	v_mfma_f32_16x16x32_bf16 v[188:191], v[188:191], v[176:179], v[42:45]
	v_mfma_f32_16x16x32_bf16 v[192:195], v[192:195], v[176:179], v[38:41]
	v_mfma_f32_16x16x32_bf16 v[198:201], v[198:201], v[176:179], v[34:37]
	s_waitcnt vmcnt(3)
	ds_write_b128 v163, v[2:5] offset:32768
	s_waitcnt vmcnt(2)
	ds_write_b128 v163, v[6:9] offset:40960
	s_waitcnt vmcnt(1)
	ds_write_b128 v163, v[10:13] offset:49152
	s_waitcnt vmcnt(0)
; DI int TID8() { int t = threadIdx.x; asm volatile("" : "+v"(t)); return t; }
; DI void gemm8_accum(f32x4 (&acc)[8][4], const bf16_t* a, size_t lda, const bf16_t* b, size_t ldb, int nkb, bf16_t* L,
;                     const bool pre, const bf16_t* an, size_t ldan, const bf16_t* bn, size_t ldbn) {
;     ...
;   g8_compute<1, 2>(acc, L, wm, wn, lane);
;   __syncthreads();
;   g8_store1(L, ra, lrow, lch);
;   __builtin_amdgcn_sched_barrier(0);
;   g8_compute<0, 1>(acc, L + 32768, wm, wn, lane);
;   __builtin_amdgcn_sched_barrier(0);
;   g8_store1(L + 16384, rb, lrow, lch);
;   __builtin_amdgcn_sched_barrier(0);
;   g8_compute<1, 2>(acc, L + 32768, wm, wn, lane);
;   __syncthreads();
; DI void row_rs8(float (&rsv)[8], const float* rowpart, int m0) {
;   const int tid = TID8(), lane = tid & 63, wm = tid >> 8;
; #pragma unroll
;   for (int i = 0; i < 8; ++i) {
;     const int m = m0 + wm * 128 + i * 16 + (lane & 15);
;     float s = 0.f;
; #pragma unroll
;     for (int t = 0; t < 8; ++t) s += rowpart[(size_t)t * T_TOK + m];
;     rsv[i] = rsqrtf(s * (1.f / 1024.f) + 1e-6f);
;   }
	ds_write_b128 v163, v[14:17] offset:57344
	v_add3_u32 v0, s7, v202, v187
	ds_read_b128 v[2:5], v0
	ds_read_b128 v[6:9], v0 offset:2048
	ds_read_b128 v[10:13], v0 offset:4096
	ds_read_b128 v[58:61], v0 offset:6144
	ds_read_b128 v[34:37], v0 offset:8192
	ds_read_b128 v[38:41], v0 offset:10240
	ds_read_b128 v[42:45], v0 offset:12288
	ds_read_b128 v[46:49], v0 offset:14336
	v_add3_u32 v0, s13, v202, v186
	ds_read_b128 v[178:181], v0
	ds_read_b128 v[172:175], v0 offset:2048
	ds_read_b128 v[202:205], v0 offset:4096
	ds_read_b128 v[14:17], v0 offset:6144
	s_waitcnt lgkmcnt(3)
	v_mfma_f32_16x16x32_bf16 v[126:129], v[178:181], v[2:5], v[158:161]
	s_waitcnt lgkmcnt(2)
	v_mfma_f32_16x16x32_bf16 v[122:125], v[172:175], v[2:5], v[154:157]
	s_waitcnt lgkmcnt(1)
	v_mfma_f32_16x16x32_bf16 v[118:121], v[202:205], v[2:5], v[150:153]
	s_waitcnt lgkmcnt(0)
	v_mfma_f32_16x16x32_bf16 v[114:117], v[14:17], v[2:5], v[18:21]
	v_mfma_f32_16x16x32_bf16 v[110:113], v[178:181], v[6:9], v[98:101]
	v_mfma_f32_16x16x32_bf16 v[106:109], v[172:175], v[6:9], v[138:141]
	v_mfma_f32_16x16x32_bf16 v[102:105], v[202:205], v[6:9], v[134:137]
	v_mfma_f32_16x16x32_bf16 v[98:101], v[14:17], v[6:9], v[22:25]
	v_mfma_f32_16x16x32_bf16 v[94:97], v[178:181], v[10:13], v[130:133]
	v_mfma_f32_16x16x32_bf16 v[90:93], v[172:175], v[10:13], v[206:209]
	v_mfma_f32_16x16x32_bf16 v[86:89], v[202:205], v[10:13], v[210:213]
	v_mfma_f32_16x16x32_bf16 v[82:85], v[14:17], v[10:13], v[26:29]
	v_mfma_f32_16x16x32_bf16 v[78:81], v[178:181], v[58:61], v[142:145]
	v_mfma_f32_16x16x32_bf16 v[74:77], v[172:175], v[58:61], v[214:217]
	v_mfma_f32_16x16x32_bf16 v[70:73], v[202:205], v[58:61], v[218:221]
	v_mfma_f32_16x16x32_bf16 v[66:69], v[14:17], v[58:61], v[30:33]
	v_mfma_f32_16x16x32_bf16 v[62:65], v[178:181], v[34:37], v[146:149]
	v_mfma_f32_16x16x32_bf16 v[58:61], v[172:175], v[34:37], v[222:225]
	v_mfma_f32_16x16x32_bf16 v[222:225], v[202:205], v[34:37], v[226:229]
	v_mfma_f32_16x16x32_bf16 v[218:221], v[14:17], v[34:37], v[164:167]
	v_mfma_f32_16x16x32_bf16 v[214:217], v[178:181], v[38:41], v[230:233]
	v_mfma_f32_16x16x32_bf16 v[210:213], v[172:175], v[38:41], v[234:237]
	v_mfma_f32_16x16x32_bf16 v[206:209], v[202:205], v[38:41], v[238:241]
	v_mfma_f32_16x16x32_bf16 v[34:37], v[14:17], v[38:41], v[168:171]
	v_mfma_f32_16x16x32_bf16 v[30:33], v[178:181], v[42:45], v[242:245]
	v_mfma_f32_16x16x32_bf16 v[26:29], v[172:175], v[42:45], v[246:249]
	v_mfma_f32_16x16x32_bf16 v[22:25], v[202:205], v[42:45], v[54:57]
	v_mfma_f32_16x16x32_bf16 v[18:21], v[14:17], v[42:45], v[50:53]
	v_mfma_f32_16x16x32_bf16 v[38:41], v[178:181], v[46:49], v[182:185]
	v_mfma_f32_16x16x32_bf16 v[10:13], v[172:175], v[46:49], v[188:191]
	v_mfma_f32_16x16x32_bf16 v[6:9], v[202:205], v[46:49], v[192:195]
	v_mfma_f32_16x16x32_bf16 v[2:5], v[14:17], v[46:49], v[198:201]
	v_mov_b32_e32 v0, v196
	s_barrier
	v_readlane_b32 s2, v251, 51
	v_ashrrev_i32_e32 v14, 1, v0
	v_and_b32_e32 v14, 0xffffff80, v14
	v_and_or_b32 v0, v0, 15, s6
	v_add_u32_e32 v14, v0, v14
	v_ashrrev_i32_e32 v15, 31, v14
	v_readlane_b32 s3, v251, 52
	s_mov_b32 s20, 0x3a800000
	s_mov_b32 s13, 0x800000
	v_lshl_add_u64 v[140:141], v[14:15], 2, s[2:3]
	s_mov_b32 s2, 0x20000
	v_add_co_u32_e32 v138, vcc, s2, v140
	s_mov_b32 s2, 0x40000
	s_nop 0
	v_addc_co_u32_e32 v139, vcc, 0, v141, vcc
	v_add_co_u32_e32 v142, vcc, s2, v140
	s_mov_b32 s2, 0x60000
	s_nop 0
	v_addc_co_u32_e32 v143, vcc, 0, v141, vcc
	v_add_co_u32_e32 v144, vcc, s2, v140
	s_mov_b32 s2, 0x80000
	s_nop 0
	v_addc_co_u32_e32 v145, vcc, 0, v141, vcc
	v_add_co_u32_e32 v146, vcc, s2, v140
	s_mov_b32 s2, 0xa0000
	s_nop 0
	v_addc_co_u32_e32 v147, vcc, 0, v141, vcc
	v_add_co_u32_e32 v148, vcc, s2, v140
	s_mov_b32 s2, 0xc0000
	s_nop 0
	v_addc_co_u32_e32 v149, vcc, 0, v141, vcc
	v_add_co_u32_e32 v150, vcc, s2, v140
	s_mov_b32 s2, 0xe0000
	s_nop 0
	v_addc_co_u32_e32 v151, vcc, 0, v141, vcc
	v_add_co_u32_e32 v152, vcc, s2, v140
	global_load_dword v14, v[140:141], off
	global_load_dword v42, v[142:143], off
	global_load_dword v44, v[144:145], off
	global_load_dword v46, v[146:147], off
	global_load_dword v48, v[148:149], off
	global_load_dword v50, v[150:151], off
	global_load_dword v16, v[138:139], off
	v_addc_co_u32_e32 v153, vcc, 0, v141, vcc
	global_load_dword v52, v[152:153], off
	global_load_dword v15, v[140:141], off offset:64
	global_load_dword v17, v[138:139], off offset:64
	global_load_dword v43, v[142:143], off offset:64
	global_load_dword v45, v[144:145], off offset:64
	global_load_dword v47, v[146:147], off offset:64
	global_load_dword v49, v[148:149], off offset:64
	global_load_dword v51, v[150:151], off offset:64
	global_load_dword v53, v[152:153], off offset:64
	s_mov_b32 s2, 0x358637bd
	v_mov_b64_e32 v[132:133], s[2:3]
	s_mov_b32 s24, 0x45800000
	s_waitcnt vmcnt(7)
	v_pk_add_f32 v[14:15], v[14:15], 0 op_sel_hi:[1,0]
	s_waitcnt vmcnt(6)
	v_pk_add_f32 v[14:15], v[14:15], v[16:17]
	s_waitcnt vmcnt(5)
	v_pk_add_f32 v[14:15], v[14:15], v[42:43]
	s_waitcnt vmcnt(4)
	v_pk_add_f32 v[14:15], v[14:15], v[44:45]
	s_waitcnt vmcnt(3)
	v_pk_add_f32 v[14:15], v[14:15], v[46:47]
	s_waitcnt vmcnt(2)
	v_pk_add_f32 v[14:15], v[14:15], v[48:49]
	s_waitcnt vmcnt(1)
	v_pk_add_f32 v[14:15], v[14:15], v[50:51]
	s_waitcnt vmcnt(0)
; DI int TID8() { int t = threadIdx.x; asm volatile("" : "+v"(t)); return t; }
; DI void row_rs8(float (&rsv)[8], const float* rowpart, int m0) {
;   const int tid = TID8(), lane = tid & 63, wm = tid >> 8;
; #pragma unroll
;   for (int i = 0; i < 8; ++i) {
;     const int m = m0 + wm * 128 + i * 16 + (lane & 15);
;     float s = 0.f;
; #pragma unroll
;     for (int t = 0; t < 8; ++t) s += rowpart[(size_t)t * T_TOK + m];
;     rsv[i] = rsqrtf(s * (1.f / 1024.f) + 1e-6f);
;   }
; }
; DI void scale_rows8(f32x4 (&acc)[8][4], const float (&rsv)[8]) {
; #pragma unroll
;   for (int i = 0; i < 8; ++i)
; #pragma unroll
;     for (int j = 0; j < 4; ++j) acc[i][j] *= rsv[i];
	v_pk_add_f32 v[14:15], v[14:15], v[52:53]
	s_nop 0
	v_pk_fma_f32 v[14:15], v[14:15], s[20:21], v[132:133] op_sel_hi:[1,0,0]
	s_nop 0
	v_mul_f32_e32 v0, 0x4b800000, v14
	v_cmp_gt_f32_e64 s[2:3], s13, v14
	v_cmp_gt_f32_e32 vcc, s13, v15
	s_nop 0
	v_cndmask_b32_e64 v0, v14, v0, s[2:3]
	v_rsq_f32_e32 v14, v0
	v_mul_f32_e32 v0, 0x4b800000, v15
	v_cndmask_b32_e32 v0, v15, v0, vcc
	v_rsq_f32_e32 v15, v0
	s_nop 0
	v_pk_mul_f32 v[16:17], v[14:15], s[24:25] op_sel_hi:[1,0]
	s_nop 0
	v_cndmask_b32_e32 v0, v15, v17, vcc
	v_cndmask_b32_e64 v130, v14, v16, s[2:3]
	global_load_dword v14, v[140:141], off offset:128
	global_load_dword v16, v[138:139], off offset:128
	global_load_dword v42, v[142:143], off offset:128
	global_load_dword v44, v[144:145], off offset:128
	global_load_dword v46, v[146:147], off offset:128
	global_load_dword v48, v[148:149], off offset:128
	global_load_dword v50, v[150:151], off offset:128
	global_load_dword v52, v[152:153], off offset:128
	global_load_dword v15, v[140:141], off offset:192
	global_load_dword v17, v[138:139], off offset:192
	global_load_dword v43, v[142:143], off offset:192
	global_load_dword v45, v[144:145], off offset:192
	global_load_dword v47, v[146:147], off offset:192
	global_load_dword v49, v[148:149], off offset:192
	global_load_dword v51, v[150:151], off offset:192
	global_load_dword v53, v[152:153], off offset:192
	v_pk_mul_f32 v[112:113], v[112:113], v[0:1] op_sel_hi:[1,0]
	v_pk_mul_f32 v[110:111], v[110:111], v[0:1] op_sel_hi:[1,0]
	v_pk_mul_f32 v[108:109], v[108:109], v[0:1] op_sel_hi:[1,0]
	v_pk_mul_f32 v[106:107], v[106:107], v[0:1] op_sel_hi:[1,0]
	v_pk_mul_f32 v[104:105], v[104:105], v[0:1] op_sel_hi:[1,0]
	v_pk_mul_f32 v[100:101], v[100:101], v[0:1] op_sel_hi:[1,0]
	v_pk_mul_f32 v[98:99], v[98:99], v[0:1] op_sel_hi:[1,0]
	v_pk_mul_f32 v[54:55], v[116:117], v[130:131] op_sel_hi:[1,0]
	v_pk_mul_f32 v[56:57], v[114:115], v[130:131] op_sel_hi:[1,0]
	v_max_f32_e32 v116, v106, v106
	v_max_f32_e32 v117, v107, v107
	v_max_f32_e32 v114, v105, v105
	v_max_f32_e32 v107, v98, v98
	s_waitcnt vmcnt(7)
	v_pk_add_f32 v[14:15], v[14:15], 0 op_sel_hi:[1,0]
	s_waitcnt vmcnt(6)
	v_pk_add_f32 v[14:15], v[14:15], v[16:17]
	s_waitcnt vmcnt(5)
	v_pk_add_f32 v[14:15], v[14:15], v[42:43]
	s_waitcnt vmcnt(4)
	v_pk_add_f32 v[14:15], v[14:15], v[44:45]
	s_waitcnt vmcnt(3)
	v_pk_add_f32 v[14:15], v[14:15], v[46:47]
	s_waitcnt vmcnt(2)
	v_pk_add_f32 v[14:15], v[14:15], v[48:49]
	s_waitcnt vmcnt(1)
	v_pk_add_f32 v[14:15], v[14:15], v[50:51]
	s_waitcnt vmcnt(0)
	v_pk_add_f32 v[14:15], v[14:15], v[52:53]
	s_nop 0
	v_pk_fma_f32 v[14:15], v[14:15], s[20:21], v[132:133] op_sel_hi:[1,0,0]
	s_nop 0
	v_mul_f32_e32 v16, 0x4b800000, v14
	v_cmp_gt_f32_e64 s[2:3], s13, v14
	v_cmp_gt_f32_e32 vcc, s13, v15
	s_nop 0
	v_cndmask_b32_e64 v14, v14, v16, s[2:3]
	v_mul_f32_e32 v16, 0x4b800000, v15
	v_cndmask_b32_e32 v15, v15, v16, vcc
	v_rsq_f32_e32 v14, v14
	v_rsq_f32_e32 v15, v15
	s_nop 0
	v_pk_mul_f32 v[16:17], v[14:15], s[24:25] op_sel_hi:[1,0]
	s_nop 0
	v_cndmask_b32_e32 v134, v15, v17, vcc
	v_cndmask_b32_e64 v136, v14, v16, s[2:3]
	global_load_dword v14, v[140:141], off offset:256
	global_load_dword v16, v[138:139], off offset:256
	global_load_dword v42, v[142:143], off offset:256
	global_load_dword v44, v[144:145], off offset:256
	global_load_dword v46, v[146:147], off offset:256
	global_load_dword v48, v[148:149], off offset:256
	global_load_dword v50, v[150:151], off offset:256
	global_load_dword v52, v[152:153], off offset:256
	global_load_dword v15, v[140:141], off offset:320
	global_load_dword v17, v[138:139], off offset:320
	global_load_dword v43, v[142:143], off offset:320
	global_load_dword v45, v[144:145], off offset:320
	global_load_dword v47, v[146:147], off offset:320
	global_load_dword v49, v[148:149], off offset:320
	global_load_dword v51, v[150:151], off offset:320
	global_load_dword v53, v[152:153], off offset:320
	v_pk_mul_f32 v[96:97], v[96:97], v[136:137] op_sel_hi:[1,0]
	v_pk_mul_f32 v[94:95], v[94:95], v[136:137] op_sel_hi:[1,0]
	v_pk_mul_f32 v[92:93], v[92:93], v[136:137] op_sel_hi:[1,0]
	v_pk_mul_f32 v[90:91], v[90:91], v[136:137] op_sel_hi:[1,0]
	v_pk_mul_f32 v[88:89], v[88:89], v[136:137] op_sel_hi:[1,0]
	v_pk_mul_f32 v[86:87], v[86:87], v[136:137] op_sel_hi:[1,0]
	v_pk_mul_f32 v[82:83], v[82:83], v[136:137] op_sel_hi:[1,0]
	v_pk_mul_f32 v[80:81], v[80:81], v[134:135] op_sel_hi:[1,0]
	v_pk_mul_f32 v[78:79], v[78:79], v[134:135] op_sel_hi:[1,0]
	v_pk_mul_f32 v[76:77], v[76:77], v[134:135] op_sel_hi:[1,0]
	v_pk_mul_f32 v[74:75], v[74:75], v[134:135] op_sel_hi:[1,0]
	v_pk_mul_f32 v[72:73], v[72:73], v[134:135] op_sel_hi:[1,0]
	v_pk_mul_f32 v[70:71], v[70:71], v[134:135] op_sel_hi:[1,0]
	v_pk_mul_f32 v[66:67], v[66:67], v[134:135] op_sel_hi:[1,0]
	v_max_f32_e32 v105, v96, v96
	v_max_f32_e32 v106, v97, v97
	v_max_f32_e32 v98, v90, v90
	v_max_f32_e32 v96, v88, v88
	v_max_f32_e32 v97, v89, v89
	v_max_f32_e32 v90, v82, v82
	v_max_f32_e32 v88, v80, v80
	v_max_f32_e32 v89, v81, v81
	v_max_f32_e32 v81, v74, v74
	v_max_f32_e32 v82, v75, v75
	v_max_f32_e32 v80, v73, v73
	v_max_f32_e32 v73, v66, v66
	v_max_f32_e32 v74, v67, v67
	s_waitcnt vmcnt(7)
	v_pk_add_f32 v[14:15], v[14:15], 0 op_sel_hi:[1,0]
	s_waitcnt vmcnt(6)
	v_pk_add_f32 v[14:15], v[14:15], v[16:17]
	s_waitcnt vmcnt(5)
	v_pk_add_f32 v[14:15], v[14:15], v[42:43]
	s_waitcnt vmcnt(4)
	v_pk_add_f32 v[14:15], v[14:15], v[44:45]
	v_pk_mul_f32 v[44:45], v[126:127], v[130:131] op_sel_hi:[1,0]
	s_waitcnt vmcnt(3)
	v_pk_add_f32 v[14:15], v[14:15], v[46:47]
	v_pk_mul_f32 v[46:47], v[124:125], v[130:131] op_sel_hi:[1,0]
	s_waitcnt vmcnt(2)
; DI int TID8() { int t = threadIdx.x; asm volatile("" : "+v"(t)); return t; }
; DI void row_rs8(float (&rsv)[8], const float* rowpart, int m0) {
;   const int tid = TID8(), lane = tid & 63, wm = tid >> 8;
; #pragma unroll
;   for (int i = 0; i < 8; ++i) {
;     const int m = m0 + wm * 128 + i * 16 + (lane & 15);
;     float s = 0.f;
; #pragma unroll
;     for (int t = 0; t < 8; ++t) s += rowpart[(size_t)t * T_TOK + m];
;     rsv[i] = rsqrtf(s * (1.f / 1024.f) + 1e-6f);
;   }
; }
; DI void scale_rows8(f32x4 (&acc)[8][4], const float (&rsv)[8]) {
; #pragma unroll
;   for (int i = 0; i < 8; ++i)
; #pragma unroll
;     for (int j = 0; j < 4; ++j) acc[i][j] *= rsv[i];
	v_pk_add_f32 v[14:15], v[14:15], v[48:49]
	v_pk_mul_f32 v[48:49], v[122:123], v[130:131] op_sel_hi:[1,0]
	s_waitcnt vmcnt(1)
	v_pk_add_f32 v[14:15], v[14:15], v[50:51]
	v_pk_mul_f32 v[50:51], v[120:121], v[130:131] op_sel_hi:[1,0]
	s_waitcnt vmcnt(0)
	v_pk_add_f32 v[14:15], v[14:15], v[52:53]
	v_pk_mul_f32 v[52:53], v[118:119], v[130:131] op_sel_hi:[1,0]
	v_pk_fma_f32 v[14:15], v[14:15], s[20:21], v[132:133] op_sel_hi:[1,0,0]
	v_max_f32_e32 v124, v56, v56
	v_mul_f32_e32 v16, 0x4b800000, v14
	v_cmp_gt_f32_e64 s[2:3], s13, v14
	v_cmp_gt_f32_e32 vcc, s13, v15
	v_max_f32_e32 v125, v57, v57
	v_cndmask_b32_e64 v14, v14, v16, s[2:3]
	v_mul_f32_e32 v16, 0x4b800000, v15
	v_cndmask_b32_e32 v15, v15, v16, vcc
	v_rsq_f32_e32 v14, v14
	v_rsq_f32_e32 v15, v15
	v_max_f32_e32 v126, v54, v54
	v_max_f32_e32 v127, v55, v55
	v_max_f32_e32 v120, v110, v110
	v_pk_mul_f32 v[16:17], v[14:15], s[24:25] op_sel_hi:[1,0]
	v_max_f32_e32 v121, v111, v111
	v_cndmask_b32_e32 v154, v15, v17, vcc
	v_cndmask_b32_e64 v156, v14, v16, s[2:3]
	global_load_dword v14, v[140:141], off offset:384
	global_load_dword v172, v[138:139], off offset:384
	global_load_dword v170, v[142:143], off offset:384
	global_load_dword v168, v[144:145], off offset:384
	global_load_dword v166, v[146:147], off offset:384
	global_load_dword v164, v[148:149], off offset:384
	global_load_dword v160, v[150:151], off offset:384
	global_load_dword v158, v[152:153], off offset:384
	global_load_dword v15, v[140:141], off offset:448
	global_load_dword v173, v[138:139], off offset:448
	global_load_dword v171, v[142:143], off offset:448
	global_load_dword v169, v[144:145], off offset:448
	global_load_dword v167, v[146:147], off offset:448
	global_load_dword v165, v[148:149], off offset:448
	global_load_dword v161, v[150:151], off offset:448
	global_load_dword v159, v[152:153], off offset:448
	v_pk_mul_f32 v[144:145], v[84:85], v[136:137] op_sel_hi:[1,0]
	v_mov_b32_e32 v136, v196
	v_pk_mul_f32 v[142:143], v[102:103], v[0:1] op_sel_hi:[1,0]
	v_pk_mul_f32 v[146:147], v[68:69], v[134:135] op_sel_hi:[1,0]
	v_and_b32_e32 v0, 0xc0, v136
	v_lshlrev_b32_e32 v0, 1, v0
	v_pk_mul_f32 v[64:65], v[64:65], v[156:157] op_sel_hi:[1,0]
	v_pk_mul_f32 v[62:63], v[62:63], v[156:157] op_sel_hi:[1,0]
	v_pk_mul_f32 v[60:61], v[60:61], v[156:157] op_sel_hi:[1,0]
	v_pk_mul_f32 v[58:59], v[58:59], v[156:157] op_sel_hi:[1,0]
	v_pk_mul_f32 v[148:149], v[224:225], v[156:157] op_sel_hi:[1,0]
	v_pk_mul_f32 v[150:151], v[222:223], v[156:157] op_sel_hi:[1,0]
	v_pk_mul_f32 v[152:153], v[220:221], v[156:157] op_sel_hi:[1,0]
	v_pk_mul_f32 v[156:157], v[218:219], v[156:157] op_sel_hi:[1,0]
	v_pk_mul_f32 v[36:37], v[36:37], v[154:155] op_sel_hi:[1,0]
	v_max_f32_e32 v137, v44, v44
	v_max_f32_e32 v138, v45, v45
	v_max_f32_e32 v134, v46, v46
	v_max_f32_e32 v135, v47, v47
	v_max_f32_e32 v122, v112, v112
	v_max_f32_e32 v123, v113, v113
	v_max_f32_e32 v118, v108, v108
	v_max_f32_e32 v119, v109, v109
	v_max_f32_e32 v111, v142, v142
	v_max_f32_e32 v112, v143, v143
	v_max_f32_e32 v113, v104, v104
	v_max_f32_e32 v108, v99, v99
	v_max_f32_e32 v109, v100, v100
	v_max_f32_e32 v110, v101, v101
	v_max_f32_e32 v103, v94, v94
	v_max_f32_e32 v104, v95, v95
	v_max_f32_e32 v99, v91, v91
	v_max_f32_e32 v100, v92, v92
	v_max_f32_e32 v101, v93, v93
	v_max_f32_e32 v94, v86, v86
	v_max_f32_e32 v95, v87, v87
	v_max_f32_e32 v91, v83, v83
	v_max_f32_e32 v92, v144, v144
	v_max_f32_e32 v93, v145, v145
	v_max_f32_e32 v86, v78, v78
	v_max_f32_e32 v87, v79, v79
	v_max_f32_e32 v83, v76, v76
	v_max_f32_e32 v84, v77, v77
	v_max_f32_e32 v77, v70, v70
	v_max_f32_e32 v78, v71, v71
	v_max_f32_e32 v79, v72, v72
	v_max_f32_e32 v75, v146, v146
	v_max_f32_e32 v76, v147, v147
	v_max_f32_e32 v69, v62, v62
	v_max_f32_e32 v70, v63, v63
	v_max_f32_e32 v71, v64, v64
	v_max_f32_e32 v72, v65, v65
	v_max_f32_e32 v64, v58, v58
	v_max_f32_e32 v65, v59, v59
	v_max_f32_e32 v66, v60, v60
	v_max_f32_e32 v67, v61, v61
	v_max_f32_e32 v60, v150, v150
	v_max_f32_e32 v61, v151, v151
	v_max_f32_e32 v62, v148, v148
	v_max_f32_e32 v63, v149, v149
	v_max_f32_e32 v56, v156, v156
	v_max_f32_e32 v57, v157, v157
	v_max_f32_e32 v58, v152, v152
	v_max_f32_e32 v59, v153, v153
	s_waitcnt vmcnt(7)
	v_pk_add_f32 v[140:141], v[14:15], 0 op_sel_hi:[1,0]
	s_waitcnt vmcnt(6)
	v_pk_add_f32 v[14:15], v[140:141], v[172:173]
	s_waitcnt vmcnt(5)
	v_pk_add_f32 v[14:15], v[14:15], v[170:171]
	v_pk_mul_f32 v[170:171], v[206:207], v[154:155] op_sel_hi:[1,0]
	s_waitcnt vmcnt(4)
	v_pk_add_f32 v[14:15], v[14:15], v[168:169]
	v_pk_mul_f32 v[168:169], v[208:209], v[154:155] op_sel_hi:[1,0]
	s_waitcnt vmcnt(3)
	v_pk_add_f32 v[14:15], v[14:15], v[166:167]
	v_pk_mul_f32 v[166:167], v[210:211], v[154:155] op_sel_hi:[1,0]
	s_waitcnt vmcnt(2)
	v_pk_add_f32 v[14:15], v[14:15], v[164:165]
	v_pk_mul_f32 v[164:165], v[212:213], v[154:155] op_sel_hi:[1,0]
	s_waitcnt vmcnt(1)
	v_pk_add_f32 v[14:15], v[14:15], v[160:161]
	v_pk_mul_f32 v[160:161], v[214:215], v[154:155] op_sel_hi:[1,0]
	s_waitcnt vmcnt(0)
; DI int TID8() { int t = threadIdx.x; asm volatile("" : "+v"(t)); return t; }
; template <class F>
; DI void gemm8_epi_staged(f32x4 (&acc)[8][4], int m0, int n0, bf16_t* L0, F f, bf16_t* dst, size_t ld, int nmax) {
;   bf16_t* L = L0 + 32768;
;   const int tid = TID8(), lane = tid & 63, w = tid >> 6;
;   const int wm = w >> 2, wn = w & 3;
; #pragma unroll
;   for (int half = 0; half < 2; ++half) {
;     if (wm == half) {
; #pragma unroll
;       for (int i = 0; i < 8; ++i)
; #pragma unroll
;         for (int j = 0; j < 4; ++j) {
;           const int ml = i * 16 + (lane & 15);
;           const int nl = wn * 64 + j * 16 + (lane >> 4) * 4;
;           f32x4 a = acc[i][j];
;           f(m0 + half * 128 + ml, n0 + nl, a);
;           uint2 u;
;           u.x = pack2(a[0], a[1]);
;           u.y = pack2(a[2], a[3]);
;           *(uint2*)(L + ml * 264 + nl) = u;
;         }
; DI void row_rs8(float (&rsv)[8], const float* rowpart, int m0) {
;   const int tid = TID8(), lane = tid & 63, wm = tid >> 8;
; #pragma unroll
;   for (int i = 0; i < 8; ++i) {
;     const int m = m0 + wm * 128 + i * 16 + (lane & 15);
;     float s = 0.f;
; #pragma unroll
;     for (int t = 0; t < 8; ++t) s += rowpart[(size_t)t * T_TOK + m];
;     rsv[i] = rsqrtf(s * (1.f / 1024.f) + 1e-6f);
;   }
; }
; DI void scale_rows8(f32x4 (&acc)[8][4], const float (&rsv)[8]) {
; #pragma unroll
;   for (int i = 0; i < 8; ++i)
; #pragma unroll
;     for (int j = 0; j < 4; ++j) acc[i][j] *= rsv[i];
	v_pk_add_f32 v[14:15], v[14:15], v[158:159]
	v_pk_mul_f32 v[158:159], v[216:217], v[154:155] op_sel_hi:[1,0]
	v_pk_fma_f32 v[14:15], v[14:15], s[20:21], v[132:133] op_sel_hi:[1,0,0]
	v_pk_mul_f32 v[154:155], v[34:35], v[154:155] op_sel_hi:[1,0]
	v_mul_f32_e32 v16, 0x4b800000, v14
	v_cmp_gt_f32_e64 s[2:3], s13, v14
	v_cmp_gt_f32_e32 vcc, s13, v15
	v_max_f32_e32 v132, v48, v48
	v_cndmask_b32_e64 v14, v14, v16, s[2:3]
	v_mul_f32_e32 v16, 0x4b800000, v15
	v_cndmask_b32_e32 v15, v15, v16, vcc
	v_rsq_f32_e32 v14, v14
	v_rsq_f32_e32 v15, v15
	v_max_f32_e32 v133, v49, v49
	v_max_f32_e32 v54, v158, v158
	v_max_f32_e32 v55, v159, v159
	v_pk_mul_f32 v[16:17], v[14:15], s[24:25] op_sel_hi:[1,0]
	v_max_f32_e32 v47, v166, v166
	v_cndmask_b32_e32 v42, v15, v17, vcc
	v_pk_mul_f32 v[178:179], v[6:7], v[42:43] op_sel_hi:[1,0]
	v_lshrrev_b32_e32 v7, 1, v136
	v_cndmask_b32_e64 v14, v14, v16, s[2:3]
	v_and_b32_e32 v7, 24, v7
	s_movk_i32 s2, 0x100
	v_and_b32_e32 v6, 15, v136
	v_add3_u32 v0, s7, v0, v7
	v_cmp_gt_u32_e32 vcc, s2, v136
	s_movk_i32 s2, 0x210
	v_pk_mul_f32 v[16:17], v[128:129], v[130:131] op_sel_hi:[1,0]
	v_pk_mul_f32 v[32:33], v[32:33], v[14:15] op_sel_hi:[1,0]
	v_pk_mul_f32 v[30:31], v[30:31], v[14:15] op_sel_hi:[1,0]
	v_pk_mul_f32 v[28:29], v[28:29], v[14:15] op_sel_hi:[1,0]
	v_pk_mul_f32 v[26:27], v[26:27], v[14:15] op_sel_hi:[1,0]
	v_pk_mul_f32 v[24:25], v[24:25], v[14:15] op_sel_hi:[1,0]
	v_pk_mul_f32 v[22:23], v[22:23], v[14:15] op_sel_hi:[1,0]
	v_pk_mul_f32 v[20:21], v[20:21], v[14:15] op_sel_hi:[1,0]
	v_pk_mul_f32 v[14:15], v[18:19], v[14:15] op_sel_hi:[1,0]
	v_pk_mul_f32 v[172:173], v[40:41], v[42:43] op_sel_hi:[1,0]
	v_pk_mul_f32 v[18:19], v[38:39], v[42:43] op_sel_hi:[1,0]
	v_pk_mul_f32 v[174:175], v[12:13], v[42:43] op_sel_hi:[1,0]
	v_pk_mul_f32 v[10:11], v[10:11], v[42:43] op_sel_hi:[1,0]
	v_pk_mul_f32 v[176:177], v[8:9], v[42:43] op_sel_hi:[1,0]
	v_pk_mul_f32 v[4:5], v[4:5], v[42:43] op_sel_hi:[1,0]
	v_pk_mul_f32 v[2:3], v[2:3], v[42:43] op_sel_hi:[1,0]
	v_mad_u32_u24 v115, v6, s2, v0
	v_max_f32_e32 v139, v16, v16
	v_max_f32_e32 v140, v17, v17
	v_max_f32_e32 v128, v52, v52
	v_max_f32_e32 v129, v53, v53
	v_max_f32_e32 v130, v50, v50
	v_max_f32_e32 v131, v51, v51
	v_add_u32_e32 v102, 0x2000, v115
	v_add_u32_e32 v85, 0x4000, v115
	v_add_u32_e32 v68, 0x6000, v115
	v_add_u32_e32 v51, 0x8000, v115
	v_max_f32_e32 v52, v160, v160
	v_max_f32_e32 v53, v161, v161
	v_max_f32_e32 v48, v167, v167
	v_max_f32_e32 v49, v164, v164
	v_max_f32_e32 v50, v165, v165
	v_add_u32_e32 v34, 0xa000, v115
	v_max_f32_e32 v43, v170, v170
	v_max_f32_e32 v44, v171, v171
	v_max_f32_e32 v45, v168, v168
	v_max_f32_e32 v46, v169, v169
	v_max_f32_e32 v39, v154, v154
	v_max_f32_e32 v40, v155, v155
	v_max_f32_e32 v41, v36, v36
	v_max_f32_e32 v42, v37, v37
	v_max_f32_e32 v35, v30, v30
	v_max_f32_e32 v36, v31, v31
	v_max_f32_e32 v37, v32, v32
	v_max_f32_e32 v38, v33, v33
	v_max_f32_e32 v30, v26, v26
	v_max_f32_e32 v31, v27, v27
	v_max_f32_e32 v32, v28, v28
	v_max_f32_e32 v33, v29, v29
	v_add_u32_e32 v17, 0xc000, v115
	v_max_f32_e32 v26, v22, v22
	v_max_f32_e32 v27, v23, v23
	v_max_f32_e32 v28, v24, v24
	v_max_f32_e32 v29, v25, v25
	v_max_f32_e32 v22, v14, v14
	v_max_f32_e32 v23, v15, v15
	v_max_f32_e32 v24, v20, v20
	v_max_f32_e32 v25, v21, v21
	v_max_f32_e32 v18, v18, v18
	v_max_f32_e32 v19, v19, v19
	v_max_f32_e32 v20, v172, v172
	v_max_f32_e32 v21, v173, v173
	v_max_f32_e32 v13, v10, v10
	v_max_f32_e32 v14, v11, v11
	v_max_f32_e32 v15, v174, v174
	v_max_f32_e32 v16, v175, v175
	v_add_u32_e32 v6, 0xe000, v115
	v_max_f32_e32 v9, v178, v178
	v_max_f32_e32 v10, v179, v179
	v_max_f32_e32 v11, v176, v176
	v_max_f32_e32 v12, v177, v177
	v_max_f32_e32 v7, v2, v2
	v_max_f32_e32 v8, v3, v3
	v_max_f32_e32 v4, v4, v4
	s_and_saveexec_b64 s[2:3], vcc
	s_cbranch_execz .LBB0_895
	v_max_f32_e32 v2, 0, v137
	v_max_f32_e32 v3, 0, v138
	v_max_f32_e32 v142, 0, v139
	v_max_f32_e32 v143, 0, v140
	v_pk_mul_f32 v[2:3], v[2:3], v[2:3]
	v_pk_mul_f32 v[142:143], v[142:143], v[142:143]
	v_cvt_pk_bf16_f32 v2, v2, v3
	v_cvt_pk_bf16_f32 v3, v142, v143
	v_max_f32_e32 v142, 0, v132
	v_max_f32_e32 v143, 0, v133
	v_max_f32_e32 v144, 0, v134
	v_max_f32_e32 v145, 0, v135
	v_pk_mul_f32 v[142:143], v[142:143], v[142:143]
	v_pk_mul_f32 v[144:145], v[144:145], v[144:145]
	v_cvt_pk_bf16_f32 v142, v142, v143
	v_cvt_pk_bf16_f32 v143, v144, v145
	ds_write2_b64 v115, v[2:3], v[142:143] offset1:4
	v_max_f32_e32 v2, 0, v128
	v_max_f32_e32 v3, 0, v129
	v_max_f32_e32 v142, 0, v130
	v_max_f32_e32 v143, 0, v131
	v_pk_mul_f32 v[2:3], v[2:3], v[2:3]
	v_pk_mul_f32 v[142:143], v[142:143], v[142:143]
	v_cvt_pk_bf16_f32 v2, v2, v3
	v_cvt_pk_bf16_f32 v3, v142, v143
	v_max_f32_e32 v142, 0, v124
	v_max_f32_e32 v143, 0, v125
	v_max_f32_e32 v144, 0, v126
	v_max_f32_e32 v145, 0, v127
	v_pk_mul_f32 v[142:143], v[142:143], v[142:143]
	v_pk_mul_f32 v[144:145], v[144:145], v[144:145]
	v_cvt_pk_bf16_f32 v142, v142, v143
	v_cvt_pk_bf16_f32 v143, v144, v145
	ds_write2_b64 v115, v[2:3], v[142:143] offset0:8 offset1:12
	v_max_f32_e32 v2, 0, v120
	v_max_f32_e32 v3, 0, v121
	v_max_f32_e32 v142, 0, v122
	v_max_f32_e32 v143, 0, v123
	v_pk_mul_f32 v[2:3], v[2:3], v[2:3]
	v_pk_mul_f32 v[142:143], v[142:143], v[142:143]
	v_cvt_pk_bf16_f32 v2, v2, v3
	v_cvt_pk_bf16_f32 v3, v142, v143
	v_max_f32_e32 v142, 0, v116
	v_max_f32_e32 v143, 0, v117
	v_max_f32_e32 v144, 0, v118
	v_max_f32_e32 v145, 0, v119
	v_pk_mul_f32 v[142:143], v[142:143], v[142:143]
	v_pk_mul_f32 v[144:145], v[144:145], v[144:145]
	v_cvt_pk_bf16_f32 v142, v142, v143
	v_cvt_pk_bf16_f32 v143, v144, v145
	ds_write2_b64 v102, v[2:3], v[142:143] offset0:32 offset1:36
	v_max_f32_e32 v2, 0, v111
; template <class F>
; DI void gemm8_epi_staged(f32x4 (&acc)[8][4], int m0, int n0, bf16_t* L0, F f, bf16_t* dst, size_t ld, int nmax) {
;     ...
;     if (wm == half) {
; #pragma unroll
;       for (int i = 0; i < 8; ++i)
; #pragma unroll
;         for (int j = 0; j < 4; ++j) {
;           const int ml = i * 16 + (lane & 15);
;           const int nl = wn * 64 + j * 16 + (lane >> 4) * 4;
;           f32x4 a = acc[i][j];
;           f(m0 + half * 128 + ml, n0 + nl, a);
;           uint2 u;
;           u.x = pack2(a[0], a[1]);
;           u.y = pack2(a[2], a[3]);
;           *(uint2*)(L + ml * 264 + nl) = u;
;         }
; __global__ void __launch_bounds__(512, 2) mega(Params p) {
;     ...
;       gemm8_epi_staged(acc8, m0, n0, lds_all, [&](int, int, f32x4& a) {
;         float r0 = fmaxf(a[0], 0.f), r1 = fmaxf(a[1], 0.f), r2 = fmaxf(a[2], 0.f), r3 = fmaxf(a[3], 0.f);
;         a[0] = r0 * r0; a[1] = r1 * r1; a[2] = r2 * r2; a[3] = r3 * r3;
;       }, ubuf, 4096, 4096);
	v_max_f32_e32 v3, 0, v112
	v_max_f32_e32 v142, 0, v113
	v_max_f32_e32 v143, 0, v114
	v_pk_mul_f32 v[2:3], v[2:3], v[2:3]
	v_pk_mul_f32 v[142:143], v[142:143], v[142:143]
	v_cvt_pk_bf16_f32 v2, v2, v3
	v_cvt_pk_bf16_f32 v3, v142, v143
	v_max_f32_e32 v142, 0, v107
	v_max_f32_e32 v143, 0, v108
	v_max_f32_e32 v144, 0, v109
	v_max_f32_e32 v145, 0, v110
	v_pk_mul_f32 v[142:143], v[142:143], v[142:143]
	v_pk_mul_f32 v[144:145], v[144:145], v[144:145]
	v_cvt_pk_bf16_f32 v142, v142, v143
	v_cvt_pk_bf16_f32 v143, v144, v145
	ds_write2_b64 v102, v[2:3], v[142:143] offset0:40 offset1:44
	v_max_f32_e32 v2, 0, v103
	v_max_f32_e32 v3, 0, v104
	v_max_f32_e32 v142, 0, v105
	v_max_f32_e32 v143, 0, v106
	v_pk_mul_f32 v[2:3], v[2:3], v[2:3]
	v_pk_mul_f32 v[142:143], v[142:143], v[142:143]
	v_cvt_pk_bf16_f32 v2, v2, v3
	v_cvt_pk_bf16_f32 v3, v142, v143
	v_max_f32_e32 v142, 0, v98
	v_max_f32_e32 v143, 0, v99
	v_max_f32_e32 v144, 0, v100
	v_max_f32_e32 v145, 0, v101
	v_pk_mul_f32 v[142:143], v[142:143], v[142:143]
	v_pk_mul_f32 v[144:145], v[144:145], v[144:145]
	v_cvt_pk_bf16_f32 v142, v142, v143
	v_cvt_pk_bf16_f32 v143, v144, v145
	ds_write2_b64 v85, v[2:3], v[142:143] offset0:64 offset1:68
	v_max_f32_e32 v2, 0, v94
	v_max_f32_e32 v3, 0, v95
	v_max_f32_e32 v142, 0, v96
	v_max_f32_e32 v143, 0, v97
	v_pk_mul_f32 v[2:3], v[2:3], v[2:3]
	v_pk_mul_f32 v[142:143], v[142:143], v[142:143]
	v_cvt_pk_bf16_f32 v2, v2, v3
	v_cvt_pk_bf16_f32 v3, v142, v143
	v_max_f32_e32 v142, 0, v90
	v_max_f32_e32 v143, 0, v91
	v_max_f32_e32 v144, 0, v92
	v_max_f32_e32 v145, 0, v93
	v_pk_mul_f32 v[142:143], v[142:143], v[142:143]
	v_pk_mul_f32 v[144:145], v[144:145], v[144:145]
	v_cvt_pk_bf16_f32 v142, v142, v143
	v_cvt_pk_bf16_f32 v143, v144, v145
	ds_write2_b64 v85, v[2:3], v[142:143] offset0:72 offset1:76
	v_max_f32_e32 v2, 0, v86
	v_max_f32_e32 v3, 0, v87
	v_max_f32_e32 v142, 0, v88
	v_max_f32_e32 v143, 0, v89
	v_pk_mul_f32 v[2:3], v[2:3], v[2:3]
	v_pk_mul_f32 v[142:143], v[142:143], v[142:143]
	v_cvt_pk_bf16_f32 v2, v2, v3
	v_cvt_pk_bf16_f32 v3, v142, v143
	v_max_f32_e32 v142, 0, v81
	v_max_f32_e32 v143, 0, v82
	v_max_f32_e32 v144, 0, v83
	v_max_f32_e32 v145, 0, v84
	v_pk_mul_f32 v[142:143], v[142:143], v[142:143]
	v_pk_mul_f32 v[144:145], v[144:145], v[144:145]
	v_cvt_pk_bf16_f32 v142, v142, v143
	v_cvt_pk_bf16_f32 v143, v144, v145
	ds_write2_b64 v68, v[2:3], v[142:143] offset0:96 offset1:100
	v_max_f32_e32 v2, 0, v77
	v_max_f32_e32 v3, 0, v78
	v_max_f32_e32 v142, 0, v79
	v_max_f32_e32 v143, 0, v80
	v_pk_mul_f32 v[2:3], v[2:3], v[2:3]
	v_pk_mul_f32 v[142:143], v[142:143], v[142:143]
	v_cvt_pk_bf16_f32 v2, v2, v3
	v_cvt_pk_bf16_f32 v3, v142, v143
	v_max_f32_e32 v142, 0, v73
	v_max_f32_e32 v143, 0, v74
	v_max_f32_e32 v144, 0, v75
	v_max_f32_e32 v145, 0, v76
	v_pk_mul_f32 v[142:143], v[142:143], v[142:143]
	v_pk_mul_f32 v[144:145], v[144:145], v[144:145]
	v_cvt_pk_bf16_f32 v142, v142, v143
	v_cvt_pk_bf16_f32 v143, v144, v145
	ds_write2_b64 v68, v[2:3], v[142:143] offset0:104 offset1:108
	v_max_f32_e32 v2, 0, v69
	v_max_f32_e32 v3, 0, v70
	v_max_f32_e32 v142, 0, v71
	v_max_f32_e32 v143, 0, v72
	v_pk_mul_f32 v[2:3], v[2:3], v[2:3]
	v_pk_mul_f32 v[142:143], v[142:143], v[142:143]
	v_cvt_pk_bf16_f32 v2, v2, v3
	v_cvt_pk_bf16_f32 v3, v142, v143
	v_max_f32_e32 v142, 0, v64
	v_max_f32_e32 v143, 0, v65
	v_max_f32_e32 v144, 0, v66
	v_max_f32_e32 v145, 0, v67
	v_pk_mul_f32 v[142:143], v[142:143], v[142:143]
	v_pk_mul_f32 v[144:145], v[144:145], v[144:145]
	v_cvt_pk_bf16_f32 v142, v142, v143
	v_cvt_pk_bf16_f32 v143, v144, v145
	ds_write2_b64 v51, v[2:3], v[142:143] offset0:128 offset1:132
	v_max_f32_e32 v2, 0, v60
	v_max_f32_e32 v3, 0, v61
	v_max_f32_e32 v142, 0, v62
	v_max_f32_e32 v143, 0, v63
	v_pk_mul_f32 v[2:3], v[2:3], v[2:3]
	v_pk_mul_f32 v[142:143], v[142:143], v[142:143]
	v_cvt_pk_bf16_f32 v2, v2, v3
	v_cvt_pk_bf16_f32 v3, v142, v143
	v_max_f32_e32 v142, 0, v56
	v_max_f32_e32 v143, 0, v57
; template <class F>
; DI void gemm8_epi_staged(f32x4 (&acc)[8][4], int m0, int n0, bf16_t* L0, F f, bf16_t* dst, size_t ld, int nmax) {
;     ...
;     if (wm == half) {
; #pragma unroll
;       for (int i = 0; i < 8; ++i)
; #pragma unroll
;         for (int j = 0; j < 4; ++j) {
;           const int ml = i * 16 + (lane & 15);
;           const int nl = wn * 64 + j * 16 + (lane >> 4) * 4;
;           f32x4 a = acc[i][j];
;           f(m0 + half * 128 + ml, n0 + nl, a);
;           uint2 u;
;           u.x = pack2(a[0], a[1]);
;           u.y = pack2(a[2], a[3]);
;           *(uint2*)(L + ml * 264 + nl) = u;
;         }
; __global__ void __launch_bounds__(512, 2) mega(Params p) {
;     ...
;       gemm8_epi_staged(acc8, m0, n0, lds_all, [&](int, int, f32x4& a) {
;         float r0 = fmaxf(a[0], 0.f), r1 = fmaxf(a[1], 0.f), r2 = fmaxf(a[2], 0.f), r3 = fmaxf(a[3], 0.f);
;         a[0] = r0 * r0; a[1] = r1 * r1; a[2] = r2 * r2; a[3] = r3 * r3;
;       }, ubuf, 4096, 4096);
	v_max_f32_e32 v144, 0, v58
	v_max_f32_e32 v145, 0, v59
	v_pk_mul_f32 v[142:143], v[142:143], v[142:143]
	v_pk_mul_f32 v[144:145], v[144:145], v[144:145]
	v_cvt_pk_bf16_f32 v142, v142, v143
	v_cvt_pk_bf16_f32 v143, v144, v145
	ds_write2_b64 v51, v[2:3], v[142:143] offset0:136 offset1:140
	v_max_f32_e32 v2, 0, v52
	v_max_f32_e32 v3, 0, v53
	v_max_f32_e32 v142, 0, v54
	v_max_f32_e32 v143, 0, v55
	v_pk_mul_f32 v[2:3], v[2:3], v[2:3]
	v_pk_mul_f32 v[142:143], v[142:143], v[142:143]
	v_cvt_pk_bf16_f32 v2, v2, v3
	v_cvt_pk_bf16_f32 v3, v142, v143
	v_max_f32_e32 v142, 0, v47
	v_max_f32_e32 v143, 0, v48
	v_max_f32_e32 v144, 0, v49
	v_max_f32_e32 v145, 0, v50
	v_pk_mul_f32 v[142:143], v[142:143], v[142:143]
	v_pk_mul_f32 v[144:145], v[144:145], v[144:145]
	v_cvt_pk_bf16_f32 v142, v142, v143
	v_cvt_pk_bf16_f32 v143, v144, v145
	ds_write2_b64 v34, v[2:3], v[142:143] offset0:160 offset1:164
	v_max_f32_e32 v2, 0, v43
	v_max_f32_e32 v3, 0, v44
	v_max_f32_e32 v142, 0, v45
	v_max_f32_e32 v143, 0, v46
	v_pk_mul_f32 v[2:3], v[2:3], v[2:3]
	v_pk_mul_f32 v[142:143], v[142:143], v[142:143]
	v_cvt_pk_bf16_f32 v2, v2, v3
	v_cvt_pk_bf16_f32 v3, v142, v143
	v_max_f32_e32 v142, 0, v39
	v_max_f32_e32 v143, 0, v40
	v_max_f32_e32 v144, 0, v41
	v_max_f32_e32 v145, 0, v42
	v_pk_mul_f32 v[142:143], v[142:143], v[142:143]
	v_pk_mul_f32 v[144:145], v[144:145], v[144:145]
	v_cvt_pk_bf16_f32 v142, v142, v143
	v_cvt_pk_bf16_f32 v143, v144, v145
	ds_write2_b64 v34, v[2:3], v[142:143] offset0:168 offset1:172
	v_max_f32_e32 v2, 0, v35
	v_max_f32_e32 v3, 0, v36
	v_max_f32_e32 v142, 0, v37
	v_max_f32_e32 v143, 0, v38
	v_pk_mul_f32 v[2:3], v[2:3], v[2:3]
	v_pk_mul_f32 v[142:143], v[142:143], v[142:143]
	v_cvt_pk_bf16_f32 v2, v2, v3
	v_cvt_pk_bf16_f32 v3, v142, v143
	v_max_f32_e32 v142, 0, v30
	v_max_f32_e32 v143, 0, v31
	v_max_f32_e32 v144, 0, v32
	v_max_f32_e32 v145, 0, v33
	v_pk_mul_f32 v[142:143], v[142:143], v[142:143]
	v_pk_mul_f32 v[144:145], v[144:145], v[144:145]
	v_cvt_pk_bf16_f32 v142, v142, v143
	v_cvt_pk_bf16_f32 v143, v144, v145
	ds_write2_b64 v17, v[2:3], v[142:143] offset0:192 offset1:196
	v_max_f32_e32 v2, 0, v26
	v_max_f32_e32 v3, 0, v27
	v_max_f32_e32 v142, 0, v28
	v_max_f32_e32 v143, 0, v29
	v_pk_mul_f32 v[2:3], v[2:3], v[2:3]
	v_pk_mul_f32 v[142:143], v[142:143], v[142:143]
	v_cvt_pk_bf16_f32 v2, v2, v3
	v_cvt_pk_bf16_f32 v3, v142, v143
	v_max_f32_e32 v142, 0, v22
	v_max_f32_e32 v143, 0, v23
	v_max_f32_e32 v144, 0, v24
	v_max_f32_e32 v145, 0, v25
	v_pk_mul_f32 v[142:143], v[142:143], v[142:143]
	v_pk_mul_f32 v[144:145], v[144:145], v[144:145]
	v_cvt_pk_bf16_f32 v142, v142, v143
	v_cvt_pk_bf16_f32 v143, v144, v145
	ds_write2_b64 v17, v[2:3], v[142:143] offset0:200 offset1:204
	v_max_f32_e32 v2, 0, v18
	v_max_f32_e32 v3, 0, v19
	v_max_f32_e32 v142, 0, v20
	v_max_f32_e32 v143, 0, v21
	v_pk_mul_f32 v[2:3], v[2:3], v[2:3]
	v_pk_mul_f32 v[142:143], v[142:143], v[142:143]
	v_cvt_pk_bf16_f32 v2, v2, v3
	v_cvt_pk_bf16_f32 v3, v142, v143
	v_max_f32_e32 v142, 0, v13
	v_max_f32_e32 v143, 0, v14
	v_max_f32_e32 v144, 0, v15
	v_max_f32_e32 v145, 0, v16
	v_pk_mul_f32 v[142:143], v[142:143], v[142:143]
	v_pk_mul_f32 v[144:145], v[144:145], v[144:145]
	v_cvt_pk_bf16_f32 v142, v142, v143
	v_cvt_pk_bf16_f32 v143, v144, v145
	ds_write2_b64 v6, v[2:3], v[142:143] offset0:224 offset1:228
	v_max_f32_e32 v2, 0, v9
	v_max_f32_e32 v3, 0, v10
	v_max_f32_e32 v142, 0, v11
	v_max_f32_e32 v143, 0, v12
	v_pk_mul_f32 v[2:3], v[2:3], v[2:3]
	v_pk_mul_f32 v[142:143], v[142:143], v[142:143]
	v_max_f32_e32 v0, v5, v5
	v_cvt_pk_bf16_f32 v2, v2, v3
	v_cvt_pk_bf16_f32 v3, v142, v143
	v_max_f32_e32 v142, 0, v7
	v_max_f32_e32 v143, 0, v8
	v_max_f32_e32 v144, 0, v4
	v_max_f32_e32 v145, 0, v0
	v_pk_mul_f32 v[142:143], v[142:143], v[142:143]
	v_pk_mul_f32 v[144:145], v[144:145], v[144:145]
	v_cvt_pk_bf16_f32 v142, v142, v143
	v_cvt_pk_bf16_f32 v143, v144, v145
	ds_write2_b64 v6, v[2:3], v[142:143] offset0:232 offset1:236

; DI f32x4 mfma16(bf16x8 a, bf16x8 b, f32x4 c) { return __builtin_amdgcn_mfma_f32_16x16x32_bf16(a, b, c, 0, 0, 0); }
; #pragma unroll
;   for (int ks = KS0; ks < KS1; ++ks) {
;     bf16x8 af[8], bfr[4];
; #pragma unroll
;     for (int i = 0; i < 8; ++i) {
;       const int r = wm * 128 + i * 16 + (lane & 15);
;       af[i] = *(const bf16x8*)(S + r * 64 + (((ks * 4 + (lane >> 4)) ^ ((r >> 1) & 7)) << 3));
;     }
; #pragma unroll
;     for (int j = 0; j < 4; ++j) {
;       const int r = wn * 64 + j * 16 + (lane & 15);
;       bfr[j] = *(const bf16x8*)(S + 16384 + r * 64 + (((ks * 4 + (lane >> 4)) ^ ((r >> 1) & 7)) << 3));
;     }
;     __builtin_amdgcn_s_setprio(1);
; #pragma unroll
;     for (int i = 0; i < 8; ++i)
; #pragma unroll
;       for (int j = 0; j < 4; ++j) acc[i][j] = mfma16(bfr[j], af[i], acc[i][j]);
;     __builtin_amdgcn_s_setprio(0);
;   }
; }
; DI void gemm8_accum(f32x4 (&acc)[8][4], const bf16_t* a, size_t lda, const bf16_t* b, size_t ldb, int nkb, bf16_t* L,
;                     const bool pre, const bf16_t* an, size_t ldan, const bf16_t* bn, size_t ldbn) {
;     ...
;   for (int kb = 0; kb + 2 < nkb; ++kb) {
;     __syncthreads();
;     g8_store1(L + ((kb + 1) & 1) * 32768, ra, lrow, lch);
;     g8_load1o(ra, a + (kb + 2) * 64, offa);
;     __builtin_amdgcn_sched_barrier(0);
;     g8_compute<0, 1>(acc, L + (kb & 1) * 32768, wm, wn, lane);
;     __builtin_amdgcn_sched_barrier(0);
;     g8_store1(L + ((kb + 1) & 1) * 32768 + 16384, rb, lrow, lch);
;     g8_load1o(rb, b + (kb + 2) * 64, offb);
;     __builtin_amdgcn_sched_barrier(0);
;     g8_compute<1, 2>(acc, L + (kb & 1) * 32768, wm, wn, lane);
;   }
.LBB0_942:
	s_add_i32 s3, s2, 0x8000
	s_and_b32 s7, s3, 0x8000
	v_lshl_add_u32 v167, s7, 1, v163
	s_waitcnt lgkmcnt(0)
	s_barrier
	s_cmp_eq_u32 s100, 0
	s_cbranch_scc1 .Lstg_942_a
	v_mfma_f32_16x16x32_bf16 v[158:161], v[226:229], v[192:195], v[158:161]
	v_mfma_f32_16x16x32_bf16 v[154:157], v[230:233], v[192:195], v[154:157]
	v_mfma_f32_16x16x32_bf16 v[150:153], v[234:237], v[192:195], v[150:153]
	v_mfma_f32_16x16x32_bf16 v[146:149], v[238:241], v[192:195], v[146:149]
	v_mfma_f32_16x16x32_bf16 v[142:145], v[226:229], v[198:201], v[142:145]
	v_mfma_f32_16x16x32_bf16 v[138:141], v[230:233], v[198:201], v[138:141]
	v_mfma_f32_16x16x32_bf16 v[134:137], v[234:237], v[198:201], v[134:137]
	v_mfma_f32_16x16x32_bf16 v[130:133], v[238:241], v[198:201], v[130:133]
	v_mfma_f32_16x16x32_bf16 v[126:129], v[226:229], v[202:205], v[126:129]
	v_mfma_f32_16x16x32_bf16 v[122:125], v[230:233], v[202:205], v[122:125]
	v_mfma_f32_16x16x32_bf16 v[118:121], v[234:237], v[202:205], v[118:121]
	v_mfma_f32_16x16x32_bf16 v[114:117], v[238:241], v[202:205], v[114:117]
	v_mfma_f32_16x16x32_bf16 v[110:113], v[226:229], v[206:209], v[110:113]
	v_mfma_f32_16x16x32_bf16 v[106:109], v[230:233], v[206:209], v[106:109]
	v_mfma_f32_16x16x32_bf16 v[102:105], v[234:237], v[206:209], v[102:105]
	v_mfma_f32_16x16x32_bf16 v[98:101], v[238:241], v[206:209], v[98:101]
	v_mfma_f32_16x16x32_bf16 v[94:97], v[226:229], v[210:213], v[94:97]
	v_mfma_f32_16x16x32_bf16 v[90:93], v[230:233], v[210:213], v[90:93]
	v_mfma_f32_16x16x32_bf16 v[86:89], v[234:237], v[210:213], v[86:89]
	v_mfma_f32_16x16x32_bf16 v[82:85], v[238:241], v[210:213], v[82:85]
	v_mfma_f32_16x16x32_bf16 v[78:81], v[226:229], v[214:217], v[78:81]
	v_mfma_f32_16x16x32_bf16 v[74:77], v[230:233], v[214:217], v[74:77]
	v_mfma_f32_16x16x32_bf16 v[70:73], v[234:237], v[214:217], v[70:73]
	v_mfma_f32_16x16x32_bf16 v[66:69], v[238:241], v[214:217], v[66:69]
	v_mfma_f32_16x16x32_bf16 v[62:65], v[226:229], v[218:221], v[62:65]
	v_mfma_f32_16x16x32_bf16 v[58:61], v[230:233], v[218:221], v[58:61]
	v_mfma_f32_16x16x32_bf16 v[54:57], v[234:237], v[218:221], v[54:57]
	v_mfma_f32_16x16x32_bf16 v[50:53], v[238:241], v[218:221], v[50:53]
	v_mfma_f32_16x16x32_bf16 v[46:49], v[226:229], v[222:225], v[46:49]
	v_mfma_f32_16x16x32_bf16 v[42:45], v[230:233], v[222:225], v[42:45]
	v_mfma_f32_16x16x32_bf16 v[38:41], v[234:237], v[222:225], v[38:41]
	v_mfma_f32_16x16x32_bf16 v[34:37], v[238:241], v[222:225], v[34:37]
.Lstg_942_a:
	s_waitcnt vmcnt(5)
	ds_write_b128 v167, v[22:25]
	ds_write_b128 v167, v[18:21] offset:8192
	ds_write_b128 v167, v[26:29] offset:16384
	s_waitcnt vmcnt(4)
	ds_write_b128 v167, v[30:33] offset:24576
	v_lshl_add_u64 v[18:19], v[184:185], 0, s[0:1]
	v_lshl_add_u64 v[26:27], v[180:181], 0, s[0:1]
	global_load_dwordx4 v[22:25], v[18:19], off
	v_lshl_add_u64 v[30:31], v[178:179], 0, s[0:1]
	global_load_dwordx4 v[26:29], v[26:27], off
	v_lshl_add_u64 v[18:19], v[182:183], 0, s[0:1]
	global_load_dwordx4 v[18:21], v[18:19], off
	s_nop 0
	global_load_dwordx4 v[30:33], v[30:31], off
	s_and_b32 s2, s2, 0x8000
	s_lshl_b32 s2, s2, 1
	s_add_i32 s2, s2, 0
	v_lshl_add_u32 v169, v191, 1, s2
	v_add_u32_e32 v222, v169, v187
	ds_read_b128 v[192:195], v222
	ds_read_b128 v[198:201], v222 offset:2048
	ds_read_b128 v[202:205], v222 offset:4096
	ds_read_b128 v[206:209], v222 offset:6144
	ds_read_b128 v[210:213], v222 offset:8192
	ds_read_b128 v[214:217], v222 offset:10240
	ds_read_b128 v[218:221], v222 offset:12288
	ds_read_b128 v[222:225], v222 offset:14336
	v_add_u32_e32 v169, v169, v186
	ds_read_b128 v[226:229], v169 offset:32768
	ds_read_b128 v[230:233], v169 offset:34816
	ds_read_b128 v[234:237], v169 offset:36864
	ds_read_b128 v[238:241], v169 offset:38912
	s_waitcnt lgkmcnt(3)
	v_mfma_f32_16x16x32_bf16 v[158:161], v[226:229], v[192:195], v[158:161]
	s_waitcnt lgkmcnt(2)
	v_mfma_f32_16x16x32_bf16 v[154:157], v[230:233], v[192:195], v[154:157]
	s_waitcnt lgkmcnt(1)
	v_mfma_f32_16x16x32_bf16 v[150:153], v[234:237], v[192:195], v[150:153]
	s_waitcnt lgkmcnt(0)
	v_mfma_f32_16x16x32_bf16 v[146:149], v[238:241], v[192:195], v[146:149]
	v_mfma_f32_16x16x32_bf16 v[142:145], v[226:229], v[198:201], v[142:145]
	v_mfma_f32_16x16x32_bf16 v[138:141], v[230:233], v[198:201], v[138:141]
	v_mfma_f32_16x16x32_bf16 v[134:137], v[234:237], v[198:201], v[134:137]
	v_mfma_f32_16x16x32_bf16 v[130:133], v[238:241], v[198:201], v[130:133]
	v_mfma_f32_16x16x32_bf16 v[126:129], v[226:229], v[202:205], v[126:129]
	v_mfma_f32_16x16x32_bf16 v[122:125], v[230:233], v[202:205], v[122:125]
	v_mfma_f32_16x16x32_bf16 v[118:121], v[234:237], v[202:205], v[118:121]
	v_mfma_f32_16x16x32_bf16 v[114:117], v[238:241], v[202:205], v[114:117]
	v_mfma_f32_16x16x32_bf16 v[110:113], v[226:229], v[206:209], v[110:113]
	v_mfma_f32_16x16x32_bf16 v[106:109], v[230:233], v[206:209], v[106:109]
	v_mfma_f32_16x16x32_bf16 v[102:105], v[234:237], v[206:209], v[102:105]
	v_mfma_f32_16x16x32_bf16 v[98:101], v[238:241], v[206:209], v[98:101]
	v_mfma_f32_16x16x32_bf16 v[94:97], v[226:229], v[210:213], v[94:97]
	v_mfma_f32_16x16x32_bf16 v[90:93], v[230:233], v[210:213], v[90:93]
	v_mfma_f32_16x16x32_bf16 v[86:89], v[234:237], v[210:213], v[86:89]
	v_mfma_f32_16x16x32_bf16 v[82:85], v[238:241], v[210:213], v[82:85]
	v_mfma_f32_16x16x32_bf16 v[78:81], v[226:229], v[214:217], v[78:81]
	v_mfma_f32_16x16x32_bf16 v[74:77], v[230:233], v[214:217], v[74:77]
	v_mfma_f32_16x16x32_bf16 v[70:73], v[234:237], v[214:217], v[70:73]
	v_mfma_f32_16x16x32_bf16 v[66:69], v[238:241], v[214:217], v[66:69]
	v_mfma_f32_16x16x32_bf16 v[62:65], v[226:229], v[218:221], v[62:65]
	v_mfma_f32_16x16x32_bf16 v[58:61], v[230:233], v[218:221], v[58:61]
	v_mfma_f32_16x16x32_bf16 v[54:57], v[234:237], v[218:221], v[54:57]
	v_mfma_f32_16x16x32_bf16 v[50:53], v[238:241], v[218:221], v[50:53]
	v_mfma_f32_16x16x32_bf16 v[46:49], v[226:229], v[222:225], v[46:49]
	v_mfma_f32_16x16x32_bf16 v[42:45], v[230:233], v[222:225], v[42:45]
	v_mfma_f32_16x16x32_bf16 v[38:41], v[234:237], v[222:225], v[38:41]
	v_mfma_f32_16x16x32_bf16 v[34:37], v[238:241], v[222:225], v[34:37]
	s_waitcnt vmcnt(7)
; DI f32x4 mfma16(bf16x8 a, bf16x8 b, f32x4 c) { return __builtin_amdgcn_mfma_f32_16x16x32_bf16(a, b, c, 0, 0, 0); }
; #pragma unroll
;   for (int ks = KS0; ks < KS1; ++ks) {
;     bf16x8 af[8], bfr[4];
; #pragma unroll
;     for (int i = 0; i < 8; ++i) {
;       const int r = wm * 128 + i * 16 + (lane & 15);
;       af[i] = *(const bf16x8*)(S + r * 64 + (((ks * 4 + (lane >> 4)) ^ ((r >> 1) & 7)) << 3));
;     }
; #pragma unroll
;     for (int j = 0; j < 4; ++j) {
;       const int r = wn * 64 + j * 16 + (lane & 15);
;       bfr[j] = *(const bf16x8*)(S + 16384 + r * 64 + (((ks * 4 + (lane >> 4)) ^ ((r >> 1) & 7)) << 3));
;     }
;     __builtin_amdgcn_s_setprio(1);
; #pragma unroll
;     for (int i = 0; i < 8; ++i)
; #pragma unroll
;       for (int j = 0; j < 4; ++j) acc[i][j] = mfma16(bfr[j], af[i], acc[i][j]);
;     __builtin_amdgcn_s_setprio(0);
;   }
; }
; DI void gemm8_accum(f32x4 (&acc)[8][4], const bf16_t* a, size_t lda, const bf16_t* b, size_t ldb, int nkb, bf16_t* L,
;                     const bool pre, const bf16_t* an, size_t ldan, const bf16_t* bn, size_t ldbn) {
;     ...
;   for (int kb = 0; kb + 2 < nkb; ++kb) {
;     __syncthreads();
;     g8_store1(L + ((kb + 1) & 1) * 32768, ra, lrow, lch);
;     g8_load1o(ra, a + (kb + 2) * 64, offa);
;     __builtin_amdgcn_sched_barrier(0);
;     g8_compute<0, 1>(acc, L + (kb & 1) * 32768, wm, wn, lane);
;     __builtin_amdgcn_sched_barrier(0);
;     g8_store1(L + ((kb + 1) & 1) * 32768 + 16384, rb, lrow, lch);
;     g8_load1o(rb, b + (kb + 2) * 64, offb);
;     __builtin_amdgcn_sched_barrier(0);
;     g8_compute<1, 2>(acc, L + (kb & 1) * 32768, wm, wn, lane);
;   }
	ds_write_b128 v167, v[14:17] offset:32768
	s_waitcnt vmcnt(6)
	ds_write_b128 v167, v[2:5] offset:40960
	s_waitcnt vmcnt(5)
	ds_write_b128 v167, v[6:9] offset:49152
	s_waitcnt vmcnt(4)
	ds_write_b128 v167, v[10:13] offset:57344
	v_lshl_add_u64 v[2:3], v[176:177], 0, s[0:1]
	v_lshl_add_u64 v[4:5], v[174:175], 0, s[0:1]
	v_lshl_add_u64 v[6:7], v[172:173], 0, s[0:1]
	v_lshl_add_u64 v[10:11], v[170:171], 0, s[0:1]
	global_load_dwordx4 v[14:17], v[2:3], off
	s_nop 0
	global_load_dwordx4 v[2:5], v[4:5], off
	s_nop 0
	global_load_dwordx4 v[6:9], v[6:7], off
	s_nop 0
	global_load_dwordx4 v[10:13], v[10:11], off
	v_lshl_add_u32 v167, v188, 1, s2
	v_add_u32_e32 v169, v167, v187
	ds_read_b128 v[192:195], v169
	ds_read_b128 v[198:201], v169 offset:2048
	ds_read_b128 v[202:205], v169 offset:4096
	ds_read_b128 v[206:209], v169 offset:6144
	ds_read_b128 v[210:213], v169 offset:8192
	ds_read_b128 v[214:217], v169 offset:10240
	ds_read_b128 v[218:221], v169 offset:12288
	ds_read_b128 v[222:225], v169 offset:14336
	v_add_u32_e32 v167, v167, v186
	ds_read_b128 v[226:229], v167 offset:32768
	ds_read_b128 v[230:233], v167 offset:34816
	ds_read_b128 v[234:237], v167 offset:36864
	ds_read_b128 v[238:241], v167 offset:38912
	s_cmp_lg_u32 s101, 0
	s_cbranch_scc1 .Lstg_942_b
	s_waitcnt lgkmcnt(3)
	v_mfma_f32_16x16x32_bf16 v[158:161], v[226:229], v[192:195], v[158:161]
	s_waitcnt lgkmcnt(2)
	v_mfma_f32_16x16x32_bf16 v[154:157], v[230:233], v[192:195], v[154:157]
	s_waitcnt lgkmcnt(1)
	v_mfma_f32_16x16x32_bf16 v[150:153], v[234:237], v[192:195], v[150:153]
	s_waitcnt lgkmcnt(0)
	v_mfma_f32_16x16x32_bf16 v[146:149], v[238:241], v[192:195], v[146:149]
	v_mfma_f32_16x16x32_bf16 v[142:145], v[226:229], v[198:201], v[142:145]
	v_mfma_f32_16x16x32_bf16 v[138:141], v[230:233], v[198:201], v[138:141]
	v_mfma_f32_16x16x32_bf16 v[134:137], v[234:237], v[198:201], v[134:137]
	v_mfma_f32_16x16x32_bf16 v[130:133], v[238:241], v[198:201], v[130:133]
	v_mfma_f32_16x16x32_bf16 v[126:129], v[226:229], v[202:205], v[126:129]
	v_mfma_f32_16x16x32_bf16 v[122:125], v[230:233], v[202:205], v[122:125]
	v_mfma_f32_16x16x32_bf16 v[118:121], v[234:237], v[202:205], v[118:121]
	v_mfma_f32_16x16x32_bf16 v[114:117], v[238:241], v[202:205], v[114:117]
	v_mfma_f32_16x16x32_bf16 v[110:113], v[226:229], v[206:209], v[110:113]
	v_mfma_f32_16x16x32_bf16 v[106:109], v[230:233], v[206:209], v[106:109]
	v_mfma_f32_16x16x32_bf16 v[102:105], v[234:237], v[206:209], v[102:105]
	v_mfma_f32_16x16x32_bf16 v[98:101], v[238:241], v[206:209], v[98:101]
	v_mfma_f32_16x16x32_bf16 v[94:97], v[226:229], v[210:213], v[94:97]
	v_mfma_f32_16x16x32_bf16 v[90:93], v[230:233], v[210:213], v[90:93]
	v_mfma_f32_16x16x32_bf16 v[86:89], v[234:237], v[210:213], v[86:89]
	v_mfma_f32_16x16x32_bf16 v[82:85], v[238:241], v[210:213], v[82:85]
	v_mfma_f32_16x16x32_bf16 v[78:81], v[226:229], v[214:217], v[78:81]
	v_mfma_f32_16x16x32_bf16 v[74:77], v[230:233], v[214:217], v[74:77]
	v_mfma_f32_16x16x32_bf16 v[70:73], v[234:237], v[214:217], v[70:73]
	v_mfma_f32_16x16x32_bf16 v[66:69], v[238:241], v[214:217], v[66:69]
	v_mfma_f32_16x16x32_bf16 v[62:65], v[226:229], v[218:221], v[62:65]
	v_mfma_f32_16x16x32_bf16 v[58:61], v[230:233], v[218:221], v[58:61]
	v_mfma_f32_16x16x32_bf16 v[54:57], v[234:237], v[218:221], v[54:57]
	v_mfma_f32_16x16x32_bf16 v[50:53], v[238:241], v[218:221], v[50:53]
	v_mfma_f32_16x16x32_bf16 v[46:49], v[226:229], v[222:225], v[46:49]
	v_mfma_f32_16x16x32_bf16 v[42:45], v[230:233], v[222:225], v[42:45]
	v_mfma_f32_16x16x32_bf16 v[38:41], v[234:237], v[222:225], v[38:41]
	v_mfma_f32_16x16x32_bf16 v[34:37], v[238:241], v[222:225], v[34:37]
.Lstg_942_b:
	s_mov_b32 s100, s101
	s_add_u32 s0, s0, 0x80
	s_addc_u32 s1, s1, 0
	s_cmpk_lg_i32 s0, 0x1f00
	s_mov_b32 s2, s3
	s_cbranch_scc1 .LBB0_942
	s_cmp_eq_u32 s100, 0
	s_cbranch_scc1 .Lstg_942_c
	s_waitcnt lgkmcnt(0)
	v_mfma_f32_16x16x32_bf16 v[158:161], v[226:229], v[192:195], v[158:161]
	v_mfma_f32_16x16x32_bf16 v[154:157], v[230:233], v[192:195], v[154:157]
	v_mfma_f32_16x16x32_bf16 v[150:153], v[234:237], v[192:195], v[150:153]
	v_mfma_f32_16x16x32_bf16 v[146:149], v[238:241], v[192:195], v[146:149]
	v_mfma_f32_16x16x32_bf16 v[142:145], v[226:229], v[198:201], v[142:145]
	v_mfma_f32_16x16x32_bf16 v[138:141], v[230:233], v[198:201], v[138:141]
	v_mfma_f32_16x16x32_bf16 v[134:137], v[234:237], v[198:201], v[134:137]
	v_mfma_f32_16x16x32_bf16 v[130:133], v[238:241], v[198:201], v[130:133]
	v_mfma_f32_16x16x32_bf16 v[126:129], v[226:229], v[202:205], v[126:129]
	v_mfma_f32_16x16x32_bf16 v[122:125], v[230:233], v[202:205], v[122:125]
	v_mfma_f32_16x16x32_bf16 v[118:121], v[234:237], v[202:205], v[118:121]
	v_mfma_f32_16x16x32_bf16 v[114:117], v[238:241], v[202:205], v[114:117]
	v_mfma_f32_16x16x32_bf16 v[110:113], v[226:229], v[206:209], v[110:113]
	v_mfma_f32_16x16x32_bf16 v[106:109], v[230:233], v[206:209], v[106:109]
	v_mfma_f32_16x16x32_bf16 v[102:105], v[234:237], v[206:209], v[102:105]
	v_mfma_f32_16x16x32_bf16 v[98:101], v[238:241], v[206:209], v[98:101]
	v_mfma_f32_16x16x32_bf16 v[94:97], v[226:229], v[210:213], v[94:97]
	v_mfma_f32_16x16x32_bf16 v[90:93], v[230:233], v[210:213], v[90:93]
	v_mfma_f32_16x16x32_bf16 v[86:89], v[234:237], v[210:213], v[86:89]
	v_mfma_f32_16x16x32_bf16 v[82:85], v[238:241], v[210:213], v[82:85]
	v_mfma_f32_16x16x32_bf16 v[78:81], v[226:229], v[214:217], v[78:81]
	v_mfma_f32_16x16x32_bf16 v[74:77], v[230:233], v[214:217], v[74:77]
	v_mfma_f32_16x16x32_bf16 v[70:73], v[234:237], v[214:217], v[70:73]
	v_mfma_f32_16x16x32_bf16 v[66:69], v[238:241], v[214:217], v[66:69]
	v_mfma_f32_16x16x32_bf16 v[62:65], v[226:229], v[218:221], v[62:65]
	v_mfma_f32_16x16x32_bf16 v[58:61], v[230:233], v[218:221], v[58:61]
	v_mfma_f32_16x16x32_bf16 v[54:57], v[234:237], v[218:221], v[54:57]
	v_mfma_f32_16x16x32_bf16 v[50:53], v[238:241], v[218:221], v[50:53]
	v_mfma_f32_16x16x32_bf16 v[46:49], v[226:229], v[222:225], v[46:49]
	v_mfma_f32_16x16x32_bf16 v[42:45], v[230:233], v[222:225], v[42:45]
	v_mfma_f32_16x16x32_bf16 v[38:41], v[234:237], v[222:225], v[38:41]
	v_mfma_f32_16x16x32_bf16 v[34:37], v[238:241], v[222:225], v[34:37]
	s_mov_b32 s100, 0
; DI void gemm8_accum(f32x4 (&acc)[8][4], const bf16_t* a, size_t lda, const bf16_t* b, size_t ldb, int nkb, bf16_t* L,
;                     const bool pre, const bf16_t* an, size_t ldan, const bf16_t* bn, size_t ldbn) {
;     ...
;   __syncthreads();
;   g8_store1(L + 32768, ra, lrow, lch);
;   g8_load1(ra, an, ldan, 0, lrow, lch);
;   __builtin_amdgcn_sched_barrier(0);
;   g8_compute<0, 1>(acc, L, wm, wn, lane);
;   __builtin_amdgcn_sched_barrier(0);
;   g8_store1(L + 32768 + 16384, rb, lrow, lch);
;   g8_load1(rb, bn, ldbn, 0, lrow, lch);
;   __builtin_amdgcn_sched_barrier(0);
;   g8_compute<1, 2>(acc, L, wm, wn, lane);
;   __syncthreads();
;   g8_store1(L, ra, lrow, lch);
;   __builtin_amdgcn_sched_barrier(0);
;   g8_compute<0, 1>(acc, L + 32768, wm, wn, lane);
;   __builtin_amdgcn_sched_barrier(0);
;   g8_store1(L + 16384, rb, lrow, lch);
;   __builtin_amdgcn_sched_barrier(0);
;   g8_compute<1, 2>(acc, L + 32768, wm, wn, lane);
.Lstg_942_c:
	v_readlane_b32 s0, v254, 18
	s_add_i32 s12, s13, s0
	s_cmp_gt_u32 s12, 63
	s_cselect_b64 s[0:1], -1, 0
	s_cmp_lt_u32 s12, 64
	s_cselect_b32 s7, s12, s13
	s_lshl_b32 s2, s7, 1
	s_and_b32 s2, s2, 0x7fffffe0
	s_and_b32 s3, s7, 3
	s_or_b32 s2, s3, s2
	v_readlane_b32 s3, v252, 25
	s_or_b32 s28, s2, s3
	s_lshl_b32 s13, s11, 8
	s_lshl_b64 s[2:3], s[28:29], 21
	s_add_u32 s2, s16, s2
	v_mov_b32_e32 v169, v1
	v_mov_b32_e32 v167, v1
	s_addc_u32 s3, s17, s3
	v_lshlrev_b64 v[184:185], 1, v[168:169]
	v_lshlrev_b64 v[166:167], 1, v[166:167]
	v_lshlrev_b64 v[226:227], 1, v[0:1]
	v_lshl_add_u64 v[170:171], s[2:3], 0, v[164:165]
	v_lshl_add_u64 v[172:173], s[2:3], 0, v[184:185]
	v_lshl_add_u64 v[176:177], s[2:3], 0, v[166:167]
	v_lshl_add_u64 v[180:181], s[2:3], 0, v[226:227]
	s_barrier
	global_load_dwordx4 v[168:171], v[170:171], off
	s_nop 0
	global_load_dwordx4 v[172:175], v[172:173], off
	s_nop 0
	global_load_dwordx4 v[176:179], v[176:177], off
	s_nop 0
	global_load_dwordx4 v[180:183], v[180:181], off
	s_lshl_b32 s2, s7, 19
	s_and_b32 s2, s2, 0x600000
	v_readlane_b32 s20, v251, 59
	v_readlane_b32 s21, v251, 60
	s_add_u32 s2, s20, s2
	s_addc_u32 s3, s21, 0
	s_add_i32 s7, 0, 0x10000
	v_add3_u32 v0, s7, v189, v190
	s_waitcnt vmcnt(11)
	ds_write_b128 v0, v[22:25]
	s_waitcnt vmcnt(9)
	ds_write_b128 v0, v[18:21] offset:8192
	ds_write_b128 v0, v[26:29] offset:16384
	s_waitcnt vmcnt(8)
	ds_write_b128 v0, v[30:33] offset:24576
	v_lshlrev_b32_e32 v0, 1, v191
	v_add_u32_e32 v191, 0, v0
	v_add_u32_e32 v206, v191, v187
	ds_read_b128 v[18:21], v206
	ds_read_b128 v[22:25], v206 offset:2048
	ds_read_b128 v[26:29], v206 offset:4096
	ds_read_b128 v[30:33], v206 offset:6144
	ds_read_b128 v[192:195], v206 offset:8192
	ds_read_b128 v[198:201], v206 offset:10240
	ds_read_b128 v[202:205], v206 offset:12288
	ds_read_b128 v[206:209], v206 offset:14336
	v_add_u32_e32 v191, v191, v186
	ds_read_b128 v[210:213], v191 offset:32768
	ds_read_b128 v[214:217], v191 offset:34816
	ds_read_b128 v[218:221], v191 offset:36864
	ds_read_b128 v[222:225], v191 offset:38912
	s_waitcnt lgkmcnt(3)
	v_mfma_f32_16x16x32_bf16 v[158:161], v[210:213], v[18:21], v[158:161]
	s_waitcnt lgkmcnt(2)
	v_mfma_f32_16x16x32_bf16 v[154:157], v[214:217], v[18:21], v[154:157]
	s_waitcnt lgkmcnt(1)
	v_mfma_f32_16x16x32_bf16 v[150:153], v[218:221], v[18:21], v[150:153]
	s_waitcnt lgkmcnt(0)
	v_mfma_f32_16x16x32_bf16 v[18:21], v[222:225], v[18:21], v[146:149]
	v_mfma_f32_16x16x32_bf16 v[142:145], v[210:213], v[22:25], v[142:145]
	v_mfma_f32_16x16x32_bf16 v[138:141], v[214:217], v[22:25], v[138:141]
	v_mfma_f32_16x16x32_bf16 v[134:137], v[218:221], v[22:25], v[134:137]
	v_mfma_f32_16x16x32_bf16 v[22:25], v[222:225], v[22:25], v[130:133]
	v_mfma_f32_16x16x32_bf16 v[126:129], v[210:213], v[26:29], v[126:129]
	v_mfma_f32_16x16x32_bf16 v[122:125], v[214:217], v[26:29], v[122:125]
	v_mfma_f32_16x16x32_bf16 v[118:121], v[218:221], v[26:29], v[118:121]
	v_mfma_f32_16x16x32_bf16 v[26:29], v[222:225], v[26:29], v[114:117]
	v_mfma_f32_16x16x32_bf16 v[110:113], v[210:213], v[30:33], v[110:113]
	v_mfma_f32_16x16x32_bf16 v[106:109], v[214:217], v[30:33], v[106:109]
	v_mfma_f32_16x16x32_bf16 v[102:105], v[218:221], v[30:33], v[102:105]
	v_mfma_f32_16x16x32_bf16 v[30:33], v[222:225], v[30:33], v[98:101]
	v_mfma_f32_16x16x32_bf16 v[94:97], v[210:213], v[192:195], v[94:97]
	v_mfma_f32_16x16x32_bf16 v[90:93], v[214:217], v[192:195], v[90:93]
	v_mfma_f32_16x16x32_bf16 v[86:89], v[218:221], v[192:195], v[86:89]
	v_mfma_f32_16x16x32_bf16 v[82:85], v[222:225], v[192:195], v[82:85]
	v_mfma_f32_16x16x32_bf16 v[78:81], v[210:213], v[198:201], v[78:81]
	v_mfma_f32_16x16x32_bf16 v[74:77], v[214:217], v[198:201], v[74:77]
	v_mfma_f32_16x16x32_bf16 v[70:73], v[218:221], v[198:201], v[70:73]
	v_mfma_f32_16x16x32_bf16 v[66:69], v[222:225], v[198:201], v[66:69]
	v_mfma_f32_16x16x32_bf16 v[62:65], v[210:213], v[202:205], v[62:65]
	v_mfma_f32_16x16x32_bf16 v[58:61], v[214:217], v[202:205], v[58:61]
	v_mfma_f32_16x16x32_bf16 v[54:57], v[218:221], v[202:205], v[54:57]
	v_mfma_f32_16x16x32_bf16 v[50:53], v[222:225], v[202:205], v[50:53]
	v_mfma_f32_16x16x32_bf16 v[46:49], v[210:213], v[206:209], v[46:49]
	v_mfma_f32_16x16x32_bf16 v[42:45], v[214:217], v[206:209], v[42:45]
	v_mfma_f32_16x16x32_bf16 v[38:41], v[218:221], v[206:209], v[38:41]
	v_mfma_f32_16x16x32_bf16 v[34:37], v[222:225], v[206:209], v[34:37]
	v_readlane_b32 s20, v254, 36
	s_nop 1
	v_add3_u32 v98, s20, v189, v190
	s_waitcnt vmcnt(7)
	ds_write_b128 v98, v[14:17]
	s_waitcnt vmcnt(6)
	ds_write_b128 v98, v[2:5] offset:8192
	s_waitcnt vmcnt(5)
	ds_write_b128 v98, v[6:9] offset:16384
	s_waitcnt vmcnt(4)
	ds_write_b128 v98, v[10:13] offset:24576
	v_lshl_add_u64 v[2:3], s[2:3], 0, v[164:165]
	v_lshl_add_u64 v[6:7], s[2:3], 0, v[184:185]
	v_lshl_add_u64 v[10:11], s[2:3], 0, v[166:167]
	v_lshl_add_u64 v[14:15], s[2:3], 0, v[226:227]
	global_load_dwordx4 v[2:5], v[2:3], off
	s_nop 0
	global_load_dwordx4 v[6:9], v[6:7], off
	s_nop 0
	global_load_dwordx4 v[10:13], v[10:11], off
	s_nop 0
	global_load_dwordx4 v[14:17], v[14:15], off
	v_lshlrev_b32_e32 v184, 1, v188
	v_add_u32_e32 v185, 0, v184
	v_add_u32_e32 v198, v185, v187
	ds_read_b128 v[98:101], v198
	ds_read_b128 v[114:117], v198 offset:2048
	ds_read_b128 v[130:133], v198 offset:4096
	ds_read_b128 v[146:149], v198 offset:6144
	ds_read_b128 v[164:167], v198 offset:8192
	ds_read_b128 v[188:191], v198 offset:10240
	ds_read_b128 v[192:195], v198 offset:12288
	ds_read_b128 v[198:201], v198 offset:14336
	v_add_u32_e32 v185, v185, v186
	ds_read_b128 v[202:205], v185 offset:32768
	ds_read_b128 v[206:209], v185 offset:34816
	ds_read_b128 v[210:213], v185 offset:36864
	ds_read_b128 v[214:217], v185 offset:38912
	s_waitcnt lgkmcnt(3)
; DI f32x4 mfma16(bf16x8 a, bf16x8 b, f32x4 c) { return __builtin_amdgcn_mfma_f32_16x16x32_bf16(a, b, c, 0, 0, 0); }
; #pragma unroll
;   for (int ks = KS0; ks < KS1; ++ks) {
;     bf16x8 af[8], bfr[4];
; #pragma unroll
;     for (int i = 0; i < 8; ++i) {
;       const int r = wm * 128 + i * 16 + (lane & 15);
;       af[i] = *(const bf16x8*)(S + r * 64 + (((ks * 4 + (lane >> 4)) ^ ((r >> 1) & 7)) << 3));
;     }
; #pragma unroll
;     for (int j = 0; j < 4; ++j) {
;       const int r = wn * 64 + j * 16 + (lane & 15);
;       bfr[j] = *(const bf16x8*)(S + 16384 + r * 64 + (((ks * 4 + (lane >> 4)) ^ ((r >> 1) & 7)) << 3));
;     }
;     __builtin_amdgcn_s_setprio(1);
; #pragma unroll
;     for (int i = 0; i < 8; ++i)
; #pragma unroll
;       for (int j = 0; j < 4; ++j) acc[i][j] = mfma16(bfr[j], af[i], acc[i][j]);
;     __builtin_amdgcn_s_setprio(0);
;   }
; DI void gemm8_accum(f32x4 (&acc)[8][4], const bf16_t* a, size_t lda, const bf16_t* b, size_t ldb, int nkb, bf16_t* L,
;                     const bool pre, const bf16_t* an, size_t ldan, const bf16_t* bn, size_t ldbn) {
;     ...
;   g8_compute<0, 1>(acc, L, wm, wn, lane);
;   __builtin_amdgcn_sched_barrier(0);
;   g8_store1(L + 32768 + 16384, rb, lrow, lch);
;   g8_load1(rb, bn, ldbn, 0, lrow, lch);
;   __builtin_amdgcn_sched_barrier(0);
;   g8_compute<1, 2>(acc, L, wm, wn, lane);
;   __syncthreads();
;   g8_store1(L, ra, lrow, lch);
;   __builtin_amdgcn_sched_barrier(0);
;   g8_compute<0, 1>(acc, L + 32768, wm, wn, lane);
;   __builtin_amdgcn_sched_barrier(0);
;   g8_store1(L + 16384, rb, lrow, lch);
;   __builtin_amdgcn_sched_barrier(0);
;   g8_compute<1, 2>(acc, L + 32768, wm, wn, lane);
	v_mfma_f32_16x16x32_bf16 v[158:161], v[202:205], v[98:101], v[158:161]
	s_waitcnt lgkmcnt(2)
	v_mfma_f32_16x16x32_bf16 v[154:157], v[206:209], v[98:101], v[154:157]
	s_waitcnt lgkmcnt(1)
	v_mfma_f32_16x16x32_bf16 v[150:153], v[210:213], v[98:101], v[150:153]
	s_waitcnt lgkmcnt(0)
	v_mfma_f32_16x16x32_bf16 v[18:21], v[214:217], v[98:101], v[18:21]
	v_mfma_f32_16x16x32_bf16 v[98:101], v[202:205], v[114:117], v[142:145]
	v_mfma_f32_16x16x32_bf16 v[138:141], v[206:209], v[114:117], v[138:141]
	v_mfma_f32_16x16x32_bf16 v[134:137], v[210:213], v[114:117], v[134:137]
	v_mfma_f32_16x16x32_bf16 v[22:25], v[214:217], v[114:117], v[22:25]
	v_mfma_f32_16x16x32_bf16 v[114:117], v[202:205], v[130:133], v[126:129]
	v_mfma_f32_16x16x32_bf16 v[122:125], v[206:209], v[130:133], v[122:125]
	v_mfma_f32_16x16x32_bf16 v[118:121], v[210:213], v[130:133], v[118:121]
	v_mfma_f32_16x16x32_bf16 v[26:29], v[214:217], v[130:133], v[26:29]
	v_mfma_f32_16x16x32_bf16 v[110:113], v[202:205], v[146:149], v[110:113]
	v_mfma_f32_16x16x32_bf16 v[106:109], v[206:209], v[146:149], v[106:109]
	v_mfma_f32_16x16x32_bf16 v[102:105], v[210:213], v[146:149], v[102:105]
	v_mfma_f32_16x16x32_bf16 v[30:33], v[214:217], v[146:149], v[30:33]
	v_mfma_f32_16x16x32_bf16 v[94:97], v[202:205], v[164:167], v[94:97]
	v_mfma_f32_16x16x32_bf16 v[90:93], v[206:209], v[164:167], v[90:93]
	v_mfma_f32_16x16x32_bf16 v[86:89], v[210:213], v[164:167], v[86:89]
	v_mfma_f32_16x16x32_bf16 v[82:85], v[214:217], v[164:167], v[82:85]
	v_mfma_f32_16x16x32_bf16 v[78:81], v[202:205], v[188:191], v[78:81]
	v_mfma_f32_16x16x32_bf16 v[74:77], v[206:209], v[188:191], v[74:77]
	v_mfma_f32_16x16x32_bf16 v[70:73], v[210:213], v[188:191], v[70:73]
	v_mfma_f32_16x16x32_bf16 v[66:69], v[214:217], v[188:191], v[66:69]
	v_mfma_f32_16x16x32_bf16 v[62:65], v[202:205], v[192:195], v[62:65]
	v_mfma_f32_16x16x32_bf16 v[58:61], v[206:209], v[192:195], v[58:61]
	v_mfma_f32_16x16x32_bf16 v[54:57], v[210:213], v[192:195], v[54:57]
	v_mfma_f32_16x16x32_bf16 v[50:53], v[214:217], v[192:195], v[50:53]
	v_mfma_f32_16x16x32_bf16 v[46:49], v[202:205], v[198:201], v[46:49]
	v_mfma_f32_16x16x32_bf16 v[42:45], v[206:209], v[198:201], v[42:45]
	v_mfma_f32_16x16x32_bf16 v[38:41], v[210:213], v[198:201], v[38:41]
	v_mfma_f32_16x16x32_bf16 v[34:37], v[214:217], v[198:201], v[34:37]
	s_barrier
	s_waitcnt vmcnt(7)
	ds_write_b128 v163, v[168:171]
	s_waitcnt vmcnt(6)
	ds_write_b128 v163, v[172:175] offset:8192
	s_waitcnt vmcnt(5)
	ds_write_b128 v163, v[176:179] offset:16384
	s_waitcnt vmcnt(4)
	ds_write_b128 v163, v[180:183] offset:24576
	v_add3_u32 v176, s7, v0, v187
	ds_read_b128 v[126:129], v176
	ds_read_b128 v[130:133], v176 offset:2048
	ds_read_b128 v[142:145], v176 offset:4096
	ds_read_b128 v[146:149], v176 offset:6144
	ds_read_b128 v[164:167], v176 offset:8192
	ds_read_b128 v[168:171], v176 offset:10240
	ds_read_b128 v[172:175], v176 offset:12288
	ds_read_b128 v[176:179], v176 offset:14336
	v_add3_u32 v0, s20, v0, v186
	ds_read_b128 v[180:183], v0
	ds_read_b128 v[188:191], v0 offset:2048
	ds_read_b128 v[192:195], v0 offset:4096
	ds_read_b128 v[198:201], v0 offset:6144
	s_waitcnt lgkmcnt(3)
	v_mfma_f32_16x16x32_bf16 v[158:161], v[180:183], v[126:129], v[158:161]
	s_waitcnt lgkmcnt(2)
	v_mfma_f32_16x16x32_bf16 v[154:157], v[188:191], v[126:129], v[154:157]
	s_waitcnt lgkmcnt(1)
	v_mfma_f32_16x16x32_bf16 v[150:153], v[192:195], v[126:129], v[150:153]
	s_waitcnt lgkmcnt(0)
	v_mfma_f32_16x16x32_bf16 v[18:21], v[198:201], v[126:129], v[18:21]
	v_mfma_f32_16x16x32_bf16 v[98:101], v[180:183], v[130:133], v[98:101]
	v_mfma_f32_16x16x32_bf16 v[126:129], v[188:191], v[130:133], v[138:141]
	v_mfma_f32_16x16x32_bf16 v[22:25], v[198:201], v[130:133], v[22:25]
	v_mfma_f32_16x16x32_bf16 v[114:117], v[180:183], v[142:145], v[114:117]
	v_mfma_f32_16x16x32_bf16 v[122:125], v[188:191], v[142:145], v[122:125]
	v_mfma_f32_16x16x32_bf16 v[118:121], v[192:195], v[142:145], v[118:121]
	v_mfma_f32_16x16x32_bf16 v[26:29], v[198:201], v[142:145], v[26:29]
	v_mfma_f32_16x16x32_bf16 v[30:33], v[198:201], v[146:149], v[30:33]
	v_mfma_f32_16x16x32_bf16 v[134:137], v[192:195], v[130:133], v[134:137]
	v_mfma_f32_16x16x32_bf16 v[130:133], v[180:183], v[146:149], v[110:113]
	v_mfma_f32_16x16x32_bf16 v[138:141], v[188:191], v[146:149], v[106:109]
	v_mfma_f32_16x16x32_bf16 v[142:145], v[192:195], v[146:149], v[102:105]
	v_mfma_f32_16x16x32_bf16 v[146:149], v[180:183], v[164:167], v[94:97]
	v_mfma_f32_16x16x32_bf16 v[202:205], v[188:191], v[164:167], v[90:93]
	v_mfma_f32_16x16x32_bf16 v[206:209], v[192:195], v[164:167], v[86:89]
	v_mfma_f32_16x16x32_bf16 v[164:167], v[198:201], v[164:167], v[82:85]
	v_mfma_f32_16x16x32_bf16 v[210:213], v[180:183], v[168:171], v[78:81]
	v_mfma_f32_16x16x32_bf16 v[214:217], v[188:191], v[168:171], v[74:77]
	v_mfma_f32_16x16x32_bf16 v[218:221], v[192:195], v[168:171], v[70:73]
	v_mfma_f32_16x16x32_bf16 v[168:171], v[198:201], v[168:171], v[66:69]
	v_mfma_f32_16x16x32_bf16 v[222:225], v[180:183], v[172:175], v[62:65]
	v_mfma_f32_16x16x32_bf16 v[226:229], v[188:191], v[172:175], v[58:61]
	v_mfma_f32_16x16x32_bf16 v[230:233], v[192:195], v[172:175], v[54:57]
	v_mfma_f32_16x16x32_bf16 v[172:175], v[198:201], v[172:175], v[50:53]
	v_mfma_f32_16x16x32_bf16 v[180:183], v[180:183], v[176:179], v[46:49]
	v_mfma_f32_16x16x32_bf16 v[188:191], v[188:191], v[176:179], v[42:45]
	v_mfma_f32_16x16x32_bf16 v[192:195], v[192:195], v[176:179], v[38:41]
	v_mfma_f32_16x16x32_bf16 v[176:179], v[198:201], v[176:179], v[34:37]
	s_waitcnt vmcnt(3)
	ds_write_b128 v163, v[2:5] offset:32768
	s_waitcnt vmcnt(2)
	ds_write_b128 v163, v[6:9] offset:40960
	s_waitcnt vmcnt(1)
; DI int TID8() { int t = threadIdx.x; asm volatile("" : "+v"(t)); return t; }
; DI void gemm8_accum(f32x4 (&acc)[8][4], const bf16_t* a, size_t lda, const bf16_t* b, size_t ldb, int nkb, bf16_t* L,
;                     const bool pre, const bf16_t* an, size_t ldan, const bf16_t* bn, size_t ldbn) {
;     ...
;   g8_store1(L + 16384, rb, lrow, lch);
;   __builtin_amdgcn_sched_barrier(0);
;   g8_compute<1, 2>(acc, L + 32768, wm, wn, lane);
;   __syncthreads();
; DI void gemm8_epi_resid(f32x4 (&acc)[8][4], int m0, int n0, int ntile8, bf16_t* L, const float* xin, float* out, bf16_t* xb, float* rowpart) {
;   const int tid = TID8(), lane = tid & 63, w = tid >> 6;
;   const int wm = w >> 2, wn = w & 3;
;   float* red = (float*)(L + 32768);
; #pragma unroll
;   for (int i = 0; i < 8; ++i) {
;     const int ml = wm * 128 + i * 16 + (lane & 15);
;     const size_t rowoff = (size_t)(m0 + ml) * DM;
;     float ss = 0.f;
; #pragma unroll
;     for (int j = 0; j < 4; ++j) {
;       const int n = n0 + wn * 64 + j * 16 + (lane >> 4) * 4;
;       const float4 xv = *(const float4*)(xin + rowoff + n);
	ds_write_b128 v163, v[10:13] offset:49152
	s_waitcnt vmcnt(0)
	ds_write_b128 v163, v[14:17] offset:57344
	v_add3_u32 v0, s7, v184, v187
	ds_read_b128 v[2:5], v0
	ds_read_b128 v[6:9], v0 offset:2048
	ds_read_b128 v[10:13], v0 offset:4096
	ds_read_b128 v[14:17], v0 offset:6144
	ds_read_b128 v[34:37], v0 offset:8192
	ds_read_b128 v[198:201], v0 offset:10240
	ds_read_b128 v[234:237], v0 offset:12288
	ds_read_b128 v[238:241], v0 offset:14336
	v_add3_u32 v0, s20, v184, v186
	ds_read_b128 v[184:187], v0
	ds_read_b128 v[242:245], v0 offset:2048
	ds_read_b128 v[246:249], v0 offset:4096
	ds_read_b128 v[38:41], v0 offset:6144
	s_waitcnt lgkmcnt(3)
	v_mfma_f32_16x16x32_bf16 v[158:161], v[184:187], v[2:5], v[158:161]
	s_waitcnt lgkmcnt(2)
	v_mfma_f32_16x16x32_bf16 v[154:157], v[242:245], v[2:5], v[154:157]
	s_waitcnt lgkmcnt(1)
	v_mfma_f32_16x16x32_bf16 v[150:153], v[246:249], v[2:5], v[150:153]
	s_waitcnt lgkmcnt(0)
	v_mfma_f32_16x16x32_bf16 v[2:5], v[38:41], v[2:5], v[18:21]
	v_mfma_f32_16x16x32_bf16 v[110:113], v[184:187], v[6:9], v[98:101]
	v_mfma_f32_16x16x32_bf16 v[106:109], v[242:245], v[6:9], v[126:129]
	v_mfma_f32_16x16x32_bf16 v[102:105], v[246:249], v[6:9], v[134:137]
	v_mfma_f32_16x16x32_bf16 v[98:101], v[38:41], v[6:9], v[22:25]
	v_mfma_f32_16x16x32_bf16 v[94:97], v[184:187], v[10:13], v[114:117]
	v_mfma_f32_16x16x32_bf16 v[90:93], v[242:245], v[10:13], v[122:125]
	v_mfma_f32_16x16x32_bf16 v[86:89], v[246:249], v[10:13], v[118:121]
	v_mfma_f32_16x16x32_bf16 v[82:85], v[38:41], v[10:13], v[26:29]
	v_mfma_f32_16x16x32_bf16 v[78:81], v[184:187], v[14:17], v[130:133]
	v_mfma_f32_16x16x32_bf16 v[74:77], v[242:245], v[14:17], v[138:141]
	v_mfma_f32_16x16x32_bf16 v[70:73], v[246:249], v[14:17], v[142:145]
	v_mfma_f32_16x16x32_bf16 v[66:69], v[38:41], v[14:17], v[30:33]
	v_mfma_f32_16x16x32_bf16 v[62:65], v[184:187], v[34:37], v[146:149]
	v_mfma_f32_16x16x32_bf16 v[58:61], v[242:245], v[34:37], v[202:205]
	v_mfma_f32_16x16x32_bf16 v[54:57], v[246:249], v[34:37], v[206:209]
	v_mfma_f32_16x16x32_bf16 v[50:53], v[38:41], v[34:37], v[164:167]
	v_mfma_f32_16x16x32_bf16 v[46:49], v[184:187], v[198:201], v[210:213]
	v_mfma_f32_16x16x32_bf16 v[42:45], v[242:245], v[198:201], v[214:217]
	v_mfma_f32_16x16x32_bf16 v[124:127], v[246:249], v[198:201], v[218:221]
	v_mfma_f32_16x16x32_bf16 v[34:37], v[38:41], v[198:201], v[168:171]
	v_mfma_f32_16x16x32_bf16 v[30:33], v[184:187], v[234:237], v[222:225]
	v_mfma_f32_16x16x32_bf16 v[26:29], v[242:245], v[234:237], v[226:229]
	v_mfma_f32_16x16x32_bf16 v[22:25], v[246:249], v[234:237], v[230:233]
	v_mfma_f32_16x16x32_bf16 v[18:21], v[38:41], v[234:237], v[172:175]
	v_mfma_f32_16x16x32_bf16 v[14:17], v[184:187], v[238:241], v[180:183]
	v_mfma_f32_16x16x32_bf16 v[10:13], v[242:245], v[238:241], v[188:191]
	v_mfma_f32_16x16x32_bf16 v[6:9], v[246:249], v[238:241], v[192:195]
	v_mfma_f32_16x16x32_bf16 v[38:41], v[38:41], v[238:241], v[176:179]
	v_mov_b32_e32 v118, v196
	s_barrier
	s_movk_i32 s2, 0xff80
	v_ashrrev_i32_e32 v115, 1, v118
	v_and_b32_e32 v116, 15, v118
	v_bfe_u32 v114, v118, 6, 2
	v_and_or_b32 v121, v115, s2, v116
	v_lshrrev_b32_e32 v116, 2, v118
	v_and_b32_e32 v0, 63, v118
	v_lshlrev_b32_e32 v115, 6, v114
	v_and_b32_e32 v116, 12, v116
	v_or3_b32 v138, v116, s13, v115
	v_lshlrev_b32_e32 v115, 2, v0
	v_lshl_add_u32 v146, v114, 10, s7
	v_add_u32_e32 v114, s6, v121
	v_xor_b32_e32 v120, 64, v115
	v_xor_b32_e32 v119, 0x80, v115
	v_ashrrev_i32_e32 v115, 31, v114
	v_readlane_b32 s24, v251, 33
	v_lshlrev_b64 v[116:117], 12, v[114:115]
	v_readlane_b32 s26, v251, 35
	v_readlane_b32 s27, v251, 36
	v_cmp_gt_u32_e32 vcc, 16, v0
	v_lshlrev_b32_e32 v0, 2, v138
	v_lshl_add_u64 v[116:117], s[26:27], 0, v[116:117]
	v_lshl_add_u64 v[132:133], v[116:117], 0, v[0:1]
	v_lshlrev_b64 v[122:123], 11, v[114:115]
	v_lshl_add_u64 v[122:123], s[18:19], 0, v[122:123]
	v_lshlrev_b32_e32 v116, 1, v138
	v_mov_b32_e32 v117, v1
	v_lshl_add_u64 v[122:123], v[122:123], 0, v[116:117]
	v_readlane_b32 s25, v251, 34
	v_lshl_add_u32 v188, v121, 2, v146
	v_mov_b32_e32 v189, v120
	v_mov_b32_e32 v190, v119
	v_and_b32_e32 v240, 63, v118
	v_cmp_gt_u32_e64 s[88:89], 16, v240
	v_and_b32_e32 v243, 15, v118
	v_bfe_u32 v242, v118, 4, 2
	v_and_b32_e32 v240, 8, v243
	v_cmp_eq_u32_e64 s[90:91], 0, v240
	v_lshlrev_b32_e32 v236, 12, v243
	v_lshl_or_b32 v236, v242, 4, v236
	v_lshlrev_b32_e32 v237, 11, v243
	v_lshl_or_b32 v237, v242, 3, v237
	v_sub_co_u32_e32 v238, vcc, v132, v236
	v_subbrev_co_u32_e32 v239, vcc, 0, v133, vcc
	s_nop 0
	v_readfirstlane_b32 s40, v238
	v_readfirstlane_b32 s41, v239
	v_sub_co_u32_e32 v238, vcc, v132, v236
	v_subbrev_co_u32_e32 v239, vcc, 0, v133, vcc
	s_nop 0
	v_readfirstlane_b32 s44, v238
	v_readfirstlane_b32 s45, v239
	v_sub_co_u32_e32 v238, vcc, v122, v237
	v_subbrev_co_u32_e32 v239, vcc, 0, v123, vcc
	s_nop 0
	v_readfirstlane_b32 s48, v238
	v_readfirstlane_b32 s49, v239
	s_add_u32 s42, s40, 0x8000
	s_addc_u32 s43, s41, 0
	s_add_u32 s46, s44, 0x8000
	s_addc_u32 s47, s45, 0
	s_add_u32 s50, s48, 0x4000
	s_addc_u32 s51, s49, 0
	v_and_b32_e32 v238, 7, v243
	v_lshrrev_b32_e32 v239, 3, v243
	v_lshlrev_b32_e32 v244, 12, v238
	v_lshl_or_b32 v244, v239, 6, v244
	v_lshl_or_b32 v244, v242, 4, v244
	v_lshlrev_b32_e32 v245, 11, v238
	v_lshl_or_b32 v245, v239, 5, v245
	v_lshl_or_b32 v245, v242, 3, v245
	global_load_dwordx4 v[192:195], v244, s[40:41]
	global_load_dwordx4 v[198:201], v244, s[40:41] offset:128
	global_load_dwordx4 v[202:205], v244, s[42:43]
	global_load_dwordx4 v[206:209], v244, s[42:43] offset:128
	s_add_u32 s40, s40, 0x10000
	s_addc_u32 s41, s41, 0
	s_add_u32 s42, s42, 0x10000
	s_addc_u32 s43, s43, 0
	global_load_dwordx4 v[216:219], v244, s[40:41]
	global_load_dwordx4 v[220:223], v244, s[40:41] offset:128
	global_load_dwordx4 v[224:227], v244, s[42:43]
	global_load_dwordx4 v[228:231], v244, s[42:43] offset:128
	s_add_u32 s40, s40, 0x10000
	s_addc_u32 s41, s41, 0
	s_add_u32 s42, s42, 0x10000
	s_addc_u32 s43, s43, 0
	s_waitcnt vmcnt(4)
; DI void gemm8_epi_resid(f32x4 (&acc)[8][4], int m0, int n0, int ntile8, bf16_t* L, const float* xin, float* out, bf16_t* xb, float* rowpart) {
;     ...
; #pragma unroll
;   for (int i = 0; i < 8; ++i) {
;     const int ml = wm * 128 + i * 16 + (lane & 15);
;     const size_t rowoff = (size_t)(m0 + ml) * DM;
;     float ss = 0.f;
; #pragma unroll
;     for (int j = 0; j < 4; ++j) {
;       const int n = n0 + wn * 64 + j * 16 + (lane >> 4) * 4;
;       const float4 xv = *(const float4*)(xin + rowoff + n);
;       const float o0 = xv.x + acc[i][j][0], o1 = xv.y + acc[i][j][1], o2 = xv.z + acc[i][j][2], o3 = xv.w + acc[i][j][3];
;       *(float4*)(out + rowoff + n) = make_float4(o0, o1, o2, o3);
;       ss += o0 * o0 + o1 * o1 + o2 * o2 + o3 * o3;
;       uint2 u;
;       u.x = pack2(o0, o1);
;       u.y = pack2(o2, o3);
;       *(uint2*)(xb + rowoff + n) = u;
;     }
;     ss += shx(ss, 16, lane);
;     ss += shx(ss, 32, lane);
;     if ((lane >> 4) == 0) red[wn * 256 + ml] = ss;
;   }
	v_mov_b32_dpp v232, v154 row_ror:8 row_mask:0xf bank_mask:0xf
	v_mov_b32_dpp v233, v155 row_ror:8 row_mask:0xf bank_mask:0xf
	v_mov_b32_dpp v234, v156 row_ror:8 row_mask:0xf bank_mask:0xf
	v_mov_b32_dpp v235, v157 row_ror:8 row_mask:0xf bank_mask:0xf
	v_cndmask_b32_e64 v232, v232, v158, s[90:91]
	v_cndmask_b32_e64 v233, v233, v159, s[90:91]
	v_cndmask_b32_e64 v234, v234, v160, s[90:91]
	v_cndmask_b32_e64 v235, v235, v161, s[90:91]
	v_pk_add_f32 v[232:233], v[232:233], v[192:193]
	v_pk_add_f32 v[234:235], v[234:235], v[194:195]
	s_nop 0
	global_store_dwordx4 v244, v[232:235], s[44:45]
	v_cvt_pk_bf16_f32 v240, v232, v233
	v_cvt_pk_bf16_f32 v241, v234, v235
	v_pk_mul_f32 v[236:237], v[232:233], v[232:233]
	v_pk_mul_f32 v[238:239], v[234:235], v[234:235]
	global_store_dwordx2 v245, v[240:241], s[48:49]
	v_add_f32_e32 v242, v236, v237
	v_add_f32_e32 v242, v242, v238
	v_add_f32_e32 v242, v242, v239
	v_mov_b32_dpp v232, v158 row_ror:8 row_mask:0xf bank_mask:0xf
	v_mov_b32_dpp v233, v159 row_ror:8 row_mask:0xf bank_mask:0xf
	v_mov_b32_dpp v234, v160 row_ror:8 row_mask:0xf bank_mask:0xf
	v_mov_b32_dpp v235, v161 row_ror:8 row_mask:0xf bank_mask:0xf
	v_cndmask_b32_e64 v232, v154, v232, s[90:91]
	v_cndmask_b32_e64 v233, v155, v233, s[90:91]
	v_cndmask_b32_e64 v234, v156, v234, s[90:91]
	v_cndmask_b32_e64 v235, v157, v235, s[90:91]
	v_pk_add_f32 v[232:233], v[232:233], v[202:203]
	v_pk_add_f32 v[234:235], v[234:235], v[204:205]
	s_nop 0
	global_store_dwordx4 v244, v[232:235], s[46:47]
	v_cvt_pk_bf16_f32 v240, v232, v233
	v_cvt_pk_bf16_f32 v241, v234, v235
	v_pk_mul_f32 v[236:237], v[232:233], v[232:233]
	v_pk_mul_f32 v[238:239], v[234:235], v[234:235]
	global_store_dwordx2 v245, v[240:241], s[50:51]
	v_add_f32_e32 v191, v236, v237
	v_add_f32_e32 v191, v191, v238
	v_add_f32_e32 v191, v191, v239
	v_mov_b32_dpp v232, v2 row_ror:8 row_mask:0xf bank_mask:0xf
	v_mov_b32_dpp v233, v3 row_ror:8 row_mask:0xf bank_mask:0xf
	v_mov_b32_dpp v234, v4 row_ror:8 row_mask:0xf bank_mask:0xf
	v_mov_b32_dpp v235, v5 row_ror:8 row_mask:0xf bank_mask:0xf
	v_cndmask_b32_e64 v232, v232, v150, s[90:91]
	v_cndmask_b32_e64 v233, v233, v151, s[90:91]
	v_cndmask_b32_e64 v234, v234, v152, s[90:91]
	v_cndmask_b32_e64 v235, v235, v153, s[90:91]
	v_pk_add_f32 v[232:233], v[232:233], v[198:199]
	v_pk_add_f32 v[234:235], v[234:235], v[200:201]
	s_nop 0
	global_store_dwordx4 v244, v[232:235], s[44:45] offset:128
	v_cvt_pk_bf16_f32 v240, v232, v233
	v_cvt_pk_bf16_f32 v241, v234, v235
	v_pk_mul_f32 v[236:237], v[232:233], v[232:233]
	v_pk_mul_f32 v[238:239], v[234:235], v[234:235]
	global_store_dwordx2 v245, v[240:241], s[48:49] offset:64
	v_add_f32_e32 v242, v242, v236
	v_add_f32_e32 v242, v242, v237
	v_add_f32_e32 v242, v242, v238
	v_add_f32_e32 v242, v242, v239
	v_mov_b32_dpp v232, v150 row_ror:8 row_mask:0xf bank_mask:0xf
	v_mov_b32_dpp v233, v151 row_ror:8 row_mask:0xf bank_mask:0xf
	v_mov_b32_dpp v234, v152 row_ror:8 row_mask:0xf bank_mask:0xf
	v_mov_b32_dpp v235, v153 row_ror:8 row_mask:0xf bank_mask:0xf
	v_cndmask_b32_e64 v232, v2, v232, s[90:91]
	v_cndmask_b32_e64 v233, v3, v233, s[90:91]
	v_cndmask_b32_e64 v234, v4, v234, s[90:91]
	v_cndmask_b32_e64 v235, v5, v235, s[90:91]
	v_pk_add_f32 v[232:233], v[232:233], v[206:207]
	v_pk_add_f32 v[234:235], v[234:235], v[208:209]
	s_nop 0
	global_store_dwordx4 v244, v[232:235], s[46:47] offset:128
	v_cvt_pk_bf16_f32 v240, v232, v233
	v_cvt_pk_bf16_f32 v241, v234, v235
	v_pk_mul_f32 v[236:237], v[232:233], v[232:233]
	v_pk_mul_f32 v[238:239], v[234:235], v[234:235]
	global_store_dwordx2 v245, v[240:241], s[50:51] offset:64
	v_add_f32_e32 v191, v191, v236
	v_add_f32_e32 v191, v191, v237
	v_add_f32_e32 v191, v191, v238
	v_add_f32_e32 v191, v191, v239
	s_nop 1
	v_add_f32_dpp v242, v242, v242 row_ror:8 row_mask:0xf bank_mask:0xf
	v_add_f32_dpp v191, v191, v191 row_ror:8 row_mask:0xf bank_mask:0xf
	s_add_u32 s44, s44, 0x10000
	s_addc_u32 s45, s45, 0
	s_add_u32 s46, s46, 0x10000
	s_addc_u32 s47, s47, 0
	s_add_u32 s48, s48, 0x8000
	s_addc_u32 s49, s49, 0
	s_add_u32 s50, s50, 0x8000
	s_addc_u32 s51, s51, 0
	v_cndmask_b32_e64 v242, v191, v242, s[90:91]
	ds_bpermute_b32 v243, v189, v242
	global_load_dwordx4 v[192:195], v244, s[40:41]
	global_load_dwordx4 v[198:201], v244, s[40:41] offset:128
	global_load_dwordx4 v[202:205], v244, s[42:43]
	global_load_dwordx4 v[206:209], v244, s[42:43] offset:128
	s_add_u32 s40, s40, 0x10000
	s_addc_u32 s41, s41, 0
	s_add_u32 s42, s42, 0x10000
	s_addc_u32 s43, s43, 0
	s_waitcnt lgkmcnt(0)
	v_add_f32_e32 v242, v242, v243
	ds_bpermute_b32 v243, v190, v242
	s_waitcnt lgkmcnt(0)
	v_add_f32_e32 v242, v242, v243
	s_and_saveexec_b64 s[2:3], s[88:89]
	ds_write_b32 v188, v242
	s_or_b64 exec, exec, s[2:3]
	s_waitcnt vmcnt(12)
; DI void gemm8_epi_resid(f32x4 (&acc)[8][4], int m0, int n0, int ntile8, bf16_t* L, const float* xin, float* out, bf16_t* xb, float* rowpart) {
;     ...
; #pragma unroll
;   for (int i = 0; i < 8; ++i) {
;     const int ml = wm * 128 + i * 16 + (lane & 15);
;     const size_t rowoff = (size_t)(m0 + ml) * DM;
;     float ss = 0.f;
; #pragma unroll
;     for (int j = 0; j < 4; ++j) {
;       const int n = n0 + wn * 64 + j * 16 + (lane >> 4) * 4;
;       const float4 xv = *(const float4*)(xin + rowoff + n);
;       const float o0 = xv.x + acc[i][j][0], o1 = xv.y + acc[i][j][1], o2 = xv.z + acc[i][j][2], o3 = xv.w + acc[i][j][3];
;       *(float4*)(out + rowoff + n) = make_float4(o0, o1, o2, o3);
;       ss += o0 * o0 + o1 * o1 + o2 * o2 + o3 * o3;
;       uint2 u;
;       u.x = pack2(o0, o1);
;       u.y = pack2(o2, o3);
;       *(uint2*)(xb + rowoff + n) = u;
;     }
;     ss += shx(ss, 16, lane);
;     ss += shx(ss, 32, lane);
;     if ((lane >> 4) == 0) red[wn * 256 + ml] = ss;
;   }
	v_mov_b32_dpp v232, v106 row_ror:8 row_mask:0xf bank_mask:0xf
	v_mov_b32_dpp v233, v107 row_ror:8 row_mask:0xf bank_mask:0xf
	v_mov_b32_dpp v234, v108 row_ror:8 row_mask:0xf bank_mask:0xf
	v_mov_b32_dpp v235, v109 row_ror:8 row_mask:0xf bank_mask:0xf
	v_cndmask_b32_e64 v232, v232, v110, s[90:91]
	v_cndmask_b32_e64 v233, v233, v111, s[90:91]
	v_cndmask_b32_e64 v234, v234, v112, s[90:91]
	v_cndmask_b32_e64 v235, v235, v113, s[90:91]
	v_pk_add_f32 v[232:233], v[232:233], v[216:217]
	v_pk_add_f32 v[234:235], v[234:235], v[218:219]
	s_nop 0
	global_store_dwordx4 v244, v[232:235], s[44:45]
	v_cvt_pk_bf16_f32 v240, v232, v233
	v_cvt_pk_bf16_f32 v241, v234, v235
	v_pk_mul_f32 v[236:237], v[232:233], v[232:233]
	v_pk_mul_f32 v[238:239], v[234:235], v[234:235]
	global_store_dwordx2 v245, v[240:241], s[48:49]
	v_add_f32_e32 v242, v236, v237
	v_add_f32_e32 v242, v242, v238
	v_add_f32_e32 v242, v242, v239
	v_mov_b32_dpp v232, v110 row_ror:8 row_mask:0xf bank_mask:0xf
	v_mov_b32_dpp v233, v111 row_ror:8 row_mask:0xf bank_mask:0xf
	v_mov_b32_dpp v234, v112 row_ror:8 row_mask:0xf bank_mask:0xf
	v_mov_b32_dpp v235, v113 row_ror:8 row_mask:0xf bank_mask:0xf
	v_cndmask_b32_e64 v232, v106, v232, s[90:91]
	v_cndmask_b32_e64 v233, v107, v233, s[90:91]
	v_cndmask_b32_e64 v234, v108, v234, s[90:91]
	v_cndmask_b32_e64 v235, v109, v235, s[90:91]
	v_pk_add_f32 v[232:233], v[232:233], v[224:225]
	v_pk_add_f32 v[234:235], v[234:235], v[226:227]
	s_nop 0
	global_store_dwordx4 v244, v[232:235], s[46:47]
	v_cvt_pk_bf16_f32 v240, v232, v233
	v_cvt_pk_bf16_f32 v241, v234, v235
	v_pk_mul_f32 v[236:237], v[232:233], v[232:233]
	v_pk_mul_f32 v[238:239], v[234:235], v[234:235]
	global_store_dwordx2 v245, v[240:241], s[50:51]
	v_add_f32_e32 v191, v236, v237
	v_add_f32_e32 v191, v191, v238
	v_add_f32_e32 v191, v191, v239
	v_mov_b32_dpp v232, v98 row_ror:8 row_mask:0xf bank_mask:0xf
	v_mov_b32_dpp v233, v99 row_ror:8 row_mask:0xf bank_mask:0xf
	v_mov_b32_dpp v234, v100 row_ror:8 row_mask:0xf bank_mask:0xf
	v_mov_b32_dpp v235, v101 row_ror:8 row_mask:0xf bank_mask:0xf
	v_cndmask_b32_e64 v232, v232, v102, s[90:91]
	v_cndmask_b32_e64 v233, v233, v103, s[90:91]
	v_cndmask_b32_e64 v234, v234, v104, s[90:91]
	v_cndmask_b32_e64 v235, v235, v105, s[90:91]
	v_pk_add_f32 v[232:233], v[232:233], v[220:221]
	v_pk_add_f32 v[234:235], v[234:235], v[222:223]
	s_nop 0
	global_store_dwordx4 v244, v[232:235], s[44:45] offset:128
	v_cvt_pk_bf16_f32 v240, v232, v233
	v_cvt_pk_bf16_f32 v241, v234, v235
	v_pk_mul_f32 v[236:237], v[232:233], v[232:233]
	v_pk_mul_f32 v[238:239], v[234:235], v[234:235]
	global_store_dwordx2 v245, v[240:241], s[48:49] offset:64
	v_add_f32_e32 v242, v242, v236
	v_add_f32_e32 v242, v242, v237
	v_add_f32_e32 v242, v242, v238
	v_add_f32_e32 v242, v242, v239
	v_mov_b32_dpp v232, v102 row_ror:8 row_mask:0xf bank_mask:0xf
	v_mov_b32_dpp v233, v103 row_ror:8 row_mask:0xf bank_mask:0xf
	v_mov_b32_dpp v234, v104 row_ror:8 row_mask:0xf bank_mask:0xf
	v_mov_b32_dpp v235, v105 row_ror:8 row_mask:0xf bank_mask:0xf
	v_cndmask_b32_e64 v232, v98, v232, s[90:91]
	v_cndmask_b32_e64 v233, v99, v233, s[90:91]
	v_cndmask_b32_e64 v234, v100, v234, s[90:91]
	v_cndmask_b32_e64 v235, v101, v235, s[90:91]
	v_pk_add_f32 v[232:233], v[232:233], v[228:229]
	v_pk_add_f32 v[234:235], v[234:235], v[230:231]
	s_nop 0
	global_store_dwordx4 v244, v[232:235], s[46:47] offset:128
	v_cvt_pk_bf16_f32 v240, v232, v233
	v_cvt_pk_bf16_f32 v241, v234, v235
	v_pk_mul_f32 v[236:237], v[232:233], v[232:233]
	v_pk_mul_f32 v[238:239], v[234:235], v[234:235]
	global_store_dwordx2 v245, v[240:241], s[50:51] offset:64
	v_add_f32_e32 v191, v191, v236
	v_add_f32_e32 v191, v191, v237
	v_add_f32_e32 v191, v191, v238
	v_add_f32_e32 v191, v191, v239
	s_nop 1
	v_add_f32_dpp v242, v242, v242 row_ror:8 row_mask:0xf bank_mask:0xf
	v_add_f32_dpp v191, v191, v191 row_ror:8 row_mask:0xf bank_mask:0xf
	s_add_u32 s44, s44, 0x10000
	s_addc_u32 s45, s45, 0
	s_add_u32 s46, s46, 0x10000
	s_addc_u32 s47, s47, 0
	s_add_u32 s48, s48, 0x8000
	s_addc_u32 s49, s49, 0
	s_add_u32 s50, s50, 0x8000
	s_addc_u32 s51, s51, 0
	v_cndmask_b32_e64 v242, v191, v242, s[90:91]
	ds_bpermute_b32 v243, v189, v242
	global_load_dwordx4 v[216:219], v244, s[40:41]
	global_load_dwordx4 v[220:223], v244, s[40:41] offset:128
	global_load_dwordx4 v[224:227], v244, s[42:43]
	global_load_dwordx4 v[228:231], v244, s[42:43] offset:128
	s_add_u32 s40, s40, 0x10000
	s_addc_u32 s41, s41, 0
	s_add_u32 s42, s42, 0x10000
	s_addc_u32 s43, s43, 0
	s_waitcnt lgkmcnt(0)
	v_add_f32_e32 v242, v242, v243
	ds_bpermute_b32 v243, v190, v242
	s_waitcnt lgkmcnt(0)
	v_add_f32_e32 v242, v242, v243
	s_and_saveexec_b64 s[2:3], s[88:89]
	ds_write_b32 v188, v242 offset:64
	s_or_b64 exec, exec, s[2:3]
	s_waitcnt vmcnt(12)
; DI void gemm8_epi_resid(f32x4 (&acc)[8][4], int m0, int n0, int ntile8, bf16_t* L, const float* xin, float* out, bf16_t* xb, float* rowpart) {
;     ...
; #pragma unroll
;   for (int i = 0; i < 8; ++i) {
;     const int ml = wm * 128 + i * 16 + (lane & 15);
;     const size_t rowoff = (size_t)(m0 + ml) * DM;
;     float ss = 0.f;
; #pragma unroll
;     for (int j = 0; j < 4; ++j) {
;       const int n = n0 + wn * 64 + j * 16 + (lane >> 4) * 4;
;       const float4 xv = *(const float4*)(xin + rowoff + n);
;       const float o0 = xv.x + acc[i][j][0], o1 = xv.y + acc[i][j][1], o2 = xv.z + acc[i][j][2], o3 = xv.w + acc[i][j][3];
;       *(float4*)(out + rowoff + n) = make_float4(o0, o1, o2, o3);
;       ss += o0 * o0 + o1 * o1 + o2 * o2 + o3 * o3;
;       uint2 u;
;       u.x = pack2(o0, o1);
;       u.y = pack2(o2, o3);
;       *(uint2*)(xb + rowoff + n) = u;
;     }
;     ss += shx(ss, 16, lane);
;     ss += shx(ss, 32, lane);
;     if ((lane >> 4) == 0) red[wn * 256 + ml] = ss;
;   }
	v_mov_b32_dpp v232, v90 row_ror:8 row_mask:0xf bank_mask:0xf
	v_mov_b32_dpp v233, v91 row_ror:8 row_mask:0xf bank_mask:0xf
	v_mov_b32_dpp v234, v92 row_ror:8 row_mask:0xf bank_mask:0xf
	v_mov_b32_dpp v235, v93 row_ror:8 row_mask:0xf bank_mask:0xf
	v_cndmask_b32_e64 v232, v232, v94, s[90:91]
	v_cndmask_b32_e64 v233, v233, v95, s[90:91]
	v_cndmask_b32_e64 v234, v234, v96, s[90:91]
	v_cndmask_b32_e64 v235, v235, v97, s[90:91]
	v_pk_add_f32 v[232:233], v[232:233], v[192:193]
	v_pk_add_f32 v[234:235], v[234:235], v[194:195]
	s_nop 0
	global_store_dwordx4 v244, v[232:235], s[44:45]
	v_cvt_pk_bf16_f32 v240, v232, v233
	v_cvt_pk_bf16_f32 v241, v234, v235
	v_pk_mul_f32 v[236:237], v[232:233], v[232:233]
	v_pk_mul_f32 v[238:239], v[234:235], v[234:235]
	global_store_dwordx2 v245, v[240:241], s[48:49]
	v_add_f32_e32 v242, v236, v237
	v_add_f32_e32 v242, v242, v238
	v_add_f32_e32 v242, v242, v239
	v_mov_b32_dpp v232, v94 row_ror:8 row_mask:0xf bank_mask:0xf
	v_mov_b32_dpp v233, v95 row_ror:8 row_mask:0xf bank_mask:0xf
	v_mov_b32_dpp v234, v96 row_ror:8 row_mask:0xf bank_mask:0xf
	v_mov_b32_dpp v235, v97 row_ror:8 row_mask:0xf bank_mask:0xf
	v_cndmask_b32_e64 v232, v90, v232, s[90:91]
	v_cndmask_b32_e64 v233, v91, v233, s[90:91]
	v_cndmask_b32_e64 v234, v92, v234, s[90:91]
	v_cndmask_b32_e64 v235, v93, v235, s[90:91]
	v_pk_add_f32 v[232:233], v[232:233], v[202:203]
	v_pk_add_f32 v[234:235], v[234:235], v[204:205]
	s_nop 0
	global_store_dwordx4 v244, v[232:235], s[46:47]
	v_cvt_pk_bf16_f32 v240, v232, v233
	v_cvt_pk_bf16_f32 v241, v234, v235
	v_pk_mul_f32 v[236:237], v[232:233], v[232:233]
	v_pk_mul_f32 v[238:239], v[234:235], v[234:235]
	global_store_dwordx2 v245, v[240:241], s[50:51]
	v_add_f32_e32 v191, v236, v237
	v_add_f32_e32 v191, v191, v238
	v_add_f32_e32 v191, v191, v239
	v_mov_b32_dpp v232, v82 row_ror:8 row_mask:0xf bank_mask:0xf
	v_mov_b32_dpp v233, v83 row_ror:8 row_mask:0xf bank_mask:0xf
	v_mov_b32_dpp v234, v84 row_ror:8 row_mask:0xf bank_mask:0xf
	v_mov_b32_dpp v235, v85 row_ror:8 row_mask:0xf bank_mask:0xf
	v_cndmask_b32_e64 v232, v232, v86, s[90:91]
	v_cndmask_b32_e64 v233, v233, v87, s[90:91]
	v_cndmask_b32_e64 v234, v234, v88, s[90:91]
	v_cndmask_b32_e64 v235, v235, v89, s[90:91]
	v_pk_add_f32 v[232:233], v[232:233], v[198:199]
	v_pk_add_f32 v[234:235], v[234:235], v[200:201]
	s_nop 0
	global_store_dwordx4 v244, v[232:235], s[44:45] offset:128
	v_cvt_pk_bf16_f32 v240, v232, v233
	v_cvt_pk_bf16_f32 v241, v234, v235
	v_pk_mul_f32 v[236:237], v[232:233], v[232:233]
	v_pk_mul_f32 v[238:239], v[234:235], v[234:235]
	global_store_dwordx2 v245, v[240:241], s[48:49] offset:64
	v_add_f32_e32 v242, v242, v236
	v_add_f32_e32 v242, v242, v237
	v_add_f32_e32 v242, v242, v238
	v_add_f32_e32 v242, v242, v239
	v_mov_b32_dpp v232, v86 row_ror:8 row_mask:0xf bank_mask:0xf
	v_mov_b32_dpp v233, v87 row_ror:8 row_mask:0xf bank_mask:0xf
	v_mov_b32_dpp v234, v88 row_ror:8 row_mask:0xf bank_mask:0xf
	v_mov_b32_dpp v235, v89 row_ror:8 row_mask:0xf bank_mask:0xf
	v_cndmask_b32_e64 v232, v82, v232, s[90:91]
	v_cndmask_b32_e64 v233, v83, v233, s[90:91]
	v_cndmask_b32_e64 v234, v84, v234, s[90:91]
	v_cndmask_b32_e64 v235, v85, v235, s[90:91]
	v_pk_add_f32 v[232:233], v[232:233], v[206:207]
	v_pk_add_f32 v[234:235], v[234:235], v[208:209]
	s_nop 0
	global_store_dwordx4 v244, v[232:235], s[46:47] offset:128
	v_cvt_pk_bf16_f32 v240, v232, v233
	v_cvt_pk_bf16_f32 v241, v234, v235
	v_pk_mul_f32 v[236:237], v[232:233], v[232:233]
	v_pk_mul_f32 v[238:239], v[234:235], v[234:235]
	global_store_dwordx2 v245, v[240:241], s[50:51] offset:64
	v_add_f32_e32 v191, v191, v236
	v_add_f32_e32 v191, v191, v237
	v_add_f32_e32 v191, v191, v238
	v_add_f32_e32 v191, v191, v239
	s_nop 1
	v_add_f32_dpp v242, v242, v242 row_ror:8 row_mask:0xf bank_mask:0xf
	v_add_f32_dpp v191, v191, v191 row_ror:8 row_mask:0xf bank_mask:0xf
	s_add_u32 s44, s44, 0x10000
	s_addc_u32 s45, s45, 0
	s_add_u32 s46, s46, 0x10000
	s_addc_u32 s47, s47, 0
	s_add_u32 s48, s48, 0x8000
	s_addc_u32 s49, s49, 0
	s_add_u32 s50, s50, 0x8000
	s_addc_u32 s51, s51, 0
	v_cndmask_b32_e64 v242, v191, v242, s[90:91]
	ds_bpermute_b32 v243, v189, v242
	global_load_dwordx4 v[192:195], v244, s[40:41]
	global_load_dwordx4 v[198:201], v244, s[40:41] offset:128
	global_load_dwordx4 v[202:205], v244, s[42:43]
	global_load_dwordx4 v[206:209], v244, s[42:43] offset:128
	s_add_u32 s40, s40, 0x10000
	s_addc_u32 s41, s41, 0
	s_add_u32 s42, s42, 0x10000
	s_addc_u32 s43, s43, 0
	s_waitcnt lgkmcnt(0)
	v_add_f32_e32 v242, v242, v243
	ds_bpermute_b32 v243, v190, v242
	s_waitcnt lgkmcnt(0)
	v_add_f32_e32 v242, v242, v243
	s_and_saveexec_b64 s[2:3], s[88:89]
	ds_write_b32 v188, v242 offset:128
	s_or_b64 exec, exec, s[2:3]
	s_waitcnt vmcnt(12)
; DI void gemm8_epi_resid(f32x4 (&acc)[8][4], int m0, int n0, int ntile8, bf16_t* L, const float* xin, float* out, bf16_t* xb, float* rowpart) {
;     ...
; #pragma unroll
;   for (int i = 0; i < 8; ++i) {
;     const int ml = wm * 128 + i * 16 + (lane & 15);
;     const size_t rowoff = (size_t)(m0 + ml) * DM;
;     float ss = 0.f;
; #pragma unroll
;     for (int j = 0; j < 4; ++j) {
;       const int n = n0 + wn * 64 + j * 16 + (lane >> 4) * 4;
;       const float4 xv = *(const float4*)(xin + rowoff + n);
;       const float o0 = xv.x + acc[i][j][0], o1 = xv.y + acc[i][j][1], o2 = xv.z + acc[i][j][2], o3 = xv.w + acc[i][j][3];
;       *(float4*)(out + rowoff + n) = make_float4(o0, o1, o2, o3);
;       ss += o0 * o0 + o1 * o1 + o2 * o2 + o3 * o3;
;       uint2 u;
;       u.x = pack2(o0, o1);
;       u.y = pack2(o2, o3);
;       *(uint2*)(xb + rowoff + n) = u;
;     }
;     ss += shx(ss, 16, lane);
;     ss += shx(ss, 32, lane);
;     if ((lane >> 4) == 0) red[wn * 256 + ml] = ss;
;   }
	v_mov_b32_dpp v232, v74 row_ror:8 row_mask:0xf bank_mask:0xf
	v_mov_b32_dpp v233, v75 row_ror:8 row_mask:0xf bank_mask:0xf
	v_mov_b32_dpp v234, v76 row_ror:8 row_mask:0xf bank_mask:0xf
	v_mov_b32_dpp v235, v77 row_ror:8 row_mask:0xf bank_mask:0xf
	v_cndmask_b32_e64 v232, v232, v78, s[90:91]
	v_cndmask_b32_e64 v233, v233, v79, s[90:91]
	v_cndmask_b32_e64 v234, v234, v80, s[90:91]
	v_cndmask_b32_e64 v235, v235, v81, s[90:91]
	v_pk_add_f32 v[232:233], v[232:233], v[216:217]
	v_pk_add_f32 v[234:235], v[234:235], v[218:219]
	s_nop 0
	global_store_dwordx4 v244, v[232:235], s[44:45]
	v_cvt_pk_bf16_f32 v240, v232, v233
	v_cvt_pk_bf16_f32 v241, v234, v235
	v_pk_mul_f32 v[236:237], v[232:233], v[232:233]
	v_pk_mul_f32 v[238:239], v[234:235], v[234:235]
	global_store_dwordx2 v245, v[240:241], s[48:49]
	v_add_f32_e32 v242, v236, v237
	v_add_f32_e32 v242, v242, v238
	v_add_f32_e32 v242, v242, v239
	v_mov_b32_dpp v232, v78 row_ror:8 row_mask:0xf bank_mask:0xf
	v_mov_b32_dpp v233, v79 row_ror:8 row_mask:0xf bank_mask:0xf
	v_mov_b32_dpp v234, v80 row_ror:8 row_mask:0xf bank_mask:0xf
	v_mov_b32_dpp v235, v81 row_ror:8 row_mask:0xf bank_mask:0xf
	v_cndmask_b32_e64 v232, v74, v232, s[90:91]
	v_cndmask_b32_e64 v233, v75, v233, s[90:91]
	v_cndmask_b32_e64 v234, v76, v234, s[90:91]
	v_cndmask_b32_e64 v235, v77, v235, s[90:91]
	v_pk_add_f32 v[232:233], v[232:233], v[224:225]
	v_pk_add_f32 v[234:235], v[234:235], v[226:227]
	s_nop 0
	global_store_dwordx4 v244, v[232:235], s[46:47]
	v_cvt_pk_bf16_f32 v240, v232, v233
	v_cvt_pk_bf16_f32 v241, v234, v235
	v_pk_mul_f32 v[236:237], v[232:233], v[232:233]
	v_pk_mul_f32 v[238:239], v[234:235], v[234:235]
	global_store_dwordx2 v245, v[240:241], s[50:51]
	v_add_f32_e32 v191, v236, v237
	v_add_f32_e32 v191, v191, v238
	v_add_f32_e32 v191, v191, v239
	v_mov_b32_dpp v232, v66 row_ror:8 row_mask:0xf bank_mask:0xf
	v_mov_b32_dpp v233, v67 row_ror:8 row_mask:0xf bank_mask:0xf
	v_mov_b32_dpp v234, v68 row_ror:8 row_mask:0xf bank_mask:0xf
	v_mov_b32_dpp v235, v69 row_ror:8 row_mask:0xf bank_mask:0xf
	v_cndmask_b32_e64 v232, v232, v70, s[90:91]
	v_cndmask_b32_e64 v233, v233, v71, s[90:91]
	v_cndmask_b32_e64 v234, v234, v72, s[90:91]
	v_cndmask_b32_e64 v235, v235, v73, s[90:91]
	v_pk_add_f32 v[232:233], v[232:233], v[220:221]
	v_pk_add_f32 v[234:235], v[234:235], v[222:223]
	s_nop 0
	global_store_dwordx4 v244, v[232:235], s[44:45] offset:128
	v_cvt_pk_bf16_f32 v240, v232, v233
	v_cvt_pk_bf16_f32 v241, v234, v235
	v_pk_mul_f32 v[236:237], v[232:233], v[232:233]
	v_pk_mul_f32 v[238:239], v[234:235], v[234:235]
	global_store_dwordx2 v245, v[240:241], s[48:49] offset:64
	v_add_f32_e32 v242, v242, v236
	v_add_f32_e32 v242, v242, v237
	v_add_f32_e32 v242, v242, v238
	v_add_f32_e32 v242, v242, v239
	v_mov_b32_dpp v232, v70 row_ror:8 row_mask:0xf bank_mask:0xf
	v_mov_b32_dpp v233, v71 row_ror:8 row_mask:0xf bank_mask:0xf
	v_mov_b32_dpp v234, v72 row_ror:8 row_mask:0xf bank_mask:0xf
	v_mov_b32_dpp v235, v73 row_ror:8 row_mask:0xf bank_mask:0xf
	v_cndmask_b32_e64 v232, v66, v232, s[90:91]
	v_cndmask_b32_e64 v233, v67, v233, s[90:91]
	v_cndmask_b32_e64 v234, v68, v234, s[90:91]
	v_cndmask_b32_e64 v235, v69, v235, s[90:91]
	v_pk_add_f32 v[232:233], v[232:233], v[228:229]
	v_pk_add_f32 v[234:235], v[234:235], v[230:231]
	s_nop 0
	global_store_dwordx4 v244, v[232:235], s[46:47] offset:128
	v_cvt_pk_bf16_f32 v240, v232, v233
	v_cvt_pk_bf16_f32 v241, v234, v235
	v_pk_mul_f32 v[236:237], v[232:233], v[232:233]
	v_pk_mul_f32 v[238:239], v[234:235], v[234:235]
	global_store_dwordx2 v245, v[240:241], s[50:51] offset:64
	v_add_f32_e32 v191, v191, v236
	v_add_f32_e32 v191, v191, v237
	v_add_f32_e32 v191, v191, v238
	v_add_f32_e32 v191, v191, v239
	s_nop 1
	v_add_f32_dpp v242, v242, v242 row_ror:8 row_mask:0xf bank_mask:0xf
	v_add_f32_dpp v191, v191, v191 row_ror:8 row_mask:0xf bank_mask:0xf
	s_add_u32 s44, s44, 0x10000
	s_addc_u32 s45, s45, 0
	s_add_u32 s46, s46, 0x10000
	s_addc_u32 s47, s47, 0
	s_add_u32 s48, s48, 0x8000
	s_addc_u32 s49, s49, 0
	s_add_u32 s50, s50, 0x8000
	s_addc_u32 s51, s51, 0
	v_cndmask_b32_e64 v242, v191, v242, s[90:91]
	ds_bpermute_b32 v243, v189, v242
	global_load_dwordx4 v[216:219], v244, s[40:41]
	global_load_dwordx4 v[220:223], v244, s[40:41] offset:128
	global_load_dwordx4 v[224:227], v244, s[42:43]
	global_load_dwordx4 v[228:231], v244, s[42:43] offset:128
	s_add_u32 s40, s40, 0x10000
	s_addc_u32 s41, s41, 0
	s_add_u32 s42, s42, 0x10000
	s_addc_u32 s43, s43, 0
	s_waitcnt lgkmcnt(0)
	v_add_f32_e32 v242, v242, v243
	ds_bpermute_b32 v243, v190, v242
	s_waitcnt lgkmcnt(0)
	v_add_f32_e32 v242, v242, v243
	s_and_saveexec_b64 s[2:3], s[88:89]
	ds_write_b32 v188, v242 offset:192
	s_or_b64 exec, exec, s[2:3]
	s_waitcnt vmcnt(12)
; DI void gemm8_epi_resid(f32x4 (&acc)[8][4], int m0, int n0, int ntile8, bf16_t* L, const float* xin, float* out, bf16_t* xb, float* rowpart) {
;     ...
; #pragma unroll
;   for (int i = 0; i < 8; ++i) {
;     const int ml = wm * 128 + i * 16 + (lane & 15);
;     const size_t rowoff = (size_t)(m0 + ml) * DM;
;     float ss = 0.f;
; #pragma unroll
;     for (int j = 0; j < 4; ++j) {
;       const int n = n0 + wn * 64 + j * 16 + (lane >> 4) * 4;
;       const float4 xv = *(const float4*)(xin + rowoff + n);
;       const float o0 = xv.x + acc[i][j][0], o1 = xv.y + acc[i][j][1], o2 = xv.z + acc[i][j][2], o3 = xv.w + acc[i][j][3];
;       *(float4*)(out + rowoff + n) = make_float4(o0, o1, o2, o3);
;       ss += o0 * o0 + o1 * o1 + o2 * o2 + o3 * o3;
;       uint2 u;
;       u.x = pack2(o0, o1);
;       u.y = pack2(o2, o3);
;       *(uint2*)(xb + rowoff + n) = u;
;     }
;     ss += shx(ss, 16, lane);
;     ss += shx(ss, 32, lane);
;     if ((lane >> 4) == 0) red[wn * 256 + ml] = ss;
;   }
	v_mov_b32_dpp v232, v58 row_ror:8 row_mask:0xf bank_mask:0xf
	v_mov_b32_dpp v233, v59 row_ror:8 row_mask:0xf bank_mask:0xf
	v_mov_b32_dpp v234, v60 row_ror:8 row_mask:0xf bank_mask:0xf
	v_mov_b32_dpp v235, v61 row_ror:8 row_mask:0xf bank_mask:0xf
	v_cndmask_b32_e64 v232, v232, v62, s[90:91]
	v_cndmask_b32_e64 v233, v233, v63, s[90:91]
	v_cndmask_b32_e64 v234, v234, v64, s[90:91]
	v_cndmask_b32_e64 v235, v235, v65, s[90:91]
	v_pk_add_f32 v[232:233], v[232:233], v[192:193]
	v_pk_add_f32 v[234:235], v[234:235], v[194:195]
	s_nop 0
	global_store_dwordx4 v244, v[232:235], s[44:45]
	v_cvt_pk_bf16_f32 v240, v232, v233
	v_cvt_pk_bf16_f32 v241, v234, v235
	v_pk_mul_f32 v[236:237], v[232:233], v[232:233]
	v_pk_mul_f32 v[238:239], v[234:235], v[234:235]
	global_store_dwordx2 v245, v[240:241], s[48:49]
	v_add_f32_e32 v242, v236, v237
	v_add_f32_e32 v242, v242, v238
	v_add_f32_e32 v242, v242, v239
	v_mov_b32_dpp v232, v62 row_ror:8 row_mask:0xf bank_mask:0xf
	v_mov_b32_dpp v233, v63 row_ror:8 row_mask:0xf bank_mask:0xf
	v_mov_b32_dpp v234, v64 row_ror:8 row_mask:0xf bank_mask:0xf
	v_mov_b32_dpp v235, v65 row_ror:8 row_mask:0xf bank_mask:0xf
	v_cndmask_b32_e64 v232, v58, v232, s[90:91]
	v_cndmask_b32_e64 v233, v59, v233, s[90:91]
	v_cndmask_b32_e64 v234, v60, v234, s[90:91]
	v_cndmask_b32_e64 v235, v61, v235, s[90:91]
	v_pk_add_f32 v[232:233], v[232:233], v[202:203]
	v_pk_add_f32 v[234:235], v[234:235], v[204:205]
	s_nop 0
	global_store_dwordx4 v244, v[232:235], s[46:47]
	v_cvt_pk_bf16_f32 v240, v232, v233
	v_cvt_pk_bf16_f32 v241, v234, v235
	v_pk_mul_f32 v[236:237], v[232:233], v[232:233]
	v_pk_mul_f32 v[238:239], v[234:235], v[234:235]
	global_store_dwordx2 v245, v[240:241], s[50:51]
	v_add_f32_e32 v191, v236, v237
	v_add_f32_e32 v191, v191, v238
	v_add_f32_e32 v191, v191, v239
	v_mov_b32_dpp v232, v50 row_ror:8 row_mask:0xf bank_mask:0xf
	v_mov_b32_dpp v233, v51 row_ror:8 row_mask:0xf bank_mask:0xf
	v_mov_b32_dpp v234, v52 row_ror:8 row_mask:0xf bank_mask:0xf
	v_mov_b32_dpp v235, v53 row_ror:8 row_mask:0xf bank_mask:0xf
	v_cndmask_b32_e64 v232, v232, v54, s[90:91]
	v_cndmask_b32_e64 v233, v233, v55, s[90:91]
	v_cndmask_b32_e64 v234, v234, v56, s[90:91]
	v_cndmask_b32_e64 v235, v235, v57, s[90:91]
	v_pk_add_f32 v[232:233], v[232:233], v[198:199]
	v_pk_add_f32 v[234:235], v[234:235], v[200:201]
	s_nop 0
	global_store_dwordx4 v244, v[232:235], s[44:45] offset:128
	v_cvt_pk_bf16_f32 v240, v232, v233
	v_cvt_pk_bf16_f32 v241, v234, v235
	v_pk_mul_f32 v[236:237], v[232:233], v[232:233]
	v_pk_mul_f32 v[238:239], v[234:235], v[234:235]
	global_store_dwordx2 v245, v[240:241], s[48:49] offset:64
	v_add_f32_e32 v242, v242, v236
	v_add_f32_e32 v242, v242, v237
	v_add_f32_e32 v242, v242, v238
	v_add_f32_e32 v242, v242, v239
	v_mov_b32_dpp v232, v54 row_ror:8 row_mask:0xf bank_mask:0xf
	v_mov_b32_dpp v233, v55 row_ror:8 row_mask:0xf bank_mask:0xf
	v_mov_b32_dpp v234, v56 row_ror:8 row_mask:0xf bank_mask:0xf
	v_mov_b32_dpp v235, v57 row_ror:8 row_mask:0xf bank_mask:0xf
	v_cndmask_b32_e64 v232, v50, v232, s[90:91]
	v_cndmask_b32_e64 v233, v51, v233, s[90:91]
	v_cndmask_b32_e64 v234, v52, v234, s[90:91]
	v_cndmask_b32_e64 v235, v53, v235, s[90:91]
	v_pk_add_f32 v[232:233], v[232:233], v[206:207]
	v_pk_add_f32 v[234:235], v[234:235], v[208:209]
	s_nop 0
	global_store_dwordx4 v244, v[232:235], s[46:47] offset:128
	v_cvt_pk_bf16_f32 v240, v232, v233
	v_cvt_pk_bf16_f32 v241, v234, v235
	v_pk_mul_f32 v[236:237], v[232:233], v[232:233]
	v_pk_mul_f32 v[238:239], v[234:235], v[234:235]
	global_store_dwordx2 v245, v[240:241], s[50:51] offset:64
	v_add_f32_e32 v191, v191, v236
	v_add_f32_e32 v191, v191, v237
	v_add_f32_e32 v191, v191, v238
	v_add_f32_e32 v191, v191, v239
	s_nop 1
	v_add_f32_dpp v242, v242, v242 row_ror:8 row_mask:0xf bank_mask:0xf
	v_add_f32_dpp v191, v191, v191 row_ror:8 row_mask:0xf bank_mask:0xf
	s_add_u32 s44, s44, 0x10000
	s_addc_u32 s45, s45, 0
	s_add_u32 s46, s46, 0x10000
	s_addc_u32 s47, s47, 0
	s_add_u32 s48, s48, 0x8000
	s_addc_u32 s49, s49, 0
	s_add_u32 s50, s50, 0x8000
	s_addc_u32 s51, s51, 0
	v_cndmask_b32_e64 v242, v191, v242, s[90:91]
	ds_bpermute_b32 v243, v189, v242
	global_load_dwordx4 v[192:195], v244, s[40:41]
	global_load_dwordx4 v[198:201], v244, s[40:41] offset:128
	global_load_dwordx4 v[202:205], v244, s[42:43]
	global_load_dwordx4 v[206:209], v244, s[42:43] offset:128
	s_add_u32 s40, s40, 0x10000
	s_addc_u32 s41, s41, 0
	s_add_u32 s42, s42, 0x10000
	s_addc_u32 s43, s43, 0
	s_waitcnt lgkmcnt(0)
	v_add_f32_e32 v242, v242, v243
	ds_bpermute_b32 v243, v190, v242
	s_waitcnt lgkmcnt(0)
	v_add_f32_e32 v242, v242, v243
	s_and_saveexec_b64 s[2:3], s[88:89]
	ds_write_b32 v188, v242 offset:256
	s_or_b64 exec, exec, s[2:3]
	s_waitcnt vmcnt(12)
; DI void gemm8_epi_resid(f32x4 (&acc)[8][4], int m0, int n0, int ntile8, bf16_t* L, const float* xin, float* out, bf16_t* xb, float* rowpart) {
;     ...
; #pragma unroll
;   for (int i = 0; i < 8; ++i) {
;     const int ml = wm * 128 + i * 16 + (lane & 15);
;     const size_t rowoff = (size_t)(m0 + ml) * DM;
;     float ss = 0.f;
; #pragma unroll
;     for (int j = 0; j < 4; ++j) {
;       const int n = n0 + wn * 64 + j * 16 + (lane >> 4) * 4;
;       const float4 xv = *(const float4*)(xin + rowoff + n);
;       const float o0 = xv.x + acc[i][j][0], o1 = xv.y + acc[i][j][1], o2 = xv.z + acc[i][j][2], o3 = xv.w + acc[i][j][3];
;       *(float4*)(out + rowoff + n) = make_float4(o0, o1, o2, o3);
;       ss += o0 * o0 + o1 * o1 + o2 * o2 + o3 * o3;
;       uint2 u;
;       u.x = pack2(o0, o1);
;       u.y = pack2(o2, o3);
;       *(uint2*)(xb + rowoff + n) = u;
;     }
;     ss += shx(ss, 16, lane);
;     ss += shx(ss, 32, lane);
;     if ((lane >> 4) == 0) red[wn * 256 + ml] = ss;
;   }
	v_mov_b32_dpp v232, v42 row_ror:8 row_mask:0xf bank_mask:0xf
	v_mov_b32_dpp v233, v43 row_ror:8 row_mask:0xf bank_mask:0xf
	v_mov_b32_dpp v234, v44 row_ror:8 row_mask:0xf bank_mask:0xf
	v_mov_b32_dpp v235, v45 row_ror:8 row_mask:0xf bank_mask:0xf
	v_cndmask_b32_e64 v232, v232, v46, s[90:91]
	v_cndmask_b32_e64 v233, v233, v47, s[90:91]
	v_cndmask_b32_e64 v234, v234, v48, s[90:91]
	v_cndmask_b32_e64 v235, v235, v49, s[90:91]
	v_pk_add_f32 v[232:233], v[232:233], v[216:217]
	v_pk_add_f32 v[234:235], v[234:235], v[218:219]
	s_nop 0
	global_store_dwordx4 v244, v[232:235], s[44:45]
	v_cvt_pk_bf16_f32 v240, v232, v233
	v_cvt_pk_bf16_f32 v241, v234, v235
	v_pk_mul_f32 v[236:237], v[232:233], v[232:233]
	v_pk_mul_f32 v[238:239], v[234:235], v[234:235]
	global_store_dwordx2 v245, v[240:241], s[48:49]
	v_add_f32_e32 v242, v236, v237
	v_add_f32_e32 v242, v242, v238
	v_add_f32_e32 v242, v242, v239
	v_mov_b32_dpp v232, v46 row_ror:8 row_mask:0xf bank_mask:0xf
	v_mov_b32_dpp v233, v47 row_ror:8 row_mask:0xf bank_mask:0xf
	v_mov_b32_dpp v234, v48 row_ror:8 row_mask:0xf bank_mask:0xf
	v_mov_b32_dpp v235, v49 row_ror:8 row_mask:0xf bank_mask:0xf
	v_cndmask_b32_e64 v232, v42, v232, s[90:91]
	v_cndmask_b32_e64 v233, v43, v233, s[90:91]
	v_cndmask_b32_e64 v234, v44, v234, s[90:91]
	v_cndmask_b32_e64 v235, v45, v235, s[90:91]
	v_pk_add_f32 v[232:233], v[232:233], v[224:225]
	v_pk_add_f32 v[234:235], v[234:235], v[226:227]
	s_nop 0
	global_store_dwordx4 v244, v[232:235], s[46:47]
	v_cvt_pk_bf16_f32 v240, v232, v233
	v_cvt_pk_bf16_f32 v241, v234, v235
	v_pk_mul_f32 v[236:237], v[232:233], v[232:233]
	v_pk_mul_f32 v[238:239], v[234:235], v[234:235]
	global_store_dwordx2 v245, v[240:241], s[50:51]
	v_add_f32_e32 v191, v236, v237
	v_add_f32_e32 v191, v191, v238
	v_add_f32_e32 v191, v191, v239
	v_mov_b32_dpp v232, v34 row_ror:8 row_mask:0xf bank_mask:0xf
	v_mov_b32_dpp v233, v35 row_ror:8 row_mask:0xf bank_mask:0xf
	v_mov_b32_dpp v234, v36 row_ror:8 row_mask:0xf bank_mask:0xf
	v_mov_b32_dpp v235, v37 row_ror:8 row_mask:0xf bank_mask:0xf
	v_cndmask_b32_e64 v232, v232, v124, s[90:91]
	v_cndmask_b32_e64 v233, v233, v125, s[90:91]
	v_cndmask_b32_e64 v234, v234, v126, s[90:91]
	v_cndmask_b32_e64 v235, v235, v127, s[90:91]
	v_pk_add_f32 v[232:233], v[232:233], v[220:221]
	v_pk_add_f32 v[234:235], v[234:235], v[222:223]
	s_nop 0
	global_store_dwordx4 v244, v[232:235], s[44:45] offset:128
	v_cvt_pk_bf16_f32 v240, v232, v233
	v_cvt_pk_bf16_f32 v241, v234, v235
	v_pk_mul_f32 v[236:237], v[232:233], v[232:233]
	v_pk_mul_f32 v[238:239], v[234:235], v[234:235]
	global_store_dwordx2 v245, v[240:241], s[48:49] offset:64
	v_add_f32_e32 v242, v242, v236
	v_add_f32_e32 v242, v242, v237
	v_add_f32_e32 v242, v242, v238
	v_add_f32_e32 v242, v242, v239
	v_mov_b32_dpp v232, v124 row_ror:8 row_mask:0xf bank_mask:0xf
	v_mov_b32_dpp v233, v125 row_ror:8 row_mask:0xf bank_mask:0xf
	v_mov_b32_dpp v234, v126 row_ror:8 row_mask:0xf bank_mask:0xf
	v_mov_b32_dpp v235, v127 row_ror:8 row_mask:0xf bank_mask:0xf
	v_cndmask_b32_e64 v232, v34, v232, s[90:91]
	v_cndmask_b32_e64 v233, v35, v233, s[90:91]
	v_cndmask_b32_e64 v234, v36, v234, s[90:91]
	v_cndmask_b32_e64 v235, v37, v235, s[90:91]
	v_pk_add_f32 v[232:233], v[232:233], v[228:229]
	v_pk_add_f32 v[234:235], v[234:235], v[230:231]
	s_nop 0
	global_store_dwordx4 v244, v[232:235], s[46:47] offset:128
	v_cvt_pk_bf16_f32 v240, v232, v233
	v_cvt_pk_bf16_f32 v241, v234, v235
	v_pk_mul_f32 v[236:237], v[232:233], v[232:233]
	v_pk_mul_f32 v[238:239], v[234:235], v[234:235]
	global_store_dwordx2 v245, v[240:241], s[50:51] offset:64
	v_add_f32_e32 v191, v191, v236
	v_add_f32_e32 v191, v191, v237
	v_add_f32_e32 v191, v191, v238
	v_add_f32_e32 v191, v191, v239
	s_nop 1
	v_add_f32_dpp v242, v242, v242 row_ror:8 row_mask:0xf bank_mask:0xf
	v_add_f32_dpp v191, v191, v191 row_ror:8 row_mask:0xf bank_mask:0xf
	s_add_u32 s44, s44, 0x10000
	s_addc_u32 s45, s45, 0
	s_add_u32 s46, s46, 0x10000
	s_addc_u32 s47, s47, 0
	s_add_u32 s48, s48, 0x8000
	s_addc_u32 s49, s49, 0
	s_add_u32 s50, s50, 0x8000
	s_addc_u32 s51, s51, 0
	v_cndmask_b32_e64 v242, v191, v242, s[90:91]
	ds_bpermute_b32 v243, v189, v242
	global_load_dwordx4 v[216:219], v244, s[40:41]
	global_load_dwordx4 v[220:223], v244, s[40:41] offset:128
	global_load_dwordx4 v[224:227], v244, s[42:43]
	global_load_dwordx4 v[228:231], v244, s[42:43] offset:128
	s_add_u32 s40, s40, 0x10000
	s_addc_u32 s41, s41, 0
	s_add_u32 s42, s42, 0x10000
	s_addc_u32 s43, s43, 0
	s_waitcnt lgkmcnt(0)
	v_add_f32_e32 v242, v242, v243
	ds_bpermute_b32 v243, v190, v242
	s_waitcnt lgkmcnt(0)
	v_add_f32_e32 v242, v242, v243
	s_and_saveexec_b64 s[2:3], s[88:89]
	ds_write_b32 v188, v242 offset:320
	s_or_b64 exec, exec, s[2:3]
	s_waitcnt vmcnt(12)
; DI void gemm8_epi_resid(f32x4 (&acc)[8][4], int m0, int n0, int ntile8, bf16_t* L, const float* xin, float* out, bf16_t* xb, float* rowpart) {
;     ...
; #pragma unroll
;   for (int i = 0; i < 8; ++i) {
;     const int ml = wm * 128 + i * 16 + (lane & 15);
;     const size_t rowoff = (size_t)(m0 + ml) * DM;
;     float ss = 0.f;
; #pragma unroll
;     for (int j = 0; j < 4; ++j) {
;       const int n = n0 + wn * 64 + j * 16 + (lane >> 4) * 4;
;       const float4 xv = *(const float4*)(xin + rowoff + n);
;       const float o0 = xv.x + acc[i][j][0], o1 = xv.y + acc[i][j][1], o2 = xv.z + acc[i][j][2], o3 = xv.w + acc[i][j][3];
;       *(float4*)(out + rowoff + n) = make_float4(o0, o1, o2, o3);
;       ss += o0 * o0 + o1 * o1 + o2 * o2 + o3 * o3;
;       uint2 u;
;       u.x = pack2(o0, o1);
;       u.y = pack2(o2, o3);
;       *(uint2*)(xb + rowoff + n) = u;
;     }
;     ss += shx(ss, 16, lane);
;     ss += shx(ss, 32, lane);
;     if ((lane >> 4) == 0) red[wn * 256 + ml] = ss;
;   }
	v_mov_b32_dpp v232, v26 row_ror:8 row_mask:0xf bank_mask:0xf
	v_mov_b32_dpp v233, v27 row_ror:8 row_mask:0xf bank_mask:0xf
	v_mov_b32_dpp v234, v28 row_ror:8 row_mask:0xf bank_mask:0xf
	v_mov_b32_dpp v235, v29 row_ror:8 row_mask:0xf bank_mask:0xf
	v_cndmask_b32_e64 v232, v232, v30, s[90:91]
	v_cndmask_b32_e64 v233, v233, v31, s[90:91]
	v_cndmask_b32_e64 v234, v234, v32, s[90:91]
	v_cndmask_b32_e64 v235, v235, v33, s[90:91]
	v_pk_add_f32 v[232:233], v[232:233], v[192:193]
	v_pk_add_f32 v[234:235], v[234:235], v[194:195]
	s_nop 0
	global_store_dwordx4 v244, v[232:235], s[44:45]
	v_cvt_pk_bf16_f32 v240, v232, v233
	v_cvt_pk_bf16_f32 v241, v234, v235
	v_pk_mul_f32 v[236:237], v[232:233], v[232:233]
	v_pk_mul_f32 v[238:239], v[234:235], v[234:235]
	global_store_dwordx2 v245, v[240:241], s[48:49]
	v_add_f32_e32 v242, v236, v237
	v_add_f32_e32 v242, v242, v238
	v_add_f32_e32 v242, v242, v239
	v_mov_b32_dpp v232, v30 row_ror:8 row_mask:0xf bank_mask:0xf
	v_mov_b32_dpp v233, v31 row_ror:8 row_mask:0xf bank_mask:0xf
	v_mov_b32_dpp v234, v32 row_ror:8 row_mask:0xf bank_mask:0xf
	v_mov_b32_dpp v235, v33 row_ror:8 row_mask:0xf bank_mask:0xf
	v_cndmask_b32_e64 v232, v26, v232, s[90:91]
	v_cndmask_b32_e64 v233, v27, v233, s[90:91]
	v_cndmask_b32_e64 v234, v28, v234, s[90:91]
	v_cndmask_b32_e64 v235, v29, v235, s[90:91]
	v_pk_add_f32 v[232:233], v[232:233], v[202:203]
	v_pk_add_f32 v[234:235], v[234:235], v[204:205]
	s_nop 0
	global_store_dwordx4 v244, v[232:235], s[46:47]
	v_cvt_pk_bf16_f32 v240, v232, v233
	v_cvt_pk_bf16_f32 v241, v234, v235
	v_pk_mul_f32 v[236:237], v[232:233], v[232:233]
	v_pk_mul_f32 v[238:239], v[234:235], v[234:235]
	global_store_dwordx2 v245, v[240:241], s[50:51]
	v_add_f32_e32 v191, v236, v237
	v_add_f32_e32 v191, v191, v238
	v_add_f32_e32 v191, v191, v239
	v_mov_b32_dpp v232, v18 row_ror:8 row_mask:0xf bank_mask:0xf
	v_mov_b32_dpp v233, v19 row_ror:8 row_mask:0xf bank_mask:0xf
	v_mov_b32_dpp v234, v20 row_ror:8 row_mask:0xf bank_mask:0xf
	v_mov_b32_dpp v235, v21 row_ror:8 row_mask:0xf bank_mask:0xf
	v_cndmask_b32_e64 v232, v232, v22, s[90:91]
	v_cndmask_b32_e64 v233, v233, v23, s[90:91]
	v_cndmask_b32_e64 v234, v234, v24, s[90:91]
	v_cndmask_b32_e64 v235, v235, v25, s[90:91]
	v_pk_add_f32 v[232:233], v[232:233], v[198:199]
	v_pk_add_f32 v[234:235], v[234:235], v[200:201]
	s_nop 0
	global_store_dwordx4 v244, v[232:235], s[44:45] offset:128
	v_cvt_pk_bf16_f32 v240, v232, v233
	v_cvt_pk_bf16_f32 v241, v234, v235
	v_pk_mul_f32 v[236:237], v[232:233], v[232:233]
	v_pk_mul_f32 v[238:239], v[234:235], v[234:235]
	global_store_dwordx2 v245, v[240:241], s[48:49] offset:64
	v_add_f32_e32 v242, v242, v236
	v_add_f32_e32 v242, v242, v237
	v_add_f32_e32 v242, v242, v238
	v_add_f32_e32 v242, v242, v239
	v_mov_b32_dpp v232, v22 row_ror:8 row_mask:0xf bank_mask:0xf
	v_mov_b32_dpp v233, v23 row_ror:8 row_mask:0xf bank_mask:0xf
	v_mov_b32_dpp v234, v24 row_ror:8 row_mask:0xf bank_mask:0xf
	v_mov_b32_dpp v235, v25 row_ror:8 row_mask:0xf bank_mask:0xf
	v_cndmask_b32_e64 v232, v18, v232, s[90:91]
	v_cndmask_b32_e64 v233, v19, v233, s[90:91]
	v_cndmask_b32_e64 v234, v20, v234, s[90:91]
	v_cndmask_b32_e64 v235, v21, v235, s[90:91]
	v_pk_add_f32 v[232:233], v[232:233], v[206:207]
	v_pk_add_f32 v[234:235], v[234:235], v[208:209]
	s_nop 0
	global_store_dwordx4 v244, v[232:235], s[46:47] offset:128
	v_cvt_pk_bf16_f32 v240, v232, v233
	v_cvt_pk_bf16_f32 v241, v234, v235
	v_pk_mul_f32 v[236:237], v[232:233], v[232:233]
	v_pk_mul_f32 v[238:239], v[234:235], v[234:235]
	global_store_dwordx2 v245, v[240:241], s[50:51] offset:64
	v_add_f32_e32 v191, v191, v236
	v_add_f32_e32 v191, v191, v237
	v_add_f32_e32 v191, v191, v238
	v_add_f32_e32 v191, v191, v239
	s_nop 1
	v_add_f32_dpp v242, v242, v242 row_ror:8 row_mask:0xf bank_mask:0xf
	v_add_f32_dpp v191, v191, v191 row_ror:8 row_mask:0xf bank_mask:0xf
	s_add_u32 s44, s44, 0x10000
	s_addc_u32 s45, s45, 0
	s_add_u32 s46, s46, 0x10000
	s_addc_u32 s47, s47, 0
	s_add_u32 s48, s48, 0x8000
	s_addc_u32 s49, s49, 0
	s_add_u32 s50, s50, 0x8000
	s_addc_u32 s51, s51, 0
	v_cndmask_b32_e64 v242, v191, v242, s[90:91]
	ds_bpermute_b32 v243, v189, v242
	s_waitcnt lgkmcnt(0)
	v_add_f32_e32 v242, v242, v243
	ds_bpermute_b32 v243, v190, v242
	s_waitcnt lgkmcnt(0)
	v_add_f32_e32 v242, v242, v243
	s_and_saveexec_b64 s[2:3], s[88:89]
	ds_write_b32 v188, v242 offset:384
	s_or_b64 exec, exec, s[2:3]
	s_waitcnt vmcnt(8)
; DI void gemm8_epi_resid(f32x4 (&acc)[8][4], int m0, int n0, int ntile8, bf16_t* L, const float* xin, float* out, bf16_t* xb, float* rowpart) {
;     ...
; #pragma unroll
;   for (int i = 0; i < 8; ++i) {
;     const int ml = wm * 128 + i * 16 + (lane & 15);
;     const size_t rowoff = (size_t)(m0 + ml) * DM;
;     float ss = 0.f;
; #pragma unroll
;     for (int j = 0; j < 4; ++j) {
;       const int n = n0 + wn * 64 + j * 16 + (lane >> 4) * 4;
;       const float4 xv = *(const float4*)(xin + rowoff + n);
;       const float o0 = xv.x + acc[i][j][0], o1 = xv.y + acc[i][j][1], o2 = xv.z + acc[i][j][2], o3 = xv.w + acc[i][j][3];
;       *(float4*)(out + rowoff + n) = make_float4(o0, o1, o2, o3);
;       ss += o0 * o0 + o1 * o1 + o2 * o2 + o3 * o3;
;       uint2 u;
;       u.x = pack2(o0, o1);
;       u.y = pack2(o2, o3);
;       *(uint2*)(xb + rowoff + n) = u;
;     }
;     ss += shx(ss, 16, lane);
;     ss += shx(ss, 32, lane);
;     if ((lane >> 4) == 0) red[wn * 256 + ml] = ss;
;   }
	v_mov_b32_dpp v232, v10 row_ror:8 row_mask:0xf bank_mask:0xf
	v_mov_b32_dpp v233, v11 row_ror:8 row_mask:0xf bank_mask:0xf
	v_mov_b32_dpp v234, v12 row_ror:8 row_mask:0xf bank_mask:0xf
	v_mov_b32_dpp v235, v13 row_ror:8 row_mask:0xf bank_mask:0xf
	v_cndmask_b32_e64 v232, v232, v14, s[90:91]
	v_cndmask_b32_e64 v233, v233, v15, s[90:91]
	v_cndmask_b32_e64 v234, v234, v16, s[90:91]
	v_cndmask_b32_e64 v235, v235, v17, s[90:91]
	v_pk_add_f32 v[232:233], v[232:233], v[216:217]
	v_pk_add_f32 v[234:235], v[234:235], v[218:219]
	s_nop 0
	global_store_dwordx4 v244, v[232:235], s[44:45]
	v_cvt_pk_bf16_f32 v240, v232, v233
	v_cvt_pk_bf16_f32 v241, v234, v235
	v_pk_mul_f32 v[236:237], v[232:233], v[232:233]
	v_pk_mul_f32 v[238:239], v[234:235], v[234:235]
	global_store_dwordx2 v245, v[240:241], s[48:49]
	v_add_f32_e32 v242, v236, v237
	v_add_f32_e32 v242, v242, v238
	v_add_f32_e32 v242, v242, v239
	v_mov_b32_dpp v232, v14 row_ror:8 row_mask:0xf bank_mask:0xf
	v_mov_b32_dpp v233, v15 row_ror:8 row_mask:0xf bank_mask:0xf
	v_mov_b32_dpp v234, v16 row_ror:8 row_mask:0xf bank_mask:0xf
	v_mov_b32_dpp v235, v17 row_ror:8 row_mask:0xf bank_mask:0xf
	v_cndmask_b32_e64 v232, v10, v232, s[90:91]
	v_cndmask_b32_e64 v233, v11, v233, s[90:91]
	v_cndmask_b32_e64 v234, v12, v234, s[90:91]
	v_cndmask_b32_e64 v235, v13, v235, s[90:91]
	v_pk_add_f32 v[232:233], v[232:233], v[224:225]
	v_pk_add_f32 v[234:235], v[234:235], v[226:227]
	s_nop 0
	global_store_dwordx4 v244, v[232:235], s[46:47]
	v_cvt_pk_bf16_f32 v240, v232, v233
	v_cvt_pk_bf16_f32 v241, v234, v235
	v_pk_mul_f32 v[236:237], v[232:233], v[232:233]
	v_pk_mul_f32 v[238:239], v[234:235], v[234:235]
	global_store_dwordx2 v245, v[240:241], s[50:51]
	v_add_f32_e32 v191, v236, v237
	v_add_f32_e32 v191, v191, v238
	v_add_f32_e32 v191, v191, v239
	v_mov_b32_dpp v232, v38 row_ror:8 row_mask:0xf bank_mask:0xf
	v_mov_b32_dpp v233, v39 row_ror:8 row_mask:0xf bank_mask:0xf
	v_mov_b32_dpp v234, v40 row_ror:8 row_mask:0xf bank_mask:0xf
	v_mov_b32_dpp v235, v41 row_ror:8 row_mask:0xf bank_mask:0xf
	v_cndmask_b32_e64 v232, v232, v6, s[90:91]
	v_cndmask_b32_e64 v233, v233, v7, s[90:91]
	v_cndmask_b32_e64 v234, v234, v8, s[90:91]
	v_cndmask_b32_e64 v235, v235, v9, s[90:91]
	v_pk_add_f32 v[232:233], v[232:233], v[220:221]
	v_pk_add_f32 v[234:235], v[234:235], v[222:223]
	s_nop 0
	global_store_dwordx4 v244, v[232:235], s[44:45] offset:128
	v_cvt_pk_bf16_f32 v240, v232, v233
	v_cvt_pk_bf16_f32 v241, v234, v235
	v_pk_mul_f32 v[236:237], v[232:233], v[232:233]
	v_pk_mul_f32 v[238:239], v[234:235], v[234:235]
	global_store_dwordx2 v245, v[240:241], s[48:49] offset:64
	v_add_f32_e32 v242, v242, v236
	v_add_f32_e32 v242, v242, v237
	v_add_f32_e32 v242, v242, v238
	v_add_f32_e32 v242, v242, v239
	v_mov_b32_dpp v232, v6 row_ror:8 row_mask:0xf bank_mask:0xf
	v_mov_b32_dpp v233, v7 row_ror:8 row_mask:0xf bank_mask:0xf
	v_mov_b32_dpp v234, v8 row_ror:8 row_mask:0xf bank_mask:0xf
	v_mov_b32_dpp v235, v9 row_ror:8 row_mask:0xf bank_mask:0xf
	v_cndmask_b32_e64 v232, v38, v232, s[90:91]
	v_cndmask_b32_e64 v233, v39, v233, s[90:91]
	v_cndmask_b32_e64 v234, v40, v234, s[90:91]
	v_cndmask_b32_e64 v235, v41, v235, s[90:91]
	v_pk_add_f32 v[232:233], v[232:233], v[228:229]
	v_pk_add_f32 v[234:235], v[234:235], v[230:231]
	s_nop 0
	global_store_dwordx4 v244, v[232:235], s[46:47] offset:128
	v_cvt_pk_bf16_f32 v240, v232, v233
	v_cvt_pk_bf16_f32 v241, v234, v235
	v_pk_mul_f32 v[236:237], v[232:233], v[232:233]
	v_pk_mul_f32 v[238:239], v[234:235], v[234:235]
	global_store_dwordx2 v245, v[240:241], s[50:51] offset:64
	v_add_f32_e32 v191, v191, v236
	v_add_f32_e32 v191, v191, v237
	v_add_f32_e32 v191, v191, v238
	v_add_f32_e32 v191, v191, v239
	s_nop 1
	v_add_f32_dpp v242, v242, v242 row_ror:8 row_mask:0xf bank_mask:0xf
	v_add_f32_dpp v191, v191, v191 row_ror:8 row_mask:0xf bank_mask:0xf
	s_add_u32 s44, s44, 0x10000
	s_addc_u32 s45, s45, 0
	s_add_u32 s46, s46, 0x10000
	s_addc_u32 s47, s47, 0
	s_add_u32 s48, s48, 0x8000
	s_addc_u32 s49, s49, 0
	s_add_u32 s50, s50, 0x8000
	s_addc_u32 s51, s51, 0
	v_cndmask_b32_e64 v242, v191, v242, s[90:91]
	ds_bpermute_b32 v243, v189, v242
	s_waitcnt lgkmcnt(0)
	v_add_f32_e32 v242, v242, v243
	ds_bpermute_b32 v243, v190, v242
	s_waitcnt lgkmcnt(0)
	v_add_f32_e32 v242, v242, v243
	s_and_saveexec_b64 s[2:3], s[88:89]
	ds_write_b32 v188, v242 offset:448
	s_or_b64 exec, exec, s[2:3]
	s_branch .LBB0_936

; DI f32x4 mfma16(bf16x8 a, bf16x8 b, f32x4 c) { return __builtin_amdgcn_mfma_f32_16x16x32_bf16(a, b, c, 0, 0, 0); }
; #pragma unroll
;   for (int ks = KS0; ks < KS1; ++ks) {
;     bf16x8 af[8], bfr[4];
; #pragma unroll
;     for (int i = 0; i < 8; ++i) {
;       const int r = wm * 128 + i * 16 + (lane & 15);
;       af[i] = *(const bf16x8*)(S + r * 64 + (((ks * 4 + (lane >> 4)) ^ ((r >> 1) & 7)) << 3));
;     }
; #pragma unroll
;     for (int j = 0; j < 4; ++j) {
;       const int r = wn * 64 + j * 16 + (lane & 15);
;       bfr[j] = *(const bf16x8*)(S + 16384 + r * 64 + (((ks * 4 + (lane >> 4)) ^ ((r >> 1) & 7)) << 3));
;     }
;     __builtin_amdgcn_s_setprio(1);
; #pragma unroll
;     for (int i = 0; i < 8; ++i)
; #pragma unroll
;       for (int j = 0; j < 4; ++j) acc[i][j] = mfma16(bfr[j], af[i], acc[i][j]);
;     __builtin_amdgcn_s_setprio(0);
;   }
; DI void gemm8_accum(f32x4 (&acc)[8][4], const bf16_t* a, size_t lda, const bf16_t* b, size_t ldb, int nkb, bf16_t* L,
;                     const bool pre, const bf16_t* an, size_t ldan, const bf16_t* bn, size_t ldbn) {
;     ...
;   if (!pre) {
;     g8_load1o(ra, a, offa);
;     g8_load1o(rb, b, offb);
;     __syncthreads();
;     g8_store(L, ra, rb, lrow, lch);
;   }
;   g8_load1o(ra, a + 64, offa);
;   g8_load1o(rb, b + 64, offb);
;   for (int kb = 0; kb + 2 < nkb; ++kb) {
;     __syncthreads();
;     g8_store1(L + ((kb + 1) & 1) * 32768, ra, lrow, lch);
;     g8_load1o(ra, a + (kb + 2) * 64, offa);
;     __builtin_amdgcn_sched_barrier(0);
;     g8_compute<0, 1>(acc, L + (kb & 1) * 32768, wm, wn, lane);
;     __builtin_amdgcn_sched_barrier(0);
;     g8_store1(L + ((kb + 1) & 1) * 32768 + 16384, rb, lrow, lch);
;     g8_load1o(rb, b + (kb + 2) * 64, offb);
;     __builtin_amdgcn_sched_barrier(0);
;     g8_compute<1, 2>(acc, L + (kb & 1) * 32768, wm, wn, lane);
.LBB0_1002:
	v_lshlrev_b64 v[20:21], 1, v[4:5]
	v_lshlrev_b64 v[26:27], 1, v[2:3]
	v_lshlrev_b64 v[30:31], 1, v[0:1]
	global_load_dwordx4 v[12:15], v[36:37], off offset:128
	v_lshl_add_u64 v[44:45], s[6:7], 0, v[20:21]
	v_lshl_add_u64 v[46:47], s[6:7], 0, v[26:27]
	v_lshl_add_u64 v[48:49], s[6:7], 0, v[30:31]
	global_load_dwordx4 v[16:19], v[44:45], off offset:128
	global_load_dwordx4 v[2:5], v[46:47], off offset:128
	global_load_dwordx4 v[56:59], v[48:49], off offset:128
	global_load_dwordx4 v[6:9], v[34:35], off offset:128
	s_lshl_b32 s13, s2, 8
	s_lshl_b32 s0, s13, 11
	s_add_u32 s2, s18, s0
	s_addc_u32 s3, s19, 0
	s_lshl_b32 s0, s12, 11
	v_readlane_b32 s24, v251, 57
	v_readlane_b32 s25, v251, 58
	s_add_u32 s0, s24, s0
	s_addc_u32 s1, s25, 0
	v_lshl_add_u64 v[38:39], s[4:5], 0, v[20:21]
	v_bfe_u32 v0, v55, 4, 2
	v_lshrrev_b32_e32 v20, 1, v55
	v_bfe_u32 v21, v55, 1, 3
	v_lshlrev_b32_e32 v161, 1, v11
	s_add_i32 s7, 0, 0x10000
	v_lshlrev_b32_e32 v163, 1, v10
	v_lshl_add_u64 v[40:41], s[4:5], 0, v[26:27]
	v_lshl_add_u64 v[42:43], s[4:5], 0, v[30:31]
	v_bitop3_b32 v60, v20, v0, 7 bitop3:0x6c
	v_lshlrev_b32_e32 v20, 5, v55
	v_bitop3_b32 v160, v0, v21, 4 bitop3:0x36
	v_add3_u32 v0, s7, v161, v163
	global_load_dwordx4 v[22:25], v[38:39], off offset:128
	global_load_dwordx4 v[26:29], v[40:41], off offset:128
	global_load_dwordx4 v[30:33], v[42:43], off offset:128
	v_and_b32_e32 v20, 0x7fffe000, v20
	v_lshlrev_b32_e32 v61, 6, v55
	s_movk_i32 s4, 0x3c0
	s_waitcnt lgkmcnt(0)
	s_barrier
	v_and_or_b32 v61, v61, s4, v20
	s_waitcnt vmcnt(7)
	ds_write_b128 v0, v[12:15]
	s_waitcnt vmcnt(6)
	ds_write_b128 v0, v[16:19] offset:8192
	s_waitcnt vmcnt(5)
	ds_write_b128 v0, v[2:5] offset:16384
	s_waitcnt vmcnt(4)
	ds_write_b128 v0, v[56:59] offset:24576
	global_load_dwordx4 v[2:5], v[36:37], off offset:256
	global_load_dwordx4 v[10:13], v[44:45], off offset:256
	global_load_dwordx4 v[14:17], v[46:47], off offset:256
	global_load_dwordx4 v[18:21], v[48:49], off offset:256
	v_lshlrev_b32_e32 v238, 4, v60
	v_add_u32_e32 v88, 0, v238
	v_lshlrev_b32_e32 v239, 1, v61
	v_add_u32_e32 v240, v88, v239
	ds_read_b128 v[56:59], v240
	ds_read_b128 v[60:63], v240 offset:2048
	ds_read_b128 v[64:67], v240 offset:4096
	ds_read_b128 v[68:71], v240 offset:6144
	ds_read_b128 v[72:75], v240 offset:8192
	ds_read_b128 v[76:79], v240 offset:10240
	ds_read_b128 v[80:83], v240 offset:12288
	ds_read_b128 v[84:87], v240 offset:14336
	v_lshlrev_b32_e32 v55, 7, v55
	v_and_b32_e32 v55, 0x6780, v55
	v_add_u32_e32 v241, v88, v55
	ds_read_b128 v[88:91], v241 offset:32768
	ds_read_b128 v[92:95], v241 offset:34816
	ds_read_b128 v[96:99], v241 offset:36864
	ds_read_b128 v[100:103], v241 offset:38912
	s_waitcnt lgkmcnt(3)
	v_mfma_f32_16x16x32_bf16 v[104:107], v[88:91], v[56:59], 0
	s_waitcnt lgkmcnt(2)
	v_mfma_f32_16x16x32_bf16 v[108:111], v[92:95], v[56:59], 0
	s_waitcnt lgkmcnt(1)
	v_mfma_f32_16x16x32_bf16 v[112:115], v[96:99], v[56:59], 0
	s_waitcnt lgkmcnt(0)
	v_mfma_f32_16x16x32_bf16 v[56:59], v[100:103], v[56:59], 0
	v_mfma_f32_16x16x32_bf16 v[116:119], v[88:91], v[60:63], 0
	v_mfma_f32_16x16x32_bf16 v[120:123], v[92:95], v[60:63], 0
	v_mfma_f32_16x16x32_bf16 v[124:127], v[96:99], v[60:63], 0
	v_mfma_f32_16x16x32_bf16 v[60:63], v[100:103], v[60:63], 0
	v_mfma_f32_16x16x32_bf16 v[128:131], v[88:91], v[64:67], 0
	v_mfma_f32_16x16x32_bf16 v[132:135], v[92:95], v[64:67], 0
	v_mfma_f32_16x16x32_bf16 v[136:139], v[96:99], v[64:67], 0
	v_mfma_f32_16x16x32_bf16 v[64:67], v[100:103], v[64:67], 0
	v_mfma_f32_16x16x32_bf16 v[140:143], v[88:91], v[68:71], 0
	v_mfma_f32_16x16x32_bf16 v[144:147], v[92:95], v[68:71], 0
	v_mfma_f32_16x16x32_bf16 v[148:151], v[96:99], v[68:71], 0
	v_mfma_f32_16x16x32_bf16 v[68:71], v[100:103], v[68:71], 0
	v_mfma_f32_16x16x32_bf16 v[152:155], v[88:91], v[72:75], 0
	v_mfma_f32_16x16x32_bf16 v[156:159], v[92:95], v[72:75], 0
	v_mfma_f32_16x16x32_bf16 v[164:167], v[96:99], v[72:75], 0
	v_mfma_f32_16x16x32_bf16 v[72:75], v[100:103], v[72:75], 0
	v_mfma_f32_16x16x32_bf16 v[168:171], v[88:91], v[76:79], 0
	v_mfma_f32_16x16x32_bf16 v[172:175], v[92:95], v[76:79], 0
	v_mfma_f32_16x16x32_bf16 v[176:179], v[96:99], v[76:79], 0
	v_mfma_f32_16x16x32_bf16 v[76:79], v[100:103], v[76:79], 0
	v_mfma_f32_16x16x32_bf16 v[180:183], v[88:91], v[80:83], 0
	v_mfma_f32_16x16x32_bf16 v[184:187], v[92:95], v[80:83], 0
	v_mfma_f32_16x16x32_bf16 v[188:191], v[96:99], v[80:83], 0
	v_mfma_f32_16x16x32_bf16 v[80:83], v[100:103], v[80:83], 0
	v_mfma_f32_16x16x32_bf16 v[88:91], v[88:91], v[84:87], 0
	v_mfma_f32_16x16x32_bf16 v[92:95], v[92:95], v[84:87], 0
	v_mfma_f32_16x16x32_bf16 v[96:99], v[96:99], v[84:87], 0
	v_mfma_f32_16x16x32_bf16 v[84:87], v[100:103], v[84:87], 0
	v_readlane_b32 s4, v254, 36
	s_nop 1
	v_add3_u32 v242, s4, v161, v163
	s_waitcnt vmcnt(7)
	ds_write_b128 v242, v[6:9]
	s_waitcnt vmcnt(6)
	ds_write_b128 v242, v[22:25] offset:8192
	s_waitcnt vmcnt(5)
	ds_write_b128 v242, v[26:29] offset:16384
	s_waitcnt vmcnt(4)
	ds_write_b128 v242, v[30:33] offset:24576
	global_load_dwordx4 v[6:9], v[34:35], off offset:256
	global_load_dwordx4 v[22:25], v[38:39], off offset:256
	global_load_dwordx4 v[26:29], v[40:41], off offset:256
	global_load_dwordx4 v[30:33], v[42:43], off offset:256
	v_lshlrev_b32_e32 v160, 4, v160
	v_add_u32_e32 v222, 0, v160
	v_add_u32_e32 v243, v222, v239
	ds_read_b128 v[100:103], v243
	ds_read_b128 v[192:195], v243 offset:2048
	ds_read_b128 v[198:201], v243 offset:4096
	ds_read_b128 v[202:205], v243 offset:6144
	ds_read_b128 v[206:209], v243 offset:8192
	ds_read_b128 v[210:213], v243 offset:10240
	ds_read_b128 v[214:217], v243 offset:12288
	ds_read_b128 v[218:221], v243 offset:14336
	v_add_u32_e32 v244, v222, v55
	ds_read_b128 v[222:225], v244 offset:32768
	ds_read_b128 v[226:229], v244 offset:34816
	ds_read_b128 v[230:233], v244 offset:36864
	ds_read_b128 v[234:237], v244 offset:38912
	s_waitcnt lgkmcnt(0)
; DI f32x4 mfma16(bf16x8 a, bf16x8 b, f32x4 c) { return __builtin_amdgcn_mfma_f32_16x16x32_bf16(a, b, c, 0, 0, 0); }
; #pragma unroll
;   for (int ks = KS0; ks < KS1; ++ks) {
;     bf16x8 af[8], bfr[4];
; #pragma unroll
;     for (int i = 0; i < 8; ++i) {
;       const int r = wm * 128 + i * 16 + (lane & 15);
;       af[i] = *(const bf16x8*)(S + r * 64 + (((ks * 4 + (lane >> 4)) ^ ((r >> 1) & 7)) << 3));
;     }
; #pragma unroll
;     for (int j = 0; j < 4; ++j) {
;       const int r = wn * 64 + j * 16 + (lane & 15);
;       bfr[j] = *(const bf16x8*)(S + 16384 + r * 64 + (((ks * 4 + (lane >> 4)) ^ ((r >> 1) & 7)) << 3));
;     }
;     __builtin_amdgcn_s_setprio(1);
; #pragma unroll
;     for (int i = 0; i < 8; ++i)
; #pragma unroll
;       for (int j = 0; j < 4; ++j) acc[i][j] = mfma16(bfr[j], af[i], acc[i][j]);
;     __builtin_amdgcn_s_setprio(0);
;   }
; DI void gemm8_accum(f32x4 (&acc)[8][4], const bf16_t* a, size_t lda, const bf16_t* b, size_t ldb, int nkb, bf16_t* L,
;                     const bool pre, const bf16_t* an, size_t ldan, const bf16_t* bn, size_t ldbn) {
;     ...
;   for (int kb = 0; kb + 2 < nkb; ++kb) {
;     __syncthreads();
;     g8_store1(L + ((kb + 1) & 1) * 32768, ra, lrow, lch);
;     g8_load1o(ra, a + (kb + 2) * 64, offa);
;     __builtin_amdgcn_sched_barrier(0);
;     g8_compute<0, 1>(acc, L + (kb & 1) * 32768, wm, wn, lane);
;     __builtin_amdgcn_sched_barrier(0);
;     g8_store1(L + ((kb + 1) & 1) * 32768 + 16384, rb, lrow, lch);
;     g8_load1o(rb, b + (kb + 2) * 64, offb);
;     __builtin_amdgcn_sched_barrier(0);
;     g8_compute<1, 2>(acc, L + (kb & 1) * 32768, wm, wn, lane);
	v_mfma_f32_16x16x32_bf16 v[56:59], v[234:237], v[100:103], v[56:59]
	v_mfma_f32_16x16x32_bf16 v[60:63], v[234:237], v[192:195], v[60:63]
	v_mfma_f32_16x16x32_bf16 v[64:67], v[234:237], v[198:201], v[64:67]
	v_mfma_f32_16x16x32_bf16 v[68:71], v[234:237], v[202:205], v[68:71]
	v_mfma_f32_16x16x32_bf16 v[72:75], v[234:237], v[206:209], v[72:75]
	v_mfma_f32_16x16x32_bf16 v[76:79], v[234:237], v[210:213], v[76:79]
	v_mfma_f32_16x16x32_bf16 v[104:107], v[222:225], v[100:103], v[104:107]
	v_mfma_f32_16x16x32_bf16 v[108:111], v[226:229], v[100:103], v[108:111]
	v_mfma_f32_16x16x32_bf16 v[112:115], v[230:233], v[100:103], v[112:115]
	v_mfma_f32_16x16x32_bf16 v[100:103], v[222:225], v[192:195], v[116:119]
	v_mfma_f32_16x16x32_bf16 v[116:119], v[226:229], v[192:195], v[120:123]
	v_mfma_f32_16x16x32_bf16 v[120:123], v[230:233], v[192:195], v[124:127]
	v_mfma_f32_16x16x32_bf16 v[124:127], v[222:225], v[198:201], v[128:131]
	v_mfma_f32_16x16x32_bf16 v[128:131], v[226:229], v[198:201], v[132:135]
	v_mfma_f32_16x16x32_bf16 v[132:135], v[230:233], v[198:201], v[136:139]
	v_mfma_f32_16x16x32_bf16 v[136:139], v[222:225], v[202:205], v[140:143]
	v_mfma_f32_16x16x32_bf16 v[140:143], v[226:229], v[202:205], v[144:147]
	v_mfma_f32_16x16x32_bf16 v[144:147], v[230:233], v[202:205], v[148:151]
	v_mfma_f32_16x16x32_bf16 v[148:151], v[222:225], v[206:209], v[152:155]
	v_mfma_f32_16x16x32_bf16 v[152:155], v[226:229], v[206:209], v[156:159]
	v_mfma_f32_16x16x32_bf16 v[156:159], v[230:233], v[206:209], v[164:167]
	v_mfma_f32_16x16x32_bf16 v[164:167], v[222:225], v[210:213], v[168:171]
	v_mfma_f32_16x16x32_bf16 v[168:171], v[226:229], v[210:213], v[172:175]
	v_mfma_f32_16x16x32_bf16 v[172:175], v[230:233], v[210:213], v[176:179]
	v_mfma_f32_16x16x32_bf16 v[176:179], v[222:225], v[214:217], v[180:183]
	v_mfma_f32_16x16x32_bf16 v[180:183], v[226:229], v[214:217], v[184:187]
	v_mfma_f32_16x16x32_bf16 v[184:187], v[230:233], v[214:217], v[188:191]
	v_mfma_f32_16x16x32_bf16 v[80:83], v[234:237], v[214:217], v[80:83]
	v_mfma_f32_16x16x32_bf16 v[88:91], v[222:225], v[218:221], v[88:91]
	v_mfma_f32_16x16x32_bf16 v[92:95], v[226:229], v[218:221], v[92:95]
	v_mfma_f32_16x16x32_bf16 v[96:99], v[230:233], v[218:221], v[96:99]
	v_mfma_f32_16x16x32_bf16 v[84:87], v[234:237], v[218:221], v[84:87]
	v_add3_u32 v163, 0, v161, v163
	s_barrier
	s_waitcnt vmcnt(7)
	ds_write_b128 v163, v[2:5]
	s_waitcnt vmcnt(6)
	ds_write_b128 v163, v[10:13] offset:8192
	s_waitcnt vmcnt(5)
	ds_write_b128 v163, v[14:17] offset:16384
	s_waitcnt vmcnt(4)
	ds_write_b128 v163, v[18:21] offset:24576
	global_load_dwordx4 v[2:5], v[36:37], off offset:384
	global_load_dwordx4 v[10:13], v[44:45], off offset:384
	global_load_dwordx4 v[14:17], v[46:47], off offset:384
	global_load_dwordx4 v[18:21], v[48:49], off offset:384
	v_add3_u32 v234, s7, v238, v239
	ds_read_b128 v[44:47], v234
	ds_read_b128 v[188:191], v234 offset:2048
	ds_read_b128 v[192:195], v234 offset:4096
	ds_read_b128 v[198:201], v234 offset:6144
	ds_read_b128 v[202:205], v234 offset:8192
	ds_read_b128 v[206:209], v234 offset:10240
	ds_read_b128 v[210:213], v234 offset:12288
	ds_read_b128 v[214:217], v234 offset:14336
	v_add3_u32 v235, s4, v238, v55
	ds_read_b128 v[218:221], v235
	ds_read_b128 v[222:225], v235 offset:2048
	ds_read_b128 v[226:229], v235 offset:4096
	ds_read_b128 v[230:233], v235 offset:6144
	s_waitcnt lgkmcnt(3)
	v_mfma_f32_16x16x32_bf16 v[104:107], v[218:221], v[44:47], v[104:107]
	s_waitcnt lgkmcnt(2)
	v_mfma_f32_16x16x32_bf16 v[108:111], v[222:225], v[44:47], v[108:111]
	s_waitcnt lgkmcnt(1)
	v_mfma_f32_16x16x32_bf16 v[112:115], v[226:229], v[44:47], v[112:115]
	s_waitcnt lgkmcnt(0)
	v_mfma_f32_16x16x32_bf16 v[44:47], v[230:233], v[44:47], v[56:59]
	v_mfma_f32_16x16x32_bf16 v[56:59], v[218:221], v[188:191], v[100:103]
	v_mfma_f32_16x16x32_bf16 v[60:63], v[230:233], v[188:191], v[60:63]
	v_mfma_f32_16x16x32_bf16 v[64:67], v[230:233], v[192:195], v[64:67]
	v_mfma_f32_16x16x32_bf16 v[68:71], v[230:233], v[198:201], v[68:71]
	v_mfma_f32_16x16x32_bf16 v[72:75], v[230:233], v[202:205], v[72:75]
	v_mfma_f32_16x16x32_bf16 v[76:79], v[230:233], v[206:209], v[76:79]
	v_mfma_f32_16x16x32_bf16 v[100:103], v[222:225], v[188:191], v[116:119]
	v_mfma_f32_16x16x32_bf16 v[116:119], v[226:229], v[188:191], v[120:123]
	v_mfma_f32_16x16x32_bf16 v[120:123], v[218:221], v[192:195], v[124:127]
	v_mfma_f32_16x16x32_bf16 v[124:127], v[222:225], v[192:195], v[128:131]
	v_mfma_f32_16x16x32_bf16 v[128:131], v[226:229], v[192:195], v[132:135]
	v_mfma_f32_16x16x32_bf16 v[132:135], v[218:221], v[198:201], v[136:139]
	v_mfma_f32_16x16x32_bf16 v[136:139], v[222:225], v[198:201], v[140:143]
	v_mfma_f32_16x16x32_bf16 v[140:143], v[226:229], v[198:201], v[144:147]
	v_mfma_f32_16x16x32_bf16 v[144:147], v[218:221], v[202:205], v[148:151]
	v_mfma_f32_16x16x32_bf16 v[148:151], v[222:225], v[202:205], v[152:155]
	v_mfma_f32_16x16x32_bf16 v[152:155], v[226:229], v[202:205], v[156:159]
	v_mfma_f32_16x16x32_bf16 v[156:159], v[218:221], v[206:209], v[164:167]
	v_mfma_f32_16x16x32_bf16 v[164:167], v[222:225], v[206:209], v[168:171]
	v_mfma_f32_16x16x32_bf16 v[168:171], v[226:229], v[206:209], v[172:175]
	v_mfma_f32_16x16x32_bf16 v[172:175], v[218:221], v[210:213], v[176:179]
	v_mfma_f32_16x16x32_bf16 v[176:179], v[222:225], v[210:213], v[180:183]
	v_mfma_f32_16x16x32_bf16 v[180:183], v[226:229], v[210:213], v[184:187]
	v_mfma_f32_16x16x32_bf16 v[80:83], v[230:233], v[210:213], v[80:83]
	v_mfma_f32_16x16x32_bf16 v[88:91], v[218:221], v[214:217], v[88:91]
	v_mfma_f32_16x16x32_bf16 v[92:95], v[222:225], v[214:217], v[92:95]
	v_mfma_f32_16x16x32_bf16 v[96:99], v[226:229], v[214:217], v[96:99]
	v_mfma_f32_16x16x32_bf16 v[84:87], v[230:233], v[214:217], v[84:87]
	s_waitcnt vmcnt(7)
; DI void gemm8_accum(f32x4 (&acc)[8][4], const bf16_t* a, size_t lda, const bf16_t* b, size_t ldb, int nkb, bf16_t* L,
;                     const bool pre, const bf16_t* an, size_t ldan, const bf16_t* bn, size_t ldbn) {
;     ...
;   for (int kb = 0; kb + 2 < nkb; ++kb) {
;     __syncthreads();
;     g8_store1(L + ((kb + 1) & 1) * 32768, ra, lrow, lch);
;     g8_load1o(ra, a + (kb + 2) * 64, offa);
;     __builtin_amdgcn_sched_barrier(0);
;     g8_compute<0, 1>(acc, L + (kb & 1) * 32768, wm, wn, lane);
;     __builtin_amdgcn_sched_barrier(0);
;     g8_store1(L + ((kb + 1) & 1) * 32768 + 16384, rb, lrow, lch);
;     g8_load1o(rb, b + (kb + 2) * 64, offb);
;     __builtin_amdgcn_sched_barrier(0);
;     g8_compute<1, 2>(acc, L + (kb & 1) * 32768, wm, wn, lane);
;   }
;   __syncthreads();
;   g8_store1(L + 32768, ra, lrow, lch);
;   g8_load1(ra, an, ldan, 0, lrow, lch);
;   __builtin_amdgcn_sched_barrier(0);
;   g8_compute<0, 1>(acc, L, wm, wn, lane);
;   __builtin_amdgcn_sched_barrier(0);
;   g8_store1(L + 32768 + 16384, rb, lrow, lch);
;   g8_load1(rb, bn, ldbn, 0, lrow, lch);
;   __builtin_amdgcn_sched_barrier(0);
;   g8_compute<1, 2>(acc, L, wm, wn, lane);
	ds_write_b128 v163, v[6:9] offset:32768
	s_waitcnt vmcnt(6)
	ds_write_b128 v163, v[22:25] offset:40960
	s_waitcnt vmcnt(5)
	ds_write_b128 v163, v[26:29] offset:49152
	s_waitcnt vmcnt(4)
	ds_write_b128 v163, v[30:33] offset:57344
	global_load_dwordx4 v[6:9], v[34:35], off offset:384
	global_load_dwordx4 v[22:25], v[38:39], off offset:384
	global_load_dwordx4 v[26:29], v[40:41], off offset:384
	global_load_dwordx4 v[30:33], v[42:43], off offset:384
	v_add3_u32 v226, s7, v160, v239
	ds_read_b128 v[34:37], v226
	ds_read_b128 v[38:41], v226 offset:2048
	ds_read_b128 v[184:187], v226 offset:4096
	ds_read_b128 v[188:191], v226 offset:6144
	ds_read_b128 v[192:195], v226 offset:8192
	ds_read_b128 v[198:201], v226 offset:10240
	ds_read_b128 v[202:205], v226 offset:12288
	ds_read_b128 v[206:209], v226 offset:14336
	v_add3_u32 v227, s4, v160, v55
	ds_read_b128 v[210:213], v227
	ds_read_b128 v[214:217], v227 offset:2048
	ds_read_b128 v[218:221], v227 offset:4096
	ds_read_b128 v[222:225], v227 offset:6144
	s_waitcnt lgkmcnt(3)
	v_mfma_f32_16x16x32_bf16 v[104:107], v[210:213], v[34:37], v[104:107]
	s_waitcnt lgkmcnt(2)
	v_mfma_f32_16x16x32_bf16 v[108:111], v[214:217], v[34:37], v[108:111]
	s_waitcnt lgkmcnt(1)
	v_mfma_f32_16x16x32_bf16 v[112:115], v[218:221], v[34:37], v[112:115]
	s_waitcnt lgkmcnt(0)
	v_mfma_f32_16x16x32_bf16 v[34:37], v[222:225], v[34:37], v[44:47]
	v_mfma_f32_16x16x32_bf16 v[42:45], v[210:213], v[38:41], v[56:59]
	v_mfma_f32_16x16x32_bf16 v[46:49], v[214:217], v[38:41], v[100:103]
	v_mfma_f32_16x16x32_bf16 v[56:59], v[218:221], v[38:41], v[116:119]
	v_mfma_f32_16x16x32_bf16 v[38:41], v[222:225], v[38:41], v[60:63]
	v_mfma_f32_16x16x32_bf16 v[60:63], v[210:213], v[184:187], v[120:123]
	v_mfma_f32_16x16x32_bf16 v[64:67], v[222:225], v[184:187], v[64:67]
	v_mfma_f32_16x16x32_bf16 v[68:71], v[222:225], v[188:191], v[68:71]
	v_mfma_f32_16x16x32_bf16 v[72:75], v[222:225], v[192:195], v[72:75]
	v_mfma_f32_16x16x32_bf16 v[76:79], v[222:225], v[198:201], v[76:79]
	v_mfma_f32_16x16x32_bf16 v[100:103], v[214:217], v[184:187], v[124:127]
	v_mfma_f32_16x16x32_bf16 v[116:119], v[218:221], v[184:187], v[128:131]
	v_mfma_f32_16x16x32_bf16 v[120:123], v[210:213], v[188:191], v[132:135]
	v_mfma_f32_16x16x32_bf16 v[124:127], v[214:217], v[188:191], v[136:139]
	v_mfma_f32_16x16x32_bf16 v[128:131], v[218:221], v[188:191], v[140:143]
	v_mfma_f32_16x16x32_bf16 v[132:135], v[210:213], v[192:195], v[144:147]
	v_mfma_f32_16x16x32_bf16 v[136:139], v[214:217], v[192:195], v[148:151]
	v_mfma_f32_16x16x32_bf16 v[140:143], v[218:221], v[192:195], v[152:155]
	v_mfma_f32_16x16x32_bf16 v[144:147], v[210:213], v[198:201], v[156:159]
	v_mfma_f32_16x16x32_bf16 v[148:151], v[214:217], v[198:201], v[164:167]
	v_mfma_f32_16x16x32_bf16 v[152:155], v[218:221], v[198:201], v[168:171]
	v_mfma_f32_16x16x32_bf16 v[156:159], v[210:213], v[202:205], v[172:175]
	v_mfma_f32_16x16x32_bf16 v[164:167], v[214:217], v[202:205], v[176:179]
	v_mfma_f32_16x16x32_bf16 v[168:171], v[218:221], v[202:205], v[180:183]
	v_mfma_f32_16x16x32_bf16 v[80:83], v[222:225], v[202:205], v[80:83]
	v_mfma_f32_16x16x32_bf16 v[88:91], v[210:213], v[206:209], v[88:91]
	v_mfma_f32_16x16x32_bf16 v[92:95], v[214:217], v[206:209], v[92:95]
	v_mfma_f32_16x16x32_bf16 v[96:99], v[218:221], v[206:209], v[96:99]
	v_mfma_f32_16x16x32_bf16 v[84:87], v[222:225], v[206:209], v[84:87]
	s_barrier
	s_waitcnt vmcnt(7)
	ds_write_b128 v0, v[2:5]
	s_waitcnt vmcnt(6)
	ds_write_b128 v0, v[10:13] offset:8192
	s_waitcnt vmcnt(5)
	ds_write_b128 v0, v[14:17] offset:16384
	s_waitcnt vmcnt(4)
	ds_write_b128 v0, v[18:21] offset:24576
	v_lshl_or_b32 v0, v54, 10, v50
	v_lshlrev_b64 v[160:161], 1, v[0:1]
	v_lshl_or_b32 v0, v53, 10, v50
	v_lshlrev_b64 v[218:219], 1, v[0:1]
	v_lshl_or_b32 v0, v52, 10, v50
	v_lshlrev_b64 v[220:221], 1, v[0:1]
	v_lshl_or_b32 v0, v51, 10, v50
	v_lshlrev_b64 v[222:223], 1, v[0:1]
	v_lshl_add_u64 v[2:3], s[2:3], 0, v[160:161]
	v_lshl_add_u64 v[10:11], s[2:3], 0, v[218:219]
	v_lshl_add_u64 v[14:15], s[2:3], 0, v[220:221]
	v_lshl_add_u64 v[18:19], s[2:3], 0, v[222:223]
	global_load_dwordx4 v[2:5], v[2:3], off
	s_nop 0
	global_load_dwordx4 v[10:13], v[10:11], off
	s_nop 0
	global_load_dwordx4 v[14:17], v[14:15], off
	s_nop 0
	global_load_dwordx4 v[18:21], v[18:19], off
	ds_read_b128 v[50:53], v240
	ds_read_b128 v[172:175], v240 offset:2048
	ds_read_b128 v[176:179], v240 offset:4096
	ds_read_b128 v[180:183], v240 offset:6144
	ds_read_b128 v[184:187], v240 offset:8192
	ds_read_b128 v[188:191], v240 offset:10240
	ds_read_b128 v[192:195], v240 offset:12288
	ds_read_b128 v[198:201], v240 offset:14336
	ds_read_b128 v[202:205], v241 offset:32768
	ds_read_b128 v[206:209], v241 offset:34816
	ds_read_b128 v[210:213], v241 offset:36864
	ds_read_b128 v[214:217], v241 offset:38912
	s_waitcnt lgkmcnt(3)
	v_mfma_f32_16x16x32_bf16 v[104:107], v[202:205], v[50:53], v[104:107]
	s_waitcnt lgkmcnt(2)
	v_mfma_f32_16x16x32_bf16 v[108:111], v[206:209], v[50:53], v[108:111]
	s_waitcnt lgkmcnt(1)
	v_mfma_f32_16x16x32_bf16 v[112:115], v[210:213], v[50:53], v[112:115]
	s_waitcnt lgkmcnt(0)
; DI void gemm8_accum(f32x4 (&acc)[8][4], const bf16_t* a, size_t lda, const bf16_t* b, size_t ldb, int nkb, bf16_t* L,
;                     const bool pre, const bf16_t* an, size_t ldan, const bf16_t* bn, size_t ldbn) {
;     ...
;   g8_store1(L + 32768 + 16384, rb, lrow, lch);
;   g8_load1(rb, bn, ldbn, 0, lrow, lch);
;   __builtin_amdgcn_sched_barrier(0);
;   g8_compute<1, 2>(acc, L, wm, wn, lane);
;   __syncthreads();
;   g8_store1(L, ra, lrow, lch);
;   __builtin_amdgcn_sched_barrier(0);
;   g8_compute<0, 1>(acc, L + 32768, wm, wn, lane);
;   __builtin_amdgcn_sched_barrier(0);
;   g8_store1(L + 16384, rb, lrow, lch);
;   __builtin_amdgcn_sched_barrier(0);
;   g8_compute<1, 2>(acc, L + 32768, wm, wn, lane);
;   __syncthreads();
	v_mfma_f32_16x16x32_bf16 v[34:37], v[214:217], v[50:53], v[34:37]
	v_mfma_f32_16x16x32_bf16 v[42:45], v[202:205], v[172:175], v[42:45]
	v_mfma_f32_16x16x32_bf16 v[46:49], v[206:209], v[172:175], v[46:49]
	v_mfma_f32_16x16x32_bf16 v[50:53], v[210:213], v[172:175], v[56:59]
	v_mfma_f32_16x16x32_bf16 v[38:41], v[214:217], v[172:175], v[38:41]
	v_mfma_f32_16x16x32_bf16 v[54:57], v[202:205], v[176:179], v[60:63]
	v_mfma_f32_16x16x32_bf16 v[58:61], v[206:209], v[176:179], v[100:103]
	v_mfma_f32_16x16x32_bf16 v[62:65], v[214:217], v[176:179], v[64:67]
	v_mfma_f32_16x16x32_bf16 v[66:69], v[214:217], v[180:183], v[68:71]
	v_mfma_f32_16x16x32_bf16 v[70:73], v[214:217], v[184:187], v[72:75]
	v_mfma_f32_16x16x32_bf16 v[74:77], v[214:217], v[188:191], v[76:79]
	v_mfma_f32_16x16x32_bf16 v[100:103], v[210:213], v[176:179], v[116:119]
	v_mfma_f32_16x16x32_bf16 v[116:119], v[202:205], v[180:183], v[120:123]
	v_mfma_f32_16x16x32_bf16 v[120:123], v[206:209], v[180:183], v[124:127]
	v_mfma_f32_16x16x32_bf16 v[124:127], v[210:213], v[180:183], v[128:131]
	v_mfma_f32_16x16x32_bf16 v[128:131], v[202:205], v[184:187], v[132:135]
	v_mfma_f32_16x16x32_bf16 v[132:135], v[206:209], v[184:187], v[136:139]
	v_mfma_f32_16x16x32_bf16 v[136:139], v[210:213], v[184:187], v[140:143]
	v_mfma_f32_16x16x32_bf16 v[140:143], v[202:205], v[188:191], v[144:147]
	v_mfma_f32_16x16x32_bf16 v[144:147], v[206:209], v[188:191], v[148:151]
	v_mfma_f32_16x16x32_bf16 v[148:151], v[210:213], v[188:191], v[152:155]
	v_mfma_f32_16x16x32_bf16 v[152:155], v[202:205], v[192:195], v[156:159]
	v_mfma_f32_16x16x32_bf16 v[156:159], v[206:209], v[192:195], v[164:167]
	v_mfma_f32_16x16x32_bf16 v[164:167], v[210:213], v[192:195], v[168:171]
	v_mfma_f32_16x16x32_bf16 v[78:81], v[214:217], v[192:195], v[80:83]
	v_mfma_f32_16x16x32_bf16 v[88:91], v[202:205], v[198:201], v[88:91]
	v_mfma_f32_16x16x32_bf16 v[92:95], v[206:209], v[198:201], v[92:95]
	v_mfma_f32_16x16x32_bf16 v[96:99], v[210:213], v[198:201], v[96:99]
	v_mfma_f32_16x16x32_bf16 v[82:85], v[214:217], v[198:201], v[84:87]
	s_waitcnt vmcnt(7)
	ds_write_b128 v242, v[6:9]
	s_waitcnt vmcnt(6)
	ds_write_b128 v242, v[22:25] offset:8192
	s_waitcnt vmcnt(5)
	ds_write_b128 v242, v[26:29] offset:16384
	s_waitcnt vmcnt(4)
	ds_write_b128 v242, v[30:33] offset:24576
	v_lshl_add_u64 v[6:7], s[0:1], 0, v[160:161]
	v_lshl_add_u64 v[22:23], s[0:1], 0, v[218:219]
	v_lshl_add_u64 v[26:27], s[0:1], 0, v[220:221]
	v_lshl_add_u64 v[30:31], s[0:1], 0, v[222:223]
	global_load_dwordx4 v[6:9], v[6:7], off
	s_nop 0
	global_load_dwordx4 v[22:25], v[22:23], off
	s_nop 0
	global_load_dwordx4 v[26:29], v[26:27], off
	s_nop 0
	global_load_dwordx4 v[30:33], v[30:31], off
	ds_read_b128 v[168:171], v243
	ds_read_b128 v[172:175], v243 offset:2048
	ds_read_b128 v[176:179], v243 offset:4096
	ds_read_b128 v[180:183], v243 offset:6144
	ds_read_b128 v[184:187], v243 offset:8192
	ds_read_b128 v[188:191], v243 offset:10240
	ds_read_b128 v[192:195], v243 offset:12288
	ds_read_b128 v[198:201], v243 offset:14336
	ds_read_b128 v[202:205], v244 offset:32768
	ds_read_b128 v[206:209], v244 offset:34816
	ds_read_b128 v[210:213], v244 offset:36864
	ds_read_b128 v[214:217], v244 offset:38912
	s_waitcnt lgkmcnt(0)
	v_mfma_f32_16x16x32_bf16 v[34:37], v[214:217], v[168:171], v[34:37]
	v_mfma_f32_16x16x32_bf16 v[42:45], v[202:205], v[172:175], v[42:45]
	v_mfma_f32_16x16x32_bf16 v[46:49], v[206:209], v[172:175], v[46:49]
	v_mfma_f32_16x16x32_bf16 v[50:53], v[210:213], v[172:175], v[50:53]
	v_mfma_f32_16x16x32_bf16 v[38:41], v[214:217], v[172:175], v[38:41]
	v_mfma_f32_16x16x32_bf16 v[54:57], v[202:205], v[176:179], v[54:57]
	v_mfma_f32_16x16x32_bf16 v[58:61], v[206:209], v[176:179], v[58:61]
	v_mfma_f32_16x16x32_bf16 v[62:65], v[214:217], v[176:179], v[62:65]
	v_mfma_f32_16x16x32_bf16 v[66:69], v[214:217], v[180:183], v[66:69]
	v_mfma_f32_16x16x32_bf16 v[70:73], v[214:217], v[184:187], v[70:73]
	v_mfma_f32_16x16x32_bf16 v[74:77], v[214:217], v[188:191], v[74:77]
	v_mfma_f32_16x16x32_bf16 v[104:107], v[202:205], v[168:171], v[104:107]
	v_mfma_f32_16x16x32_bf16 v[108:111], v[206:209], v[168:171], v[108:111]
	v_mfma_f32_16x16x32_bf16 v[112:115], v[210:213], v[168:171], v[112:115]
	v_mfma_f32_16x16x32_bf16 v[100:103], v[210:213], v[176:179], v[100:103]
	v_mfma_f32_16x16x32_bf16 v[116:119], v[202:205], v[180:183], v[116:119]
	v_mfma_f32_16x16x32_bf16 v[120:123], v[206:209], v[180:183], v[120:123]
	v_mfma_f32_16x16x32_bf16 v[124:127], v[210:213], v[180:183], v[124:127]
	v_mfma_f32_16x16x32_bf16 v[128:131], v[202:205], v[184:187], v[128:131]
	v_mfma_f32_16x16x32_bf16 v[132:135], v[206:209], v[184:187], v[132:135]
	v_mfma_f32_16x16x32_bf16 v[136:139], v[210:213], v[184:187], v[136:139]
	v_mfma_f32_16x16x32_bf16 v[140:143], v[202:205], v[188:191], v[140:143]
	v_mfma_f32_16x16x32_bf16 v[144:147], v[206:209], v[188:191], v[144:147]
	v_mfma_f32_16x16x32_bf16 v[148:151], v[210:213], v[188:191], v[148:151]
	v_mfma_f32_16x16x32_bf16 v[152:155], v[202:205], v[192:195], v[152:155]
	v_mfma_f32_16x16x32_bf16 v[156:159], v[206:209], v[192:195], v[156:159]
	v_mfma_f32_16x16x32_bf16 v[164:167], v[210:213], v[192:195], v[164:167]
	v_mfma_f32_16x16x32_bf16 v[78:81], v[214:217], v[192:195], v[78:81]
	v_mfma_f32_16x16x32_bf16 v[86:89], v[202:205], v[198:201], v[88:91]
	v_mfma_f32_16x16x32_bf16 v[90:93], v[206:209], v[198:201], v[92:95]
	v_mfma_f32_16x16x32_bf16 v[94:97], v[210:213], v[198:201], v[96:99]
	v_mfma_f32_16x16x32_bf16 v[82:85], v[214:217], v[198:201], v[82:85]
	s_barrier
; DI void gemm8_accum(f32x4 (&acc)[8][4], const bf16_t* a, size_t lda, const bf16_t* b, size_t ldb, int nkb, bf16_t* L,
;                     const bool pre, const bf16_t* an, size_t ldan, const bf16_t* bn, size_t ldbn) {
;     ...
;   __syncthreads();
;   g8_store1(L, ra, lrow, lch);
;   __builtin_amdgcn_sched_barrier(0);
;   g8_compute<0, 1>(acc, L + 32768, wm, wn, lane);
;   __builtin_amdgcn_sched_barrier(0);
;   g8_store1(L + 16384, rb, lrow, lch);
;   __builtin_amdgcn_sched_barrier(0);
;   g8_compute<1, 2>(acc, L + 32768, wm, wn, lane);
;   __syncthreads();
	s_waitcnt vmcnt(7)
	ds_write_b128 v163, v[2:5]
	s_waitcnt vmcnt(6)
	ds_write_b128 v163, v[10:13] offset:8192
	s_waitcnt vmcnt(5)
	ds_write_b128 v163, v[14:17] offset:16384
	s_waitcnt vmcnt(4)
	ds_write_b128 v163, v[18:21] offset:24576
	ds_read_b128 v[2:5], v234
	ds_read_b128 v[10:13], v234 offset:2048
	ds_read_b128 v[14:17], v234 offset:4096
	ds_read_b128 v[18:21], v234 offset:6144
	ds_read_b128 v[168:171], v234 offset:8192
	ds_read_b128 v[172:175], v234 offset:10240
	ds_read_b128 v[176:179], v234 offset:12288
	ds_read_b128 v[180:183], v234 offset:14336
	ds_read_b128 v[184:187], v235
	ds_read_b128 v[188:191], v235 offset:2048
	ds_read_b128 v[192:195], v235 offset:4096
	ds_read_b128 v[198:201], v235 offset:6144
	s_waitcnt lgkmcnt(3)
	v_mfma_f32_16x16x32_bf16 v[104:107], v[184:187], v[2:5], v[104:107]
	s_waitcnt lgkmcnt(2)
	v_mfma_f32_16x16x32_bf16 v[108:111], v[188:191], v[2:5], v[108:111]
	s_waitcnt lgkmcnt(1)
	v_mfma_f32_16x16x32_bf16 v[112:115], v[192:195], v[2:5], v[112:115]
	s_waitcnt lgkmcnt(0)
	v_mfma_f32_16x16x32_bf16 v[2:5], v[198:201], v[2:5], v[34:37]
	v_mfma_f32_16x16x32_bf16 v[34:37], v[184:187], v[10:13], v[42:45]
	v_mfma_f32_16x16x32_bf16 v[42:45], v[188:191], v[10:13], v[46:49]
	v_mfma_f32_16x16x32_bf16 v[46:49], v[192:195], v[10:13], v[50:53]
	v_mfma_f32_16x16x32_bf16 v[10:13], v[198:201], v[10:13], v[38:41]
	v_mfma_f32_16x16x32_bf16 v[38:41], v[184:187], v[14:17], v[54:57]
	v_mfma_f32_16x16x32_bf16 v[50:53], v[188:191], v[14:17], v[58:61]
	v_mfma_f32_16x16x32_bf16 v[54:57], v[192:195], v[14:17], v[100:103]
	v_mfma_f32_16x16x32_bf16 v[14:17], v[198:201], v[14:17], v[62:65]
	v_mfma_f32_16x16x32_bf16 v[58:61], v[184:187], v[18:21], v[116:119]
	v_mfma_f32_16x16x32_bf16 v[62:65], v[188:191], v[18:21], v[120:123]
	v_mfma_f32_16x16x32_bf16 v[98:101], v[192:195], v[18:21], v[124:127]
	v_mfma_f32_16x16x32_bf16 v[18:21], v[198:201], v[18:21], v[66:69]
	v_mfma_f32_16x16x32_bf16 v[66:69], v[184:187], v[168:171], v[128:131]
	v_mfma_f32_16x16x32_bf16 v[70:73], v[198:201], v[168:171], v[70:73]
	v_mfma_f32_16x16x32_bf16 v[74:77], v[198:201], v[172:175], v[74:77]
	v_mfma_f32_16x16x32_bf16 v[116:119], v[188:191], v[168:171], v[132:135]
	v_mfma_f32_16x16x32_bf16 v[120:123], v[192:195], v[168:171], v[136:139]
	v_mfma_f32_16x16x32_bf16 v[124:127], v[184:187], v[172:175], v[140:143]
	v_mfma_f32_16x16x32_bf16 v[128:131], v[188:191], v[172:175], v[144:147]
	v_mfma_f32_16x16x32_bf16 v[132:135], v[192:195], v[172:175], v[148:151]
	v_mfma_f32_16x16x32_bf16 v[136:139], v[184:187], v[176:179], v[152:155]
	v_mfma_f32_16x16x32_bf16 v[140:143], v[188:191], v[176:179], v[156:159]
	v_mfma_f32_16x16x32_bf16 v[144:147], v[192:195], v[176:179], v[164:167]
	v_mfma_f32_16x16x32_bf16 v[78:81], v[198:201], v[176:179], v[78:81]
	v_mfma_f32_16x16x32_bf16 v[86:89], v[184:187], v[180:183], v[86:89]
	v_mfma_f32_16x16x32_bf16 v[90:93], v[188:191], v[180:183], v[90:93]
	v_mfma_f32_16x16x32_bf16 v[94:97], v[192:195], v[180:183], v[94:97]
	v_mfma_f32_16x16x32_bf16 v[82:85], v[198:201], v[180:183], v[82:85]
	s_waitcnt vmcnt(3)
	ds_write_b128 v163, v[6:9] offset:32768
	s_waitcnt vmcnt(2)
	ds_write_b128 v163, v[22:25] offset:40960
	s_waitcnt vmcnt(1)
	ds_write_b128 v163, v[26:29] offset:49152
	s_waitcnt vmcnt(0)
	ds_write_b128 v163, v[30:33] offset:57344
	ds_read_b128 v[6:9], v226
	ds_read_b128 v[22:25], v226 offset:2048
	ds_read_b128 v[26:29], v226 offset:4096
	ds_read_b128 v[30:33], v226 offset:6144
	ds_read_b128 v[148:151], v226 offset:8192
	ds_read_b128 v[152:155], v226 offset:10240
	ds_read_b128 v[156:159], v226 offset:12288
	ds_read_b128 v[164:167], v226 offset:14336
	ds_read_b128 v[168:171], v227
	ds_read_b128 v[172:175], v227 offset:2048
	ds_read_b128 v[176:179], v227 offset:4096
	ds_read_b128 v[180:183], v227 offset:6144
	s_waitcnt lgkmcnt(3)
	v_mfma_f32_16x16x32_bf16 v[102:105], v[168:171], v[6:9], v[104:107]
	s_waitcnt lgkmcnt(2)
	v_mfma_f32_16x16x32_bf16 v[106:109], v[172:175], v[6:9], v[108:111]
	s_waitcnt lgkmcnt(1)
	v_mfma_f32_16x16x32_bf16 v[110:113], v[176:179], v[6:9], v[112:115]
	s_waitcnt lgkmcnt(0)
	v_mfma_f32_16x16x32_bf16 v[2:5], v[180:183], v[6:9], v[2:5]
	v_mfma_f32_16x16x32_bf16 v[6:9], v[168:171], v[22:25], v[34:37]
	v_mfma_f32_16x16x32_bf16 v[34:37], v[172:175], v[22:25], v[42:45]
	v_mfma_f32_16x16x32_bf16 v[42:45], v[176:179], v[22:25], v[46:49]
	v_mfma_f32_16x16x32_bf16 v[10:13], v[180:183], v[22:25], v[10:13]
	v_mfma_f32_16x16x32_bf16 v[22:25], v[168:171], v[26:29], v[38:41]
	v_mfma_f32_16x16x32_bf16 v[184:187], v[172:175], v[26:29], v[50:53]
	v_mfma_f32_16x16x32_bf16 v[188:191], v[176:179], v[26:29], v[54:57]
	v_mfma_f32_16x16x32_bf16 v[14:17], v[180:183], v[26:29], v[14:17]
	v_mfma_f32_16x16x32_bf16 v[26:29], v[168:171], v[30:33], v[58:61]
	v_mfma_f32_16x16x32_bf16 v[18:21], v[180:183], v[30:33], v[18:21]
	v_mfma_f32_16x16x32_bf16 v[66:69], v[168:171], v[148:151], v[66:69]
	v_mfma_f32_16x16x32_bf16 v[192:195], v[172:175], v[30:33], v[62:65]
	v_mfma_f32_16x16x32_bf16 v[98:101], v[176:179], v[30:33], v[98:101]
	v_mfma_f32_16x16x32_bf16 v[114:117], v[172:175], v[148:151], v[116:119]
	v_mfma_f32_16x16x32_bf16 v[118:121], v[176:179], v[148:151], v[120:123]
	v_mfma_f32_16x16x32_bf16 v[148:151], v[180:183], v[148:151], v[70:73]
	v_mfma_f32_16x16x32_bf16 v[122:125], v[168:171], v[152:155], v[124:127]
	v_mfma_f32_16x16x32_bf16 v[126:129], v[172:175], v[152:155], v[128:131]
	v_mfma_f32_16x16x32_bf16 v[130:133], v[176:179], v[152:155], v[132:135]
	v_mfma_f32_16x16x32_bf16 v[152:155], v[180:183], v[152:155], v[74:77]
	v_mfma_f32_16x16x32_bf16 v[134:137], v[168:171], v[156:159], v[136:139]
	v_mfma_f32_16x16x32_bf16 v[138:141], v[172:175], v[156:159], v[140:143]
	v_mfma_f32_16x16x32_bf16 v[142:145], v[176:179], v[156:159], v[144:147]
	v_mfma_f32_16x16x32_bf16 v[78:81], v[180:183], v[156:159], v[78:81]
	v_mfma_f32_16x16x32_bf16 v[86:89], v[168:171], v[164:167], v[86:89]
	v_mfma_f32_16x16x32_bf16 v[90:93], v[172:175], v[164:167], v[90:93]
	v_mfma_f32_16x16x32_bf16 v[94:97], v[176:179], v[164:167], v[94:97]
	v_mfma_f32_16x16x32_bf16 v[82:85], v[180:183], v[164:167], v[82:85]
	v_mov_b32_e32 v76, v196
	s_barrier
; template <class F>
; DI void gemm8_epi_staged(f32x4 (&acc)[8][4], int m0, int n0, bf16_t* L0, F f, bf16_t* dst, size_t ld, int nmax) {
;     ...
; #pragma unroll
;   for (int half = 0; half < 2; ++half) {
;     if (wm == half) {
; #pragma unroll
;       for (int i = 0; i < 8; ++i)
; #pragma unroll
;         for (int j = 0; j < 4; ++j) {
;           const int ml = i * 16 + (lane & 15);
;           const int nl = wn * 64 + j * 16 + (lane >> 4) * 4;
;           f32x4 a = acc[i][j];
;           f(m0 + half * 128 + ml, n0 + nl, a);
;           uint2 u;
;           u.x = pack2(a[0], a[1]);
;           u.y = pack2(a[2], a[3]);
;           *(uint2*)(L + ml * 264 + nl) = u;
;         }
;     }
	s_movk_i32 s4, 0x100
	v_and_b32_e32 v0, 0xc0, v76
	v_lshrrev_b32_e32 v31, 1, v76
	v_lshlrev_b32_e32 v0, 1, v0
	v_and_b32_e32 v31, 24, v31
	v_and_b32_e32 v30, 15, v76
	v_add3_u32 v0, s7, v0, v31
	v_cmp_gt_u32_e32 vcc, s4, v76
	s_movk_i32 s4, 0x210
	v_mad_u32_u24 v71, v30, s4, v0
	v_cvt_pk_bf16_f32 v60, v102, v103
	v_cvt_pk_bf16_f32 v61, v104, v105
	v_cvt_pk_bf16_f32 v64, v106, v107
	v_cvt_pk_bf16_f32 v65, v108, v109
	v_cvt_pk_bf16_f32 v54, v110, v111
	v_cvt_pk_bf16_f32 v55, v112, v113
	v_cvt_pk_bf16_f32 v62, v2, v3
	v_cvt_pk_bf16_f32 v63, v4, v5
	v_cvt_pk_bf16_f32 v48, v6, v7
	v_cvt_pk_bf16_f32 v49, v8, v9
	v_cvt_pk_bf16_f32 v58, v34, v35
	v_cvt_pk_bf16_f32 v59, v36, v37
	v_add_u32_e32 v75, 0x2000, v71
	v_cvt_pk_bf16_f32 v46, v42, v43
	v_cvt_pk_bf16_f32 v47, v44, v45
	v_cvt_pk_bf16_f32 v56, v10, v11
	v_cvt_pk_bf16_f32 v57, v12, v13
	v_cvt_pk_bf16_f32 v40, v22, v23
	v_cvt_pk_bf16_f32 v41, v24, v25
	v_cvt_pk_bf16_f32 v52, v184, v185
	v_cvt_pk_bf16_f32 v53, v186, v187
	v_add_u32_e32 v74, 0x4000, v71
	v_cvt_pk_bf16_f32 v38, v188, v189
	v_cvt_pk_bf16_f32 v39, v190, v191
	v_cvt_pk_bf16_f32 v50, v14, v15
	v_cvt_pk_bf16_f32 v51, v16, v17
	v_cvt_pk_bf16_f32 v32, v26, v27
	v_cvt_pk_bf16_f32 v33, v28, v29
	v_cvt_pk_bf16_f32 v44, v192, v193
	v_cvt_pk_bf16_f32 v45, v194, v195
	v_add_u32_e32 v73, 0x6000, v71
	v_cvt_pk_bf16_f32 v30, v98, v99
	v_cvt_pk_bf16_f32 v31, v100, v101
	v_cvt_pk_bf16_f32 v42, v18, v19
	v_cvt_pk_bf16_f32 v43, v20, v21
	v_cvt_pk_bf16_f32 v24, v66, v67
	v_cvt_pk_bf16_f32 v25, v68, v69
	v_cvt_pk_bf16_f32 v36, v114, v115
	v_cvt_pk_bf16_f32 v37, v116, v117
	v_add_u32_e32 v72, 0x8000, v71
	v_cvt_pk_bf16_f32 v22, v118, v119
	v_cvt_pk_bf16_f32 v23, v120, v121
	v_cvt_pk_bf16_f32 v34, v148, v149
	v_cvt_pk_bf16_f32 v35, v150, v151
	v_cvt_pk_bf16_f32 v16, v122, v123
	v_cvt_pk_bf16_f32 v17, v124, v125
	v_cvt_pk_bf16_f32 v28, v126, v127
	v_cvt_pk_bf16_f32 v29, v128, v129
	v_add_u32_e32 v70, 0xa000, v71
	v_cvt_pk_bf16_f32 v14, v130, v131
	v_cvt_pk_bf16_f32 v15, v132, v133
	v_cvt_pk_bf16_f32 v26, v152, v153
	v_cvt_pk_bf16_f32 v27, v154, v155
	v_cvt_pk_bf16_f32 v8, v134, v135
	v_cvt_pk_bf16_f32 v9, v136, v137
	v_cvt_pk_bf16_f32 v20, v138, v139
	v_cvt_pk_bf16_f32 v21, v140, v141
	v_add_u32_e32 v69, 0xc000, v71
	v_cvt_pk_bf16_f32 v6, v142, v143
	v_cvt_pk_bf16_f32 v7, v144, v145
	v_cvt_pk_bf16_f32 v18, v78, v79
	v_cvt_pk_bf16_f32 v19, v80, v81
	v_cvt_pk_bf16_f32 v4, v86, v87
	v_cvt_pk_bf16_f32 v5, v88, v89
	v_cvt_pk_bf16_f32 v12, v90, v91
	v_cvt_pk_bf16_f32 v13, v92, v93
	v_add_u32_e32 v68, 0xe000, v71
	v_cvt_pk_bf16_f32 v2, v94, v95
	v_cvt_pk_bf16_f32 v3, v96, v97
	v_cvt_pk_bf16_f32 v10, v82, v83
	v_cvt_pk_bf16_f32 v11, v84, v85
	s_and_saveexec_b64 s[4:5], vcc
	s_cbranch_execz .LBB0_1004
	ds_write2_b64 v71, v[60:61], v[64:65] offset1:4
	ds_write2_b64 v71, v[54:55], v[62:63] offset0:8 offset1:12
	ds_write2_b64 v75, v[48:49], v[58:59] offset0:32 offset1:36
	ds_write2_b64 v75, v[46:47], v[56:57] offset0:40 offset1:44
	ds_write2_b64 v74, v[40:41], v[52:53] offset0:64 offset1:68
	ds_write2_b64 v74, v[38:39], v[50:51] offset0:72 offset1:76
	ds_write2_b64 v73, v[32:33], v[44:45] offset0:96 offset1:100
	ds_write2_b64 v73, v[30:31], v[42:43] offset0:104 offset1:108
	ds_write2_b64 v72, v[24:25], v[36:37] offset0:128 offset1:132
	ds_write2_b64 v72, v[22:23], v[34:35] offset0:136 offset1:140
	ds_write2_b64 v70, v[16:17], v[28:29] offset0:160 offset1:164
	ds_write2_b64 v70, v[14:15], v[26:27] offset0:168 offset1:172
	ds_write2_b64 v69, v[8:9], v[20:21] offset0:192 offset1:196
	ds_write2_b64 v69, v[6:7], v[18:19] offset0:200 offset1:204
	ds_write2_b64 v68, v[4:5], v[12:13] offset0:224 offset1:228
	ds_write2_b64 v68, v[2:3], v[10:11] offset0:232 offset1:236

; DI f32x4 mfma16(bf16x8 a, bf16x8 b, f32x4 c) { return __builtin_amdgcn_mfma_f32_16x16x32_bf16(a, b, c, 0, 0, 0); }
; #pragma unroll
;   for (int ks = KS0; ks < KS1; ++ks) {
;     bf16x8 af[8], bfr[4];
; #pragma unroll
;     for (int i = 0; i < 8; ++i) {
;       const int r = wm * 128 + i * 16 + (lane & 15);
;       af[i] = *(const bf16x8*)(S + r * 64 + (((ks * 4 + (lane >> 4)) ^ ((r >> 1) & 7)) << 3));
;     }
; #pragma unroll
;     for (int j = 0; j < 4; ++j) {
;       const int r = wn * 64 + j * 16 + (lane & 15);
;       bfr[j] = *(const bf16x8*)(S + 16384 + r * 64 + (((ks * 4 + (lane >> 4)) ^ ((r >> 1) & 7)) << 3));
;     }
;     __builtin_amdgcn_s_setprio(1);
; #pragma unroll
;     for (int i = 0; i < 8; ++i)
; #pragma unroll
;       for (int j = 0; j < 4; ++j) acc[i][j] = mfma16(bfr[j], af[i], acc[i][j]);
;     __builtin_amdgcn_s_setprio(0);
;   }
; DI void gemm8_accum(f32x4 (&acc)[8][4], const bf16_t* a, size_t lda, const bf16_t* b, size_t ldb, int nkb, bf16_t* L,
;                     const bool pre, const bf16_t* an, size_t ldan, const bf16_t* bn, size_t ldbn) {
;     ...
;   for (int kb = 0; kb + 2 < nkb; ++kb) {
;     __syncthreads();
;     g8_store1(L + ((kb + 1) & 1) * 32768, ra, lrow, lch);
;     g8_load1o(ra, a + (kb + 2) * 64, offa);
;     __builtin_amdgcn_sched_barrier(0);
;     g8_compute<0, 1>(acc, L + (kb & 1) * 32768, wm, wn, lane);
;     __builtin_amdgcn_sched_barrier(0);
;     g8_store1(L + ((kb + 1) & 1) * 32768 + 16384, rb, lrow, lch);
;     g8_load1o(rb, b + (kb + 2) * 64, offb);
;     __builtin_amdgcn_sched_barrier(0);
;     g8_compute<1, 2>(acc, L + (kb & 1) * 32768, wm, wn, lane);
;   }
.LBB0_1007:
	s_add_i32 s3, s2, 0x8000
	s_and_b32 s4, s3, 0x8000
	v_lshl_add_u32 v0, s4, 1, v163
	s_waitcnt lgkmcnt(0)
	s_barrier
	s_cmp_eq_u32 s100, 0
	s_cbranch_scc1 .Lstg_1007_a
	v_mfma_f32_16x16x32_bf16 v[158:161], v[226:229], v[192:195], v[158:161]
	v_mfma_f32_16x16x32_bf16 v[154:157], v[230:233], v[192:195], v[154:157]
	v_mfma_f32_16x16x32_bf16 v[150:153], v[234:237], v[192:195], v[150:153]
	v_mfma_f32_16x16x32_bf16 v[146:149], v[238:241], v[192:195], v[146:149]
	v_mfma_f32_16x16x32_bf16 v[142:145], v[226:229], v[198:201], v[142:145]
	v_mfma_f32_16x16x32_bf16 v[138:141], v[230:233], v[198:201], v[138:141]
	v_mfma_f32_16x16x32_bf16 v[134:137], v[234:237], v[198:201], v[134:137]
	v_mfma_f32_16x16x32_bf16 v[130:133], v[238:241], v[198:201], v[130:133]
	v_mfma_f32_16x16x32_bf16 v[126:129], v[226:229], v[202:205], v[126:129]
	v_mfma_f32_16x16x32_bf16 v[122:125], v[230:233], v[202:205], v[122:125]
	v_mfma_f32_16x16x32_bf16 v[118:121], v[234:237], v[202:205], v[118:121]
	v_mfma_f32_16x16x32_bf16 v[114:117], v[238:241], v[202:205], v[114:117]
	v_mfma_f32_16x16x32_bf16 v[110:113], v[226:229], v[206:209], v[110:113]
	v_mfma_f32_16x16x32_bf16 v[106:109], v[230:233], v[206:209], v[106:109]
	v_mfma_f32_16x16x32_bf16 v[102:105], v[234:237], v[206:209], v[102:105]
	v_mfma_f32_16x16x32_bf16 v[98:101], v[238:241], v[206:209], v[98:101]
	v_mfma_f32_16x16x32_bf16 v[90:93], v[226:229], v[210:213], v[90:93]
	v_mfma_f32_16x16x32_bf16 v[86:89], v[230:233], v[210:213], v[86:89]
	v_mfma_f32_16x16x32_bf16 v[82:85], v[234:237], v[210:213], v[82:85]
	v_mfma_f32_16x16x32_bf16 v[78:81], v[238:241], v[210:213], v[78:81]
	v_mfma_f32_16x16x32_bf16 v[74:77], v[226:229], v[214:217], v[74:77]
	v_mfma_f32_16x16x32_bf16 v[70:73], v[230:233], v[214:217], v[70:73]
	v_mfma_f32_16x16x32_bf16 v[66:69], v[234:237], v[214:217], v[66:69]
	v_mfma_f32_16x16x32_bf16 v[62:65], v[238:241], v[214:217], v[62:65]
	v_mfma_f32_16x16x32_bf16 v[58:61], v[226:229], v[218:221], v[58:61]
	v_mfma_f32_16x16x32_bf16 v[50:53], v[230:233], v[218:221], v[50:53]
	v_mfma_f32_16x16x32_bf16 v[46:49], v[234:237], v[218:221], v[46:49]
	v_mfma_f32_16x16x32_bf16 v[38:41], v[238:241], v[218:221], v[38:41]
	v_mfma_f32_16x16x32_bf16 v[30:33], v[226:229], v[222:225], v[30:33]
	v_mfma_f32_16x16x32_bf16 v[26:29], v[230:233], v[222:225], v[26:29]
	v_mfma_f32_16x16x32_bf16 v[22:25], v[234:237], v[222:225], v[22:25]
	v_mfma_f32_16x16x32_bf16 v[18:21], v[238:241], v[222:225], v[18:21]
.Lstg_1007_a:
	s_waitcnt vmcnt(7)
	ds_write_b128 v0, v[34:37]
	s_waitcnt vmcnt(6)
	ds_write_b128 v0, v[42:45] offset:8192
	s_waitcnt vmcnt(5)
	ds_write_b128 v0, v[54:57] offset:16384
	s_waitcnt vmcnt(4)
	ds_write_b128 v0, v[94:97] offset:24576
	v_lshl_add_u64 v[34:35], v[178:179], 0, s[0:1]
	v_lshl_add_u64 v[42:43], v[176:177], 0, s[0:1]
	v_lshl_add_u64 v[54:55], v[174:175], 0, s[0:1]
	v_lshl_add_u64 v[94:95], v[172:173], 0, s[0:1]
	global_load_dwordx4 v[34:37], v[34:35], off
	s_nop 0
	global_load_dwordx4 v[42:45], v[42:43], off
	s_nop 0
	global_load_dwordx4 v[54:57], v[54:55], off
	s_nop 0
	global_load_dwordx4 v[94:97], v[94:95], off
	s_and_b32 s2, s2, 0x8000
	s_lshl_b32 s2, s2, 1
	s_add_i32 s2, s2, 0
	v_lshl_add_u32 v191, v186, 1, s2
	v_add_u32_e32 v222, v191, v181
	ds_read_b128 v[192:195], v222
	ds_read_b128 v[198:201], v222 offset:2048
	ds_read_b128 v[202:205], v222 offset:4096
	ds_read_b128 v[206:209], v222 offset:6144
	ds_read_b128 v[210:213], v222 offset:8192
	ds_read_b128 v[214:217], v222 offset:10240
	ds_read_b128 v[218:221], v222 offset:12288
	ds_read_b128 v[222:225], v222 offset:14336
	v_add_u32_e32 v191, v191, v180
	ds_read_b128 v[226:229], v191 offset:32768
	ds_read_b128 v[230:233], v191 offset:34816
	ds_read_b128 v[234:237], v191 offset:36864
	ds_read_b128 v[238:241], v191 offset:38912
	s_waitcnt lgkmcnt(3)
	v_mfma_f32_16x16x32_bf16 v[158:161], v[226:229], v[192:195], v[158:161]
	s_waitcnt lgkmcnt(2)
	v_mfma_f32_16x16x32_bf16 v[154:157], v[230:233], v[192:195], v[154:157]
	s_waitcnt lgkmcnt(1)
	v_mfma_f32_16x16x32_bf16 v[150:153], v[234:237], v[192:195], v[150:153]
	s_waitcnt lgkmcnt(0)
	v_mfma_f32_16x16x32_bf16 v[146:149], v[238:241], v[192:195], v[146:149]
	v_mfma_f32_16x16x32_bf16 v[142:145], v[226:229], v[198:201], v[142:145]
	v_mfma_f32_16x16x32_bf16 v[138:141], v[230:233], v[198:201], v[138:141]
	v_mfma_f32_16x16x32_bf16 v[134:137], v[234:237], v[198:201], v[134:137]
	v_mfma_f32_16x16x32_bf16 v[130:133], v[238:241], v[198:201], v[130:133]
	v_mfma_f32_16x16x32_bf16 v[126:129], v[226:229], v[202:205], v[126:129]
	v_mfma_f32_16x16x32_bf16 v[122:125], v[230:233], v[202:205], v[122:125]
	v_mfma_f32_16x16x32_bf16 v[118:121], v[234:237], v[202:205], v[118:121]
	v_mfma_f32_16x16x32_bf16 v[114:117], v[238:241], v[202:205], v[114:117]
	v_mfma_f32_16x16x32_bf16 v[110:113], v[226:229], v[206:209], v[110:113]
	v_mfma_f32_16x16x32_bf16 v[106:109], v[230:233], v[206:209], v[106:109]
	v_mfma_f32_16x16x32_bf16 v[102:105], v[234:237], v[206:209], v[102:105]
	v_mfma_f32_16x16x32_bf16 v[98:101], v[238:241], v[206:209], v[98:101]
	v_mfma_f32_16x16x32_bf16 v[90:93], v[226:229], v[210:213], v[90:93]
	v_mfma_f32_16x16x32_bf16 v[86:89], v[230:233], v[210:213], v[86:89]
	v_mfma_f32_16x16x32_bf16 v[82:85], v[234:237], v[210:213], v[82:85]
	v_mfma_f32_16x16x32_bf16 v[78:81], v[238:241], v[210:213], v[78:81]
	v_mfma_f32_16x16x32_bf16 v[74:77], v[226:229], v[214:217], v[74:77]
	v_mfma_f32_16x16x32_bf16 v[70:73], v[230:233], v[214:217], v[70:73]
	v_mfma_f32_16x16x32_bf16 v[66:69], v[234:237], v[214:217], v[66:69]
	v_mfma_f32_16x16x32_bf16 v[62:65], v[238:241], v[214:217], v[62:65]
	v_mfma_f32_16x16x32_bf16 v[58:61], v[226:229], v[218:221], v[58:61]
	v_mfma_f32_16x16x32_bf16 v[50:53], v[230:233], v[218:221], v[50:53]
	v_mfma_f32_16x16x32_bf16 v[46:49], v[234:237], v[218:221], v[46:49]
	v_mfma_f32_16x16x32_bf16 v[38:41], v[238:241], v[218:221], v[38:41]
	v_mfma_f32_16x16x32_bf16 v[30:33], v[226:229], v[222:225], v[30:33]
	v_mfma_f32_16x16x32_bf16 v[26:29], v[230:233], v[222:225], v[26:29]
	v_mfma_f32_16x16x32_bf16 v[22:25], v[234:237], v[222:225], v[22:25]
	v_mfma_f32_16x16x32_bf16 v[18:21], v[238:241], v[222:225], v[18:21]
	s_waitcnt vmcnt(7)
; DI f32x4 mfma16(bf16x8 a, bf16x8 b, f32x4 c) { return __builtin_amdgcn_mfma_f32_16x16x32_bf16(a, b, c, 0, 0, 0); }
; #pragma unroll
;   for (int ks = KS0; ks < KS1; ++ks) {
;     bf16x8 af[8], bfr[4];
; #pragma unroll
;     for (int i = 0; i < 8; ++i) {
;       const int r = wm * 128 + i * 16 + (lane & 15);
;       af[i] = *(const bf16x8*)(S + r * 64 + (((ks * 4 + (lane >> 4)) ^ ((r >> 1) & 7)) << 3));
;     }
; #pragma unroll
;     for (int j = 0; j < 4; ++j) {
;       const int r = wn * 64 + j * 16 + (lane & 15);
;       bfr[j] = *(const bf16x8*)(S + 16384 + r * 64 + (((ks * 4 + (lane >> 4)) ^ ((r >> 1) & 7)) << 3));
;     }
;     __builtin_amdgcn_s_setprio(1);
; #pragma unroll
;     for (int i = 0; i < 8; ++i)
; #pragma unroll
;       for (int j = 0; j < 4; ++j) acc[i][j] = mfma16(bfr[j], af[i], acc[i][j]);
;     __builtin_amdgcn_s_setprio(0);
;   }
; DI void gemm8_accum(f32x4 (&acc)[8][4], const bf16_t* a, size_t lda, const bf16_t* b, size_t ldb, int nkb, bf16_t* L,
;                     const bool pre, const bf16_t* an, size_t ldan, const bf16_t* bn, size_t ldbn) {
;     ...
;   for (int kb = 0; kb + 2 < nkb; ++kb) {
;     __syncthreads();
;     g8_store1(L + ((kb + 1) & 1) * 32768, ra, lrow, lch);
;     g8_load1o(ra, a + (kb + 2) * 64, offa);
;     __builtin_amdgcn_sched_barrier(0);
;     g8_compute<0, 1>(acc, L + (kb & 1) * 32768, wm, wn, lane);
;     __builtin_amdgcn_sched_barrier(0);
;     g8_store1(L + ((kb + 1) & 1) * 32768 + 16384, rb, lrow, lch);
;     g8_load1o(rb, b + (kb + 2) * 64, offb);
;     __builtin_amdgcn_sched_barrier(0);
;     g8_compute<1, 2>(acc, L + (kb & 1) * 32768, wm, wn, lane);
;   }
	ds_write_b128 v0, v[14:17] offset:32768
	s_waitcnt vmcnt(6)
	ds_write_b128 v0, v[2:5] offset:40960
	s_waitcnt vmcnt(5)
	ds_write_b128 v0, v[6:9] offset:49152
	s_waitcnt vmcnt(4)
	ds_write_b128 v0, v[10:13] offset:57344
	v_lshl_add_u64 v[2:3], v[170:171], 0, s[0:1]
	v_lshl_add_u64 v[4:5], v[168:169], 0, s[0:1]
	v_lshl_add_u64 v[6:7], v[166:167], 0, s[0:1]
	v_lshl_add_u64 v[10:11], v[164:165], 0, s[0:1]
	global_load_dwordx4 v[14:17], v[2:3], off
	s_nop 0
	global_load_dwordx4 v[2:5], v[4:5], off
	s_nop 0
	global_load_dwordx4 v[6:9], v[6:7], off
	s_nop 0
	global_load_dwordx4 v[10:13], v[10:11], off
	v_lshl_add_u32 v0, v182, 1, s2
	v_add_u32_e32 v191, v0, v181
	ds_read_b128 v[192:195], v191
	ds_read_b128 v[198:201], v191 offset:2048
	ds_read_b128 v[202:205], v191 offset:4096
	ds_read_b128 v[206:209], v191 offset:6144
	ds_read_b128 v[210:213], v191 offset:8192
	ds_read_b128 v[214:217], v191 offset:10240
	ds_read_b128 v[218:221], v191 offset:12288
	ds_read_b128 v[222:225], v191 offset:14336
	v_add_u32_e32 v0, v0, v180
	ds_read_b128 v[226:229], v0 offset:32768
	ds_read_b128 v[230:233], v0 offset:34816
	ds_read_b128 v[234:237], v0 offset:36864
	ds_read_b128 v[238:241], v0 offset:38912
	s_cmp_lg_u32 s101, 0
	s_cbranch_scc1 .Lstg_1007_b
	s_waitcnt lgkmcnt(3)
	v_mfma_f32_16x16x32_bf16 v[158:161], v[226:229], v[192:195], v[158:161]
	s_waitcnt lgkmcnt(2)
	v_mfma_f32_16x16x32_bf16 v[154:157], v[230:233], v[192:195], v[154:157]
	s_waitcnt lgkmcnt(1)
	v_mfma_f32_16x16x32_bf16 v[150:153], v[234:237], v[192:195], v[150:153]
	s_waitcnt lgkmcnt(0)
	v_mfma_f32_16x16x32_bf16 v[146:149], v[238:241], v[192:195], v[146:149]
	v_mfma_f32_16x16x32_bf16 v[142:145], v[226:229], v[198:201], v[142:145]
	v_mfma_f32_16x16x32_bf16 v[138:141], v[230:233], v[198:201], v[138:141]
	v_mfma_f32_16x16x32_bf16 v[134:137], v[234:237], v[198:201], v[134:137]
	v_mfma_f32_16x16x32_bf16 v[130:133], v[238:241], v[198:201], v[130:133]
	v_mfma_f32_16x16x32_bf16 v[126:129], v[226:229], v[202:205], v[126:129]
	v_mfma_f32_16x16x32_bf16 v[122:125], v[230:233], v[202:205], v[122:125]
	v_mfma_f32_16x16x32_bf16 v[118:121], v[234:237], v[202:205], v[118:121]
	v_mfma_f32_16x16x32_bf16 v[114:117], v[238:241], v[202:205], v[114:117]
	v_mfma_f32_16x16x32_bf16 v[110:113], v[226:229], v[206:209], v[110:113]
	v_mfma_f32_16x16x32_bf16 v[106:109], v[230:233], v[206:209], v[106:109]
	v_mfma_f32_16x16x32_bf16 v[102:105], v[234:237], v[206:209], v[102:105]
	v_mfma_f32_16x16x32_bf16 v[98:101], v[238:241], v[206:209], v[98:101]
	v_mfma_f32_16x16x32_bf16 v[90:93], v[226:229], v[210:213], v[90:93]
	v_mfma_f32_16x16x32_bf16 v[86:89], v[230:233], v[210:213], v[86:89]
	v_mfma_f32_16x16x32_bf16 v[82:85], v[234:237], v[210:213], v[82:85]
	v_mfma_f32_16x16x32_bf16 v[78:81], v[238:241], v[210:213], v[78:81]
	v_mfma_f32_16x16x32_bf16 v[74:77], v[226:229], v[214:217], v[74:77]
	v_mfma_f32_16x16x32_bf16 v[70:73], v[230:233], v[214:217], v[70:73]
	v_mfma_f32_16x16x32_bf16 v[66:69], v[234:237], v[214:217], v[66:69]
	v_mfma_f32_16x16x32_bf16 v[62:65], v[238:241], v[214:217], v[62:65]
	v_mfma_f32_16x16x32_bf16 v[58:61], v[226:229], v[218:221], v[58:61]
	v_mfma_f32_16x16x32_bf16 v[50:53], v[230:233], v[218:221], v[50:53]
	v_mfma_f32_16x16x32_bf16 v[46:49], v[234:237], v[218:221], v[46:49]
	v_mfma_f32_16x16x32_bf16 v[38:41], v[238:241], v[218:221], v[38:41]
	v_mfma_f32_16x16x32_bf16 v[30:33], v[226:229], v[222:225], v[30:33]
	v_mfma_f32_16x16x32_bf16 v[26:29], v[230:233], v[222:225], v[26:29]
	v_mfma_f32_16x16x32_bf16 v[22:25], v[234:237], v[222:225], v[22:25]
	v_mfma_f32_16x16x32_bf16 v[18:21], v[238:241], v[222:225], v[18:21]
.Lstg_1007_b:
	s_mov_b32 s100, s101
	s_add_u32 s0, s0, 0x80
	s_addc_u32 s1, s1, 0
	s_cmpk_lg_i32 s0, 0x700
	s_mov_b32 s2, s3
	s_cbranch_scc1 .LBB0_1007
	s_cmp_eq_u32 s100, 0
	s_cbranch_scc1 .Lstg_1007_c
	s_waitcnt lgkmcnt(0)
	v_mfma_f32_16x16x32_bf16 v[158:161], v[226:229], v[192:195], v[158:161]
	v_mfma_f32_16x16x32_bf16 v[154:157], v[230:233], v[192:195], v[154:157]
	v_mfma_f32_16x16x32_bf16 v[150:153], v[234:237], v[192:195], v[150:153]
	v_mfma_f32_16x16x32_bf16 v[146:149], v[238:241], v[192:195], v[146:149]
	v_mfma_f32_16x16x32_bf16 v[142:145], v[226:229], v[198:201], v[142:145]
	v_mfma_f32_16x16x32_bf16 v[138:141], v[230:233], v[198:201], v[138:141]
	v_mfma_f32_16x16x32_bf16 v[134:137], v[234:237], v[198:201], v[134:137]
	v_mfma_f32_16x16x32_bf16 v[130:133], v[238:241], v[198:201], v[130:133]
	v_mfma_f32_16x16x32_bf16 v[126:129], v[226:229], v[202:205], v[126:129]
	v_mfma_f32_16x16x32_bf16 v[122:125], v[230:233], v[202:205], v[122:125]
	v_mfma_f32_16x16x32_bf16 v[118:121], v[234:237], v[202:205], v[118:121]
	v_mfma_f32_16x16x32_bf16 v[114:117], v[238:241], v[202:205], v[114:117]
	v_mfma_f32_16x16x32_bf16 v[110:113], v[226:229], v[206:209], v[110:113]
	v_mfma_f32_16x16x32_bf16 v[106:109], v[230:233], v[206:209], v[106:109]
	v_mfma_f32_16x16x32_bf16 v[102:105], v[234:237], v[206:209], v[102:105]
	v_mfma_f32_16x16x32_bf16 v[98:101], v[238:241], v[206:209], v[98:101]
	v_mfma_f32_16x16x32_bf16 v[90:93], v[226:229], v[210:213], v[90:93]
	v_mfma_f32_16x16x32_bf16 v[86:89], v[230:233], v[210:213], v[86:89]
	v_mfma_f32_16x16x32_bf16 v[82:85], v[234:237], v[210:213], v[82:85]
	v_mfma_f32_16x16x32_bf16 v[78:81], v[238:241], v[210:213], v[78:81]
	v_mfma_f32_16x16x32_bf16 v[74:77], v[226:229], v[214:217], v[74:77]
	v_mfma_f32_16x16x32_bf16 v[70:73], v[230:233], v[214:217], v[70:73]
	v_mfma_f32_16x16x32_bf16 v[66:69], v[234:237], v[214:217], v[66:69]
	v_mfma_f32_16x16x32_bf16 v[62:65], v[238:241], v[214:217], v[62:65]
	v_mfma_f32_16x16x32_bf16 v[58:61], v[226:229], v[218:221], v[58:61]
	v_mfma_f32_16x16x32_bf16 v[50:53], v[230:233], v[218:221], v[50:53]
	v_mfma_f32_16x16x32_bf16 v[46:49], v[234:237], v[218:221], v[46:49]
	v_mfma_f32_16x16x32_bf16 v[38:41], v[238:241], v[218:221], v[38:41]
	v_mfma_f32_16x16x32_bf16 v[30:33], v[226:229], v[222:225], v[30:33]
	v_mfma_f32_16x16x32_bf16 v[26:29], v[230:233], v[222:225], v[26:29]
	v_mfma_f32_16x16x32_bf16 v[22:25], v[234:237], v[222:225], v[22:25]
	v_mfma_f32_16x16x32_bf16 v[18:21], v[238:241], v[222:225], v[18:21]
	s_mov_b32 s100, 0
; DI void gemm8_accum(f32x4 (&acc)[8][4], const bf16_t* a, size_t lda, const bf16_t* b, size_t ldb, int nkb, bf16_t* L,
;                     const bool pre, const bf16_t* an, size_t ldan, const bf16_t* bn, size_t ldbn) {
;     ...
;   __syncthreads();
;   g8_store1(L + 32768, ra, lrow, lch);
;   g8_load1(ra, an, ldan, 0, lrow, lch);
;   __builtin_amdgcn_sched_barrier(0);
;   g8_compute<0, 1>(acc, L, wm, wn, lane);
;   __builtin_amdgcn_sched_barrier(0);
;   g8_store1(L + 32768 + 16384, rb, lrow, lch);
;   g8_load1(rb, bn, ldbn, 0, lrow, lch);
;   __builtin_amdgcn_sched_barrier(0);
;   g8_compute<1, 2>(acc, L, wm, wn, lane);
; __global__ void __launch_bounds__(512, 2) mega(Params p) {
;     ...
;       gemm8_accum(acc8, hbuf + (size_t)m0 * DM, DM, wl + W_PG + (size_t)n0 * 1024, 1024, 16, lds_all, true,
;                   p16 + (size_t)mtn * 256 * 256, 256, wl + W_PLE + (size_t)ntilen * 256 * 256, 256);
.Lstg_1007_c:
	v_readlane_b32 s21, v254, 18
	s_add_i32 s6, s20, s21
	s_cmp_lt_u32 s6, 64
	s_cselect_b64 s[4:5], -1, 0
	s_and_b64 s[0:1], s[4:5], exec
	s_cselect_b32 s2, s6, s20
	s_lshl_b32 s0, s2, 1
	v_lshlrev_b32_e32 v226, 1, v190
	s_and_b32 s0, s0, 0x7fffffe0
	s_and_b32 s1, s2, 3
	v_add3_u32 v0, s7, v183, v226
	s_or_b32 s0, s1, s0
	v_readlane_b32 s26, v252, 25
	s_barrier
	s_waitcnt vmcnt(7)
	ds_write_b128 v0, v[34:37]
	s_waitcnt vmcnt(6)
	ds_write_b128 v0, v[42:45] offset:8192
	s_waitcnt vmcnt(5)
	ds_write_b128 v0, v[54:57] offset:16384
	s_waitcnt vmcnt(4)
	ds_write_b128 v0, v[94:97] offset:24576
	v_lshl_or_b32 v0, v189, 8, v184
	s_or_b32 s28, s0, s26
	s_lshl_b32 s2, s2, 15
	v_lshlrev_b64 v[218:219], 1, v[0:1]
	v_lshl_or_b32 v0, v188, 8, v184
	s_lshl_b64 s[0:1], s[28:29], 17
	s_and_b32 s20, s2, 0x60000
	v_lshlrev_b64 v[220:221], 1, v[0:1]
	v_lshl_or_b32 v0, v187, 8, v184
	s_add_u32 s2, s38, s0
	v_lshlrev_b64 v[222:223], 1, v[0:1]
	v_lshl_or_b32 v0, v185, 8, v184
	s_addc_u32 s3, s39, s1
	v_lshlrev_b64 v[224:225], 1, v[0:1]
	v_lshl_add_u64 v[34:35], s[2:3], 0, v[218:219]
	v_lshl_add_u64 v[42:43], s[2:3], 0, v[220:221]
	v_lshl_add_u64 v[54:55], s[2:3], 0, v[222:223]
	v_lshl_add_u64 v[94:95], s[2:3], 0, v[224:225]
	global_load_dwordx4 v[34:37], v[34:35], off
	v_readlane_b32 s24, v254, 47
	global_load_dwordx4 v[42:45], v[42:43], off
	v_readlane_b32 s25, v254, 48
	global_load_dwordx4 v[54:57], v[54:55], off
	s_add_u32 s0, s24, s20
	global_load_dwordx4 v[94:97], v[94:95], off
	s_addc_u32 s1, s25, 0
	v_lshlrev_b32_e32 v0, 1, v186
	v_add_u32_e32 v202, 0, v0
	v_add_u32_e32 v198, v202, v181
	ds_read_b128 v[164:167], v198
	ds_read_b128 v[168:171], v198 offset:2048
	ds_read_b128 v[172:175], v198 offset:4096
	ds_read_b128 v[176:179], v198 offset:6144
	ds_read_b128 v[184:187], v198 offset:8192
	ds_read_b128 v[188:191], v198 offset:10240
	ds_read_b128 v[192:195], v198 offset:12288
	ds_read_b128 v[198:201], v198 offset:14336
	v_add_u32_e32 v214, v202, v180
	ds_read_b128 v[202:205], v214 offset:32768
	ds_read_b128 v[206:209], v214 offset:34816
	ds_read_b128 v[210:213], v214 offset:36864
	ds_read_b128 v[214:217], v214 offset:38912
	s_waitcnt lgkmcnt(3)
	v_mfma_f32_16x16x32_bf16 v[158:161], v[202:205], v[164:167], v[158:161]
	s_waitcnt lgkmcnt(2)
	v_mfma_f32_16x16x32_bf16 v[154:157], v[206:209], v[164:167], v[154:157]
	s_waitcnt lgkmcnt(1)
	v_mfma_f32_16x16x32_bf16 v[150:153], v[210:213], v[164:167], v[150:153]
	s_waitcnt lgkmcnt(0)
	v_mfma_f32_16x16x32_bf16 v[146:149], v[214:217], v[164:167], v[146:149]
	v_mfma_f32_16x16x32_bf16 v[142:145], v[202:205], v[168:171], v[142:145]
	v_mfma_f32_16x16x32_bf16 v[138:141], v[206:209], v[168:171], v[138:141]
	v_mfma_f32_16x16x32_bf16 v[134:137], v[210:213], v[168:171], v[134:137]
	v_mfma_f32_16x16x32_bf16 v[130:133], v[214:217], v[168:171], v[130:133]
	v_mfma_f32_16x16x32_bf16 v[126:129], v[202:205], v[172:175], v[126:129]
	v_mfma_f32_16x16x32_bf16 v[122:125], v[206:209], v[172:175], v[122:125]
	v_mfma_f32_16x16x32_bf16 v[118:121], v[210:213], v[172:175], v[118:121]
	v_mfma_f32_16x16x32_bf16 v[114:117], v[214:217], v[172:175], v[114:117]
	v_mfma_f32_16x16x32_bf16 v[110:113], v[202:205], v[176:179], v[110:113]
	v_mfma_f32_16x16x32_bf16 v[106:109], v[206:209], v[176:179], v[106:109]
	v_mfma_f32_16x16x32_bf16 v[102:105], v[210:213], v[176:179], v[102:105]
	v_mfma_f32_16x16x32_bf16 v[98:101], v[214:217], v[176:179], v[98:101]
	v_mfma_f32_16x16x32_bf16 v[90:93], v[202:205], v[184:187], v[90:93]
	v_mfma_f32_16x16x32_bf16 v[86:89], v[206:209], v[184:187], v[86:89]
	v_mfma_f32_16x16x32_bf16 v[82:85], v[210:213], v[184:187], v[82:85]
	v_mfma_f32_16x16x32_bf16 v[78:81], v[214:217], v[184:187], v[78:81]
	v_mfma_f32_16x16x32_bf16 v[74:77], v[202:205], v[188:191], v[74:77]
	v_mfma_f32_16x16x32_bf16 v[70:73], v[206:209], v[188:191], v[70:73]
	v_mfma_f32_16x16x32_bf16 v[66:69], v[210:213], v[188:191], v[66:69]
	v_mfma_f32_16x16x32_bf16 v[62:65], v[214:217], v[188:191], v[62:65]
	v_mfma_f32_16x16x32_bf16 v[58:61], v[202:205], v[192:195], v[58:61]
	v_mfma_f32_16x16x32_bf16 v[50:53], v[206:209], v[192:195], v[50:53]
	v_mfma_f32_16x16x32_bf16 v[46:49], v[210:213], v[192:195], v[46:49]
	v_mfma_f32_16x16x32_bf16 v[38:41], v[214:217], v[192:195], v[38:41]
	v_mfma_f32_16x16x32_bf16 v[30:33], v[202:205], v[198:201], v[30:33]
	v_mfma_f32_16x16x32_bf16 v[26:29], v[206:209], v[198:201], v[26:29]
	v_mfma_f32_16x16x32_bf16 v[22:25], v[210:213], v[198:201], v[22:25]
	v_mfma_f32_16x16x32_bf16 v[18:21], v[214:217], v[198:201], v[18:21]
	v_readlane_b32 s2, v254, 36
	s_nop 1
	v_add3_u32 v164, s2, v183, v226
	s_waitcnt vmcnt(7)
	ds_write_b128 v164, v[14:17]
	s_waitcnt vmcnt(6)
	ds_write_b128 v164, v[2:5] offset:8192
	s_waitcnt vmcnt(5)
	ds_write_b128 v164, v[6:9] offset:16384
	s_waitcnt vmcnt(4)
	ds_write_b128 v164, v[10:13] offset:24576
	v_lshl_add_u64 v[2:3], s[0:1], 0, v[218:219]
	v_lshl_add_u64 v[6:7], s[0:1], 0, v[220:221]
	v_lshl_add_u64 v[10:11], s[0:1], 0, v[222:223]
	v_lshl_add_u64 v[14:15], s[0:1], 0, v[224:225]
	global_load_dwordx4 v[2:5], v[2:3], off
	s_nop 0
	global_load_dwordx4 v[6:9], v[6:7], off
	s_nop 0
	global_load_dwordx4 v[10:13], v[10:11], off
	s_nop 0
	global_load_dwordx4 v[14:17], v[14:15], off
	v_lshlrev_b32_e32 v194, 1, v182
	v_add_u32_e32 v195, 0, v194
	v_add_u32_e32 v198, v195, v181
	ds_read_b128 v[164:167], v198
	ds_read_b128 v[168:171], v198 offset:2048
	ds_read_b128 v[172:175], v198 offset:4096
	ds_read_b128 v[176:179], v198 offset:6144
	ds_read_b128 v[182:185], v198 offset:8192
	ds_read_b128 v[186:189], v198 offset:10240
	ds_read_b128 v[190:193], v198 offset:12288
	ds_read_b128 v[198:201], v198 offset:14336
	v_add_u32_e32 v195, v195, v180
	ds_read_b128 v[202:205], v195 offset:32768
	ds_read_b128 v[206:209], v195 offset:34816
	ds_read_b128 v[210:213], v195 offset:36864
	ds_read_b128 v[214:217], v195 offset:38912
	s_waitcnt lgkmcnt(3)
; DI void gemm8_accum(f32x4 (&acc)[8][4], const bf16_t* a, size_t lda, const bf16_t* b, size_t ldb, int nkb, bf16_t* L,
;                     const bool pre, const bf16_t* an, size_t ldan, const bf16_t* bn, size_t ldbn) {
;     ...
;   g8_store1(L + 32768 + 16384, rb, lrow, lch);
;   g8_load1(rb, bn, ldbn, 0, lrow, lch);
;   __builtin_amdgcn_sched_barrier(0);
;   g8_compute<1, 2>(acc, L, wm, wn, lane);
;   __syncthreads();
;   g8_store1(L, ra, lrow, lch);
;   __builtin_amdgcn_sched_barrier(0);
;   g8_compute<0, 1>(acc, L + 32768, wm, wn, lane);
;   __builtin_amdgcn_sched_barrier(0);
;   g8_store1(L + 16384, rb, lrow, lch);
;   __builtin_amdgcn_sched_barrier(0);
;   g8_compute<1, 2>(acc, L + 32768, wm, wn, lane);
;   __syncthreads();
	v_mfma_f32_16x16x32_bf16 v[158:161], v[202:205], v[164:167], v[158:161]
	s_waitcnt lgkmcnt(2)
	v_mfma_f32_16x16x32_bf16 v[154:157], v[206:209], v[164:167], v[154:157]
	s_waitcnt lgkmcnt(1)
	v_mfma_f32_16x16x32_bf16 v[150:153], v[210:213], v[164:167], v[150:153]
	s_waitcnt lgkmcnt(0)
	v_mfma_f32_16x16x32_bf16 v[146:149], v[214:217], v[164:167], v[146:149]
	v_mfma_f32_16x16x32_bf16 v[142:145], v[202:205], v[168:171], v[142:145]
	v_mfma_f32_16x16x32_bf16 v[138:141], v[206:209], v[168:171], v[138:141]
	v_mfma_f32_16x16x32_bf16 v[134:137], v[210:213], v[168:171], v[134:137]
	v_mfma_f32_16x16x32_bf16 v[130:133], v[214:217], v[168:171], v[130:133]
	v_mfma_f32_16x16x32_bf16 v[126:129], v[202:205], v[172:175], v[126:129]
	v_mfma_f32_16x16x32_bf16 v[122:125], v[206:209], v[172:175], v[122:125]
	v_mfma_f32_16x16x32_bf16 v[118:121], v[210:213], v[172:175], v[118:121]
	v_mfma_f32_16x16x32_bf16 v[114:117], v[214:217], v[172:175], v[114:117]
	v_mfma_f32_16x16x32_bf16 v[110:113], v[202:205], v[176:179], v[110:113]
	v_mfma_f32_16x16x32_bf16 v[106:109], v[206:209], v[176:179], v[106:109]
	v_mfma_f32_16x16x32_bf16 v[102:105], v[210:213], v[176:179], v[102:105]
	v_mfma_f32_16x16x32_bf16 v[98:101], v[214:217], v[176:179], v[98:101]
	v_mfma_f32_16x16x32_bf16 v[90:93], v[202:205], v[182:185], v[90:93]
	v_mfma_f32_16x16x32_bf16 v[86:89], v[206:209], v[182:185], v[86:89]
	v_mfma_f32_16x16x32_bf16 v[82:85], v[210:213], v[182:185], v[82:85]
	v_mfma_f32_16x16x32_bf16 v[78:81], v[214:217], v[182:185], v[78:81]
	v_mfma_f32_16x16x32_bf16 v[74:77], v[202:205], v[186:189], v[74:77]
	v_mfma_f32_16x16x32_bf16 v[70:73], v[206:209], v[186:189], v[70:73]
	v_mfma_f32_16x16x32_bf16 v[66:69], v[210:213], v[186:189], v[66:69]
	v_mfma_f32_16x16x32_bf16 v[62:65], v[214:217], v[186:189], v[62:65]
	v_mfma_f32_16x16x32_bf16 v[58:61], v[202:205], v[190:193], v[58:61]
	v_mfma_f32_16x16x32_bf16 v[50:53], v[206:209], v[190:193], v[50:53]
	v_mfma_f32_16x16x32_bf16 v[46:49], v[210:213], v[190:193], v[46:49]
	v_mfma_f32_16x16x32_bf16 v[38:41], v[214:217], v[190:193], v[38:41]
	v_mfma_f32_16x16x32_bf16 v[30:33], v[202:205], v[198:201], v[30:33]
	v_mfma_f32_16x16x32_bf16 v[26:29], v[206:209], v[198:201], v[26:29]
	v_mfma_f32_16x16x32_bf16 v[22:25], v[210:213], v[198:201], v[22:25]
	v_mfma_f32_16x16x32_bf16 v[18:21], v[214:217], v[198:201], v[18:21]
	s_barrier
	s_waitcnt vmcnt(7)
	ds_write_b128 v163, v[34:37]
	s_waitcnt vmcnt(6)
	ds_write_b128 v163, v[42:45] offset:8192
	s_waitcnt vmcnt(5)
	ds_write_b128 v163, v[54:57] offset:16384
	s_waitcnt vmcnt(4)
	ds_write_b128 v163, v[94:97] offset:24576
	v_add3_u32 v176, s7, v0, v181
	ds_read_b128 v[34:37], v176
	ds_read_b128 v[42:45], v176 offset:2048
	ds_read_b128 v[54:57], v176 offset:4096
	ds_read_b128 v[94:97], v176 offset:6144
	ds_read_b128 v[164:167], v176 offset:8192
	ds_read_b128 v[168:171], v176 offset:10240
	ds_read_b128 v[172:175], v176 offset:12288
	ds_read_b128 v[176:179], v176 offset:14336
	v_add3_u32 v0, s2, v0, v180
	ds_read_b128 v[182:185], v0
	ds_read_b128 v[186:189], v0 offset:2048
	ds_read_b128 v[190:193], v0 offset:4096
	ds_read_b128 v[198:201], v0 offset:6144
	s_waitcnt lgkmcnt(3)
	v_mfma_f32_16x16x32_bf16 v[158:161], v[182:185], v[34:37], v[158:161]
	s_waitcnt lgkmcnt(2)
	v_mfma_f32_16x16x32_bf16 v[154:157], v[186:189], v[34:37], v[154:157]
	s_waitcnt lgkmcnt(1)
	v_mfma_f32_16x16x32_bf16 v[150:153], v[190:193], v[34:37], v[150:153]
	s_waitcnt lgkmcnt(0)
	v_mfma_f32_16x16x32_bf16 v[34:37], v[198:201], v[34:37], v[146:149]
	v_mfma_f32_16x16x32_bf16 v[142:145], v[182:185], v[42:45], v[142:145]
	v_mfma_f32_16x16x32_bf16 v[138:141], v[186:189], v[42:45], v[138:141]
	v_mfma_f32_16x16x32_bf16 v[134:137], v[190:193], v[42:45], v[134:137]
	v_mfma_f32_16x16x32_bf16 v[42:45], v[198:201], v[42:45], v[130:133]
	v_mfma_f32_16x16x32_bf16 v[130:133], v[182:185], v[54:57], v[126:129]
	v_mfma_f32_16x16x32_bf16 v[146:149], v[186:189], v[54:57], v[122:125]
	v_mfma_f32_16x16x32_bf16 v[202:205], v[190:193], v[54:57], v[118:121]
	v_mfma_f32_16x16x32_bf16 v[54:57], v[198:201], v[54:57], v[114:117]
	v_mfma_f32_16x16x32_bf16 v[206:209], v[182:185], v[94:97], v[110:113]
	v_mfma_f32_16x16x32_bf16 v[210:213], v[186:189], v[94:97], v[106:109]
	v_mfma_f32_16x16x32_bf16 v[214:217], v[190:193], v[94:97], v[102:105]
	v_mfma_f32_16x16x32_bf16 v[218:221], v[198:201], v[94:97], v[98:101]
	v_mfma_f32_16x16x32_bf16 v[222:225], v[182:185], v[164:167], v[90:93]
	v_mfma_f32_16x16x32_bf16 v[226:229], v[186:189], v[164:167], v[86:89]
	v_mfma_f32_16x16x32_bf16 v[230:233], v[190:193], v[164:167], v[82:85]
	v_mfma_f32_16x16x32_bf16 v[164:167], v[198:201], v[164:167], v[78:81]
	v_mfma_f32_16x16x32_bf16 v[234:237], v[182:185], v[168:171], v[74:77]
	v_mfma_f32_16x16x32_bf16 v[238:241], v[186:189], v[168:171], v[70:73]
	v_mfma_f32_16x16x32_bf16 v[242:245], v[190:193], v[168:171], v[66:69]
	v_mfma_f32_16x16x32_bf16 v[168:171], v[198:201], v[168:171], v[62:65]
	v_mfma_f32_16x16x32_bf16 v[246:249], v[182:185], v[172:175], v[58:61]
	v_mfma_f32_16x16x32_bf16 v[50:53], v[186:189], v[172:175], v[50:53]
	v_mfma_f32_16x16x32_bf16 v[46:49], v[190:193], v[172:175], v[46:49]
	v_mfma_f32_16x16x32_bf16 v[172:175], v[198:201], v[172:175], v[38:41]
	v_mfma_f32_16x16x32_bf16 v[182:185], v[182:185], v[176:179], v[30:33]
	v_mfma_f32_16x16x32_bf16 v[186:189], v[186:189], v[176:179], v[26:29]
	v_mfma_f32_16x16x32_bf16 v[190:193], v[190:193], v[176:179], v[22:25]
	v_mfma_f32_16x16x32_bf16 v[176:179], v[198:201], v[176:179], v[18:21]
	s_waitcnt vmcnt(3)
	ds_write_b128 v163, v[2:5] offset:32768
	s_waitcnt vmcnt(2)
	ds_write_b128 v163, v[6:9] offset:40960
	s_waitcnt vmcnt(1)
; DI int TID8() { int t = threadIdx.x; asm volatile("" : "+v"(t)); return t; }
; DI void gemm8_accum(f32x4 (&acc)[8][4], const bf16_t* a, size_t lda, const bf16_t* b, size_t ldb, int nkb, bf16_t* L,
;                     const bool pre, const bf16_t* an, size_t ldan, const bf16_t* bn, size_t ldbn) {
;     ...
;   g8_compute<0, 1>(acc, L + 32768, wm, wn, lane);
;   __builtin_amdgcn_sched_barrier(0);
;   g8_store1(L + 16384, rb, lrow, lch);
;   __builtin_amdgcn_sched_barrier(0);
;   g8_compute<1, 2>(acc, L + 32768, wm, wn, lane);
;   __syncthreads();
; DI void row_rs8(float (&rsv)[8], const float* rowpart, int m0) {
;   const int tid = TID8(), lane = tid & 63, wm = tid >> 8;
; #pragma unroll
;   for (int i = 0; i < 8; ++i) {
;     const int m = m0 + wm * 128 + i * 16 + (lane & 15);
;     float s = 0.f;
; #pragma unroll
;     for (int t = 0; t < 8; ++t) s += rowpart[(size_t)t * T_TOK + m];
;     rsv[i] = rsqrtf(s * (1.f / 1024.f) + 1e-6f);
;   }
	ds_write_b128 v163, v[10:13] offset:49152
	s_waitcnt vmcnt(0)
	ds_write_b128 v163, v[14:17] offset:57344
	v_add3_u32 v0, s7, v194, v181
	ds_read_b128 v[2:5], v0
	ds_read_b128 v[6:9], v0 offset:2048
	ds_read_b128 v[10:13], v0 offset:4096
	ds_read_b128 v[14:17], v0 offset:6144
	ds_read_b128 v[18:21], v0 offset:8192
	ds_read_b128 v[22:25], v0 offset:10240
	ds_read_b128 v[198:201], v0 offset:12288
	ds_read_b128 v[26:29], v0 offset:14336
	v_add3_u32 v0, s2, v194, v180
	ds_read_b128 v[30:33], v0
	ds_read_b128 v[38:41], v0 offset:2048
	ds_read_b128 v[58:61], v0 offset:4096
	ds_read_b128 v[62:65], v0 offset:6144
	s_waitcnt lgkmcnt(3)
	v_mfma_f32_16x16x32_bf16 v[126:129], v[30:33], v[2:5], v[158:161]
	s_waitcnt lgkmcnt(2)
	v_mfma_f32_16x16x32_bf16 v[122:125], v[38:41], v[2:5], v[154:157]
	s_waitcnt lgkmcnt(1)
	v_mfma_f32_16x16x32_bf16 v[118:121], v[58:61], v[2:5], v[150:153]
	s_waitcnt lgkmcnt(0)
	v_mfma_f32_16x16x32_bf16 v[114:117], v[62:65], v[2:5], v[34:37]
	v_mfma_f32_16x16x32_bf16 v[110:113], v[30:33], v[6:9], v[142:145]
	v_mfma_f32_16x16x32_bf16 v[106:109], v[38:41], v[6:9], v[138:141]
	v_mfma_f32_16x16x32_bf16 v[102:105], v[58:61], v[6:9], v[134:137]
	v_mfma_f32_16x16x32_bf16 v[98:101], v[62:65], v[6:9], v[42:45]
	v_mfma_f32_16x16x32_bf16 v[94:97], v[30:33], v[10:13], v[130:133]
	v_mfma_f32_16x16x32_bf16 v[90:93], v[38:41], v[10:13], v[146:149]
	v_mfma_f32_16x16x32_bf16 v[86:89], v[58:61], v[10:13], v[202:205]
	v_mfma_f32_16x16x32_bf16 v[82:85], v[62:65], v[10:13], v[54:57]
	v_mfma_f32_16x16x32_bf16 v[78:81], v[30:33], v[14:17], v[206:209]
	v_mfma_f32_16x16x32_bf16 v[74:77], v[38:41], v[14:17], v[210:213]
	v_mfma_f32_16x16x32_bf16 v[70:73], v[58:61], v[14:17], v[214:217]
	v_mfma_f32_16x16x32_bf16 v[66:69], v[62:65], v[14:17], v[218:221]
	v_mfma_f32_16x16x32_bf16 v[214:217], v[30:33], v[18:21], v[222:225]
	v_mfma_f32_16x16x32_bf16 v[210:213], v[38:41], v[18:21], v[226:229]
	v_mfma_f32_16x16x32_bf16 v[54:57], v[58:61], v[18:21], v[230:233]
	v_mfma_f32_16x16x32_bf16 v[158:161], v[62:65], v[18:21], v[164:167]
	v_mfma_f32_16x16x32_bf16 v[164:167], v[30:33], v[22:25], v[234:237]
	v_mfma_f32_16x16x32_bf16 v[42:45], v[38:41], v[22:25], v[238:241]
	v_mfma_f32_16x16x32_bf16 v[206:209], v[58:61], v[22:25], v[242:245]
	v_mfma_f32_16x16x32_bf16 v[34:37], v[62:65], v[22:25], v[168:171]
	v_mfma_f32_16x16x32_bf16 v[202:205], v[30:33], v[198:201], v[246:249]
	v_mfma_f32_16x16x32_bf16 v[168:171], v[38:41], v[198:201], v[50:53]
	v_mfma_f32_16x16x32_bf16 v[22:25], v[58:61], v[198:201], v[46:49]
	v_mfma_f32_16x16x32_bf16 v[18:21], v[62:65], v[198:201], v[172:175]
	v_mfma_f32_16x16x32_bf16 v[14:17], v[30:33], v[26:29], v[182:185]
	v_mfma_f32_16x16x32_bf16 v[10:13], v[38:41], v[26:29], v[186:189]
	v_mfma_f32_16x16x32_bf16 v[6:9], v[58:61], v[26:29], v[190:193]
	v_mfma_f32_16x16x32_bf16 v[2:5], v[62:65], v[26:29], v[176:179]
	v_mov_b32_e32 v0, v196
	s_barrier
	v_readlane_b32 s0, v251, 51
	v_ashrrev_i32_e32 v26, 1, v0
	v_and_b32_e32 v26, 0xffffff80, v26
	v_and_or_b32 v0, v0, 15, s13
	v_add_u32_e32 v26, v0, v26
	v_ashrrev_i32_e32 v27, 31, v26
	v_readlane_b32 s1, v251, 52
	s_mov_b32 s20, 0x3a800000
	s_mov_b32 s28, 0x45800000
	v_lshl_add_u64 v[148:149], v[26:27], 2, s[0:1]
	s_mov_b32 s0, 0x20000
	v_add_co_u32_e32 v146, vcc, s0, v148
	s_mov_b32 s0, 0x40000
	s_nop 0
	v_addc_co_u32_e32 v147, vcc, 0, v149, vcc
	v_add_co_u32_e32 v144, vcc, s0, v148
	s_mov_b32 s0, 0x60000
	s_nop 0
	v_addc_co_u32_e32 v145, vcc, 0, v149, vcc
	v_add_co_u32_e32 v142, vcc, s0, v148
	s_mov_b32 s0, 0x80000
	s_nop 0
	v_addc_co_u32_e32 v143, vcc, 0, v149, vcc
	v_add_co_u32_e32 v136, vcc, s0, v148
	s_mov_b32 s0, 0xa0000
	s_nop 0
	v_addc_co_u32_e32 v137, vcc, 0, v149, vcc
	v_add_co_u32_e32 v134, vcc, s0, v148
	s_mov_b32 s0, 0xc0000
	s_nop 0
	v_addc_co_u32_e32 v135, vcc, 0, v149, vcc
	v_add_co_u32_e32 v132, vcc, s0, v148
	s_mov_b32 s0, 0xe0000
	s_nop 0
	v_addc_co_u32_e32 v133, vcc, 0, v149, vcc
	v_add_co_u32_e32 v130, vcc, s0, v148
	global_load_dword v26, v[148:149], off
	global_load_dword v28, v[146:147], off
	global_load_dword v30, v[144:145], off
	global_load_dword v32, v[142:143], off
	global_load_dword v38, v[136:137], off
	global_load_dword v40, v[134:135], off
	global_load_dword v46, v[132:133], off
	v_addc_co_u32_e32 v131, vcc, 0, v149, vcc
	global_load_dword v48, v[130:131], off
	global_load_dword v27, v[148:149], off offset:64
	global_load_dword v29, v[146:147], off offset:64
	global_load_dword v31, v[144:145], off offset:64
	global_load_dword v33, v[142:143], off offset:64
	global_load_dword v39, v[136:137], off offset:64
	global_load_dword v41, v[134:135], off offset:64
	global_load_dword v47, v[132:133], off offset:64
	global_load_dword v49, v[130:131], off offset:64
	s_mov_b32 s0, 0x358637bd
	v_mov_b64_e32 v[140:141], s[0:1]
	s_mov_b32 s0, 0x800000
	s_add_i32 s9, s9, s21
	s_waitcnt vmcnt(7)
	v_pk_add_f32 v[26:27], v[26:27], 0 op_sel_hi:[1,0]
	s_waitcnt vmcnt(6)
	v_pk_add_f32 v[26:27], v[26:27], v[28:29]
	s_waitcnt vmcnt(5)
	v_pk_add_f32 v[26:27], v[26:27], v[30:31]
	s_waitcnt vmcnt(4)
	v_pk_add_f32 v[26:27], v[26:27], v[32:33]
	s_waitcnt vmcnt(3)
	v_pk_add_f32 v[26:27], v[26:27], v[38:39]
	s_waitcnt vmcnt(2)
	v_pk_add_f32 v[26:27], v[26:27], v[40:41]
	s_waitcnt vmcnt(1)
	v_pk_add_f32 v[26:27], v[26:27], v[46:47]
	s_waitcnt vmcnt(0)
; DI int TID8() { int t = threadIdx.x; asm volatile("" : "+v"(t)); return t; }
; DI void row_rs8(float (&rsv)[8], const float* rowpart, int m0) {
;   const int tid = TID8(), lane = tid & 63, wm = tid >> 8;
; #pragma unroll
;   for (int i = 0; i < 8; ++i) {
;     const int m = m0 + wm * 128 + i * 16 + (lane & 15);
;     float s = 0.f;
; #pragma unroll
;     for (int t = 0; t < 8; ++t) s += rowpart[(size_t)t * T_TOK + m];
;     rsv[i] = rsqrtf(s * (1.f / 1024.f) + 1e-6f);
;   }
	v_pk_add_f32 v[26:27], v[26:27], v[48:49]
	s_nop 0
	v_pk_fma_f32 v[26:27], v[26:27], s[20:21], v[140:141] op_sel_hi:[1,0,0]
	s_nop 0
	v_mul_f32_e32 v0, 0x4b800000, v26
	v_cmp_gt_f32_e64 s[2:3], s0, v26
	v_cmp_gt_f32_e32 vcc, s0, v27
	s_nop 0
	v_cndmask_b32_e64 v0, v26, v0, s[2:3]
	v_rsq_f32_e32 v26, v0
	v_mul_f32_e32 v0, 0x4b800000, v27
	v_cndmask_b32_e32 v0, v27, v0, vcc
	v_rsq_f32_e32 v27, v0
	s_nop 0
	v_pk_mul_f32 v[28:29], v[26:27], s[28:29] op_sel_hi:[1,0]
	s_nop 0
	v_cndmask_b32_e32 v0, v27, v29, vcc
	v_cndmask_b32_e64 v138, v26, v28, s[2:3]
	global_load_dword v26, v[148:149], off offset:128
	global_load_dword v28, v[146:147], off offset:128
	global_load_dword v30, v[144:145], off offset:128
	global_load_dword v32, v[142:143], off offset:128
	global_load_dword v38, v[136:137], off offset:128
	global_load_dword v40, v[134:135], off offset:128
	global_load_dword v46, v[132:133], off offset:128
	global_load_dword v48, v[130:131], off offset:128
	global_load_dword v27, v[148:149], off offset:192
	global_load_dword v29, v[146:147], off offset:192
	global_load_dword v31, v[144:145], off offset:192
	global_load_dword v33, v[142:143], off offset:192
	global_load_dword v39, v[136:137], off offset:192
	global_load_dword v41, v[134:135], off offset:192
	global_load_dword v47, v[132:133], off offset:192
	global_load_dword v49, v[130:131], off offset:192
	s_waitcnt vmcnt(7)
	v_pk_add_f32 v[26:27], v[26:27], 0 op_sel_hi:[1,0]
	s_waitcnt vmcnt(6)
	v_pk_add_f32 v[26:27], v[26:27], v[28:29]
	s_waitcnt vmcnt(5)
	v_pk_add_f32 v[26:27], v[26:27], v[30:31]
	s_waitcnt vmcnt(4)
	v_pk_add_f32 v[26:27], v[26:27], v[32:33]
	s_waitcnt vmcnt(3)
	v_pk_add_f32 v[26:27], v[26:27], v[38:39]
	s_waitcnt vmcnt(2)
	v_pk_add_f32 v[26:27], v[26:27], v[40:41]
	s_waitcnt vmcnt(1)
	v_pk_add_f32 v[26:27], v[26:27], v[46:47]
	s_waitcnt vmcnt(0)
	v_pk_add_f32 v[26:27], v[26:27], v[48:49]
	s_nop 0
	v_pk_fma_f32 v[26:27], v[26:27], s[20:21], v[140:141] op_sel_hi:[1,0,0]
	s_nop 0
	v_mul_f32_e32 v28, 0x4b800000, v26
	v_cmp_gt_f32_e64 s[2:3], s0, v26
	v_cmp_gt_f32_e32 vcc, s0, v27
	s_nop 0
	v_cndmask_b32_e64 v26, v26, v28, s[2:3]
	v_mul_f32_e32 v28, 0x4b800000, v27
	v_cndmask_b32_e32 v27, v27, v28, vcc
	v_rsq_f32_e32 v26, v26
	v_rsq_f32_e32 v27, v27
	s_nop 0
	v_pk_mul_f32 v[28:29], v[26:27], s[28:29] op_sel_hi:[1,0]
	s_nop 0
	v_cndmask_b32_e32 v150, v27, v29, vcc
	v_cndmask_b32_e64 v152, v26, v28, s[2:3]
	global_load_dword v26, v[148:149], off offset:256
	global_load_dword v28, v[146:147], off offset:256
	global_load_dword v30, v[144:145], off offset:256
	global_load_dword v32, v[142:143], off offset:256
	global_load_dword v38, v[136:137], off offset:256
	global_load_dword v40, v[134:135], off offset:256
	global_load_dword v46, v[132:133], off offset:256
	global_load_dword v48, v[130:131], off offset:256
	global_load_dword v27, v[148:149], off offset:320
	global_load_dword v29, v[146:147], off offset:320
	global_load_dword v31, v[144:145], off offset:320
	global_load_dword v33, v[142:143], off offset:320
	global_load_dword v39, v[136:137], off offset:320
	global_load_dword v41, v[134:135], off offset:320
	global_load_dword v47, v[132:133], off offset:320
	global_load_dword v49, v[130:131], off offset:320
	s_waitcnt vmcnt(7)
	v_pk_add_f32 v[26:27], v[26:27], 0 op_sel_hi:[1,0]
	s_waitcnt vmcnt(6)
	v_pk_add_f32 v[26:27], v[26:27], v[28:29]
	s_waitcnt vmcnt(5)
	v_pk_add_f32 v[26:27], v[26:27], v[30:31]
	s_waitcnt vmcnt(4)
	v_pk_add_f32 v[26:27], v[26:27], v[32:33]
	s_waitcnt vmcnt(3)
	v_pk_add_f32 v[26:27], v[26:27], v[38:39]
	s_waitcnt vmcnt(2)
	v_pk_add_f32 v[26:27], v[26:27], v[40:41]
	s_waitcnt vmcnt(1)
	v_pk_add_f32 v[26:27], v[26:27], v[46:47]
	s_waitcnt vmcnt(0)
	v_pk_add_f32 v[26:27], v[26:27], v[48:49]
	s_nop 0
	v_pk_fma_f32 v[26:27], v[26:27], s[20:21], v[140:141] op_sel_hi:[1,0,0]
	s_nop 0
	v_mul_f32_e32 v28, 0x4b800000, v26
	v_cmp_gt_f32_e64 s[2:3], s0, v26
	v_cmp_gt_f32_e32 vcc, s0, v27
	s_nop 0
	v_cndmask_b32_e64 v26, v26, v28, s[2:3]
	v_mul_f32_e32 v28, 0x4b800000, v27
	v_cndmask_b32_e32 v27, v27, v28, vcc
	v_rsq_f32_e32 v26, v26
	v_rsq_f32_e32 v27, v27
	s_nop 0
	v_pk_mul_f32 v[28:29], v[26:27], s[28:29] op_sel_hi:[1,0]
	s_nop 0
	v_cndmask_b32_e32 v154, v27, v29, vcc
	v_cndmask_b32_e64 v156, v26, v28, s[2:3]
	global_load_dword v26, v[148:149], off offset:384
	global_load_dword v28, v[146:147], off offset:384
	global_load_dword v30, v[144:145], off offset:384
	global_load_dword v32, v[142:143], off offset:384
	global_load_dword v38, v[136:137], off offset:384
	global_load_dword v40, v[134:135], off offset:384
	global_load_dword v46, v[132:133], off offset:384
	global_load_dword v48, v[130:131], off offset:384
	global_load_dword v27, v[148:149], off offset:448
	global_load_dword v29, v[146:147], off offset:448
	global_load_dword v31, v[144:145], off offset:448
	global_load_dword v33, v[142:143], off offset:448
	global_load_dword v39, v[136:137], off offset:448
	global_load_dword v41, v[134:135], off offset:448
	global_load_dword v47, v[132:133], off offset:448
	global_load_dword v49, v[130:131], off offset:448
	v_pk_mul_f32 v[134:135], v[128:129], v[138:139] op_sel_hi:[1,0]
	v_pk_mul_f32 v[128:129], v[124:125], v[138:139] op_sel_hi:[1,0]
	v_pk_mul_f32 v[132:133], v[122:123], v[138:139] op_sel_hi:[1,0]
	v_pk_mul_f32 v[122:123], v[120:121], v[138:139] op_sel_hi:[1,0]
	v_pk_mul_f32 v[124:125], v[118:119], v[138:139] op_sel_hi:[1,0]
	v_pk_mul_f32 v[118:119], v[116:117], v[138:139] op_sel_hi:[1,0]
	v_pk_mul_f32 v[120:121], v[114:115], v[138:139] op_sel_hi:[1,0]
	v_pk_mul_f32 v[114:115], v[112:113], v[0:1] op_sel_hi:[1,0]
	v_pk_mul_f32 v[116:117], v[110:111], v[0:1] op_sel_hi:[1,0]
; DI float bflo(unsigned u) { return __uint_as_float(u << 16); }
; DI float bfhi(unsigned u) { return __uint_as_float(u & 0xffff0000u); }
; DI float sigmoidf(float x) { return __builtin_amdgcn_rcpf(1.f + __expf(-x)); }
; DI void scale_rows8(f32x4 (&acc)[8][4], const float (&rsv)[8]) {
; #pragma unroll
;   for (int i = 0; i < 8; ++i)
; #pragma unroll
;     for (int j = 0; j < 4; ++j) acc[i][j] *= rsv[i];
; }
; __global__ void __launch_bounds__(512, 2) mega(Params p) {
;     ...
;       gemm8_epi(acc8, m0, n0, [&](int m, int n, f32x4& a) {
;         uint2 pv = *(const uint2*)(ppb + (size_t)m * DM + n);
;         float4* o = (float4*)(p.out + (size_t)m * DM + n);
;         float4 xv = *o;
;         *o = make_float4(xv.x + sigmoidf(a[0]) * bflo(pv.x), xv.y + sigmoidf(a[1]) * bfhi(pv.x),
;                          xv.z + sigmoidf(a[2]) * bflo(pv.y), xv.w + sigmoidf(a[3]) * bfhi(pv.y));
;       });
	v_pk_mul_f32 v[110:111], v[108:109], v[0:1] op_sel_hi:[1,0]
	v_pk_mul_f32 v[112:113], v[106:107], v[0:1] op_sel_hi:[1,0]
	v_pk_mul_f32 v[106:107], v[104:105], v[0:1] op_sel_hi:[1,0]
	v_pk_mul_f32 v[108:109], v[102:103], v[0:1] op_sel_hi:[1,0]
	v_pk_mul_f32 v[102:103], v[100:101], v[0:1] op_sel_hi:[1,0]
	v_pk_mul_f32 v[104:105], v[98:99], v[0:1] op_sel_hi:[1,0]
	v_mov_b32_e32 v0, v196
	v_pk_mul_f32 v[136:137], v[126:127], v[138:139] op_sel_hi:[1,0]
	v_pk_mul_f32 v[100:101], v[94:95], v[152:153] op_sel_hi:[1,0]
	v_pk_mul_f32 v[98:99], v[96:97], v[152:153] op_sel_hi:[1,0]
	v_pk_mul_f32 v[96:97], v[90:91], v[152:153] op_sel_hi:[1,0]
	v_pk_mul_f32 v[94:95], v[92:93], v[152:153] op_sel_hi:[1,0]
	v_pk_mul_f32 v[92:93], v[86:87], v[152:153] op_sel_hi:[1,0]
	v_pk_mul_f32 v[90:91], v[88:89], v[152:153] op_sel_hi:[1,0]
	v_pk_mul_f32 v[88:89], v[82:83], v[152:153] op_sel_hi:[1,0]
	v_pk_mul_f32 v[86:87], v[84:85], v[152:153] op_sel_hi:[1,0]
	v_pk_mul_f32 v[84:85], v[78:79], v[150:151] op_sel_hi:[1,0]
	v_pk_mul_f32 v[82:83], v[80:81], v[150:151] op_sel_hi:[1,0]
	v_pk_mul_f32 v[80:81], v[74:75], v[150:151] op_sel_hi:[1,0]
	v_pk_mul_f32 v[78:79], v[76:77], v[150:151] op_sel_hi:[1,0]
	v_pk_mul_f32 v[76:77], v[70:71], v[150:151] op_sel_hi:[1,0]
	v_pk_mul_f32 v[74:75], v[72:73], v[150:151] op_sel_hi:[1,0]
	v_pk_mul_f32 v[72:73], v[66:67], v[150:151] op_sel_hi:[1,0]
	v_pk_mul_f32 v[70:71], v[68:69], v[150:151] op_sel_hi:[1,0]
	v_pk_mul_f32 v[68:69], v[214:215], v[156:157] op_sel_hi:[1,0]
	v_pk_mul_f32 v[66:67], v[216:217], v[156:157] op_sel_hi:[1,0]
	v_pk_mul_f32 v[64:65], v[210:211], v[156:157] op_sel_hi:[1,0]
	v_pk_mul_f32 v[62:63], v[212:213], v[156:157] op_sel_hi:[1,0]
	v_pk_mul_f32 v[60:61], v[54:55], v[156:157] op_sel_hi:[1,0]
	v_pk_mul_f32 v[58:59], v[56:57], v[156:157] op_sel_hi:[1,0]
	v_pk_mul_f32 v[56:57], v[158:159], v[156:157] op_sel_hi:[1,0]
	v_pk_mul_f32 v[54:55], v[160:161], v[156:157] op_sel_hi:[1,0]
	v_pk_mul_f32 v[52:53], v[164:165], v[154:155] op_sel_hi:[1,0]
	v_pk_mul_f32 v[50:51], v[166:167], v[154:155] op_sel_hi:[1,0]
	s_waitcnt vmcnt(7)
	v_pk_add_f32 v[26:27], v[26:27], 0 op_sel_hi:[1,0]
	s_waitcnt vmcnt(6)
	v_pk_add_f32 v[26:27], v[26:27], v[28:29]
	s_waitcnt vmcnt(5)
	v_pk_add_f32 v[26:27], v[26:27], v[30:31]
	s_waitcnt vmcnt(4)
	v_pk_add_f32 v[26:27], v[26:27], v[32:33]
	s_waitcnt vmcnt(3)
	v_pk_add_f32 v[26:27], v[26:27], v[38:39]
	v_pk_mul_f32 v[38:39], v[36:37], v[154:155] op_sel_hi:[1,0]
	s_waitcnt vmcnt(2)
	v_pk_add_f32 v[26:27], v[26:27], v[40:41]
	v_pk_mul_f32 v[40:41], v[34:35], v[154:155] op_sel_hi:[1,0]
	s_waitcnt vmcnt(1)
	v_pk_add_f32 v[26:27], v[26:27], v[46:47]
	v_pk_mul_f32 v[46:47], v[44:45], v[154:155] op_sel_hi:[1,0]
	s_waitcnt vmcnt(0)
	v_pk_add_f32 v[26:27], v[26:27], v[48:49]
	v_pk_mul_f32 v[48:49], v[42:43], v[154:155] op_sel_hi:[1,0]
	v_pk_fma_f32 v[26:27], v[26:27], s[20:21], v[140:141] op_sel_hi:[1,0,0]
	v_pk_mul_f32 v[44:45], v[206:207], v[154:155] op_sel_hi:[1,0]
	v_mul_f32_e32 v28, 0x4b800000, v26
	v_cmp_gt_f32_e64 s[2:3], s0, v26
	v_cmp_gt_f32_e32 vcc, s0, v27
	v_pk_mul_f32 v[42:43], v[208:209], v[154:155] op_sel_hi:[1,0]
	v_cndmask_b32_e64 v26, v26, v28, s[2:3]
	v_mul_f32_e32 v28, 0x4b800000, v27
	v_cndmask_b32_e32 v27, v27, v28, vcc
	v_rsq_f32_e32 v26, v26
	v_rsq_f32_e32 v27, v27
	s_mov_b32 s20, s6
	v_pk_mul_f32 v[28:29], v[26:27], s[28:29] op_sel_hi:[1,0]
	s_nop 0
	v_cndmask_b32_e64 v28, v26, v28, s[2:3]
	v_cndmask_b32_e32 v130, v27, v29, vcc
	v_pk_mul_f32 v[26:27], v[22:23], v[28:29] op_sel_hi:[1,0]
	v_ashrrev_i32_e32 v23, 1, v0
	v_pk_mul_f32 v[34:35], v[204:205], v[28:29] op_sel_hi:[1,0]
	v_pk_mul_f32 v[36:37], v[202:203], v[28:29] op_sel_hi:[1,0]
	v_pk_mul_f32 v[30:31], v[170:171], v[28:29] op_sel_hi:[1,0]
	v_pk_mul_f32 v[32:33], v[168:169], v[28:29] op_sel_hi:[1,0]
	v_pk_mul_f32 v[24:25], v[24:25], v[28:29] op_sel_hi:[1,0]
	v_pk_mul_f32 v[20:21], v[20:21], v[28:29] op_sel_hi:[1,0]
	v_pk_mul_f32 v[18:19], v[18:19], v[28:29] op_sel_hi:[1,0]
	v_and_b32_e32 v22, 0xc0, v0
	v_and_b32_e32 v23, 0xffffff80, v23
	v_and_or_b32 v28, v0, 15, s13
	v_lshrrev_b32_e32 v0, 2, v0
	v_add_u32_e32 v28, v28, v23
	v_and_b32_e32 v0, 12, v0
	v_or3_b32 v140, v22, v0, s12
	v_ashrrev_i32_e32 v29, 31, v28
	v_readlane_b32 s12, v252, 47
	v_lshlrev_b64 v[22:23], 11, v[28:29]
	v_readlane_b32 s13, v252, 48
	v_lshlrev_b32_e32 v0, 1, v140
	v_pk_mul_f32 v[16:17], v[16:17], v[130:131] op_sel_hi:[1,0]
	v_lshl_add_u64 v[22:23], s[12:13], 0, v[22:23]
	v_pk_mul_f32 v[14:15], v[14:15], v[130:131] op_sel_hi:[1,0]
	v_pk_mul_f32 v[12:13], v[12:13], v[130:131] op_sel_hi:[1,0]
	v_pk_mul_f32 v[10:11], v[10:11], v[130:131] op_sel_hi:[1,0]
	v_pk_mul_f32 v[8:9], v[8:9], v[130:131] op_sel_hi:[1,0]
	v_pk_mul_f32 v[6:7], v[6:7], v[130:131] op_sel_hi:[1,0]
	v_pk_mul_f32 v[4:5], v[4:5], v[130:131] op_sel_hi:[1,0]
	v_pk_mul_f32 v[2:3], v[2:3], v[130:131] op_sel_hi:[1,0]
	v_lshl_add_u64 v[130:131], v[22:23], 0, v[0:1]
	v_lshlrev_b64 v[22:23], 12, v[28:29]
	v_mul_f32_e32 v29, 0xbfb8aa3b, v136
	v_exp_f32_e32 v29, v29
	v_readlane_b32 s0, v251, 33
	v_readlane_b32 s2, v251, 35
	v_readlane_b32 s3, v251, 36
	v_add_f32_e32 v29, 1.0, v29
	global_load_dwordx2 v[138:139], v[130:131], off
	v_lshl_add_u64 v[126:127], s[2:3], 0, v[22:23]
	v_lshlrev_b32_e32 v22, 2, v140
	v_rcp_f32_e32 v140, v29
	v_mul_f32_e32 v29, 0xbfb8aa3b, v137
	v_exp_f32_e32 v29, v29
	v_mov_b32_e32 v23, v1
	v_lshl_add_u64 v[126:127], v[126:127], 0, v[22:23]
	v_mul_f32_e32 v26, 0xbfb8aa3b, v26
	v_add_f32_e32 v29, 1.0, v29
	v_rcp_f32_e32 v141, v29
	v_mul_f32_e32 v29, 0xbfb8aa3b, v134
	v_exp_f32_e32 v29, v29
	v_mul_f32_e32 v24, 0xbfb8aa3b, v24
	v_exp_f32_e32 v26, v26
	v_exp_f32_e32 v24, v24
	v_add_f32_e32 v29, 1.0, v29
	v_rcp_f32_e32 v144, v29
	v_mul_f32_e32 v29, 0xbfb8aa3b, v135
	global_load_dwordx4 v[134:137], v[126:127], off
	v_exp_f32_e32 v29, v29
	v_add_f32_e32 v26, 1.0, v26
	v_add_f32_e32 v24, 1.0, v24
	v_mul_f32_e32 v18, 0xbfb8aa3b, v18
	v_add_f32_e32 v29, 1.0, v29
	v_rcp_f32_e32 v145, v29
	v_mul_f32_e32 v29, 0xbfb8aa3b, v132
	v_exp_f32_e32 v29, v29
	v_exp_f32_e32 v18, v18
	v_readlane_b32 s0, v254, 13
	v_readlane_b32 s1, v251, 34
	v_add_f32_e32 v29, 1.0, v29
	v_rcp_f32_e32 v132, v29
	v_mul_f32_e32 v29, 0xbfb8aa3b, v133
	v_exp_f32_e32 v29, v29
	v_add_f32_e32 v18, 1.0, v18
	s_add_i32 s11, s11, s0
	v_readlane_b32 s0, v254, 19
	v_add_f32_e32 v29, 1.0, v29
	v_rcp_f32_e32 v133, v29
	v_mul_f32_e32 v29, 0xbfb8aa3b, v128
	v_exp_f32_e32 v29, v29
	s_add_i32 s10, s10, s0
	s_mov_b64 s[0:1], -1
	s_and_b64 vcc, s[4:5], exec
	v_add_f32_e32 v29, 1.0, v29
	v_rcp_f32_e32 v128, v29
	v_mul_f32_e32 v29, 0xbfb8aa3b, v129
	v_exp_f32_e32 v29, v29
	s_waitcnt vmcnt(1)
; DI float bflo(unsigned u) { return __uint_as_float(u << 16); }
; DI float bfhi(unsigned u) { return __uint_as_float(u & 0xffff0000u); }
; DI float sigmoidf(float x) { return __builtin_amdgcn_rcpf(1.f + __expf(-x)); }
; __global__ void __launch_bounds__(512, 2) mega(Params p) {
;     ...
;       gemm8_epi(acc8, m0, n0, [&](int m, int n, f32x4& a) {
;         uint2 pv = *(const uint2*)(ppb + (size_t)m * DM + n);
;         float4* o = (float4*)(p.out + (size_t)m * DM + n);
;         float4 xv = *o;
;         *o = make_float4(xv.x + sigmoidf(a[0]) * bflo(pv.x), xv.y + sigmoidf(a[1]) * bfhi(pv.x),
;                          xv.z + sigmoidf(a[2]) * bflo(pv.y), xv.w + sigmoidf(a[3]) * bfhi(pv.y));
;       });
	v_lshlrev_b32_e32 v142, 16, v138
	v_and_b32_e32 v143, 0xffff0000, v138
	v_lshlrev_b32_e32 v138, 16, v139
	v_and_b32_e32 v139, 0xffff0000, v139
	v_add_f32_e32 v29, 1.0, v29
	v_rcp_f32_e32 v129, v29
	v_mul_f32_e32 v29, 0xbfb8aa3b, v124
	v_exp_f32_e32 v29, v29
	s_waitcnt vmcnt(0)
	v_pk_fma_f32 v[134:135], v[140:141], v[142:143], v[134:135]
	v_pk_fma_f32 v[136:137], v[144:145], v[138:139], v[136:137]
	global_store_dwordx4 v[126:127], v[134:137], off
	global_load_dwordx2 v[136:137], v[130:131], off offset:32
	v_add_f32_e32 v29, 1.0, v29
	global_load_dwordx4 v[138:141], v[126:127], off offset:64
	s_waitcnt vmcnt(1)
	v_lshlrev_b32_e32 v134, 16, v136
	v_and_b32_e32 v135, 0xffff0000, v136
	v_lshlrev_b32_e32 v136, 16, v137
	v_and_b32_e32 v137, 0xffff0000, v137
	s_waitcnt vmcnt(0)
	v_pk_fma_f32 v[132:133], v[132:133], v[134:135], v[138:139]
	v_pk_fma_f32 v[134:135], v[128:129], v[136:137], v[140:141]
	global_store_dwordx4 v[126:127], v[132:135], off offset:64
	global_load_dwordx2 v[128:129], v[130:131], off offset:64
	s_nop 0
	v_rcp_f32_e32 v132, v29
	v_mul_f32_e32 v29, 0xbfb8aa3b, v125
	v_exp_f32_e32 v29, v29
	s_waitcnt vmcnt(0)
	v_lshlrev_b32_e32 v134, 16, v128
	v_add_f32_e32 v29, 1.0, v29
	v_rcp_f32_e32 v133, v29
	v_mul_f32_e32 v29, 0xbfb8aa3b, v122
	v_exp_f32_e32 v29, v29
	v_and_b32_e32 v135, 0xffff0000, v128
	v_lshlrev_b32_e32 v128, 16, v129
	v_and_b32_e32 v129, 0xffff0000, v129
	v_add_f32_e32 v29, 1.0, v29
	v_rcp_f32_e32 v136, v29
	v_mul_f32_e32 v29, 0xbfb8aa3b, v123
	global_load_dwordx4 v[122:125], v[126:127], off offset:128
	v_exp_f32_e32 v29, v29
	s_waitcnt vmcnt(0)
	v_pk_fma_f32 v[122:123], v[132:133], v[134:135], v[122:123]
	v_add_f32_e32 v29, 1.0, v29
	v_rcp_f32_e32 v137, v29
	v_mul_f32_e32 v29, 0xbfb8aa3b, v120
	v_exp_f32_e32 v29, v29
	v_pk_fma_f32 v[124:125], v[136:137], v[128:129], v[124:125]
	global_store_dwordx4 v[126:127], v[122:125], off offset:128
	v_add_f32_e32 v29, 1.0, v29
	global_load_dwordx2 v[122:123], v[130:131], off offset:96
	v_rcp_f32_e32 v124, v29
	v_mul_f32_e32 v29, 0xbfb8aa3b, v121
	v_exp_f32_e32 v29, v29
	s_waitcnt vmcnt(0)
	v_lshlrev_b32_e32 v128, 16, v122
	v_add_f32_e32 v29, 1.0, v29
	v_rcp_f32_e32 v125, v29
	v_mul_f32_e32 v29, 0xbfb8aa3b, v118
	v_exp_f32_e32 v29, v29
	v_and_b32_e32 v129, 0xffff0000, v122
	v_lshlrev_b32_e32 v122, 16, v123
	v_and_b32_e32 v123, 0xffff0000, v123
	v_add_f32_e32 v29, 1.0, v29
	v_rcp_f32_e32 v130, v29
	v_mul_f32_e32 v29, 0xbfb8aa3b, v119
	global_load_dwordx4 v[118:121], v[126:127], off offset:192
	v_exp_f32_e32 v29, v29
	s_waitcnt vmcnt(0)
	v_pk_fma_f32 v[118:119], v[124:125], v[128:129], v[118:119]
	v_add_f32_e32 v29, 1.0, v29
	v_rcp_f32_e32 v131, v29
	v_mul_f32_e32 v29, 0xbfb8aa3b, v116
	v_exp_f32_e32 v29, v29
	v_pk_fma_f32 v[120:121], v[130:131], v[122:123], v[120:121]
	global_store_dwordx4 v[126:127], v[118:121], off offset:192
	v_add_f32_e32 v29, 1.0, v29
	v_rcp_f32_e32 v124, v29
	v_mul_f32_e32 v29, 0xbfb8aa3b, v117
	v_exp_f32_e32 v29, v29
	v_or_b32_e32 v118, 16, v28
	v_ashrrev_i32_e32 v119, 31, v118
	v_lshlrev_b64 v[120:121], 11, v[118:119]
	v_add_f32_e32 v29, 1.0, v29
	v_rcp_f32_e32 v125, v29
	v_mul_f32_e32 v29, 0xbfb8aa3b, v114
	v_exp_f32_e32 v29, v29
	v_lshl_add_u64 v[120:121], s[12:13], 0, v[120:121]
	v_lshlrev_b64 v[118:119], 12, v[118:119]
	v_lshl_add_u64 v[120:121], v[120:121], 0, v[0:1]
	v_lshl_add_u64 v[118:119], s[2:3], 0, v[118:119]
	global_load_dwordx2 v[122:123], v[120:121], off
	v_lshl_add_u64 v[118:119], v[118:119], 0, v[22:23]
	v_add_f32_e32 v29, 1.0, v29
	v_rcp_f32_e32 v128, v29
	v_mul_f32_e32 v29, 0xbfb8aa3b, v115
	global_load_dwordx4 v[114:117], v[118:119], off
	v_exp_f32_e32 v29, v29
	s_waitcnt vmcnt(1)
	v_lshlrev_b32_e32 v126, 16, v122
	v_add_f32_e32 v29, 1.0, v29
	v_rcp_f32_e32 v129, v29
	v_and_b32_e32 v127, 0xffff0000, v122
	v_lshlrev_b32_e32 v122, 16, v123
	v_and_b32_e32 v123, 0xffff0000, v123
	s_waitcnt vmcnt(0)
	v_pk_fma_f32 v[114:115], v[124:125], v[126:127], v[114:115]
	v_pk_fma_f32 v[116:117], v[128:129], v[122:123], v[116:117]
	global_store_dwordx4 v[118:119], v[114:117], off
	global_load_dwordx2 v[116:117], v[120:121], off offset:32
	v_mul_f32_e32 v29, 0xbfb8aa3b, v112
	global_load_dwordx4 v[122:125], v[118:119], off offset:64
	v_exp_f32_e32 v29, v29
	s_waitcnt vmcnt(1)
	v_lshlrev_b32_e32 v114, 16, v116
	v_add_f32_e32 v29, 1.0, v29
	v_rcp_f32_e32 v112, v29
	v_mul_f32_e32 v29, 0xbfb8aa3b, v113
	v_exp_f32_e32 v29, v29
	v_and_b32_e32 v115, 0xffff0000, v116
	v_lshlrev_b32_e32 v116, 16, v117
	v_and_b32_e32 v117, 0xffff0000, v117
	v_add_f32_e32 v29, 1.0, v29
	v_rcp_f32_e32 v113, v29
	v_mul_f32_e32 v29, 0xbfb8aa3b, v110
	v_exp_f32_e32 v29, v29
	s_waitcnt vmcnt(0)
	v_pk_fma_f32 v[112:113], v[112:113], v[114:115], v[122:123]
	v_add_f32_e32 v29, 1.0, v29
	v_rcp_f32_e32 v110, v29
	v_mul_f32_e32 v29, 0xbfb8aa3b, v111
	v_exp_f32_e32 v29, v29
	s_nop 0
	v_add_f32_e32 v29, 1.0, v29
	v_rcp_f32_e32 v111, v29
	v_mul_f32_e32 v29, 0xbfb8aa3b, v108
	v_exp_f32_e32 v29, v29
	v_pk_fma_f32 v[114:115], v[110:111], v[116:117], v[124:125]
	global_store_dwordx4 v[118:119], v[112:115], off offset:64
	v_add_f32_e32 v29, 1.0, v29
	global_load_dwordx2 v[110:111], v[120:121], off offset:64
	v_rcp_f32_e32 v112, v29
	v_mul_f32_e32 v29, 0xbfb8aa3b, v109
	v_exp_f32_e32 v29, v29
	s_waitcnt vmcnt(0)
	v_lshlrev_b32_e32 v114, 16, v110
	v_add_f32_e32 v29, 1.0, v29
	v_rcp_f32_e32 v113, v29
	v_mul_f32_e32 v29, 0xbfb8aa3b, v106
	v_exp_f32_e32 v29, v29
	v_and_b32_e32 v115, 0xffff0000, v110
	v_lshlrev_b32_e32 v110, 16, v111
	v_and_b32_e32 v111, 0xffff0000, v111
	v_add_f32_e32 v29, 1.0, v29
	v_rcp_f32_e32 v116, v29
	v_mul_f32_e32 v29, 0xbfb8aa3b, v107
	global_load_dwordx4 v[106:109], v[118:119], off offset:128
	v_exp_f32_e32 v29, v29
	s_waitcnt vmcnt(0)
; DI float bflo(unsigned u) { return __uint_as_float(u << 16); }
; DI float bfhi(unsigned u) { return __uint_as_float(u & 0xffff0000u); }
; DI float sigmoidf(float x) { return __builtin_amdgcn_rcpf(1.f + __expf(-x)); }
; __global__ void __launch_bounds__(512, 2) mega(Params p) {
;     ...
;       gemm8_epi(acc8, m0, n0, [&](int m, int n, f32x4& a) {
;         uint2 pv = *(const uint2*)(ppb + (size_t)m * DM + n);
;         float4* o = (float4*)(p.out + (size_t)m * DM + n);
;         float4 xv = *o;
;         *o = make_float4(xv.x + sigmoidf(a[0]) * bflo(pv.x), xv.y + sigmoidf(a[1]) * bfhi(pv.x),
;                          xv.z + sigmoidf(a[2]) * bflo(pv.y), xv.w + sigmoidf(a[3]) * bfhi(pv.y));
;       });
	v_pk_fma_f32 v[106:107], v[112:113], v[114:115], v[106:107]
	v_add_f32_e32 v29, 1.0, v29
	v_rcp_f32_e32 v117, v29
	v_mul_f32_e32 v29, 0xbfb8aa3b, v104
	v_exp_f32_e32 v29, v29
	v_pk_fma_f32 v[108:109], v[116:117], v[110:111], v[108:109]
	global_store_dwordx4 v[118:119], v[106:109], off offset:128
	v_add_f32_e32 v29, 1.0, v29
	global_load_dwordx2 v[106:107], v[120:121], off offset:96
	v_rcp_f32_e32 v108, v29
	v_mul_f32_e32 v29, 0xbfb8aa3b, v105
	v_exp_f32_e32 v29, v29
	s_waitcnt vmcnt(0)
	v_lshlrev_b32_e32 v110, 16, v106
	v_add_f32_e32 v29, 1.0, v29
	v_rcp_f32_e32 v109, v29
	v_mul_f32_e32 v29, 0xbfb8aa3b, v102
	v_exp_f32_e32 v29, v29
	v_and_b32_e32 v111, 0xffff0000, v106
	v_lshlrev_b32_e32 v106, 16, v107
	v_and_b32_e32 v107, 0xffff0000, v107
	v_add_f32_e32 v29, 1.0, v29
	v_rcp_f32_e32 v112, v29
	v_mul_f32_e32 v29, 0xbfb8aa3b, v103
	global_load_dwordx4 v[102:105], v[118:119], off offset:192
	v_exp_f32_e32 v29, v29
	s_waitcnt vmcnt(0)
	v_pk_fma_f32 v[102:103], v[108:109], v[110:111], v[102:103]
	v_add_f32_e32 v29, 1.0, v29
	v_rcp_f32_e32 v113, v29
	v_mul_f32_e32 v29, 0xbfb8aa3b, v100
	v_exp_f32_e32 v29, v29
	v_pk_fma_f32 v[104:105], v[112:113], v[106:107], v[104:105]
	global_store_dwordx4 v[118:119], v[102:105], off offset:192
	v_add_f32_e32 v29, 1.0, v29
	v_rcp_f32_e32 v108, v29
	v_mul_f32_e32 v29, 0xbfb8aa3b, v101
	v_exp_f32_e32 v29, v29
	v_or_b32_e32 v102, 32, v28
	v_ashrrev_i32_e32 v103, 31, v102
	v_lshlrev_b64 v[104:105], 11, v[102:103]
	v_add_f32_e32 v29, 1.0, v29
	v_rcp_f32_e32 v109, v29
	v_mul_f32_e32 v29, 0xbfb8aa3b, v98
	v_exp_f32_e32 v29, v29
	v_lshl_add_u64 v[104:105], s[12:13], 0, v[104:105]
	v_lshlrev_b64 v[102:103], 12, v[102:103]
	v_lshl_add_u64 v[104:105], v[104:105], 0, v[0:1]
	v_lshl_add_u64 v[102:103], s[2:3], 0, v[102:103]
	global_load_dwordx2 v[106:107], v[104:105], off
	v_lshl_add_u64 v[102:103], v[102:103], 0, v[22:23]
	v_add_f32_e32 v29, 1.0, v29
	v_rcp_f32_e32 v112, v29
	v_mul_f32_e32 v29, 0xbfb8aa3b, v99
	global_load_dwordx4 v[98:101], v[102:103], off
	v_exp_f32_e32 v29, v29
	s_waitcnt vmcnt(1)
	v_lshlrev_b32_e32 v110, 16, v106
	v_add_f32_e32 v29, 1.0, v29
	v_rcp_f32_e32 v113, v29
	v_and_b32_e32 v111, 0xffff0000, v106
	v_lshlrev_b32_e32 v106, 16, v107
	v_and_b32_e32 v107, 0xffff0000, v107
	s_waitcnt vmcnt(0)
	v_pk_fma_f32 v[98:99], v[108:109], v[110:111], v[98:99]
	v_pk_fma_f32 v[100:101], v[112:113], v[106:107], v[100:101]
	global_store_dwordx4 v[102:103], v[98:101], off
	global_load_dwordx2 v[100:101], v[104:105], off offset:32
	v_mul_f32_e32 v29, 0xbfb8aa3b, v96
	global_load_dwordx4 v[106:109], v[102:103], off offset:64
	v_exp_f32_e32 v29, v29
	s_waitcnt vmcnt(1)
	v_lshlrev_b32_e32 v98, 16, v100
	v_add_f32_e32 v29, 1.0, v29
	v_rcp_f32_e32 v96, v29
	v_mul_f32_e32 v29, 0xbfb8aa3b, v97
	v_exp_f32_e32 v29, v29
	v_and_b32_e32 v99, 0xffff0000, v100
	v_lshlrev_b32_e32 v100, 16, v101
	v_and_b32_e32 v101, 0xffff0000, v101
	v_add_f32_e32 v29, 1.0, v29
	v_rcp_f32_e32 v97, v29
	v_mul_f32_e32 v29, 0xbfb8aa3b, v94
	v_exp_f32_e32 v29, v29
	s_waitcnt vmcnt(0)
	v_pk_fma_f32 v[96:97], v[96:97], v[98:99], v[106:107]
	v_add_f32_e32 v29, 1.0, v29
	v_rcp_f32_e32 v94, v29
	v_mul_f32_e32 v29, 0xbfb8aa3b, v95
	v_exp_f32_e32 v29, v29
	s_nop 0
	v_add_f32_e32 v29, 1.0, v29
	v_rcp_f32_e32 v95, v29
	v_mul_f32_e32 v29, 0xbfb8aa3b, v92
	v_exp_f32_e32 v29, v29
	v_pk_fma_f32 v[98:99], v[94:95], v[100:101], v[108:109]
	global_store_dwordx4 v[102:103], v[96:99], off offset:64
	v_add_f32_e32 v29, 1.0, v29
	global_load_dwordx2 v[94:95], v[104:105], off offset:64
	v_rcp_f32_e32 v96, v29
	v_mul_f32_e32 v29, 0xbfb8aa3b, v93
	v_exp_f32_e32 v29, v29
	s_waitcnt vmcnt(0)
	v_lshlrev_b32_e32 v98, 16, v94
	v_add_f32_e32 v29, 1.0, v29
	v_rcp_f32_e32 v97, v29
	v_mul_f32_e32 v29, 0xbfb8aa3b, v90
	v_exp_f32_e32 v29, v29
	v_and_b32_e32 v99, 0xffff0000, v94
	v_lshlrev_b32_e32 v94, 16, v95
	v_and_b32_e32 v95, 0xffff0000, v95
	v_add_f32_e32 v29, 1.0, v29
	v_rcp_f32_e32 v100, v29
	v_mul_f32_e32 v29, 0xbfb8aa3b, v91
	global_load_dwordx4 v[90:93], v[102:103], off offset:128
	v_exp_f32_e32 v29, v29
	s_waitcnt vmcnt(0)
	v_pk_fma_f32 v[90:91], v[96:97], v[98:99], v[90:91]
	v_add_f32_e32 v29, 1.0, v29
	v_rcp_f32_e32 v101, v29
	v_mul_f32_e32 v29, 0xbfb8aa3b, v88
	v_exp_f32_e32 v29, v29
	v_pk_fma_f32 v[92:93], v[100:101], v[94:95], v[92:93]
	global_store_dwordx4 v[102:103], v[90:93], off offset:128
	v_add_f32_e32 v29, 1.0, v29
	global_load_dwordx2 v[90:91], v[104:105], off offset:96
	v_rcp_f32_e32 v92, v29
	v_mul_f32_e32 v29, 0xbfb8aa3b, v89
	v_exp_f32_e32 v29, v29
	s_waitcnt vmcnt(0)
	v_lshlrev_b32_e32 v94, 16, v90
	v_add_f32_e32 v29, 1.0, v29
	v_rcp_f32_e32 v93, v29
	v_mul_f32_e32 v29, 0xbfb8aa3b, v86
	v_exp_f32_e32 v29, v29
	v_and_b32_e32 v95, 0xffff0000, v90
	v_lshlrev_b32_e32 v90, 16, v91
	v_and_b32_e32 v91, 0xffff0000, v91
	v_add_f32_e32 v29, 1.0, v29
	v_rcp_f32_e32 v96, v29
	v_mul_f32_e32 v29, 0xbfb8aa3b, v87
	global_load_dwordx4 v[86:89], v[102:103], off offset:192
	v_exp_f32_e32 v29, v29
	s_waitcnt vmcnt(0)
	v_pk_fma_f32 v[86:87], v[92:93], v[94:95], v[86:87]
	v_add_f32_e32 v29, 1.0, v29
	v_rcp_f32_e32 v97, v29
	v_mul_f32_e32 v29, 0xbfb8aa3b, v84
	v_exp_f32_e32 v29, v29
	v_pk_fma_f32 v[88:89], v[96:97], v[90:91], v[88:89]
	global_store_dwordx4 v[102:103], v[86:89], off offset:192
	v_add_f32_e32 v29, 1.0, v29
	v_rcp_f32_e32 v92, v29
	v_mul_f32_e32 v29, 0xbfb8aa3b, v85
	v_exp_f32_e32 v29, v29
	v_or_b32_e32 v86, 48, v28
	v_ashrrev_i32_e32 v87, 31, v86
	v_lshlrev_b64 v[88:89], 11, v[86:87]
	v_add_f32_e32 v29, 1.0, v29
	v_rcp_f32_e32 v93, v29
	v_mul_f32_e32 v29, 0xbfb8aa3b, v82
	v_exp_f32_e32 v29, v29
	v_lshl_add_u64 v[88:89], s[12:13], 0, v[88:89]
	v_lshlrev_b64 v[86:87], 12, v[86:87]
	v_lshl_add_u64 v[88:89], v[88:89], 0, v[0:1]
	v_lshl_add_u64 v[86:87], s[2:3], 0, v[86:87]
	global_load_dwordx2 v[90:91], v[88:89], off
	v_lshl_add_u64 v[86:87], v[86:87], 0, v[22:23]
	v_add_f32_e32 v29, 1.0, v29
	v_rcp_f32_e32 v96, v29
	v_mul_f32_e32 v29, 0xbfb8aa3b, v83
	global_load_dwordx4 v[82:85], v[86:87], off
	v_exp_f32_e32 v29, v29
	s_waitcnt vmcnt(1)
; DI float bflo(unsigned u) { return __uint_as_float(u << 16); }
; DI float bfhi(unsigned u) { return __uint_as_float(u & 0xffff0000u); }
; DI float sigmoidf(float x) { return __builtin_amdgcn_rcpf(1.f + __expf(-x)); }
; __global__ void __launch_bounds__(512, 2) mega(Params p) {
;     ...
;       gemm8_epi(acc8, m0, n0, [&](int m, int n, f32x4& a) {
;         uint2 pv = *(const uint2*)(ppb + (size_t)m * DM + n);
;         float4* o = (float4*)(p.out + (size_t)m * DM + n);
;         float4 xv = *o;
;         *o = make_float4(xv.x + sigmoidf(a[0]) * bflo(pv.x), xv.y + sigmoidf(a[1]) * bfhi(pv.x),
;                          xv.z + sigmoidf(a[2]) * bflo(pv.y), xv.w + sigmoidf(a[3]) * bfhi(pv.y));
;       });
	v_lshlrev_b32_e32 v94, 16, v90
	v_add_f32_e32 v29, 1.0, v29
	v_rcp_f32_e32 v97, v29
	v_and_b32_e32 v95, 0xffff0000, v90
	v_lshlrev_b32_e32 v90, 16, v91
	v_and_b32_e32 v91, 0xffff0000, v91
	s_waitcnt vmcnt(0)
	v_pk_fma_f32 v[82:83], v[92:93], v[94:95], v[82:83]
	v_pk_fma_f32 v[84:85], v[96:97], v[90:91], v[84:85]
	global_store_dwordx4 v[86:87], v[82:85], off
	global_load_dwordx2 v[84:85], v[88:89], off offset:32
	v_mul_f32_e32 v29, 0xbfb8aa3b, v80
	global_load_dwordx4 v[90:93], v[86:87], off offset:64
	v_exp_f32_e32 v29, v29
	s_waitcnt vmcnt(1)
	v_lshlrev_b32_e32 v82, 16, v84
	v_add_f32_e32 v29, 1.0, v29
	v_rcp_f32_e32 v80, v29
	v_mul_f32_e32 v29, 0xbfb8aa3b, v81
	v_exp_f32_e32 v29, v29
	v_and_b32_e32 v83, 0xffff0000, v84
	v_lshlrev_b32_e32 v84, 16, v85
	v_and_b32_e32 v85, 0xffff0000, v85
	v_add_f32_e32 v29, 1.0, v29
	v_rcp_f32_e32 v81, v29
	v_mul_f32_e32 v29, 0xbfb8aa3b, v78
	v_exp_f32_e32 v29, v29
	s_waitcnt vmcnt(0)
	v_pk_fma_f32 v[80:81], v[80:81], v[82:83], v[90:91]
	v_add_f32_e32 v29, 1.0, v29
	v_rcp_f32_e32 v78, v29
	v_mul_f32_e32 v29, 0xbfb8aa3b, v79
	v_exp_f32_e32 v29, v29
	s_nop 0
	v_add_f32_e32 v29, 1.0, v29
	v_rcp_f32_e32 v79, v29
	v_mul_f32_e32 v29, 0xbfb8aa3b, v76
	v_exp_f32_e32 v29, v29
	v_pk_fma_f32 v[82:83], v[78:79], v[84:85], v[92:93]
	global_store_dwordx4 v[86:87], v[80:83], off offset:64
	v_add_f32_e32 v29, 1.0, v29
	global_load_dwordx2 v[78:79], v[88:89], off offset:64
	v_rcp_f32_e32 v80, v29
	v_mul_f32_e32 v29, 0xbfb8aa3b, v77
	v_exp_f32_e32 v29, v29
	s_waitcnt vmcnt(0)
	v_lshlrev_b32_e32 v82, 16, v78
	v_add_f32_e32 v29, 1.0, v29
	v_rcp_f32_e32 v81, v29
	v_mul_f32_e32 v29, 0xbfb8aa3b, v74
	v_exp_f32_e32 v29, v29
	v_and_b32_e32 v83, 0xffff0000, v78
	v_lshlrev_b32_e32 v78, 16, v79
	v_and_b32_e32 v79, 0xffff0000, v79
	v_add_f32_e32 v29, 1.0, v29
	v_rcp_f32_e32 v84, v29
	v_mul_f32_e32 v29, 0xbfb8aa3b, v75
	global_load_dwordx4 v[74:77], v[86:87], off offset:128
	v_exp_f32_e32 v29, v29
	s_waitcnt vmcnt(0)
	v_pk_fma_f32 v[74:75], v[80:81], v[82:83], v[74:75]
	v_add_f32_e32 v29, 1.0, v29
	v_rcp_f32_e32 v85, v29
	v_mul_f32_e32 v29, 0xbfb8aa3b, v72
	v_exp_f32_e32 v29, v29
	v_pk_fma_f32 v[76:77], v[84:85], v[78:79], v[76:77]
	global_store_dwordx4 v[86:87], v[74:77], off offset:128
	v_add_f32_e32 v29, 1.0, v29
	global_load_dwordx2 v[74:75], v[88:89], off offset:96
	v_rcp_f32_e32 v76, v29
	v_mul_f32_e32 v29, 0xbfb8aa3b, v73
	v_exp_f32_e32 v29, v29
	s_waitcnt vmcnt(0)
	v_lshlrev_b32_e32 v78, 16, v74
	v_add_f32_e32 v29, 1.0, v29
	v_rcp_f32_e32 v77, v29
	v_mul_f32_e32 v29, 0xbfb8aa3b, v70
	v_exp_f32_e32 v29, v29
	v_and_b32_e32 v79, 0xffff0000, v74
	v_lshlrev_b32_e32 v74, 16, v75
	v_and_b32_e32 v75, 0xffff0000, v75
	v_add_f32_e32 v29, 1.0, v29
	v_rcp_f32_e32 v80, v29
	v_mul_f32_e32 v29, 0xbfb8aa3b, v71
	global_load_dwordx4 v[70:73], v[86:87], off offset:192
	v_exp_f32_e32 v29, v29
	s_waitcnt vmcnt(0)
	v_pk_fma_f32 v[70:71], v[76:77], v[78:79], v[70:71]
	v_add_f32_e32 v29, 1.0, v29
	v_rcp_f32_e32 v81, v29
	v_mul_f32_e32 v29, 0xbfb8aa3b, v68
	v_exp_f32_e32 v29, v29
	v_pk_fma_f32 v[72:73], v[80:81], v[74:75], v[72:73]
	global_store_dwordx4 v[86:87], v[70:73], off offset:192
	v_add_f32_e32 v29, 1.0, v29
	v_rcp_f32_e32 v76, v29
	v_mul_f32_e32 v29, 0xbfb8aa3b, v69
	v_exp_f32_e32 v29, v29
	v_or_b32_e32 v70, 64, v28
	v_ashrrev_i32_e32 v71, 31, v70
	v_lshlrev_b64 v[72:73], 11, v[70:71]
	v_add_f32_e32 v29, 1.0, v29
	v_rcp_f32_e32 v77, v29
	v_mul_f32_e32 v29, 0xbfb8aa3b, v66
	v_exp_f32_e32 v29, v29
	v_lshl_add_u64 v[72:73], s[12:13], 0, v[72:73]
	v_lshlrev_b64 v[70:71], 12, v[70:71]
	v_lshl_add_u64 v[72:73], v[72:73], 0, v[0:1]
	v_lshl_add_u64 v[70:71], s[2:3], 0, v[70:71]
	global_load_dwordx2 v[74:75], v[72:73], off
	v_lshl_add_u64 v[70:71], v[70:71], 0, v[22:23]
	v_add_f32_e32 v29, 1.0, v29
	v_rcp_f32_e32 v80, v29
	v_mul_f32_e32 v29, 0xbfb8aa3b, v67
	global_load_dwordx4 v[66:69], v[70:71], off
	v_exp_f32_e32 v29, v29
	s_waitcnt vmcnt(1)
	v_lshlrev_b32_e32 v78, 16, v74
	v_add_f32_e32 v29, 1.0, v29
	v_rcp_f32_e32 v81, v29
	v_and_b32_e32 v79, 0xffff0000, v74
	v_lshlrev_b32_e32 v74, 16, v75
	v_and_b32_e32 v75, 0xffff0000, v75
	s_waitcnt vmcnt(0)
	v_pk_fma_f32 v[66:67], v[76:77], v[78:79], v[66:67]
	v_pk_fma_f32 v[68:69], v[80:81], v[74:75], v[68:69]
	global_store_dwordx4 v[70:71], v[66:69], off
	global_load_dwordx2 v[68:69], v[72:73], off offset:32
	v_mul_f32_e32 v29, 0xbfb8aa3b, v64
	global_load_dwordx4 v[74:77], v[70:71], off offset:64
	v_exp_f32_e32 v29, v29
	s_waitcnt vmcnt(1)
	v_lshlrev_b32_e32 v66, 16, v68
	v_add_f32_e32 v29, 1.0, v29
	v_rcp_f32_e32 v64, v29
	v_mul_f32_e32 v29, 0xbfb8aa3b, v65
	v_exp_f32_e32 v29, v29
	v_and_b32_e32 v67, 0xffff0000, v68
	v_lshlrev_b32_e32 v68, 16, v69
	v_and_b32_e32 v69, 0xffff0000, v69
	v_add_f32_e32 v29, 1.0, v29
	v_rcp_f32_e32 v65, v29
	v_mul_f32_e32 v29, 0xbfb8aa3b, v62
	v_exp_f32_e32 v29, v29
	s_waitcnt vmcnt(0)
	v_pk_fma_f32 v[64:65], v[64:65], v[66:67], v[74:75]
	v_add_f32_e32 v29, 1.0, v29
	v_rcp_f32_e32 v62, v29
	v_mul_f32_e32 v29, 0xbfb8aa3b, v63
	v_exp_f32_e32 v29, v29
	s_nop 0
	v_add_f32_e32 v29, 1.0, v29
	v_rcp_f32_e32 v63, v29
	v_mul_f32_e32 v29, 0xbfb8aa3b, v60
	v_exp_f32_e32 v29, v29
	v_pk_fma_f32 v[66:67], v[62:63], v[68:69], v[76:77]
	global_store_dwordx4 v[70:71], v[64:67], off offset:64
	v_add_f32_e32 v29, 1.0, v29
	global_load_dwordx2 v[62:63], v[72:73], off offset:64
	v_rcp_f32_e32 v64, v29
	v_mul_f32_e32 v29, 0xbfb8aa3b, v61
	v_exp_f32_e32 v29, v29
	s_waitcnt vmcnt(0)
; DI float bflo(unsigned u) { return __uint_as_float(u << 16); }
; DI float bfhi(unsigned u) { return __uint_as_float(u & 0xffff0000u); }
; DI float sigmoidf(float x) { return __builtin_amdgcn_rcpf(1.f + __expf(-x)); }
; __global__ void __launch_bounds__(512, 2) mega(Params p) {
;     ...
;       gemm8_epi(acc8, m0, n0, [&](int m, int n, f32x4& a) {
;         uint2 pv = *(const uint2*)(ppb + (size_t)m * DM + n);
;         float4* o = (float4*)(p.out + (size_t)m * DM + n);
;         float4 xv = *o;
;         *o = make_float4(xv.x + sigmoidf(a[0]) * bflo(pv.x), xv.y + sigmoidf(a[1]) * bfhi(pv.x),
;                          xv.z + sigmoidf(a[2]) * bflo(pv.y), xv.w + sigmoidf(a[3]) * bfhi(pv.y));
;       });
	v_lshlrev_b32_e32 v66, 16, v62
	v_add_f32_e32 v29, 1.0, v29
	v_rcp_f32_e32 v65, v29
	v_mul_f32_e32 v29, 0xbfb8aa3b, v58
	v_exp_f32_e32 v29, v29
	v_and_b32_e32 v67, 0xffff0000, v62
	v_lshlrev_b32_e32 v62, 16, v63
	v_and_b32_e32 v63, 0xffff0000, v63
	v_add_f32_e32 v29, 1.0, v29
	v_rcp_f32_e32 v68, v29
	v_mul_f32_e32 v29, 0xbfb8aa3b, v59
	global_load_dwordx4 v[58:61], v[70:71], off offset:128
	v_exp_f32_e32 v29, v29
	s_waitcnt vmcnt(0)
	v_pk_fma_f32 v[58:59], v[64:65], v[66:67], v[58:59]
	v_add_f32_e32 v29, 1.0, v29
	v_rcp_f32_e32 v69, v29
	v_mul_f32_e32 v29, 0xbfb8aa3b, v56
	v_exp_f32_e32 v29, v29
	v_pk_fma_f32 v[60:61], v[68:69], v[62:63], v[60:61]
	global_store_dwordx4 v[70:71], v[58:61], off offset:128
	v_add_f32_e32 v29, 1.0, v29
	global_load_dwordx2 v[58:59], v[72:73], off offset:96
	v_rcp_f32_e32 v60, v29
	v_mul_f32_e32 v29, 0xbfb8aa3b, v57
	v_exp_f32_e32 v29, v29
	s_waitcnt vmcnt(0)
	v_lshlrev_b32_e32 v62, 16, v58
	v_add_f32_e32 v29, 1.0, v29
	v_rcp_f32_e32 v61, v29
	v_mul_f32_e32 v29, 0xbfb8aa3b, v54
	v_exp_f32_e32 v29, v29
	v_and_b32_e32 v63, 0xffff0000, v58
	v_lshlrev_b32_e32 v58, 16, v59
	v_and_b32_e32 v59, 0xffff0000, v59
	v_add_f32_e32 v29, 1.0, v29
	v_rcp_f32_e32 v64, v29
	v_mul_f32_e32 v29, 0xbfb8aa3b, v55
	global_load_dwordx4 v[54:57], v[70:71], off offset:192
	v_exp_f32_e32 v29, v29
	s_waitcnt vmcnt(0)
	v_pk_fma_f32 v[54:55], v[60:61], v[62:63], v[54:55]
	v_add_f32_e32 v29, 1.0, v29
	v_rcp_f32_e32 v65, v29
	v_mul_f32_e32 v29, 0xbfb8aa3b, v52
	v_exp_f32_e32 v29, v29
	v_pk_fma_f32 v[56:57], v[64:65], v[58:59], v[56:57]
	global_store_dwordx4 v[70:71], v[54:57], off offset:192
	v_add_f32_e32 v29, 1.0, v29
	v_rcp_f32_e32 v60, v29
	v_mul_f32_e32 v29, 0xbfb8aa3b, v53
	v_exp_f32_e32 v29, v29
	v_or_b32_e32 v54, 0x50, v28
	v_ashrrev_i32_e32 v55, 31, v54
	v_lshlrev_b64 v[56:57], 11, v[54:55]
	v_add_f32_e32 v29, 1.0, v29
	v_rcp_f32_e32 v61, v29
	v_mul_f32_e32 v29, 0xbfb8aa3b, v50
	v_exp_f32_e32 v29, v29
	v_lshl_add_u64 v[56:57], s[12:13], 0, v[56:57]
	v_lshlrev_b64 v[54:55], 12, v[54:55]
	v_lshl_add_u64 v[56:57], v[56:57], 0, v[0:1]
	v_lshl_add_u64 v[54:55], s[2:3], 0, v[54:55]
	global_load_dwordx2 v[58:59], v[56:57], off
	v_lshl_add_u64 v[54:55], v[54:55], 0, v[22:23]
	v_add_f32_e32 v29, 1.0, v29
	v_rcp_f32_e32 v64, v29
	v_mul_f32_e32 v29, 0xbfb8aa3b, v51
	global_load_dwordx4 v[50:53], v[54:55], off
	v_exp_f32_e32 v29, v29
	s_waitcnt vmcnt(1)
	v_lshlrev_b32_e32 v62, 16, v58
	v_add_f32_e32 v29, 1.0, v29
	v_rcp_f32_e32 v65, v29
	v_and_b32_e32 v63, 0xffff0000, v58
	v_lshlrev_b32_e32 v58, 16, v59
	v_and_b32_e32 v59, 0xffff0000, v59
	s_waitcnt vmcnt(0)
	v_pk_fma_f32 v[50:51], v[60:61], v[62:63], v[50:51]
	v_pk_fma_f32 v[52:53], v[64:65], v[58:59], v[52:53]
	global_store_dwordx4 v[54:55], v[50:53], off
	global_load_dwordx2 v[52:53], v[56:57], off offset:32
	v_mul_f32_e32 v29, 0xbfb8aa3b, v48
	global_load_dwordx4 v[58:61], v[54:55], off offset:64
	v_exp_f32_e32 v29, v29
	s_waitcnt vmcnt(1)
	v_lshlrev_b32_e32 v50, 16, v52
	v_add_f32_e32 v29, 1.0, v29
	v_rcp_f32_e32 v48, v29
	v_mul_f32_e32 v29, 0xbfb8aa3b, v49
	v_exp_f32_e32 v29, v29
	v_and_b32_e32 v51, 0xffff0000, v52
	v_lshlrev_b32_e32 v52, 16, v53
	v_and_b32_e32 v53, 0xffff0000, v53
	v_add_f32_e32 v29, 1.0, v29
	v_rcp_f32_e32 v49, v29
	v_mul_f32_e32 v29, 0xbfb8aa3b, v46
	v_exp_f32_e32 v29, v29
	s_waitcnt vmcnt(0)
	v_pk_fma_f32 v[48:49], v[48:49], v[50:51], v[58:59]
	v_add_f32_e32 v29, 1.0, v29
	v_rcp_f32_e32 v46, v29
	v_mul_f32_e32 v29, 0xbfb8aa3b, v47
	v_exp_f32_e32 v29, v29
	s_nop 0
	v_add_f32_e32 v29, 1.0, v29
	v_rcp_f32_e32 v47, v29
	v_mul_f32_e32 v29, 0xbfb8aa3b, v44
	v_exp_f32_e32 v29, v29
	v_pk_fma_f32 v[50:51], v[46:47], v[52:53], v[60:61]
	global_store_dwordx4 v[54:55], v[48:51], off offset:64
	v_add_f32_e32 v29, 1.0, v29
	global_load_dwordx2 v[46:47], v[56:57], off offset:64
	v_rcp_f32_e32 v48, v29
	v_mul_f32_e32 v29, 0xbfb8aa3b, v45
	v_exp_f32_e32 v29, v29
	s_waitcnt vmcnt(0)
	v_lshlrev_b32_e32 v50, 16, v46
	v_add_f32_e32 v29, 1.0, v29
	v_rcp_f32_e32 v49, v29
	v_mul_f32_e32 v29, 0xbfb8aa3b, v42
	v_exp_f32_e32 v29, v29
	v_and_b32_e32 v51, 0xffff0000, v46
	v_lshlrev_b32_e32 v46, 16, v47
	v_and_b32_e32 v47, 0xffff0000, v47
	v_add_f32_e32 v29, 1.0, v29
	v_rcp_f32_e32 v52, v29
	v_mul_f32_e32 v29, 0xbfb8aa3b, v43
	global_load_dwordx4 v[42:45], v[54:55], off offset:128
	v_exp_f32_e32 v29, v29
	s_waitcnt vmcnt(0)
	v_pk_fma_f32 v[42:43], v[48:49], v[50:51], v[42:43]
	v_add_f32_e32 v29, 1.0, v29
	v_rcp_f32_e32 v53, v29
	v_mul_f32_e32 v29, 0xbfb8aa3b, v40
	v_exp_f32_e32 v29, v29
	v_pk_fma_f32 v[44:45], v[52:53], v[46:47], v[44:45]
	global_store_dwordx4 v[54:55], v[42:45], off offset:128
	v_add_f32_e32 v29, 1.0, v29
	global_load_dwordx2 v[42:43], v[56:57], off offset:96
	v_rcp_f32_e32 v44, v29
	v_mul_f32_e32 v29, 0xbfb8aa3b, v41
	v_exp_f32_e32 v29, v29
	s_waitcnt vmcnt(0)
	v_lshlrev_b32_e32 v46, 16, v42
	v_add_f32_e32 v29, 1.0, v29
	v_rcp_f32_e32 v45, v29
	v_mul_f32_e32 v29, 0xbfb8aa3b, v38
	v_exp_f32_e32 v29, v29
	v_and_b32_e32 v47, 0xffff0000, v42
	v_lshlrev_b32_e32 v42, 16, v43
	v_and_b32_e32 v43, 0xffff0000, v43
	v_add_f32_e32 v29, 1.0, v29
	v_rcp_f32_e32 v48, v29
	v_mul_f32_e32 v29, 0xbfb8aa3b, v39
	global_load_dwordx4 v[38:41], v[54:55], off offset:192
	v_exp_f32_e32 v29, v29
	s_waitcnt vmcnt(0)
; DI float bflo(unsigned u) { return __uint_as_float(u << 16); }
; DI float bfhi(unsigned u) { return __uint_as_float(u & 0xffff0000u); }
; DI float sigmoidf(float x) { return __builtin_amdgcn_rcpf(1.f + __expf(-x)); }
; __global__ void __launch_bounds__(512, 2) mega(Params p) {
;     ...
;       gemm8_epi(acc8, m0, n0, [&](int m, int n, f32x4& a) {
;         uint2 pv = *(const uint2*)(ppb + (size_t)m * DM + n);
;         float4* o = (float4*)(p.out + (size_t)m * DM + n);
;         float4 xv = *o;
;         *o = make_float4(xv.x + sigmoidf(a[0]) * bflo(pv.x), xv.y + sigmoidf(a[1]) * bfhi(pv.x),
;                          xv.z + sigmoidf(a[2]) * bflo(pv.y), xv.w + sigmoidf(a[3]) * bfhi(pv.y));
;       });
	v_pk_fma_f32 v[38:39], v[44:45], v[46:47], v[38:39]
	v_add_f32_e32 v29, 1.0, v29
	v_rcp_f32_e32 v49, v29
	v_mul_f32_e32 v29, 0xbfb8aa3b, v36
	v_exp_f32_e32 v29, v29
	v_pk_fma_f32 v[40:41], v[48:49], v[42:43], v[40:41]
	global_store_dwordx4 v[54:55], v[38:41], off offset:192
	v_add_f32_e32 v29, 1.0, v29
	v_rcp_f32_e32 v44, v29
	v_mul_f32_e32 v29, 0xbfb8aa3b, v37
	v_exp_f32_e32 v29, v29
	v_or_b32_e32 v38, 0x60, v28
	v_ashrrev_i32_e32 v39, 31, v38
	v_lshlrev_b64 v[40:41], 11, v[38:39]
	v_add_f32_e32 v29, 1.0, v29
	v_rcp_f32_e32 v45, v29
	v_mul_f32_e32 v29, 0xbfb8aa3b, v34
	v_exp_f32_e32 v29, v29
	v_lshl_add_u64 v[40:41], s[12:13], 0, v[40:41]
	v_lshlrev_b64 v[38:39], 12, v[38:39]
	v_lshl_add_u64 v[40:41], v[40:41], 0, v[0:1]
	v_lshl_add_u64 v[38:39], s[2:3], 0, v[38:39]
	global_load_dwordx2 v[42:43], v[40:41], off
	v_lshl_add_u64 v[38:39], v[38:39], 0, v[22:23]
	v_add_f32_e32 v29, 1.0, v29
	v_rcp_f32_e32 v48, v29
	v_mul_f32_e32 v29, 0xbfb8aa3b, v35
	global_load_dwordx4 v[34:37], v[38:39], off
	v_exp_f32_e32 v29, v29
	s_waitcnt vmcnt(1)
	v_lshlrev_b32_e32 v46, 16, v42
	v_add_f32_e32 v29, 1.0, v29
	v_rcp_f32_e32 v49, v29
	v_and_b32_e32 v47, 0xffff0000, v42
	v_lshlrev_b32_e32 v42, 16, v43
	v_and_b32_e32 v43, 0xffff0000, v43
	s_waitcnt vmcnt(0)
	v_pk_fma_f32 v[34:35], v[44:45], v[46:47], v[34:35]
	v_pk_fma_f32 v[36:37], v[48:49], v[42:43], v[36:37]
	global_store_dwordx4 v[38:39], v[34:37], off
	global_load_dwordx2 v[36:37], v[40:41], off offset:32
	v_mul_f32_e32 v29, 0xbfb8aa3b, v32
	global_load_dwordx4 v[42:45], v[38:39], off offset:64
	v_exp_f32_e32 v29, v29
	s_waitcnt vmcnt(1)
	v_lshlrev_b32_e32 v34, 16, v36
	v_add_f32_e32 v29, 1.0, v29
	v_rcp_f32_e32 v32, v29
	v_mul_f32_e32 v29, 0xbfb8aa3b, v33
	v_exp_f32_e32 v29, v29
	v_and_b32_e32 v35, 0xffff0000, v36
	v_lshlrev_b32_e32 v36, 16, v37
	v_and_b32_e32 v37, 0xffff0000, v37
	v_add_f32_e32 v29, 1.0, v29
	v_rcp_f32_e32 v33, v29
	v_mul_f32_e32 v29, 0xbfb8aa3b, v30
	v_exp_f32_e32 v29, v29
	s_waitcnt vmcnt(0)
	v_pk_fma_f32 v[32:33], v[32:33], v[34:35], v[42:43]
	v_add_f32_e32 v29, 1.0, v29
	v_rcp_f32_e32 v30, v29
	v_mul_f32_e32 v29, 0xbfb8aa3b, v31
	v_exp_f32_e32 v29, v29
	s_nop 0
	v_add_f32_e32 v29, 1.0, v29
	v_rcp_f32_e32 v31, v29
	s_nop 0
	v_pk_fma_f32 v[34:35], v[30:31], v[36:37], v[44:45]
	global_store_dwordx4 v[38:39], v[32:35], off offset:64
	v_rcp_f32_e32 v36, v24
	v_mul_f32_e32 v24, 0xbfb8aa3b, v25
	v_rcp_f32_e32 v32, v26
	v_mul_f32_e32 v26, 0xbfb8aa3b, v27
	v_exp_f32_e32 v26, v26
	v_exp_f32_e32 v24, v24
	global_load_dwordx2 v[30:31], v[40:41], off offset:64
	v_add_f32_e32 v26, 1.0, v26
	v_add_f32_e32 v24, 1.0, v24
	v_rcp_f32_e32 v33, v26
	v_rcp_f32_e32 v37, v24
	global_load_dwordx4 v[24:27], v[38:39], off offset:128
	s_waitcnt vmcnt(1)
	v_lshlrev_b32_e32 v34, 16, v30
	v_and_b32_e32 v35, 0xffff0000, v30
	v_lshlrev_b32_e32 v30, 16, v31
	v_and_b32_e32 v31, 0xffff0000, v31
	s_waitcnt vmcnt(0)
	v_pk_fma_f32 v[24:25], v[32:33], v[34:35], v[24:25]
	v_pk_fma_f32 v[26:27], v[36:37], v[30:31], v[26:27]
	global_store_dwordx4 v[38:39], v[24:27], off offset:128
	global_load_dwordx2 v[24:25], v[40:41], off offset:96
	s_waitcnt vmcnt(0)
	v_lshlrev_b32_e32 v30, 16, v24
	v_rcp_f32_e32 v26, v18
	v_mul_f32_e32 v18, 0xbfb8aa3b, v19
	v_exp_f32_e32 v18, v18
	v_and_b32_e32 v31, 0xffff0000, v24
	v_lshlrev_b32_e32 v24, 16, v25
	v_and_b32_e32 v25, 0xffff0000, v25
	v_add_f32_e32 v18, 1.0, v18
	v_rcp_f32_e32 v27, v18
	v_mul_f32_e32 v18, 0xbfb8aa3b, v20
	v_exp_f32_e32 v18, v18
	s_nop 0
	v_add_f32_e32 v18, 1.0, v18
	v_rcp_f32_e32 v32, v18
	v_mul_f32_e32 v18, 0xbfb8aa3b, v21
	v_exp_f32_e32 v18, v18
	s_nop 0
	v_add_f32_e32 v18, 1.0, v18
	v_rcp_f32_e32 v33, v18
	global_load_dwordx4 v[18:21], v[38:39], off offset:192
	s_waitcnt vmcnt(0)
; DI float bflo(unsigned u) { return __uint_as_float(u << 16); }
; DI float bfhi(unsigned u) { return __uint_as_float(u & 0xffff0000u); }
; DI float sigmoidf(float x) { return __builtin_amdgcn_rcpf(1.f + __expf(-x)); }
; __global__ void __launch_bounds__(512, 2) mega(Params p) {
;     ...
;       gemm8_epi(acc8, m0, n0, [&](int m, int n, f32x4& a) {
;         uint2 pv = *(const uint2*)(ppb + (size_t)m * DM + n);
;         float4* o = (float4*)(p.out + (size_t)m * DM + n);
;         float4 xv = *o;
;         *o = make_float4(xv.x + sigmoidf(a[0]) * bflo(pv.x), xv.y + sigmoidf(a[1]) * bfhi(pv.x),
;                          xv.z + sigmoidf(a[2]) * bflo(pv.y), xv.w + sigmoidf(a[3]) * bfhi(pv.y));
;       });
	v_pk_fma_f32 v[18:19], v[26:27], v[30:31], v[18:19]
	v_pk_fma_f32 v[20:21], v[32:33], v[24:25], v[20:21]
	global_store_dwordx4 v[38:39], v[18:21], off offset:192
	s_nop 1
	v_or_b32_e32 v18, 0x70, v28
	v_ashrrev_i32_e32 v19, 31, v18
	v_lshlrev_b64 v[20:21], 11, v[18:19]
	v_lshl_add_u64 v[20:21], s[12:13], 0, v[20:21]
	v_lshl_add_u64 v[20:21], v[20:21], 0, v[0:1]
	v_mul_f32_e32 v0, 0xbfb8aa3b, v14
	v_exp_f32_e32 v0, v0
	v_lshlrev_b64 v[18:19], 12, v[18:19]
	v_lshl_add_u64 v[18:19], s[2:3], 0, v[18:19]
	v_lshl_add_u64 v[18:19], v[18:19], 0, v[22:23]
	v_add_f32_e32 v0, 1.0, v0
	v_rcp_f32_e32 v22, v0
	v_mul_f32_e32 v0, 0xbfb8aa3b, v15
	v_exp_f32_e32 v0, v0
	global_load_dwordx2 v[24:25], v[20:21], off
	v_add_f32_e32 v0, 1.0, v0
	v_rcp_f32_e32 v23, v0
	v_mul_f32_e32 v0, 0xbfb8aa3b, v16
	v_exp_f32_e32 v0, v0
	s_waitcnt vmcnt(0)
	v_lshlrev_b32_e32 v26, 16, v24
	v_add_f32_e32 v0, 1.0, v0
	v_rcp_f32_e32 v28, v0
	v_mul_f32_e32 v0, 0xbfb8aa3b, v17
	global_load_dwordx4 v[14:17], v[18:19], off
	v_exp_f32_e32 v0, v0
	v_and_b32_e32 v27, 0xffff0000, v24
	v_lshlrev_b32_e32 v24, 16, v25
	v_and_b32_e32 v25, 0xffff0000, v25
	v_add_f32_e32 v0, 1.0, v0
	v_rcp_f32_e32 v29, v0
	v_mul_f32_e32 v0, 0xbfb8aa3b, v10
	v_exp_f32_e32 v0, v0
	s_waitcnt vmcnt(0)
	v_pk_fma_f32 v[14:15], v[22:23], v[26:27], v[14:15]
	v_pk_fma_f32 v[16:17], v[28:29], v[24:25], v[16:17]
	global_store_dwordx4 v[18:19], v[14:17], off
	global_load_dwordx2 v[16:17], v[20:21], off offset:32
	v_add_f32_e32 v0, 1.0, v0
	global_load_dwordx4 v[22:25], v[18:19], off offset:64
	v_rcp_f32_e32 v10, v0
	v_mul_f32_e32 v0, 0xbfb8aa3b, v11
	v_exp_f32_e32 v0, v0
	s_waitcnt vmcnt(1)
	v_lshlrev_b32_e32 v14, 16, v16
	v_add_f32_e32 v0, 1.0, v0
	v_rcp_f32_e32 v11, v0
	v_mul_f32_e32 v0, 0xbfb8aa3b, v12
	v_exp_f32_e32 v0, v0
	v_and_b32_e32 v15, 0xffff0000, v16
	v_lshlrev_b32_e32 v16, 16, v17
	v_and_b32_e32 v17, 0xffff0000, v17
	v_add_f32_e32 v0, 1.0, v0
	v_rcp_f32_e32 v12, v0
	v_mul_f32_e32 v0, 0xbfb8aa3b, v13
	v_exp_f32_e32 v0, v0
	s_waitcnt vmcnt(0)
	v_pk_fma_f32 v[10:11], v[10:11], v[14:15], v[22:23]
	v_add_f32_e32 v0, 1.0, v0
	v_rcp_f32_e32 v13, v0
	v_mul_f32_e32 v0, 0xbfb8aa3b, v6
	v_exp_f32_e32 v0, v0
	v_pk_fma_f32 v[12:13], v[12:13], v[16:17], v[24:25]
	global_store_dwordx4 v[18:19], v[10:13], off offset:64
	v_add_f32_e32 v0, 1.0, v0
	global_load_dwordx2 v[10:11], v[20:21], off offset:64
	v_rcp_f32_e32 v12, v0
	v_mul_f32_e32 v0, 0xbfb8aa3b, v7
	v_exp_f32_e32 v0, v0
	s_waitcnt vmcnt(0)
	v_lshlrev_b32_e32 v14, 16, v10
	v_add_f32_e32 v0, 1.0, v0
	v_rcp_f32_e32 v13, v0
	v_mul_f32_e32 v0, 0xbfb8aa3b, v8
	v_exp_f32_e32 v0, v0
	v_and_b32_e32 v15, 0xffff0000, v10
	v_lshlrev_b32_e32 v10, 16, v11
	v_and_b32_e32 v11, 0xffff0000, v11
	v_add_f32_e32 v0, 1.0, v0
	v_rcp_f32_e32 v16, v0
	v_mul_f32_e32 v0, 0xbfb8aa3b, v9
	global_load_dwordx4 v[6:9], v[18:19], off offset:128
	v_exp_f32_e32 v0, v0
	s_waitcnt vmcnt(0)
	v_pk_fma_f32 v[6:7], v[12:13], v[14:15], v[6:7]
	v_add_f32_e32 v0, 1.0, v0
	v_rcp_f32_e32 v17, v0
	v_mul_f32_e32 v0, 0xbfb8aa3b, v2
	v_exp_f32_e32 v0, v0
	v_pk_fma_f32 v[8:9], v[16:17], v[10:11], v[8:9]
	global_store_dwordx4 v[18:19], v[6:9], off offset:128
	v_add_f32_e32 v0, 1.0, v0
	global_load_dwordx2 v[6:7], v[20:21], off offset:96
	v_rcp_f32_e32 v8, v0
	v_mul_f32_e32 v0, 0xbfb8aa3b, v3
	v_exp_f32_e32 v0, v0
	s_waitcnt vmcnt(0)
	v_lshlrev_b32_e32 v10, 16, v6
	v_add_f32_e32 v0, 1.0, v0
	v_rcp_f32_e32 v9, v0
	v_mul_f32_e32 v0, 0xbfb8aa3b, v4
	v_exp_f32_e32 v0, v0
	v_and_b32_e32 v11, 0xffff0000, v6
	v_lshlrev_b32_e32 v6, 16, v7
	v_and_b32_e32 v7, 0xffff0000, v7
	v_add_f32_e32 v0, 1.0, v0
	v_rcp_f32_e32 v12, v0
	v_mul_f32_e32 v0, 0xbfb8aa3b, v5
	global_load_dwordx4 v[2:5], v[18:19], off offset:192
	v_exp_f32_e32 v0, v0
	s_waitcnt vmcnt(0)
	v_pk_fma_f32 v[2:3], v[8:9], v[10:11], v[2:3]
	v_add_f32_e32 v0, 1.0, v0
	v_rcp_f32_e32 v13, v0
	s_nop 0
	v_pk_fma_f32 v[4:5], v[12:13], v[6:7], v[4:5]
	global_store_dwordx4 v[18:19], v[2:5], off offset:192
	s_cbranch_vccnz .LBB0_998
